# prologue de-serialisation: the 14 weight-transpose load loops fully unrolled (16 src + 16 gain loads in flight, one wait); all priority inserts padded to 8 bytes and padding added so later code keeps
# speedup vs baseline: 1.0128x; 1.0128x over previous
; DI void transpose_mat(const float* __restrict__ src, int ld_src, bf16_t* __restrict__ dst, int N, int K, const float* __restrict__ gain, int map, float* lds, int rot) {
;     ...
; #pragma unroll 4
;     for (int r = 0; r < 16; ++r) {
;       const int kk = r * 4 + rq;
;       float v = 0.f;
;       if (sc >= 0) { v = src[(size_t)(k0 + kk) * ld_src + sc]; if (gain) v *= gain[k0 + kk]; }
;       lds[c * 65 + kk] = v;
;     }
; DI void phase_prologue(const Params& p, char* lds) {
;     ...
;     transpose_mat(p.in[5] + (size_t)L * 1024 * 5632, 5632, wl + W_FFN1_IN, 5632, 1024, p.in[4] + L * 1024, 1, tl, rot); rot += 88 * 16;
.LBB0_10:
.LBB0_11:
	v_mov_b32_e32 v64, 0
	v_mov_b32_e32 v65, 0
	v_mov_b32_e32 v66, 0
	v_mov_b32_e32 v67, 0
	v_mov_b32_e32 v68, 0
	v_mov_b32_e32 v69, 0
	v_mov_b32_e32 v70, 0
	v_mov_b32_e32 v71, 0
	v_mov_b32_e32 v72, 0
	v_mov_b32_e32 v73, 0
	v_mov_b32_e32 v74, 0
	v_mov_b32_e32 v75, 0
	v_mov_b32_e32 v76, 0
	v_mov_b32_e32 v77, 0
	v_mov_b32_e32 v78, 0
	v_mov_b32_e32 v79, 0
	v_mov_b32_e32 v15, 0
	v_cmp_ne_u32_e64 s[4:5], 1, v27
	v_mov_b32_e32 v24, 0
	s_and_saveexec_b64 s[54:55], s[2:3]
	s_cbranch_execz .Ltp0_skip
	v_add_u32_e32 v22, s89, v2
	v_mad_i64_i32 v[30:31], s[90:91], v22, s78, v[18:19]
	global_load_dword v64, v[30:31], off
	s_and_b64 vcc, exec, s[4:5]
	s_cbranch_vccnz .Ltp0_ng0
	v_ashrrev_i32_e32 v23, 31, v22
	v_lshl_add_u64 v[22:23], v[22:23], 2, s[48:49]
	global_load_dword v80, v[22:23], off
.Ltp0_ng0:
	v_add3_u32 v15, v2, s89, 4
	v_mad_i64_i32 v[22:23], s[90:91], v15, s78, v[18:19]
	global_load_dword v65, v[22:23], off
	s_and_b64 vcc, exec, s[4:5]
	s_cbranch_vccnz .Ltp0_ng1
	global_load_dword v81, v[20:21], off offset:-16
.Ltp0_ng1:
	v_add3_u32 v22, v2, s89, 8
	v_mad_i64_i32 v[22:23], s[90:91], v22, s78, v[18:19]
	global_load_dword v66, v[22:23], off
	s_and_b64 vcc, exec, s[4:5]
	s_cbranch_vccnz .Ltp0_ng2
	global_load_dword v82, v[20:21], off
.Ltp0_ng2:
	v_add3_u32 v15, v2, s89, 12
	v_mad_i64_i32 v[22:23], s[90:91], v15, s78, v[18:19]
	global_load_dword v67, v[22:23], off
	s_and_b64 vcc, exec, s[4:5]
	s_cbranch_vccnz .Ltp0_ng3
	global_load_dword v83, v[20:21], off offset:16
.Ltp0_ng3:
	s_add_i32 s89, s89, 16
	v_lshl_add_u64 v[20:21], v[20:21], 0, 64
	v_add_u32_e32 v22, s89, v2
	v_mad_i64_i32 v[30:31], s[90:91], v22, s78, v[18:19]
	global_load_dword v68, v[30:31], off
	s_and_b64 vcc, exec, s[4:5]
	s_cbranch_vccnz .Ltp0_ng4
	v_ashrrev_i32_e32 v23, 31, v22
	v_lshl_add_u64 v[22:23], v[22:23], 2, s[48:49]
	global_load_dword v84, v[22:23], off
.Ltp0_ng4:
	v_add3_u32 v15, v2, s89, 4
	v_mad_i64_i32 v[22:23], s[90:91], v15, s78, v[18:19]
	global_load_dword v69, v[22:23], off
	s_and_b64 vcc, exec, s[4:5]
	s_cbranch_vccnz .Ltp0_ng5
	global_load_dword v85, v[20:21], off offset:-16
.Ltp0_ng5:
	v_add3_u32 v22, v2, s89, 8
	v_mad_i64_i32 v[22:23], s[90:91], v22, s78, v[18:19]
	global_load_dword v70, v[22:23], off
	s_and_b64 vcc, exec, s[4:5]
	s_cbranch_vccnz .Ltp0_ng6
	global_load_dword v86, v[20:21], off
.Ltp0_ng6:
	v_add3_u32 v15, v2, s89, 12
	v_mad_i64_i32 v[22:23], s[90:91], v15, s78, v[18:19]
	global_load_dword v71, v[22:23], off
	s_and_b64 vcc, exec, s[4:5]
	s_cbranch_vccnz .Ltp0_ng7
	global_load_dword v87, v[20:21], off offset:16
.Ltp0_ng7:
	s_add_i32 s89, s89, 16
	v_lshl_add_u64 v[20:21], v[20:21], 0, 64
	v_add_u32_e32 v22, s89, v2
	v_mad_i64_i32 v[30:31], s[90:91], v22, s78, v[18:19]
	global_load_dword v72, v[30:31], off
	s_and_b64 vcc, exec, s[4:5]
	s_cbranch_vccnz .Ltp0_ng8
	v_ashrrev_i32_e32 v23, 31, v22
	v_lshl_add_u64 v[22:23], v[22:23], 2, s[48:49]
	global_load_dword v88, v[22:23], off
.Ltp0_ng8:
	v_add3_u32 v15, v2, s89, 4
	v_mad_i64_i32 v[22:23], s[90:91], v15, s78, v[18:19]
	global_load_dword v73, v[22:23], off
	s_and_b64 vcc, exec, s[4:5]
	s_cbranch_vccnz .Ltp0_ng9
	global_load_dword v89, v[20:21], off offset:-16
.Ltp0_ng9:
	v_add3_u32 v22, v2, s89, 8
	v_mad_i64_i32 v[22:23], s[90:91], v22, s78, v[18:19]
	global_load_dword v74, v[22:23], off
	s_and_b64 vcc, exec, s[4:5]
	s_cbranch_vccnz .Ltp0_ng10
	global_load_dword v90, v[20:21], off
.Ltp0_ng10:
	v_add3_u32 v15, v2, s89, 12
	v_mad_i64_i32 v[22:23], s[90:91], v15, s78, v[18:19]
	global_load_dword v75, v[22:23], off
	s_and_b64 vcc, exec, s[4:5]
	s_cbranch_vccnz .Ltp0_ng11
	global_load_dword v91, v[20:21], off offset:16
.Ltp0_ng11:
	s_add_i32 s89, s89, 16
	v_lshl_add_u64 v[20:21], v[20:21], 0, 64
	v_add_u32_e32 v22, s89, v2
	v_mad_i64_i32 v[30:31], s[90:91], v22, s78, v[18:19]
	global_load_dword v76, v[30:31], off
	s_and_b64 vcc, exec, s[4:5]
	s_cbranch_vccnz .Ltp0_ng12
	v_ashrrev_i32_e32 v23, 31, v22
	v_lshl_add_u64 v[22:23], v[22:23], 2, s[48:49]
	global_load_dword v92, v[22:23], off
.Ltp0_ng12:
	v_add3_u32 v15, v2, s89, 4
	v_mad_i64_i32 v[22:23], s[90:91], v15, s78, v[18:19]
	global_load_dword v77, v[22:23], off
	s_and_b64 vcc, exec, s[4:5]
	s_cbranch_vccnz .Ltp0_ng13
	global_load_dword v93, v[20:21], off offset:-16
.Ltp0_ng13:
	v_add3_u32 v22, v2, s89, 8
	v_mad_i64_i32 v[22:23], s[90:91], v22, s78, v[18:19]
	global_load_dword v78, v[22:23], off
	s_and_b64 vcc, exec, s[4:5]
	s_cbranch_vccnz .Ltp0_ng14
	global_load_dword v94, v[20:21], off
.Ltp0_ng14:
	v_add3_u32 v15, v2, s89, 12
	v_mad_i64_i32 v[22:23], s[90:91], v15, s78, v[18:19]
	global_load_dword v79, v[22:23], off
	s_and_b64 vcc, exec, s[4:5]
	s_cbranch_vccnz .Ltp0_ng15
	global_load_dword v95, v[20:21], off offset:16
.Ltp0_ng15:
	s_and_b64 vcc, exec, s[4:5]
	s_cbranch_vccnz .Ltp0_nomul
	s_waitcnt vmcnt(0)
	v_mul_f32_e32 v64, v64, v80
	v_mul_f32_e32 v65, v65, v81
	v_mul_f32_e32 v66, v66, v82
	v_mul_f32_e32 v67, v67, v83
	v_mul_f32_e32 v68, v68, v84
	v_mul_f32_e32 v69, v69, v85
	v_mul_f32_e32 v70, v70, v86
	v_mul_f32_e32 v71, v71, v87
	v_mul_f32_e32 v72, v72, v88
	v_mul_f32_e32 v73, v73, v89
	v_mul_f32_e32 v74, v74, v90
	v_mul_f32_e32 v75, v75, v91
	v_mul_f32_e32 v76, v76, v92
	v_mul_f32_e32 v77, v77, v93
	v_mul_f32_e32 v78, v78, v94
	v_mul_f32_e32 v79, v79, v95
.Ltp0_nomul:
.Ltp0_skip:
	s_or_b64 exec, exec, s[54:55]
	s_waitcnt vmcnt(0)
	ds_write_b32 v13, v64
	ds_write_b32 v13, v65 offset:16
	ds_write_b32 v13, v66 offset:32
	ds_write_b32 v13, v67 offset:48
	ds_write_b32 v13, v68 offset:64
	ds_write_b32 v13, v69 offset:80
	ds_write_b32 v13, v70 offset:96
	ds_write_b32 v13, v71 offset:112
	ds_write_b32 v13, v72 offset:128
	ds_write_b32 v13, v73 offset:144
	ds_write_b32 v13, v74 offset:160
	ds_write_b32 v13, v75 offset:176
	ds_write_b32 v13, v76 offset:192
	ds_write_b32 v13, v77 offset:208
	ds_write_b32 v13, v78 offset:224
	ds_write_b32 v13, v79 offset:240
	s_movk_i32 s89, 0x40
	v_lshl_add_u64 v[20:21], v[20:21], 0, 64
	v_add_u32_e32 v13, 0x100, v13

; DI void transpose_mat(const float* __restrict__ src, int ld_src, bf16_t* __restrict__ dst, int N, int K, const float* __restrict__ gain, int map, float* lds, int rot) {
;     ...
; #pragma unroll 4
;     for (int r = 0; r < 16; ++r) {
;       const int kk = r * 4 + rq;
;       float v = 0.f;
;       if (sc >= 0) { v = src[(size_t)(k0 + kk) * ld_src + sc]; if (gain) v *= gain[k0 + kk]; }
;       lds[c * 65 + kk] = v;
;     }
; DI void phase_prologue(const Params& p, char* lds) {
;     ...
;     transpose_mat(p.in[6] + (size_t)L * 2816 * 1024, 1024, wl + W_FFN1_OUT, 1024, 2816, nullptr, 0, tl, rot); rot += 16 * 44;
.LBB0_29:
.LBB0_30:
	v_mov_b32_e32 v64, 0
	v_mov_b32_e32 v65, 0
	v_mov_b32_e32 v66, 0
	v_mov_b32_e32 v67, 0
	v_mov_b32_e32 v68, 0
	v_mov_b32_e32 v69, 0
	v_mov_b32_e32 v70, 0
	v_mov_b32_e32 v71, 0
	v_mov_b32_e32 v72, 0
	v_mov_b32_e32 v73, 0
	v_mov_b32_e32 v74, 0
	v_mov_b32_e32 v75, 0
	v_mov_b32_e32 v76, 0
	v_mov_b32_e32 v77, 0
	v_mov_b32_e32 v78, 0
	v_mov_b32_e32 v79, 0
	v_cndmask_b32_e64 v18, 0, 1, s[46:47]
	v_mov_b32_e32 v15, 0
	v_cmp_ne_u32_e64 s[2:3], 1, v18
	s_andn2_b64 vcc, exec, s[46:47]
	v_mov_b32_e32 v18, 0
	s_cbranch_vccnz .Ltp1_skip
	v_add_u32_e32 v18, s55, v2
	v_ashrrev_i32_e32 v19, 31, v18
	v_lshlrev_b64 v[18:19], 12, v[18:19]
	v_lshl_add_u64 v[18:19], v[16:17], 0, v[18:19]
	global_load_dword v64, v[18:19], off
	v_add3_u32 v18, v2, s55, 4
	v_ashrrev_i32_e32 v19, 31, v18
	v_lshlrev_b64 v[18:19], 12, v[18:19]
	v_lshl_add_u64 v[18:19], v[16:17], 0, v[18:19]
	global_load_dword v65, v[18:19], off
	v_add3_u32 v18, v2, s55, 8
	v_ashrrev_i32_e32 v19, 31, v18
	v_lshlrev_b64 v[18:19], 12, v[18:19]
	v_lshl_add_u64 v[18:19], v[16:17], 0, v[18:19]
	global_load_dword v66, v[18:19], off
	v_add3_u32 v18, v2, s55, 12
	v_ashrrev_i32_e32 v19, 31, v18
	v_lshlrev_b64 v[18:19], 12, v[18:19]
	v_lshl_add_u64 v[18:19], v[16:17], 0, v[18:19]
	global_load_dword v67, v[18:19], off
	s_add_i32 s55, s55, 16
	v_add_u32_e32 v18, s55, v2
	v_ashrrev_i32_e32 v19, 31, v18
	v_lshlrev_b64 v[18:19], 12, v[18:19]
	v_lshl_add_u64 v[18:19], v[16:17], 0, v[18:19]
	global_load_dword v68, v[18:19], off
	v_add3_u32 v18, v2, s55, 4
	v_ashrrev_i32_e32 v19, 31, v18
	v_lshlrev_b64 v[18:19], 12, v[18:19]
	v_lshl_add_u64 v[18:19], v[16:17], 0, v[18:19]
	global_load_dword v69, v[18:19], off
	v_add3_u32 v18, v2, s55, 8
	v_ashrrev_i32_e32 v19, 31, v18
	v_lshlrev_b64 v[18:19], 12, v[18:19]
	v_lshl_add_u64 v[18:19], v[16:17], 0, v[18:19]
	global_load_dword v70, v[18:19], off
	v_add3_u32 v18, v2, s55, 12
	v_ashrrev_i32_e32 v19, 31, v18
	v_lshlrev_b64 v[18:19], 12, v[18:19]
	v_lshl_add_u64 v[18:19], v[16:17], 0, v[18:19]
	global_load_dword v71, v[18:19], off
	s_add_i32 s55, s55, 16
	v_add_u32_e32 v18, s55, v2
	v_ashrrev_i32_e32 v19, 31, v18
	v_lshlrev_b64 v[18:19], 12, v[18:19]
	v_lshl_add_u64 v[18:19], v[16:17], 0, v[18:19]
	global_load_dword v72, v[18:19], off
	v_add3_u32 v18, v2, s55, 4
	v_ashrrev_i32_e32 v19, 31, v18
	v_lshlrev_b64 v[18:19], 12, v[18:19]
	v_lshl_add_u64 v[18:19], v[16:17], 0, v[18:19]
	global_load_dword v73, v[18:19], off
	v_add3_u32 v18, v2, s55, 8
	v_ashrrev_i32_e32 v19, 31, v18
	v_lshlrev_b64 v[18:19], 12, v[18:19]
	v_lshl_add_u64 v[18:19], v[16:17], 0, v[18:19]
	global_load_dword v74, v[18:19], off
	v_add3_u32 v18, v2, s55, 12
	v_ashrrev_i32_e32 v19, 31, v18
	v_lshlrev_b64 v[18:19], 12, v[18:19]
	v_lshl_add_u64 v[18:19], v[16:17], 0, v[18:19]
	global_load_dword v75, v[18:19], off
	s_add_i32 s55, s55, 16
	v_add_u32_e32 v18, s55, v2
	v_ashrrev_i32_e32 v19, 31, v18
	v_lshlrev_b64 v[18:19], 12, v[18:19]
	v_lshl_add_u64 v[18:19], v[16:17], 0, v[18:19]
	global_load_dword v76, v[18:19], off
	v_add3_u32 v18, v2, s55, 4
	v_ashrrev_i32_e32 v19, 31, v18
	v_lshlrev_b64 v[18:19], 12, v[18:19]
	v_lshl_add_u64 v[18:19], v[16:17], 0, v[18:19]
	global_load_dword v77, v[18:19], off
	v_add3_u32 v18, v2, s55, 8
	v_ashrrev_i32_e32 v19, 31, v18
	v_lshlrev_b64 v[18:19], 12, v[18:19]
	v_lshl_add_u64 v[18:19], v[16:17], 0, v[18:19]
	global_load_dword v78, v[18:19], off
	v_add3_u32 v18, v2, s55, 12
	v_ashrrev_i32_e32 v19, 31, v18
	v_lshlrev_b64 v[18:19], 12, v[18:19]
	v_lshl_add_u64 v[18:19], v[16:17], 0, v[18:19]
	global_load_dword v79, v[18:19], off
.Ltp1_skip:
	s_waitcnt vmcnt(0)
	ds_write_b32 v13, v64
	ds_write_b32 v13, v65 offset:16
	ds_write_b32 v13, v66 offset:32
	ds_write_b32 v13, v67 offset:48
	ds_write_b32 v13, v68 offset:64
	ds_write_b32 v13, v69 offset:80
	ds_write_b32 v13, v70 offset:96
	ds_write_b32 v13, v71 offset:112
	ds_write_b32 v13, v72 offset:128
	ds_write_b32 v13, v73 offset:144
	ds_write_b32 v13, v74 offset:160
	ds_write_b32 v13, v75 offset:176
	ds_write_b32 v13, v76 offset:192
	ds_write_b32 v13, v77 offset:208
	ds_write_b32 v13, v78 offset:224
	ds_write_b32 v13, v79 offset:240
	s_movk_i32 s55, 0x40
	v_add_u32_e32 v13, 0x100, v13

; DI void transpose_mat(const float* __restrict__ src, int ld_src, bf16_t* __restrict__ dst, int N, int K, const float* __restrict__ gain, int map, float* lds, int rot) {
;     ...
; #pragma unroll 4
;     for (int r = 0; r < 16; ++r) {
;       const int kk = r * 4 + rq;
;       float v = 0.f;
;       if (sc >= 0) { v = src[(size_t)(k0 + kk) * ld_src + sc]; if (gain) v *= gain[k0 + kk]; }
;       lds[c * 65 + kk] = v;
;     }
; DI void phase_prologue(const Params& p, char* lds) {
;     ...
;     transpose_mat(p.in[8] + (size_t)L * 1024 * 3488, 3488, wl + W_IN, 3584, 1024, p.in[7] + L * 1024, 2, tl, rot); rot += 56 * 16;
.LBB0_50:
.LBB0_51:
	v_mov_b32_e32 v64, 0
	v_mov_b32_e32 v65, 0
	v_mov_b32_e32 v66, 0
	v_mov_b32_e32 v67, 0
	v_mov_b32_e32 v68, 0
	v_mov_b32_e32 v69, 0
	v_mov_b32_e32 v70, 0
	v_mov_b32_e32 v71, 0
	v_mov_b32_e32 v72, 0
	v_mov_b32_e32 v73, 0
	v_mov_b32_e32 v74, 0
	v_mov_b32_e32 v75, 0
	v_mov_b32_e32 v76, 0
	v_mov_b32_e32 v77, 0
	v_mov_b32_e32 v78, 0
	v_mov_b32_e32 v79, 0
	v_mov_b32_e32 v15, 0
	v_mov_b32_e32 v24, 0
	s_and_saveexec_b64 s[58:59], s[4:5]
	s_cbranch_execz .Ltp2_skip
	v_add_u32_e32 v22, s96, v2
	v_mad_i64_i32 v[30:31], vcc, v22, s82, v[18:19]
	global_load_dword v64, v[30:31], off
	s_andn2_b64 vcc, exec, s[0:1]
	s_cbranch_vccnz .Ltp2_ng0
	v_ashrrev_i32_e32 v23, 31, v22
	v_lshl_add_u64 v[22:23], v[22:23], 2, s[52:53]
	global_load_dword v80, v[22:23], off
.Ltp2_ng0:
	v_add3_u32 v15, v2, s96, 4
	v_mad_i64_i32 v[22:23], vcc, v15, s82, v[18:19]
	global_load_dword v65, v[22:23], off
	s_andn2_b64 vcc, exec, s[0:1]
	s_cbranch_vccnz .Ltp2_ng1
	global_load_dword v81, v[20:21], off offset:-16
.Ltp2_ng1:
	v_add3_u32 v22, v2, s96, 8
	v_mad_i64_i32 v[22:23], vcc, v22, s82, v[18:19]
	global_load_dword v66, v[22:23], off
	s_andn2_b64 vcc, exec, s[0:1]
	s_cbranch_vccnz .Ltp2_ng2
	global_load_dword v82, v[20:21], off
.Ltp2_ng2:
	v_add3_u32 v15, v2, s96, 12
	v_mad_i64_i32 v[22:23], vcc, v15, s82, v[18:19]
	global_load_dword v67, v[22:23], off
	s_andn2_b64 vcc, exec, s[0:1]
	s_cbranch_vccnz .Ltp2_ng3
	global_load_dword v83, v[20:21], off offset:16
.Ltp2_ng3:
	s_add_i32 s96, s96, 16
	v_lshl_add_u64 v[20:21], v[20:21], 0, 64
	v_add_u32_e32 v22, s96, v2
	v_mad_i64_i32 v[30:31], vcc, v22, s82, v[18:19]
	global_load_dword v68, v[30:31], off
	s_andn2_b64 vcc, exec, s[0:1]
	s_cbranch_vccnz .Ltp2_ng4
	v_ashrrev_i32_e32 v23, 31, v22
	v_lshl_add_u64 v[22:23], v[22:23], 2, s[52:53]
	global_load_dword v84, v[22:23], off
.Ltp2_ng4:
	v_add3_u32 v15, v2, s96, 4
	v_mad_i64_i32 v[22:23], vcc, v15, s82, v[18:19]
	global_load_dword v69, v[22:23], off
	s_andn2_b64 vcc, exec, s[0:1]
	s_cbranch_vccnz .Ltp2_ng5
	global_load_dword v85, v[20:21], off offset:-16
.Ltp2_ng5:
	v_add3_u32 v22, v2, s96, 8
	v_mad_i64_i32 v[22:23], vcc, v22, s82, v[18:19]
	global_load_dword v70, v[22:23], off
	s_andn2_b64 vcc, exec, s[0:1]
	s_cbranch_vccnz .Ltp2_ng6
	global_load_dword v86, v[20:21], off
.Ltp2_ng6:
	v_add3_u32 v15, v2, s96, 12
	v_mad_i64_i32 v[22:23], vcc, v15, s82, v[18:19]
	global_load_dword v71, v[22:23], off
	s_andn2_b64 vcc, exec, s[0:1]
	s_cbranch_vccnz .Ltp2_ng7
	global_load_dword v87, v[20:21], off offset:16
.Ltp2_ng7:
	s_add_i32 s96, s96, 16
	v_lshl_add_u64 v[20:21], v[20:21], 0, 64
	v_add_u32_e32 v22, s96, v2
	v_mad_i64_i32 v[30:31], vcc, v22, s82, v[18:19]
	global_load_dword v72, v[30:31], off
	s_andn2_b64 vcc, exec, s[0:1]
	s_cbranch_vccnz .Ltp2_ng8
	v_ashrrev_i32_e32 v23, 31, v22
	v_lshl_add_u64 v[22:23], v[22:23], 2, s[52:53]
	global_load_dword v88, v[22:23], off
.Ltp2_ng8:
	v_add3_u32 v15, v2, s96, 4
	v_mad_i64_i32 v[22:23], vcc, v15, s82, v[18:19]
	global_load_dword v73, v[22:23], off
	s_andn2_b64 vcc, exec, s[0:1]
	s_cbranch_vccnz .Ltp2_ng9
	global_load_dword v89, v[20:21], off offset:-16
.Ltp2_ng9:
	v_add3_u32 v22, v2, s96, 8
	v_mad_i64_i32 v[22:23], vcc, v22, s82, v[18:19]
	global_load_dword v74, v[22:23], off
	s_andn2_b64 vcc, exec, s[0:1]
	s_cbranch_vccnz .Ltp2_ng10
	global_load_dword v90, v[20:21], off
.Ltp2_ng10:
	v_add3_u32 v15, v2, s96, 12
	v_mad_i64_i32 v[22:23], vcc, v15, s82, v[18:19]
	global_load_dword v75, v[22:23], off
	s_andn2_b64 vcc, exec, s[0:1]
	s_cbranch_vccnz .Ltp2_ng11
	global_load_dword v91, v[20:21], off offset:16
.Ltp2_ng11:
	s_add_i32 s96, s96, 16
	v_lshl_add_u64 v[20:21], v[20:21], 0, 64
	v_add_u32_e32 v22, s96, v2
	v_mad_i64_i32 v[30:31], vcc, v22, s82, v[18:19]
	global_load_dword v76, v[30:31], off
	s_andn2_b64 vcc, exec, s[0:1]
	s_cbranch_vccnz .Ltp2_ng12
	v_ashrrev_i32_e32 v23, 31, v22
	v_lshl_add_u64 v[22:23], v[22:23], 2, s[52:53]
	global_load_dword v92, v[22:23], off
.Ltp2_ng12:
	v_add3_u32 v15, v2, s96, 4
	v_mad_i64_i32 v[22:23], vcc, v15, s82, v[18:19]
	global_load_dword v77, v[22:23], off
	s_andn2_b64 vcc, exec, s[0:1]
	s_cbranch_vccnz .Ltp2_ng13
	global_load_dword v93, v[20:21], off offset:-16
.Ltp2_ng13:
	v_add3_u32 v22, v2, s96, 8
	v_mad_i64_i32 v[22:23], vcc, v22, s82, v[18:19]
	global_load_dword v78, v[22:23], off
	s_andn2_b64 vcc, exec, s[0:1]
	s_cbranch_vccnz .Ltp2_ng14
	global_load_dword v94, v[20:21], off
.Ltp2_ng14:
	v_add3_u32 v15, v2, s96, 12
	v_mad_i64_i32 v[22:23], vcc, v15, s82, v[18:19]
	global_load_dword v79, v[22:23], off
	s_andn2_b64 vcc, exec, s[0:1]
	s_cbranch_vccnz .Ltp2_ng15
	global_load_dword v95, v[20:21], off offset:16
.Ltp2_ng15:
	s_andn2_b64 vcc, exec, s[0:1]
	s_cbranch_vccnz .Ltp2_nomul
	s_waitcnt vmcnt(0)
	v_mul_f32_e32 v64, v64, v80
	v_mul_f32_e32 v65, v65, v81
	v_mul_f32_e32 v66, v66, v82
	v_mul_f32_e32 v67, v67, v83
	v_mul_f32_e32 v68, v68, v84
	v_mul_f32_e32 v69, v69, v85
	v_mul_f32_e32 v70, v70, v86
	v_mul_f32_e32 v71, v71, v87
	v_mul_f32_e32 v72, v72, v88
	v_mul_f32_e32 v73, v73, v89
	v_mul_f32_e32 v74, v74, v90
	v_mul_f32_e32 v75, v75, v91
	v_mul_f32_e32 v76, v76, v92
	v_mul_f32_e32 v77, v77, v93
	v_mul_f32_e32 v78, v78, v94
	v_mul_f32_e32 v79, v79, v95
.Ltp2_nomul:
.Ltp2_skip:
	s_or_b64 exec, exec, s[58:59]
	s_waitcnt vmcnt(0)
	ds_write_b32 v13, v64
	ds_write_b32 v13, v65 offset:16
	ds_write_b32 v13, v66 offset:32
	ds_write_b32 v13, v67 offset:48
	ds_write_b32 v13, v68 offset:64
	ds_write_b32 v13, v69 offset:80
	ds_write_b32 v13, v70 offset:96
	ds_write_b32 v13, v71 offset:112
	ds_write_b32 v13, v72 offset:128
	ds_write_b32 v13, v73 offset:144
	ds_write_b32 v13, v74 offset:160
	ds_write_b32 v13, v75 offset:176
	ds_write_b32 v13, v76 offset:192
	ds_write_b32 v13, v77 offset:208
	ds_write_b32 v13, v78 offset:224
	ds_write_b32 v13, v79 offset:240
	s_movk_i32 s96, 0x40
	v_lshl_add_u64 v[20:21], v[20:21], 0, 64
	v_add_u32_e32 v13, 0x100, v13

; DI void transpose_mat(const float* __restrict__ src, int ld_src, bf16_t* __restrict__ dst, int N, int K, const float* __restrict__ gain, int map, float* lds, int rot) {
;     ...
; #pragma unroll 4
;     for (int r = 0; r < 16; ++r) {
;       const int kk = r * 4 + rq;
;       float v = 0.f;
;       if (sc >= 0) { v = src[(size_t)(k0 + kk) * ld_src + sc]; if (gain) v *= gain[k0 + kk]; }
;       lds[c * 65 + kk] = v;
;     }
; DI void phase_prologue(const Params& p, char* lds) {
;     ...
;     transpose_mat(p.in[20] + (size_t)L * 1024 * 3072, 3072, wl + W_GATE, 3072, 1024, p.in[7] + L * 1024, 0, tl, rot); rot += 48 * 16;
.LBB0_69:
.LBB0_70:
	v_mov_b32_e32 v64, 0
	v_mov_b32_e32 v65, 0
	v_mov_b32_e32 v66, 0
	v_mov_b32_e32 v67, 0
	v_mov_b32_e32 v68, 0
	v_mov_b32_e32 v69, 0
	v_mov_b32_e32 v70, 0
	v_mov_b32_e32 v71, 0
	v_mov_b32_e32 v72, 0
	v_mov_b32_e32 v73, 0
	v_mov_b32_e32 v74, 0
	v_mov_b32_e32 v75, 0
	v_mov_b32_e32 v76, 0
	v_mov_b32_e32 v77, 0
	v_mov_b32_e32 v78, 0
	v_mov_b32_e32 v79, 0
	v_cndmask_b32_e64 v22, 0, 1, s[58:59]
	v_cmp_ne_u32_e64 s[4:5], 1, v22
	v_cndmask_b32_e64 v22, 0, 1, s[0:1]
	v_mov_b32_e32 v15, 0
	s_andn2_b64 vcc, exec, s[58:59]
	v_cmp_ne_u32_e64 s[2:3], 1, v22
	v_mov_b32_e32 v24, 0
	s_cbranch_vccnz .Ltp3_skip
	v_add_u32_e32 v22, s96, v2
	v_mad_i64_i32 v[30:31], vcc, v22, s83, v[18:19]
	global_load_dword v64, v[30:31], off
	s_and_b64 vcc, exec, s[2:3]
	s_cbranch_vccnz .Ltp3_ng0
	v_ashrrev_i32_e32 v23, 31, v22
	v_lshl_add_u64 v[22:23], v[22:23], 2, s[52:53]
	global_load_dword v80, v[22:23], off
.Ltp3_ng0:
	v_add3_u32 v15, v2, s96, 4
	v_mad_i64_i32 v[22:23], vcc, v15, s83, v[18:19]
	global_load_dword v65, v[22:23], off
	s_and_b64 vcc, exec, s[2:3]
	s_cbranch_vccnz .Ltp3_ng1
	global_load_dword v81, v[20:21], off offset:-16
.Ltp3_ng1:
	v_add3_u32 v22, v2, s96, 8
	v_mad_i64_i32 v[22:23], vcc, v22, s83, v[18:19]
	global_load_dword v66, v[22:23], off
	s_and_b64 vcc, exec, s[2:3]
	s_cbranch_vccnz .Ltp3_ng2
	global_load_dword v82, v[20:21], off
.Ltp3_ng2:
	v_add3_u32 v15, v2, s96, 12
	v_mad_i64_i32 v[22:23], s[4:5], v15, s83, v[18:19]
	global_load_dword v67, v[22:23], off
	s_and_b64 vcc, exec, s[2:3]
	s_cbranch_vccnz .Ltp3_ng3
	global_load_dword v83, v[20:21], off offset:16
.Ltp3_ng3:
	s_add_i32 s96, s96, 16
	v_lshl_add_u64 v[20:21], v[20:21], 0, 64
	v_add_u32_e32 v22, s96, v2
	v_mad_i64_i32 v[30:31], vcc, v22, s83, v[18:19]
	global_load_dword v68, v[30:31], off
	s_and_b64 vcc, exec, s[2:3]
	s_cbranch_vccnz .Ltp3_ng4
	v_ashrrev_i32_e32 v23, 31, v22
	v_lshl_add_u64 v[22:23], v[22:23], 2, s[52:53]
	global_load_dword v84, v[22:23], off
.Ltp3_ng4:
	v_add3_u32 v15, v2, s96, 4
	v_mad_i64_i32 v[22:23], vcc, v15, s83, v[18:19]
	global_load_dword v69, v[22:23], off
	s_and_b64 vcc, exec, s[2:3]
	s_cbranch_vccnz .Ltp3_ng5
	global_load_dword v85, v[20:21], off offset:-16
.Ltp3_ng5:
	v_add3_u32 v22, v2, s96, 8
	v_mad_i64_i32 v[22:23], vcc, v22, s83, v[18:19]
	global_load_dword v70, v[22:23], off
	s_and_b64 vcc, exec, s[2:3]
	s_cbranch_vccnz .Ltp3_ng6
	global_load_dword v86, v[20:21], off
.Ltp3_ng6:
	v_add3_u32 v15, v2, s96, 12
	v_mad_i64_i32 v[22:23], s[4:5], v15, s83, v[18:19]
	global_load_dword v71, v[22:23], off
	s_and_b64 vcc, exec, s[2:3]
	s_cbranch_vccnz .Ltp3_ng7
	global_load_dword v87, v[20:21], off offset:16
.Ltp3_ng7:
	s_add_i32 s96, s96, 16
	v_lshl_add_u64 v[20:21], v[20:21], 0, 64
	v_add_u32_e32 v22, s96, v2
	v_mad_i64_i32 v[30:31], vcc, v22, s83, v[18:19]
	global_load_dword v72, v[30:31], off
	s_and_b64 vcc, exec, s[2:3]
	s_cbranch_vccnz .Ltp3_ng8
	v_ashrrev_i32_e32 v23, 31, v22
	v_lshl_add_u64 v[22:23], v[22:23], 2, s[52:53]
	global_load_dword v88, v[22:23], off
.Ltp3_ng8:
	v_add3_u32 v15, v2, s96, 4
	v_mad_i64_i32 v[22:23], vcc, v15, s83, v[18:19]
	global_load_dword v73, v[22:23], off
	s_and_b64 vcc, exec, s[2:3]
	s_cbranch_vccnz .Ltp3_ng9
	global_load_dword v89, v[20:21], off offset:-16
.Ltp3_ng9:
	v_add3_u32 v22, v2, s96, 8
	v_mad_i64_i32 v[22:23], vcc, v22, s83, v[18:19]
	global_load_dword v74, v[22:23], off
	s_and_b64 vcc, exec, s[2:3]
	s_cbranch_vccnz .Ltp3_ng10
	global_load_dword v90, v[20:21], off
.Ltp3_ng10:
	v_add3_u32 v15, v2, s96, 12
	v_mad_i64_i32 v[22:23], s[4:5], v15, s83, v[18:19]
	global_load_dword v75, v[22:23], off
	s_and_b64 vcc, exec, s[2:3]
	s_cbranch_vccnz .Ltp3_ng11
	global_load_dword v91, v[20:21], off offset:16
.Ltp3_ng11:
	s_add_i32 s96, s96, 16
	v_lshl_add_u64 v[20:21], v[20:21], 0, 64
	v_add_u32_e32 v22, s96, v2
	v_mad_i64_i32 v[30:31], vcc, v22, s83, v[18:19]
	global_load_dword v76, v[30:31], off
	s_and_b64 vcc, exec, s[2:3]
	s_cbranch_vccnz .Ltp3_ng12
	v_ashrrev_i32_e32 v23, 31, v22
	v_lshl_add_u64 v[22:23], v[22:23], 2, s[52:53]
	global_load_dword v92, v[22:23], off
.Ltp3_ng12:
	v_add3_u32 v15, v2, s96, 4
	v_mad_i64_i32 v[22:23], vcc, v15, s83, v[18:19]
	global_load_dword v77, v[22:23], off
	s_and_b64 vcc, exec, s[2:3]
	s_cbranch_vccnz .Ltp3_ng13
	global_load_dword v93, v[20:21], off offset:-16
.Ltp3_ng13:
	v_add3_u32 v22, v2, s96, 8
	v_mad_i64_i32 v[22:23], vcc, v22, s83, v[18:19]
	global_load_dword v78, v[22:23], off
	s_and_b64 vcc, exec, s[2:3]
	s_cbranch_vccnz .Ltp3_ng14
	global_load_dword v94, v[20:21], off
.Ltp3_ng14:
	v_add3_u32 v15, v2, s96, 12
	v_mad_i64_i32 v[22:23], s[4:5], v15, s83, v[18:19]
	global_load_dword v79, v[22:23], off
	s_and_b64 vcc, exec, s[2:3]
	s_cbranch_vccnz .Ltp3_ng15
	global_load_dword v95, v[20:21], off offset:16
.Ltp3_ng15:
	s_and_b64 vcc, exec, s[2:3]
	s_cbranch_vccnz .Ltp3_nomul
	s_waitcnt vmcnt(0)
	v_mul_f32_e32 v64, v64, v80
	v_mul_f32_e32 v65, v65, v81
	v_mul_f32_e32 v66, v66, v82
	v_mul_f32_e32 v67, v67, v83
	v_mul_f32_e32 v68, v68, v84
	v_mul_f32_e32 v69, v69, v85
	v_mul_f32_e32 v70, v70, v86
	v_mul_f32_e32 v71, v71, v87
	v_mul_f32_e32 v72, v72, v88
	v_mul_f32_e32 v73, v73, v89
	v_mul_f32_e32 v74, v74, v90
	v_mul_f32_e32 v75, v75, v91
	v_mul_f32_e32 v76, v76, v92
	v_mul_f32_e32 v77, v77, v93
	v_mul_f32_e32 v78, v78, v94
	v_mul_f32_e32 v79, v79, v95
.Ltp3_nomul:
.Ltp3_skip:
	s_waitcnt vmcnt(0)
	ds_write_b32 v13, v64
	ds_write_b32 v13, v65 offset:16
	ds_write_b32 v13, v66 offset:32
	ds_write_b32 v13, v67 offset:48
	ds_write_b32 v13, v68 offset:64
	ds_write_b32 v13, v69 offset:80
	ds_write_b32 v13, v70 offset:96
	ds_write_b32 v13, v71 offset:112
	ds_write_b32 v13, v72 offset:128
	ds_write_b32 v13, v73 offset:144
	ds_write_b32 v13, v74 offset:160
	ds_write_b32 v13, v75 offset:176
	ds_write_b32 v13, v76 offset:192
	ds_write_b32 v13, v77 offset:208
	ds_write_b32 v13, v78 offset:224
	ds_write_b32 v13, v79 offset:240
	s_movk_i32 s96, 0x40
	v_lshl_add_u64 v[20:21], v[20:21], 0, 64
	v_add_u32_e32 v13, 0x100, v13

; DI void transpose_mat(const float* __restrict__ src, int ld_src, bf16_t* __restrict__ dst, int N, int K, const float* __restrict__ gain, int map, float* lds, int rot) {
;     ...
; #pragma unroll 4
;     for (int r = 0; r < 16; ++r) {
;       const int kk = r * 4 + rq;
;       float v = 0.f;
;       if (sc >= 0) { v = src[(size_t)(k0 + kk) * ld_src + sc]; if (gain) v *= gain[k0 + kk]; }
;       lds[c * 65 + kk] = v;
;     }
; DI void phase_prologue(const Params& p, char* lds) {
;     ...
;     transpose_mat(p.in[11] + (size_t)L * 256 * 768, 768, wl + W_UQ, 768, 256, p.in[9] + L * 256, 3, tl, rot); rot += 12 * 4;
.LBB0_92:
.LBB0_93:
	v_mov_b32_e32 v64, 0
	v_mov_b32_e32 v65, 0
	v_mov_b32_e32 v66, 0
	v_mov_b32_e32 v67, 0
	v_mov_b32_e32 v68, 0
	v_mov_b32_e32 v69, 0
	v_mov_b32_e32 v70, 0
	v_mov_b32_e32 v71, 0
	v_mov_b32_e32 v72, 0
	v_mov_b32_e32 v73, 0
	v_mov_b32_e32 v74, 0
	v_mov_b32_e32 v75, 0
	v_mov_b32_e32 v76, 0
	v_mov_b32_e32 v77, 0
	v_mov_b32_e32 v78, 0
	v_mov_b32_e32 v79, 0
	v_cndmask_b32_e64 v17, 0, 1, s[24:25]
	v_mov_b32_e32 v15, 0
	v_cmp_ne_u32_e64 s[4:5], 1, v17
	v_mov_b32_e32 v17, 0
	s_and_saveexec_b64 s[56:57], s[2:3]
	s_cbranch_execz .Ltp4_skip
	v_add_u32_e32 v24, s91, v2
	v_mad_i64_i32 v[32:33], s[96:97], v24, s85, v[20:21]
	global_load_dword v64, v[32:33], off
	s_and_b64 vcc, exec, s[4:5]
	s_cbranch_vccnz .Ltp4_ng0
	v_ashrrev_i32_e32 v25, 31, v24
	v_lshl_add_u64 v[24:25], v[24:25], 2, s[54:55]
	global_load_dword v80, v[24:25], off
.Ltp4_ng0:
	v_add3_u32 v15, v2, s91, 4
	v_mad_i64_i32 v[24:25], s[96:97], v15, s85, v[20:21]
	global_load_dword v65, v[24:25], off
	s_and_b64 vcc, exec, s[4:5]
	s_cbranch_vccnz .Ltp4_ng1
	global_load_dword v81, v[22:23], off offset:-16
.Ltp4_ng1:
	v_add3_u32 v17, v2, s91, 8
	v_mad_i64_i32 v[24:25], s[96:97], v17, s85, v[20:21]
	global_load_dword v66, v[24:25], off
	s_and_b64 vcc, exec, s[4:5]
	s_cbranch_vccnz .Ltp4_ng2
	global_load_dword v82, v[22:23], off
.Ltp4_ng2:
	v_add3_u32 v15, v2, s91, 12
	v_mad_i64_i32 v[24:25], s[96:97], v15, s85, v[20:21]
	global_load_dword v67, v[24:25], off
	s_and_b64 vcc, exec, s[4:5]
	s_cbranch_vccnz .Ltp4_ng3
	global_load_dword v83, v[22:23], off offset:16
.Ltp4_ng3:
	s_add_i32 s91, s91, 16
	v_lshl_add_u64 v[22:23], v[22:23], 0, 64
	v_add_u32_e32 v24, s91, v2
	v_mad_i64_i32 v[32:33], s[96:97], v24, s85, v[20:21]
	global_load_dword v68, v[32:33], off
	s_and_b64 vcc, exec, s[4:5]
	s_cbranch_vccnz .Ltp4_ng4
	v_ashrrev_i32_e32 v25, 31, v24
	v_lshl_add_u64 v[24:25], v[24:25], 2, s[54:55]
	global_load_dword v84, v[24:25], off
.Ltp4_ng4:
	v_add3_u32 v15, v2, s91, 4
	v_mad_i64_i32 v[24:25], s[96:97], v15, s85, v[20:21]
	global_load_dword v69, v[24:25], off
	s_and_b64 vcc, exec, s[4:5]
	s_cbranch_vccnz .Ltp4_ng5
	global_load_dword v85, v[22:23], off offset:-16
.Ltp4_ng5:
	v_add3_u32 v17, v2, s91, 8
	v_mad_i64_i32 v[24:25], s[96:97], v17, s85, v[20:21]
	global_load_dword v70, v[24:25], off
	s_and_b64 vcc, exec, s[4:5]
	s_cbranch_vccnz .Ltp4_ng6
	global_load_dword v86, v[22:23], off
.Ltp4_ng6:
	v_add3_u32 v15, v2, s91, 12
	v_mad_i64_i32 v[24:25], s[96:97], v15, s85, v[20:21]
	global_load_dword v71, v[24:25], off
	s_and_b64 vcc, exec, s[4:5]
	s_cbranch_vccnz .Ltp4_ng7
	global_load_dword v87, v[22:23], off offset:16
.Ltp4_ng7:
	s_add_i32 s91, s91, 16
	v_lshl_add_u64 v[22:23], v[22:23], 0, 64
	v_add_u32_e32 v24, s91, v2
	v_mad_i64_i32 v[32:33], s[96:97], v24, s85, v[20:21]
	global_load_dword v72, v[32:33], off
	s_and_b64 vcc, exec, s[4:5]
	s_cbranch_vccnz .Ltp4_ng8
	v_ashrrev_i32_e32 v25, 31, v24
	v_lshl_add_u64 v[24:25], v[24:25], 2, s[54:55]
	global_load_dword v88, v[24:25], off
.Ltp4_ng8:
	v_add3_u32 v15, v2, s91, 4
	v_mad_i64_i32 v[24:25], s[96:97], v15, s85, v[20:21]
	global_load_dword v73, v[24:25], off
	s_and_b64 vcc, exec, s[4:5]
	s_cbranch_vccnz .Ltp4_ng9
	global_load_dword v89, v[22:23], off offset:-16
.Ltp4_ng9:
	v_add3_u32 v17, v2, s91, 8
	v_mad_i64_i32 v[24:25], s[96:97], v17, s85, v[20:21]
	global_load_dword v74, v[24:25], off
	s_and_b64 vcc, exec, s[4:5]
	s_cbranch_vccnz .Ltp4_ng10
	global_load_dword v90, v[22:23], off
.Ltp4_ng10:
	v_add3_u32 v15, v2, s91, 12
	v_mad_i64_i32 v[24:25], s[96:97], v15, s85, v[20:21]
	global_load_dword v75, v[24:25], off
	s_and_b64 vcc, exec, s[4:5]
	s_cbranch_vccnz .Ltp4_ng11
	global_load_dword v91, v[22:23], off offset:16
.Ltp4_ng11:
	s_add_i32 s91, s91, 16
	v_lshl_add_u64 v[22:23], v[22:23], 0, 64
	v_add_u32_e32 v24, s91, v2
	v_mad_i64_i32 v[32:33], s[96:97], v24, s85, v[20:21]
	global_load_dword v76, v[32:33], off
	s_and_b64 vcc, exec, s[4:5]
	s_cbranch_vccnz .Ltp4_ng12
	v_ashrrev_i32_e32 v25, 31, v24
	v_lshl_add_u64 v[24:25], v[24:25], 2, s[54:55]
	global_load_dword v92, v[24:25], off
.Ltp4_ng12:
	v_add3_u32 v15, v2, s91, 4
	v_mad_i64_i32 v[24:25], s[96:97], v15, s85, v[20:21]
	global_load_dword v77, v[24:25], off
	s_and_b64 vcc, exec, s[4:5]
	s_cbranch_vccnz .Ltp4_ng13
	global_load_dword v93, v[22:23], off offset:-16
.Ltp4_ng13:
	v_add3_u32 v17, v2, s91, 8
	v_mad_i64_i32 v[24:25], s[96:97], v17, s85, v[20:21]
	global_load_dword v78, v[24:25], off
	s_and_b64 vcc, exec, s[4:5]
	s_cbranch_vccnz .Ltp4_ng14
	global_load_dword v94, v[22:23], off
.Ltp4_ng14:
	v_add3_u32 v15, v2, s91, 12
	v_mad_i64_i32 v[24:25], s[96:97], v15, s85, v[20:21]
	global_load_dword v79, v[24:25], off
	s_and_b64 vcc, exec, s[4:5]
	s_cbranch_vccnz .Ltp4_ng15
	global_load_dword v95, v[22:23], off offset:16

; DI void transpose_mat(const float* __restrict__ src, int ld_src, bf16_t* __restrict__ dst, int N, int K, const float* __restrict__ gain, int map, float* lds, int rot) {
;     ...
;       if (sc >= 0) { v = src[(size_t)(k0 + kk) * ld_src + sc]; if (gain) v *= gain[k0 + kk]; }
;       lds[c * 65 + kk] = v;
;     }
.Ltp4_nomul:
.Ltp4_skip:
	s_or_b64 exec, exec, s[56:57]
	s_waitcnt vmcnt(0)
	ds_write_b32 v13, v64
	ds_write_b32 v13, v65 offset:16
	ds_write_b32 v13, v66 offset:32
	ds_write_b32 v13, v67 offset:48
	ds_write_b32 v13, v68 offset:64
	ds_write_b32 v13, v69 offset:80
	ds_write_b32 v13, v70 offset:96
	ds_write_b32 v13, v71 offset:112
	ds_write_b32 v13, v72 offset:128
	ds_write_b32 v13, v73 offset:144
	ds_write_b32 v13, v74 offset:160
	ds_write_b32 v13, v75 offset:176
	ds_write_b32 v13, v76 offset:192
	ds_write_b32 v13, v77 offset:208
	ds_write_b32 v13, v78 offset:224
	ds_write_b32 v13, v79 offset:240
	s_movk_i32 s91, 0x40
	v_lshl_add_u64 v[22:23], v[22:23], 0, 64
	v_add_u32_e32 v13, 0x100, v13

; DI void transpose_mat(const float* __restrict__ src, int ld_src, bf16_t* __restrict__ dst, int N, int K, const float* __restrict__ gain, int map, float* lds, int rot) {
;     ...
; #pragma unroll 4
;     for (int r = 0; r < 16; ++r) {
;       const int kk = r * 4 + rq;
;       float v = 0.f;
;       if (sc >= 0) { v = src[(size_t)(k0 + kk) * ld_src + sc]; if (gain) v *= gain[k0 + kk]; }
;       lds[c * 65 + kk] = v;
;     }
; DI void phase_prologue(const Params& p, char* lds) {
;     ...
;     transpose_mat(p.in[12] + (size_t)L * 128 * 1024, 1024, wl + W_UKV, 1024, 128, p.in[10] + L * 128, 4, tl, rot); rot += 16 * 2;
.LBB0_115:
.LBB0_116:
	v_mov_b32_e32 v64, 0
	v_mov_b32_e32 v65, 0
	v_mov_b32_e32 v66, 0
	v_mov_b32_e32 v67, 0
	v_mov_b32_e32 v68, 0
	v_mov_b32_e32 v69, 0
	v_mov_b32_e32 v70, 0
	v_mov_b32_e32 v71, 0
	v_mov_b32_e32 v72, 0
	v_mov_b32_e32 v73, 0
	v_mov_b32_e32 v74, 0
	v_mov_b32_e32 v75, 0
	v_mov_b32_e32 v76, 0
	v_mov_b32_e32 v77, 0
	v_mov_b32_e32 v78, 0
	v_mov_b32_e32 v79, 0
	v_cndmask_b32_e64 v22, 0, 1, s[26:27]
	v_mov_b32_e32 v15, 0
	v_cmp_ne_u32_e64 s[4:5], 1, v22
	v_mov_b32_e32 v24, 0
	s_and_saveexec_b64 s[58:59], s[2:3]
	s_cbranch_execz .Ltp5_skip
	v_add_u32_e32 v22, s97, v2
	v_ashrrev_i32_e32 v23, 31, v22
	v_lshlrev_b64 v[30:31], 12, v[22:23]
	v_lshl_add_u64 v[30:31], v[18:19], 0, v[30:31]
	global_load_dword v64, v[30:31], off
	s_and_b64 vcc, exec, s[4:5]
	s_cbranch_vccnz .Ltp5_ng0
	v_lshl_add_u64 v[22:23], v[22:23], 2, s[54:55]
	global_load_dword v80, v[22:23], off
.Ltp5_ng0:
	v_add3_u32 v22, v2, s97, 4
	v_ashrrev_i32_e32 v23, 31, v22
	v_lshlrev_b64 v[22:23], 12, v[22:23]
	v_lshl_add_u64 v[22:23], v[18:19], 0, v[22:23]
	global_load_dword v65, v[22:23], off
	s_and_b64 vcc, exec, s[4:5]
	s_cbranch_vccnz .Ltp5_ng1
	global_load_dword v81, v[20:21], off offset:-16
.Ltp5_ng1:
	v_add3_u32 v22, v2, s97, 8
	v_ashrrev_i32_e32 v23, 31, v22
	v_lshlrev_b64 v[22:23], 12, v[22:23]
	v_lshl_add_u64 v[22:23], v[18:19], 0, v[22:23]
	global_load_dword v66, v[22:23], off
	s_and_b64 vcc, exec, s[4:5]
	s_cbranch_vccnz .Ltp5_ng2
	global_load_dword v82, v[20:21], off
.Ltp5_ng2:
	v_add3_u32 v22, v2, s97, 12
	v_ashrrev_i32_e32 v23, 31, v22
	v_lshlrev_b64 v[22:23], 12, v[22:23]
	v_lshl_add_u64 v[22:23], v[18:19], 0, v[22:23]
	global_load_dword v67, v[22:23], off
	s_and_b64 vcc, exec, s[4:5]
	s_cbranch_vccnz .Ltp5_ng3
	global_load_dword v83, v[20:21], off offset:16
.Ltp5_ng3:
	s_add_i32 s97, s97, 16
	v_lshl_add_u64 v[20:21], v[20:21], 0, 64
	v_add_u32_e32 v22, s97, v2
	v_ashrrev_i32_e32 v23, 31, v22
	v_lshlrev_b64 v[30:31], 12, v[22:23]
	v_lshl_add_u64 v[30:31], v[18:19], 0, v[30:31]
	global_load_dword v68, v[30:31], off
	s_and_b64 vcc, exec, s[4:5]
	s_cbranch_vccnz .Ltp5_ng4
	v_lshl_add_u64 v[22:23], v[22:23], 2, s[54:55]
	global_load_dword v84, v[22:23], off
.Ltp5_ng4:
	v_add3_u32 v22, v2, s97, 4
	v_ashrrev_i32_e32 v23, 31, v22
	v_lshlrev_b64 v[22:23], 12, v[22:23]
	v_lshl_add_u64 v[22:23], v[18:19], 0, v[22:23]
	global_load_dword v69, v[22:23], off
	s_and_b64 vcc, exec, s[4:5]
	s_cbranch_vccnz .Ltp5_ng5
	global_load_dword v85, v[20:21], off offset:-16
.Ltp5_ng5:
	v_add3_u32 v22, v2, s97, 8
	v_ashrrev_i32_e32 v23, 31, v22
	v_lshlrev_b64 v[22:23], 12, v[22:23]
	v_lshl_add_u64 v[22:23], v[18:19], 0, v[22:23]
	global_load_dword v70, v[22:23], off
	s_and_b64 vcc, exec, s[4:5]
	s_cbranch_vccnz .Ltp5_ng6
	global_load_dword v86, v[20:21], off
.Ltp5_ng6:
	v_add3_u32 v22, v2, s97, 12
	v_ashrrev_i32_e32 v23, 31, v22
	v_lshlrev_b64 v[22:23], 12, v[22:23]
	v_lshl_add_u64 v[22:23], v[18:19], 0, v[22:23]
	global_load_dword v71, v[22:23], off
	s_and_b64 vcc, exec, s[4:5]
	s_cbranch_vccnz .Ltp5_ng7
	global_load_dword v87, v[20:21], off offset:16
.Ltp5_ng7:
	s_add_i32 s97, s97, 16
	v_lshl_add_u64 v[20:21], v[20:21], 0, 64
	v_add_u32_e32 v22, s97, v2
	v_ashrrev_i32_e32 v23, 31, v22
	v_lshlrev_b64 v[30:31], 12, v[22:23]
	v_lshl_add_u64 v[30:31], v[18:19], 0, v[30:31]
	global_load_dword v72, v[30:31], off
	s_and_b64 vcc, exec, s[4:5]
	s_cbranch_vccnz .Ltp5_ng8
	v_lshl_add_u64 v[22:23], v[22:23], 2, s[54:55]
	global_load_dword v88, v[22:23], off
.Ltp5_ng8:
	v_add3_u32 v22, v2, s97, 4
	v_ashrrev_i32_e32 v23, 31, v22
	v_lshlrev_b64 v[22:23], 12, v[22:23]
	v_lshl_add_u64 v[22:23], v[18:19], 0, v[22:23]
	global_load_dword v73, v[22:23], off
	s_and_b64 vcc, exec, s[4:5]
	s_cbranch_vccnz .Ltp5_ng9
	global_load_dword v89, v[20:21], off offset:-16
.Ltp5_ng9:
	v_add3_u32 v22, v2, s97, 8
	v_ashrrev_i32_e32 v23, 31, v22
	v_lshlrev_b64 v[22:23], 12, v[22:23]
	v_lshl_add_u64 v[22:23], v[18:19], 0, v[22:23]
	global_load_dword v74, v[22:23], off
	s_and_b64 vcc, exec, s[4:5]
	s_cbranch_vccnz .Ltp5_ng10
	global_load_dword v90, v[20:21], off
.Ltp5_ng10:
	v_add3_u32 v22, v2, s97, 12
	v_ashrrev_i32_e32 v23, 31, v22
	v_lshlrev_b64 v[22:23], 12, v[22:23]
	v_lshl_add_u64 v[22:23], v[18:19], 0, v[22:23]
	global_load_dword v75, v[22:23], off
	s_and_b64 vcc, exec, s[4:5]
	s_cbranch_vccnz .Ltp5_ng11
	global_load_dword v91, v[20:21], off offset:16
.Ltp5_ng11:
	s_add_i32 s97, s97, 16
	v_lshl_add_u64 v[20:21], v[20:21], 0, 64
	v_add_u32_e32 v22, s97, v2
	v_ashrrev_i32_e32 v23, 31, v22
	v_lshlrev_b64 v[30:31], 12, v[22:23]
	v_lshl_add_u64 v[30:31], v[18:19], 0, v[30:31]
	global_load_dword v76, v[30:31], off
	s_and_b64 vcc, exec, s[4:5]
	s_cbranch_vccnz .Ltp5_ng12
	v_lshl_add_u64 v[22:23], v[22:23], 2, s[54:55]
	global_load_dword v92, v[22:23], off
.Ltp5_ng12:
	v_add3_u32 v22, v2, s97, 4
	v_ashrrev_i32_e32 v23, 31, v22
	v_lshlrev_b64 v[22:23], 12, v[22:23]
	v_lshl_add_u64 v[22:23], v[18:19], 0, v[22:23]
	global_load_dword v77, v[22:23], off
	s_and_b64 vcc, exec, s[4:5]
	s_cbranch_vccnz .Ltp5_ng13
	global_load_dword v93, v[20:21], off offset:-16
.Ltp5_ng13:
	v_add3_u32 v22, v2, s97, 8
	v_ashrrev_i32_e32 v23, 31, v22
	v_lshlrev_b64 v[22:23], 12, v[22:23]
	v_lshl_add_u64 v[22:23], v[18:19], 0, v[22:23]
	global_load_dword v78, v[22:23], off
	s_and_b64 vcc, exec, s[4:5]
	s_cbranch_vccnz .Ltp5_ng14
	global_load_dword v94, v[20:21], off
.Ltp5_ng14:
	v_add3_u32 v22, v2, s97, 12
	v_ashrrev_i32_e32 v23, 31, v22
	v_lshlrev_b64 v[22:23], 12, v[22:23]
	v_lshl_add_u64 v[22:23], v[18:19], 0, v[22:23]
	global_load_dword v79, v[22:23], off
	s_and_b64 vcc, exec, s[4:5]
	s_cbranch_vccnz .Ltp5_ng15
	global_load_dword v95, v[20:21], off offset:16

; DI void transpose_mat(const float* __restrict__ src, int ld_src, bf16_t* __restrict__ dst, int N, int K, const float* __restrict__ gain, int map, float* lds, int rot) {
;     ...
;       if (sc >= 0) { v = src[(size_t)(k0 + kk) * ld_src + sc]; if (gain) v *= gain[k0 + kk]; }
;       lds[c * 65 + kk] = v;
;     }
.Ltp5_nomul:
.Ltp5_skip:
	s_or_b64 exec, exec, s[58:59]
	s_waitcnt vmcnt(0)
	ds_write_b32 v13, v64
	ds_write_b32 v13, v65 offset:16
	ds_write_b32 v13, v66 offset:32
	ds_write_b32 v13, v67 offset:48
	ds_write_b32 v13, v68 offset:64
	ds_write_b32 v13, v69 offset:80
	ds_write_b32 v13, v70 offset:96
	ds_write_b32 v13, v71 offset:112
	ds_write_b32 v13, v72 offset:128
	ds_write_b32 v13, v73 offset:144
	ds_write_b32 v13, v74 offset:160
	ds_write_b32 v13, v75 offset:176
	ds_write_b32 v13, v76 offset:192
	ds_write_b32 v13, v77 offset:208
	ds_write_b32 v13, v78 offset:224
	ds_write_b32 v13, v79 offset:240
	s_movk_i32 s97, 0x40
	v_lshl_add_u64 v[20:21], v[20:21], 0, 64
	v_add_u32_e32 v13, 0x100, v13

; DI void transpose_mat(const float* __restrict__ src, int ld_src, bf16_t* __restrict__ dst, int N, int K, const float* __restrict__ gain, int map, float* lds, int rot) {
;     ...
; #pragma unroll 4
;     for (int r = 0; r < 16; ++r) {
;       const int kk = r * 4 + rq;
;       float v = 0.f;
;       if (sc >= 0) { v = src[(size_t)(k0 + kk) * ld_src + sc]; if (gain) v *= gain[k0 + kk]; }
;       lds[c * 65 + kk] = v;
;     }
; DI void phase_prologue(const Params& p, char* lds) {
;     ...
;     transpose_mat(p.in[22] + (size_t)L * 512 * 1024, 1024, wl + W_OA, 1024, 512, nullptr, 0, tl, rot); rot += 16 * 8;
.LBB0_134:
.LBB0_135:
	v_mov_b32_e32 v64, 0
	v_mov_b32_e32 v65, 0
	v_mov_b32_e32 v66, 0
	v_mov_b32_e32 v67, 0
	v_mov_b32_e32 v68, 0
	v_mov_b32_e32 v69, 0
	v_mov_b32_e32 v70, 0
	v_mov_b32_e32 v71, 0
	v_mov_b32_e32 v72, 0
	v_mov_b32_e32 v73, 0
	v_mov_b32_e32 v74, 0
	v_mov_b32_e32 v75, 0
	v_mov_b32_e32 v76, 0
	v_mov_b32_e32 v77, 0
	v_mov_b32_e32 v78, 0
	v_mov_b32_e32 v79, 0
	v_cndmask_b32_e64 v18, 0, 1, s[50:51]
	v_mov_b32_e32 v15, 0
	v_cmp_ne_u32_e64 s[2:3], 1, v18
	s_andn2_b64 vcc, exec, s[50:51]
	v_mov_b32_e32 v18, 0
	s_cbranch_vccnz .Ltp6_skip
	v_add_u32_e32 v18, s57, v2
	v_ashrrev_i32_e32 v19, 31, v18
	v_lshlrev_b64 v[18:19], 12, v[18:19]
	v_lshl_add_u64 v[18:19], v[16:17], 0, v[18:19]
	global_load_dword v64, v[18:19], off
	v_add3_u32 v18, v2, s57, 4
	v_ashrrev_i32_e32 v19, 31, v18
	v_lshlrev_b64 v[18:19], 12, v[18:19]
	v_lshl_add_u64 v[18:19], v[16:17], 0, v[18:19]
	global_load_dword v65, v[18:19], off
	v_add3_u32 v18, v2, s57, 8
	v_ashrrev_i32_e32 v19, 31, v18
	v_lshlrev_b64 v[18:19], 12, v[18:19]
	v_lshl_add_u64 v[18:19], v[16:17], 0, v[18:19]
	global_load_dword v66, v[18:19], off
	v_add3_u32 v18, v2, s57, 12
	v_ashrrev_i32_e32 v19, 31, v18
	v_lshlrev_b64 v[18:19], 12, v[18:19]
	v_lshl_add_u64 v[18:19], v[16:17], 0, v[18:19]
	global_load_dword v67, v[18:19], off
	s_add_i32 s57, s57, 16
	v_add_u32_e32 v18, s57, v2
	v_ashrrev_i32_e32 v19, 31, v18
	v_lshlrev_b64 v[18:19], 12, v[18:19]
	v_lshl_add_u64 v[18:19], v[16:17], 0, v[18:19]
	global_load_dword v68, v[18:19], off
	v_add3_u32 v18, v2, s57, 4
	v_ashrrev_i32_e32 v19, 31, v18
	v_lshlrev_b64 v[18:19], 12, v[18:19]
	v_lshl_add_u64 v[18:19], v[16:17], 0, v[18:19]
	global_load_dword v69, v[18:19], off
	v_add3_u32 v18, v2, s57, 8
	v_ashrrev_i32_e32 v19, 31, v18
	v_lshlrev_b64 v[18:19], 12, v[18:19]
	v_lshl_add_u64 v[18:19], v[16:17], 0, v[18:19]
	global_load_dword v70, v[18:19], off
	v_add3_u32 v18, v2, s57, 12
	v_ashrrev_i32_e32 v19, 31, v18
	v_lshlrev_b64 v[18:19], 12, v[18:19]
	v_lshl_add_u64 v[18:19], v[16:17], 0, v[18:19]
	global_load_dword v71, v[18:19], off
	s_add_i32 s57, s57, 16
	v_add_u32_e32 v18, s57, v2
	v_ashrrev_i32_e32 v19, 31, v18
	v_lshlrev_b64 v[18:19], 12, v[18:19]
	v_lshl_add_u64 v[18:19], v[16:17], 0, v[18:19]
	global_load_dword v72, v[18:19], off
	v_add3_u32 v18, v2, s57, 4
	v_ashrrev_i32_e32 v19, 31, v18
	v_lshlrev_b64 v[18:19], 12, v[18:19]
	v_lshl_add_u64 v[18:19], v[16:17], 0, v[18:19]
	global_load_dword v73, v[18:19], off
	v_add3_u32 v18, v2, s57, 8
	v_ashrrev_i32_e32 v19, 31, v18
	v_lshlrev_b64 v[18:19], 12, v[18:19]
	v_lshl_add_u64 v[18:19], v[16:17], 0, v[18:19]
	global_load_dword v74, v[18:19], off
	v_add3_u32 v18, v2, s57, 12
	v_ashrrev_i32_e32 v19, 31, v18
	v_lshlrev_b64 v[18:19], 12, v[18:19]
	v_lshl_add_u64 v[18:19], v[16:17], 0, v[18:19]
	global_load_dword v75, v[18:19], off
	s_add_i32 s57, s57, 16
	v_add_u32_e32 v18, s57, v2
	v_ashrrev_i32_e32 v19, 31, v18
	v_lshlrev_b64 v[18:19], 12, v[18:19]
	v_lshl_add_u64 v[18:19], v[16:17], 0, v[18:19]
	global_load_dword v76, v[18:19], off
	v_add3_u32 v18, v2, s57, 4
	v_ashrrev_i32_e32 v19, 31, v18
	v_lshlrev_b64 v[18:19], 12, v[18:19]
	v_lshl_add_u64 v[18:19], v[16:17], 0, v[18:19]
	global_load_dword v77, v[18:19], off
	v_add3_u32 v18, v2, s57, 8
	v_ashrrev_i32_e32 v19, 31, v18
	v_lshlrev_b64 v[18:19], 12, v[18:19]
	v_lshl_add_u64 v[18:19], v[16:17], 0, v[18:19]
	global_load_dword v78, v[18:19], off
	v_add3_u32 v18, v2, s57, 12
	v_ashrrev_i32_e32 v19, 31, v18
	v_lshlrev_b64 v[18:19], 12, v[18:19]
	v_lshl_add_u64 v[18:19], v[16:17], 0, v[18:19]
	global_load_dword v79, v[18:19], off
.Ltp6_skip:
	s_waitcnt vmcnt(0)
	ds_write_b32 v13, v64
	ds_write_b32 v13, v65 offset:16
	ds_write_b32 v13, v66 offset:32
	ds_write_b32 v13, v67 offset:48
	ds_write_b32 v13, v68 offset:64
	ds_write_b32 v13, v69 offset:80
	ds_write_b32 v13, v70 offset:96
	ds_write_b32 v13, v71 offset:112
	ds_write_b32 v13, v72 offset:128
	ds_write_b32 v13, v73 offset:144
	ds_write_b32 v13, v74 offset:160
	ds_write_b32 v13, v75 offset:176
	ds_write_b32 v13, v76 offset:192
	ds_write_b32 v13, v77 offset:208
	ds_write_b32 v13, v78 offset:224
	ds_write_b32 v13, v79 offset:240
	s_movk_i32 s57, 0x40
	v_add_u32_e32 v13, 0x100, v13

; DI void transpose_mat(const float* __restrict__ src, int ld_src, bf16_t* __restrict__ dst, int N, int K, const float* __restrict__ gain, int map, float* lds, int rot) {
;     ...
; #pragma unroll 4
;     for (int r = 0; r < 16; ++r) {
;       const int kk = r * 4 + rq;
;       float v = 0.f;
;       if (sc >= 0) { v = src[(size_t)(k0 + kk) * ld_src + sc]; if (gain) v *= gain[k0 + kk]; }
;       lds[c * 65 + kk] = v;
;     }
; DI void phase_prologue(const Params& p, char* lds) {
;     ...
;     transpose_mat(p.in[23] + (size_t)L * 256 * 1024, 1024, wl + W_OB, 1024, 256, nullptr, 0, tl, rot); rot += 16 * 4;
.LBB0_149:
.LBB0_150:
	v_mov_b32_e32 v64, 0
	v_mov_b32_e32 v65, 0
	v_mov_b32_e32 v66, 0
	v_mov_b32_e32 v67, 0
	v_mov_b32_e32 v68, 0
	v_mov_b32_e32 v69, 0
	v_mov_b32_e32 v70, 0
	v_mov_b32_e32 v71, 0
	v_mov_b32_e32 v72, 0
	v_mov_b32_e32 v73, 0
	v_mov_b32_e32 v74, 0
	v_mov_b32_e32 v75, 0
	v_mov_b32_e32 v76, 0
	v_mov_b32_e32 v77, 0
	v_mov_b32_e32 v78, 0
	v_mov_b32_e32 v79, 0
	v_cndmask_b32_e64 v18, 0, 1, s[54:55]
	v_mov_b32_e32 v15, 0
	v_cmp_ne_u32_e64 s[2:3], 1, v18
	s_andn2_b64 vcc, exec, s[54:55]
	v_mov_b32_e32 v18, 0
	s_cbranch_vccnz .Ltp7_skip
	v_add_u32_e32 v18, s59, v2
	v_ashrrev_i32_e32 v19, 31, v18
	v_lshlrev_b64 v[18:19], 12, v[18:19]
	v_lshl_add_u64 v[18:19], v[16:17], 0, v[18:19]
	global_load_dword v64, v[18:19], off
	v_add3_u32 v18, v2, s59, 4
	v_ashrrev_i32_e32 v19, 31, v18
	v_lshlrev_b64 v[18:19], 12, v[18:19]
	v_lshl_add_u64 v[18:19], v[16:17], 0, v[18:19]
	global_load_dword v65, v[18:19], off
	v_add3_u32 v18, v2, s59, 8
	v_ashrrev_i32_e32 v19, 31, v18
	v_lshlrev_b64 v[18:19], 12, v[18:19]
	v_lshl_add_u64 v[18:19], v[16:17], 0, v[18:19]
	global_load_dword v66, v[18:19], off
	v_add3_u32 v18, v2, s59, 12
	v_ashrrev_i32_e32 v19, 31, v18
	v_lshlrev_b64 v[18:19], 12, v[18:19]
	v_lshl_add_u64 v[18:19], v[16:17], 0, v[18:19]
	global_load_dword v67, v[18:19], off
	s_add_i32 s59, s59, 16
	v_add_u32_e32 v18, s59, v2
	v_ashrrev_i32_e32 v19, 31, v18
	v_lshlrev_b64 v[18:19], 12, v[18:19]
	v_lshl_add_u64 v[18:19], v[16:17], 0, v[18:19]
	global_load_dword v68, v[18:19], off
	v_add3_u32 v18, v2, s59, 4
	v_ashrrev_i32_e32 v19, 31, v18
	v_lshlrev_b64 v[18:19], 12, v[18:19]
	v_lshl_add_u64 v[18:19], v[16:17], 0, v[18:19]
	global_load_dword v69, v[18:19], off
	v_add3_u32 v18, v2, s59, 8
	v_ashrrev_i32_e32 v19, 31, v18
	v_lshlrev_b64 v[18:19], 12, v[18:19]
	v_lshl_add_u64 v[18:19], v[16:17], 0, v[18:19]
	global_load_dword v70, v[18:19], off
	v_add3_u32 v18, v2, s59, 12
	v_ashrrev_i32_e32 v19, 31, v18
	v_lshlrev_b64 v[18:19], 12, v[18:19]
	v_lshl_add_u64 v[18:19], v[16:17], 0, v[18:19]
	global_load_dword v71, v[18:19], off
	s_add_i32 s59, s59, 16
	v_add_u32_e32 v18, s59, v2
	v_ashrrev_i32_e32 v19, 31, v18
	v_lshlrev_b64 v[18:19], 12, v[18:19]
	v_lshl_add_u64 v[18:19], v[16:17], 0, v[18:19]
	global_load_dword v72, v[18:19], off
	v_add3_u32 v18, v2, s59, 4
	v_ashrrev_i32_e32 v19, 31, v18
	v_lshlrev_b64 v[18:19], 12, v[18:19]
	v_lshl_add_u64 v[18:19], v[16:17], 0, v[18:19]
	global_load_dword v73, v[18:19], off
	v_add3_u32 v18, v2, s59, 8
	v_ashrrev_i32_e32 v19, 31, v18
	v_lshlrev_b64 v[18:19], 12, v[18:19]
	v_lshl_add_u64 v[18:19], v[16:17], 0, v[18:19]
	global_load_dword v74, v[18:19], off
	v_add3_u32 v18, v2, s59, 12
	v_ashrrev_i32_e32 v19, 31, v18
	v_lshlrev_b64 v[18:19], 12, v[18:19]
	v_lshl_add_u64 v[18:19], v[16:17], 0, v[18:19]
	global_load_dword v75, v[18:19], off
	s_add_i32 s59, s59, 16
	v_add_u32_e32 v18, s59, v2
	v_ashrrev_i32_e32 v19, 31, v18
	v_lshlrev_b64 v[18:19], 12, v[18:19]
	v_lshl_add_u64 v[18:19], v[16:17], 0, v[18:19]
	global_load_dword v76, v[18:19], off
	v_add3_u32 v18, v2, s59, 4
	v_ashrrev_i32_e32 v19, 31, v18
	v_lshlrev_b64 v[18:19], 12, v[18:19]
	v_lshl_add_u64 v[18:19], v[16:17], 0, v[18:19]
	global_load_dword v77, v[18:19], off
	v_add3_u32 v18, v2, s59, 8
	v_ashrrev_i32_e32 v19, 31, v18
	v_lshlrev_b64 v[18:19], 12, v[18:19]
	v_lshl_add_u64 v[18:19], v[16:17], 0, v[18:19]
	global_load_dword v78, v[18:19], off
	v_add3_u32 v18, v2, s59, 12
	v_ashrrev_i32_e32 v19, 31, v18
	v_lshlrev_b64 v[18:19], 12, v[18:19]
	v_lshl_add_u64 v[18:19], v[16:17], 0, v[18:19]
	global_load_dword v79, v[18:19], off
.Ltp7_skip:
	s_waitcnt vmcnt(0)
	ds_write_b32 v13, v64
	ds_write_b32 v13, v65 offset:16
	ds_write_b32 v13, v66 offset:32
	ds_write_b32 v13, v67 offset:48
	ds_write_b32 v13, v68 offset:64
	ds_write_b32 v13, v69 offset:80
	ds_write_b32 v13, v70 offset:96
	ds_write_b32 v13, v71 offset:112
	ds_write_b32 v13, v72 offset:128
	ds_write_b32 v13, v73 offset:144
	ds_write_b32 v13, v74 offset:160
	ds_write_b32 v13, v75 offset:176
	ds_write_b32 v13, v76 offset:192
	ds_write_b32 v13, v77 offset:208
	ds_write_b32 v13, v78 offset:224
	ds_write_b32 v13, v79 offset:240
	s_movk_i32 s59, 0x40
	v_add_u32_e32 v13, 0x100, v13

; DI void transpose_mat(const float* __restrict__ src, int ld_src, bf16_t* __restrict__ dst, int N, int K, const float* __restrict__ gain, int map, float* lds, int rot) {
;     ...
; #pragma unroll 4
;     for (int r = 0; r < 16; ++r) {
;       const int kk = r * 4 + rq;
;       float v = 0.f;
;       if (sc >= 0) { v = src[(size_t)(k0 + kk) * ld_src + sc]; if (gain) v *= gain[k0 + kk]; }
;       lds[c * 65 + kk] = v;
;     }
; DI void phase_prologue(const Params& p, char* lds) {
;     ...
;     transpose_mat(p.in[24] + (size_t)L * 512 * 1024, 1024, wl + W_OC, 1024, 512, nullptr, 0, tl, rot); rot += 16 * 8;
.LBB0_164:
.LBB0_165:
	v_mov_b32_e32 v64, 0
	v_mov_b32_e32 v65, 0
	v_mov_b32_e32 v66, 0
	v_mov_b32_e32 v67, 0
	v_mov_b32_e32 v68, 0
	v_mov_b32_e32 v69, 0
	v_mov_b32_e32 v70, 0
	v_mov_b32_e32 v71, 0
	v_mov_b32_e32 v72, 0
	v_mov_b32_e32 v73, 0
	v_mov_b32_e32 v74, 0
	v_mov_b32_e32 v75, 0
	v_mov_b32_e32 v76, 0
	v_mov_b32_e32 v77, 0
	v_mov_b32_e32 v78, 0
	v_mov_b32_e32 v79, 0
	v_cndmask_b32_e64 v18, 0, 1, s[52:53]
	v_mov_b32_e32 v15, 0
	v_cmp_ne_u32_e64 s[2:3], 1, v18
	s_andn2_b64 vcc, exec, s[52:53]
	v_mov_b32_e32 v18, 0
	s_cbranch_vccnz .Ltp8_skip
	v_add_u32_e32 v18, s57, v2
	v_ashrrev_i32_e32 v19, 31, v18
	v_lshlrev_b64 v[18:19], 12, v[18:19]
	v_lshl_add_u64 v[18:19], v[16:17], 0, v[18:19]
	global_load_dword v64, v[18:19], off
	v_add3_u32 v18, v2, s57, 4
	v_ashrrev_i32_e32 v19, 31, v18
	v_lshlrev_b64 v[18:19], 12, v[18:19]
	v_lshl_add_u64 v[18:19], v[16:17], 0, v[18:19]
	global_load_dword v65, v[18:19], off
	v_add3_u32 v18, v2, s57, 8
	v_ashrrev_i32_e32 v19, 31, v18
	v_lshlrev_b64 v[18:19], 12, v[18:19]
	v_lshl_add_u64 v[18:19], v[16:17], 0, v[18:19]
	global_load_dword v66, v[18:19], off
	v_add3_u32 v18, v2, s57, 12
	v_ashrrev_i32_e32 v19, 31, v18
	v_lshlrev_b64 v[18:19], 12, v[18:19]
	v_lshl_add_u64 v[18:19], v[16:17], 0, v[18:19]
	global_load_dword v67, v[18:19], off
	s_add_i32 s57, s57, 16
	v_add_u32_e32 v18, s57, v2
	v_ashrrev_i32_e32 v19, 31, v18
	v_lshlrev_b64 v[18:19], 12, v[18:19]
	v_lshl_add_u64 v[18:19], v[16:17], 0, v[18:19]
	global_load_dword v68, v[18:19], off
	v_add3_u32 v18, v2, s57, 4
	v_ashrrev_i32_e32 v19, 31, v18
	v_lshlrev_b64 v[18:19], 12, v[18:19]
	v_lshl_add_u64 v[18:19], v[16:17], 0, v[18:19]
	global_load_dword v69, v[18:19], off
	v_add3_u32 v18, v2, s57, 8
	v_ashrrev_i32_e32 v19, 31, v18
	v_lshlrev_b64 v[18:19], 12, v[18:19]
	v_lshl_add_u64 v[18:19], v[16:17], 0, v[18:19]
	global_load_dword v70, v[18:19], off
	v_add3_u32 v18, v2, s57, 12
	v_ashrrev_i32_e32 v19, 31, v18
	v_lshlrev_b64 v[18:19], 12, v[18:19]
	v_lshl_add_u64 v[18:19], v[16:17], 0, v[18:19]
	global_load_dword v71, v[18:19], off
	s_add_i32 s57, s57, 16
	v_add_u32_e32 v18, s57, v2
	v_ashrrev_i32_e32 v19, 31, v18
	v_lshlrev_b64 v[18:19], 12, v[18:19]
	v_lshl_add_u64 v[18:19], v[16:17], 0, v[18:19]
	global_load_dword v72, v[18:19], off
	v_add3_u32 v18, v2, s57, 4
	v_ashrrev_i32_e32 v19, 31, v18
	v_lshlrev_b64 v[18:19], 12, v[18:19]
	v_lshl_add_u64 v[18:19], v[16:17], 0, v[18:19]
	global_load_dword v73, v[18:19], off
	v_add3_u32 v18, v2, s57, 8
	v_ashrrev_i32_e32 v19, 31, v18
	v_lshlrev_b64 v[18:19], 12, v[18:19]
	v_lshl_add_u64 v[18:19], v[16:17], 0, v[18:19]
	global_load_dword v74, v[18:19], off
	v_add3_u32 v18, v2, s57, 12
	v_ashrrev_i32_e32 v19, 31, v18
	v_lshlrev_b64 v[18:19], 12, v[18:19]
	v_lshl_add_u64 v[18:19], v[16:17], 0, v[18:19]
	global_load_dword v75, v[18:19], off
	s_add_i32 s57, s57, 16
	v_add_u32_e32 v18, s57, v2
	v_ashrrev_i32_e32 v19, 31, v18
	v_lshlrev_b64 v[18:19], 12, v[18:19]
	v_lshl_add_u64 v[18:19], v[16:17], 0, v[18:19]
	global_load_dword v76, v[18:19], off
	v_add3_u32 v18, v2, s57, 4
	v_ashrrev_i32_e32 v19, 31, v18
	v_lshlrev_b64 v[18:19], 12, v[18:19]
	v_lshl_add_u64 v[18:19], v[16:17], 0, v[18:19]
	global_load_dword v77, v[18:19], off
	v_add3_u32 v18, v2, s57, 8
	v_ashrrev_i32_e32 v19, 31, v18
	v_lshlrev_b64 v[18:19], 12, v[18:19]
	v_lshl_add_u64 v[18:19], v[16:17], 0, v[18:19]
	global_load_dword v78, v[18:19], off
	v_add3_u32 v18, v2, s57, 12
	v_ashrrev_i32_e32 v19, 31, v18
	v_lshlrev_b64 v[18:19], 12, v[18:19]
	v_lshl_add_u64 v[18:19], v[16:17], 0, v[18:19]
	global_load_dword v79, v[18:19], off

; DI void transpose_mat(const float* __restrict__ src, int ld_src, bf16_t* __restrict__ dst, int N, int K, const float* __restrict__ gain, int map, float* lds, int rot) {
;     ...
; #pragma unroll 4
;     for (int r = 0; r < 16; ++r) {
;       const int kk = r * 4 + rq;
;       float v = 0.f;
;       if (sc >= 0) { v = src[(size_t)(k0 + kk) * ld_src + sc]; if (gain) v *= gain[k0 + kk]; }
;       lds[c * 65 + kk] = v;
;     }
; DI void phase_prologue(const Params& p, char* lds) {
;     ...
;     transpose_mat(p.in[27] + (size_t)L * 1024 * 5632, 5632, wl + W_FFN2_IN, 5632, 1024, p.in[26] + L * 1024, 1, tl, rot); rot += 88 * 16;
.LBB0_194:
.LBB0_195:
	v_mov_b32_e32 v64, 0
	v_mov_b32_e32 v65, 0
	v_mov_b32_e32 v66, 0
	v_mov_b32_e32 v67, 0
	v_mov_b32_e32 v68, 0
	v_mov_b32_e32 v69, 0
	v_mov_b32_e32 v70, 0
	v_mov_b32_e32 v71, 0
	v_mov_b32_e32 v72, 0
	v_mov_b32_e32 v73, 0
	v_mov_b32_e32 v74, 0
	v_mov_b32_e32 v75, 0
	v_mov_b32_e32 v76, 0
	v_mov_b32_e32 v77, 0
	v_mov_b32_e32 v78, 0
	v_mov_b32_e32 v79, 0
	v_cndmask_b32_e64 v22, 0, 1, s[28:29]
	v_mov_b32_e32 v15, 0
	v_cmp_ne_u32_e64 s[4:5], 1, v22
	v_mov_b32_e32 v24, 0
	s_and_saveexec_b64 s[58:59], s[2:3]
	s_cbranch_execz .Ltp10_skip
	v_add_u32_e32 v22, s97, v2
	v_mad_i64_i32 v[30:31], vcc, v22, s78, v[18:19]
	global_load_dword v64, v[30:31], off
	s_and_b64 vcc, exec, s[4:5]
	s_cbranch_vccnz .Ltp10_ng0
	v_ashrrev_i32_e32 v23, 31, v22
	v_lshl_add_u64 v[22:23], v[22:23], 2, s[54:55]
	global_load_dword v80, v[22:23], off
.Ltp10_ng0:
	v_add3_u32 v15, v2, s97, 4
	v_mad_i64_i32 v[22:23], vcc, v15, s78, v[18:19]
	global_load_dword v65, v[22:23], off
	s_and_b64 vcc, exec, s[4:5]
	s_cbranch_vccnz .Ltp10_ng1
	global_load_dword v81, v[20:21], off offset:-16
.Ltp10_ng1:
	v_add3_u32 v22, v2, s97, 8
	v_mad_i64_i32 v[22:23], vcc, v22, s78, v[18:19]
	global_load_dword v66, v[22:23], off
	s_and_b64 vcc, exec, s[4:5]
	s_cbranch_vccnz .Ltp10_ng2
	global_load_dword v82, v[20:21], off
.Ltp10_ng2:
	v_add3_u32 v15, v2, s97, 12
	v_mad_i64_i32 v[22:23], vcc, v15, s78, v[18:19]
	global_load_dword v67, v[22:23], off
	s_and_b64 vcc, exec, s[4:5]
	s_cbranch_vccnz .Ltp10_ng3
	global_load_dword v83, v[20:21], off offset:16
.Ltp10_ng3:
	s_add_i32 s97, s97, 16
	v_lshl_add_u64 v[20:21], v[20:21], 0, 64
	v_add_u32_e32 v22, s97, v2
	v_mad_i64_i32 v[30:31], vcc, v22, s78, v[18:19]
	global_load_dword v68, v[30:31], off
	s_and_b64 vcc, exec, s[4:5]
	s_cbranch_vccnz .Ltp10_ng4
	v_ashrrev_i32_e32 v23, 31, v22
	v_lshl_add_u64 v[22:23], v[22:23], 2, s[54:55]
	global_load_dword v84, v[22:23], off
.Ltp10_ng4:
	v_add3_u32 v15, v2, s97, 4
	v_mad_i64_i32 v[22:23], vcc, v15, s78, v[18:19]
	global_load_dword v69, v[22:23], off
	s_and_b64 vcc, exec, s[4:5]
	s_cbranch_vccnz .Ltp10_ng5
	global_load_dword v85, v[20:21], off offset:-16
.Ltp10_ng5:
	v_add3_u32 v22, v2, s97, 8
	v_mad_i64_i32 v[22:23], vcc, v22, s78, v[18:19]
	global_load_dword v70, v[22:23], off
	s_and_b64 vcc, exec, s[4:5]
	s_cbranch_vccnz .Ltp10_ng6
	global_load_dword v86, v[20:21], off
.Ltp10_ng6:
	v_add3_u32 v15, v2, s97, 12
	v_mad_i64_i32 v[22:23], vcc, v15, s78, v[18:19]
	global_load_dword v71, v[22:23], off
	s_and_b64 vcc, exec, s[4:5]
	s_cbranch_vccnz .Ltp10_ng7
	global_load_dword v87, v[20:21], off offset:16
.Ltp10_ng7:
	s_add_i32 s97, s97, 16
	v_lshl_add_u64 v[20:21], v[20:21], 0, 64
	v_add_u32_e32 v22, s97, v2
	v_mad_i64_i32 v[30:31], vcc, v22, s78, v[18:19]
	global_load_dword v72, v[30:31], off
	s_and_b64 vcc, exec, s[4:5]
	s_cbranch_vccnz .Ltp10_ng8
	v_ashrrev_i32_e32 v23, 31, v22
	v_lshl_add_u64 v[22:23], v[22:23], 2, s[54:55]
	global_load_dword v88, v[22:23], off
.Ltp10_ng8:
	v_add3_u32 v15, v2, s97, 4
	v_mad_i64_i32 v[22:23], vcc, v15, s78, v[18:19]
	global_load_dword v73, v[22:23], off
	s_and_b64 vcc, exec, s[4:5]
	s_cbranch_vccnz .Ltp10_ng9
	global_load_dword v89, v[20:21], off offset:-16
.Ltp10_ng9:
	v_add3_u32 v22, v2, s97, 8
	v_mad_i64_i32 v[22:23], vcc, v22, s78, v[18:19]
	global_load_dword v74, v[22:23], off
	s_and_b64 vcc, exec, s[4:5]
	s_cbranch_vccnz .Ltp10_ng10
	global_load_dword v90, v[20:21], off
.Ltp10_ng10:
	v_add3_u32 v15, v2, s97, 12
	v_mad_i64_i32 v[22:23], vcc, v15, s78, v[18:19]
	global_load_dword v75, v[22:23], off
	s_and_b64 vcc, exec, s[4:5]
	s_cbranch_vccnz .Ltp10_ng11
	global_load_dword v91, v[20:21], off offset:16
.Ltp10_ng11:
	s_add_i32 s97, s97, 16
	v_lshl_add_u64 v[20:21], v[20:21], 0, 64
	v_add_u32_e32 v22, s97, v2
	v_mad_i64_i32 v[30:31], vcc, v22, s78, v[18:19]
	global_load_dword v76, v[30:31], off
	s_and_b64 vcc, exec, s[4:5]
	s_cbranch_vccnz .Ltp10_ng12
	v_ashrrev_i32_e32 v23, 31, v22
	v_lshl_add_u64 v[22:23], v[22:23], 2, s[54:55]
	global_load_dword v92, v[22:23], off
.Ltp10_ng12:
	v_add3_u32 v15, v2, s97, 4
	v_mad_i64_i32 v[22:23], vcc, v15, s78, v[18:19]
	global_load_dword v77, v[22:23], off
	s_and_b64 vcc, exec, s[4:5]
	s_cbranch_vccnz .Ltp10_ng13
	global_load_dword v93, v[20:21], off offset:-16
.Ltp10_ng13:
	v_add3_u32 v22, v2, s97, 8
	v_mad_i64_i32 v[22:23], vcc, v22, s78, v[18:19]
	global_load_dword v78, v[22:23], off
	s_and_b64 vcc, exec, s[4:5]
	s_cbranch_vccnz .Ltp10_ng14
	global_load_dword v94, v[20:21], off
.Ltp10_ng14:
	v_add3_u32 v15, v2, s97, 12
	v_mad_i64_i32 v[22:23], vcc, v15, s78, v[18:19]
	global_load_dword v79, v[22:23], off
	s_and_b64 vcc, exec, s[4:5]
	s_cbranch_vccnz .Ltp10_ng15
	global_load_dword v95, v[20:21], off offset:16

; DI void transpose_mat(const float* __restrict__ src, int ld_src, bf16_t* __restrict__ dst, int N, int K, const float* __restrict__ gain, int map, float* lds, int rot) {
;     ...
; #pragma unroll 4
;     for (int r = 0; r < 16; ++r) {
;       const int kk = r * 4 + rq;
;       float v = 0.f;
;       if (sc >= 0) { v = src[(size_t)(k0 + kk) * ld_src + sc]; if (gain) v *= gain[k0 + kk]; }
;       lds[c * 65 + kk] = v;
;     }
; DI void phase_prologue(const Params& p, char* lds) {
;     ...
;     transpose_mat(p.in[28] + (size_t)L * 2816 * 1024, 1024, wl + W_FFN2_OUT, 1024, 2816, nullptr, 0, tl, rot); rot += 16 * 44;
.LBB0_213:
.LBB0_214:
	v_mov_b32_e32 v64, 0
	v_mov_b32_e32 v65, 0
	v_mov_b32_e32 v66, 0
	v_mov_b32_e32 v67, 0
	v_mov_b32_e32 v68, 0
	v_mov_b32_e32 v69, 0
	v_mov_b32_e32 v70, 0
	v_mov_b32_e32 v71, 0
	v_mov_b32_e32 v72, 0
	v_mov_b32_e32 v73, 0
	v_mov_b32_e32 v74, 0
	v_mov_b32_e32 v75, 0
	v_mov_b32_e32 v76, 0
	v_mov_b32_e32 v77, 0
	v_mov_b32_e32 v78, 0
	v_mov_b32_e32 v79, 0
	v_cndmask_b32_e64 v18, 0, 1, s[44:45]
	v_mov_b32_e32 v15, 0
	v_cmp_ne_u32_e64 s[2:3], 1, v18
	s_andn2_b64 vcc, exec, s[44:45]
	v_mov_b32_e32 v18, 0
	s_cbranch_vccnz .Ltp11_skip
	v_add_u32_e32 v18, s55, v2
	v_ashrrev_i32_e32 v19, 31, v18
	v_lshlrev_b64 v[18:19], 12, v[18:19]
	v_lshl_add_u64 v[18:19], v[16:17], 0, v[18:19]
	global_load_dword v64, v[18:19], off
	v_add3_u32 v18, v2, s55, 4
	v_ashrrev_i32_e32 v19, 31, v18
	v_lshlrev_b64 v[18:19], 12, v[18:19]
	v_lshl_add_u64 v[18:19], v[16:17], 0, v[18:19]
	global_load_dword v65, v[18:19], off
	v_add3_u32 v18, v2, s55, 8
	v_ashrrev_i32_e32 v19, 31, v18
	v_lshlrev_b64 v[18:19], 12, v[18:19]
	v_lshl_add_u64 v[18:19], v[16:17], 0, v[18:19]
	global_load_dword v66, v[18:19], off
	v_add3_u32 v18, v2, s55, 12
	v_ashrrev_i32_e32 v19, 31, v18
	v_lshlrev_b64 v[18:19], 12, v[18:19]
	v_lshl_add_u64 v[18:19], v[16:17], 0, v[18:19]
	global_load_dword v67, v[18:19], off
	s_add_i32 s55, s55, 16
	v_add_u32_e32 v18, s55, v2
	v_ashrrev_i32_e32 v19, 31, v18
	v_lshlrev_b64 v[18:19], 12, v[18:19]
	v_lshl_add_u64 v[18:19], v[16:17], 0, v[18:19]
	global_load_dword v68, v[18:19], off
	v_add3_u32 v18, v2, s55, 4
	v_ashrrev_i32_e32 v19, 31, v18
	v_lshlrev_b64 v[18:19], 12, v[18:19]
	v_lshl_add_u64 v[18:19], v[16:17], 0, v[18:19]
	global_load_dword v69, v[18:19], off
	v_add3_u32 v18, v2, s55, 8
	v_ashrrev_i32_e32 v19, 31, v18
	v_lshlrev_b64 v[18:19], 12, v[18:19]
	v_lshl_add_u64 v[18:19], v[16:17], 0, v[18:19]
	global_load_dword v70, v[18:19], off
	v_add3_u32 v18, v2, s55, 12
	v_ashrrev_i32_e32 v19, 31, v18
	v_lshlrev_b64 v[18:19], 12, v[18:19]
	v_lshl_add_u64 v[18:19], v[16:17], 0, v[18:19]
	global_load_dword v71, v[18:19], off
	s_add_i32 s55, s55, 16
	v_add_u32_e32 v18, s55, v2
	v_ashrrev_i32_e32 v19, 31, v18
	v_lshlrev_b64 v[18:19], 12, v[18:19]
	v_lshl_add_u64 v[18:19], v[16:17], 0, v[18:19]
	global_load_dword v72, v[18:19], off
	v_add3_u32 v18, v2, s55, 4
	v_ashrrev_i32_e32 v19, 31, v18
	v_lshlrev_b64 v[18:19], 12, v[18:19]
	v_lshl_add_u64 v[18:19], v[16:17], 0, v[18:19]
	global_load_dword v73, v[18:19], off
	v_add3_u32 v18, v2, s55, 8
	v_ashrrev_i32_e32 v19, 31, v18
	v_lshlrev_b64 v[18:19], 12, v[18:19]
	v_lshl_add_u64 v[18:19], v[16:17], 0, v[18:19]
	global_load_dword v74, v[18:19], off
	v_add3_u32 v18, v2, s55, 12
	v_ashrrev_i32_e32 v19, 31, v18
	v_lshlrev_b64 v[18:19], 12, v[18:19]
	v_lshl_add_u64 v[18:19], v[16:17], 0, v[18:19]
	global_load_dword v75, v[18:19], off
	s_add_i32 s55, s55, 16
	v_add_u32_e32 v18, s55, v2
	v_ashrrev_i32_e32 v19, 31, v18
	v_lshlrev_b64 v[18:19], 12, v[18:19]
	v_lshl_add_u64 v[18:19], v[16:17], 0, v[18:19]
	global_load_dword v76, v[18:19], off
	v_add3_u32 v18, v2, s55, 4
	v_ashrrev_i32_e32 v19, 31, v18
	v_lshlrev_b64 v[18:19], 12, v[18:19]
	v_lshl_add_u64 v[18:19], v[16:17], 0, v[18:19]
	global_load_dword v77, v[18:19], off
	v_add3_u32 v18, v2, s55, 8
	v_ashrrev_i32_e32 v19, 31, v18
	v_lshlrev_b64 v[18:19], 12, v[18:19]
	v_lshl_add_u64 v[18:19], v[16:17], 0, v[18:19]
	global_load_dword v78, v[18:19], off
	v_add3_u32 v18, v2, s55, 12
	v_ashrrev_i32_e32 v19, 31, v18
	v_lshlrev_b64 v[18:19], 12, v[18:19]
	v_lshl_add_u64 v[18:19], v[16:17], 0, v[18:19]
	global_load_dword v79, v[18:19], off

; DI void transpose_mat(const float* __restrict__ src, int ld_src, bf16_t* __restrict__ dst, int N, int K, const float* __restrict__ gain, int map, float* lds, int rot) {
;     ...
; #pragma unroll 4
;     for (int r = 0; r < 16; ++r) {
;       const int kk = r * 4 + rq;
;       float v = 0.f;
;       if (sc >= 0) { v = src[(size_t)(k0 + kk) * ld_src + sc]; if (gain) v *= gain[k0 + kk]; }
;       lds[c * 65 + kk] = v;
;     }
.LBB0_228:
.LBB0_229:
	v_mov_b32_e32 v64, 0
	v_mov_b32_e32 v65, 0
	v_mov_b32_e32 v66, 0
	v_mov_b32_e32 v67, 0
	v_mov_b32_e32 v68, 0
	v_mov_b32_e32 v69, 0
	v_mov_b32_e32 v70, 0
	v_mov_b32_e32 v71, 0
	v_mov_b32_e32 v72, 0
	v_mov_b32_e32 v73, 0
	v_mov_b32_e32 v74, 0
	v_mov_b32_e32 v75, 0
	v_mov_b32_e32 v76, 0
	v_mov_b32_e32 v77, 0
	v_mov_b32_e32 v78, 0
	v_mov_b32_e32 v79, 0
	v_cndmask_b32_e64 v22, 0, 1, s[52:53]
	v_cmp_ne_u32_e64 s[4:5], 1, v22
	v_cndmask_b32_e64 v22, 0, 1, s[30:31]
	v_mov_b32_e32 v15, 0
	s_andn2_b64 vcc, exec, s[52:53]
	v_cmp_ne_u32_e64 s[2:3], 1, v22
	v_mov_b32_e32 v24, 0
	s_cbranch_vccnz .Ltp12_skip
	v_add_u32_e32 v22, s57, v2
	v_ashrrev_i32_e32 v23, 31, v22
	v_lshlrev_b64 v[30:31], 12, v[22:23]
	v_lshl_add_u64 v[30:31], v[18:19], 0, v[30:31]
	global_load_dword v64, v[30:31], off
	s_and_b64 vcc, exec, s[2:3]
	s_cbranch_vccnz .Ltp12_ng0
	v_lshl_add_u64 v[22:23], v[22:23], 2, s[46:47]
	global_load_dword v80, v[22:23], off
.Ltp12_ng0:
	v_add3_u32 v22, v2, s57, 4
	v_ashrrev_i32_e32 v23, 31, v22
	v_lshlrev_b64 v[22:23], 12, v[22:23]
	v_lshl_add_u64 v[22:23], v[18:19], 0, v[22:23]
	global_load_dword v65, v[22:23], off
	s_and_b64 vcc, exec, s[2:3]
	s_cbranch_vccnz .Ltp12_ng1
	global_load_dword v81, v[20:21], off offset:-16
.Ltp12_ng1:
	v_add3_u32 v22, v2, s57, 8
	v_ashrrev_i32_e32 v23, 31, v22
	v_lshlrev_b64 v[22:23], 12, v[22:23]
	v_lshl_add_u64 v[22:23], v[18:19], 0, v[22:23]
	global_load_dword v66, v[22:23], off
	s_and_b64 vcc, exec, s[2:3]
	s_cbranch_vccnz .Ltp12_ng2
	global_load_dword v82, v[20:21], off
.Ltp12_ng2:
	v_add3_u32 v22, v2, s57, 12
	v_ashrrev_i32_e32 v23, 31, v22
	v_lshlrev_b64 v[22:23], 12, v[22:23]
	v_lshl_add_u64 v[22:23], v[18:19], 0, v[22:23]
	global_load_dword v67, v[22:23], off
	s_and_b64 vcc, exec, s[2:3]
	s_cbranch_vccnz .Ltp12_ng3
	global_load_dword v83, v[20:21], off offset:16
.Ltp12_ng3:
	s_add_i32 s57, s57, 16
	v_lshl_add_u64 v[20:21], v[20:21], 0, 64
	v_add_u32_e32 v22, s57, v2
	v_ashrrev_i32_e32 v23, 31, v22
	v_lshlrev_b64 v[30:31], 12, v[22:23]
	v_lshl_add_u64 v[30:31], v[18:19], 0, v[30:31]
	global_load_dword v68, v[30:31], off
	s_and_b64 vcc, exec, s[2:3]
	s_cbranch_vccnz .Ltp12_ng4
	v_lshl_add_u64 v[22:23], v[22:23], 2, s[46:47]
	global_load_dword v84, v[22:23], off
.Ltp12_ng4:
	v_add3_u32 v22, v2, s57, 4
	v_ashrrev_i32_e32 v23, 31, v22
	v_lshlrev_b64 v[22:23], 12, v[22:23]
	v_lshl_add_u64 v[22:23], v[18:19], 0, v[22:23]
	global_load_dword v69, v[22:23], off
	s_and_b64 vcc, exec, s[2:3]
	s_cbranch_vccnz .Ltp12_ng5
	global_load_dword v85, v[20:21], off offset:-16
.Ltp12_ng5:
	v_add3_u32 v22, v2, s57, 8
	v_ashrrev_i32_e32 v23, 31, v22
	v_lshlrev_b64 v[22:23], 12, v[22:23]
	v_lshl_add_u64 v[22:23], v[18:19], 0, v[22:23]
	global_load_dword v70, v[22:23], off
	s_and_b64 vcc, exec, s[2:3]
	s_cbranch_vccnz .Ltp12_ng6
	global_load_dword v86, v[20:21], off
.Ltp12_ng6:
	v_add3_u32 v22, v2, s57, 12
	v_ashrrev_i32_e32 v23, 31, v22
	v_lshlrev_b64 v[22:23], 12, v[22:23]
	v_lshl_add_u64 v[22:23], v[18:19], 0, v[22:23]
	global_load_dword v71, v[22:23], off
	s_and_b64 vcc, exec, s[2:3]
	s_cbranch_vccnz .Ltp12_ng7
	global_load_dword v87, v[20:21], off offset:16
.Ltp12_ng7:
	s_add_i32 s57, s57, 16
	v_lshl_add_u64 v[20:21], v[20:21], 0, 64
	v_add_u32_e32 v22, s57, v2
	v_ashrrev_i32_e32 v23, 31, v22
	v_lshlrev_b64 v[30:31], 12, v[22:23]
	v_lshl_add_u64 v[30:31], v[18:19], 0, v[30:31]
	global_load_dword v72, v[30:31], off
	s_and_b64 vcc, exec, s[2:3]
	s_cbranch_vccnz .Ltp12_ng8
	v_lshl_add_u64 v[22:23], v[22:23], 2, s[46:47]
	global_load_dword v88, v[22:23], off
.Ltp12_ng8:
	v_add3_u32 v22, v2, s57, 4
	v_ashrrev_i32_e32 v23, 31, v22
	v_lshlrev_b64 v[22:23], 12, v[22:23]
	v_lshl_add_u64 v[22:23], v[18:19], 0, v[22:23]
	global_load_dword v73, v[22:23], off
	s_and_b64 vcc, exec, s[2:3]
	s_cbranch_vccnz .Ltp12_ng9
	global_load_dword v89, v[20:21], off offset:-16
.Ltp12_ng9:
	v_add3_u32 v22, v2, s57, 8
	v_ashrrev_i32_e32 v23, 31, v22
	v_lshlrev_b64 v[22:23], 12, v[22:23]
	v_lshl_add_u64 v[22:23], v[18:19], 0, v[22:23]
	global_load_dword v74, v[22:23], off
	s_and_b64 vcc, exec, s[2:3]
	s_cbranch_vccnz .Ltp12_ng10
	global_load_dword v90, v[20:21], off
.Ltp12_ng10:
	v_add3_u32 v22, v2, s57, 12
	v_ashrrev_i32_e32 v23, 31, v22
	v_lshlrev_b64 v[22:23], 12, v[22:23]
	v_lshl_add_u64 v[22:23], v[18:19], 0, v[22:23]
	global_load_dword v75, v[22:23], off
	s_and_b64 vcc, exec, s[2:3]
	s_cbranch_vccnz .Ltp12_ng11
	global_load_dword v91, v[20:21], off offset:16
.Ltp12_ng11:
	s_add_i32 s57, s57, 16
	v_lshl_add_u64 v[20:21], v[20:21], 0, 64
	v_add_u32_e32 v22, s57, v2
	v_ashrrev_i32_e32 v23, 31, v22
	v_lshlrev_b64 v[30:31], 12, v[22:23]
	v_lshl_add_u64 v[30:31], v[18:19], 0, v[30:31]
	global_load_dword v76, v[30:31], off
	s_and_b64 vcc, exec, s[2:3]
	s_cbranch_vccnz .Ltp12_ng12
	v_lshl_add_u64 v[22:23], v[22:23], 2, s[46:47]
	global_load_dword v92, v[22:23], off
.Ltp12_ng12:
	v_add3_u32 v22, v2, s57, 4
	v_ashrrev_i32_e32 v23, 31, v22
	v_lshlrev_b64 v[22:23], 12, v[22:23]
	v_lshl_add_u64 v[22:23], v[18:19], 0, v[22:23]
	global_load_dword v77, v[22:23], off
	s_and_b64 vcc, exec, s[2:3]
	s_cbranch_vccnz .Ltp12_ng13
	global_load_dword v93, v[20:21], off offset:-16
.Ltp12_ng13:
	v_add3_u32 v22, v2, s57, 8
	v_ashrrev_i32_e32 v23, 31, v22
	v_lshlrev_b64 v[22:23], 12, v[22:23]
	v_lshl_add_u64 v[22:23], v[18:19], 0, v[22:23]
	global_load_dword v78, v[22:23], off
	s_and_b64 vcc, exec, s[2:3]
	s_cbranch_vccnz .Ltp12_ng14
	global_load_dword v94, v[20:21], off
.Ltp12_ng14:
	v_add3_u32 v22, v2, s57, 12
	v_ashrrev_i32_e32 v23, 31, v22
	v_lshlrev_b64 v[22:23], 12, v[22:23]
	v_lshl_add_u64 v[22:23], v[18:19], 0, v[22:23]
	global_load_dword v79, v[22:23], off
	s_and_b64 vcc, exec, s[2:3]
	s_cbranch_vccnz .Ltp12_ng15
	global_load_dword v95, v[20:21], off offset:16

; DI void transpose_mat(const float* __restrict__ src, int ld_src, bf16_t* __restrict__ dst, int N, int K, const float* __restrict__ gain, int map, float* lds, int rot) {
;     ...
; #pragma unroll 4
;     for (int r = 0; r < 16; ++r) {
;       const int kk = r * 4 + rq;
;       float v = 0.f;
;       if (sc >= 0) { v = src[(size_t)(k0 + kk) * ld_src + sc]; if (gain) v *= gain[k0 + kk]; }
;       lds[c * 65 + kk] = v;
;     }
.Ltp12_nomul:
.Ltp12_skip:
	s_waitcnt vmcnt(0)
	ds_write_b32 v13, v64
	ds_write_b32 v13, v65 offset:16
	ds_write_b32 v13, v66 offset:32
	ds_write_b32 v13, v67 offset:48
	ds_write_b32 v13, v68 offset:64
	ds_write_b32 v13, v69 offset:80
	ds_write_b32 v13, v70 offset:96
	ds_write_b32 v13, v71 offset:112
	ds_write_b32 v13, v72 offset:128
	ds_write_b32 v13, v73 offset:144
	ds_write_b32 v13, v74 offset:160
	ds_write_b32 v13, v75 offset:176
	ds_write_b32 v13, v76 offset:192
	ds_write_b32 v13, v77 offset:208
	ds_write_b32 v13, v78 offset:224
	ds_write_b32 v13, v79 offset:240
	s_movk_i32 s57, 0x40
	v_lshl_add_u64 v[20:21], v[20:21], 0, 64
	v_add_u32_e32 v13, 0x100, v13

; DI void transpose_mat(const float* __restrict__ src, int ld_src, bf16_t* __restrict__ dst, int N, int K, const float* __restrict__ gain, int map, float* lds, int rot) {
;     ...
; #pragma unroll 4
;     for (int r = 0; r < 16; ++r) {
;       const int kk = r * 4 + rq;
;       float v = 0.f;
;       if (sc >= 0) { v = src[(size_t)(k0 + kk) * ld_src + sc]; if (gain) v *= gain[k0 + kk]; }
;       lds[c * 65 + kk] = v;
;     }
.LBB0_247:
.LBB0_248:
	v_mov_b32_e32 v64, 0
	v_mov_b32_e32 v65, 0
	v_mov_b32_e32 v66, 0
	v_mov_b32_e32 v67, 0
	v_mov_b32_e32 v68, 0
	v_mov_b32_e32 v69, 0
	v_mov_b32_e32 v70, 0
	v_mov_b32_e32 v71, 0
	v_mov_b32_e32 v72, 0
	v_mov_b32_e32 v73, 0
	v_mov_b32_e32 v74, 0
	v_mov_b32_e32 v75, 0
	v_mov_b32_e32 v76, 0
	v_mov_b32_e32 v77, 0
	v_mov_b32_e32 v78, 0
	v_mov_b32_e32 v79, 0
	v_cndmask_b32_e64 v18, 0, 1, s[42:43]
	v_mov_b32_e32 v15, 0
	v_cmp_ne_u32_e64 s[2:3], 1, v18
	s_andn2_b64 vcc, exec, s[42:43]
	v_mov_b32_e32 v18, 0
	s_cbranch_vccnz .Ltp13_skip
	v_add_u32_e32 v18, s46, v2
	v_ashrrev_i32_e32 v19, 31, v18
	v_lshlrev_b64 v[18:19], 12, v[18:19]
	v_lshl_add_u64 v[18:19], v[16:17], 0, v[18:19]
	global_load_dword v64, v[18:19], off
	v_add3_u32 v18, v2, s46, 4
	v_ashrrev_i32_e32 v19, 31, v18
	v_lshlrev_b64 v[18:19], 12, v[18:19]
	v_lshl_add_u64 v[18:19], v[16:17], 0, v[18:19]
	global_load_dword v65, v[18:19], off
	v_add3_u32 v18, v2, s46, 8
	v_ashrrev_i32_e32 v19, 31, v18
	v_lshlrev_b64 v[18:19], 12, v[18:19]
	v_lshl_add_u64 v[18:19], v[16:17], 0, v[18:19]
	global_load_dword v66, v[18:19], off
	v_add3_u32 v18, v2, s46, 12
	v_ashrrev_i32_e32 v19, 31, v18
	v_lshlrev_b64 v[18:19], 12, v[18:19]
	v_lshl_add_u64 v[18:19], v[16:17], 0, v[18:19]
	global_load_dword v67, v[18:19], off
	s_add_i32 s46, s46, 16
	v_add_u32_e32 v18, s46, v2
	v_ashrrev_i32_e32 v19, 31, v18
	v_lshlrev_b64 v[18:19], 12, v[18:19]
	v_lshl_add_u64 v[18:19], v[16:17], 0, v[18:19]
	global_load_dword v68, v[18:19], off
	v_add3_u32 v18, v2, s46, 4
	v_ashrrev_i32_e32 v19, 31, v18
	v_lshlrev_b64 v[18:19], 12, v[18:19]
	v_lshl_add_u64 v[18:19], v[16:17], 0, v[18:19]
	global_load_dword v69, v[18:19], off
	v_add3_u32 v18, v2, s46, 8
	v_ashrrev_i32_e32 v19, 31, v18
	v_lshlrev_b64 v[18:19], 12, v[18:19]
	v_lshl_add_u64 v[18:19], v[16:17], 0, v[18:19]
	global_load_dword v70, v[18:19], off
	v_add3_u32 v18, v2, s46, 12
	v_ashrrev_i32_e32 v19, 31, v18
	v_lshlrev_b64 v[18:19], 12, v[18:19]
	v_lshl_add_u64 v[18:19], v[16:17], 0, v[18:19]
	global_load_dword v71, v[18:19], off
	s_add_i32 s46, s46, 16
	v_add_u32_e32 v18, s46, v2
	v_ashrrev_i32_e32 v19, 31, v18
	v_lshlrev_b64 v[18:19], 12, v[18:19]
	v_lshl_add_u64 v[18:19], v[16:17], 0, v[18:19]
	global_load_dword v72, v[18:19], off
	v_add3_u32 v18, v2, s46, 4
	v_ashrrev_i32_e32 v19, 31, v18
	v_lshlrev_b64 v[18:19], 12, v[18:19]
	v_lshl_add_u64 v[18:19], v[16:17], 0, v[18:19]
	global_load_dword v73, v[18:19], off
	v_add3_u32 v18, v2, s46, 8
	v_ashrrev_i32_e32 v19, 31, v18
	v_lshlrev_b64 v[18:19], 12, v[18:19]
	v_lshl_add_u64 v[18:19], v[16:17], 0, v[18:19]
	global_load_dword v74, v[18:19], off
	v_add3_u32 v18, v2, s46, 12
	v_ashrrev_i32_e32 v19, 31, v18
	v_lshlrev_b64 v[18:19], 12, v[18:19]
	v_lshl_add_u64 v[18:19], v[16:17], 0, v[18:19]
	global_load_dword v75, v[18:19], off
	s_add_i32 s46, s46, 16
	v_add_u32_e32 v18, s46, v2
	v_ashrrev_i32_e32 v19, 31, v18
	v_lshlrev_b64 v[18:19], 12, v[18:19]
	v_lshl_add_u64 v[18:19], v[16:17], 0, v[18:19]
	global_load_dword v76, v[18:19], off
	v_add3_u32 v18, v2, s46, 4
	v_ashrrev_i32_e32 v19, 31, v18
	v_lshlrev_b64 v[18:19], 12, v[18:19]
	v_lshl_add_u64 v[18:19], v[16:17], 0, v[18:19]
	global_load_dword v77, v[18:19], off
	v_add3_u32 v18, v2, s46, 8
	v_ashrrev_i32_e32 v19, 31, v18
	v_lshlrev_b64 v[18:19], 12, v[18:19]
	v_lshl_add_u64 v[18:19], v[16:17], 0, v[18:19]
	global_load_dword v78, v[18:19], off
	v_add3_u32 v18, v2, s46, 12
	v_ashrrev_i32_e32 v19, 31, v18
	v_lshlrev_b64 v[18:19], 12, v[18:19]
	v_lshl_add_u64 v[18:19], v[16:17], 0, v[18:19]
	global_load_dword v79, v[18:19], off
.Ltp13_skip:
	s_waitcnt vmcnt(0)
	ds_write_b32 v13, v64
	ds_write_b32 v13, v65 offset:16
	ds_write_b32 v13, v66 offset:32
	ds_write_b32 v13, v67 offset:48
	ds_write_b32 v13, v68 offset:64
	ds_write_b32 v13, v69 offset:80
	ds_write_b32 v13, v70 offset:96
	ds_write_b32 v13, v71 offset:112
	ds_write_b32 v13, v72 offset:128
	ds_write_b32 v13, v73 offset:144
	ds_write_b32 v13, v74 offset:160
	ds_write_b32 v13, v75 offset:176
	ds_write_b32 v13, v76 offset:192
	ds_write_b32 v13, v77 offset:208
	ds_write_b32 v13, v78 offset:224
	ds_write_b32 v13, v79 offset:240
	s_movk_i32 s46, 0x40
	v_add_u32_e32 v13, 0x100, v13

; #define GSYNC() do { xcd_barrier(xb); xcd_barrier(xb); } while (0)
; #define GSYNC() xcd_barrier(xb)
; #define REP(n) for (int rep_ = 0; rep_ < ((DUP == (n) || (DUP == 100 && ((n) == 2 || (n) == 10))) ? 2 : 1); ++rep_)
; __global__ void __launch_bounds__(NTHREADS, 2) mega_kernel(Params p) {
;     ...
;   for (int chunk = 0; chunk < 3; ++chunk) {
;     Ctx c;
;     c.p = &p; c.chunk = chunk; c.layer = 0; c.ws = p.ws; c.lds = lds;
;     c.S = chunk == 0 ? 4096 : 16384; c.sshift = chunk == 0 ? 12 : 14;
;     c.x = p.out + (size_t)chunk * TC * DM;
;     c.xin = chunk == 0 ? p.in[0] : p.in[1] + (size_t)(chunk - 1) * TC * DM;
;     c.pe0 = chunk == 0 ? p.in[2] : p.in[3] + (size_t)(chunk - 1) * TC * 256;
;     c.pe_ls = chunk == 0 ? (size_t)TC * 256 : (size_t)2 * TC * 256;
;     REP(1) { if (PH(1)) phase_init(c); GSYNC(); }
; #pragma unroll 1
;     for (int layer = 0; layer < 2; ++layer) {
;       c.layer = layer;
.LBB0_285:
	s_or_b64 exec, exec, s[0:1]
	s_add_u32 s0, s94, 0x7214000
	s_addc_u32 s1, s95, 0
	v_writelane_b32 v252, s0, 7
	s_lshl_b32 s4, s34, 2
	s_mov_b64 s[78:79], src_shared_base
	v_writelane_b32 v252, s1, 8
	s_lshl_b32 s1, s64, 2
	s_add_u32 s24, s94, 0x7415900
	s_addc_u32 s25, s95, 0
	v_writelane_b32 v252, s1, 9
	s_add_u32 s1, s94, 0x7535900
	v_writelane_b32 v252, s1, 10
	s_addc_u32 s1, s95, 0
	s_mul_i32 s0, s35, s34
	s_add_u32 s2, s94, 0xb935900
	v_writelane_b32 v252, s1, 11
	s_addc_u32 s3, s95, 0
	s_mul_i32 s0, s0, s65
	v_writelane_b32 v252, s2, 12
	v_writelane_b32 v251, s0, 52
	s_add_u32 s0, s94, 0x7210200
	v_writelane_b32 v252, s3, 13
	s_addc_u32 s1, s95, 0
	v_writelane_b32 v252, s0, 14
	v_cvt_f32_u32_e32 v0, s82
	s_mov_b32 s73, 0
	v_writelane_b32 v252, s1, 15
	s_add_u32 s0, s94, 0x7210400
	s_addc_u32 s1, s95, 0
	v_writelane_b32 v251, s0, 0
	v_rcp_iflag_f32_e32 v0, v0
	s_mov_b32 s83, s82
	v_writelane_b32 v251, s1, 1
	s_add_u32 s0, s94, 0x7210500
	s_addc_u32 s1, s95, 0
	v_writelane_b32 v252, s0, 16
	v_mul_f32_e32 v0, 0x4f7ffffe, v0
	v_cvt_u32_f32_e32 v0, v0
	v_writelane_b32 v252, s1, 17
	s_add_u32 s0, s94, 0x7210600
	s_addc_u32 s1, s95, 0
	v_writelane_b32 v252, s0, 18
	v_mov_b32_e32 v218, 1
	v_mov_b32_e32 v198, 0x358637bd
	v_writelane_b32 v252, s1, 19
	s_add_u32 s0, s94, 0x7210700
	s_addc_u32 s1, s95, 0
	v_writelane_b32 v252, s0, 20
	v_mov_b64_e32 v[200:201], 0x7415900
	v_bfrev_b32_e32 v227, 60
	v_writelane_b32 v252, s1, 21
	s_add_u32 s0, s94, 0x7210800
	s_addc_u32 s1, s95, 0
	v_writelane_b32 v252, s0, 22
	v_mov_b32_e32 v228, 0x3b800000
	v_mov_b32_e32 v229, 0x41b17218
	v_writelane_b32 v252, s1, 23
	s_add_u32 s0, s94, 0x7210900
	s_addc_u32 s1, s95, 0
	v_writelane_b32 v252, s0, 24
	s_movk_i32 s9, 0x880
	s_movk_i32 s15, 0x210
	v_writelane_b32 v252, s1, 25
	s_add_u32 s0, s94, 0x7210a00
	s_addc_u32 s1, s95, 0
	v_writelane_b32 v252, s0, 26
	s_movk_i32 s16, 0x90
	s_mov_b32 s17, 0xfffffc0
	v_writelane_b32 v252, s1, 27
	s_add_u32 s0, s94, 0x7210b00
	s_addc_u32 s1, s95, 0
	v_writelane_b32 v252, s0, 28
	s_movk_i32 s18, 0x81
	s_mov_b64 s[80:81], 0x7535900
	v_writelane_b32 v252, s1, 29
	s_add_u32 s0, s94, 0x7210c00
	s_addc_u32 s1, s95, 0
	v_writelane_b32 v252, s0, 30
	s_mov_b64 s[90:91], 0x11000
	s_mov_b64 s[76:77], 0x80
	v_writelane_b32 v252, s1, 31
	s_add_u32 s0, s94, 0x7210d00
	s_addc_u32 s1, s95, 0
	v_writelane_b32 v252, s0, 32
	s_mov_b64 s[88:89], 0x2000
	s_mov_b64 s[84:85], 0x3000
	v_writelane_b32 v252, s1, 33
	s_add_u32 s0, s94, 0x7210e00
	s_addc_u32 s1, s95, 0
	v_writelane_b32 v252, s0, 34
	s_barrier
	s_nop 0
	v_writelane_b32 v252, s1, 35
	s_add_u32 s0, s94, 0x7210f00
	s_addc_u32 s1, s95, 0
	v_writelane_b32 v252, s0, 36
	s_nop 1
	v_writelane_b32 v252, s1, 37
	s_add_u32 s0, s94, 0x7211000
	s_addc_u32 s1, s95, 0
	v_writelane_b32 v252, s0, 38
	s_nop 1
	v_writelane_b32 v252, s1, 39
	s_add_u32 s0, s94, 0x7211100
	s_addc_u32 s1, s95, 0
	s_add_u32 s28, s94, 0x7211200
	s_addc_u32 s29, s95, 0
	s_add_u32 s30, s94, 0x7211300
	s_addc_u32 s31, s95, 0
	v_writelane_b32 v252, s0, 40
	s_cmp_eq_u32 s33, 15
	s_nop 0
	v_writelane_b32 v252, s1, 41
	s_cselect_b64 s[0:1], -1, 0
	v_writelane_b32 v252, s0, 42
	s_cmp_eq_u32 s33, 14
	s_nop 0
	v_writelane_b32 v252, s1, 43
	s_cselect_b64 s[0:1], -1, 0
	v_writelane_b32 v252, s0, 44
	s_cmp_eq_u32 s33, 13
	s_nop 0
	v_writelane_b32 v252, s1, 45
	s_cselect_b64 s[0:1], -1, 0
	v_writelane_b32 v252, s0, 46
	s_cmp_eq_u32 s33, 12
	s_nop 0
	v_writelane_b32 v252, s1, 47
	s_cselect_b64 s[0:1], -1, 0
	v_writelane_b32 v252, s0, 48
	s_cmp_eq_u32 s33, 11
	s_nop 0
	v_writelane_b32 v252, s1, 49
	s_cselect_b64 s[0:1], -1, 0
	v_writelane_b32 v252, s0, 50
	s_cmp_eq_u32 s33, 10
	s_nop 0
	v_writelane_b32 v252, s1, 51
	s_cselect_b64 s[0:1], -1, 0
	v_writelane_b32 v252, s0, 52
	s_cmp_eq_u32 s33, 9
	s_nop 0
	v_writelane_b32 v252, s1, 53
	s_cselect_b64 s[0:1], -1, 0
	v_writelane_b32 v252, s0, 54
	s_cmp_eq_u32 s33, 8
	s_nop 0
	v_writelane_b32 v252, s1, 55
	s_cselect_b64 s[0:1], -1, 0
	v_writelane_b32 v252, s0, 56
	s_cmp_eq_u32 s33, 7
	s_nop 0
	v_writelane_b32 v252, s1, 57
	s_cselect_b64 s[0:1], -1, 0
	v_writelane_b32 v252, s0, 58
	s_cmp_eq_u32 s33, 6
	s_nop 0
	v_writelane_b32 v252, s1, 59
	s_cselect_b64 s[0:1], -1, 0
	v_writelane_b32 v252, s0, 60
	s_cmp_eq_u32 s33, 5
	s_nop 0
	v_writelane_b32 v252, s1, 61
	s_cselect_b64 s[0:1], -1, 0
	v_writelane_b32 v252, s0, 62
	s_cmp_eq_u32 s33, 4
	s_nop 0
	v_writelane_b32 v252, s1, 63
	s_cselect_b64 s[0:1], -1, 0
	v_writelane_b32 v250, s0, 0
	s_cmp_eq_u32 s33, 3
	s_nop 0
	v_writelane_b32 v250, s1, 1
	s_cselect_b64 s[0:1], -1, 0
	v_writelane_b32 v250, s0, 2
	s_cmp_eq_u32 s33, 2
	s_nop 0
	v_writelane_b32 v250, s1, 3
	s_cselect_b64 s[0:1], -1, 0
	v_writelane_b32 v250, s0, 4
	s_cmp_eq_u32 s33, 1
	s_nop 0
	v_writelane_b32 v250, s1, 5
	s_cselect_b64 s[0:1], -1, 0
	v_writelane_b32 v250, s0, 6
	s_cmp_eq_u32 s33, 0
	s_nop 0
	v_writelane_b32 v250, s1, 7
	s_cselect_b64 s[0:1], -1, 0
	v_writelane_b32 v250, s0, 8
	s_nop 1
	v_writelane_b32 v250, s1, 9
	s_lshl_b32 s0, s33, 8
	s_add_u32 s0, s36, s0
	s_addc_u32 s1, s37, 0
	s_add_u32 s2, s0, 0x1400
	s_addc_u32 s3, s1, 0
	v_writelane_b32 v250, s2, 10
	s_add_u32 s0, s0, 0x2400
	s_addc_u32 s1, s1, 0
	v_writelane_b32 v250, s3, 11
	v_writelane_b32 v250, s0, 12
	s_nop 1
	v_writelane_b32 v250, s1, 13
	s_add_u32 s0, s94, 0x7213400
	s_addc_u32 s1, s95, 0
	v_writelane_b32 v250, s0, 14
	s_nop 1
	v_writelane_b32 v250, s1, 15
	s_add_u32 s0, s94, 0x7213500
	s_addc_u32 s1, s95, 0
	s_add_u32 s86, s94, 0xcd35900
	v_writelane_b32 v250, s0, 16
	s_addc_u32 s87, s95, 0
	s_and_b32 s3, s64, 7
	v_writelane_b32 v250, s1, 17
	s_lshl_b32 s0, s3, 2
	s_add_u32 s0, s94, s0
	s_addc_u32 s1, s95, 0
; #define GSYNC() do { xcd_barrier(xb); xcd_barrier(xb); } while (0)
; #define GSYNC() xcd_barrier(xb)
; #define REP(n) for (int rep_ = 0; rep_ < ((DUP == (n) || (DUP == 100 && ((n) == 2 || (n) == 10))) ? 2 : 1); ++rep_)
; __global__ void __launch_bounds__(NTHREADS, 2) mega_kernel(Params p) {
;     ...
;   for (int chunk = 0; chunk < 3; ++chunk) {
;     Ctx c;
;     c.p = &p; c.chunk = chunk; c.layer = 0; c.ws = p.ws; c.lds = lds;
;     c.S = chunk == 0 ? 4096 : 16384; c.sshift = chunk == 0 ? 12 : 14;
;     c.x = p.out + (size_t)chunk * TC * DM;
;     c.xin = chunk == 0 ? p.in[0] : p.in[1] + (size_t)(chunk - 1) * TC * DM;
;     c.pe0 = chunk == 0 ? p.in[2] : p.in[3] + (size_t)(chunk - 1) * TC * 256;
;     c.pe_ls = chunk == 0 ? (size_t)TC * 256 : (size_t)2 * TC * 256;
;     REP(1) { if (PH(1)) phase_init(c); GSYNC(); }
; #pragma unroll 1
;     for (int layer = 0; layer < 2; ++layer) {
;       c.layer = layer;
	s_add_u32 s2, s0, 0x7213800
	v_writelane_b32 v250, s2, 18
	s_addc_u32 s2, s1, 0
	v_writelane_b32 v250, s2, 19
	s_lshl_b32 s2, s3, 4
	v_writelane_b32 v250, s2, 20
	s_add_u32 s2, s94, 0x7425900
	v_writelane_b32 v250, s2, 21
	s_addc_u32 s2, s95, 0
	s_lshr_b32 s33, s34, 3
	s_cmpk_lt_u32 s64, 0x400
	v_writelane_b32 v250, s2, 22
	s_cselect_b64 s[6:7], -1, 0
	v_writelane_b32 v250, s6, 23
	s_lshl_b32 s2, s64, 4
	s_and_b32 s78, s2, 0x70
	v_writelane_b32 v250, s7, 24
	s_lshr_b32 s2, s64, 3
	v_writelane_b32 v250, s2, 25
	s_add_u32 s2, s0, 0x7213c00
	v_writelane_b32 v250, s2, 26
	s_addc_u32 s2, s1, 0
	s_add_u32 s6, s94, 0x179d5900
	v_writelane_b32 v250, s2, 27
	s_addc_u32 s7, s95, 0
	v_writelane_b32 v250, s6, 28
	s_nop 1
	v_writelane_b32 v250, s7, 29
	s_add_u32 s6, s94, 0x14d75900
	s_addc_u32 s7, s95, 0
	v_writelane_b32 v250, s6, 30
	s_cmpk_lt_u32 s64, 0x700
	s_nop 0
	v_writelane_b32 v250, s7, 31
	s_cselect_b64 s[6:7], -1, 0
	v_writelane_b32 v250, s6, 32
	s_add_u32 s2, s94, 0xd735900
	s_nop 0
	v_writelane_b32 v250, s7, 33
	v_writelane_b32 v250, s2, 34
	s_addc_u32 s2, s95, 0
	s_add_u32 s6, s94, 0x10d35900
	v_writelane_b32 v250, s2, 35
	s_addc_u32 s7, s95, 0
	v_writelane_b32 v250, s6, 36
	s_nop 1
	v_writelane_b32 v250, s7, 37
	s_add_u32 s6, s94, 0xf535900
	s_addc_u32 s7, s95, 0
	v_writelane_b32 v250, s6, 38
	s_nop 1
	v_writelane_b32 v250, s7, 39
	s_add_u32 s6, s94, 0xdd35900
	s_addc_u32 s7, s95, 0
	v_writelane_b32 v250, s6, 40
	s_add_u32 s0, s0, 0x7213700
	s_nop 0
	v_writelane_b32 v250, s7, 41
	v_writelane_b32 v250, s0, 42
	s_addc_u32 s0, s1, 0
	v_writelane_b32 v250, s0, 43
	s_bfe_u32 s0, s64, 0x10002
	v_writelane_b32 v250, s0, 44
	s_add_u32 s0, s94, 0x11d75900
	v_writelane_b32 v250, s0, 45
	s_addc_u32 s0, s95, 0
	v_writelane_b32 v250, s0, 46
	s_add_u32 s0, s94, 0x13575900
	v_writelane_b32 v250, s0, 47
	s_addc_u32 s0, s95, 0
	v_writelane_b32 v250, s0, 48
	s_add_u32 s0, s94, 0x18fe5900
	s_addc_u32 s1, s95, 0
	v_writelane_b32 v250, s0, 49
	s_nop 1
	v_writelane_b32 v250, s1, 50
	s_add_u32 s0, s94, 0x1a7e5900
	s_addc_u32 s1, s95, 0
	v_writelane_b32 v250, s0, 51
	s_nop 1
	v_writelane_b32 v250, s1, 52
	s_add_u32 s0, s94, 0x165d5900
	v_writelane_b32 v250, s0, 53
	s_addc_u32 s0, s95, 0
	v_writelane_b32 v250, s0, 54
	s_add_u32 s0, s94, 0x175d5900
	v_writelane_b32 v250, s0, 55
	s_addc_u32 s0, s95, 0
	v_writelane_b32 v250, s0, 56
	s_lshl_b32 s0, s3, 7
	s_add_u32 s0, s94, s0
	s_addc_u32 s1, s95, 0
	s_add_u32 s2, s0, 0x1b2a5900
	v_writelane_b32 v250, s2, 57
	s_addc_u32 s2, s1, 0
	v_writelane_b32 v250, s2, 58
	s_add_u32 s0, s0, 0x17de5900
	v_writelane_b32 v250, s0, 59
	s_addc_u32 s0, s1, 0
	s_add_u32 s26, s94, 0x1a8a5900
	s_addc_u32 s27, s95, 0
	s_add_u32 s74, s94, 0x1c4a5900
	s_addc_u32 s75, s95, 0
	v_writelane_b32 v250, s0, 60
	s_add_u32 s0, s94, 0x7435900
	v_writelane_b32 v250, s0, 61
	s_addc_u32 s0, s95, 0
	v_writelane_b32 v250, s0, 62
	s_sub_i32 s0, 0, s82
	v_mul_lo_u32 v1, s0, v0
	s_mov_b32 s1, -1
	s_mov_b32 s0, s73
	s_and_b64 s[0:1], s[82:83], s[0:1]
	v_writelane_b32 v250, s0, 63
	s_ashr_i32 s5, s4, 31
	s_lshl_b32 s40, s34, 9
	v_writelane_b32 v249, s1, 0
	v_readlane_b32 s0, v252, 4
	s_add_i32 s0, s0, s82
	s_mov_b32 s41, s40
	v_writelane_b32 v249, s0, 1
	s_addk_i32 s0, 0x4000
	v_writelane_b32 v249, s0, 2
	s_lshl_b64 s[0:1], s[4:5], 2
	v_writelane_b32 v249, s0, 3
	v_mul_hi_u32 v1, v0, v1
	v_add_u32_e32 v205, v0, v1
	v_writelane_b32 v249, s1, 4
	s_add_u32 s0, s92, 0xc00
	s_addc_u32 s1, s93, 0
	v_writelane_b32 v249, s0, 5
	s_ashr_i32 s83, s82, 31
	s_lshl_b32 s10, s3, 11
	v_writelane_b32 v249, s1, 6
	s_lshl_b32 s0, s34, 10
	v_writelane_b32 v249, s0, 7
	s_lshl_b32 s0, s34, 11
	v_writelane_b32 v249, s0, 8
	s_mul_i32 s0, s34, 0x2200
	s_mul_hi_i32 s1, s4, 0x880
	v_writelane_b32 v249, s0, 9
	s_and_b32 s8, s34, -8
	s_or_b32 s11, s10, 24
	v_writelane_b32 v249, s1, 10
	s_lshl_b32 s0, s64, 10
	v_writelane_b32 v249, s0, 11
	s_and_b32 s0, s64, -8
	v_writelane_b32 v249, s0, 12
	s_lshl_b32 s0, s64, 11
	v_writelane_b32 v249, s0, 13
	s_mov_b32 s0, s4
	v_writelane_b32 v249, s0, 14
	s_or_b32 s12, s10, 16
	s_or_b32 s13, s10, 8
	v_writelane_b32 v249, s1, 15
	s_lshl_b64 s[0:1], s[4:5], 12
	v_writelane_b32 v249, s0, 16
	s_lshl_b64 s[42:43], s[82:83], 2
	v_mbcnt_lo_u32_b32 v0, -1, 0
	v_writelane_b32 v249, s1, 17
	s_lshl_b64 s[0:1], s[82:83], 4
	v_writelane_b32 v249, s0, 18
	v_mbcnt_hi_u32_b32 v219, -1, v0
	v_and_b32_e32 v0, 64, v219
	v_writelane_b32 v249, s1, 19
	s_add_u32 s0, s94, 0x7535980
	v_writelane_b32 v249, s0, 20
	s_addc_u32 s0, s95, 0
	v_writelane_b32 v249, s0, 21
	s_mul_i32 s0, s3, 0x440000
	v_writelane_b32 v249, s0, 22
	s_add_u32 s0, s94, 0x18c0080
	v_writelane_b32 v249, s0, 23
	s_addc_u32 s0, s95, 0
	v_writelane_b32 v249, s0, 24
	s_add_u32 s0, s94, 0x3648080
	v_writelane_b32 v249, s0, 25
	s_addc_u32 s0, s95, 0
	v_writelane_b32 v249, s0, 26
	s_add_i32 s0, 0, 0x12200
	v_writelane_b32 v249, s0, 27
	s_add_i32 s0, 0, 0x12204
	v_writelane_b32 v249, s0, 28
	s_add_i32 s0, 0, 0x12040
	v_writelane_b32 v249, s0, 29
	s_add_i32 s0, 0, 0x8f80
	v_writelane_b32 v249, s0, 30
	v_writelane_b32 v249, s3, 31
	s_lshl_b32 s0, s3, 2
	v_writelane_b32 v249, s0, 32
	v_writelane_b32 v249, s40, 33
	v_writelane_b32 v249, s41, 34
	v_writelane_b32 v249, s42, 35
	v_mov_b32_e32 v1, 0
	v_add_u32_e32 v220, 64, v0
	v_writelane_b32 v249, s43, 36
	v_writelane_b32 v249, s82, 37
	v_xor_b32_e32 v221, 32, v219
	v_xor_b32_e32 v222, 16, v219
	v_writelane_b32 v249, s83, 38
	v_writelane_b32 v249, s24, 39
	v_xor_b32_e32 v223, 8, v219
	v_xor_b32_e32 v224, 4, v219
	v_writelane_b32 v249, s25, 40
	v_xor_b32_e32 v225, 2, v219
	v_xor_b32_e32 v226, 1, v219
	s_add_i32 s14, 0, 0x12000
	s_mov_b32 s2, 0
	v_writelane_b32 v249, s26, 41
	s_nop 1
	v_writelane_b32 v249, s27, 42
	s_branch .LBB0_287
	s_nop 0
	s_nop 0
	s_nop 0
	s_nop 0
	s_nop 0
	s_nop 0
	s_nop 0
	s_nop 0
	s_nop 0
	s_nop 0
	s_nop 0
	s_nop 0
	s_nop 0
	s_nop 0
	s_nop 0
	s_nop 0
	s_nop 0
	s_nop 0
	s_nop 0
	s_nop 0
	s_nop 0
	s_nop 0
	s_nop 0
	s_nop 0
	s_nop 0
	s_nop 0
	s_nop 0
	s_nop 0
	s_nop 0
	s_nop 0
	s_nop 0
	s_nop 0
	s_nop 0

; #define GL1_(RA, RB, i) { RA[i] = *(const u32x4*)(ap + (aoff + (i) * astep)); if ((i) < NB) RB[(i) < NB ? (i) : 0] = *(const u32x4*)(bp + (boff + (i) * bstep)); }
; #define LS1_(RA, RB, ST, i) { char* sn_ = lds + (ST) * STAGE; *(u32x4*)(sn_ + wofs + (i) * 32 * LROW) = RA[i]; \
;                               if ((i) < NB) *(u32x4*)(sn_ + STAGE_OP + wofs + (i) * 32 * LROW) = RB[(i) < NB ? (i) : 0]; }
; template <int NJ> DI void gemm_mainloop_reg(const bf16_t* __restrict__ A, int lda, const bf16_t* __restrict__ Bt, int ldb, int K, f32x16 (&acc)[2][NJ], char* lds) {
;     ...
; #pragma unroll
;   for (int i = 0; i < 4; ++i) GL1_(ra0, rb0, i);
;   ap += 128; bp += 128;
; #pragma unroll
;   for (int i = 0; i < 4; ++i) GL1_(ra1, rb1, i);
;   ap += 128; bp += 128;
; #pragma unroll
;   for (int i = 0; i < 4; ++i) LS1_(ra0, rb0, 0, i);
;   __syncthreads();
;   const int nk = K >> 6;
;   for (int kt = 0; kt < nk; kt += 2) {
;     const bool l0 = (kt + 2 < nk), l1 = (kt + 3 < nk);
;     STEP_(0, l0, ra0, rb0, true, ra1, rb1);
; DI void phase_ffn_in(const Ctx& c, const bf16_t* A, size_t woff, int site) {
;     ...
;     const int j_ = grab_next(ctr, c.lds);
;     if (j_ >= 128 * 6) break;
;     const int mt = xcd_ * 16 + (j_ & 7) + 8 * ((j_ >> 6) & 1), nt = (j_ >> 7) * 8 + ((j_ >> 3) & 7);
;     if (nt >= 44) continue;
;     f32x16 acc[2][2]; zero_acc<2>(acc);
;     gemm_mainloop_reg<2>(A + (size_t)mt * 128 * LDX, LDX, Bt + (size_t)nt * 128 * LDX, LDX, DM, acc, c.lds);
.LBB0_365:
	s_or_b64 exec, exec, s[2:3]
	s_add_i32 s24, 0, 0x12210
	s_cmp_lg_u32 s24, -1
	s_cselect_b32 s2, s24, 0
	s_cselect_b32 s3, s79, 0
	v_mov_b32_e32 v2, s2
	v_mov_b32_e32 v3, s3
	s_waitcnt lgkmcnt(0)
	s_barrier
	flat_load_dword v2, v[2:3] sc0 sc1
	s_waitcnt vmcnt(0)
	s_mov_b64 s[2:3], -1
	s_waitcnt lgkmcnt(0)
	s_barrier
	v_readfirstlane_b32 s4, v2
	s_cmpk_gt_i32 s4, 0x2ff
	s_cbranch_scc1 .LBB0_360
	s_ashr_i32 s2, s4, 4
	s_and_b32 s2, s2, -8
	s_bfe_u32 s3, s4, 0x30003
	s_or_b32 s6, s2, s3
	s_cmp_gt_i32 s6, 43
	s_cbranch_scc1 .LBB0_359
	s_lshr_b32 s2, s4, 3
	s_and_b32 s7, s4, 7
	s_and_b32 s27, s2, 8
	s_or_b32 s2, s7, s27
	v_readlane_b32 s3, v250, 20
	s_or_b32 s34, s2, s3
	v_mov_b32_e32 v34, v199
	s_mul_i32 s2, s34, 0x44000
	s_add_u32 s2, s25, s2
	v_ashrrev_i32_e32 v35, 3, v34
	v_lshlrev_b32_e32 v2, 4, v34
	v_and_b32_e32 v36, 0x70, v2
	v_mul_lo_u32 v2, v35, s9
	s_addc_u32 s3, s26, 0
	s_mul_i32 s4, s6, 0x44000
	v_or_b32_e32 v80, v36, v2
	s_mul_hi_i32 s5, s6, 0x44000
	s_add_u32 s4, s22, s4
	v_add_u32_e32 v79, 0x11000, v80
	v_add_u32_e32 v78, 0x22000, v80
	v_add_u32_e32 v77, 0x33000, v80
	s_addc_u32 s5, s23, s5
	global_load_dwordx4 v[2:5], v80, s[2:3]
	global_load_dwordx4 v[6:9], v79, s[2:3]
	global_load_dwordx4 v[10:13], v78, s[2:3]
	global_load_dwordx4 v[14:17], v77, s[2:3]
	global_load_dwordx4 v[18:21], v80, s[4:5]
	global_load_dwordx4 v[22:25], v79, s[4:5]
	global_load_dwordx4 v[26:29], v78, s[4:5]
	global_load_dwordx4 v[30:33], v77, s[4:5]
	v_mul_lo_u32 v35, v35, s16
	v_lshrrev_b32_e32 v37, 1, v34
	v_and_b32_e32 v38, 31, v34
	v_add3_u32 v75, v35, v36, 0
	v_and_b32_e32 v39, 16, v37
	v_and_or_b32 v37, v37, s17, v38
	global_load_dwordx4 v[82:85], v80, s[2:3] offset:128
	global_load_dwordx4 v[86:89], v79, s[2:3] offset:128
	global_load_dwordx4 v[90:93], v78, s[2:3] offset:128
	global_load_dwordx4 v[94:97], v77, s[2:3] offset:128
	global_load_dwordx4 v[98:101], v80, s[4:5] offset:128
	global_load_dwordx4 v[102:105], v79, s[4:5] offset:128
	global_load_dwordx4 v[106:109], v78, s[4:5] offset:128
	global_load_dwordx4 v[110:113], v77, s[4:5] offset:128
	v_mul_lo_u32 v35, v37, s16
	v_add3_u32 v73, v35, v39, 0
	v_add_u32_e32 v76, 0xd800, v75
	s_waitcnt vmcnt(15)
	ds_write_b128 v75, v[2:5]
	s_waitcnt vmcnt(14)
	ds_write_b128 v75, v[6:9] offset:4608
	s_waitcnt vmcnt(13)
	ds_write_b128 v75, v[10:13] offset:9216
	s_waitcnt vmcnt(12)
	ds_write_b128 v75, v[14:17] offset:13824
	s_waitcnt vmcnt(11)
	ds_write_b128 v75, v[18:21] offset:18432
	s_waitcnt vmcnt(10)
	ds_write_b128 v75, v[22:25] offset:23040
	s_waitcnt vmcnt(9)
	ds_write_b128 v75, v[26:29] offset:27648
	s_waitcnt vmcnt(8)
	ds_write_b128 v75, v[30:33] offset:32256
	v_and_b32_e32 v2, 0x5f, v34
	v_mul_u32_u24_e32 v2, 0x90, v2
	v_add3_u32 v74, v2, v39, 0
	s_waitcnt lgkmcnt(0)
	s_barrier
	ds_read_b128 v[18:21], v73
	ds_read_b128 v[2:5], v74 offset:18432
	ds_read_b128 v[114:117], v73 offset:32
	ds_read_b128 v[118:121], v74 offset:18464
	ds_read_b128 v[22:25], v73 offset:4608
	ds_read_b128 v[122:125], v73 offset:4640
	ds_read_b128 v[26:29], v74 offset:23040
	ds_read_b128 v[126:129], v74 offset:23072
	global_load_dwordx4 v[130:133], v80, s[2:3] offset:256
	global_load_dwordx4 v[134:137], v80, s[4:5] offset:256
	s_waitcnt lgkmcnt(6)
	s_setprio 1
	s_nop 0
	v_mfma_f32_32x32x16_bf16 v[34:49], v[18:21], v[2:5], 0
	s_waitcnt vmcnt(9)
	ds_write_b128 v75, v[82:85] offset:36864
	s_waitcnt vmcnt(5)
	ds_write_b128 v75, v[98:101] offset:55296
	s_waitcnt lgkmcnt(5)
	v_mfma_f32_32x32x16_bf16 v[2:17], v[22:25], v[2:5], 0
	s_waitcnt lgkmcnt(3)
	v_mfma_f32_32x32x16_bf16 v[50:65], v[18:21], v[26:29], 0
	v_mfma_f32_32x32x16_bf16 v[18:33], v[22:25], v[26:29], 0
	global_load_dwordx4 v[82:85], v79, s[2:3] offset:256
	global_load_dwordx4 v[98:101], v79, s[4:5] offset:256
	v_mfma_f32_32x32x16_bf16 v[34:49], v[114:117], v[118:121], v[34:49]
	v_mfma_f32_32x32x16_bf16 v[2:17], v[122:125], v[118:121], v[2:17]
	s_waitcnt lgkmcnt(2)
	v_mfma_f32_32x32x16_bf16 v[50:65], v[114:117], v[126:129], v[50:65]
	ds_read_b128 v[114:117], v73 offset:64
	ds_read_b128 v[118:121], v73 offset:4672
	ds_read_b128 v[138:141], v74 offset:18496
	ds_read_b128 v[142:145], v74 offset:23104
	ds_write_b128 v75, v[86:89] offset:41472
	s_waitcnt vmcnt(6)
	ds_write_b128 v75, v[102:105] offset:59904
	v_mfma_f32_32x32x16_bf16 v[18:33], v[122:125], v[126:129], v[18:33]
	global_load_dwordx4 v[86:89], v78, s[2:3] offset:256
	global_load_dwordx4 v[102:105], v78, s[4:5] offset:256
	s_waitcnt lgkmcnt(3)
	v_mfma_f32_32x32x16_bf16 v[34:49], v[114:117], v[138:141], v[34:49]
	v_mfma_f32_32x32x16_bf16 v[2:17], v[118:121], v[138:141], v[2:17]
	s_waitcnt lgkmcnt(2)
	v_mfma_f32_32x32x16_bf16 v[50:65], v[114:117], v[142:145], v[50:65]
	ds_read_b128 v[114:117], v73 offset:96
	ds_read_b128 v[122:125], v73 offset:4704
	ds_read_b128 v[126:129], v74 offset:18528
	ds_read_b128 v[138:141], v74 offset:23136
	ds_write_b128 v75, v[90:93] offset:46080
	s_waitcnt vmcnt(7)
	ds_write_b128 v75, v[106:109] offset:64512
	v_mfma_f32_32x32x16_bf16 v[18:33], v[118:121], v[142:145], v[18:33]
	global_load_dwordx4 v[90:93], v77, s[2:3] offset:256
	global_load_dwordx4 v[106:109], v77, s[4:5] offset:256
	s_waitcnt lgkmcnt(3)
	v_mfma_f32_32x32x16_bf16 v[34:49], v[114:117], v[126:129], v[34:49]
	ds_write_b128 v75, v[94:97] offset:50688
	s_waitcnt vmcnt(8)
	ds_write_b128 v76, v[110:113] offset:13824
	v_mfma_f32_32x32x16_bf16 v[2:17], v[122:125], v[126:129], v[2:17]
	s_waitcnt lgkmcnt(4)
	v_mfma_f32_32x32x16_bf16 v[50:65], v[114:117], v[138:141], v[50:65]
	v_mfma_f32_32x32x16_bf16 v[18:33], v[122:125], v[138:141], v[18:33]
	s_waitcnt lgkmcnt(0)
	s_barrier
; #define GL1_(RA, RB, i) { RA[i] = *(const u32x4*)(ap + (aoff + (i) * astep)); if ((i) < NB) RB[(i) < NB ? (i) : 0] = *(const u32x4*)(bp + (boff + (i) * bstep)); }
; #define LS1_(RA, RB, ST, i) { char* sn_ = lds + (ST) * STAGE; *(u32x4*)(sn_ + wofs + (i) * 32 * LROW) = RA[i]; \
;                               if ((i) < NB) *(u32x4*)(sn_ + STAGE_OP + wofs + (i) * 32 * LROW) = RB[(i) < NB ? (i) : 0]; }
; template <int NJ> DI void gemm_mainloop_reg(const bf16_t* __restrict__ A, int lda, const bf16_t* __restrict__ Bt, int ldb, int K, f32x16 (&acc)[2][NJ], char* lds) {
;     ...
; #pragma unroll
;   for (int i = 0; i < 4; ++i) GL1_(ra0, rb0, i);
;   ap += 128; bp += 128;
; #pragma unroll
;   for (int i = 0; i < 4; ++i) GL1_(ra1, rb1, i);
;   ap += 128; bp += 128;
; #pragma unroll
;   for (int i = 0; i < 4; ++i) LS1_(ra0, rb0, 0, i);
;   __syncthreads();
;   const int nk = K >> 6;
;   for (int kt = 0; kt < nk; kt += 2) {
;     const bool l0 = (kt + 2 < nk), l1 = (kt + 3 < nk);
;     STEP_(0, l0, ra0, rb0, true, ra1, rb1);
;     __syncthreads();
;     STEP_(1, l1, ra1, rb1, l0, ra0, rb0);
;     __syncthreads();
;   }
	ds_read_b128 v[94:97], v73 offset:36864
	ds_read_b128 v[110:113], v74 offset:55296
	ds_read_b128 v[114:117], v73 offset:36896
	ds_read_b128 v[118:121], v74 offset:55328
	ds_read_b128 v[122:125], v73 offset:41472
	ds_read_b128 v[126:129], v73 offset:41504
	s_waitcnt lgkmcnt(4)
	v_mfma_f32_32x32x16_bf16 v[34:49], v[94:97], v[110:113], v[34:49]
	s_waitcnt lgkmcnt(1)
	v_mfma_f32_32x32x16_bf16 v[2:17], v[122:125], v[110:113], v[2:17]
	ds_read_b128 v[110:113], v74 offset:59904
	ds_read_b128 v[138:141], v74 offset:59936
	s_waitcnt lgkmcnt(1)
	v_mfma_f32_32x32x16_bf16 v[50:65], v[94:97], v[110:113], v[50:65]
	global_load_dwordx4 v[94:97], v80, s[2:3] offset:384
	global_load_dwordx4 v[142:145], v80, s[4:5] offset:384
	s_waitcnt vmcnt(9)
	ds_write_b128 v75, v[130:133]
	s_waitcnt vmcnt(8)
	ds_write_b128 v75, v[134:137] offset:18432
	v_mfma_f32_32x32x16_bf16 v[18:33], v[122:125], v[110:113], v[18:33]
	v_mfma_f32_32x32x16_bf16 v[34:49], v[114:117], v[118:121], v[34:49]
	s_waitcnt lgkmcnt(2)
	v_mfma_f32_32x32x16_bf16 v[50:65], v[114:117], v[138:141], v[50:65]
	global_load_dwordx4 v[110:113], v79, s[2:3] offset:384
	global_load_dwordx4 v[114:117], v79, s[4:5] offset:384
	v_mfma_f32_32x32x16_bf16 v[2:17], v[126:129], v[118:121], v[2:17]
	ds_read_b128 v[118:121], v73 offset:36928
	ds_read_b128 v[122:125], v73 offset:41536
	ds_read_b128 v[130:133], v74 offset:55360
	ds_read_b128 v[134:137], v74 offset:59968
	s_waitcnt vmcnt(9)
	ds_write_b128 v75, v[82:85] offset:4608
	s_waitcnt vmcnt(8)
	ds_write_b128 v75, v[98:101] offset:23040
	v_mfma_f32_32x32x16_bf16 v[18:33], v[126:129], v[138:141], v[18:33]
	global_load_dwordx4 v[82:85], v78, s[2:3] offset:384
	global_load_dwordx4 v[98:101], v78, s[4:5] offset:384
	s_waitcnt lgkmcnt(3)
	v_mfma_f32_32x32x16_bf16 v[34:49], v[118:121], v[130:133], v[34:49]
	v_mfma_f32_32x32x16_bf16 v[2:17], v[122:125], v[130:133], v[2:17]
	s_waitcnt lgkmcnt(2)
	v_mfma_f32_32x32x16_bf16 v[50:65], v[118:121], v[134:137], v[50:65]
	ds_read_b128 v[118:121], v73 offset:36960
	ds_read_b128 v[126:129], v73 offset:41568
	ds_read_b128 v[130:133], v74 offset:55392
	ds_read_b128 v[138:141], v74 offset:60000
	s_waitcnt vmcnt(9)
	ds_write_b128 v75, v[86:89] offset:9216
	s_waitcnt vmcnt(8)
	ds_write_b128 v75, v[102:105] offset:27648
	v_mfma_f32_32x32x16_bf16 v[18:33], v[122:125], v[134:137], v[18:33]
	global_load_dwordx4 v[86:89], v77, s[2:3] offset:384
	global_load_dwordx4 v[102:105], v77, s[4:5] offset:384
	s_waitcnt lgkmcnt(3)
	v_mfma_f32_32x32x16_bf16 v[34:49], v[118:121], v[130:133], v[34:49]
	s_waitcnt vmcnt(9)
	ds_write_b128 v75, v[90:93] offset:13824
	s_waitcnt vmcnt(8)
	ds_write_b128 v75, v[106:109] offset:32256
	v_mfma_f32_32x32x16_bf16 v[2:17], v[126:129], v[130:133], v[2:17]
	s_waitcnt lgkmcnt(4)
	v_mfma_f32_32x32x16_bf16 v[50:65], v[118:121], v[138:141], v[50:65]
	v_mfma_f32_32x32x16_bf16 v[18:33], v[126:129], v[138:141], v[18:33]
	s_waitcnt lgkmcnt(0)
	s_barrier
	ds_read_b128 v[90:93], v73
	ds_read_b128 v[106:109], v74 offset:18432
	ds_read_b128 v[118:121], v73 offset:32
	ds_read_b128 v[122:125], v74 offset:18464
	ds_read_b128 v[126:129], v73 offset:4608
	ds_read_b128 v[130:133], v73 offset:4640
	s_waitcnt lgkmcnt(4)
	v_mfma_f32_32x32x16_bf16 v[34:49], v[90:93], v[106:109], v[34:49]
	s_waitcnt lgkmcnt(1)
	v_mfma_f32_32x32x16_bf16 v[2:17], v[126:129], v[106:109], v[2:17]
	ds_read_b128 v[106:109], v74 offset:23040
	ds_read_b128 v[134:137], v74 offset:23072
	s_waitcnt lgkmcnt(1)
	v_mfma_f32_32x32x16_bf16 v[50:65], v[90:93], v[106:109], v[50:65]
	global_load_dwordx4 v[90:93], v80, s[2:3] offset:512
	global_load_dwordx4 v[138:141], v80, s[4:5] offset:512
	s_waitcnt vmcnt(9)
	ds_write_b128 v75, v[94:97] offset:36864
	s_waitcnt vmcnt(8)
	ds_write_b128 v75, v[142:145] offset:55296
	v_mfma_f32_32x32x16_bf16 v[18:33], v[126:129], v[106:109], v[18:33]
	global_load_dwordx4 v[94:97], v79, s[2:3] offset:512
	global_load_dwordx4 v[106:109], v79, s[4:5] offset:512
	v_mfma_f32_32x32x16_bf16 v[34:49], v[118:121], v[122:125], v[34:49]
	v_mfma_f32_32x32x16_bf16 v[2:17], v[130:133], v[122:125], v[2:17]
	s_waitcnt lgkmcnt(2)
	v_mfma_f32_32x32x16_bf16 v[50:65], v[118:121], v[134:137], v[50:65]
	ds_read_b128 v[118:121], v73 offset:64
	ds_read_b128 v[122:125], v73 offset:4672
	ds_read_b128 v[126:129], v74 offset:18496
	ds_read_b128 v[142:145], v74 offset:23104
	s_waitcnt vmcnt(9)
	ds_write_b128 v75, v[110:113] offset:41472
	s_waitcnt vmcnt(8)
	ds_write_b128 v75, v[114:117] offset:59904
	v_mfma_f32_32x32x16_bf16 v[18:33], v[130:133], v[134:137], v[18:33]
	global_load_dwordx4 v[110:113], v78, s[2:3] offset:512
	global_load_dwordx4 v[114:117], v78, s[4:5] offset:512
	s_waitcnt lgkmcnt(3)
	v_mfma_f32_32x32x16_bf16 v[34:49], v[118:121], v[126:129], v[34:49]
	v_mfma_f32_32x32x16_bf16 v[2:17], v[122:125], v[126:129], v[2:17]
	s_waitcnt lgkmcnt(2)
	v_mfma_f32_32x32x16_bf16 v[50:65], v[118:121], v[142:145], v[50:65]
	ds_read_b128 v[118:121], v73 offset:96
	ds_read_b128 v[126:129], v73 offset:4704
	ds_read_b128 v[130:133], v74 offset:18528
	ds_read_b128 v[134:137], v74 offset:23136
	s_waitcnt vmcnt(9)
	ds_write_b128 v75, v[82:85] offset:46080
	s_waitcnt vmcnt(8)
	ds_write_b128 v75, v[98:101] offset:64512
	v_mfma_f32_32x32x16_bf16 v[18:33], v[122:125], v[142:145], v[18:33]
	global_load_dwordx4 v[82:85], v77, s[2:3] offset:512
	global_load_dwordx4 v[98:101], v77, s[4:5] offset:512
	s_waitcnt lgkmcnt(3)
	v_mfma_f32_32x32x16_bf16 v[34:49], v[118:121], v[130:133], v[34:49]
	s_waitcnt vmcnt(9)
	ds_write_b128 v75, v[86:89] offset:50688
	s_waitcnt vmcnt(8)
	ds_write_b128 v76, v[102:105] offset:13824
	v_mfma_f32_32x32x16_bf16 v[2:17], v[126:129], v[130:133], v[2:17]
	s_waitcnt lgkmcnt(4)
	v_mfma_f32_32x32x16_bf16 v[50:65], v[118:121], v[134:137], v[50:65]
	v_mfma_f32_32x32x16_bf16 v[18:33], v[126:129], v[134:137], v[18:33]
	s_waitcnt lgkmcnt(0)
	s_barrier
; #define GL1_(RA, RB, i) { RA[i] = *(const u32x4*)(ap + (aoff + (i) * astep)); if ((i) < NB) RB[(i) < NB ? (i) : 0] = *(const u32x4*)(bp + (boff + (i) * bstep)); }
; #define LS1_(RA, RB, ST, i) { char* sn_ = lds + (ST) * STAGE; *(u32x4*)(sn_ + wofs + (i) * 32 * LROW) = RA[i]; \
;                               if ((i) < NB) *(u32x4*)(sn_ + STAGE_OP + wofs + (i) * 32 * LROW) = RB[(i) < NB ? (i) : 0]; }
; template <int NJ> DI void gemm_mainloop_reg(const bf16_t* __restrict__ A, int lda, const bf16_t* __restrict__ Bt, int ldb, int K, f32x16 (&acc)[2][NJ], char* lds) {
;     ...
; #pragma unroll
;   for (int i = 0; i < 4; ++i) GL1_(ra0, rb0, i);
;   ap += 128; bp += 128;
; #pragma unroll
;   for (int i = 0; i < 4; ++i) GL1_(ra1, rb1, i);
;   ap += 128; bp += 128;
; #pragma unroll
;   for (int i = 0; i < 4; ++i) LS1_(ra0, rb0, 0, i);
;   __syncthreads();
;   const int nk = K >> 6;
;   for (int kt = 0; kt < nk; kt += 2) {
;     const bool l0 = (kt + 2 < nk), l1 = (kt + 3 < nk);
;     STEP_(0, l0, ra0, rb0, true, ra1, rb1);
;     __syncthreads();
;     STEP_(1, l1, ra1, rb1, l0, ra0, rb0);
;     __syncthreads();
;   }
	ds_read_b128 v[86:89], v73 offset:36864
	ds_read_b128 v[102:105], v74 offset:55296
	ds_read_b128 v[118:121], v73 offset:36896
	ds_read_b128 v[122:125], v74 offset:55328
	ds_read_b128 v[126:129], v73 offset:41472
	ds_read_b128 v[130:133], v73 offset:41504
	s_waitcnt lgkmcnt(4)
	v_mfma_f32_32x32x16_bf16 v[34:49], v[86:89], v[102:105], v[34:49]
	s_waitcnt lgkmcnt(1)
	v_mfma_f32_32x32x16_bf16 v[2:17], v[126:129], v[102:105], v[2:17]
	ds_read_b128 v[102:105], v74 offset:59904
	ds_read_b128 v[134:137], v74 offset:59936
	s_waitcnt lgkmcnt(1)
	v_mfma_f32_32x32x16_bf16 v[50:65], v[86:89], v[102:105], v[50:65]
	global_load_dwordx4 v[86:89], v80, s[2:3] offset:640
	global_load_dwordx4 v[142:145], v80, s[4:5] offset:640
	s_waitcnt vmcnt(9)
	ds_write_b128 v75, v[90:93]
	s_waitcnt vmcnt(8)
	ds_write_b128 v75, v[138:141] offset:18432
	v_mfma_f32_32x32x16_bf16 v[18:33], v[126:129], v[102:105], v[18:33]
	global_load_dwordx4 v[90:93], v79, s[2:3] offset:640
	global_load_dwordx4 v[102:105], v79, s[4:5] offset:640
	v_mfma_f32_32x32x16_bf16 v[34:49], v[118:121], v[122:125], v[34:49]
	v_mfma_f32_32x32x16_bf16 v[2:17], v[130:133], v[122:125], v[2:17]
	s_waitcnt lgkmcnt(2)
	v_mfma_f32_32x32x16_bf16 v[50:65], v[118:121], v[134:137], v[50:65]
	ds_read_b128 v[118:121], v73 offset:36928
	ds_read_b128 v[122:125], v73 offset:41536
	ds_read_b128 v[126:129], v74 offset:55360
	ds_read_b128 v[138:141], v74 offset:59968
	s_waitcnt vmcnt(9)
	ds_write_b128 v75, v[94:97] offset:4608
	s_waitcnt vmcnt(8)
	ds_write_b128 v75, v[106:109] offset:23040
	v_mfma_f32_32x32x16_bf16 v[18:33], v[130:133], v[134:137], v[18:33]
	global_load_dwordx4 v[94:97], v78, s[2:3] offset:640
	global_load_dwordx4 v[106:109], v78, s[4:5] offset:640
	s_waitcnt lgkmcnt(3)
	v_mfma_f32_32x32x16_bf16 v[34:49], v[118:121], v[126:129], v[34:49]
	v_mfma_f32_32x32x16_bf16 v[2:17], v[122:125], v[126:129], v[2:17]
	s_waitcnt lgkmcnt(2)
	v_mfma_f32_32x32x16_bf16 v[50:65], v[118:121], v[138:141], v[50:65]
	ds_read_b128 v[118:121], v73 offset:36960
	ds_read_b128 v[126:129], v73 offset:41568
	ds_read_b128 v[130:133], v74 offset:55392
	ds_read_b128 v[134:137], v74 offset:60000
	s_waitcnt vmcnt(9)
	ds_write_b128 v75, v[110:113] offset:9216
	s_waitcnt vmcnt(8)
	ds_write_b128 v75, v[114:117] offset:27648
	v_mfma_f32_32x32x16_bf16 v[18:33], v[122:125], v[138:141], v[18:33]
	global_load_dwordx4 v[110:113], v77, s[2:3] offset:640
	global_load_dwordx4 v[114:117], v77, s[4:5] offset:640
	s_waitcnt lgkmcnt(3)
	v_mfma_f32_32x32x16_bf16 v[34:49], v[118:121], v[130:133], v[34:49]
	s_waitcnt vmcnt(9)
	ds_write_b128 v75, v[82:85] offset:13824
	s_waitcnt vmcnt(8)
	ds_write_b128 v75, v[98:101] offset:32256
	v_mfma_f32_32x32x16_bf16 v[2:17], v[126:129], v[130:133], v[2:17]
	s_waitcnt lgkmcnt(4)
	v_mfma_f32_32x32x16_bf16 v[50:65], v[118:121], v[134:137], v[50:65]
	v_mfma_f32_32x32x16_bf16 v[18:33], v[126:129], v[134:137], v[18:33]
	s_waitcnt lgkmcnt(0)
	s_barrier
	ds_read_b128 v[82:85], v73
	ds_read_b128 v[98:101], v74 offset:18432
	ds_read_b128 v[118:121], v73 offset:32
	ds_read_b128 v[122:125], v74 offset:18464
	ds_read_b128 v[126:129], v73 offset:4608
	ds_read_b128 v[130:133], v73 offset:4640
	s_waitcnt lgkmcnt(4)
	v_mfma_f32_32x32x16_bf16 v[34:49], v[82:85], v[98:101], v[34:49]
	s_waitcnt lgkmcnt(1)
	v_mfma_f32_32x32x16_bf16 v[2:17], v[126:129], v[98:101], v[2:17]
	ds_read_b128 v[98:101], v74 offset:23040
	ds_read_b128 v[134:137], v74 offset:23072
	s_waitcnt lgkmcnt(1)
	v_mfma_f32_32x32x16_bf16 v[50:65], v[82:85], v[98:101], v[50:65]
	global_load_dwordx4 v[82:85], v80, s[2:3] offset:768
	global_load_dwordx4 v[138:141], v80, s[4:5] offset:768
	s_waitcnt vmcnt(9)
	ds_write_b128 v75, v[86:89] offset:36864
	s_waitcnt vmcnt(8)
	ds_write_b128 v75, v[142:145] offset:55296
	v_mfma_f32_32x32x16_bf16 v[18:33], v[126:129], v[98:101], v[18:33]
	global_load_dwordx4 v[86:89], v79, s[2:3] offset:768
	global_load_dwordx4 v[98:101], v79, s[4:5] offset:768
	v_mfma_f32_32x32x16_bf16 v[34:49], v[118:121], v[122:125], v[34:49]
	v_mfma_f32_32x32x16_bf16 v[2:17], v[130:133], v[122:125], v[2:17]
	s_waitcnt lgkmcnt(2)
	v_mfma_f32_32x32x16_bf16 v[50:65], v[118:121], v[134:137], v[50:65]
	ds_read_b128 v[118:121], v73 offset:64
	ds_read_b128 v[122:125], v73 offset:4672
	ds_read_b128 v[126:129], v74 offset:18496
	ds_read_b128 v[142:145], v74 offset:23104
	s_waitcnt vmcnt(9)
	ds_write_b128 v75, v[90:93] offset:41472
	s_waitcnt vmcnt(8)
	ds_write_b128 v75, v[102:105] offset:59904
	v_mfma_f32_32x32x16_bf16 v[18:33], v[130:133], v[134:137], v[18:33]
	global_load_dwordx4 v[90:93], v78, s[2:3] offset:768
	global_load_dwordx4 v[102:105], v78, s[4:5] offset:768
	s_waitcnt lgkmcnt(3)
	v_mfma_f32_32x32x16_bf16 v[34:49], v[118:121], v[126:129], v[34:49]
	v_mfma_f32_32x32x16_bf16 v[2:17], v[122:125], v[126:129], v[2:17]
	s_waitcnt lgkmcnt(2)
	v_mfma_f32_32x32x16_bf16 v[50:65], v[118:121], v[142:145], v[50:65]
	ds_read_b128 v[118:121], v73 offset:96
	ds_read_b128 v[126:129], v73 offset:4704
	ds_read_b128 v[130:133], v74 offset:18528
	ds_read_b128 v[134:137], v74 offset:23136
	s_waitcnt vmcnt(9)
	ds_write_b128 v75, v[94:97] offset:46080
	s_waitcnt vmcnt(8)
	ds_write_b128 v75, v[106:109] offset:64512
	v_mfma_f32_32x32x16_bf16 v[18:33], v[122:125], v[142:145], v[18:33]
	global_load_dwordx4 v[94:97], v77, s[2:3] offset:768
	global_load_dwordx4 v[106:109], v77, s[4:5] offset:768
	s_waitcnt lgkmcnt(3)
	v_mfma_f32_32x32x16_bf16 v[34:49], v[118:121], v[130:133], v[34:49]
	s_waitcnt vmcnt(9)
	ds_write_b128 v75, v[110:113] offset:50688
	s_waitcnt vmcnt(8)
	ds_write_b128 v76, v[114:117] offset:13824
	v_mfma_f32_32x32x16_bf16 v[2:17], v[126:129], v[130:133], v[2:17]
	s_waitcnt lgkmcnt(4)
	v_mfma_f32_32x32x16_bf16 v[50:65], v[118:121], v[134:137], v[50:65]
	v_mfma_f32_32x32x16_bf16 v[18:33], v[126:129], v[134:137], v[18:33]
	s_waitcnt lgkmcnt(0)
	s_barrier
; #define GL1_(RA, RB, i) { RA[i] = *(const u32x4*)(ap + (aoff + (i) * astep)); if ((i) < NB) RB[(i) < NB ? (i) : 0] = *(const u32x4*)(bp + (boff + (i) * bstep)); }
; #define LS1_(RA, RB, ST, i) { char* sn_ = lds + (ST) * STAGE; *(u32x4*)(sn_ + wofs + (i) * 32 * LROW) = RA[i]; \
;                               if ((i) < NB) *(u32x4*)(sn_ + STAGE_OP + wofs + (i) * 32 * LROW) = RB[(i) < NB ? (i) : 0]; }
; template <int NJ> DI void gemm_mainloop_reg(const bf16_t* __restrict__ A, int lda, const bf16_t* __restrict__ Bt, int ldb, int K, f32x16 (&acc)[2][NJ], char* lds) {
;     ...
; #pragma unroll
;   for (int i = 0; i < 4; ++i) GL1_(ra0, rb0, i);
;   ap += 128; bp += 128;
; #pragma unroll
;   for (int i = 0; i < 4; ++i) GL1_(ra1, rb1, i);
;   ap += 128; bp += 128;
; #pragma unroll
;   for (int i = 0; i < 4; ++i) LS1_(ra0, rb0, 0, i);
;   __syncthreads();
;   const int nk = K >> 6;
;   for (int kt = 0; kt < nk; kt += 2) {
;     const bool l0 = (kt + 2 < nk), l1 = (kt + 3 < nk);
;     STEP_(0, l0, ra0, rb0, true, ra1, rb1);
;     __syncthreads();
;     STEP_(1, l1, ra1, rb1, l0, ra0, rb0);
;     __syncthreads();
;   }
	ds_read_b128 v[110:113], v73 offset:36864
	ds_read_b128 v[114:117], v74 offset:55296
	ds_read_b128 v[118:121], v73 offset:36896
	ds_read_b128 v[122:125], v74 offset:55328
	ds_read_b128 v[126:129], v73 offset:41472
	ds_read_b128 v[130:133], v73 offset:41504
	s_waitcnt lgkmcnt(4)
	v_mfma_f32_32x32x16_bf16 v[34:49], v[110:113], v[114:117], v[34:49]
	s_waitcnt lgkmcnt(1)
	v_mfma_f32_32x32x16_bf16 v[2:17], v[126:129], v[114:117], v[2:17]
	ds_read_b128 v[114:117], v74 offset:59904
	ds_read_b128 v[134:137], v74 offset:59936
	s_waitcnt lgkmcnt(1)
	v_mfma_f32_32x32x16_bf16 v[50:65], v[110:113], v[114:117], v[50:65]
	global_load_dwordx4 v[110:113], v80, s[2:3] offset:896
	global_load_dwordx4 v[142:145], v80, s[4:5] offset:896
	s_waitcnt vmcnt(9)
	ds_write_b128 v75, v[82:85]
	s_waitcnt vmcnt(8)
	ds_write_b128 v75, v[138:141] offset:18432
	v_mfma_f32_32x32x16_bf16 v[18:33], v[126:129], v[114:117], v[18:33]
	global_load_dwordx4 v[82:85], v79, s[2:3] offset:896
	global_load_dwordx4 v[114:117], v79, s[4:5] offset:896
	v_mfma_f32_32x32x16_bf16 v[34:49], v[118:121], v[122:125], v[34:49]
	v_mfma_f32_32x32x16_bf16 v[2:17], v[130:133], v[122:125], v[2:17]
	s_waitcnt lgkmcnt(2)
	v_mfma_f32_32x32x16_bf16 v[50:65], v[118:121], v[134:137], v[50:65]
	ds_read_b128 v[118:121], v73 offset:36928
	ds_read_b128 v[122:125], v73 offset:41536
	ds_read_b128 v[126:129], v74 offset:55360
	ds_read_b128 v[138:141], v74 offset:59968
	s_waitcnt vmcnt(9)
	ds_write_b128 v75, v[86:89] offset:4608
	s_waitcnt vmcnt(8)
	ds_write_b128 v75, v[98:101] offset:23040
	v_mfma_f32_32x32x16_bf16 v[18:33], v[130:133], v[134:137], v[18:33]
	global_load_dwordx4 v[86:89], v78, s[2:3] offset:896
	global_load_dwordx4 v[98:101], v78, s[4:5] offset:896
	s_waitcnt lgkmcnt(3)
	v_mfma_f32_32x32x16_bf16 v[34:49], v[118:121], v[126:129], v[34:49]
	v_mfma_f32_32x32x16_bf16 v[2:17], v[122:125], v[126:129], v[2:17]
	s_waitcnt lgkmcnt(2)
	v_mfma_f32_32x32x16_bf16 v[50:65], v[118:121], v[138:141], v[50:65]
	ds_read_b128 v[118:121], v73 offset:36960
	ds_read_b128 v[126:129], v73 offset:41568
	ds_read_b128 v[130:133], v74 offset:55392
	ds_read_b128 v[134:137], v74 offset:60000
	s_waitcnt vmcnt(9)
	ds_write_b128 v75, v[90:93] offset:9216
	s_waitcnt vmcnt(8)
	ds_write_b128 v75, v[102:105] offset:27648
	v_mfma_f32_32x32x16_bf16 v[18:33], v[122:125], v[138:141], v[18:33]
	global_load_dwordx4 v[90:93], v77, s[2:3] offset:896
	global_load_dwordx4 v[102:105], v77, s[4:5] offset:896
	s_waitcnt lgkmcnt(3)
	v_mfma_f32_32x32x16_bf16 v[34:49], v[118:121], v[130:133], v[34:49]
	s_waitcnt vmcnt(9)
	ds_write_b128 v75, v[94:97] offset:13824
	s_waitcnt vmcnt(8)
	ds_write_b128 v75, v[106:109] offset:32256
	v_mfma_f32_32x32x16_bf16 v[2:17], v[126:129], v[130:133], v[2:17]
	s_waitcnt lgkmcnt(4)
	v_mfma_f32_32x32x16_bf16 v[50:65], v[118:121], v[134:137], v[50:65]
	v_mfma_f32_32x32x16_bf16 v[18:33], v[126:129], v[134:137], v[18:33]
	s_waitcnt lgkmcnt(0)
	s_barrier
	ds_read_b128 v[94:97], v73
	ds_read_b128 v[106:109], v74 offset:18432
	ds_read_b128 v[118:121], v73 offset:32
	ds_read_b128 v[122:125], v74 offset:18464
	ds_read_b128 v[126:129], v73 offset:4608
	ds_read_b128 v[130:133], v73 offset:4640
	s_waitcnt lgkmcnt(4)
	v_mfma_f32_32x32x16_bf16 v[34:49], v[94:97], v[106:109], v[34:49]
	s_waitcnt lgkmcnt(1)
	v_mfma_f32_32x32x16_bf16 v[2:17], v[126:129], v[106:109], v[2:17]
	ds_read_b128 v[106:109], v74 offset:23040
	ds_read_b128 v[134:137], v74 offset:23072
	s_waitcnt lgkmcnt(1)
	v_mfma_f32_32x32x16_bf16 v[50:65], v[94:97], v[106:109], v[50:65]
	global_load_dwordx4 v[94:97], v80, s[2:3] offset:1024
	global_load_dwordx4 v[138:141], v80, s[4:5] offset:1024
	s_waitcnt vmcnt(9)
	ds_write_b128 v75, v[110:113] offset:36864
	s_waitcnt vmcnt(8)
	ds_write_b128 v75, v[142:145] offset:55296
	v_mfma_f32_32x32x16_bf16 v[18:33], v[126:129], v[106:109], v[18:33]
	global_load_dwordx4 v[106:109], v79, s[2:3] offset:1024
	global_load_dwordx4 v[110:113], v79, s[4:5] offset:1024
	v_mfma_f32_32x32x16_bf16 v[34:49], v[118:121], v[122:125], v[34:49]
	v_mfma_f32_32x32x16_bf16 v[2:17], v[130:133], v[122:125], v[2:17]
	s_waitcnt lgkmcnt(2)
	v_mfma_f32_32x32x16_bf16 v[50:65], v[118:121], v[134:137], v[50:65]
	ds_read_b128 v[118:121], v73 offset:64
	ds_read_b128 v[122:125], v73 offset:4672
	ds_read_b128 v[126:129], v74 offset:18496
	ds_read_b128 v[142:145], v74 offset:23104
	s_waitcnt vmcnt(9)
	ds_write_b128 v75, v[82:85] offset:41472
	s_waitcnt vmcnt(8)
	ds_write_b128 v75, v[114:117] offset:59904
	v_mfma_f32_32x32x16_bf16 v[18:33], v[130:133], v[134:137], v[18:33]
	global_load_dwordx4 v[82:85], v78, s[2:3] offset:1024
	global_load_dwordx4 v[114:117], v78, s[4:5] offset:1024
	s_waitcnt lgkmcnt(3)
	v_mfma_f32_32x32x16_bf16 v[34:49], v[118:121], v[126:129], v[34:49]
	v_mfma_f32_32x32x16_bf16 v[2:17], v[122:125], v[126:129], v[2:17]
	s_waitcnt lgkmcnt(2)
	v_mfma_f32_32x32x16_bf16 v[50:65], v[118:121], v[142:145], v[50:65]
	ds_read_b128 v[118:121], v73 offset:96
	ds_read_b128 v[126:129], v73 offset:4704
	ds_read_b128 v[130:133], v74 offset:18528
	ds_read_b128 v[134:137], v74 offset:23136
	s_waitcnt vmcnt(9)
	ds_write_b128 v75, v[86:89] offset:46080
	s_waitcnt vmcnt(8)
	ds_write_b128 v75, v[98:101] offset:64512
	v_mfma_f32_32x32x16_bf16 v[18:33], v[122:125], v[142:145], v[18:33]
	global_load_dwordx4 v[86:89], v77, s[2:3] offset:1024
	global_load_dwordx4 v[98:101], v77, s[4:5] offset:1024
	s_waitcnt lgkmcnt(3)
	v_mfma_f32_32x32x16_bf16 v[34:49], v[118:121], v[130:133], v[34:49]
	s_waitcnt vmcnt(9)
	ds_write_b128 v75, v[90:93] offset:50688
	s_waitcnt vmcnt(8)
	ds_write_b128 v76, v[102:105] offset:13824
	v_mfma_f32_32x32x16_bf16 v[2:17], v[126:129], v[130:133], v[2:17]
	s_waitcnt lgkmcnt(4)
	v_mfma_f32_32x32x16_bf16 v[50:65], v[118:121], v[134:137], v[50:65]
	v_mfma_f32_32x32x16_bf16 v[18:33], v[126:129], v[134:137], v[18:33]
	s_waitcnt lgkmcnt(0)
	s_barrier
; #define GL1_(RA, RB, i) { RA[i] = *(const u32x4*)(ap + (aoff + (i) * astep)); if ((i) < NB) RB[(i) < NB ? (i) : 0] = *(const u32x4*)(bp + (boff + (i) * bstep)); }
; #define LS1_(RA, RB, ST, i) { char* sn_ = lds + (ST) * STAGE; *(u32x4*)(sn_ + wofs + (i) * 32 * LROW) = RA[i]; \
;                               if ((i) < NB) *(u32x4*)(sn_ + STAGE_OP + wofs + (i) * 32 * LROW) = RB[(i) < NB ? (i) : 0]; }
; template <int NJ> DI void gemm_mainloop_reg(const bf16_t* __restrict__ A, int lda, const bf16_t* __restrict__ Bt, int ldb, int K, f32x16 (&acc)[2][NJ], char* lds) {
;     ...
; #pragma unroll
;   for (int i = 0; i < 4; ++i) GL1_(ra0, rb0, i);
;   ap += 128; bp += 128;
; #pragma unroll
;   for (int i = 0; i < 4; ++i) GL1_(ra1, rb1, i);
;   ap += 128; bp += 128;
; #pragma unroll
;   for (int i = 0; i < 4; ++i) LS1_(ra0, rb0, 0, i);
;   __syncthreads();
;   const int nk = K >> 6;
;   for (int kt = 0; kt < nk; kt += 2) {
;     const bool l0 = (kt + 2 < nk), l1 = (kt + 3 < nk);
;     STEP_(0, l0, ra0, rb0, true, ra1, rb1);
;     __syncthreads();
;     STEP_(1, l1, ra1, rb1, l0, ra0, rb0);
;     __syncthreads();
;   }
	ds_read_b128 v[90:93], v73 offset:36864
	ds_read_b128 v[102:105], v74 offset:55296
	ds_read_b128 v[118:121], v73 offset:36896
	ds_read_b128 v[122:125], v74 offset:55328
	ds_read_b128 v[126:129], v73 offset:41472
	ds_read_b128 v[130:133], v73 offset:41504
	s_waitcnt lgkmcnt(4)
	v_mfma_f32_32x32x16_bf16 v[34:49], v[90:93], v[102:105], v[34:49]
	s_waitcnt lgkmcnt(1)
	v_mfma_f32_32x32x16_bf16 v[2:17], v[126:129], v[102:105], v[2:17]
	ds_read_b128 v[102:105], v74 offset:59904
	ds_read_b128 v[134:137], v74 offset:59936
	s_waitcnt lgkmcnt(1)
	v_mfma_f32_32x32x16_bf16 v[50:65], v[90:93], v[102:105], v[50:65]
	global_load_dwordx4 v[90:93], v80, s[2:3] offset:1152
	global_load_dwordx4 v[142:145], v80, s[4:5] offset:1152
	s_waitcnt vmcnt(9)
	ds_write_b128 v75, v[94:97]
	s_waitcnt vmcnt(8)
	ds_write_b128 v75, v[138:141] offset:18432
	v_mfma_f32_32x32x16_bf16 v[18:33], v[126:129], v[102:105], v[18:33]
	global_load_dwordx4 v[94:97], v79, s[2:3] offset:1152
	global_load_dwordx4 v[102:105], v79, s[4:5] offset:1152
	v_mfma_f32_32x32x16_bf16 v[34:49], v[118:121], v[122:125], v[34:49]
	v_mfma_f32_32x32x16_bf16 v[2:17], v[130:133], v[122:125], v[2:17]
	s_waitcnt lgkmcnt(2)
	v_mfma_f32_32x32x16_bf16 v[50:65], v[118:121], v[134:137], v[50:65]
	ds_read_b128 v[118:121], v73 offset:36928
	ds_read_b128 v[122:125], v73 offset:41536
	ds_read_b128 v[126:129], v74 offset:55360
	ds_read_b128 v[138:141], v74 offset:59968
	s_waitcnt vmcnt(9)
	ds_write_b128 v75, v[106:109] offset:4608
	s_waitcnt vmcnt(8)
	ds_write_b128 v75, v[110:113] offset:23040
	v_mfma_f32_32x32x16_bf16 v[18:33], v[130:133], v[134:137], v[18:33]
	global_load_dwordx4 v[106:109], v78, s[2:3] offset:1152
	global_load_dwordx4 v[110:113], v78, s[4:5] offset:1152
	s_waitcnt lgkmcnt(3)
	v_mfma_f32_32x32x16_bf16 v[34:49], v[118:121], v[126:129], v[34:49]
	v_mfma_f32_32x32x16_bf16 v[2:17], v[122:125], v[126:129], v[2:17]
	s_waitcnt lgkmcnt(2)
	v_mfma_f32_32x32x16_bf16 v[50:65], v[118:121], v[138:141], v[50:65]
	ds_read_b128 v[118:121], v73 offset:36960
	ds_read_b128 v[126:129], v73 offset:41568
	ds_read_b128 v[130:133], v74 offset:55392
	ds_read_b128 v[134:137], v74 offset:60000
	s_waitcnt vmcnt(9)
	ds_write_b128 v75, v[82:85] offset:9216
	s_waitcnt vmcnt(8)
	ds_write_b128 v75, v[114:117] offset:27648
	v_mfma_f32_32x32x16_bf16 v[18:33], v[122:125], v[138:141], v[18:33]
	global_load_dwordx4 v[82:85], v77, s[2:3] offset:1152
	global_load_dwordx4 v[114:117], v77, s[4:5] offset:1152
	s_waitcnt lgkmcnt(3)
	v_mfma_f32_32x32x16_bf16 v[34:49], v[118:121], v[130:133], v[34:49]
	s_waitcnt vmcnt(9)
	ds_write_b128 v75, v[86:89] offset:13824
	s_waitcnt vmcnt(8)
	ds_write_b128 v75, v[98:101] offset:32256
	v_mfma_f32_32x32x16_bf16 v[2:17], v[126:129], v[130:133], v[2:17]
	s_waitcnt lgkmcnt(4)
	v_mfma_f32_32x32x16_bf16 v[50:65], v[118:121], v[134:137], v[50:65]
	v_mfma_f32_32x32x16_bf16 v[18:33], v[126:129], v[134:137], v[18:33]
	s_waitcnt lgkmcnt(0)
	s_barrier
	ds_read_b128 v[86:89], v73
	ds_read_b128 v[98:101], v74 offset:18432
	ds_read_b128 v[118:121], v73 offset:32
	ds_read_b128 v[122:125], v74 offset:18464
	ds_read_b128 v[126:129], v73 offset:4608
	ds_read_b128 v[130:133], v73 offset:4640
	s_waitcnt lgkmcnt(4)
	v_mfma_f32_32x32x16_bf16 v[34:49], v[86:89], v[98:101], v[34:49]
	s_waitcnt lgkmcnt(1)
	v_mfma_f32_32x32x16_bf16 v[2:17], v[126:129], v[98:101], v[2:17]
	ds_read_b128 v[98:101], v74 offset:23040
	ds_read_b128 v[134:137], v74 offset:23072
	s_waitcnt lgkmcnt(1)
	v_mfma_f32_32x32x16_bf16 v[50:65], v[86:89], v[98:101], v[50:65]
	global_load_dwordx4 v[86:89], v80, s[2:3] offset:1280
	global_load_dwordx4 v[138:141], v80, s[4:5] offset:1280
	s_waitcnt vmcnt(9)
	ds_write_b128 v75, v[90:93] offset:36864
	s_waitcnt vmcnt(8)
	ds_write_b128 v75, v[142:145] offset:55296
	v_mfma_f32_32x32x16_bf16 v[18:33], v[126:129], v[98:101], v[18:33]
	global_load_dwordx4 v[90:93], v79, s[2:3] offset:1280
	global_load_dwordx4 v[98:101], v79, s[4:5] offset:1280
	v_mfma_f32_32x32x16_bf16 v[34:49], v[118:121], v[122:125], v[34:49]
	v_mfma_f32_32x32x16_bf16 v[2:17], v[130:133], v[122:125], v[2:17]
	s_waitcnt lgkmcnt(2)
	v_mfma_f32_32x32x16_bf16 v[50:65], v[118:121], v[134:137], v[50:65]
	ds_read_b128 v[118:121], v73 offset:64
	ds_read_b128 v[122:125], v73 offset:4672
	ds_read_b128 v[126:129], v74 offset:18496
	ds_read_b128 v[142:145], v74 offset:23104
	s_waitcnt vmcnt(9)
	ds_write_b128 v75, v[94:97] offset:41472
	s_waitcnt vmcnt(8)
	ds_write_b128 v75, v[102:105] offset:59904
	v_mfma_f32_32x32x16_bf16 v[18:33], v[130:133], v[134:137], v[18:33]
	global_load_dwordx4 v[94:97], v78, s[2:3] offset:1280
	global_load_dwordx4 v[102:105], v78, s[4:5] offset:1280
	s_waitcnt lgkmcnt(3)
	v_mfma_f32_32x32x16_bf16 v[34:49], v[118:121], v[126:129], v[34:49]
	v_mfma_f32_32x32x16_bf16 v[2:17], v[122:125], v[126:129], v[2:17]
	s_waitcnt lgkmcnt(2)
	v_mfma_f32_32x32x16_bf16 v[50:65], v[118:121], v[142:145], v[50:65]
	ds_read_b128 v[118:121], v73 offset:96
	ds_read_b128 v[126:129], v73 offset:4704
	ds_read_b128 v[130:133], v74 offset:18528
	ds_read_b128 v[134:137], v74 offset:23136
	s_waitcnt vmcnt(9)
	ds_write_b128 v75, v[106:109] offset:46080
	s_waitcnt vmcnt(8)
	ds_write_b128 v75, v[110:113] offset:64512
	v_mfma_f32_32x32x16_bf16 v[18:33], v[122:125], v[142:145], v[18:33]
	global_load_dwordx4 v[106:109], v77, s[2:3] offset:1280
	global_load_dwordx4 v[110:113], v77, s[4:5] offset:1280
	s_waitcnt lgkmcnt(3)
	v_mfma_f32_32x32x16_bf16 v[34:49], v[118:121], v[130:133], v[34:49]
	s_waitcnt vmcnt(9)
	ds_write_b128 v75, v[82:85] offset:50688
	s_waitcnt vmcnt(8)
	ds_write_b128 v76, v[114:117] offset:13824
	v_mfma_f32_32x32x16_bf16 v[2:17], v[126:129], v[130:133], v[2:17]
	s_waitcnt lgkmcnt(4)
	v_mfma_f32_32x32x16_bf16 v[50:65], v[118:121], v[134:137], v[50:65]
	v_mfma_f32_32x32x16_bf16 v[18:33], v[126:129], v[134:137], v[18:33]
	s_waitcnt lgkmcnt(0)
	s_barrier
; #define GL1_(RA, RB, i) { RA[i] = *(const u32x4*)(ap + (aoff + (i) * astep)); if ((i) < NB) RB[(i) < NB ? (i) : 0] = *(const u32x4*)(bp + (boff + (i) * bstep)); }
; #define LS1_(RA, RB, ST, i) { char* sn_ = lds + (ST) * STAGE; *(u32x4*)(sn_ + wofs + (i) * 32 * LROW) = RA[i]; \
;                               if ((i) < NB) *(u32x4*)(sn_ + STAGE_OP + wofs + (i) * 32 * LROW) = RB[(i) < NB ? (i) : 0]; }
; template <int NJ> DI void gemm_mainloop_reg(const bf16_t* __restrict__ A, int lda, const bf16_t* __restrict__ Bt, int ldb, int K, f32x16 (&acc)[2][NJ], char* lds) {
;     ...
; #pragma unroll
;   for (int i = 0; i < 4; ++i) GL1_(ra0, rb0, i);
;   ap += 128; bp += 128;
; #pragma unroll
;   for (int i = 0; i < 4; ++i) GL1_(ra1, rb1, i);
;   ap += 128; bp += 128;
; #pragma unroll
;   for (int i = 0; i < 4; ++i) LS1_(ra0, rb0, 0, i);
;   __syncthreads();
;   const int nk = K >> 6;
;   for (int kt = 0; kt < nk; kt += 2) {
;     const bool l0 = (kt + 2 < nk), l1 = (kt + 3 < nk);
;     STEP_(0, l0, ra0, rb0, true, ra1, rb1);
;     __syncthreads();
;     STEP_(1, l1, ra1, rb1, l0, ra0, rb0);
;     __syncthreads();
;   }
	ds_read_b128 v[82:85], v73 offset:36864
	ds_read_b128 v[114:117], v74 offset:55296
	ds_read_b128 v[118:121], v73 offset:36896
	ds_read_b128 v[122:125], v74 offset:55328
	ds_read_b128 v[126:129], v73 offset:41472
	ds_read_b128 v[130:133], v73 offset:41504
	s_waitcnt lgkmcnt(4)
	v_mfma_f32_32x32x16_bf16 v[34:49], v[82:85], v[114:117], v[34:49]
	s_waitcnt lgkmcnt(1)
	v_mfma_f32_32x32x16_bf16 v[2:17], v[126:129], v[114:117], v[2:17]
	ds_read_b128 v[114:117], v74 offset:59904
	ds_read_b128 v[134:137], v74 offset:59936
	s_waitcnt lgkmcnt(1)
	v_mfma_f32_32x32x16_bf16 v[50:65], v[82:85], v[114:117], v[50:65]
	global_load_dwordx4 v[82:85], v80, s[2:3] offset:1408
	global_load_dwordx4 v[142:145], v80, s[4:5] offset:1408
	s_waitcnt vmcnt(9)
	ds_write_b128 v75, v[86:89]
	s_waitcnt vmcnt(8)
	ds_write_b128 v75, v[138:141] offset:18432
	v_mfma_f32_32x32x16_bf16 v[18:33], v[126:129], v[114:117], v[18:33]
	global_load_dwordx4 v[86:89], v79, s[2:3] offset:1408
	global_load_dwordx4 v[114:117], v79, s[4:5] offset:1408
	v_mfma_f32_32x32x16_bf16 v[34:49], v[118:121], v[122:125], v[34:49]
	v_mfma_f32_32x32x16_bf16 v[2:17], v[130:133], v[122:125], v[2:17]
	s_waitcnt lgkmcnt(2)
	v_mfma_f32_32x32x16_bf16 v[50:65], v[118:121], v[134:137], v[50:65]
	ds_read_b128 v[118:121], v73 offset:36928
	ds_read_b128 v[122:125], v73 offset:41536
	ds_read_b128 v[126:129], v74 offset:55360
	ds_read_b128 v[138:141], v74 offset:59968
	s_waitcnt vmcnt(9)
	ds_write_b128 v75, v[90:93] offset:4608
	s_waitcnt vmcnt(8)
	ds_write_b128 v75, v[98:101] offset:23040
	v_mfma_f32_32x32x16_bf16 v[18:33], v[130:133], v[134:137], v[18:33]
	global_load_dwordx4 v[90:93], v78, s[2:3] offset:1408
	global_load_dwordx4 v[98:101], v78, s[4:5] offset:1408
	s_waitcnt lgkmcnt(3)
	v_mfma_f32_32x32x16_bf16 v[34:49], v[118:121], v[126:129], v[34:49]
	v_mfma_f32_32x32x16_bf16 v[2:17], v[122:125], v[126:129], v[2:17]
	s_waitcnt lgkmcnt(2)
	v_mfma_f32_32x32x16_bf16 v[50:65], v[118:121], v[138:141], v[50:65]
	ds_read_b128 v[118:121], v73 offset:36960
	ds_read_b128 v[126:129], v73 offset:41568
	ds_read_b128 v[130:133], v74 offset:55392
	ds_read_b128 v[134:137], v74 offset:60000
	s_waitcnt vmcnt(9)
	ds_write_b128 v75, v[94:97] offset:9216
	s_waitcnt vmcnt(8)
	ds_write_b128 v75, v[102:105] offset:27648
	v_mfma_f32_32x32x16_bf16 v[18:33], v[122:125], v[138:141], v[18:33]
	global_load_dwordx4 v[94:97], v77, s[2:3] offset:1408
	global_load_dwordx4 v[102:105], v77, s[4:5] offset:1408
	s_waitcnt lgkmcnt(3)
	v_mfma_f32_32x32x16_bf16 v[34:49], v[118:121], v[130:133], v[34:49]
	s_waitcnt vmcnt(9)
	ds_write_b128 v75, v[106:109] offset:13824
	s_waitcnt vmcnt(8)
	ds_write_b128 v75, v[110:113] offset:32256
	v_mfma_f32_32x32x16_bf16 v[2:17], v[126:129], v[130:133], v[2:17]
	s_waitcnt lgkmcnt(4)
	v_mfma_f32_32x32x16_bf16 v[50:65], v[118:121], v[134:137], v[50:65]
	v_mfma_f32_32x32x16_bf16 v[18:33], v[126:129], v[134:137], v[18:33]
	s_waitcnt lgkmcnt(0)
	s_barrier
	ds_read_b128 v[106:109], v73
	ds_read_b128 v[110:113], v74 offset:18432
	ds_read_b128 v[118:121], v73 offset:32
	ds_read_b128 v[122:125], v74 offset:18464
	ds_read_b128 v[126:129], v73 offset:4608
	ds_read_b128 v[130:133], v73 offset:4640
	s_waitcnt lgkmcnt(4)
	v_mfma_f32_32x32x16_bf16 v[34:49], v[106:109], v[110:113], v[34:49]
	s_waitcnt lgkmcnt(1)
	v_mfma_f32_32x32x16_bf16 v[2:17], v[126:129], v[110:113], v[2:17]
	ds_read_b128 v[110:113], v74 offset:23040
	ds_read_b128 v[134:137], v74 offset:23072
	s_waitcnt lgkmcnt(1)
	v_mfma_f32_32x32x16_bf16 v[50:65], v[106:109], v[110:113], v[50:65]
	global_load_dwordx4 v[106:109], v80, s[2:3] offset:1536
	global_load_dwordx4 v[138:141], v80, s[4:5] offset:1536
	s_waitcnt vmcnt(9)
	ds_write_b128 v75, v[82:85] offset:36864
	s_waitcnt vmcnt(8)
	ds_write_b128 v75, v[142:145] offset:55296
	v_mfma_f32_32x32x16_bf16 v[18:33], v[126:129], v[110:113], v[18:33]
	global_load_dwordx4 v[82:85], v79, s[2:3] offset:1536
	global_load_dwordx4 v[110:113], v79, s[4:5] offset:1536
	v_mfma_f32_32x32x16_bf16 v[34:49], v[118:121], v[122:125], v[34:49]
	v_mfma_f32_32x32x16_bf16 v[2:17], v[130:133], v[122:125], v[2:17]
	s_waitcnt lgkmcnt(2)
	v_mfma_f32_32x32x16_bf16 v[50:65], v[118:121], v[134:137], v[50:65]
	ds_read_b128 v[118:121], v73 offset:64
	ds_read_b128 v[122:125], v73 offset:4672
	ds_read_b128 v[126:129], v74 offset:18496
	ds_read_b128 v[142:145], v74 offset:23104
	s_waitcnt vmcnt(9)
	ds_write_b128 v75, v[86:89] offset:41472
	s_waitcnt vmcnt(8)
	ds_write_b128 v75, v[114:117] offset:59904
	v_mfma_f32_32x32x16_bf16 v[18:33], v[130:133], v[134:137], v[18:33]
	global_load_dwordx4 v[86:89], v78, s[2:3] offset:1536
	global_load_dwordx4 v[114:117], v78, s[4:5] offset:1536
	s_waitcnt lgkmcnt(3)
	v_mfma_f32_32x32x16_bf16 v[34:49], v[118:121], v[126:129], v[34:49]
	v_mfma_f32_32x32x16_bf16 v[2:17], v[122:125], v[126:129], v[2:17]
	s_waitcnt lgkmcnt(2)
	v_mfma_f32_32x32x16_bf16 v[50:65], v[118:121], v[142:145], v[50:65]
	ds_read_b128 v[118:121], v73 offset:96
	ds_read_b128 v[126:129], v73 offset:4704
	ds_read_b128 v[130:133], v74 offset:18528
	ds_read_b128 v[134:137], v74 offset:23136
	s_waitcnt vmcnt(9)
	ds_write_b128 v75, v[90:93] offset:46080
	s_waitcnt vmcnt(8)
	ds_write_b128 v75, v[98:101] offset:64512
	v_mfma_f32_32x32x16_bf16 v[18:33], v[122:125], v[142:145], v[18:33]
	global_load_dwordx4 v[90:93], v77, s[2:3] offset:1536
	global_load_dwordx4 v[98:101], v77, s[4:5] offset:1536
	s_waitcnt lgkmcnt(3)
	v_mfma_f32_32x32x16_bf16 v[34:49], v[118:121], v[130:133], v[34:49]
	s_waitcnt vmcnt(9)
	ds_write_b128 v75, v[94:97] offset:50688
	s_waitcnt vmcnt(8)
	ds_write_b128 v76, v[102:105] offset:13824
	v_mfma_f32_32x32x16_bf16 v[2:17], v[126:129], v[130:133], v[2:17]
	s_waitcnt lgkmcnt(4)
	v_mfma_f32_32x32x16_bf16 v[50:65], v[118:121], v[134:137], v[50:65]
	v_mfma_f32_32x32x16_bf16 v[18:33], v[126:129], v[134:137], v[18:33]
	s_waitcnt lgkmcnt(0)
	s_barrier
; #define GL1_(RA, RB, i) { RA[i] = *(const u32x4*)(ap + (aoff + (i) * astep)); if ((i) < NB) RB[(i) < NB ? (i) : 0] = *(const u32x4*)(bp + (boff + (i) * bstep)); }
; #define LS1_(RA, RB, ST, i) { char* sn_ = lds + (ST) * STAGE; *(u32x4*)(sn_ + wofs + (i) * 32 * LROW) = RA[i]; \
;                               if ((i) < NB) *(u32x4*)(sn_ + STAGE_OP + wofs + (i) * 32 * LROW) = RB[(i) < NB ? (i) : 0]; }
; template <int NJ> DI void gemm_mainloop_reg(const bf16_t* __restrict__ A, int lda, const bf16_t* __restrict__ Bt, int ldb, int K, f32x16 (&acc)[2][NJ], char* lds) {
;     ...
; #pragma unroll
;   for (int i = 0; i < 4; ++i) GL1_(ra0, rb0, i);
;   ap += 128; bp += 128;
; #pragma unroll
;   for (int i = 0; i < 4; ++i) GL1_(ra1, rb1, i);
;   ap += 128; bp += 128;
; #pragma unroll
;   for (int i = 0; i < 4; ++i) LS1_(ra0, rb0, 0, i);
;   __syncthreads();
;   const int nk = K >> 6;
;   for (int kt = 0; kt < nk; kt += 2) {
;     const bool l0 = (kt + 2 < nk), l1 = (kt + 3 < nk);
;     STEP_(0, l0, ra0, rb0, true, ra1, rb1);
;     __syncthreads();
;     STEP_(1, l1, ra1, rb1, l0, ra0, rb0);
;     __syncthreads();
;   }
	ds_read_b128 v[94:97], v73 offset:36864
	ds_read_b128 v[102:105], v74 offset:55296
	ds_read_b128 v[118:121], v73 offset:36896
	ds_read_b128 v[122:125], v74 offset:55328
	ds_read_b128 v[126:129], v73 offset:41472
	ds_read_b128 v[130:133], v73 offset:41504
	s_waitcnt lgkmcnt(4)
	v_mfma_f32_32x32x16_bf16 v[34:49], v[94:97], v[102:105], v[34:49]
	s_waitcnt lgkmcnt(1)
	v_mfma_f32_32x32x16_bf16 v[2:17], v[126:129], v[102:105], v[2:17]
	ds_read_b128 v[102:105], v74 offset:59904
	ds_read_b128 v[134:137], v74 offset:59936
	s_waitcnt lgkmcnt(1)
	v_mfma_f32_32x32x16_bf16 v[50:65], v[94:97], v[102:105], v[50:65]
	global_load_dwordx4 v[94:97], v80, s[2:3] offset:1664
	global_load_dwordx4 v[142:145], v80, s[4:5] offset:1664
	s_waitcnt vmcnt(9)
	ds_write_b128 v75, v[106:109]
	s_waitcnt vmcnt(8)
	ds_write_b128 v75, v[138:141] offset:18432
	v_mfma_f32_32x32x16_bf16 v[18:33], v[126:129], v[102:105], v[18:33]
	global_load_dwordx4 v[102:105], v79, s[2:3] offset:1664
	global_load_dwordx4 v[106:109], v79, s[4:5] offset:1664
	v_mfma_f32_32x32x16_bf16 v[34:49], v[118:121], v[122:125], v[34:49]
	v_mfma_f32_32x32x16_bf16 v[2:17], v[130:133], v[122:125], v[2:17]
	s_waitcnt lgkmcnt(2)
	v_mfma_f32_32x32x16_bf16 v[50:65], v[118:121], v[134:137], v[50:65]
	ds_read_b128 v[118:121], v73 offset:36928
	ds_read_b128 v[122:125], v73 offset:41536
	ds_read_b128 v[126:129], v74 offset:55360
	ds_read_b128 v[138:141], v74 offset:59968
	s_waitcnt vmcnt(9)
	ds_write_b128 v75, v[82:85] offset:4608
	s_waitcnt vmcnt(8)
	ds_write_b128 v75, v[110:113] offset:23040
	v_mfma_f32_32x32x16_bf16 v[18:33], v[130:133], v[134:137], v[18:33]
	global_load_dwordx4 v[82:85], v78, s[2:3] offset:1664
	global_load_dwordx4 v[110:113], v78, s[4:5] offset:1664
	s_waitcnt lgkmcnt(3)
	v_mfma_f32_32x32x16_bf16 v[34:49], v[118:121], v[126:129], v[34:49]
	v_mfma_f32_32x32x16_bf16 v[2:17], v[122:125], v[126:129], v[2:17]
	s_waitcnt lgkmcnt(2)
	v_mfma_f32_32x32x16_bf16 v[50:65], v[118:121], v[138:141], v[50:65]
	ds_read_b128 v[118:121], v73 offset:36960
	ds_read_b128 v[126:129], v73 offset:41568
	ds_read_b128 v[130:133], v74 offset:55392
	ds_read_b128 v[134:137], v74 offset:60000
	s_waitcnt vmcnt(9)
	ds_write_b128 v75, v[86:89] offset:9216
	s_waitcnt vmcnt(8)
	ds_write_b128 v75, v[114:117] offset:27648
	v_mfma_f32_32x32x16_bf16 v[18:33], v[122:125], v[138:141], v[18:33]
	global_load_dwordx4 v[86:89], v77, s[2:3] offset:1664
	global_load_dwordx4 v[114:117], v77, s[4:5] offset:1664
	s_waitcnt lgkmcnt(3)
	v_mfma_f32_32x32x16_bf16 v[34:49], v[118:121], v[130:133], v[34:49]
	s_waitcnt vmcnt(9)
	ds_write_b128 v75, v[90:93] offset:13824
	s_waitcnt vmcnt(8)
	ds_write_b128 v75, v[98:101] offset:32256
	v_mfma_f32_32x32x16_bf16 v[2:17], v[126:129], v[130:133], v[2:17]
	s_waitcnt lgkmcnt(4)
	v_mfma_f32_32x32x16_bf16 v[50:65], v[118:121], v[134:137], v[50:65]
	v_mfma_f32_32x32x16_bf16 v[18:33], v[126:129], v[134:137], v[18:33]
	s_waitcnt lgkmcnt(0)
	s_barrier
	ds_read_b128 v[90:93], v73
	ds_read_b128 v[98:101], v74 offset:18432
	ds_read_b128 v[118:121], v73 offset:32
	ds_read_b128 v[122:125], v74 offset:18464
	ds_read_b128 v[126:129], v73 offset:4608
	ds_read_b128 v[130:133], v73 offset:4640
	s_waitcnt lgkmcnt(4)
	v_mfma_f32_32x32x16_bf16 v[34:49], v[90:93], v[98:101], v[34:49]
	s_waitcnt lgkmcnt(1)
	v_mfma_f32_32x32x16_bf16 v[2:17], v[126:129], v[98:101], v[2:17]
	ds_read_b128 v[98:101], v74 offset:23040
	ds_read_b128 v[134:137], v74 offset:23072
	s_waitcnt lgkmcnt(1)
	v_mfma_f32_32x32x16_bf16 v[50:65], v[90:93], v[98:101], v[50:65]
	global_load_dwordx4 v[90:93], v80, s[2:3] offset:1792
	global_load_dwordx4 v[138:141], v80, s[4:5] offset:1792
	s_waitcnt vmcnt(9)
	ds_write_b128 v75, v[94:97] offset:36864
	s_waitcnt vmcnt(8)
	ds_write_b128 v75, v[142:145] offset:55296
	v_mfma_f32_32x32x16_bf16 v[18:33], v[126:129], v[98:101], v[18:33]
	global_load_dwordx4 v[94:97], v79, s[2:3] offset:1792
	global_load_dwordx4 v[98:101], v79, s[4:5] offset:1792
	v_mfma_f32_32x32x16_bf16 v[34:49], v[118:121], v[122:125], v[34:49]
	v_mfma_f32_32x32x16_bf16 v[2:17], v[130:133], v[122:125], v[2:17]
	s_waitcnt lgkmcnt(2)
	v_mfma_f32_32x32x16_bf16 v[50:65], v[118:121], v[134:137], v[50:65]
	ds_read_b128 v[118:121], v73 offset:64
	ds_read_b128 v[122:125], v73 offset:4672
	ds_read_b128 v[126:129], v74 offset:18496
	ds_read_b128 v[142:145], v74 offset:23104
	s_waitcnt vmcnt(9)
	ds_write_b128 v75, v[102:105] offset:41472
	s_waitcnt vmcnt(8)
	ds_write_b128 v75, v[106:109] offset:59904
	v_mfma_f32_32x32x16_bf16 v[18:33], v[130:133], v[134:137], v[18:33]
	global_load_dwordx4 v[102:105], v78, s[2:3] offset:1792
	global_load_dwordx4 v[106:109], v78, s[4:5] offset:1792
	s_waitcnt lgkmcnt(3)
	v_mfma_f32_32x32x16_bf16 v[34:49], v[118:121], v[126:129], v[34:49]
	v_mfma_f32_32x32x16_bf16 v[2:17], v[122:125], v[126:129], v[2:17]
	s_waitcnt lgkmcnt(2)
	v_mfma_f32_32x32x16_bf16 v[50:65], v[118:121], v[142:145], v[50:65]
	ds_read_b128 v[118:121], v73 offset:96
	ds_read_b128 v[126:129], v73 offset:4704
	ds_read_b128 v[130:133], v74 offset:18528
	ds_read_b128 v[134:137], v74 offset:23136
	s_waitcnt vmcnt(9)
	ds_write_b128 v75, v[82:85] offset:46080
	s_waitcnt vmcnt(8)
	ds_write_b128 v75, v[110:113] offset:64512
	v_mfma_f32_32x32x16_bf16 v[18:33], v[122:125], v[142:145], v[18:33]
	global_load_dwordx4 v[82:85], v77, s[2:3] offset:1792
	global_load_dwordx4 v[110:113], v77, s[4:5] offset:1792
	s_waitcnt lgkmcnt(3)
	v_mfma_f32_32x32x16_bf16 v[34:49], v[118:121], v[130:133], v[34:49]
	s_waitcnt vmcnt(9)
	ds_write_b128 v75, v[86:89] offset:50688
	s_waitcnt vmcnt(8)
	ds_write_b128 v76, v[114:117] offset:13824
	v_mfma_f32_32x32x16_bf16 v[2:17], v[126:129], v[130:133], v[2:17]
	s_waitcnt lgkmcnt(4)
	v_mfma_f32_32x32x16_bf16 v[50:65], v[118:121], v[134:137], v[50:65]
	v_mfma_f32_32x32x16_bf16 v[18:33], v[126:129], v[134:137], v[18:33]
	s_waitcnt lgkmcnt(0)
	s_barrier
; #define GL1_(RA, RB, i) { RA[i] = *(const u32x4*)(ap + (aoff + (i) * astep)); if ((i) < NB) RB[(i) < NB ? (i) : 0] = *(const u32x4*)(bp + (boff + (i) * bstep)); }
; #define LS1_(RA, RB, ST, i) { char* sn_ = lds + (ST) * STAGE; *(u32x4*)(sn_ + wofs + (i) * 32 * LROW) = RA[i]; \
;                               if ((i) < NB) *(u32x4*)(sn_ + STAGE_OP + wofs + (i) * 32 * LROW) = RB[(i) < NB ? (i) : 0]; }
; template <int NJ> DI void gemm_mainloop_reg(const bf16_t* __restrict__ A, int lda, const bf16_t* __restrict__ Bt, int ldb, int K, f32x16 (&acc)[2][NJ], char* lds) {
;     ...
; #pragma unroll
;   for (int i = 0; i < 4; ++i) GL1_(ra0, rb0, i);
;   ap += 128; bp += 128;
; #pragma unroll
;   for (int i = 0; i < 4; ++i) GL1_(ra1, rb1, i);
;   ap += 128; bp += 128;
; #pragma unroll
;   for (int i = 0; i < 4; ++i) LS1_(ra0, rb0, 0, i);
;   __syncthreads();
;   const int nk = K >> 6;
;   for (int kt = 0; kt < nk; kt += 2) {
;     const bool l0 = (kt + 2 < nk), l1 = (kt + 3 < nk);
;     STEP_(0, l0, ra0, rb0, true, ra1, rb1);
;     __syncthreads();
;     STEP_(1, l1, ra1, rb1, l0, ra0, rb0);
;     __syncthreads();
;   }
	ds_read_b128 v[86:89], v73 offset:36864
	ds_read_b128 v[114:117], v74 offset:55296
	ds_read_b128 v[118:121], v73 offset:41472
	s_waitcnt lgkmcnt(1)
	v_mfma_f32_32x32x16_bf16 v[34:49], v[86:89], v[114:117], v[34:49]
	s_waitcnt lgkmcnt(0)
	v_mfma_f32_32x32x16_bf16 v[2:17], v[118:121], v[114:117], v[2:17]
	ds_read_b128 v[114:117], v74 offset:59904
	s_waitcnt lgkmcnt(0)
	v_mfma_f32_32x32x16_bf16 v[50:65], v[86:89], v[114:117], v[50:65]
	global_load_dwordx4 v[86:89], v80, s[2:3] offset:1920
	global_load_dwordx4 v[122:125], v80, s[4:5] offset:1920
	ds_read_b128 v[126:129], v73 offset:36896
	ds_read_b128 v[130:133], v74 offset:55328
	ds_read_b128 v[134:137], v73 offset:41504
	ds_read_b128 v[142:145], v74 offset:59936
	s_waitcnt vmcnt(9)
	ds_write_b128 v75, v[90:93]
	s_waitcnt vmcnt(8)
	ds_write_b128 v75, v[138:141] offset:18432
	v_mfma_f32_32x32x16_bf16 v[18:33], v[118:121], v[114:117], v[18:33]
	global_load_dwordx4 v[90:93], v79, s[2:3] offset:1920
	global_load_dwordx4 v[114:117], v79, s[4:5] offset:1920
	s_waitcnt lgkmcnt(4)
	v_mfma_f32_32x32x16_bf16 v[34:49], v[126:129], v[130:133], v[34:49]
	s_waitcnt lgkmcnt(3)
	v_mfma_f32_32x32x16_bf16 v[2:17], v[134:137], v[130:133], v[2:17]
	s_waitcnt lgkmcnt(2)
	v_mfma_f32_32x32x16_bf16 v[50:65], v[126:129], v[142:145], v[50:65]
	ds_read_b128 v[118:121], v73 offset:36928
	ds_read_b128 v[126:129], v73 offset:41536
	ds_read_b128 v[130:133], v74 offset:55360
	ds_read_b128 v[138:141], v74 offset:59968
	s_waitcnt vmcnt(9)
	ds_write_b128 v75, v[94:97] offset:4608
	s_waitcnt vmcnt(8)
	ds_write_b128 v75, v[98:101] offset:23040
	v_mfma_f32_32x32x16_bf16 v[18:33], v[134:137], v[142:145], v[18:33]
	global_load_dwordx4 v[94:97], v78, s[2:3] offset:1920
	s_nop 0
	global_load_dwordx4 v[78:81], v78, s[4:5] offset:1920
	s_waitcnt lgkmcnt(3)
	v_mfma_f32_32x32x16_bf16 v[34:49], v[118:121], v[130:133], v[34:49]
	v_mfma_f32_32x32x16_bf16 v[2:17], v[126:129], v[130:133], v[2:17]
	s_waitcnt lgkmcnt(2)
	v_mfma_f32_32x32x16_bf16 v[50:65], v[118:121], v[138:141], v[50:65]
	ds_read_b128 v[98:101], v73 offset:36960
	ds_read_b128 v[118:121], v73 offset:41568
	ds_read_b128 v[130:133], v74 offset:55392
	ds_read_b128 v[134:137], v74 offset:60000
	s_waitcnt vmcnt(9)
	ds_write_b128 v75, v[102:105] offset:9216
	s_waitcnt vmcnt(8)
	ds_write_b128 v75, v[106:109] offset:27648
	v_mfma_f32_32x32x16_bf16 v[18:33], v[126:129], v[138:141], v[18:33]
	s_waitcnt lgkmcnt(3)
	v_mfma_f32_32x32x16_bf16 v[34:49], v[98:101], v[130:133], v[34:49]
	s_waitcnt lgkmcnt(2)
	v_mfma_f32_32x32x16_bf16 v[50:65], v[98:101], v[134:137], v[50:65]
	global_load_dwordx4 v[98:101], v77, s[2:3] offset:1920
	global_load_dwordx4 v[102:105], v77, s[4:5] offset:1920
	s_waitcnt vmcnt(9)
	ds_write_b128 v75, v[82:85] offset:13824
	s_waitcnt vmcnt(8)
	ds_write_b128 v75, v[110:113] offset:32256
	v_mfma_f32_32x32x16_bf16 v[2:17], v[118:121], v[130:133], v[2:17]
	v_mfma_f32_32x32x16_bf16 v[18:33], v[118:121], v[134:137], v[18:33]
	s_waitcnt lgkmcnt(0)
	s_barrier
	ds_read_b128 v[82:85], v73
	ds_read_b128 v[106:109], v74 offset:18432
	ds_read_b128 v[110:113], v73 offset:4608
	s_waitcnt lgkmcnt(1)
	v_mfma_f32_32x32x16_bf16 v[34:49], v[82:85], v[106:109], v[34:49]
	s_waitcnt lgkmcnt(0)
	v_mfma_f32_32x32x16_bf16 v[2:17], v[110:113], v[106:109], v[2:17]
	ds_read_b128 v[106:109], v74 offset:23040
	s_waitcnt lgkmcnt(0)
	v_mfma_f32_32x32x16_bf16 v[50:65], v[82:85], v[106:109], v[50:65]
	ds_read_b128 v[82:85], v73 offset:32
	ds_read_b128 v[118:121], v74 offset:18464
	ds_read_b128 v[126:129], v73 offset:4640
	ds_read_b128 v[130:133], v74 offset:23072
	s_waitcnt vmcnt(7)
	ds_write_b128 v75, v[86:89] offset:36864
	s_waitcnt vmcnt(6)
	ds_write_b128 v75, v[122:125] offset:55296
	v_mfma_f32_32x32x16_bf16 v[18:33], v[110:113], v[106:109], v[18:33]
	s_waitcnt lgkmcnt(4)
	v_mfma_f32_32x32x16_bf16 v[34:49], v[82:85], v[118:121], v[34:49]
	s_waitcnt lgkmcnt(2)
	v_mfma_f32_32x32x16_bf16 v[50:65], v[82:85], v[130:133], v[50:65]
	ds_read_b128 v[82:85], v73 offset:64
	ds_read_b128 v[86:89], v73 offset:4672
	ds_read_b128 v[106:109], v74 offset:18496
	ds_read_b128 v[110:113], v74 offset:23104
	s_waitcnt vmcnt(5)
	ds_write_b128 v75, v[90:93] offset:41472
	s_waitcnt vmcnt(4)
	ds_write_b128 v75, v[114:117] offset:59904
	v_mfma_f32_32x32x16_bf16 v[2:17], v[126:129], v[118:121], v[2:17]
	v_mfma_f32_32x32x16_bf16 v[18:33], v[126:129], v[130:133], v[18:33]
	s_waitcnt lgkmcnt(3)
	v_mfma_f32_32x32x16_bf16 v[34:49], v[82:85], v[106:109], v[34:49]
	v_mfma_f32_32x32x16_bf16 v[2:17], v[86:89], v[106:109], v[2:17]
	s_waitcnt lgkmcnt(2)
	v_mfma_f32_32x32x16_bf16 v[50:65], v[82:85], v[110:113], v[50:65]
	ds_read_b128 v[82:85], v73 offset:96
	ds_read_b128 v[90:93], v73 offset:4704
	ds_read_b128 v[106:109], v74 offset:18528
	ds_read_b128 v[114:117], v74 offset:23136
	s_waitcnt vmcnt(3)
	ds_write_b128 v75, v[94:97] offset:46080
	s_waitcnt vmcnt(2)
	ds_write_b128 v75, v[78:81] offset:64512
	v_mfma_f32_32x32x16_bf16 v[18:33], v[86:89], v[110:113], v[18:33]
	s_waitcnt lgkmcnt(3)
	v_mfma_f32_32x32x16_bf16 v[34:49], v[82:85], v[106:109], v[34:49]
	s_waitcnt vmcnt(1)
	ds_write_b128 v75, v[98:101] offset:50688
	s_waitcnt vmcnt(0)
	ds_write_b128 v76, v[102:105] offset:13824
	v_mfma_f32_32x32x16_bf16 v[2:17], v[90:93], v[106:109], v[2:17]
	s_waitcnt lgkmcnt(4)
	v_mfma_f32_32x32x16_bf16 v[50:65], v[82:85], v[114:117], v[50:65]
	v_mfma_f32_32x32x16_bf16 v[18:33], v[90:93], v[114:117], v[18:33]
	s_waitcnt lgkmcnt(0)
	s_barrier
; DI int tid_() { int t = threadIdx.x; asm volatile("" : "+v"(t)); return t; }
; template <int NJ> DI void acc_to_lds(const f32x16 (&acc)[2][NJ], float* cl) {
;   const int tid = tid_(), lane = tid & 63, w = tid >> 6, wm = w >> 1, wn = w & 1, h = lane >> 5, c = lane & 31;
; #pragma unroll
;   for (int i = 0; i < 2; ++i)
; #pragma unroll
;     for (int j = 0; j < NJ; ++j)
; #pragma unroll
;       for (int r = 0; r < 16; ++r) {
;         const int row = wm * 64 + i * 32 + (r & 3) + 8 * (r >> 2) + 4 * h;
;         cl[row * CLD + wn * 32 * NJ + j * 32 + c] = acc[i][j][r];
;       }
; }
; DI void phase_ffn_in(const Ctx& c, const bf16_t* A, size_t woff, int site) {
;     ...
;     if (tid < 128) rr[tid] = rsqrtf(ss[mt * 128 + tid] * (1.0f / DM) + EPS);
;     __syncthreads();
	ds_read_b128 v[76:79], v73 offset:36864
	ds_read_b128 v[80:83], v74 offset:55296
	ds_read_b128 v[84:87], v73 offset:41472
	s_waitcnt lgkmcnt(1)
	v_mfma_f32_32x32x16_bf16 v[34:49], v[76:79], v[80:83], v[34:49]
	s_waitcnt lgkmcnt(0)
	v_mfma_f32_32x32x16_bf16 v[2:17], v[84:87], v[80:83], v[2:17]
	ds_read_b128 v[80:83], v74 offset:59904
	s_waitcnt lgkmcnt(0)
	v_mfma_f32_32x32x16_bf16 v[50:65], v[76:79], v[80:83], v[50:65]
	ds_read_b128 v[76:79], v73 offset:36896
	ds_read_b128 v[88:91], v74 offset:55328
	ds_read_b128 v[92:95], v73 offset:41504
	ds_read_b128 v[96:99], v74 offset:59936
	v_mfma_f32_32x32x16_bf16 v[18:33], v[84:87], v[80:83], v[18:33]
	s_waitcnt lgkmcnt(2)
	v_mfma_f32_32x32x16_bf16 v[34:49], v[76:79], v[88:91], v[34:49]
	s_waitcnt lgkmcnt(1)
	v_mfma_f32_32x32x16_bf16 v[2:17], v[92:95], v[88:91], v[2:17]
	s_waitcnt lgkmcnt(0)
	v_mfma_f32_32x32x16_bf16 v[50:65], v[76:79], v[96:99], v[50:65]
	ds_read_b128 v[76:79], v73 offset:36928
	ds_read_b128 v[80:83], v73 offset:41536
	ds_read_b128 v[84:87], v74 offset:55360
	ds_read_b128 v[88:91], v74 offset:59968
	v_mfma_f32_32x32x16_bf16 v[18:33], v[92:95], v[96:99], v[18:33]
	s_waitcnt lgkmcnt(1)
	v_mfma_f32_32x32x16_bf16 v[34:49], v[76:79], v[84:87], v[34:49]
	v_mfma_f32_32x32x16_bf16 v[2:17], v[80:83], v[84:87], v[2:17]
	s_waitcnt lgkmcnt(0)
	v_mfma_f32_32x32x16_bf16 v[50:65], v[76:79], v[88:91], v[50:65]
	ds_read_b128 v[76:79], v73 offset:36960
	ds_read_b128 v[84:87], v73 offset:41568
	ds_read_b128 v[92:95], v74 offset:55392
	ds_read_b128 v[96:99], v74 offset:60000
	v_mfma_f32_32x32x16_bf16 v[18:33], v[80:83], v[88:91], v[18:33]
	s_waitcnt lgkmcnt(1)
	v_mfma_f32_32x32x16_bf16 v[34:49], v[76:79], v[92:95], v[34:49]
	v_mfma_f32_32x32x16_bf16 v[2:17], v[84:87], v[92:95], v[2:17]
	s_waitcnt lgkmcnt(0)
	v_mfma_f32_32x32x16_bf16 v[50:65], v[76:79], v[96:99], v[50:65]
	v_mfma_f32_32x32x16_bf16 v[18:33], v[84:87], v[96:99], v[18:33]
	s_setprio 0
	s_nop 0
	v_mov_b32_e32 v73, v199
	s_barrier
	s_nop 0
	v_lshrrev_b32_e32 v75, 3, v73
	v_lshrrev_b32_e32 v74, 1, v73
	v_and_b32_e32 v75, 4, v75
	v_and_b32_e32 v73, 0x5f, v73
	v_and_or_b32 v74, v74, s17, v75
	v_mul_lo_u32 v74, v74, s15
	v_lshlrev_b32_e32 v73, 2, v73
	v_add3_u32 v73, 0, v74, v73
	ds_write2_b32 v73, v34, v50 offset1:32
	ds_write2_b32 v73, v35, v51 offset0:132 offset1:164
	v_add_u32_e32 v34, 0x400, v73
	ds_write2_b32 v34, v36, v52 offset0:8 offset1:40
	ds_write2_b32 v34, v37, v53 offset0:140 offset1:172
	v_add_u32_e32 v34, 0x1000, v73
	ds_write2_b32 v34, v38, v54 offset0:32 offset1:64
	ds_write2_b32 v34, v39, v55 offset0:164 offset1:196
	v_add_u32_e32 v34, 0x1400, v73
	ds_write2_b32 v34, v40, v56 offset0:40 offset1:72
	ds_write2_b32 v34, v41, v57 offset0:172 offset1:204
	v_add_u32_e32 v34, 0x2000, v73
	ds_write2_b32 v34, v42, v58 offset0:64 offset1:96
	ds_write2_b32 v34, v43, v59 offset0:196 offset1:228
	v_add_u32_e32 v34, 0x2400, v73
	ds_write2_b32 v34, v44, v60 offset0:72 offset1:104
	ds_write2_b32 v34, v45, v61 offset0:204 offset1:236
	v_add_u32_e32 v34, 0x3000, v73
	ds_write2_b32 v34, v46, v62 offset0:96 offset1:128
	v_add_u32_e32 v34, 0x3200, v73
	ds_write2_b32 v34, v47, v63 offset0:100 offset1:132
	v_add_u32_e32 v34, 0x3400, v73
	ds_write2_b32 v34, v48, v64 offset0:104 offset1:136
	v_add_u32_e32 v34, 0x3600, v73
	ds_write2_b32 v34, v49, v65 offset0:108 offset1:140
	v_add_u32_e32 v34, 0x4000, v73
	ds_write2_b32 v34, v2, v18 offset0:128 offset1:160
	v_add_u32_e32 v2, 0x4400, v73
	ds_write2_b32 v2, v3, v19 offset0:4 offset1:36
	ds_write2_b32 v2, v4, v20 offset0:136 offset1:168
	v_add_u32_e32 v2, 0x4800, v73
	ds_write2_b32 v2, v5, v21 offset0:12 offset1:44
	v_add_u32_e32 v2, 0x5000, v73
	ds_write2_b32 v2, v6, v22 offset0:160 offset1:192
	v_add_u32_e32 v2, 0x5400, v73
	ds_write2_b32 v2, v7, v23 offset0:36 offset1:68
	ds_write2_b32 v2, v8, v24 offset0:168 offset1:200
	v_add_u32_e32 v2, 0x5800, v73
	ds_write2_b32 v2, v9, v25 offset0:44 offset1:76
	v_add_u32_e32 v2, 0x6000, v73
	ds_write2_b32 v2, v10, v26 offset0:192 offset1:224
	v_add_u32_e32 v2, 0x6400, v73
	ds_write2_b32 v2, v11, v27 offset0:68 offset1:100
	ds_write2_b32 v2, v12, v28 offset0:200 offset1:232
	v_add_u32_e32 v2, 0x6800, v73
	ds_write2_b32 v2, v13, v29 offset0:76 offset1:108
	v_add_u32_e32 v2, 0x7200, v73
	ds_write2_b32 v2, v14, v30 offset0:96 offset1:128
	v_add_u32_e32 v2, 0x7400, v73
	ds_write2_b32 v2, v15, v31 offset0:100 offset1:132
	v_add_u32_e32 v2, 0x7600, v73
	ds_write2_b32 v2, v16, v32 offset0:104 offset1:136
	v_add_u32_e32 v2, 0x7800, v73
	ds_write2_b32 v2, v17, v33 offset0:108 offset1:140
	s_and_saveexec_b64 s[2:3], s[36:37]
	s_cbranch_execz .LBB0_369
	v_lshl_add_u32 v2, s34, 7, v68
	v_readlane_b32 s4, v248, 14
	v_ashrrev_i32_e32 v3, 31, v2
	v_readlane_b32 s5, v248, 15
	s_nop 1
	v_lshl_add_u64 v[2:3], v[2:3], 2, s[4:5]
	global_load_dword v2, v[2:3], off
	s_mov_b32 s4, 0x800000
	s_waitcnt vmcnt(0)
	v_fmamk_f32 v2, v2, 0x3a800000, v198
	v_mul_f32_e32 v3, 0x4b800000, v2
	v_cmp_gt_f32_e32 vcc, s4, v2
	s_nop 1
	v_cndmask_b32_e32 v2, v2, v3, vcc
	v_rsq_f32_e32 v2, v2
	s_nop 0
	v_mul_f32_e32 v3, 0x45800000, v2
	v_cndmask_b32_e32 v2, v2, v3, vcc
	ds_write_b32 v69, v2

; #define GL1_(RA, RB, i) { RA[i] = *(const u32x4*)(ap + (aoff + (i) * astep)); if ((i) < NB) RB[(i) < NB ? (i) : 0] = *(const u32x4*)(bp + (boff + (i) * bstep)); }
; #define LS1_(RA, RB, ST, i) { char* sn_ = lds + (ST) * STAGE; *(u32x4*)(sn_ + wofs + (i) * 32 * LROW) = RA[i]; \
;                               if ((i) < NB) *(u32x4*)(sn_ + STAGE_OP + wofs + (i) * 32 * LROW) = RB[(i) < NB ? (i) : 0]; }
; template <int NJ> DI void gemm_mainloop_reg(const bf16_t* __restrict__ A, int lda, const bf16_t* __restrict__ Bt, int ldb, int K, f32x16 (&acc)[2][NJ], char* lds) {
;     ...
; #pragma unroll
;   for (int i = 0; i < 4; ++i) GL1_(ra0, rb0, i);
;   ap += 128; bp += 128;
; #pragma unroll
;   for (int i = 0; i < 4; ++i) GL1_(ra1, rb1, i);
;   ap += 128; bp += 128;
; #pragma unroll
;   for (int i = 0; i < 4; ++i) LS1_(ra0, rb0, 0, i);
;   __syncthreads();
;   const int nk = K >> 6;
;   for (int kt = 0; kt < nk; kt += 2) {
;     const bool l0 = (kt + 2 < nk), l1 = (kt + 3 < nk);
;     STEP_(0, l0, ra0, rb0, true, ra1, rb1);
; DI void phase_resid_gemm(const Ctx& c, const bf16_t* A, int K, size_t woff, float scale, float* ssn) {
;     ...
;   for (int j_ = slot_; j_ < 16 * 8; j_ += nslot_) {
;     const int mt = xcd_ * 16 + (j_ & 15), nt = j_ >> 4;
;     f32x16 acc[2][2]; zero_acc<2>(acc);
;     gemm_mainloop_reg<2>(A + (size_t)mt * 128 * (K + PADK), K + PADK, Bt + (size_t)nt * 128 * (K + PADK), K + PADK, K, acc, c.lds);
.LBB0_427:
	s_and_b32 s0, s34, 15
	s_lshl_b32 s39, s0, 7
	s_lshl_b32 s0, s25, 1
	s_and_b32 s72, s0, 0x700
	s_lshl_b32 s0, s25, 2
	s_and_b32 s38, s0, 0xe00
	s_and_b32 s0, s35, 15
	s_add_i32 s41, s10, s39
	s_or_b32 s0, s0, s78
	s_lshl_b32 s40, s41, 2
	s_mul_i32 s0, s0, 0xb4000
	s_add_u32 s0, s86, s0
	s_addc_u32 s1, s87, 0
	s_lshl_b32 s2, s35, 3
	s_and_b32 s2, s2, 0x380
	s_mulk_i32 s2, 0x1680
	v_mov_b32_e32 v34, v199
	s_add_u32 s36, s4, s2
	s_movk_i32 s2, 0x1680
	v_ashrrev_i32_e32 v0, 3, v34
	v_lshlrev_b32_e32 v2, 4, v34
	v_and_b32_e32 v35, 0x70, v2
	v_mul_lo_u32 v2, v0, s2
	v_or_b32_e32 v72, v35, v2
	v_add_u32_e32 v71, 0x2d000, v72
	v_add_u32_e32 v70, 0x5a000, v72
	v_add_u32_e32 v69, 0x87000, v72
	s_addc_u32 s37, s5, 0
	global_load_dwordx4 v[2:5], v72, s[0:1]
	global_load_dwordx4 v[6:9], v71, s[0:1]
	global_load_dwordx4 v[10:13], v70, s[0:1]
	global_load_dwordx4 v[14:17], v69, s[0:1]
	global_load_dwordx4 v[18:21], v72, s[36:37]
	global_load_dwordx4 v[22:25], v71, s[36:37]
	global_load_dwordx4 v[26:29], v70, s[36:37]
	global_load_dwordx4 v[30:33], v69, s[36:37]
	v_mul_lo_u32 v0, v0, s16
	v_lshrrev_b32_e32 v36, 1, v34
	v_and_b32_e32 v37, 31, v34
	v_add3_u32 v67, v0, v35, 0
	v_and_b32_e32 v38, 16, v36
	v_and_or_b32 v36, v36, s17, v37
	global_load_dwordx4 v[74:77], v72, s[0:1] offset:128
	global_load_dwordx4 v[78:81], v71, s[0:1] offset:128
	global_load_dwordx4 v[82:85], v70, s[0:1] offset:128
	global_load_dwordx4 v[86:89], v69, s[0:1] offset:128
	global_load_dwordx4 v[90:93], v72, s[36:37] offset:128
	global_load_dwordx4 v[94:97], v71, s[36:37] offset:128
	global_load_dwordx4 v[98:101], v70, s[36:37] offset:128
	global_load_dwordx4 v[102:105], v69, s[36:37] offset:128
	v_mul_lo_u32 v0, v36, s16
	v_add3_u32 v0, v0, v38, 0
	v_add_u32_e32 v68, 0xd800, v67
	s_waitcnt vmcnt(15)
	ds_write_b128 v67, v[2:5]
	s_waitcnt vmcnt(14)
	ds_write_b128 v67, v[6:9] offset:4608
	s_waitcnt vmcnt(13)
	ds_write_b128 v67, v[10:13] offset:9216
	s_waitcnt vmcnt(12)
	ds_write_b128 v67, v[14:17] offset:13824
	s_waitcnt vmcnt(11)
	ds_write_b128 v67, v[18:21] offset:18432
	s_waitcnt vmcnt(10)
	ds_write_b128 v67, v[22:25] offset:23040
	s_waitcnt vmcnt(9)
	ds_write_b128 v67, v[26:29] offset:27648
	s_waitcnt vmcnt(8)
	ds_write_b128 v67, v[30:33] offset:32256
	v_and_b32_e32 v2, 0x5f, v34
	v_mul_u32_u24_e32 v2, 0x90, v2
	v_add3_u32 v66, v2, v38, 0
	s_waitcnt lgkmcnt(0)
	s_barrier
	ds_read_b128 v[18:21], v0
	ds_read_b128 v[2:5], v66 offset:18432
	ds_read_b128 v[106:109], v0 offset:32
	ds_read_b128 v[110:113], v66 offset:18464
	ds_read_b128 v[22:25], v0 offset:4608
	ds_read_b128 v[114:117], v0 offset:4640
	ds_read_b128 v[26:29], v66 offset:23040
	ds_read_b128 v[118:121], v66 offset:23072
	global_load_dwordx4 v[122:125], v72, s[0:1] offset:256
	global_load_dwordx4 v[126:129], v72, s[36:37] offset:256
	s_waitcnt lgkmcnt(6)
	s_setprio 1
	s_nop 0
	v_mfma_f32_32x32x16_bf16 v[34:49], v[18:21], v[2:5], 0
	s_waitcnt vmcnt(9)
	ds_write_b128 v67, v[74:77] offset:36864
	s_waitcnt vmcnt(5)
	ds_write_b128 v67, v[90:93] offset:55296
	s_waitcnt lgkmcnt(5)
	v_mfma_f32_32x32x16_bf16 v[2:17], v[22:25], v[2:5], 0
	s_waitcnt lgkmcnt(3)
	v_mfma_f32_32x32x16_bf16 v[50:65], v[18:21], v[26:29], 0
	v_mfma_f32_32x32x16_bf16 v[18:33], v[22:25], v[26:29], 0
	global_load_dwordx4 v[74:77], v71, s[0:1] offset:256
	global_load_dwordx4 v[90:93], v71, s[36:37] offset:256
	v_mfma_f32_32x32x16_bf16 v[2:17], v[114:117], v[110:113], v[2:17]
	s_waitcnt lgkmcnt(2)
	v_mfma_f32_32x32x16_bf16 v[18:33], v[114:117], v[118:121], v[18:33]
	v_mfma_f32_32x32x16_bf16 v[34:49], v[106:109], v[110:113], v[34:49]
	v_mfma_f32_32x32x16_bf16 v[50:65], v[106:109], v[118:121], v[50:65]
	ds_read_b128 v[106:109], v0 offset:64
	ds_read_b128 v[110:113], v0 offset:4672
	ds_read_b128 v[130:133], v66 offset:18496
	ds_read_b128 v[134:137], v66 offset:23104
	ds_write_b128 v67, v[78:81] offset:41472
	s_waitcnt vmcnt(6)
	ds_write_b128 v67, v[94:97] offset:59904
	global_load_dwordx4 v[78:81], v70, s[0:1] offset:256
	global_load_dwordx4 v[94:97], v70, s[36:37] offset:256
	s_waitcnt lgkmcnt(3)
	v_mfma_f32_32x32x16_bf16 v[2:17], v[110:113], v[130:133], v[2:17]
	s_waitcnt lgkmcnt(2)
	v_mfma_f32_32x32x16_bf16 v[18:33], v[110:113], v[134:137], v[18:33]
	v_mfma_f32_32x32x16_bf16 v[34:49], v[106:109], v[130:133], v[34:49]
	v_mfma_f32_32x32x16_bf16 v[50:65], v[106:109], v[134:137], v[50:65]
	ds_read_b128 v[106:109], v0 offset:96
	ds_read_b128 v[114:117], v0 offset:4704
	ds_read_b128 v[118:121], v66 offset:18528
	ds_read_b128 v[130:133], v66 offset:23136
	ds_write_b128 v67, v[82:85] offset:46080
	s_waitcnt vmcnt(7)
	ds_write_b128 v67, v[98:101] offset:64512
	global_load_dwordx4 v[82:85], v69, s[0:1] offset:256
	global_load_dwordx4 v[98:101], v69, s[36:37] offset:256
	s_waitcnt lgkmcnt(3)
	v_mfma_f32_32x32x16_bf16 v[2:17], v[114:117], v[118:121], v[2:17]
	ds_write_b128 v67, v[86:89] offset:50688
	s_waitcnt vmcnt(8)
	ds_write_b128 v68, v[102:105] offset:13824
	s_waitcnt lgkmcnt(4)
	v_mfma_f32_32x32x16_bf16 v[18:33], v[114:117], v[130:133], v[18:33]
	v_mfma_f32_32x32x16_bf16 v[34:49], v[106:109], v[118:121], v[34:49]
	v_mfma_f32_32x32x16_bf16 v[50:65], v[106:109], v[130:133], v[50:65]
	s_waitcnt lgkmcnt(0)
	s_barrier
; #define GL1_(RA, RB, i) { RA[i] = *(const u32x4*)(ap + (aoff + (i) * astep)); if ((i) < NB) RB[(i) < NB ? (i) : 0] = *(const u32x4*)(bp + (boff + (i) * bstep)); }
; #define LS1_(RA, RB, ST, i) { char* sn_ = lds + (ST) * STAGE; *(u32x4*)(sn_ + wofs + (i) * 32 * LROW) = RA[i]; \
;                               if ((i) < NB) *(u32x4*)(sn_ + STAGE_OP + wofs + (i) * 32 * LROW) = RB[(i) < NB ? (i) : 0]; }
; template <int NJ> DI void gemm_mainloop_reg(const bf16_t* __restrict__ A, int lda, const bf16_t* __restrict__ Bt, int ldb, int K, f32x16 (&acc)[2][NJ], char* lds) {
;     ...
; #pragma unroll
;   for (int i = 0; i < 4; ++i) GL1_(ra0, rb0, i);
;   ap += 128; bp += 128;
; #pragma unroll
;   for (int i = 0; i < 4; ++i) GL1_(ra1, rb1, i);
;   ap += 128; bp += 128;
; #pragma unroll
;   for (int i = 0; i < 4; ++i) LS1_(ra0, rb0, 0, i);
;   __syncthreads();
;   const int nk = K >> 6;
;   for (int kt = 0; kt < nk; kt += 2) {
;     const bool l0 = (kt + 2 < nk), l1 = (kt + 3 < nk);
;     STEP_(0, l0, ra0, rb0, true, ra1, rb1);
;     __syncthreads();
;     STEP_(1, l1, ra1, rb1, l0, ra0, rb0);
;     __syncthreads();
;   }
	ds_read_b128 v[86:89], v0 offset:36864
	ds_read_b128 v[102:105], v66 offset:55296
	ds_read_b128 v[106:109], v0 offset:36896
	ds_read_b128 v[110:113], v66 offset:55328
	ds_read_b128 v[114:117], v0 offset:41472
	ds_read_b128 v[118:121], v0 offset:41504
	s_waitcnt lgkmcnt(4)
	v_mfma_f32_32x32x16_bf16 v[34:49], v[86:89], v[102:105], v[34:49]
	s_waitcnt lgkmcnt(1)
	v_mfma_f32_32x32x16_bf16 v[2:17], v[114:117], v[102:105], v[2:17]
	ds_read_b128 v[102:105], v66 offset:59904
	ds_read_b128 v[130:133], v66 offset:59936
	s_waitcnt lgkmcnt(1)
	v_mfma_f32_32x32x16_bf16 v[50:65], v[86:89], v[102:105], v[50:65]
	global_load_dwordx4 v[86:89], v72, s[0:1] offset:384
	global_load_dwordx4 v[134:137], v72, s[36:37] offset:384
	s_waitcnt vmcnt(9)
	ds_write_b128 v67, v[122:125]
	s_waitcnt vmcnt(8)
	ds_write_b128 v67, v[126:129] offset:18432
	v_mfma_f32_32x32x16_bf16 v[18:33], v[114:117], v[102:105], v[18:33]
	v_mfma_f32_32x32x16_bf16 v[34:49], v[106:109], v[110:113], v[34:49]
	s_waitcnt lgkmcnt(2)
	v_mfma_f32_32x32x16_bf16 v[50:65], v[106:109], v[130:133], v[50:65]
	global_load_dwordx4 v[102:105], v71, s[0:1] offset:384
	global_load_dwordx4 v[106:109], v71, s[36:37] offset:384
	v_mfma_f32_32x32x16_bf16 v[2:17], v[118:121], v[110:113], v[2:17]
	ds_read_b128 v[110:113], v0 offset:36928
	ds_read_b128 v[114:117], v0 offset:41536
	ds_read_b128 v[122:125], v66 offset:55360
	ds_read_b128 v[126:129], v66 offset:59968
	s_waitcnt vmcnt(9)
	ds_write_b128 v67, v[74:77] offset:4608
	s_waitcnt vmcnt(8)
	ds_write_b128 v67, v[90:93] offset:23040
	v_mfma_f32_32x32x16_bf16 v[18:33], v[118:121], v[130:133], v[18:33]
	global_load_dwordx4 v[74:77], v70, s[0:1] offset:384
	global_load_dwordx4 v[90:93], v70, s[36:37] offset:384
	s_waitcnt lgkmcnt(3)
	v_mfma_f32_32x32x16_bf16 v[2:17], v[114:117], v[122:125], v[2:17]
	s_waitcnt lgkmcnt(2)
	v_mfma_f32_32x32x16_bf16 v[18:33], v[114:117], v[126:129], v[18:33]
	v_mfma_f32_32x32x16_bf16 v[34:49], v[110:113], v[122:125], v[34:49]
	v_mfma_f32_32x32x16_bf16 v[50:65], v[110:113], v[126:129], v[50:65]
	ds_read_b128 v[110:113], v0 offset:36960
	ds_read_b128 v[118:121], v0 offset:41568
	ds_read_b128 v[122:125], v66 offset:55392
	ds_read_b128 v[130:133], v66 offset:60000
	s_waitcnt vmcnt(9)
	ds_write_b128 v67, v[78:81] offset:9216
	s_waitcnt vmcnt(8)
	ds_write_b128 v67, v[94:97] offset:27648
	global_load_dwordx4 v[78:81], v69, s[0:1] offset:384
	global_load_dwordx4 v[94:97], v69, s[36:37] offset:384
	s_waitcnt lgkmcnt(3)
	v_mfma_f32_32x32x16_bf16 v[2:17], v[118:121], v[122:125], v[2:17]
	s_waitcnt vmcnt(9)
	ds_write_b128 v67, v[82:85] offset:13824
	s_waitcnt vmcnt(8)
	ds_write_b128 v67, v[98:101] offset:32256
	s_waitcnt lgkmcnt(4)
	v_mfma_f32_32x32x16_bf16 v[18:33], v[118:121], v[130:133], v[18:33]
	v_mfma_f32_32x32x16_bf16 v[34:49], v[110:113], v[122:125], v[34:49]
	v_mfma_f32_32x32x16_bf16 v[50:65], v[110:113], v[130:133], v[50:65]
	s_waitcnt lgkmcnt(0)
	s_barrier
	ds_read_b128 v[82:85], v0
	ds_read_b128 v[98:101], v66 offset:18432
	ds_read_b128 v[110:113], v0 offset:32
	ds_read_b128 v[114:117], v66 offset:18464
	ds_read_b128 v[118:121], v0 offset:4608
	ds_read_b128 v[122:125], v0 offset:4640
	s_waitcnt lgkmcnt(4)
	v_mfma_f32_32x32x16_bf16 v[34:49], v[82:85], v[98:101], v[34:49]
	s_waitcnt lgkmcnt(1)
	v_mfma_f32_32x32x16_bf16 v[2:17], v[118:121], v[98:101], v[2:17]
	ds_read_b128 v[98:101], v66 offset:23040
	ds_read_b128 v[126:129], v66 offset:23072
	s_waitcnt lgkmcnt(1)
	v_mfma_f32_32x32x16_bf16 v[50:65], v[82:85], v[98:101], v[50:65]
	global_load_dwordx4 v[82:85], v72, s[0:1] offset:512
	global_load_dwordx4 v[130:133], v72, s[36:37] offset:512
	s_waitcnt vmcnt(9)
	ds_write_b128 v67, v[86:89] offset:36864
	s_waitcnt vmcnt(8)
	ds_write_b128 v67, v[134:137] offset:55296
	v_mfma_f32_32x32x16_bf16 v[18:33], v[118:121], v[98:101], v[18:33]
	global_load_dwordx4 v[86:89], v71, s[0:1] offset:512
	global_load_dwordx4 v[98:101], v71, s[36:37] offset:512
	v_mfma_f32_32x32x16_bf16 v[2:17], v[122:125], v[114:117], v[2:17]
	s_waitcnt lgkmcnt(2)
	v_mfma_f32_32x32x16_bf16 v[18:33], v[122:125], v[126:129], v[18:33]
	v_mfma_f32_32x32x16_bf16 v[34:49], v[110:113], v[114:117], v[34:49]
	v_mfma_f32_32x32x16_bf16 v[50:65], v[110:113], v[126:129], v[50:65]
	ds_read_b128 v[110:113], v0 offset:64
	ds_read_b128 v[114:117], v0 offset:4672
	ds_read_b128 v[118:121], v66 offset:18496
	ds_read_b128 v[134:137], v66 offset:23104
	s_waitcnt vmcnt(9)
	ds_write_b128 v67, v[102:105] offset:41472
	s_waitcnt vmcnt(8)
	ds_write_b128 v67, v[106:109] offset:59904
	global_load_dwordx4 v[102:105], v70, s[0:1] offset:512
	global_load_dwordx4 v[106:109], v70, s[36:37] offset:512
	s_waitcnt lgkmcnt(3)
	v_mfma_f32_32x32x16_bf16 v[2:17], v[114:117], v[118:121], v[2:17]
	s_waitcnt lgkmcnt(2)
	v_mfma_f32_32x32x16_bf16 v[18:33], v[114:117], v[134:137], v[18:33]
	v_mfma_f32_32x32x16_bf16 v[34:49], v[110:113], v[118:121], v[34:49]
	v_mfma_f32_32x32x16_bf16 v[50:65], v[110:113], v[134:137], v[50:65]
	ds_read_b128 v[110:113], v0 offset:96
	ds_read_b128 v[118:121], v0 offset:4704
	ds_read_b128 v[122:125], v66 offset:18528
	ds_read_b128 v[126:129], v66 offset:23136
	s_waitcnt vmcnt(9)
	ds_write_b128 v67, v[74:77] offset:46080
	s_waitcnt vmcnt(8)
	ds_write_b128 v67, v[90:93] offset:64512
	global_load_dwordx4 v[74:77], v69, s[0:1] offset:512
	global_load_dwordx4 v[90:93], v69, s[36:37] offset:512
	s_waitcnt lgkmcnt(3)
	v_mfma_f32_32x32x16_bf16 v[2:17], v[118:121], v[122:125], v[2:17]
	s_waitcnt vmcnt(9)
	ds_write_b128 v67, v[78:81] offset:50688
	s_waitcnt vmcnt(8)
	ds_write_b128 v68, v[94:97] offset:13824
	s_waitcnt lgkmcnt(4)
	v_mfma_f32_32x32x16_bf16 v[18:33], v[118:121], v[126:129], v[18:33]
	v_mfma_f32_32x32x16_bf16 v[34:49], v[110:113], v[122:125], v[34:49]
	v_mfma_f32_32x32x16_bf16 v[50:65], v[110:113], v[126:129], v[50:65]
	s_waitcnt lgkmcnt(0)
	s_barrier
; #define GL1_(RA, RB, i) { RA[i] = *(const u32x4*)(ap + (aoff + (i) * astep)); if ((i) < NB) RB[(i) < NB ? (i) : 0] = *(const u32x4*)(bp + (boff + (i) * bstep)); }
; #define LS1_(RA, RB, ST, i) { char* sn_ = lds + (ST) * STAGE; *(u32x4*)(sn_ + wofs + (i) * 32 * LROW) = RA[i]; \
;                               if ((i) < NB) *(u32x4*)(sn_ + STAGE_OP + wofs + (i) * 32 * LROW) = RB[(i) < NB ? (i) : 0]; }
; template <int NJ> DI void gemm_mainloop_reg(const bf16_t* __restrict__ A, int lda, const bf16_t* __restrict__ Bt, int ldb, int K, f32x16 (&acc)[2][NJ], char* lds) {
;     ...
; #pragma unroll
;   for (int i = 0; i < 4; ++i) GL1_(ra0, rb0, i);
;   ap += 128; bp += 128;
; #pragma unroll
;   for (int i = 0; i < 4; ++i) GL1_(ra1, rb1, i);
;   ap += 128; bp += 128;
; #pragma unroll
;   for (int i = 0; i < 4; ++i) LS1_(ra0, rb0, 0, i);
;   __syncthreads();
;   const int nk = K >> 6;
;   for (int kt = 0; kt < nk; kt += 2) {
;     const bool l0 = (kt + 2 < nk), l1 = (kt + 3 < nk);
;     STEP_(0, l0, ra0, rb0, true, ra1, rb1);
;     __syncthreads();
;     STEP_(1, l1, ra1, rb1, l0, ra0, rb0);
;     __syncthreads();
;   }
	ds_read_b128 v[78:81], v0 offset:36864
	ds_read_b128 v[94:97], v66 offset:55296
	ds_read_b128 v[110:113], v0 offset:36896
	ds_read_b128 v[114:117], v66 offset:55328
	ds_read_b128 v[118:121], v0 offset:41472
	ds_read_b128 v[122:125], v0 offset:41504
	s_waitcnt lgkmcnt(4)
	v_mfma_f32_32x32x16_bf16 v[34:49], v[78:81], v[94:97], v[34:49]
	s_waitcnt lgkmcnt(1)
	v_mfma_f32_32x32x16_bf16 v[2:17], v[118:121], v[94:97], v[2:17]
	ds_read_b128 v[94:97], v66 offset:59904
	ds_read_b128 v[126:129], v66 offset:59936
	s_waitcnt lgkmcnt(1)
	v_mfma_f32_32x32x16_bf16 v[50:65], v[78:81], v[94:97], v[50:65]
	global_load_dwordx4 v[78:81], v72, s[0:1] offset:640
	global_load_dwordx4 v[134:137], v72, s[36:37] offset:640
	s_waitcnt vmcnt(9)
	ds_write_b128 v67, v[82:85]
	s_waitcnt vmcnt(8)
	ds_write_b128 v67, v[130:133] offset:18432
	v_mfma_f32_32x32x16_bf16 v[18:33], v[118:121], v[94:97], v[18:33]
	global_load_dwordx4 v[82:85], v71, s[0:1] offset:640
	global_load_dwordx4 v[94:97], v71, s[36:37] offset:640
	v_mfma_f32_32x32x16_bf16 v[2:17], v[122:125], v[114:117], v[2:17]
	s_waitcnt lgkmcnt(2)
	v_mfma_f32_32x32x16_bf16 v[18:33], v[122:125], v[126:129], v[18:33]
	v_mfma_f32_32x32x16_bf16 v[34:49], v[110:113], v[114:117], v[34:49]
	v_mfma_f32_32x32x16_bf16 v[50:65], v[110:113], v[126:129], v[50:65]
	ds_read_b128 v[110:113], v0 offset:36928
	ds_read_b128 v[114:117], v0 offset:41536
	ds_read_b128 v[118:121], v66 offset:55360
	ds_read_b128 v[130:133], v66 offset:59968
	s_waitcnt vmcnt(9)
	ds_write_b128 v67, v[86:89] offset:4608
	s_waitcnt vmcnt(8)
	ds_write_b128 v67, v[98:101] offset:23040
	global_load_dwordx4 v[86:89], v70, s[0:1] offset:640
	global_load_dwordx4 v[98:101], v70, s[36:37] offset:640
	s_waitcnt lgkmcnt(3)
	v_mfma_f32_32x32x16_bf16 v[2:17], v[114:117], v[118:121], v[2:17]
	s_waitcnt lgkmcnt(2)
	v_mfma_f32_32x32x16_bf16 v[18:33], v[114:117], v[130:133], v[18:33]
	v_mfma_f32_32x32x16_bf16 v[34:49], v[110:113], v[118:121], v[34:49]
	v_mfma_f32_32x32x16_bf16 v[50:65], v[110:113], v[130:133], v[50:65]
	ds_read_b128 v[110:113], v0 offset:36960
	ds_read_b128 v[118:121], v0 offset:41568
	ds_read_b128 v[122:125], v66 offset:55392
	ds_read_b128 v[126:129], v66 offset:60000
	s_waitcnt vmcnt(9)
	ds_write_b128 v67, v[102:105] offset:9216
	s_waitcnt vmcnt(8)
	ds_write_b128 v67, v[106:109] offset:27648
	global_load_dwordx4 v[102:105], v69, s[0:1] offset:640
	global_load_dwordx4 v[106:109], v69, s[36:37] offset:640
	s_waitcnt lgkmcnt(3)
	v_mfma_f32_32x32x16_bf16 v[2:17], v[118:121], v[122:125], v[2:17]
	s_waitcnt vmcnt(9)
	ds_write_b128 v67, v[74:77] offset:13824
	s_waitcnt vmcnt(8)
	ds_write_b128 v67, v[90:93] offset:32256
	s_waitcnt lgkmcnt(4)
	v_mfma_f32_32x32x16_bf16 v[18:33], v[118:121], v[126:129], v[18:33]
	v_mfma_f32_32x32x16_bf16 v[34:49], v[110:113], v[122:125], v[34:49]
	v_mfma_f32_32x32x16_bf16 v[50:65], v[110:113], v[126:129], v[50:65]
	s_waitcnt lgkmcnt(0)
	s_barrier
	ds_read_b128 v[74:77], v0
	ds_read_b128 v[90:93], v66 offset:18432
	ds_read_b128 v[110:113], v0 offset:32
	ds_read_b128 v[114:117], v66 offset:18464
	ds_read_b128 v[118:121], v0 offset:4608
	ds_read_b128 v[122:125], v0 offset:4640
	s_waitcnt lgkmcnt(4)
	v_mfma_f32_32x32x16_bf16 v[34:49], v[74:77], v[90:93], v[34:49]
	s_waitcnt lgkmcnt(1)
	v_mfma_f32_32x32x16_bf16 v[2:17], v[118:121], v[90:93], v[2:17]
	ds_read_b128 v[90:93], v66 offset:23040
	ds_read_b128 v[126:129], v66 offset:23072
	s_waitcnt lgkmcnt(1)
	v_mfma_f32_32x32x16_bf16 v[50:65], v[74:77], v[90:93], v[50:65]
	global_load_dwordx4 v[74:77], v72, s[0:1] offset:768
	global_load_dwordx4 v[130:133], v72, s[36:37] offset:768
	s_waitcnt vmcnt(9)
	ds_write_b128 v67, v[78:81] offset:36864
	s_waitcnt vmcnt(8)
	ds_write_b128 v67, v[134:137] offset:55296
	v_mfma_f32_32x32x16_bf16 v[18:33], v[118:121], v[90:93], v[18:33]
	global_load_dwordx4 v[78:81], v71, s[0:1] offset:768
	global_load_dwordx4 v[90:93], v71, s[36:37] offset:768
	v_mfma_f32_32x32x16_bf16 v[2:17], v[122:125], v[114:117], v[2:17]
	s_waitcnt lgkmcnt(2)
	v_mfma_f32_32x32x16_bf16 v[18:33], v[122:125], v[126:129], v[18:33]
	v_mfma_f32_32x32x16_bf16 v[34:49], v[110:113], v[114:117], v[34:49]
	v_mfma_f32_32x32x16_bf16 v[50:65], v[110:113], v[126:129], v[50:65]
	ds_read_b128 v[110:113], v0 offset:64
	ds_read_b128 v[114:117], v0 offset:4672
	ds_read_b128 v[118:121], v66 offset:18496
	ds_read_b128 v[134:137], v66 offset:23104
	s_waitcnt vmcnt(9)
	ds_write_b128 v67, v[82:85] offset:41472
	s_waitcnt vmcnt(8)
	ds_write_b128 v67, v[94:97] offset:59904
	global_load_dwordx4 v[82:85], v70, s[0:1] offset:768
	global_load_dwordx4 v[94:97], v70, s[36:37] offset:768
	s_waitcnt lgkmcnt(3)
	v_mfma_f32_32x32x16_bf16 v[2:17], v[114:117], v[118:121], v[2:17]
	s_waitcnt lgkmcnt(2)
	v_mfma_f32_32x32x16_bf16 v[18:33], v[114:117], v[134:137], v[18:33]
	v_mfma_f32_32x32x16_bf16 v[34:49], v[110:113], v[118:121], v[34:49]
	v_mfma_f32_32x32x16_bf16 v[50:65], v[110:113], v[134:137], v[50:65]
	ds_read_b128 v[110:113], v0 offset:96
	ds_read_b128 v[118:121], v0 offset:4704
	ds_read_b128 v[122:125], v66 offset:18528
	ds_read_b128 v[126:129], v66 offset:23136
	s_waitcnt vmcnt(9)
	ds_write_b128 v67, v[86:89] offset:46080
	s_waitcnt vmcnt(8)
	ds_write_b128 v67, v[98:101] offset:64512
	global_load_dwordx4 v[86:89], v69, s[0:1] offset:768
	global_load_dwordx4 v[98:101], v69, s[36:37] offset:768
	s_waitcnt lgkmcnt(3)
	v_mfma_f32_32x32x16_bf16 v[2:17], v[118:121], v[122:125], v[2:17]
	s_waitcnt vmcnt(9)
	ds_write_b128 v67, v[102:105] offset:50688
	s_waitcnt vmcnt(8)
	ds_write_b128 v68, v[106:109] offset:13824
	s_waitcnt lgkmcnt(4)
	v_mfma_f32_32x32x16_bf16 v[18:33], v[118:121], v[126:129], v[18:33]
	v_mfma_f32_32x32x16_bf16 v[34:49], v[110:113], v[122:125], v[34:49]
	v_mfma_f32_32x32x16_bf16 v[50:65], v[110:113], v[126:129], v[50:65]
	s_waitcnt lgkmcnt(0)
	s_barrier
; #define GL1_(RA, RB, i) { RA[i] = *(const u32x4*)(ap + (aoff + (i) * astep)); if ((i) < NB) RB[(i) < NB ? (i) : 0] = *(const u32x4*)(bp + (boff + (i) * bstep)); }
; #define LS1_(RA, RB, ST, i) { char* sn_ = lds + (ST) * STAGE; *(u32x4*)(sn_ + wofs + (i) * 32 * LROW) = RA[i]; \
;                               if ((i) < NB) *(u32x4*)(sn_ + STAGE_OP + wofs + (i) * 32 * LROW) = RB[(i) < NB ? (i) : 0]; }
; template <int NJ> DI void gemm_mainloop_reg(const bf16_t* __restrict__ A, int lda, const bf16_t* __restrict__ Bt, int ldb, int K, f32x16 (&acc)[2][NJ], char* lds) {
;     ...
; #pragma unroll
;   for (int i = 0; i < 4; ++i) GL1_(ra0, rb0, i);
;   ap += 128; bp += 128;
; #pragma unroll
;   for (int i = 0; i < 4; ++i) GL1_(ra1, rb1, i);
;   ap += 128; bp += 128;
; #pragma unroll
;   for (int i = 0; i < 4; ++i) LS1_(ra0, rb0, 0, i);
;   __syncthreads();
;   const int nk = K >> 6;
;   for (int kt = 0; kt < nk; kt += 2) {
;     const bool l0 = (kt + 2 < nk), l1 = (kt + 3 < nk);
;     STEP_(0, l0, ra0, rb0, true, ra1, rb1);
;     __syncthreads();
;     STEP_(1, l1, ra1, rb1, l0, ra0, rb0);
;     __syncthreads();
;   }
	ds_read_b128 v[102:105], v0 offset:36864
	ds_read_b128 v[106:109], v66 offset:55296
	ds_read_b128 v[110:113], v0 offset:36896
	ds_read_b128 v[114:117], v66 offset:55328
	ds_read_b128 v[118:121], v0 offset:41472
	ds_read_b128 v[122:125], v0 offset:41504
	s_waitcnt lgkmcnt(4)
	v_mfma_f32_32x32x16_bf16 v[34:49], v[102:105], v[106:109], v[34:49]
	s_waitcnt lgkmcnt(1)
	v_mfma_f32_32x32x16_bf16 v[2:17], v[118:121], v[106:109], v[2:17]
	ds_read_b128 v[106:109], v66 offset:59904
	ds_read_b128 v[126:129], v66 offset:59936
	s_waitcnt lgkmcnt(1)
	v_mfma_f32_32x32x16_bf16 v[50:65], v[102:105], v[106:109], v[50:65]
	global_load_dwordx4 v[102:105], v72, s[0:1] offset:896
	global_load_dwordx4 v[134:137], v72, s[36:37] offset:896
	s_waitcnt vmcnt(9)
	ds_write_b128 v67, v[74:77]
	s_waitcnt vmcnt(8)
	ds_write_b128 v67, v[130:133] offset:18432
	v_mfma_f32_32x32x16_bf16 v[18:33], v[118:121], v[106:109], v[18:33]
	global_load_dwordx4 v[74:77], v71, s[0:1] offset:896
	global_load_dwordx4 v[106:109], v71, s[36:37] offset:896
	v_mfma_f32_32x32x16_bf16 v[2:17], v[122:125], v[114:117], v[2:17]
	s_waitcnt lgkmcnt(2)
	v_mfma_f32_32x32x16_bf16 v[18:33], v[122:125], v[126:129], v[18:33]
	v_mfma_f32_32x32x16_bf16 v[34:49], v[110:113], v[114:117], v[34:49]
	v_mfma_f32_32x32x16_bf16 v[50:65], v[110:113], v[126:129], v[50:65]
	ds_read_b128 v[110:113], v0 offset:36928
	ds_read_b128 v[114:117], v0 offset:41536
	ds_read_b128 v[118:121], v66 offset:55360
	ds_read_b128 v[130:133], v66 offset:59968
	s_waitcnt vmcnt(9)
	ds_write_b128 v67, v[78:81] offset:4608
	s_waitcnt vmcnt(8)
	ds_write_b128 v67, v[90:93] offset:23040
	global_load_dwordx4 v[78:81], v70, s[0:1] offset:896
	global_load_dwordx4 v[90:93], v70, s[36:37] offset:896
	s_waitcnt lgkmcnt(3)
	v_mfma_f32_32x32x16_bf16 v[2:17], v[114:117], v[118:121], v[2:17]
	s_waitcnt lgkmcnt(2)
	v_mfma_f32_32x32x16_bf16 v[18:33], v[114:117], v[130:133], v[18:33]
	v_mfma_f32_32x32x16_bf16 v[34:49], v[110:113], v[118:121], v[34:49]
	v_mfma_f32_32x32x16_bf16 v[50:65], v[110:113], v[130:133], v[50:65]
	ds_read_b128 v[110:113], v0 offset:36960
	ds_read_b128 v[118:121], v0 offset:41568
	ds_read_b128 v[122:125], v66 offset:55392
	ds_read_b128 v[126:129], v66 offset:60000
	s_waitcnt vmcnt(9)
	ds_write_b128 v67, v[82:85] offset:9216
	s_waitcnt vmcnt(8)
	ds_write_b128 v67, v[94:97] offset:27648
	global_load_dwordx4 v[82:85], v69, s[0:1] offset:896
	global_load_dwordx4 v[94:97], v69, s[36:37] offset:896
	s_waitcnt lgkmcnt(3)
	v_mfma_f32_32x32x16_bf16 v[2:17], v[118:121], v[122:125], v[2:17]
	s_waitcnt vmcnt(9)
	ds_write_b128 v67, v[86:89] offset:13824
	s_waitcnt vmcnt(8)
	ds_write_b128 v67, v[98:101] offset:32256
	s_waitcnt lgkmcnt(4)
	v_mfma_f32_32x32x16_bf16 v[18:33], v[118:121], v[126:129], v[18:33]
	v_mfma_f32_32x32x16_bf16 v[34:49], v[110:113], v[122:125], v[34:49]
	v_mfma_f32_32x32x16_bf16 v[50:65], v[110:113], v[126:129], v[50:65]
	s_waitcnt lgkmcnt(0)
	s_barrier
	ds_read_b128 v[86:89], v0
	ds_read_b128 v[98:101], v66 offset:18432
	ds_read_b128 v[110:113], v0 offset:32
	ds_read_b128 v[114:117], v66 offset:18464
	ds_read_b128 v[118:121], v0 offset:4608
	ds_read_b128 v[122:125], v0 offset:4640
	s_waitcnt lgkmcnt(4)
	v_mfma_f32_32x32x16_bf16 v[34:49], v[86:89], v[98:101], v[34:49]
	s_waitcnt lgkmcnt(1)
	v_mfma_f32_32x32x16_bf16 v[2:17], v[118:121], v[98:101], v[2:17]
	ds_read_b128 v[98:101], v66 offset:23040
	ds_read_b128 v[126:129], v66 offset:23072
	s_waitcnt lgkmcnt(1)
	v_mfma_f32_32x32x16_bf16 v[50:65], v[86:89], v[98:101], v[50:65]
	global_load_dwordx4 v[86:89], v72, s[0:1] offset:1024
	global_load_dwordx4 v[130:133], v72, s[36:37] offset:1024
	s_waitcnt vmcnt(9)
	ds_write_b128 v67, v[102:105] offset:36864
	s_waitcnt vmcnt(8)
	ds_write_b128 v67, v[134:137] offset:55296
	v_mfma_f32_32x32x16_bf16 v[18:33], v[118:121], v[98:101], v[18:33]
	global_load_dwordx4 v[98:101], v71, s[0:1] offset:1024
	global_load_dwordx4 v[102:105], v71, s[36:37] offset:1024
	v_mfma_f32_32x32x16_bf16 v[2:17], v[122:125], v[114:117], v[2:17]
	s_waitcnt lgkmcnt(2)
	v_mfma_f32_32x32x16_bf16 v[18:33], v[122:125], v[126:129], v[18:33]
	v_mfma_f32_32x32x16_bf16 v[34:49], v[110:113], v[114:117], v[34:49]
	v_mfma_f32_32x32x16_bf16 v[50:65], v[110:113], v[126:129], v[50:65]
	ds_read_b128 v[110:113], v0 offset:64
	ds_read_b128 v[114:117], v0 offset:4672
	ds_read_b128 v[118:121], v66 offset:18496
	ds_read_b128 v[134:137], v66 offset:23104
	s_waitcnt vmcnt(9)
	ds_write_b128 v67, v[74:77] offset:41472
	s_waitcnt vmcnt(8)
	ds_write_b128 v67, v[106:109] offset:59904
	global_load_dwordx4 v[74:77], v70, s[0:1] offset:1024
	global_load_dwordx4 v[106:109], v70, s[36:37] offset:1024
	s_waitcnt lgkmcnt(3)
	v_mfma_f32_32x32x16_bf16 v[2:17], v[114:117], v[118:121], v[2:17]
	s_waitcnt lgkmcnt(2)
	v_mfma_f32_32x32x16_bf16 v[18:33], v[114:117], v[134:137], v[18:33]
	v_mfma_f32_32x32x16_bf16 v[34:49], v[110:113], v[118:121], v[34:49]
	v_mfma_f32_32x32x16_bf16 v[50:65], v[110:113], v[134:137], v[50:65]
	ds_read_b128 v[110:113], v0 offset:96
	ds_read_b128 v[118:121], v0 offset:4704
	ds_read_b128 v[122:125], v66 offset:18528
	ds_read_b128 v[126:129], v66 offset:23136
	s_waitcnt vmcnt(9)
	ds_write_b128 v67, v[78:81] offset:46080
	s_waitcnt vmcnt(8)
	ds_write_b128 v67, v[90:93] offset:64512
	global_load_dwordx4 v[78:81], v69, s[0:1] offset:1024
	global_load_dwordx4 v[90:93], v69, s[36:37] offset:1024
	s_waitcnt lgkmcnt(3)
	v_mfma_f32_32x32x16_bf16 v[2:17], v[118:121], v[122:125], v[2:17]
	s_waitcnt vmcnt(9)
	ds_write_b128 v67, v[82:85] offset:50688
	s_waitcnt vmcnt(8)
	ds_write_b128 v68, v[94:97] offset:13824
	s_waitcnt lgkmcnt(4)
	v_mfma_f32_32x32x16_bf16 v[18:33], v[118:121], v[126:129], v[18:33]
	v_mfma_f32_32x32x16_bf16 v[34:49], v[110:113], v[122:125], v[34:49]
	v_mfma_f32_32x32x16_bf16 v[50:65], v[110:113], v[126:129], v[50:65]
	s_waitcnt lgkmcnt(0)
	s_barrier
; #define GL1_(RA, RB, i) { RA[i] = *(const u32x4*)(ap + (aoff + (i) * astep)); if ((i) < NB) RB[(i) < NB ? (i) : 0] = *(const u32x4*)(bp + (boff + (i) * bstep)); }
; #define LS1_(RA, RB, ST, i) { char* sn_ = lds + (ST) * STAGE; *(u32x4*)(sn_ + wofs + (i) * 32 * LROW) = RA[i]; \
;                               if ((i) < NB) *(u32x4*)(sn_ + STAGE_OP + wofs + (i) * 32 * LROW) = RB[(i) < NB ? (i) : 0]; }
; template <int NJ> DI void gemm_mainloop_reg(const bf16_t* __restrict__ A, int lda, const bf16_t* __restrict__ Bt, int ldb, int K, f32x16 (&acc)[2][NJ], char* lds) {
;     ...
; #pragma unroll
;   for (int i = 0; i < 4; ++i) GL1_(ra0, rb0, i);
;   ap += 128; bp += 128;
; #pragma unroll
;   for (int i = 0; i < 4; ++i) GL1_(ra1, rb1, i);
;   ap += 128; bp += 128;
; #pragma unroll
;   for (int i = 0; i < 4; ++i) LS1_(ra0, rb0, 0, i);
;   __syncthreads();
;   const int nk = K >> 6;
;   for (int kt = 0; kt < nk; kt += 2) {
;     const bool l0 = (kt + 2 < nk), l1 = (kt + 3 < nk);
;     STEP_(0, l0, ra0, rb0, true, ra1, rb1);
;     __syncthreads();
;     STEP_(1, l1, ra1, rb1, l0, ra0, rb0);
;     __syncthreads();
;   }
	ds_read_b128 v[82:85], v0 offset:36864
	ds_read_b128 v[94:97], v66 offset:55296
	ds_read_b128 v[110:113], v0 offset:36896
	ds_read_b128 v[114:117], v66 offset:55328
	ds_read_b128 v[118:121], v0 offset:41472
	ds_read_b128 v[122:125], v0 offset:41504
	s_waitcnt lgkmcnt(4)
	v_mfma_f32_32x32x16_bf16 v[34:49], v[82:85], v[94:97], v[34:49]
	s_waitcnt lgkmcnt(1)
	v_mfma_f32_32x32x16_bf16 v[2:17], v[118:121], v[94:97], v[2:17]
	ds_read_b128 v[94:97], v66 offset:59904
	ds_read_b128 v[126:129], v66 offset:59936
	s_waitcnt lgkmcnt(1)
	v_mfma_f32_32x32x16_bf16 v[50:65], v[82:85], v[94:97], v[50:65]
	global_load_dwordx4 v[82:85], v72, s[0:1] offset:1152
	global_load_dwordx4 v[134:137], v72, s[36:37] offset:1152
	s_waitcnt vmcnt(9)
	ds_write_b128 v67, v[86:89]
	s_waitcnt vmcnt(8)
	ds_write_b128 v67, v[130:133] offset:18432
	v_mfma_f32_32x32x16_bf16 v[18:33], v[118:121], v[94:97], v[18:33]
	global_load_dwordx4 v[86:89], v71, s[0:1] offset:1152
	global_load_dwordx4 v[94:97], v71, s[36:37] offset:1152
	v_mfma_f32_32x32x16_bf16 v[2:17], v[122:125], v[114:117], v[2:17]
	s_waitcnt lgkmcnt(2)
	v_mfma_f32_32x32x16_bf16 v[18:33], v[122:125], v[126:129], v[18:33]
	v_mfma_f32_32x32x16_bf16 v[34:49], v[110:113], v[114:117], v[34:49]
	v_mfma_f32_32x32x16_bf16 v[50:65], v[110:113], v[126:129], v[50:65]
	ds_read_b128 v[110:113], v0 offset:36928
	ds_read_b128 v[114:117], v0 offset:41536
	ds_read_b128 v[118:121], v66 offset:55360
	ds_read_b128 v[130:133], v66 offset:59968
	s_waitcnt vmcnt(9)
	ds_write_b128 v67, v[98:101] offset:4608
	s_waitcnt vmcnt(8)
	ds_write_b128 v67, v[102:105] offset:23040
	global_load_dwordx4 v[98:101], v70, s[0:1] offset:1152
	global_load_dwordx4 v[102:105], v70, s[36:37] offset:1152
	s_waitcnt lgkmcnt(3)
	v_mfma_f32_32x32x16_bf16 v[2:17], v[114:117], v[118:121], v[2:17]
	s_waitcnt lgkmcnt(2)
	v_mfma_f32_32x32x16_bf16 v[18:33], v[114:117], v[130:133], v[18:33]
	v_mfma_f32_32x32x16_bf16 v[34:49], v[110:113], v[118:121], v[34:49]
	v_mfma_f32_32x32x16_bf16 v[50:65], v[110:113], v[130:133], v[50:65]
	ds_read_b128 v[110:113], v0 offset:36960
	ds_read_b128 v[118:121], v0 offset:41568
	ds_read_b128 v[122:125], v66 offset:55392
	ds_read_b128 v[126:129], v66 offset:60000
	s_waitcnt vmcnt(9)
	ds_write_b128 v67, v[74:77] offset:9216
	s_waitcnt vmcnt(8)
	ds_write_b128 v67, v[106:109] offset:27648
	global_load_dwordx4 v[74:77], v69, s[0:1] offset:1152
	global_load_dwordx4 v[106:109], v69, s[36:37] offset:1152
	s_waitcnt lgkmcnt(3)
	v_mfma_f32_32x32x16_bf16 v[2:17], v[118:121], v[122:125], v[2:17]
	s_waitcnt vmcnt(9)
	ds_write_b128 v67, v[78:81] offset:13824
	s_waitcnt vmcnt(8)
	ds_write_b128 v67, v[90:93] offset:32256
	s_waitcnt lgkmcnt(4)
	v_mfma_f32_32x32x16_bf16 v[18:33], v[118:121], v[126:129], v[18:33]
	v_mfma_f32_32x32x16_bf16 v[34:49], v[110:113], v[122:125], v[34:49]
	v_mfma_f32_32x32x16_bf16 v[50:65], v[110:113], v[126:129], v[50:65]
	s_waitcnt lgkmcnt(0)
	s_barrier
	ds_read_b128 v[78:81], v0
	ds_read_b128 v[90:93], v66 offset:18432
	ds_read_b128 v[110:113], v0 offset:32
	ds_read_b128 v[114:117], v66 offset:18464
	ds_read_b128 v[118:121], v0 offset:4608
	ds_read_b128 v[122:125], v0 offset:4640
	s_waitcnt lgkmcnt(4)
	v_mfma_f32_32x32x16_bf16 v[34:49], v[78:81], v[90:93], v[34:49]
	s_waitcnt lgkmcnt(1)
	v_mfma_f32_32x32x16_bf16 v[2:17], v[118:121], v[90:93], v[2:17]
	ds_read_b128 v[90:93], v66 offset:23040
	ds_read_b128 v[126:129], v66 offset:23072
	s_waitcnt lgkmcnt(1)
	v_mfma_f32_32x32x16_bf16 v[50:65], v[78:81], v[90:93], v[50:65]
	global_load_dwordx4 v[78:81], v72, s[0:1] offset:1280
	global_load_dwordx4 v[130:133], v72, s[36:37] offset:1280
	s_waitcnt vmcnt(9)
	ds_write_b128 v67, v[82:85] offset:36864
	s_waitcnt vmcnt(8)
	ds_write_b128 v67, v[134:137] offset:55296
	v_mfma_f32_32x32x16_bf16 v[18:33], v[118:121], v[90:93], v[18:33]
	global_load_dwordx4 v[82:85], v71, s[0:1] offset:1280
	global_load_dwordx4 v[90:93], v71, s[36:37] offset:1280
	v_mfma_f32_32x32x16_bf16 v[2:17], v[122:125], v[114:117], v[2:17]
	s_waitcnt lgkmcnt(2)
	v_mfma_f32_32x32x16_bf16 v[18:33], v[122:125], v[126:129], v[18:33]
	v_mfma_f32_32x32x16_bf16 v[34:49], v[110:113], v[114:117], v[34:49]
	v_mfma_f32_32x32x16_bf16 v[50:65], v[110:113], v[126:129], v[50:65]
	ds_read_b128 v[110:113], v0 offset:64
	ds_read_b128 v[114:117], v0 offset:4672
	ds_read_b128 v[118:121], v66 offset:18496
	ds_read_b128 v[134:137], v66 offset:23104
	s_waitcnt vmcnt(9)
	ds_write_b128 v67, v[86:89] offset:41472
	s_waitcnt vmcnt(8)
	ds_write_b128 v67, v[94:97] offset:59904
	global_load_dwordx4 v[86:89], v70, s[0:1] offset:1280
	global_load_dwordx4 v[94:97], v70, s[36:37] offset:1280
	s_waitcnt lgkmcnt(3)
	v_mfma_f32_32x32x16_bf16 v[2:17], v[114:117], v[118:121], v[2:17]
	s_waitcnt lgkmcnt(2)
	v_mfma_f32_32x32x16_bf16 v[18:33], v[114:117], v[134:137], v[18:33]
	v_mfma_f32_32x32x16_bf16 v[34:49], v[110:113], v[118:121], v[34:49]
	v_mfma_f32_32x32x16_bf16 v[50:65], v[110:113], v[134:137], v[50:65]
	ds_read_b128 v[110:113], v0 offset:96
	ds_read_b128 v[118:121], v0 offset:4704
	ds_read_b128 v[122:125], v66 offset:18528
	ds_read_b128 v[126:129], v66 offset:23136
	s_waitcnt vmcnt(9)
	ds_write_b128 v67, v[98:101] offset:46080
	s_waitcnt vmcnt(8)
	ds_write_b128 v67, v[102:105] offset:64512
	global_load_dwordx4 v[98:101], v69, s[0:1] offset:1280
	global_load_dwordx4 v[102:105], v69, s[36:37] offset:1280
	s_waitcnt lgkmcnt(3)
	v_mfma_f32_32x32x16_bf16 v[2:17], v[118:121], v[122:125], v[2:17]
	s_waitcnt vmcnt(9)
	ds_write_b128 v67, v[74:77] offset:50688
	s_waitcnt vmcnt(8)
	ds_write_b128 v68, v[106:109] offset:13824
	s_waitcnt lgkmcnt(4)
	v_mfma_f32_32x32x16_bf16 v[18:33], v[118:121], v[126:129], v[18:33]
	v_mfma_f32_32x32x16_bf16 v[34:49], v[110:113], v[122:125], v[34:49]
	v_mfma_f32_32x32x16_bf16 v[50:65], v[110:113], v[126:129], v[50:65]
	s_waitcnt lgkmcnt(0)
	s_barrier
; #define GL1_(RA, RB, i) { RA[i] = *(const u32x4*)(ap + (aoff + (i) * astep)); if ((i) < NB) RB[(i) < NB ? (i) : 0] = *(const u32x4*)(bp + (boff + (i) * bstep)); }
; #define LS1_(RA, RB, ST, i) { char* sn_ = lds + (ST) * STAGE; *(u32x4*)(sn_ + wofs + (i) * 32 * LROW) = RA[i]; \
;                               if ((i) < NB) *(u32x4*)(sn_ + STAGE_OP + wofs + (i) * 32 * LROW) = RB[(i) < NB ? (i) : 0]; }
; template <int NJ> DI void gemm_mainloop_reg(const bf16_t* __restrict__ A, int lda, const bf16_t* __restrict__ Bt, int ldb, int K, f32x16 (&acc)[2][NJ], char* lds) {
;     ...
; #pragma unroll
;   for (int i = 0; i < 4; ++i) GL1_(ra0, rb0, i);
;   ap += 128; bp += 128;
; #pragma unroll
;   for (int i = 0; i < 4; ++i) GL1_(ra1, rb1, i);
;   ap += 128; bp += 128;
; #pragma unroll
;   for (int i = 0; i < 4; ++i) LS1_(ra0, rb0, 0, i);
;   __syncthreads();
;   const int nk = K >> 6;
;   for (int kt = 0; kt < nk; kt += 2) {
;     const bool l0 = (kt + 2 < nk), l1 = (kt + 3 < nk);
;     STEP_(0, l0, ra0, rb0, true, ra1, rb1);
;     __syncthreads();
;     STEP_(1, l1, ra1, rb1, l0, ra0, rb0);
;     __syncthreads();
;   }
	ds_read_b128 v[74:77], v0 offset:36864
	ds_read_b128 v[106:109], v66 offset:55296
	ds_read_b128 v[110:113], v0 offset:36896
	ds_read_b128 v[114:117], v66 offset:55328
	ds_read_b128 v[118:121], v0 offset:41472
	ds_read_b128 v[122:125], v0 offset:41504
	s_waitcnt lgkmcnt(4)
	v_mfma_f32_32x32x16_bf16 v[34:49], v[74:77], v[106:109], v[34:49]
	s_waitcnt lgkmcnt(1)
	v_mfma_f32_32x32x16_bf16 v[2:17], v[118:121], v[106:109], v[2:17]
	ds_read_b128 v[106:109], v66 offset:59904
	ds_read_b128 v[126:129], v66 offset:59936
	s_waitcnt lgkmcnt(1)
	v_mfma_f32_32x32x16_bf16 v[50:65], v[74:77], v[106:109], v[50:65]
	global_load_dwordx4 v[74:77], v72, s[0:1] offset:1408
	global_load_dwordx4 v[134:137], v72, s[36:37] offset:1408
	s_waitcnt vmcnt(9)
	ds_write_b128 v67, v[78:81]
	s_waitcnt vmcnt(8)
	ds_write_b128 v67, v[130:133] offset:18432
	v_mfma_f32_32x32x16_bf16 v[18:33], v[118:121], v[106:109], v[18:33]
	global_load_dwordx4 v[78:81], v71, s[0:1] offset:1408
	global_load_dwordx4 v[106:109], v71, s[36:37] offset:1408
	v_mfma_f32_32x32x16_bf16 v[2:17], v[122:125], v[114:117], v[2:17]
	s_waitcnt lgkmcnt(2)
	v_mfma_f32_32x32x16_bf16 v[18:33], v[122:125], v[126:129], v[18:33]
	v_mfma_f32_32x32x16_bf16 v[34:49], v[110:113], v[114:117], v[34:49]
	v_mfma_f32_32x32x16_bf16 v[50:65], v[110:113], v[126:129], v[50:65]
	ds_read_b128 v[110:113], v0 offset:36928
	ds_read_b128 v[114:117], v0 offset:41536
	ds_read_b128 v[118:121], v66 offset:55360
	ds_read_b128 v[130:133], v66 offset:59968
	s_waitcnt vmcnt(9)
	ds_write_b128 v67, v[82:85] offset:4608
	s_waitcnt vmcnt(8)
	ds_write_b128 v67, v[90:93] offset:23040
	global_load_dwordx4 v[82:85], v70, s[0:1] offset:1408
	global_load_dwordx4 v[90:93], v70, s[36:37] offset:1408
	s_waitcnt lgkmcnt(3)
	v_mfma_f32_32x32x16_bf16 v[2:17], v[114:117], v[118:121], v[2:17]
	s_waitcnt lgkmcnt(2)
	v_mfma_f32_32x32x16_bf16 v[18:33], v[114:117], v[130:133], v[18:33]
	v_mfma_f32_32x32x16_bf16 v[34:49], v[110:113], v[118:121], v[34:49]
	v_mfma_f32_32x32x16_bf16 v[50:65], v[110:113], v[130:133], v[50:65]
	ds_read_b128 v[110:113], v0 offset:36960
	ds_read_b128 v[118:121], v0 offset:41568
	ds_read_b128 v[122:125], v66 offset:55392
	ds_read_b128 v[126:129], v66 offset:60000
	s_waitcnt vmcnt(9)
	ds_write_b128 v67, v[86:89] offset:9216
	s_waitcnt vmcnt(8)
	ds_write_b128 v67, v[94:97] offset:27648
	global_load_dwordx4 v[86:89], v69, s[0:1] offset:1408
	global_load_dwordx4 v[94:97], v69, s[36:37] offset:1408
	s_waitcnt lgkmcnt(3)
	v_mfma_f32_32x32x16_bf16 v[2:17], v[118:121], v[122:125], v[2:17]
	s_waitcnt vmcnt(9)
	ds_write_b128 v67, v[98:101] offset:13824
	s_waitcnt vmcnt(8)
	ds_write_b128 v67, v[102:105] offset:32256
	s_waitcnt lgkmcnt(4)
	v_mfma_f32_32x32x16_bf16 v[18:33], v[118:121], v[126:129], v[18:33]
	v_mfma_f32_32x32x16_bf16 v[34:49], v[110:113], v[122:125], v[34:49]
	v_mfma_f32_32x32x16_bf16 v[50:65], v[110:113], v[126:129], v[50:65]
	s_waitcnt lgkmcnt(0)
	s_barrier
	ds_read_b128 v[98:101], v0
	ds_read_b128 v[102:105], v66 offset:18432
	ds_read_b128 v[110:113], v0 offset:32
	ds_read_b128 v[114:117], v66 offset:18464
	ds_read_b128 v[118:121], v0 offset:4608
	ds_read_b128 v[122:125], v0 offset:4640
	s_waitcnt lgkmcnt(4)
	v_mfma_f32_32x32x16_bf16 v[34:49], v[98:101], v[102:105], v[34:49]
	s_waitcnt lgkmcnt(1)
	v_mfma_f32_32x32x16_bf16 v[2:17], v[118:121], v[102:105], v[2:17]
	ds_read_b128 v[102:105], v66 offset:23040
	ds_read_b128 v[126:129], v66 offset:23072
	s_waitcnt lgkmcnt(1)
	v_mfma_f32_32x32x16_bf16 v[50:65], v[98:101], v[102:105], v[50:65]
	global_load_dwordx4 v[98:101], v72, s[0:1] offset:1536
	global_load_dwordx4 v[130:133], v72, s[36:37] offset:1536
	s_waitcnt vmcnt(9)
	ds_write_b128 v67, v[74:77] offset:36864
	s_waitcnt vmcnt(8)
	ds_write_b128 v67, v[134:137] offset:55296
	v_mfma_f32_32x32x16_bf16 v[18:33], v[118:121], v[102:105], v[18:33]
	global_load_dwordx4 v[74:77], v71, s[0:1] offset:1536
	global_load_dwordx4 v[102:105], v71, s[36:37] offset:1536
	v_mfma_f32_32x32x16_bf16 v[2:17], v[122:125], v[114:117], v[2:17]
	s_waitcnt lgkmcnt(2)
	v_mfma_f32_32x32x16_bf16 v[18:33], v[122:125], v[126:129], v[18:33]
	v_mfma_f32_32x32x16_bf16 v[34:49], v[110:113], v[114:117], v[34:49]
	v_mfma_f32_32x32x16_bf16 v[50:65], v[110:113], v[126:129], v[50:65]
	ds_read_b128 v[110:113], v0 offset:64
	ds_read_b128 v[114:117], v0 offset:4672
	ds_read_b128 v[118:121], v66 offset:18496
	ds_read_b128 v[134:137], v66 offset:23104
	s_waitcnt vmcnt(9)
	ds_write_b128 v67, v[78:81] offset:41472
	s_waitcnt vmcnt(8)
	ds_write_b128 v67, v[106:109] offset:59904
	global_load_dwordx4 v[78:81], v70, s[0:1] offset:1536
	global_load_dwordx4 v[106:109], v70, s[36:37] offset:1536
	s_waitcnt lgkmcnt(3)
	v_mfma_f32_32x32x16_bf16 v[2:17], v[114:117], v[118:121], v[2:17]
	s_waitcnt lgkmcnt(2)
	v_mfma_f32_32x32x16_bf16 v[18:33], v[114:117], v[134:137], v[18:33]
	v_mfma_f32_32x32x16_bf16 v[34:49], v[110:113], v[118:121], v[34:49]
	v_mfma_f32_32x32x16_bf16 v[50:65], v[110:113], v[134:137], v[50:65]
	ds_read_b128 v[110:113], v0 offset:96
	ds_read_b128 v[118:121], v0 offset:4704
	ds_read_b128 v[122:125], v66 offset:18528
	ds_read_b128 v[126:129], v66 offset:23136
	s_waitcnt vmcnt(9)
	ds_write_b128 v67, v[82:85] offset:46080
	s_waitcnt vmcnt(8)
	ds_write_b128 v67, v[90:93] offset:64512
	global_load_dwordx4 v[82:85], v69, s[0:1] offset:1536
	global_load_dwordx4 v[90:93], v69, s[36:37] offset:1536
	s_waitcnt lgkmcnt(3)
	v_mfma_f32_32x32x16_bf16 v[2:17], v[118:121], v[122:125], v[2:17]
	s_waitcnt vmcnt(9)
	ds_write_b128 v67, v[86:89] offset:50688
	s_waitcnt vmcnt(8)
	ds_write_b128 v68, v[94:97] offset:13824
	s_waitcnt lgkmcnt(4)
	v_mfma_f32_32x32x16_bf16 v[18:33], v[118:121], v[126:129], v[18:33]
	v_mfma_f32_32x32x16_bf16 v[34:49], v[110:113], v[122:125], v[34:49]
	v_mfma_f32_32x32x16_bf16 v[50:65], v[110:113], v[126:129], v[50:65]
	s_waitcnt lgkmcnt(0)
	s_barrier
; #define GL1_(RA, RB, i) { RA[i] = *(const u32x4*)(ap + (aoff + (i) * astep)); if ((i) < NB) RB[(i) < NB ? (i) : 0] = *(const u32x4*)(bp + (boff + (i) * bstep)); }
; #define LS1_(RA, RB, ST, i) { char* sn_ = lds + (ST) * STAGE; *(u32x4*)(sn_ + wofs + (i) * 32 * LROW) = RA[i]; \
;                               if ((i) < NB) *(u32x4*)(sn_ + STAGE_OP + wofs + (i) * 32 * LROW) = RB[(i) < NB ? (i) : 0]; }
; template <int NJ> DI void gemm_mainloop_reg(const bf16_t* __restrict__ A, int lda, const bf16_t* __restrict__ Bt, int ldb, int K, f32x16 (&acc)[2][NJ], char* lds) {
;     ...
; #pragma unroll
;   for (int i = 0; i < 4; ++i) GL1_(ra0, rb0, i);
;   ap += 128; bp += 128;
; #pragma unroll
;   for (int i = 0; i < 4; ++i) GL1_(ra1, rb1, i);
;   ap += 128; bp += 128;
; #pragma unroll
;   for (int i = 0; i < 4; ++i) LS1_(ra0, rb0, 0, i);
;   __syncthreads();
;   const int nk = K >> 6;
;   for (int kt = 0; kt < nk; kt += 2) {
;     const bool l0 = (kt + 2 < nk), l1 = (kt + 3 < nk);
;     STEP_(0, l0, ra0, rb0, true, ra1, rb1);
;     __syncthreads();
;     STEP_(1, l1, ra1, rb1, l0, ra0, rb0);
;     __syncthreads();
;   }
	ds_read_b128 v[86:89], v0 offset:36864
	ds_read_b128 v[94:97], v66 offset:55296
	ds_read_b128 v[110:113], v0 offset:36896
	ds_read_b128 v[114:117], v66 offset:55328
	ds_read_b128 v[118:121], v0 offset:41472
	ds_read_b128 v[122:125], v0 offset:41504
	s_waitcnt lgkmcnt(4)
	v_mfma_f32_32x32x16_bf16 v[34:49], v[86:89], v[94:97], v[34:49]
	s_waitcnt lgkmcnt(1)
	v_mfma_f32_32x32x16_bf16 v[2:17], v[118:121], v[94:97], v[2:17]
	ds_read_b128 v[94:97], v66 offset:59904
	ds_read_b128 v[126:129], v66 offset:59936
	s_waitcnt lgkmcnt(1)
	v_mfma_f32_32x32x16_bf16 v[50:65], v[86:89], v[94:97], v[50:65]
	global_load_dwordx4 v[86:89], v72, s[0:1] offset:1664
	global_load_dwordx4 v[134:137], v72, s[36:37] offset:1664
	s_waitcnt vmcnt(9)
	ds_write_b128 v67, v[98:101]
	s_waitcnt vmcnt(8)
	ds_write_b128 v67, v[130:133] offset:18432
	v_mfma_f32_32x32x16_bf16 v[18:33], v[118:121], v[94:97], v[18:33]
	global_load_dwordx4 v[94:97], v71, s[0:1] offset:1664
	global_load_dwordx4 v[98:101], v71, s[36:37] offset:1664
	v_mfma_f32_32x32x16_bf16 v[2:17], v[122:125], v[114:117], v[2:17]
	s_waitcnt lgkmcnt(2)
	v_mfma_f32_32x32x16_bf16 v[18:33], v[122:125], v[126:129], v[18:33]
	v_mfma_f32_32x32x16_bf16 v[34:49], v[110:113], v[114:117], v[34:49]
	v_mfma_f32_32x32x16_bf16 v[50:65], v[110:113], v[126:129], v[50:65]
	ds_read_b128 v[110:113], v0 offset:36928
	ds_read_b128 v[114:117], v0 offset:41536
	ds_read_b128 v[118:121], v66 offset:55360
	ds_read_b128 v[130:133], v66 offset:59968
	s_waitcnt vmcnt(9)
	ds_write_b128 v67, v[74:77] offset:4608
	s_waitcnt vmcnt(8)
	ds_write_b128 v67, v[102:105] offset:23040
	global_load_dwordx4 v[74:77], v70, s[0:1] offset:1664
	global_load_dwordx4 v[102:105], v70, s[36:37] offset:1664
	s_waitcnt lgkmcnt(3)
	v_mfma_f32_32x32x16_bf16 v[2:17], v[114:117], v[118:121], v[2:17]
	s_waitcnt lgkmcnt(2)
	v_mfma_f32_32x32x16_bf16 v[18:33], v[114:117], v[130:133], v[18:33]
	v_mfma_f32_32x32x16_bf16 v[34:49], v[110:113], v[118:121], v[34:49]
	v_mfma_f32_32x32x16_bf16 v[50:65], v[110:113], v[130:133], v[50:65]
	ds_read_b128 v[110:113], v0 offset:36960
	ds_read_b128 v[118:121], v0 offset:41568
	ds_read_b128 v[122:125], v66 offset:55392
	ds_read_b128 v[126:129], v66 offset:60000
	s_waitcnt vmcnt(9)
	ds_write_b128 v67, v[78:81] offset:9216
	s_waitcnt vmcnt(8)
	ds_write_b128 v67, v[106:109] offset:27648
	global_load_dwordx4 v[78:81], v69, s[0:1] offset:1664
	global_load_dwordx4 v[106:109], v69, s[36:37] offset:1664
	s_waitcnt lgkmcnt(3)
	v_mfma_f32_32x32x16_bf16 v[2:17], v[118:121], v[122:125], v[2:17]
	s_waitcnt vmcnt(9)
	ds_write_b128 v67, v[82:85] offset:13824
	s_waitcnt vmcnt(8)
	ds_write_b128 v67, v[90:93] offset:32256
	s_waitcnt lgkmcnt(4)
	v_mfma_f32_32x32x16_bf16 v[18:33], v[118:121], v[126:129], v[18:33]
	v_mfma_f32_32x32x16_bf16 v[34:49], v[110:113], v[122:125], v[34:49]
	v_mfma_f32_32x32x16_bf16 v[50:65], v[110:113], v[126:129], v[50:65]
	s_waitcnt lgkmcnt(0)
	s_barrier
	ds_read_b128 v[82:85], v0
	ds_read_b128 v[90:93], v66 offset:18432
	ds_read_b128 v[110:113], v0 offset:32
	ds_read_b128 v[114:117], v66 offset:18464
	ds_read_b128 v[118:121], v0 offset:4608
	ds_read_b128 v[122:125], v0 offset:4640
	s_waitcnt lgkmcnt(4)
	v_mfma_f32_32x32x16_bf16 v[34:49], v[82:85], v[90:93], v[34:49]
	s_waitcnt lgkmcnt(1)
	v_mfma_f32_32x32x16_bf16 v[2:17], v[118:121], v[90:93], v[2:17]
	ds_read_b128 v[90:93], v66 offset:23040
	ds_read_b128 v[126:129], v66 offset:23072
	s_waitcnt lgkmcnt(1)
	v_mfma_f32_32x32x16_bf16 v[50:65], v[82:85], v[90:93], v[50:65]
	global_load_dwordx4 v[82:85], v72, s[0:1] offset:1792
	global_load_dwordx4 v[130:133], v72, s[36:37] offset:1792
	s_waitcnt vmcnt(9)
	ds_write_b128 v67, v[86:89] offset:36864
	s_waitcnt vmcnt(8)
	ds_write_b128 v67, v[134:137] offset:55296
	v_mfma_f32_32x32x16_bf16 v[18:33], v[118:121], v[90:93], v[18:33]
	global_load_dwordx4 v[86:89], v71, s[0:1] offset:1792
	global_load_dwordx4 v[90:93], v71, s[36:37] offset:1792
	v_mfma_f32_32x32x16_bf16 v[2:17], v[122:125], v[114:117], v[2:17]
	s_waitcnt lgkmcnt(2)
	v_mfma_f32_32x32x16_bf16 v[18:33], v[122:125], v[126:129], v[18:33]
	v_mfma_f32_32x32x16_bf16 v[34:49], v[110:113], v[114:117], v[34:49]
	v_mfma_f32_32x32x16_bf16 v[50:65], v[110:113], v[126:129], v[50:65]
	ds_read_b128 v[110:113], v0 offset:64
	ds_read_b128 v[114:117], v0 offset:4672
	ds_read_b128 v[118:121], v66 offset:18496
	ds_read_b128 v[134:137], v66 offset:23104
	s_waitcnt vmcnt(9)
	ds_write_b128 v67, v[94:97] offset:41472
	s_waitcnt vmcnt(8)
	ds_write_b128 v67, v[98:101] offset:59904
	global_load_dwordx4 v[94:97], v70, s[0:1] offset:1792
	global_load_dwordx4 v[98:101], v70, s[36:37] offset:1792
	s_waitcnt lgkmcnt(3)
	v_mfma_f32_32x32x16_bf16 v[2:17], v[114:117], v[118:121], v[2:17]
	s_waitcnt lgkmcnt(2)
	v_mfma_f32_32x32x16_bf16 v[18:33], v[114:117], v[134:137], v[18:33]
	v_mfma_f32_32x32x16_bf16 v[34:49], v[110:113], v[118:121], v[34:49]
	v_mfma_f32_32x32x16_bf16 v[50:65], v[110:113], v[134:137], v[50:65]
	ds_read_b128 v[110:113], v0 offset:96
	ds_read_b128 v[118:121], v0 offset:4704
	ds_read_b128 v[122:125], v66 offset:18528
	ds_read_b128 v[126:129], v66 offset:23136
	s_waitcnt vmcnt(9)
	ds_write_b128 v67, v[74:77] offset:46080
	s_waitcnt vmcnt(8)
	ds_write_b128 v67, v[102:105] offset:64512
	global_load_dwordx4 v[74:77], v69, s[0:1] offset:1792
	global_load_dwordx4 v[102:105], v69, s[36:37] offset:1792
	s_waitcnt lgkmcnt(3)
	v_mfma_f32_32x32x16_bf16 v[2:17], v[118:121], v[122:125], v[2:17]
	s_waitcnt vmcnt(9)
	ds_write_b128 v67, v[78:81] offset:50688
	s_waitcnt vmcnt(8)
	ds_write_b128 v68, v[106:109] offset:13824
	s_waitcnt lgkmcnt(4)
	v_mfma_f32_32x32x16_bf16 v[18:33], v[118:121], v[126:129], v[18:33]
	v_mfma_f32_32x32x16_bf16 v[34:49], v[110:113], v[122:125], v[34:49]
	v_mfma_f32_32x32x16_bf16 v[50:65], v[110:113], v[126:129], v[50:65]
	s_waitcnt lgkmcnt(0)
	s_barrier
; #define GL1_(RA, RB, i) { RA[i] = *(const u32x4*)(ap + (aoff + (i) * astep)); if ((i) < NB) RB[(i) < NB ? (i) : 0] = *(const u32x4*)(bp + (boff + (i) * bstep)); }
; #define LS1_(RA, RB, ST, i) { char* sn_ = lds + (ST) * STAGE; *(u32x4*)(sn_ + wofs + (i) * 32 * LROW) = RA[i]; \
;                               if ((i) < NB) *(u32x4*)(sn_ + STAGE_OP + wofs + (i) * 32 * LROW) = RB[(i) < NB ? (i) : 0]; }
; template <int NJ> DI void gemm_mainloop_reg(const bf16_t* __restrict__ A, int lda, const bf16_t* __restrict__ Bt, int ldb, int K, f32x16 (&acc)[2][NJ], char* lds) {
;     ...
; #pragma unroll
;   for (int i = 0; i < 4; ++i) GL1_(ra0, rb0, i);
;   ap += 128; bp += 128;
; #pragma unroll
;   for (int i = 0; i < 4; ++i) GL1_(ra1, rb1, i);
;   ap += 128; bp += 128;
; #pragma unroll
;   for (int i = 0; i < 4; ++i) LS1_(ra0, rb0, 0, i);
;   __syncthreads();
;   const int nk = K >> 6;
;   for (int kt = 0; kt < nk; kt += 2) {
;     const bool l0 = (kt + 2 < nk), l1 = (kt + 3 < nk);
;     STEP_(0, l0, ra0, rb0, true, ra1, rb1);
;     __syncthreads();
;     STEP_(1, l1, ra1, rb1, l0, ra0, rb0);
;     __syncthreads();
;   }
	ds_read_b128 v[78:81], v0 offset:36864
	ds_read_b128 v[106:109], v66 offset:55296
	ds_read_b128 v[110:113], v0 offset:36896
	ds_read_b128 v[114:117], v66 offset:55328
	ds_read_b128 v[118:121], v0 offset:41472
	ds_read_b128 v[122:125], v0 offset:41504
	s_waitcnt lgkmcnt(4)
	v_mfma_f32_32x32x16_bf16 v[34:49], v[78:81], v[106:109], v[34:49]
	s_waitcnt lgkmcnt(1)
	v_mfma_f32_32x32x16_bf16 v[2:17], v[118:121], v[106:109], v[2:17]
	ds_read_b128 v[106:109], v66 offset:59904
	ds_read_b128 v[126:129], v66 offset:59936
	s_waitcnt lgkmcnt(1)
	v_mfma_f32_32x32x16_bf16 v[50:65], v[78:81], v[106:109], v[50:65]
	global_load_dwordx4 v[78:81], v72, s[0:1] offset:1920
	global_load_dwordx4 v[134:137], v72, s[36:37] offset:1920
	s_waitcnt vmcnt(9)
	ds_write_b128 v67, v[82:85]
	s_waitcnt vmcnt(8)
	ds_write_b128 v67, v[130:133] offset:18432
	v_mfma_f32_32x32x16_bf16 v[18:33], v[118:121], v[106:109], v[18:33]
	global_load_dwordx4 v[82:85], v71, s[0:1] offset:1920
	global_load_dwordx4 v[106:109], v71, s[36:37] offset:1920
	v_mfma_f32_32x32x16_bf16 v[2:17], v[122:125], v[114:117], v[2:17]
	s_waitcnt lgkmcnt(2)
	v_mfma_f32_32x32x16_bf16 v[18:33], v[122:125], v[126:129], v[18:33]
	v_mfma_f32_32x32x16_bf16 v[34:49], v[110:113], v[114:117], v[34:49]
	v_mfma_f32_32x32x16_bf16 v[50:65], v[110:113], v[126:129], v[50:65]
	ds_read_b128 v[110:113], v0 offset:36928
	ds_read_b128 v[114:117], v0 offset:41536
	ds_read_b128 v[118:121], v66 offset:55360
	ds_read_b128 v[130:133], v66 offset:59968
	s_waitcnt vmcnt(9)
	ds_write_b128 v67, v[86:89] offset:4608
	s_waitcnt vmcnt(8)
	ds_write_b128 v67, v[90:93] offset:23040
	global_load_dwordx4 v[86:89], v70, s[0:1] offset:1920
	global_load_dwordx4 v[90:93], v70, s[36:37] offset:1920
	s_waitcnt lgkmcnt(3)
	v_mfma_f32_32x32x16_bf16 v[2:17], v[114:117], v[118:121], v[2:17]
	s_waitcnt lgkmcnt(2)
	v_mfma_f32_32x32x16_bf16 v[18:33], v[114:117], v[130:133], v[18:33]
	v_mfma_f32_32x32x16_bf16 v[34:49], v[110:113], v[118:121], v[34:49]
	v_mfma_f32_32x32x16_bf16 v[50:65], v[110:113], v[130:133], v[50:65]
	ds_read_b128 v[110:113], v0 offset:36960
	ds_read_b128 v[118:121], v0 offset:41568
	ds_read_b128 v[122:125], v66 offset:55392
	ds_read_b128 v[126:129], v66 offset:60000
	s_waitcnt vmcnt(9)
	ds_write_b128 v67, v[94:97] offset:9216
	s_waitcnt vmcnt(8)
	ds_write_b128 v67, v[98:101] offset:27648
	global_load_dwordx4 v[94:97], v69, s[0:1] offset:1920
	global_load_dwordx4 v[98:101], v69, s[36:37] offset:1920
	s_waitcnt lgkmcnt(3)
	v_mfma_f32_32x32x16_bf16 v[2:17], v[118:121], v[122:125], v[2:17]
	s_waitcnt vmcnt(9)
	ds_write_b128 v67, v[74:77] offset:13824
	s_waitcnt vmcnt(8)
	ds_write_b128 v67, v[102:105] offset:32256
	s_waitcnt lgkmcnt(4)
	v_mfma_f32_32x32x16_bf16 v[18:33], v[118:121], v[126:129], v[18:33]
	v_mfma_f32_32x32x16_bf16 v[34:49], v[110:113], v[122:125], v[34:49]
	v_mfma_f32_32x32x16_bf16 v[50:65], v[110:113], v[126:129], v[50:65]
	s_waitcnt lgkmcnt(0)
	s_barrier
	ds_read_b128 v[74:77], v0
	ds_read_b128 v[102:105], v66 offset:18432
	ds_read_b128 v[110:113], v0 offset:32
	ds_read_b128 v[114:117], v66 offset:18464
	ds_read_b128 v[118:121], v0 offset:4608
	ds_read_b128 v[122:125], v0 offset:4640
	s_waitcnt lgkmcnt(4)
	v_mfma_f32_32x32x16_bf16 v[34:49], v[74:77], v[102:105], v[34:49]
	s_waitcnt lgkmcnt(1)
	v_mfma_f32_32x32x16_bf16 v[2:17], v[118:121], v[102:105], v[2:17]
	ds_read_b128 v[102:105], v66 offset:23040
	ds_read_b128 v[126:129], v66 offset:23072
	s_waitcnt lgkmcnt(1)
	v_mfma_f32_32x32x16_bf16 v[50:65], v[74:77], v[102:105], v[50:65]
	global_load_dwordx4 v[74:77], v72, s[0:1] offset:2048
	global_load_dwordx4 v[130:133], v72, s[36:37] offset:2048
	s_waitcnt vmcnt(9)
	ds_write_b128 v67, v[78:81] offset:36864
	s_waitcnt vmcnt(8)
	ds_write_b128 v67, v[134:137] offset:55296
	v_mfma_f32_32x32x16_bf16 v[18:33], v[118:121], v[102:105], v[18:33]
	global_load_dwordx4 v[78:81], v71, s[0:1] offset:2048
	global_load_dwordx4 v[102:105], v71, s[36:37] offset:2048
	v_mfma_f32_32x32x16_bf16 v[2:17], v[122:125], v[114:117], v[2:17]
	s_waitcnt lgkmcnt(2)
	v_mfma_f32_32x32x16_bf16 v[18:33], v[122:125], v[126:129], v[18:33]
	v_mfma_f32_32x32x16_bf16 v[34:49], v[110:113], v[114:117], v[34:49]
	v_mfma_f32_32x32x16_bf16 v[50:65], v[110:113], v[126:129], v[50:65]
	ds_read_b128 v[110:113], v0 offset:64
	ds_read_b128 v[114:117], v0 offset:4672
	ds_read_b128 v[118:121], v66 offset:18496
	ds_read_b128 v[134:137], v66 offset:23104
	s_waitcnt vmcnt(9)
	ds_write_b128 v67, v[82:85] offset:41472
	s_waitcnt vmcnt(8)
	ds_write_b128 v67, v[106:109] offset:59904
	global_load_dwordx4 v[82:85], v70, s[0:1] offset:2048
	global_load_dwordx4 v[106:109], v70, s[36:37] offset:2048
	s_waitcnt lgkmcnt(3)
	v_mfma_f32_32x32x16_bf16 v[2:17], v[114:117], v[118:121], v[2:17]
	s_waitcnt lgkmcnt(2)
	v_mfma_f32_32x32x16_bf16 v[18:33], v[114:117], v[134:137], v[18:33]
	v_mfma_f32_32x32x16_bf16 v[34:49], v[110:113], v[118:121], v[34:49]
	v_mfma_f32_32x32x16_bf16 v[50:65], v[110:113], v[134:137], v[50:65]
	ds_read_b128 v[110:113], v0 offset:96
	ds_read_b128 v[118:121], v0 offset:4704
	ds_read_b128 v[122:125], v66 offset:18528
	ds_read_b128 v[126:129], v66 offset:23136
	s_waitcnt vmcnt(9)
	ds_write_b128 v67, v[86:89] offset:46080
	s_waitcnt vmcnt(8)
	ds_write_b128 v67, v[90:93] offset:64512
	global_load_dwordx4 v[86:89], v69, s[0:1] offset:2048
	global_load_dwordx4 v[90:93], v69, s[36:37] offset:2048
	s_waitcnt lgkmcnt(3)
	v_mfma_f32_32x32x16_bf16 v[2:17], v[118:121], v[122:125], v[2:17]
	s_waitcnt vmcnt(9)
	ds_write_b128 v67, v[94:97] offset:50688
	s_waitcnt vmcnt(8)
	ds_write_b128 v68, v[98:101] offset:13824
	s_waitcnt lgkmcnt(4)
	v_mfma_f32_32x32x16_bf16 v[18:33], v[118:121], v[126:129], v[18:33]
	v_mfma_f32_32x32x16_bf16 v[34:49], v[110:113], v[122:125], v[34:49]
	v_mfma_f32_32x32x16_bf16 v[50:65], v[110:113], v[126:129], v[50:65]
	s_waitcnt lgkmcnt(0)
	s_barrier
; #define GL1_(RA, RB, i) { RA[i] = *(const u32x4*)(ap + (aoff + (i) * astep)); if ((i) < NB) RB[(i) < NB ? (i) : 0] = *(const u32x4*)(bp + (boff + (i) * bstep)); }
; #define LS1_(RA, RB, ST, i) { char* sn_ = lds + (ST) * STAGE; *(u32x4*)(sn_ + wofs + (i) * 32 * LROW) = RA[i]; \
;                               if ((i) < NB) *(u32x4*)(sn_ + STAGE_OP + wofs + (i) * 32 * LROW) = RB[(i) < NB ? (i) : 0]; }
; template <int NJ> DI void gemm_mainloop_reg(const bf16_t* __restrict__ A, int lda, const bf16_t* __restrict__ Bt, int ldb, int K, f32x16 (&acc)[2][NJ], char* lds) {
;     ...
; #pragma unroll
;   for (int i = 0; i < 4; ++i) GL1_(ra0, rb0, i);
;   ap += 128; bp += 128;
; #pragma unroll
;   for (int i = 0; i < 4; ++i) GL1_(ra1, rb1, i);
;   ap += 128; bp += 128;
; #pragma unroll
;   for (int i = 0; i < 4; ++i) LS1_(ra0, rb0, 0, i);
;   __syncthreads();
;   const int nk = K >> 6;
;   for (int kt = 0; kt < nk; kt += 2) {
;     const bool l0 = (kt + 2 < nk), l1 = (kt + 3 < nk);
;     STEP_(0, l0, ra0, rb0, true, ra1, rb1);
;     __syncthreads();
;     STEP_(1, l1, ra1, rb1, l0, ra0, rb0);
;     __syncthreads();
;   }
	ds_read_b128 v[94:97], v0 offset:36864
	ds_read_b128 v[98:101], v66 offset:55296
	ds_read_b128 v[110:113], v0 offset:36896
	ds_read_b128 v[114:117], v66 offset:55328
	ds_read_b128 v[118:121], v0 offset:41472
	ds_read_b128 v[122:125], v0 offset:41504
	s_waitcnt lgkmcnt(4)
	v_mfma_f32_32x32x16_bf16 v[34:49], v[94:97], v[98:101], v[34:49]
	s_waitcnt lgkmcnt(1)
	v_mfma_f32_32x32x16_bf16 v[2:17], v[118:121], v[98:101], v[2:17]
	ds_read_b128 v[98:101], v66 offset:59904
	ds_read_b128 v[126:129], v66 offset:59936
	s_waitcnt lgkmcnt(1)
	v_mfma_f32_32x32x16_bf16 v[50:65], v[94:97], v[98:101], v[50:65]
	global_load_dwordx4 v[94:97], v72, s[0:1] offset:2176
	global_load_dwordx4 v[134:137], v72, s[36:37] offset:2176
	s_waitcnt vmcnt(9)
	ds_write_b128 v67, v[74:77]
	s_waitcnt vmcnt(8)
	ds_write_b128 v67, v[130:133] offset:18432
	v_mfma_f32_32x32x16_bf16 v[18:33], v[118:121], v[98:101], v[18:33]
	global_load_dwordx4 v[74:77], v71, s[0:1] offset:2176
	global_load_dwordx4 v[98:101], v71, s[36:37] offset:2176
	v_mfma_f32_32x32x16_bf16 v[2:17], v[122:125], v[114:117], v[2:17]
	s_waitcnt lgkmcnt(2)
	v_mfma_f32_32x32x16_bf16 v[18:33], v[122:125], v[126:129], v[18:33]
	v_mfma_f32_32x32x16_bf16 v[34:49], v[110:113], v[114:117], v[34:49]
	v_mfma_f32_32x32x16_bf16 v[50:65], v[110:113], v[126:129], v[50:65]
	ds_read_b128 v[110:113], v0 offset:36928
	ds_read_b128 v[114:117], v0 offset:41536
	ds_read_b128 v[118:121], v66 offset:55360
	ds_read_b128 v[130:133], v66 offset:59968
	s_waitcnt vmcnt(9)
	ds_write_b128 v67, v[78:81] offset:4608
	s_waitcnt vmcnt(8)
	ds_write_b128 v67, v[102:105] offset:23040
	global_load_dwordx4 v[78:81], v70, s[0:1] offset:2176
	global_load_dwordx4 v[102:105], v70, s[36:37] offset:2176
	s_waitcnt lgkmcnt(3)
	v_mfma_f32_32x32x16_bf16 v[2:17], v[114:117], v[118:121], v[2:17]
	s_waitcnt lgkmcnt(2)
	v_mfma_f32_32x32x16_bf16 v[18:33], v[114:117], v[130:133], v[18:33]
	v_mfma_f32_32x32x16_bf16 v[34:49], v[110:113], v[118:121], v[34:49]
	v_mfma_f32_32x32x16_bf16 v[50:65], v[110:113], v[130:133], v[50:65]
	ds_read_b128 v[110:113], v0 offset:36960
	ds_read_b128 v[118:121], v0 offset:41568
	ds_read_b128 v[122:125], v66 offset:55392
	ds_read_b128 v[126:129], v66 offset:60000
	s_waitcnt vmcnt(9)
	ds_write_b128 v67, v[82:85] offset:9216
	s_waitcnt vmcnt(8)
	ds_write_b128 v67, v[106:109] offset:27648
	global_load_dwordx4 v[82:85], v69, s[0:1] offset:2176
	global_load_dwordx4 v[106:109], v69, s[36:37] offset:2176
	s_waitcnt lgkmcnt(3)
	v_mfma_f32_32x32x16_bf16 v[2:17], v[118:121], v[122:125], v[2:17]
	s_waitcnt vmcnt(9)
	ds_write_b128 v67, v[86:89] offset:13824
	s_waitcnt vmcnt(8)
	ds_write_b128 v67, v[90:93] offset:32256
	s_waitcnt lgkmcnt(4)
	v_mfma_f32_32x32x16_bf16 v[18:33], v[118:121], v[126:129], v[18:33]
	v_mfma_f32_32x32x16_bf16 v[34:49], v[110:113], v[122:125], v[34:49]
	v_mfma_f32_32x32x16_bf16 v[50:65], v[110:113], v[126:129], v[50:65]
	s_waitcnt lgkmcnt(0)
	s_barrier
	ds_read_b128 v[86:89], v0
	ds_read_b128 v[90:93], v66 offset:18432
	ds_read_b128 v[110:113], v0 offset:32
	ds_read_b128 v[114:117], v66 offset:18464
	ds_read_b128 v[118:121], v0 offset:4608
	ds_read_b128 v[122:125], v0 offset:4640
	s_waitcnt lgkmcnt(4)
	v_mfma_f32_32x32x16_bf16 v[34:49], v[86:89], v[90:93], v[34:49]
	s_waitcnt lgkmcnt(1)
	v_mfma_f32_32x32x16_bf16 v[2:17], v[118:121], v[90:93], v[2:17]
	ds_read_b128 v[90:93], v66 offset:23040
	ds_read_b128 v[126:129], v66 offset:23072
	s_waitcnt lgkmcnt(1)
	v_mfma_f32_32x32x16_bf16 v[50:65], v[86:89], v[90:93], v[50:65]
	global_load_dwordx4 v[86:89], v72, s[0:1] offset:2304
	global_load_dwordx4 v[130:133], v72, s[36:37] offset:2304
	s_waitcnt vmcnt(9)
	ds_write_b128 v67, v[94:97] offset:36864
	s_waitcnt vmcnt(8)
	ds_write_b128 v67, v[134:137] offset:55296
	v_mfma_f32_32x32x16_bf16 v[18:33], v[118:121], v[90:93], v[18:33]
	global_load_dwordx4 v[90:93], v71, s[0:1] offset:2304
	global_load_dwordx4 v[94:97], v71, s[36:37] offset:2304
	v_mfma_f32_32x32x16_bf16 v[2:17], v[122:125], v[114:117], v[2:17]
	s_waitcnt lgkmcnt(2)
	v_mfma_f32_32x32x16_bf16 v[18:33], v[122:125], v[126:129], v[18:33]
	v_mfma_f32_32x32x16_bf16 v[34:49], v[110:113], v[114:117], v[34:49]
	v_mfma_f32_32x32x16_bf16 v[50:65], v[110:113], v[126:129], v[50:65]
	ds_read_b128 v[110:113], v0 offset:64
	ds_read_b128 v[114:117], v0 offset:4672
	ds_read_b128 v[118:121], v66 offset:18496
	ds_read_b128 v[134:137], v66 offset:23104
	s_waitcnt vmcnt(9)
	ds_write_b128 v67, v[74:77] offset:41472
	s_waitcnt vmcnt(8)
	ds_write_b128 v67, v[98:101] offset:59904
	global_load_dwordx4 v[74:77], v70, s[0:1] offset:2304
	global_load_dwordx4 v[98:101], v70, s[36:37] offset:2304
	s_waitcnt lgkmcnt(3)
	v_mfma_f32_32x32x16_bf16 v[2:17], v[114:117], v[118:121], v[2:17]
	s_waitcnt lgkmcnt(2)
	v_mfma_f32_32x32x16_bf16 v[18:33], v[114:117], v[134:137], v[18:33]
	v_mfma_f32_32x32x16_bf16 v[34:49], v[110:113], v[118:121], v[34:49]
	v_mfma_f32_32x32x16_bf16 v[50:65], v[110:113], v[134:137], v[50:65]
	ds_read_b128 v[110:113], v0 offset:96
	ds_read_b128 v[118:121], v0 offset:4704
	ds_read_b128 v[122:125], v66 offset:18528
	ds_read_b128 v[126:129], v66 offset:23136
	s_waitcnt vmcnt(9)
	ds_write_b128 v67, v[78:81] offset:46080
	s_waitcnt vmcnt(8)
	ds_write_b128 v67, v[102:105] offset:64512
	global_load_dwordx4 v[78:81], v69, s[0:1] offset:2304
	global_load_dwordx4 v[102:105], v69, s[36:37] offset:2304
	s_waitcnt lgkmcnt(3)
	v_mfma_f32_32x32x16_bf16 v[2:17], v[118:121], v[122:125], v[2:17]
	s_waitcnt vmcnt(9)
	ds_write_b128 v67, v[82:85] offset:50688
	s_waitcnt vmcnt(8)
	ds_write_b128 v68, v[106:109] offset:13824
	s_waitcnt lgkmcnt(4)
	v_mfma_f32_32x32x16_bf16 v[18:33], v[118:121], v[126:129], v[18:33]
	v_mfma_f32_32x32x16_bf16 v[34:49], v[110:113], v[122:125], v[34:49]
	v_mfma_f32_32x32x16_bf16 v[50:65], v[110:113], v[126:129], v[50:65]
	s_waitcnt lgkmcnt(0)
	s_barrier
; #define GL1_(RA, RB, i) { RA[i] = *(const u32x4*)(ap + (aoff + (i) * astep)); if ((i) < NB) RB[(i) < NB ? (i) : 0] = *(const u32x4*)(bp + (boff + (i) * bstep)); }
; #define LS1_(RA, RB, ST, i) { char* sn_ = lds + (ST) * STAGE; *(u32x4*)(sn_ + wofs + (i) * 32 * LROW) = RA[i]; \
;                               if ((i) < NB) *(u32x4*)(sn_ + STAGE_OP + wofs + (i) * 32 * LROW) = RB[(i) < NB ? (i) : 0]; }
; template <int NJ> DI void gemm_mainloop_reg(const bf16_t* __restrict__ A, int lda, const bf16_t* __restrict__ Bt, int ldb, int K, f32x16 (&acc)[2][NJ], char* lds) {
;     ...
; #pragma unroll
;   for (int i = 0; i < 4; ++i) GL1_(ra0, rb0, i);
;   ap += 128; bp += 128;
; #pragma unroll
;   for (int i = 0; i < 4; ++i) GL1_(ra1, rb1, i);
;   ap += 128; bp += 128;
; #pragma unroll
;   for (int i = 0; i < 4; ++i) LS1_(ra0, rb0, 0, i);
;   __syncthreads();
;   const int nk = K >> 6;
;   for (int kt = 0; kt < nk; kt += 2) {
;     const bool l0 = (kt + 2 < nk), l1 = (kt + 3 < nk);
;     STEP_(0, l0, ra0, rb0, true, ra1, rb1);
;     __syncthreads();
;     STEP_(1, l1, ra1, rb1, l0, ra0, rb0);
;     __syncthreads();
;   }
	ds_read_b128 v[82:85], v0 offset:36864
	ds_read_b128 v[106:109], v66 offset:55296
	ds_read_b128 v[110:113], v0 offset:36896
	ds_read_b128 v[114:117], v66 offset:55328
	ds_read_b128 v[118:121], v0 offset:41472
	ds_read_b128 v[122:125], v0 offset:41504
	s_waitcnt lgkmcnt(4)
	v_mfma_f32_32x32x16_bf16 v[34:49], v[82:85], v[106:109], v[34:49]
	s_waitcnt lgkmcnt(1)
	v_mfma_f32_32x32x16_bf16 v[2:17], v[118:121], v[106:109], v[2:17]
	ds_read_b128 v[106:109], v66 offset:59904
	ds_read_b128 v[126:129], v66 offset:59936
	s_waitcnt lgkmcnt(1)
	v_mfma_f32_32x32x16_bf16 v[50:65], v[82:85], v[106:109], v[50:65]
	global_load_dwordx4 v[82:85], v72, s[0:1] offset:2432
	global_load_dwordx4 v[134:137], v72, s[36:37] offset:2432
	s_waitcnt vmcnt(9)
	ds_write_b128 v67, v[86:89]
	s_waitcnt vmcnt(8)
	ds_write_b128 v67, v[130:133] offset:18432
	v_mfma_f32_32x32x16_bf16 v[18:33], v[118:121], v[106:109], v[18:33]
	global_load_dwordx4 v[86:89], v71, s[0:1] offset:2432
	global_load_dwordx4 v[106:109], v71, s[36:37] offset:2432
	v_mfma_f32_32x32x16_bf16 v[2:17], v[122:125], v[114:117], v[2:17]
	s_waitcnt lgkmcnt(2)
	v_mfma_f32_32x32x16_bf16 v[18:33], v[122:125], v[126:129], v[18:33]
	v_mfma_f32_32x32x16_bf16 v[34:49], v[110:113], v[114:117], v[34:49]
	v_mfma_f32_32x32x16_bf16 v[50:65], v[110:113], v[126:129], v[50:65]
	ds_read_b128 v[110:113], v0 offset:36928
	ds_read_b128 v[114:117], v0 offset:41536
	ds_read_b128 v[118:121], v66 offset:55360
	ds_read_b128 v[130:133], v66 offset:59968
	s_waitcnt vmcnt(9)
	ds_write_b128 v67, v[90:93] offset:4608
	s_waitcnt vmcnt(8)
	ds_write_b128 v67, v[94:97] offset:23040
	global_load_dwordx4 v[90:93], v70, s[0:1] offset:2432
	global_load_dwordx4 v[94:97], v70, s[36:37] offset:2432
	s_waitcnt lgkmcnt(3)
	v_mfma_f32_32x32x16_bf16 v[2:17], v[114:117], v[118:121], v[2:17]
	s_waitcnt lgkmcnt(2)
	v_mfma_f32_32x32x16_bf16 v[18:33], v[114:117], v[130:133], v[18:33]
	v_mfma_f32_32x32x16_bf16 v[34:49], v[110:113], v[118:121], v[34:49]
	v_mfma_f32_32x32x16_bf16 v[50:65], v[110:113], v[130:133], v[50:65]
	ds_read_b128 v[110:113], v0 offset:36960
	ds_read_b128 v[118:121], v0 offset:41568
	ds_read_b128 v[122:125], v66 offset:55392
	ds_read_b128 v[126:129], v66 offset:60000
	s_waitcnt vmcnt(9)
	ds_write_b128 v67, v[74:77] offset:9216
	s_waitcnt vmcnt(8)
	ds_write_b128 v67, v[98:101] offset:27648
	global_load_dwordx4 v[74:77], v69, s[0:1] offset:2432
	global_load_dwordx4 v[98:101], v69, s[36:37] offset:2432
	s_waitcnt lgkmcnt(3)
	v_mfma_f32_32x32x16_bf16 v[2:17], v[118:121], v[122:125], v[2:17]
	s_waitcnt vmcnt(9)
	ds_write_b128 v67, v[78:81] offset:13824
	s_waitcnt vmcnt(8)
	ds_write_b128 v67, v[102:105] offset:32256
	s_waitcnt lgkmcnt(4)
	v_mfma_f32_32x32x16_bf16 v[18:33], v[118:121], v[126:129], v[18:33]
	v_mfma_f32_32x32x16_bf16 v[34:49], v[110:113], v[122:125], v[34:49]
	v_mfma_f32_32x32x16_bf16 v[50:65], v[110:113], v[126:129], v[50:65]
	s_waitcnt lgkmcnt(0)
	s_barrier
	ds_read_b128 v[78:81], v0
	ds_read_b128 v[102:105], v66 offset:18432
	ds_read_b128 v[110:113], v0 offset:32
	ds_read_b128 v[114:117], v66 offset:18464
	ds_read_b128 v[118:121], v0 offset:4608
	ds_read_b128 v[122:125], v0 offset:4640
	s_waitcnt lgkmcnt(4)
	v_mfma_f32_32x32x16_bf16 v[34:49], v[78:81], v[102:105], v[34:49]
	s_waitcnt lgkmcnt(1)
	v_mfma_f32_32x32x16_bf16 v[2:17], v[118:121], v[102:105], v[2:17]
	ds_read_b128 v[102:105], v66 offset:23040
	ds_read_b128 v[126:129], v66 offset:23072
	s_waitcnt lgkmcnt(1)
	v_mfma_f32_32x32x16_bf16 v[50:65], v[78:81], v[102:105], v[50:65]
	global_load_dwordx4 v[78:81], v72, s[0:1] offset:2560
	global_load_dwordx4 v[130:133], v72, s[36:37] offset:2560
	s_waitcnt vmcnt(9)
	ds_write_b128 v67, v[82:85] offset:36864
	s_waitcnt vmcnt(8)
	ds_write_b128 v67, v[134:137] offset:55296
	v_mfma_f32_32x32x16_bf16 v[18:33], v[118:121], v[102:105], v[18:33]
	global_load_dwordx4 v[82:85], v71, s[0:1] offset:2560
	global_load_dwordx4 v[102:105], v71, s[36:37] offset:2560
	v_mfma_f32_32x32x16_bf16 v[2:17], v[122:125], v[114:117], v[2:17]
	s_waitcnt lgkmcnt(2)
	v_mfma_f32_32x32x16_bf16 v[18:33], v[122:125], v[126:129], v[18:33]
	v_mfma_f32_32x32x16_bf16 v[34:49], v[110:113], v[114:117], v[34:49]
	v_mfma_f32_32x32x16_bf16 v[50:65], v[110:113], v[126:129], v[50:65]
	ds_read_b128 v[110:113], v0 offset:64
	ds_read_b128 v[114:117], v0 offset:4672
	ds_read_b128 v[118:121], v66 offset:18496
	ds_read_b128 v[134:137], v66 offset:23104
	s_waitcnt vmcnt(9)
	ds_write_b128 v67, v[86:89] offset:41472
	s_waitcnt vmcnt(8)
	ds_write_b128 v67, v[106:109] offset:59904
	global_load_dwordx4 v[86:89], v70, s[0:1] offset:2560
	global_load_dwordx4 v[106:109], v70, s[36:37] offset:2560
	s_waitcnt lgkmcnt(3)
	v_mfma_f32_32x32x16_bf16 v[2:17], v[114:117], v[118:121], v[2:17]
	s_waitcnt lgkmcnt(2)
	v_mfma_f32_32x32x16_bf16 v[18:33], v[114:117], v[134:137], v[18:33]
	v_mfma_f32_32x32x16_bf16 v[34:49], v[110:113], v[118:121], v[34:49]
	v_mfma_f32_32x32x16_bf16 v[50:65], v[110:113], v[134:137], v[50:65]
	ds_read_b128 v[110:113], v0 offset:96
	ds_read_b128 v[118:121], v0 offset:4704
	ds_read_b128 v[122:125], v66 offset:18528
	ds_read_b128 v[126:129], v66 offset:23136
	s_waitcnt vmcnt(9)
	ds_write_b128 v67, v[90:93] offset:46080
	s_waitcnt vmcnt(8)
	ds_write_b128 v67, v[94:97] offset:64512
	global_load_dwordx4 v[90:93], v69, s[0:1] offset:2560
	global_load_dwordx4 v[94:97], v69, s[36:37] offset:2560
	s_waitcnt lgkmcnt(3)
	v_mfma_f32_32x32x16_bf16 v[2:17], v[118:121], v[122:125], v[2:17]
	s_waitcnt vmcnt(9)
	ds_write_b128 v67, v[74:77] offset:50688
	s_waitcnt vmcnt(8)
	ds_write_b128 v68, v[98:101] offset:13824
	s_waitcnt lgkmcnt(4)
	v_mfma_f32_32x32x16_bf16 v[18:33], v[118:121], v[126:129], v[18:33]
	v_mfma_f32_32x32x16_bf16 v[34:49], v[110:113], v[122:125], v[34:49]
	v_mfma_f32_32x32x16_bf16 v[50:65], v[110:113], v[126:129], v[50:65]
	s_waitcnt lgkmcnt(0)
	s_barrier
; #define GL1_(RA, RB, i) { RA[i] = *(const u32x4*)(ap + (aoff + (i) * astep)); if ((i) < NB) RB[(i) < NB ? (i) : 0] = *(const u32x4*)(bp + (boff + (i) * bstep)); }
; #define LS1_(RA, RB, ST, i) { char* sn_ = lds + (ST) * STAGE; *(u32x4*)(sn_ + wofs + (i) * 32 * LROW) = RA[i]; \
;                               if ((i) < NB) *(u32x4*)(sn_ + STAGE_OP + wofs + (i) * 32 * LROW) = RB[(i) < NB ? (i) : 0]; }
; template <int NJ> DI void gemm_mainloop_reg(const bf16_t* __restrict__ A, int lda, const bf16_t* __restrict__ Bt, int ldb, int K, f32x16 (&acc)[2][NJ], char* lds) {
;     ...
; #pragma unroll
;   for (int i = 0; i < 4; ++i) GL1_(ra0, rb0, i);
;   ap += 128; bp += 128;
; #pragma unroll
;   for (int i = 0; i < 4; ++i) GL1_(ra1, rb1, i);
;   ap += 128; bp += 128;
; #pragma unroll
;   for (int i = 0; i < 4; ++i) LS1_(ra0, rb0, 0, i);
;   __syncthreads();
;   const int nk = K >> 6;
;   for (int kt = 0; kt < nk; kt += 2) {
;     const bool l0 = (kt + 2 < nk), l1 = (kt + 3 < nk);
;     STEP_(0, l0, ra0, rb0, true, ra1, rb1);
;     __syncthreads();
;     STEP_(1, l1, ra1, rb1, l0, ra0, rb0);
;     __syncthreads();
;   }
	ds_read_b128 v[74:77], v0 offset:36864
	ds_read_b128 v[98:101], v66 offset:55296
	ds_read_b128 v[110:113], v0 offset:36896
	ds_read_b128 v[114:117], v66 offset:55328
	ds_read_b128 v[118:121], v0 offset:41472
	ds_read_b128 v[122:125], v0 offset:41504
	s_waitcnt lgkmcnt(4)
	v_mfma_f32_32x32x16_bf16 v[34:49], v[74:77], v[98:101], v[34:49]
	s_waitcnt lgkmcnt(1)
	v_mfma_f32_32x32x16_bf16 v[2:17], v[118:121], v[98:101], v[2:17]
	ds_read_b128 v[98:101], v66 offset:59904
	ds_read_b128 v[126:129], v66 offset:59936
	s_waitcnt lgkmcnt(1)
	v_mfma_f32_32x32x16_bf16 v[50:65], v[74:77], v[98:101], v[50:65]
	global_load_dwordx4 v[74:77], v72, s[0:1] offset:2688
	global_load_dwordx4 v[134:137], v72, s[36:37] offset:2688
	s_waitcnt vmcnt(9)
	ds_write_b128 v67, v[78:81]
	s_waitcnt vmcnt(8)
	ds_write_b128 v67, v[130:133] offset:18432
	v_mfma_f32_32x32x16_bf16 v[18:33], v[118:121], v[98:101], v[18:33]
	global_load_dwordx4 v[78:81], v71, s[0:1] offset:2688
	global_load_dwordx4 v[98:101], v71, s[36:37] offset:2688
	v_mfma_f32_32x32x16_bf16 v[2:17], v[122:125], v[114:117], v[2:17]
	s_waitcnt lgkmcnt(2)
	v_mfma_f32_32x32x16_bf16 v[18:33], v[122:125], v[126:129], v[18:33]
	v_mfma_f32_32x32x16_bf16 v[34:49], v[110:113], v[114:117], v[34:49]
	v_mfma_f32_32x32x16_bf16 v[50:65], v[110:113], v[126:129], v[50:65]
	ds_read_b128 v[110:113], v0 offset:36928
	ds_read_b128 v[114:117], v0 offset:41536
	ds_read_b128 v[118:121], v66 offset:55360
	ds_read_b128 v[130:133], v66 offset:59968
	s_waitcnt vmcnt(9)
	ds_write_b128 v67, v[82:85] offset:4608
	s_waitcnt vmcnt(8)
	ds_write_b128 v67, v[102:105] offset:23040
	global_load_dwordx4 v[82:85], v70, s[0:1] offset:2688
	global_load_dwordx4 v[102:105], v70, s[36:37] offset:2688
	s_waitcnt lgkmcnt(3)
	v_mfma_f32_32x32x16_bf16 v[2:17], v[114:117], v[118:121], v[2:17]
	s_waitcnt lgkmcnt(2)
	v_mfma_f32_32x32x16_bf16 v[18:33], v[114:117], v[130:133], v[18:33]
	v_mfma_f32_32x32x16_bf16 v[34:49], v[110:113], v[118:121], v[34:49]
	v_mfma_f32_32x32x16_bf16 v[50:65], v[110:113], v[130:133], v[50:65]
	ds_read_b128 v[110:113], v0 offset:36960
	ds_read_b128 v[118:121], v0 offset:41568
	ds_read_b128 v[122:125], v66 offset:55392
	ds_read_b128 v[126:129], v66 offset:60000
	s_waitcnt vmcnt(9)
	ds_write_b128 v67, v[86:89] offset:9216
	s_waitcnt vmcnt(8)
	ds_write_b128 v67, v[106:109] offset:27648
	global_load_dwordx4 v[86:89], v69, s[0:1] offset:2688
	global_load_dwordx4 v[106:109], v69, s[36:37] offset:2688
	s_waitcnt lgkmcnt(3)
	v_mfma_f32_32x32x16_bf16 v[2:17], v[118:121], v[122:125], v[2:17]
	s_waitcnt vmcnt(9)
	ds_write_b128 v67, v[90:93] offset:13824
	s_waitcnt vmcnt(8)
	ds_write_b128 v67, v[94:97] offset:32256
	s_waitcnt lgkmcnt(4)
	v_mfma_f32_32x32x16_bf16 v[18:33], v[118:121], v[126:129], v[18:33]
	v_mfma_f32_32x32x16_bf16 v[34:49], v[110:113], v[122:125], v[34:49]
	v_mfma_f32_32x32x16_bf16 v[50:65], v[110:113], v[126:129], v[50:65]
	s_waitcnt lgkmcnt(0)
	s_barrier
	ds_read_b128 v[90:93], v0
	ds_read_b128 v[94:97], v66 offset:18432
	ds_read_b128 v[110:113], v0 offset:32
	ds_read_b128 v[114:117], v66 offset:18464
	ds_read_b128 v[118:121], v0 offset:4608
	ds_read_b128 v[122:125], v0 offset:4640
	s_waitcnt lgkmcnt(4)
	v_mfma_f32_32x32x16_bf16 v[34:49], v[90:93], v[94:97], v[34:49]
	s_waitcnt lgkmcnt(1)
	v_mfma_f32_32x32x16_bf16 v[2:17], v[118:121], v[94:97], v[2:17]
	ds_read_b128 v[94:97], v66 offset:23040
	ds_read_b128 v[126:129], v66 offset:23072
	s_waitcnt lgkmcnt(1)
	v_mfma_f32_32x32x16_bf16 v[50:65], v[90:93], v[94:97], v[50:65]
	global_load_dwordx4 v[90:93], v72, s[0:1] offset:2816
	global_load_dwordx4 v[130:133], v72, s[36:37] offset:2816
	s_waitcnt vmcnt(9)
	ds_write_b128 v67, v[74:77] offset:36864
	s_waitcnt vmcnt(8)
	ds_write_b128 v67, v[134:137] offset:55296
	v_mfma_f32_32x32x16_bf16 v[18:33], v[118:121], v[94:97], v[18:33]
	global_load_dwordx4 v[74:77], v71, s[0:1] offset:2816
	global_load_dwordx4 v[94:97], v71, s[36:37] offset:2816
	v_mfma_f32_32x32x16_bf16 v[2:17], v[122:125], v[114:117], v[2:17]
	s_waitcnt lgkmcnt(2)
	v_mfma_f32_32x32x16_bf16 v[18:33], v[122:125], v[126:129], v[18:33]
	v_mfma_f32_32x32x16_bf16 v[34:49], v[110:113], v[114:117], v[34:49]
	v_mfma_f32_32x32x16_bf16 v[50:65], v[110:113], v[126:129], v[50:65]
	ds_read_b128 v[110:113], v0 offset:64
	ds_read_b128 v[114:117], v0 offset:4672
	ds_read_b128 v[118:121], v66 offset:18496
	ds_read_b128 v[134:137], v66 offset:23104
	s_waitcnt vmcnt(9)
	ds_write_b128 v67, v[78:81] offset:41472
	s_waitcnt vmcnt(8)
	ds_write_b128 v67, v[98:101] offset:59904
	global_load_dwordx4 v[78:81], v70, s[0:1] offset:2816
	global_load_dwordx4 v[98:101], v70, s[36:37] offset:2816
	s_waitcnt lgkmcnt(3)
	v_mfma_f32_32x32x16_bf16 v[2:17], v[114:117], v[118:121], v[2:17]
	s_waitcnt lgkmcnt(2)
	v_mfma_f32_32x32x16_bf16 v[18:33], v[114:117], v[134:137], v[18:33]
	v_mfma_f32_32x32x16_bf16 v[34:49], v[110:113], v[118:121], v[34:49]
	v_mfma_f32_32x32x16_bf16 v[50:65], v[110:113], v[134:137], v[50:65]
	ds_read_b128 v[110:113], v0 offset:96
	ds_read_b128 v[118:121], v0 offset:4704
	ds_read_b128 v[122:125], v66 offset:18528
	ds_read_b128 v[126:129], v66 offset:23136
	s_waitcnt vmcnt(9)
	ds_write_b128 v67, v[82:85] offset:46080
	s_waitcnt vmcnt(8)
	ds_write_b128 v67, v[102:105] offset:64512
	global_load_dwordx4 v[82:85], v69, s[0:1] offset:2816
	global_load_dwordx4 v[102:105], v69, s[36:37] offset:2816
	s_waitcnt lgkmcnt(3)
	v_mfma_f32_32x32x16_bf16 v[2:17], v[118:121], v[122:125], v[2:17]
	s_waitcnt vmcnt(9)
	ds_write_b128 v67, v[86:89] offset:50688
	s_waitcnt vmcnt(8)
	ds_write_b128 v68, v[106:109] offset:13824
	s_waitcnt lgkmcnt(4)
	v_mfma_f32_32x32x16_bf16 v[18:33], v[118:121], v[126:129], v[18:33]
	v_mfma_f32_32x32x16_bf16 v[34:49], v[110:113], v[122:125], v[34:49]
	v_mfma_f32_32x32x16_bf16 v[50:65], v[110:113], v[126:129], v[50:65]
	s_waitcnt lgkmcnt(0)
	s_barrier
; #define GL1_(RA, RB, i) { RA[i] = *(const u32x4*)(ap + (aoff + (i) * astep)); if ((i) < NB) RB[(i) < NB ? (i) : 0] = *(const u32x4*)(bp + (boff + (i) * bstep)); }
; #define LS1_(RA, RB, ST, i) { char* sn_ = lds + (ST) * STAGE; *(u32x4*)(sn_ + wofs + (i) * 32 * LROW) = RA[i]; \
;                               if ((i) < NB) *(u32x4*)(sn_ + STAGE_OP + wofs + (i) * 32 * LROW) = RB[(i) < NB ? (i) : 0]; }
; template <int NJ> DI void gemm_mainloop_reg(const bf16_t* __restrict__ A, int lda, const bf16_t* __restrict__ Bt, int ldb, int K, f32x16 (&acc)[2][NJ], char* lds) {
;     ...
; #pragma unroll
;   for (int i = 0; i < 4; ++i) GL1_(ra0, rb0, i);
;   ap += 128; bp += 128;
; #pragma unroll
;   for (int i = 0; i < 4; ++i) GL1_(ra1, rb1, i);
;   ap += 128; bp += 128;
; #pragma unroll
;   for (int i = 0; i < 4; ++i) LS1_(ra0, rb0, 0, i);
;   __syncthreads();
;   const int nk = K >> 6;
;   for (int kt = 0; kt < nk; kt += 2) {
;     const bool l0 = (kt + 2 < nk), l1 = (kt + 3 < nk);
;     STEP_(0, l0, ra0, rb0, true, ra1, rb1);
;     __syncthreads();
;     STEP_(1, l1, ra1, rb1, l0, ra0, rb0);
;     __syncthreads();
;   }
	ds_read_b128 v[86:89], v0 offset:36864
	ds_read_b128 v[106:109], v66 offset:55296
	ds_read_b128 v[110:113], v0 offset:36896
	ds_read_b128 v[114:117], v66 offset:55328
	ds_read_b128 v[118:121], v0 offset:41472
	ds_read_b128 v[122:125], v0 offset:41504
	s_waitcnt lgkmcnt(4)
	v_mfma_f32_32x32x16_bf16 v[34:49], v[86:89], v[106:109], v[34:49]
	s_waitcnt lgkmcnt(1)
	v_mfma_f32_32x32x16_bf16 v[2:17], v[118:121], v[106:109], v[2:17]
	ds_read_b128 v[106:109], v66 offset:59904
	ds_read_b128 v[126:129], v66 offset:59936
	s_waitcnt lgkmcnt(1)
	v_mfma_f32_32x32x16_bf16 v[50:65], v[86:89], v[106:109], v[50:65]
	global_load_dwordx4 v[86:89], v72, s[0:1] offset:2944
	global_load_dwordx4 v[134:137], v72, s[36:37] offset:2944
	s_waitcnt vmcnt(9)
	ds_write_b128 v67, v[90:93]
	s_waitcnt vmcnt(8)
	ds_write_b128 v67, v[130:133] offset:18432
	v_mfma_f32_32x32x16_bf16 v[18:33], v[118:121], v[106:109], v[18:33]
	global_load_dwordx4 v[90:93], v71, s[0:1] offset:2944
	global_load_dwordx4 v[106:109], v71, s[36:37] offset:2944
	v_mfma_f32_32x32x16_bf16 v[2:17], v[122:125], v[114:117], v[2:17]
	s_waitcnt lgkmcnt(2)
	v_mfma_f32_32x32x16_bf16 v[18:33], v[122:125], v[126:129], v[18:33]
	v_mfma_f32_32x32x16_bf16 v[34:49], v[110:113], v[114:117], v[34:49]
	v_mfma_f32_32x32x16_bf16 v[50:65], v[110:113], v[126:129], v[50:65]
	ds_read_b128 v[110:113], v0 offset:36928
	ds_read_b128 v[114:117], v0 offset:41536
	ds_read_b128 v[118:121], v66 offset:55360
	ds_read_b128 v[130:133], v66 offset:59968
	s_waitcnt vmcnt(9)
	ds_write_b128 v67, v[74:77] offset:4608
	s_waitcnt vmcnt(8)
	ds_write_b128 v67, v[94:97] offset:23040
	global_load_dwordx4 v[74:77], v70, s[0:1] offset:2944
	global_load_dwordx4 v[94:97], v70, s[36:37] offset:2944
	s_waitcnt lgkmcnt(3)
	v_mfma_f32_32x32x16_bf16 v[2:17], v[114:117], v[118:121], v[2:17]
	s_waitcnt lgkmcnt(2)
	v_mfma_f32_32x32x16_bf16 v[18:33], v[114:117], v[130:133], v[18:33]
	v_mfma_f32_32x32x16_bf16 v[34:49], v[110:113], v[118:121], v[34:49]
	v_mfma_f32_32x32x16_bf16 v[50:65], v[110:113], v[130:133], v[50:65]
	ds_read_b128 v[110:113], v0 offset:36960
	ds_read_b128 v[118:121], v0 offset:41568
	ds_read_b128 v[122:125], v66 offset:55392
	ds_read_b128 v[126:129], v66 offset:60000
	s_waitcnt vmcnt(9)
	ds_write_b128 v67, v[78:81] offset:9216
	s_waitcnt vmcnt(8)
	ds_write_b128 v67, v[98:101] offset:27648
	global_load_dwordx4 v[78:81], v69, s[0:1] offset:2944
	global_load_dwordx4 v[98:101], v69, s[36:37] offset:2944
	s_waitcnt lgkmcnt(3)
	v_mfma_f32_32x32x16_bf16 v[2:17], v[118:121], v[122:125], v[2:17]
	s_waitcnt vmcnt(9)
	ds_write_b128 v67, v[82:85] offset:13824
	s_waitcnt vmcnt(8)
	ds_write_b128 v67, v[102:105] offset:32256
	s_waitcnt lgkmcnt(4)
	v_mfma_f32_32x32x16_bf16 v[18:33], v[118:121], v[126:129], v[18:33]
	v_mfma_f32_32x32x16_bf16 v[34:49], v[110:113], v[122:125], v[34:49]
	v_mfma_f32_32x32x16_bf16 v[50:65], v[110:113], v[126:129], v[50:65]
	s_waitcnt lgkmcnt(0)
	s_barrier
	ds_read_b128 v[82:85], v0
	ds_read_b128 v[102:105], v66 offset:18432
	ds_read_b128 v[110:113], v0 offset:32
	ds_read_b128 v[114:117], v66 offset:18464
	ds_read_b128 v[118:121], v0 offset:4608
	ds_read_b128 v[122:125], v0 offset:4640
	s_waitcnt lgkmcnt(4)
	v_mfma_f32_32x32x16_bf16 v[34:49], v[82:85], v[102:105], v[34:49]
	s_waitcnt lgkmcnt(1)
	v_mfma_f32_32x32x16_bf16 v[2:17], v[118:121], v[102:105], v[2:17]
	ds_read_b128 v[102:105], v66 offset:23040
	ds_read_b128 v[126:129], v66 offset:23072
	s_waitcnt lgkmcnt(1)
	v_mfma_f32_32x32x16_bf16 v[50:65], v[82:85], v[102:105], v[50:65]
	global_load_dwordx4 v[82:85], v72, s[0:1] offset:3072
	global_load_dwordx4 v[130:133], v72, s[36:37] offset:3072
	s_waitcnt vmcnt(9)
	ds_write_b128 v67, v[86:89] offset:36864
	s_waitcnt vmcnt(8)
	ds_write_b128 v67, v[134:137] offset:55296
	v_mfma_f32_32x32x16_bf16 v[18:33], v[118:121], v[102:105], v[18:33]
	global_load_dwordx4 v[86:89], v71, s[0:1] offset:3072
	global_load_dwordx4 v[102:105], v71, s[36:37] offset:3072
	v_mfma_f32_32x32x16_bf16 v[2:17], v[122:125], v[114:117], v[2:17]
	s_waitcnt lgkmcnt(2)
	v_mfma_f32_32x32x16_bf16 v[18:33], v[122:125], v[126:129], v[18:33]
	v_mfma_f32_32x32x16_bf16 v[34:49], v[110:113], v[114:117], v[34:49]
	v_mfma_f32_32x32x16_bf16 v[50:65], v[110:113], v[126:129], v[50:65]
	ds_read_b128 v[110:113], v0 offset:64
	ds_read_b128 v[114:117], v0 offset:4672
	ds_read_b128 v[118:121], v66 offset:18496
	ds_read_b128 v[134:137], v66 offset:23104
	s_waitcnt vmcnt(9)
	ds_write_b128 v67, v[90:93] offset:41472
	s_waitcnt vmcnt(8)
	ds_write_b128 v67, v[106:109] offset:59904
	global_load_dwordx4 v[90:93], v70, s[0:1] offset:3072
	global_load_dwordx4 v[106:109], v70, s[36:37] offset:3072
	s_waitcnt lgkmcnt(3)
	v_mfma_f32_32x32x16_bf16 v[2:17], v[114:117], v[118:121], v[2:17]
	s_waitcnt lgkmcnt(2)
	v_mfma_f32_32x32x16_bf16 v[18:33], v[114:117], v[134:137], v[18:33]
	v_mfma_f32_32x32x16_bf16 v[34:49], v[110:113], v[118:121], v[34:49]
	v_mfma_f32_32x32x16_bf16 v[50:65], v[110:113], v[134:137], v[50:65]
	ds_read_b128 v[110:113], v0 offset:96
	ds_read_b128 v[118:121], v0 offset:4704
	ds_read_b128 v[122:125], v66 offset:18528
	ds_read_b128 v[126:129], v66 offset:23136
	s_waitcnt vmcnt(9)
	ds_write_b128 v67, v[74:77] offset:46080
	s_waitcnt vmcnt(8)
	ds_write_b128 v67, v[94:97] offset:64512
	global_load_dwordx4 v[74:77], v69, s[0:1] offset:3072
	global_load_dwordx4 v[94:97], v69, s[36:37] offset:3072
	s_waitcnt lgkmcnt(3)
	v_mfma_f32_32x32x16_bf16 v[2:17], v[118:121], v[122:125], v[2:17]
	s_waitcnt vmcnt(9)
	ds_write_b128 v67, v[78:81] offset:50688
	s_waitcnt vmcnt(8)
	ds_write_b128 v68, v[98:101] offset:13824
	s_waitcnt lgkmcnt(4)
	v_mfma_f32_32x32x16_bf16 v[18:33], v[118:121], v[126:129], v[18:33]
	v_mfma_f32_32x32x16_bf16 v[34:49], v[110:113], v[122:125], v[34:49]
	v_mfma_f32_32x32x16_bf16 v[50:65], v[110:113], v[126:129], v[50:65]
	s_waitcnt lgkmcnt(0)
	s_barrier
; #define GL1_(RA, RB, i) { RA[i] = *(const u32x4*)(ap + (aoff + (i) * astep)); if ((i) < NB) RB[(i) < NB ? (i) : 0] = *(const u32x4*)(bp + (boff + (i) * bstep)); }
; #define LS1_(RA, RB, ST, i) { char* sn_ = lds + (ST) * STAGE; *(u32x4*)(sn_ + wofs + (i) * 32 * LROW) = RA[i]; \
;                               if ((i) < NB) *(u32x4*)(sn_ + STAGE_OP + wofs + (i) * 32 * LROW) = RB[(i) < NB ? (i) : 0]; }
; template <int NJ> DI void gemm_mainloop_reg(const bf16_t* __restrict__ A, int lda, const bf16_t* __restrict__ Bt, int ldb, int K, f32x16 (&acc)[2][NJ], char* lds) {
;     ...
; #pragma unroll
;   for (int i = 0; i < 4; ++i) GL1_(ra0, rb0, i);
;   ap += 128; bp += 128;
; #pragma unroll
;   for (int i = 0; i < 4; ++i) GL1_(ra1, rb1, i);
;   ap += 128; bp += 128;
; #pragma unroll
;   for (int i = 0; i < 4; ++i) LS1_(ra0, rb0, 0, i);
;   __syncthreads();
;   const int nk = K >> 6;
;   for (int kt = 0; kt < nk; kt += 2) {
;     const bool l0 = (kt + 2 < nk), l1 = (kt + 3 < nk);
;     STEP_(0, l0, ra0, rb0, true, ra1, rb1);
;     __syncthreads();
;     STEP_(1, l1, ra1, rb1, l0, ra0, rb0);
;     __syncthreads();
;   }
	ds_read_b128 v[78:81], v0 offset:36864
	ds_read_b128 v[98:101], v66 offset:55296
	ds_read_b128 v[110:113], v0 offset:36896
	ds_read_b128 v[114:117], v66 offset:55328
	ds_read_b128 v[118:121], v0 offset:41472
	ds_read_b128 v[122:125], v0 offset:41504
	s_waitcnt lgkmcnt(4)
	v_mfma_f32_32x32x16_bf16 v[34:49], v[78:81], v[98:101], v[34:49]
	s_waitcnt lgkmcnt(1)
	v_mfma_f32_32x32x16_bf16 v[2:17], v[118:121], v[98:101], v[2:17]
	ds_read_b128 v[98:101], v66 offset:59904
	ds_read_b128 v[126:129], v66 offset:59936
	s_waitcnt lgkmcnt(1)
	v_mfma_f32_32x32x16_bf16 v[50:65], v[78:81], v[98:101], v[50:65]
	global_load_dwordx4 v[78:81], v72, s[0:1] offset:3200
	global_load_dwordx4 v[134:137], v72, s[36:37] offset:3200
	s_waitcnt vmcnt(9)
	ds_write_b128 v67, v[82:85]
	s_waitcnt vmcnt(8)
	ds_write_b128 v67, v[130:133] offset:18432
	v_mfma_f32_32x32x16_bf16 v[18:33], v[118:121], v[98:101], v[18:33]
	global_load_dwordx4 v[82:85], v71, s[0:1] offset:3200
	global_load_dwordx4 v[98:101], v71, s[36:37] offset:3200
	v_mfma_f32_32x32x16_bf16 v[2:17], v[122:125], v[114:117], v[2:17]
	s_waitcnt lgkmcnt(2)
	v_mfma_f32_32x32x16_bf16 v[18:33], v[122:125], v[126:129], v[18:33]
	v_mfma_f32_32x32x16_bf16 v[34:49], v[110:113], v[114:117], v[34:49]
	v_mfma_f32_32x32x16_bf16 v[50:65], v[110:113], v[126:129], v[50:65]
	ds_read_b128 v[110:113], v0 offset:36928
	ds_read_b128 v[114:117], v0 offset:41536
	ds_read_b128 v[118:121], v66 offset:55360
	ds_read_b128 v[130:133], v66 offset:59968
	s_waitcnt vmcnt(9)
	ds_write_b128 v67, v[86:89] offset:4608
	s_waitcnt vmcnt(8)
	ds_write_b128 v67, v[102:105] offset:23040
	global_load_dwordx4 v[86:89], v70, s[0:1] offset:3200
	global_load_dwordx4 v[102:105], v70, s[36:37] offset:3200
	s_waitcnt lgkmcnt(3)
	v_mfma_f32_32x32x16_bf16 v[2:17], v[114:117], v[118:121], v[2:17]
	s_waitcnt lgkmcnt(2)
	v_mfma_f32_32x32x16_bf16 v[18:33], v[114:117], v[130:133], v[18:33]
	v_mfma_f32_32x32x16_bf16 v[34:49], v[110:113], v[118:121], v[34:49]
	v_mfma_f32_32x32x16_bf16 v[50:65], v[110:113], v[130:133], v[50:65]
	ds_read_b128 v[110:113], v0 offset:36960
	ds_read_b128 v[118:121], v0 offset:41568
	ds_read_b128 v[122:125], v66 offset:55392
	ds_read_b128 v[126:129], v66 offset:60000
	s_waitcnt vmcnt(9)
	ds_write_b128 v67, v[90:93] offset:9216
	s_waitcnt vmcnt(8)
	ds_write_b128 v67, v[106:109] offset:27648
	global_load_dwordx4 v[90:93], v69, s[0:1] offset:3200
	global_load_dwordx4 v[106:109], v69, s[36:37] offset:3200
	s_waitcnt lgkmcnt(3)
	v_mfma_f32_32x32x16_bf16 v[2:17], v[118:121], v[122:125], v[2:17]
	s_waitcnt vmcnt(9)
	ds_write_b128 v67, v[74:77] offset:13824
	s_waitcnt vmcnt(8)
	ds_write_b128 v67, v[94:97] offset:32256
	s_waitcnt lgkmcnt(4)
	v_mfma_f32_32x32x16_bf16 v[18:33], v[118:121], v[126:129], v[18:33]
	v_mfma_f32_32x32x16_bf16 v[34:49], v[110:113], v[122:125], v[34:49]
	v_mfma_f32_32x32x16_bf16 v[50:65], v[110:113], v[126:129], v[50:65]
	s_waitcnt lgkmcnt(0)
	s_barrier
	ds_read_b128 v[74:77], v0
	ds_read_b128 v[94:97], v66 offset:18432
	ds_read_b128 v[110:113], v0 offset:32
	ds_read_b128 v[114:117], v66 offset:18464
	ds_read_b128 v[118:121], v0 offset:4608
	ds_read_b128 v[122:125], v0 offset:4640
	s_waitcnt lgkmcnt(4)
	v_mfma_f32_32x32x16_bf16 v[34:49], v[74:77], v[94:97], v[34:49]
	s_waitcnt lgkmcnt(1)
	v_mfma_f32_32x32x16_bf16 v[2:17], v[118:121], v[94:97], v[2:17]
	ds_read_b128 v[94:97], v66 offset:23040
	ds_read_b128 v[126:129], v66 offset:23072
	s_waitcnt lgkmcnt(1)
	v_mfma_f32_32x32x16_bf16 v[50:65], v[74:77], v[94:97], v[50:65]
	global_load_dwordx4 v[74:77], v72, s[0:1] offset:3328
	global_load_dwordx4 v[130:133], v72, s[36:37] offset:3328
	s_waitcnt vmcnt(9)
	ds_write_b128 v67, v[78:81] offset:36864
	s_waitcnt vmcnt(8)
	ds_write_b128 v67, v[134:137] offset:55296
	v_mfma_f32_32x32x16_bf16 v[18:33], v[118:121], v[94:97], v[18:33]
	global_load_dwordx4 v[78:81], v71, s[0:1] offset:3328
	global_load_dwordx4 v[94:97], v71, s[36:37] offset:3328
	v_mfma_f32_32x32x16_bf16 v[2:17], v[122:125], v[114:117], v[2:17]
	s_waitcnt lgkmcnt(2)
	v_mfma_f32_32x32x16_bf16 v[18:33], v[122:125], v[126:129], v[18:33]
	v_mfma_f32_32x32x16_bf16 v[34:49], v[110:113], v[114:117], v[34:49]
	v_mfma_f32_32x32x16_bf16 v[50:65], v[110:113], v[126:129], v[50:65]
	ds_read_b128 v[110:113], v0 offset:64
	ds_read_b128 v[114:117], v0 offset:4672
	ds_read_b128 v[118:121], v66 offset:18496
	ds_read_b128 v[134:137], v66 offset:23104
	s_waitcnt vmcnt(9)
	ds_write_b128 v67, v[82:85] offset:41472
	s_waitcnt vmcnt(8)
	ds_write_b128 v67, v[98:101] offset:59904
	global_load_dwordx4 v[82:85], v70, s[0:1] offset:3328
	global_load_dwordx4 v[98:101], v70, s[36:37] offset:3328
	s_waitcnt lgkmcnt(3)
	v_mfma_f32_32x32x16_bf16 v[2:17], v[114:117], v[118:121], v[2:17]
	s_waitcnt lgkmcnt(2)
	v_mfma_f32_32x32x16_bf16 v[18:33], v[114:117], v[134:137], v[18:33]
	v_mfma_f32_32x32x16_bf16 v[34:49], v[110:113], v[118:121], v[34:49]
	v_mfma_f32_32x32x16_bf16 v[50:65], v[110:113], v[134:137], v[50:65]
	ds_read_b128 v[110:113], v0 offset:96
	ds_read_b128 v[118:121], v0 offset:4704
	ds_read_b128 v[122:125], v66 offset:18528
	ds_read_b128 v[126:129], v66 offset:23136
	s_waitcnt vmcnt(9)
	ds_write_b128 v67, v[86:89] offset:46080
	s_waitcnt vmcnt(8)
	ds_write_b128 v67, v[102:105] offset:64512
	global_load_dwordx4 v[86:89], v69, s[0:1] offset:3328
	global_load_dwordx4 v[102:105], v69, s[36:37] offset:3328
	s_waitcnt lgkmcnt(3)
	v_mfma_f32_32x32x16_bf16 v[2:17], v[118:121], v[122:125], v[2:17]
	s_waitcnt vmcnt(9)
	ds_write_b128 v67, v[90:93] offset:50688
	s_waitcnt vmcnt(8)
	ds_write_b128 v68, v[106:109] offset:13824
	s_waitcnt lgkmcnt(4)
	v_mfma_f32_32x32x16_bf16 v[18:33], v[118:121], v[126:129], v[18:33]
	v_mfma_f32_32x32x16_bf16 v[34:49], v[110:113], v[122:125], v[34:49]
	v_mfma_f32_32x32x16_bf16 v[50:65], v[110:113], v[126:129], v[50:65]
	s_waitcnt lgkmcnt(0)
	s_barrier
; #define GL1_(RA, RB, i) { RA[i] = *(const u32x4*)(ap + (aoff + (i) * astep)); if ((i) < NB) RB[(i) < NB ? (i) : 0] = *(const u32x4*)(bp + (boff + (i) * bstep)); }
; #define LS1_(RA, RB, ST, i) { char* sn_ = lds + (ST) * STAGE; *(u32x4*)(sn_ + wofs + (i) * 32 * LROW) = RA[i]; \
;                               if ((i) < NB) *(u32x4*)(sn_ + STAGE_OP + wofs + (i) * 32 * LROW) = RB[(i) < NB ? (i) : 0]; }
; template <int NJ> DI void gemm_mainloop_reg(const bf16_t* __restrict__ A, int lda, const bf16_t* __restrict__ Bt, int ldb, int K, f32x16 (&acc)[2][NJ], char* lds) {
;     ...
; #pragma unroll
;   for (int i = 0; i < 4; ++i) GL1_(ra0, rb0, i);
;   ap += 128; bp += 128;
; #pragma unroll
;   for (int i = 0; i < 4; ++i) GL1_(ra1, rb1, i);
;   ap += 128; bp += 128;
; #pragma unroll
;   for (int i = 0; i < 4; ++i) LS1_(ra0, rb0, 0, i);
;   __syncthreads();
;   const int nk = K >> 6;
;   for (int kt = 0; kt < nk; kt += 2) {
;     const bool l0 = (kt + 2 < nk), l1 = (kt + 3 < nk);
;     STEP_(0, l0, ra0, rb0, true, ra1, rb1);
;     __syncthreads();
;     STEP_(1, l1, ra1, rb1, l0, ra0, rb0);
;     __syncthreads();
;   }
	ds_read_b128 v[90:93], v0 offset:36864
	ds_read_b128 v[106:109], v66 offset:55296
	ds_read_b128 v[110:113], v0 offset:36896
	ds_read_b128 v[114:117], v66 offset:55328
	ds_read_b128 v[118:121], v0 offset:41472
	ds_read_b128 v[122:125], v0 offset:41504
	s_waitcnt lgkmcnt(4)
	v_mfma_f32_32x32x16_bf16 v[34:49], v[90:93], v[106:109], v[34:49]
	s_waitcnt lgkmcnt(1)
	v_mfma_f32_32x32x16_bf16 v[2:17], v[118:121], v[106:109], v[2:17]
	ds_read_b128 v[106:109], v66 offset:59904
	ds_read_b128 v[126:129], v66 offset:59936
	s_waitcnt lgkmcnt(1)
	v_mfma_f32_32x32x16_bf16 v[50:65], v[90:93], v[106:109], v[50:65]
	global_load_dwordx4 v[90:93], v72, s[0:1] offset:3456
	global_load_dwordx4 v[134:137], v72, s[36:37] offset:3456
	s_waitcnt vmcnt(9)
	ds_write_b128 v67, v[74:77]
	s_waitcnt vmcnt(8)
	ds_write_b128 v67, v[130:133] offset:18432
	v_mfma_f32_32x32x16_bf16 v[18:33], v[118:121], v[106:109], v[18:33]
	global_load_dwordx4 v[74:77], v71, s[0:1] offset:3456
	global_load_dwordx4 v[106:109], v71, s[36:37] offset:3456
	v_mfma_f32_32x32x16_bf16 v[2:17], v[122:125], v[114:117], v[2:17]
	s_waitcnt lgkmcnt(2)
	v_mfma_f32_32x32x16_bf16 v[18:33], v[122:125], v[126:129], v[18:33]
	v_mfma_f32_32x32x16_bf16 v[34:49], v[110:113], v[114:117], v[34:49]
	v_mfma_f32_32x32x16_bf16 v[50:65], v[110:113], v[126:129], v[50:65]
	ds_read_b128 v[110:113], v0 offset:36928
	ds_read_b128 v[114:117], v0 offset:41536
	ds_read_b128 v[118:121], v66 offset:55360
	ds_read_b128 v[130:133], v66 offset:59968
	s_waitcnt vmcnt(9)
	ds_write_b128 v67, v[78:81] offset:4608
	s_waitcnt vmcnt(8)
	ds_write_b128 v67, v[94:97] offset:23040
	global_load_dwordx4 v[78:81], v70, s[0:1] offset:3456
	global_load_dwordx4 v[94:97], v70, s[36:37] offset:3456
	s_waitcnt lgkmcnt(3)
	v_mfma_f32_32x32x16_bf16 v[2:17], v[114:117], v[118:121], v[2:17]
	s_waitcnt lgkmcnt(2)
	v_mfma_f32_32x32x16_bf16 v[18:33], v[114:117], v[130:133], v[18:33]
	v_mfma_f32_32x32x16_bf16 v[34:49], v[110:113], v[118:121], v[34:49]
	v_mfma_f32_32x32x16_bf16 v[50:65], v[110:113], v[130:133], v[50:65]
	ds_read_b128 v[110:113], v0 offset:36960
	ds_read_b128 v[118:121], v0 offset:41568
	ds_read_b128 v[122:125], v66 offset:55392
	ds_read_b128 v[126:129], v66 offset:60000
	s_waitcnt vmcnt(9)
	ds_write_b128 v67, v[82:85] offset:9216
	s_waitcnt vmcnt(8)
	ds_write_b128 v67, v[98:101] offset:27648
	global_load_dwordx4 v[82:85], v69, s[0:1] offset:3456
	global_load_dwordx4 v[98:101], v69, s[36:37] offset:3456
	s_waitcnt lgkmcnt(3)
	v_mfma_f32_32x32x16_bf16 v[2:17], v[118:121], v[122:125], v[2:17]
	s_waitcnt vmcnt(9)
	ds_write_b128 v67, v[86:89] offset:13824
	s_waitcnt vmcnt(8)
	ds_write_b128 v67, v[102:105] offset:32256
	s_waitcnt lgkmcnt(4)
	v_mfma_f32_32x32x16_bf16 v[18:33], v[118:121], v[126:129], v[18:33]
	v_mfma_f32_32x32x16_bf16 v[34:49], v[110:113], v[122:125], v[34:49]
	v_mfma_f32_32x32x16_bf16 v[50:65], v[110:113], v[126:129], v[50:65]
	s_waitcnt lgkmcnt(0)
	s_barrier
	ds_read_b128 v[86:89], v0
	ds_read_b128 v[102:105], v66 offset:18432
	ds_read_b128 v[110:113], v0 offset:32
	ds_read_b128 v[114:117], v66 offset:18464
	ds_read_b128 v[118:121], v0 offset:4608
	ds_read_b128 v[122:125], v0 offset:4640
	s_waitcnt lgkmcnt(4)
	v_mfma_f32_32x32x16_bf16 v[34:49], v[86:89], v[102:105], v[34:49]
	s_waitcnt lgkmcnt(1)
	v_mfma_f32_32x32x16_bf16 v[2:17], v[118:121], v[102:105], v[2:17]
	ds_read_b128 v[102:105], v66 offset:23040
	ds_read_b128 v[126:129], v66 offset:23072
	s_waitcnt lgkmcnt(1)
	v_mfma_f32_32x32x16_bf16 v[50:65], v[86:89], v[102:105], v[50:65]
	global_load_dwordx4 v[86:89], v72, s[0:1] offset:3584
	global_load_dwordx4 v[130:133], v72, s[36:37] offset:3584
	s_waitcnt vmcnt(9)
	ds_write_b128 v67, v[90:93] offset:36864
	s_waitcnt vmcnt(8)
	ds_write_b128 v67, v[134:137] offset:55296
	v_mfma_f32_32x32x16_bf16 v[18:33], v[118:121], v[102:105], v[18:33]
	global_load_dwordx4 v[90:93], v71, s[0:1] offset:3584
	global_load_dwordx4 v[102:105], v71, s[36:37] offset:3584
	v_mfma_f32_32x32x16_bf16 v[2:17], v[122:125], v[114:117], v[2:17]
	s_waitcnt lgkmcnt(2)
	v_mfma_f32_32x32x16_bf16 v[18:33], v[122:125], v[126:129], v[18:33]
	v_mfma_f32_32x32x16_bf16 v[34:49], v[110:113], v[114:117], v[34:49]
	v_mfma_f32_32x32x16_bf16 v[50:65], v[110:113], v[126:129], v[50:65]
	ds_read_b128 v[110:113], v0 offset:64
	ds_read_b128 v[114:117], v0 offset:4672
	ds_read_b128 v[118:121], v66 offset:18496
	ds_read_b128 v[134:137], v66 offset:23104
	s_waitcnt vmcnt(9)
	ds_write_b128 v67, v[74:77] offset:41472
	s_waitcnt vmcnt(8)
	ds_write_b128 v67, v[106:109] offset:59904
	global_load_dwordx4 v[74:77], v70, s[0:1] offset:3584
	global_load_dwordx4 v[106:109], v70, s[36:37] offset:3584
	s_waitcnt lgkmcnt(3)
	v_mfma_f32_32x32x16_bf16 v[2:17], v[114:117], v[118:121], v[2:17]
	s_waitcnt lgkmcnt(2)
	v_mfma_f32_32x32x16_bf16 v[18:33], v[114:117], v[134:137], v[18:33]
	v_mfma_f32_32x32x16_bf16 v[34:49], v[110:113], v[118:121], v[34:49]
	v_mfma_f32_32x32x16_bf16 v[50:65], v[110:113], v[134:137], v[50:65]
	ds_read_b128 v[110:113], v0 offset:96
	ds_read_b128 v[118:121], v0 offset:4704
	ds_read_b128 v[122:125], v66 offset:18528
	ds_read_b128 v[126:129], v66 offset:23136
	s_waitcnt vmcnt(9)
	ds_write_b128 v67, v[78:81] offset:46080
	s_waitcnt vmcnt(8)
	ds_write_b128 v67, v[94:97] offset:64512
	global_load_dwordx4 v[78:81], v69, s[0:1] offset:3584
	global_load_dwordx4 v[94:97], v69, s[36:37] offset:3584
	s_waitcnt lgkmcnt(3)
	v_mfma_f32_32x32x16_bf16 v[2:17], v[118:121], v[122:125], v[2:17]
	s_waitcnt vmcnt(9)
	ds_write_b128 v67, v[82:85] offset:50688
	s_waitcnt vmcnt(8)
	ds_write_b128 v68, v[98:101] offset:13824
	s_waitcnt lgkmcnt(4)
	v_mfma_f32_32x32x16_bf16 v[18:33], v[118:121], v[126:129], v[18:33]
	v_mfma_f32_32x32x16_bf16 v[34:49], v[110:113], v[122:125], v[34:49]
	v_mfma_f32_32x32x16_bf16 v[50:65], v[110:113], v[126:129], v[50:65]
	s_waitcnt lgkmcnt(0)
	s_barrier
; #define GL1_(RA, RB, i) { RA[i] = *(const u32x4*)(ap + (aoff + (i) * astep)); if ((i) < NB) RB[(i) < NB ? (i) : 0] = *(const u32x4*)(bp + (boff + (i) * bstep)); }
; #define LS1_(RA, RB, ST, i) { char* sn_ = lds + (ST) * STAGE; *(u32x4*)(sn_ + wofs + (i) * 32 * LROW) = RA[i]; \
;                               if ((i) < NB) *(u32x4*)(sn_ + STAGE_OP + wofs + (i) * 32 * LROW) = RB[(i) < NB ? (i) : 0]; }
; template <int NJ> DI void gemm_mainloop_reg(const bf16_t* __restrict__ A, int lda, const bf16_t* __restrict__ Bt, int ldb, int K, f32x16 (&acc)[2][NJ], char* lds) {
;     ...
; #pragma unroll
;   for (int i = 0; i < 4; ++i) GL1_(ra0, rb0, i);
;   ap += 128; bp += 128;
; #pragma unroll
;   for (int i = 0; i < 4; ++i) GL1_(ra1, rb1, i);
;   ap += 128; bp += 128;
; #pragma unroll
;   for (int i = 0; i < 4; ++i) LS1_(ra0, rb0, 0, i);
;   __syncthreads();
;   const int nk = K >> 6;
;   for (int kt = 0; kt < nk; kt += 2) {
;     const bool l0 = (kt + 2 < nk), l1 = (kt + 3 < nk);
;     STEP_(0, l0, ra0, rb0, true, ra1, rb1);
;     __syncthreads();
;     STEP_(1, l1, ra1, rb1, l0, ra0, rb0);
;     __syncthreads();
;   }
	ds_read_b128 v[82:85], v0 offset:36864
	ds_read_b128 v[98:101], v66 offset:55296
	ds_read_b128 v[110:113], v0 offset:36896
	ds_read_b128 v[114:117], v66 offset:55328
	ds_read_b128 v[118:121], v0 offset:41472
	ds_read_b128 v[122:125], v0 offset:41504
	s_waitcnt lgkmcnt(4)
	v_mfma_f32_32x32x16_bf16 v[34:49], v[82:85], v[98:101], v[34:49]
	s_waitcnt lgkmcnt(1)
	v_mfma_f32_32x32x16_bf16 v[2:17], v[118:121], v[98:101], v[2:17]
	ds_read_b128 v[98:101], v66 offset:59904
	ds_read_b128 v[126:129], v66 offset:59936
	s_waitcnt lgkmcnt(1)
	v_mfma_f32_32x32x16_bf16 v[50:65], v[82:85], v[98:101], v[50:65]
	global_load_dwordx4 v[82:85], v72, s[0:1] offset:3712
	global_load_dwordx4 v[134:137], v72, s[36:37] offset:3712
	s_waitcnt vmcnt(9)
	ds_write_b128 v67, v[86:89]
	s_waitcnt vmcnt(8)
	ds_write_b128 v67, v[130:133] offset:18432
	v_mfma_f32_32x32x16_bf16 v[18:33], v[118:121], v[98:101], v[18:33]
	global_load_dwordx4 v[86:89], v71, s[0:1] offset:3712
	global_load_dwordx4 v[98:101], v71, s[36:37] offset:3712
	v_mfma_f32_32x32x16_bf16 v[2:17], v[122:125], v[114:117], v[2:17]
	s_waitcnt lgkmcnt(2)
	v_mfma_f32_32x32x16_bf16 v[18:33], v[122:125], v[126:129], v[18:33]
	v_mfma_f32_32x32x16_bf16 v[34:49], v[110:113], v[114:117], v[34:49]
	v_mfma_f32_32x32x16_bf16 v[50:65], v[110:113], v[126:129], v[50:65]
	ds_read_b128 v[110:113], v0 offset:36928
	ds_read_b128 v[114:117], v0 offset:41536
	ds_read_b128 v[118:121], v66 offset:55360
	ds_read_b128 v[130:133], v66 offset:59968
	s_waitcnt vmcnt(9)
	ds_write_b128 v67, v[90:93] offset:4608
	s_waitcnt vmcnt(8)
	ds_write_b128 v67, v[102:105] offset:23040
	global_load_dwordx4 v[90:93], v70, s[0:1] offset:3712
	global_load_dwordx4 v[102:105], v70, s[36:37] offset:3712
	s_waitcnt lgkmcnt(3)
	v_mfma_f32_32x32x16_bf16 v[2:17], v[114:117], v[118:121], v[2:17]
	s_waitcnt lgkmcnt(2)
	v_mfma_f32_32x32x16_bf16 v[18:33], v[114:117], v[130:133], v[18:33]
	v_mfma_f32_32x32x16_bf16 v[34:49], v[110:113], v[118:121], v[34:49]
	v_mfma_f32_32x32x16_bf16 v[50:65], v[110:113], v[130:133], v[50:65]
	ds_read_b128 v[110:113], v0 offset:36960
	ds_read_b128 v[118:121], v0 offset:41568
	ds_read_b128 v[122:125], v66 offset:55392
	ds_read_b128 v[126:129], v66 offset:60000
	s_waitcnt vmcnt(9)
	ds_write_b128 v67, v[74:77] offset:9216
	s_waitcnt vmcnt(8)
	ds_write_b128 v67, v[106:109] offset:27648
	global_load_dwordx4 v[74:77], v69, s[0:1] offset:3712
	global_load_dwordx4 v[106:109], v69, s[36:37] offset:3712
	s_waitcnt lgkmcnt(3)
	v_mfma_f32_32x32x16_bf16 v[2:17], v[118:121], v[122:125], v[2:17]
	s_waitcnt vmcnt(9)
	ds_write_b128 v67, v[78:81] offset:13824
	s_waitcnt vmcnt(8)
	ds_write_b128 v67, v[94:97] offset:32256
	s_waitcnt lgkmcnt(4)
	v_mfma_f32_32x32x16_bf16 v[18:33], v[118:121], v[126:129], v[18:33]
	v_mfma_f32_32x32x16_bf16 v[34:49], v[110:113], v[122:125], v[34:49]
	v_mfma_f32_32x32x16_bf16 v[50:65], v[110:113], v[126:129], v[50:65]
	s_waitcnt lgkmcnt(0)
	s_barrier
	ds_read_b128 v[78:81], v0
	ds_read_b128 v[94:97], v66 offset:18432
	ds_read_b128 v[110:113], v0 offset:32
	ds_read_b128 v[114:117], v66 offset:18464
	ds_read_b128 v[118:121], v0 offset:4608
	ds_read_b128 v[122:125], v0 offset:4640
	s_waitcnt lgkmcnt(4)
	v_mfma_f32_32x32x16_bf16 v[34:49], v[78:81], v[94:97], v[34:49]
	s_waitcnt lgkmcnt(1)
	v_mfma_f32_32x32x16_bf16 v[2:17], v[118:121], v[94:97], v[2:17]
	ds_read_b128 v[94:97], v66 offset:23040
	ds_read_b128 v[126:129], v66 offset:23072
	s_waitcnt lgkmcnt(1)
	v_mfma_f32_32x32x16_bf16 v[50:65], v[78:81], v[94:97], v[50:65]
	global_load_dwordx4 v[78:81], v72, s[0:1] offset:3840
	global_load_dwordx4 v[130:133], v72, s[36:37] offset:3840
	s_waitcnt vmcnt(9)
	ds_write_b128 v67, v[82:85] offset:36864
	s_waitcnt vmcnt(8)
	ds_write_b128 v67, v[134:137] offset:55296
	v_mfma_f32_32x32x16_bf16 v[18:33], v[118:121], v[94:97], v[18:33]
	global_load_dwordx4 v[82:85], v71, s[0:1] offset:3840
	global_load_dwordx4 v[94:97], v71, s[36:37] offset:3840
	v_mfma_f32_32x32x16_bf16 v[2:17], v[122:125], v[114:117], v[2:17]
	s_waitcnt lgkmcnt(2)
	v_mfma_f32_32x32x16_bf16 v[18:33], v[122:125], v[126:129], v[18:33]
	v_mfma_f32_32x32x16_bf16 v[34:49], v[110:113], v[114:117], v[34:49]
	v_mfma_f32_32x32x16_bf16 v[50:65], v[110:113], v[126:129], v[50:65]
	ds_read_b128 v[110:113], v0 offset:64
	ds_read_b128 v[114:117], v0 offset:4672
	ds_read_b128 v[118:121], v66 offset:18496
	ds_read_b128 v[134:137], v66 offset:23104
	s_waitcnt vmcnt(9)
	ds_write_b128 v67, v[86:89] offset:41472
	s_waitcnt vmcnt(8)
	ds_write_b128 v67, v[98:101] offset:59904
	global_load_dwordx4 v[86:89], v70, s[0:1] offset:3840
	global_load_dwordx4 v[98:101], v70, s[36:37] offset:3840
	s_waitcnt lgkmcnt(3)
	v_mfma_f32_32x32x16_bf16 v[2:17], v[114:117], v[118:121], v[2:17]
	s_waitcnt lgkmcnt(2)
	v_mfma_f32_32x32x16_bf16 v[18:33], v[114:117], v[134:137], v[18:33]
	v_mfma_f32_32x32x16_bf16 v[34:49], v[110:113], v[118:121], v[34:49]
	v_mfma_f32_32x32x16_bf16 v[50:65], v[110:113], v[134:137], v[50:65]
	ds_read_b128 v[110:113], v0 offset:96
	ds_read_b128 v[118:121], v0 offset:4704
	ds_read_b128 v[122:125], v66 offset:18528
	ds_read_b128 v[126:129], v66 offset:23136
	s_waitcnt vmcnt(9)
	ds_write_b128 v67, v[90:93] offset:46080
	s_waitcnt vmcnt(8)
	ds_write_b128 v67, v[102:105] offset:64512
	global_load_dwordx4 v[90:93], v69, s[0:1] offset:3840
	global_load_dwordx4 v[102:105], v69, s[36:37] offset:3840
	s_waitcnt lgkmcnt(3)
	v_mfma_f32_32x32x16_bf16 v[2:17], v[118:121], v[122:125], v[2:17]
	s_waitcnt vmcnt(9)
	ds_write_b128 v67, v[74:77] offset:50688
	s_waitcnt vmcnt(8)
	ds_write_b128 v68, v[106:109] offset:13824
	s_waitcnt lgkmcnt(4)
	v_mfma_f32_32x32x16_bf16 v[18:33], v[118:121], v[126:129], v[18:33]
	v_mfma_f32_32x32x16_bf16 v[34:49], v[110:113], v[122:125], v[34:49]
	v_mfma_f32_32x32x16_bf16 v[50:65], v[110:113], v[126:129], v[50:65]
	s_waitcnt lgkmcnt(0)
	s_barrier
; #define GL1_(RA, RB, i) { RA[i] = *(const u32x4*)(ap + (aoff + (i) * astep)); if ((i) < NB) RB[(i) < NB ? (i) : 0] = *(const u32x4*)(bp + (boff + (i) * bstep)); }
; #define LS1_(RA, RB, ST, i) { char* sn_ = lds + (ST) * STAGE; *(u32x4*)(sn_ + wofs + (i) * 32 * LROW) = RA[i]; \
;                               if ((i) < NB) *(u32x4*)(sn_ + STAGE_OP + wofs + (i) * 32 * LROW) = RB[(i) < NB ? (i) : 0]; }
; template <int NJ> DI void gemm_mainloop_reg(const bf16_t* __restrict__ A, int lda, const bf16_t* __restrict__ Bt, int ldb, int K, f32x16 (&acc)[2][NJ], char* lds) {
;     ...
; #pragma unroll
;   for (int i = 0; i < 4; ++i) GL1_(ra0, rb0, i);
;   ap += 128; bp += 128;
; #pragma unroll
;   for (int i = 0; i < 4; ++i) GL1_(ra1, rb1, i);
;   ap += 128; bp += 128;
; #pragma unroll
;   for (int i = 0; i < 4; ++i) LS1_(ra0, rb0, 0, i);
;   __syncthreads();
;   const int nk = K >> 6;
;   for (int kt = 0; kt < nk; kt += 2) {
;     const bool l0 = (kt + 2 < nk), l1 = (kt + 3 < nk);
;     STEP_(0, l0, ra0, rb0, true, ra1, rb1);
;     __syncthreads();
;     STEP_(1, l1, ra1, rb1, l0, ra0, rb0);
;     __syncthreads();
;   }
	ds_read_b128 v[74:77], v0 offset:36864
	ds_read_b128 v[106:109], v66 offset:55296
	ds_read_b128 v[110:113], v0 offset:36896
	ds_read_b128 v[114:117], v66 offset:55328
	ds_read_b128 v[118:121], v0 offset:41472
	ds_read_b128 v[122:125], v0 offset:41504
	s_waitcnt lgkmcnt(4)
	v_mfma_f32_32x32x16_bf16 v[34:49], v[74:77], v[106:109], v[34:49]
	s_waitcnt lgkmcnt(1)
	v_mfma_f32_32x32x16_bf16 v[2:17], v[118:121], v[106:109], v[2:17]
	ds_read_b128 v[106:109], v66 offset:59904
	ds_read_b128 v[126:129], v66 offset:59936
	s_waitcnt lgkmcnt(1)
	v_mfma_f32_32x32x16_bf16 v[50:65], v[74:77], v[106:109], v[50:65]
	global_load_dwordx4 v[74:77], v72, s[0:1] offset:3968
	global_load_dwordx4 v[134:137], v72, s[36:37] offset:3968
	s_waitcnt vmcnt(9)
	ds_write_b128 v67, v[78:81]
	s_waitcnt vmcnt(8)
	ds_write_b128 v67, v[130:133] offset:18432
	v_mfma_f32_32x32x16_bf16 v[18:33], v[118:121], v[106:109], v[18:33]
	global_load_dwordx4 v[78:81], v71, s[0:1] offset:3968
	global_load_dwordx4 v[106:109], v71, s[36:37] offset:3968
	v_mfma_f32_32x32x16_bf16 v[2:17], v[122:125], v[114:117], v[2:17]
	s_waitcnt lgkmcnt(2)
	v_mfma_f32_32x32x16_bf16 v[18:33], v[122:125], v[126:129], v[18:33]
	v_mfma_f32_32x32x16_bf16 v[34:49], v[110:113], v[114:117], v[34:49]
	v_mfma_f32_32x32x16_bf16 v[50:65], v[110:113], v[126:129], v[50:65]
	ds_read_b128 v[110:113], v0 offset:36928
	ds_read_b128 v[114:117], v0 offset:41536
	ds_read_b128 v[118:121], v66 offset:55360
	ds_read_b128 v[130:133], v66 offset:59968
	s_waitcnt vmcnt(9)
	ds_write_b128 v67, v[82:85] offset:4608
	s_waitcnt vmcnt(8)
	ds_write_b128 v67, v[94:97] offset:23040
	global_load_dwordx4 v[82:85], v70, s[0:1] offset:3968
	global_load_dwordx4 v[94:97], v70, s[36:37] offset:3968
	s_waitcnt lgkmcnt(3)
	v_mfma_f32_32x32x16_bf16 v[2:17], v[114:117], v[118:121], v[2:17]
	s_waitcnt lgkmcnt(2)
	v_mfma_f32_32x32x16_bf16 v[18:33], v[114:117], v[130:133], v[18:33]
	v_mfma_f32_32x32x16_bf16 v[34:49], v[110:113], v[118:121], v[34:49]
	v_mfma_f32_32x32x16_bf16 v[50:65], v[110:113], v[130:133], v[50:65]
	ds_read_b128 v[110:113], v0 offset:36960
	ds_read_b128 v[118:121], v0 offset:41568
	ds_read_b128 v[122:125], v66 offset:55392
	ds_read_b128 v[126:129], v66 offset:60000
	s_waitcnt vmcnt(9)
	ds_write_b128 v67, v[86:89] offset:9216
	s_waitcnt vmcnt(8)
	ds_write_b128 v67, v[98:101] offset:27648
	global_load_dwordx4 v[86:89], v69, s[0:1] offset:3968
	global_load_dwordx4 v[98:101], v69, s[36:37] offset:3968
	s_waitcnt lgkmcnt(3)
	v_mfma_f32_32x32x16_bf16 v[2:17], v[118:121], v[122:125], v[2:17]
	s_waitcnt vmcnt(9)
	ds_write_b128 v67, v[90:93] offset:13824
	s_waitcnt vmcnt(8)
	ds_write_b128 v67, v[102:105] offset:32256
	s_waitcnt lgkmcnt(4)
	v_mfma_f32_32x32x16_bf16 v[18:33], v[118:121], v[126:129], v[18:33]
	v_mfma_f32_32x32x16_bf16 v[34:49], v[110:113], v[122:125], v[34:49]
	v_mfma_f32_32x32x16_bf16 v[50:65], v[110:113], v[126:129], v[50:65]
	s_waitcnt lgkmcnt(0)
	s_barrier
	ds_read_b128 v[90:93], v0
	ds_read_b128 v[102:105], v66 offset:18432
	ds_read_b128 v[110:113], v0 offset:32
	ds_read_b128 v[114:117], v66 offset:18464
	ds_read_b128 v[118:121], v0 offset:4608
	ds_read_b128 v[122:125], v0 offset:4640
	s_waitcnt lgkmcnt(4)
	v_mfma_f32_32x32x16_bf16 v[34:49], v[90:93], v[102:105], v[34:49]
	s_add_u32 s2, s36, 0x1000
	s_addc_u32 s3, s37, 0
	s_add_u32 s26, s0, 0x1000
	s_addc_u32 s27, s1, 0
	ds_read_b128 v[126:129], v66 offset:23072
	s_waitcnt lgkmcnt(2)
	v_mfma_f32_32x32x16_bf16 v[2:17], v[118:121], v[102:105], v[2:17]
	ds_read_b128 v[102:105], v66 offset:23040
	s_waitcnt lgkmcnt(0)
	v_mfma_f32_32x32x16_bf16 v[50:65], v[90:93], v[102:105], v[50:65]
	global_load_dwordx4 v[90:93], v72, s[26:27]
	global_load_dwordx4 v[130:133], v72, s[2:3]
	s_waitcnt vmcnt(9)
	ds_write_b128 v67, v[74:77] offset:36864
	s_waitcnt vmcnt(8)
	ds_write_b128 v67, v[134:137] offset:55296
	v_mfma_f32_32x32x16_bf16 v[18:33], v[118:121], v[102:105], v[18:33]
	global_load_dwordx4 v[74:77], v71, s[26:27]
	global_load_dwordx4 v[102:105], v71, s[2:3]
	v_mfma_f32_32x32x16_bf16 v[2:17], v[122:125], v[114:117], v[2:17]
	v_mfma_f32_32x32x16_bf16 v[18:33], v[122:125], v[126:129], v[18:33]
	v_mfma_f32_32x32x16_bf16 v[34:49], v[110:113], v[114:117], v[34:49]
	v_mfma_f32_32x32x16_bf16 v[50:65], v[110:113], v[126:129], v[50:65]
	ds_read_b128 v[110:113], v0 offset:64
	ds_read_b128 v[114:117], v0 offset:4672
	ds_read_b128 v[118:121], v66 offset:18496
	ds_read_b128 v[134:137], v66 offset:23104
	s_waitcnt vmcnt(9)
	ds_write_b128 v67, v[78:81] offset:41472
	s_waitcnt vmcnt(8)
	ds_write_b128 v67, v[106:109] offset:59904
	global_load_dwordx4 v[78:81], v70, s[26:27]
	global_load_dwordx4 v[106:109], v70, s[2:3]
	s_waitcnt lgkmcnt(3)
	v_mfma_f32_32x32x16_bf16 v[2:17], v[114:117], v[118:121], v[2:17]
	s_waitcnt lgkmcnt(2)
	v_mfma_f32_32x32x16_bf16 v[18:33], v[114:117], v[134:137], v[18:33]
	v_mfma_f32_32x32x16_bf16 v[34:49], v[110:113], v[118:121], v[34:49]
	v_mfma_f32_32x32x16_bf16 v[50:65], v[110:113], v[134:137], v[50:65]
	ds_read_b128 v[110:113], v0 offset:96
	ds_read_b128 v[118:121], v0 offset:4704
	ds_read_b128 v[122:125], v66 offset:18528
	ds_read_b128 v[126:129], v66 offset:23136
	s_waitcnt vmcnt(9)
	ds_write_b128 v67, v[82:85] offset:46080
	s_waitcnt vmcnt(8)
	ds_write_b128 v67, v[94:97] offset:64512
	global_load_dwordx4 v[82:85], v69, s[26:27]
	global_load_dwordx4 v[94:97], v69, s[2:3]
	s_waitcnt lgkmcnt(3)
	v_mfma_f32_32x32x16_bf16 v[2:17], v[118:121], v[122:125], v[2:17]
	s_waitcnt vmcnt(9)
	ds_write_b128 v67, v[86:89] offset:50688
	s_waitcnt vmcnt(8)
	ds_write_b128 v68, v[98:101] offset:13824
	s_waitcnt lgkmcnt(4)
	v_mfma_f32_32x32x16_bf16 v[18:33], v[118:121], v[126:129], v[18:33]
	v_mfma_f32_32x32x16_bf16 v[34:49], v[110:113], v[122:125], v[34:49]
	v_mfma_f32_32x32x16_bf16 v[50:65], v[110:113], v[126:129], v[50:65]
	s_waitcnt lgkmcnt(0)
	s_barrier
; #define GL1_(RA, RB, i) { RA[i] = *(const u32x4*)(ap + (aoff + (i) * astep)); if ((i) < NB) RB[(i) < NB ? (i) : 0] = *(const u32x4*)(bp + (boff + (i) * bstep)); }
; #define LS1_(RA, RB, ST, i) { char* sn_ = lds + (ST) * STAGE; *(u32x4*)(sn_ + wofs + (i) * 32 * LROW) = RA[i]; \
;                               if ((i) < NB) *(u32x4*)(sn_ + STAGE_OP + wofs + (i) * 32 * LROW) = RB[(i) < NB ? (i) : 0]; }
; template <int NJ> DI void gemm_mainloop_reg(const bf16_t* __restrict__ A, int lda, const bf16_t* __restrict__ Bt, int ldb, int K, f32x16 (&acc)[2][NJ], char* lds) {
;     ...
; #pragma unroll
;   for (int i = 0; i < 4; ++i) GL1_(ra0, rb0, i);
;   ap += 128; bp += 128;
; #pragma unroll
;   for (int i = 0; i < 4; ++i) GL1_(ra1, rb1, i);
;   ap += 128; bp += 128;
; #pragma unroll
;   for (int i = 0; i < 4; ++i) LS1_(ra0, rb0, 0, i);
;   __syncthreads();
;   const int nk = K >> 6;
;   for (int kt = 0; kt < nk; kt += 2) {
;     const bool l0 = (kt + 2 < nk), l1 = (kt + 3 < nk);
;     STEP_(0, l0, ra0, rb0, true, ra1, rb1);
;     __syncthreads();
;     STEP_(1, l1, ra1, rb1, l0, ra0, rb0);
;     __syncthreads();
;   }
	ds_read_b128 v[86:89], v0 offset:36864
	ds_read_b128 v[98:101], v66 offset:55296
	ds_read_b128 v[110:113], v0 offset:36896
	ds_read_b128 v[114:117], v66 offset:55328
	ds_read_b128 v[118:121], v0 offset:41472
	ds_read_b128 v[122:125], v0 offset:41504
	s_waitcnt lgkmcnt(4)
	v_mfma_f32_32x32x16_bf16 v[34:49], v[86:89], v[98:101], v[34:49]
	s_add_u32 s2, s36, 0x1080
	s_addc_u32 s3, s37, 0
	s_add_u32 s26, s0, 0x1080
	s_addc_u32 s27, s1, 0
	ds_read_b128 v[126:129], v66 offset:59936
	s_waitcnt lgkmcnt(2)
	v_mfma_f32_32x32x16_bf16 v[2:17], v[118:121], v[98:101], v[2:17]
	ds_read_b128 v[98:101], v66 offset:59904
	s_waitcnt lgkmcnt(0)
	v_mfma_f32_32x32x16_bf16 v[50:65], v[86:89], v[98:101], v[50:65]
	global_load_dwordx4 v[86:89], v72, s[26:27]
	global_load_dwordx4 v[134:137], v72, s[2:3]
	s_waitcnt vmcnt(9)
	ds_write_b128 v67, v[90:93]
	s_waitcnt vmcnt(8)
	ds_write_b128 v67, v[130:133] offset:18432
	v_mfma_f32_32x32x16_bf16 v[18:33], v[118:121], v[98:101], v[18:33]
	global_load_dwordx4 v[90:93], v71, s[26:27]
	global_load_dwordx4 v[98:101], v71, s[2:3]
	v_mfma_f32_32x32x16_bf16 v[2:17], v[122:125], v[114:117], v[2:17]
	v_mfma_f32_32x32x16_bf16 v[18:33], v[122:125], v[126:129], v[18:33]
	v_mfma_f32_32x32x16_bf16 v[34:49], v[110:113], v[114:117], v[34:49]
	v_mfma_f32_32x32x16_bf16 v[50:65], v[110:113], v[126:129], v[50:65]
	ds_read_b128 v[110:113], v0 offset:36928
	ds_read_b128 v[114:117], v0 offset:41536
	ds_read_b128 v[118:121], v66 offset:55360
	ds_read_b128 v[130:133], v66 offset:59968
	s_waitcnt vmcnt(9)
	ds_write_b128 v67, v[74:77] offset:4608
	s_waitcnt vmcnt(8)
	ds_write_b128 v67, v[102:105] offset:23040
	global_load_dwordx4 v[74:77], v70, s[26:27]
	global_load_dwordx4 v[102:105], v70, s[2:3]
	s_waitcnt lgkmcnt(3)
	v_mfma_f32_32x32x16_bf16 v[2:17], v[114:117], v[118:121], v[2:17]
	s_waitcnt lgkmcnt(2)
	v_mfma_f32_32x32x16_bf16 v[18:33], v[114:117], v[130:133], v[18:33]
	v_mfma_f32_32x32x16_bf16 v[34:49], v[110:113], v[118:121], v[34:49]
	v_mfma_f32_32x32x16_bf16 v[50:65], v[110:113], v[130:133], v[50:65]
	ds_read_b128 v[110:113], v0 offset:36960
	ds_read_b128 v[118:121], v0 offset:41568
	ds_read_b128 v[122:125], v66 offset:55392
	ds_read_b128 v[126:129], v66 offset:60000
	s_waitcnt vmcnt(9)
	ds_write_b128 v67, v[78:81] offset:9216
	s_waitcnt vmcnt(8)
	ds_write_b128 v67, v[106:109] offset:27648
	global_load_dwordx4 v[78:81], v69, s[26:27]
	global_load_dwordx4 v[106:109], v69, s[2:3]
	s_waitcnt lgkmcnt(3)
	v_mfma_f32_32x32x16_bf16 v[2:17], v[118:121], v[122:125], v[2:17]
	s_waitcnt vmcnt(9)
	ds_write_b128 v67, v[82:85] offset:13824
	s_waitcnt vmcnt(8)
	ds_write_b128 v67, v[94:97] offset:32256
	s_waitcnt lgkmcnt(4)
	v_mfma_f32_32x32x16_bf16 v[18:33], v[118:121], v[126:129], v[18:33]
	v_mfma_f32_32x32x16_bf16 v[34:49], v[110:113], v[122:125], v[34:49]
	v_mfma_f32_32x32x16_bf16 v[50:65], v[110:113], v[126:129], v[50:65]
	s_waitcnt lgkmcnt(0)
	s_barrier
	ds_read_b128 v[82:85], v0
	ds_read_b128 v[94:97], v66 offset:18432
	ds_read_b128 v[110:113], v0 offset:32
	ds_read_b128 v[114:117], v66 offset:18464
	ds_read_b128 v[118:121], v0 offset:4608
	ds_read_b128 v[122:125], v0 offset:4640
	s_waitcnt lgkmcnt(4)
	v_mfma_f32_32x32x16_bf16 v[34:49], v[82:85], v[94:97], v[34:49]
	s_add_u32 s2, s36, 0x1100
	s_addc_u32 s3, s37, 0
	s_add_u32 s26, s0, 0x1100
	s_addc_u32 s27, s1, 0
	ds_read_b128 v[126:129], v66 offset:23072
	s_waitcnt lgkmcnt(2)
	v_mfma_f32_32x32x16_bf16 v[2:17], v[118:121], v[94:97], v[2:17]
	ds_read_b128 v[94:97], v66 offset:23040
	s_waitcnt lgkmcnt(0)
	v_mfma_f32_32x32x16_bf16 v[50:65], v[82:85], v[94:97], v[50:65]
	global_load_dwordx4 v[82:85], v72, s[26:27]
	global_load_dwordx4 v[130:133], v72, s[2:3]
	s_waitcnt vmcnt(9)
	ds_write_b128 v67, v[86:89] offset:36864
	s_waitcnt vmcnt(8)
	ds_write_b128 v67, v[134:137] offset:55296
	v_mfma_f32_32x32x16_bf16 v[18:33], v[118:121], v[94:97], v[18:33]
	global_load_dwordx4 v[86:89], v71, s[26:27]
	global_load_dwordx4 v[94:97], v71, s[2:3]
	v_mfma_f32_32x32x16_bf16 v[2:17], v[122:125], v[114:117], v[2:17]
	v_mfma_f32_32x32x16_bf16 v[18:33], v[122:125], v[126:129], v[18:33]
	v_mfma_f32_32x32x16_bf16 v[34:49], v[110:113], v[114:117], v[34:49]
	v_mfma_f32_32x32x16_bf16 v[50:65], v[110:113], v[126:129], v[50:65]
	ds_read_b128 v[110:113], v0 offset:64
	ds_read_b128 v[114:117], v0 offset:4672
	ds_read_b128 v[118:121], v66 offset:18496
	ds_read_b128 v[134:137], v66 offset:23104
	s_waitcnt vmcnt(9)
	ds_write_b128 v67, v[90:93] offset:41472
	s_waitcnt vmcnt(8)
	ds_write_b128 v67, v[98:101] offset:59904
	global_load_dwordx4 v[90:93], v70, s[26:27]
	global_load_dwordx4 v[98:101], v70, s[2:3]
	s_waitcnt lgkmcnt(3)
	v_mfma_f32_32x32x16_bf16 v[2:17], v[114:117], v[118:121], v[2:17]
	s_waitcnt lgkmcnt(2)
	v_mfma_f32_32x32x16_bf16 v[18:33], v[114:117], v[134:137], v[18:33]
	v_mfma_f32_32x32x16_bf16 v[34:49], v[110:113], v[118:121], v[34:49]
	v_mfma_f32_32x32x16_bf16 v[50:65], v[110:113], v[134:137], v[50:65]
	ds_read_b128 v[110:113], v0 offset:96
	ds_read_b128 v[118:121], v0 offset:4704
	ds_read_b128 v[122:125], v66 offset:18528
	ds_read_b128 v[126:129], v66 offset:23136
	s_waitcnt vmcnt(9)
	ds_write_b128 v67, v[74:77] offset:46080
	s_waitcnt vmcnt(8)
	ds_write_b128 v67, v[102:105] offset:64512
	global_load_dwordx4 v[74:77], v69, s[26:27]
	global_load_dwordx4 v[102:105], v69, s[2:3]
	s_waitcnt lgkmcnt(3)
	v_mfma_f32_32x32x16_bf16 v[2:17], v[118:121], v[122:125], v[2:17]
	s_waitcnt vmcnt(9)
	ds_write_b128 v67, v[78:81] offset:50688
	s_waitcnt vmcnt(8)
	ds_write_b128 v68, v[106:109] offset:13824
	s_waitcnt lgkmcnt(4)
	v_mfma_f32_32x32x16_bf16 v[18:33], v[118:121], v[126:129], v[18:33]
	v_mfma_f32_32x32x16_bf16 v[34:49], v[110:113], v[122:125], v[34:49]
	v_mfma_f32_32x32x16_bf16 v[50:65], v[110:113], v[126:129], v[50:65]
	s_waitcnt lgkmcnt(0)
	s_barrier
; #define GL1_(RA, RB, i) { RA[i] = *(const u32x4*)(ap + (aoff + (i) * astep)); if ((i) < NB) RB[(i) < NB ? (i) : 0] = *(const u32x4*)(bp + (boff + (i) * bstep)); }
; #define LS1_(RA, RB, ST, i) { char* sn_ = lds + (ST) * STAGE; *(u32x4*)(sn_ + wofs + (i) * 32 * LROW) = RA[i]; \
;                               if ((i) < NB) *(u32x4*)(sn_ + STAGE_OP + wofs + (i) * 32 * LROW) = RB[(i) < NB ? (i) : 0]; }
; template <int NJ> DI void gemm_mainloop_reg(const bf16_t* __restrict__ A, int lda, const bf16_t* __restrict__ Bt, int ldb, int K, f32x16 (&acc)[2][NJ], char* lds) {
;     ...
; #pragma unroll
;   for (int i = 0; i < 4; ++i) GL1_(ra0, rb0, i);
;   ap += 128; bp += 128;
; #pragma unroll
;   for (int i = 0; i < 4; ++i) GL1_(ra1, rb1, i);
;   ap += 128; bp += 128;
; #pragma unroll
;   for (int i = 0; i < 4; ++i) LS1_(ra0, rb0, 0, i);
;   __syncthreads();
;   const int nk = K >> 6;
;   for (int kt = 0; kt < nk; kt += 2) {
;     const bool l0 = (kt + 2 < nk), l1 = (kt + 3 < nk);
;     STEP_(0, l0, ra0, rb0, true, ra1, rb1);
;     __syncthreads();
;     STEP_(1, l1, ra1, rb1, l0, ra0, rb0);
;     __syncthreads();
;   }
	ds_read_b128 v[78:81], v0 offset:36864
	ds_read_b128 v[106:109], v66 offset:55296
	ds_read_b128 v[110:113], v0 offset:36896
	ds_read_b128 v[114:117], v66 offset:55328
	ds_read_b128 v[118:121], v0 offset:41472
	ds_read_b128 v[122:125], v0 offset:41504
	s_waitcnt lgkmcnt(4)
	v_mfma_f32_32x32x16_bf16 v[34:49], v[78:81], v[106:109], v[34:49]
	s_add_u32 s2, s36, 0x1180
	s_addc_u32 s3, s37, 0
	s_add_u32 s26, s0, 0x1180
	s_addc_u32 s27, s1, 0
	ds_read_b128 v[126:129], v66 offset:59936
	s_waitcnt lgkmcnt(2)
	v_mfma_f32_32x32x16_bf16 v[2:17], v[118:121], v[106:109], v[2:17]
	ds_read_b128 v[106:109], v66 offset:59904
	s_waitcnt lgkmcnt(0)
	v_mfma_f32_32x32x16_bf16 v[50:65], v[78:81], v[106:109], v[50:65]
	global_load_dwordx4 v[78:81], v72, s[26:27]
	global_load_dwordx4 v[134:137], v72, s[2:3]
	s_waitcnt vmcnt(9)
	ds_write_b128 v67, v[82:85]
	s_waitcnt vmcnt(8)
	ds_write_b128 v67, v[130:133] offset:18432
	v_mfma_f32_32x32x16_bf16 v[18:33], v[118:121], v[106:109], v[18:33]
	global_load_dwordx4 v[82:85], v71, s[26:27]
	global_load_dwordx4 v[106:109], v71, s[2:3]
	v_mfma_f32_32x32x16_bf16 v[2:17], v[122:125], v[114:117], v[2:17]
	v_mfma_f32_32x32x16_bf16 v[18:33], v[122:125], v[126:129], v[18:33]
	v_mfma_f32_32x32x16_bf16 v[34:49], v[110:113], v[114:117], v[34:49]
	v_mfma_f32_32x32x16_bf16 v[50:65], v[110:113], v[126:129], v[50:65]
	ds_read_b128 v[110:113], v0 offset:36928
	ds_read_b128 v[114:117], v0 offset:41536
	ds_read_b128 v[118:121], v66 offset:55360
	ds_read_b128 v[130:133], v66 offset:59968
	s_waitcnt vmcnt(9)
	ds_write_b128 v67, v[86:89] offset:4608
	s_waitcnt vmcnt(8)
	ds_write_b128 v67, v[94:97] offset:23040
	global_load_dwordx4 v[86:89], v70, s[26:27]
	global_load_dwordx4 v[94:97], v70, s[2:3]
	s_waitcnt lgkmcnt(3)
	v_mfma_f32_32x32x16_bf16 v[2:17], v[114:117], v[118:121], v[2:17]
	s_waitcnt lgkmcnt(2)
	v_mfma_f32_32x32x16_bf16 v[18:33], v[114:117], v[130:133], v[18:33]
	v_mfma_f32_32x32x16_bf16 v[34:49], v[110:113], v[118:121], v[34:49]
	v_mfma_f32_32x32x16_bf16 v[50:65], v[110:113], v[130:133], v[50:65]
	ds_read_b128 v[110:113], v0 offset:36960
	ds_read_b128 v[118:121], v0 offset:41568
	ds_read_b128 v[122:125], v66 offset:55392
	ds_read_b128 v[126:129], v66 offset:60000
	s_waitcnt vmcnt(9)
	ds_write_b128 v67, v[90:93] offset:9216
	s_waitcnt vmcnt(8)
	ds_write_b128 v67, v[98:101] offset:27648
	global_load_dwordx4 v[90:93], v69, s[26:27]
	global_load_dwordx4 v[98:101], v69, s[2:3]
	s_waitcnt lgkmcnt(3)
	v_mfma_f32_32x32x16_bf16 v[2:17], v[118:121], v[122:125], v[2:17]
	s_waitcnt vmcnt(9)
	ds_write_b128 v67, v[74:77] offset:13824
	s_waitcnt vmcnt(8)
	ds_write_b128 v67, v[102:105] offset:32256
	s_waitcnt lgkmcnt(4)
	v_mfma_f32_32x32x16_bf16 v[18:33], v[118:121], v[126:129], v[18:33]
	v_mfma_f32_32x32x16_bf16 v[34:49], v[110:113], v[122:125], v[34:49]
	v_mfma_f32_32x32x16_bf16 v[50:65], v[110:113], v[126:129], v[50:65]
	s_waitcnt lgkmcnt(0)
	s_barrier
	ds_read_b128 v[74:77], v0
	ds_read_b128 v[102:105], v66 offset:18432
	ds_read_b128 v[110:113], v0 offset:32
	ds_read_b128 v[114:117], v66 offset:18464
	ds_read_b128 v[118:121], v0 offset:4608
	ds_read_b128 v[122:125], v0 offset:4640
	s_waitcnt lgkmcnt(4)
	v_mfma_f32_32x32x16_bf16 v[34:49], v[74:77], v[102:105], v[34:49]
	s_add_u32 s2, s36, 0x1200
	s_addc_u32 s3, s37, 0
	s_add_u32 s26, s0, 0x1200
	s_addc_u32 s27, s1, 0
	ds_read_b128 v[126:129], v66 offset:23072
	s_waitcnt lgkmcnt(2)
	v_mfma_f32_32x32x16_bf16 v[2:17], v[118:121], v[102:105], v[2:17]
	ds_read_b128 v[102:105], v66 offset:23040
	s_waitcnt lgkmcnt(0)
	v_mfma_f32_32x32x16_bf16 v[50:65], v[74:77], v[102:105], v[50:65]
	global_load_dwordx4 v[74:77], v72, s[26:27]
	global_load_dwordx4 v[130:133], v72, s[2:3]
	s_waitcnt vmcnt(9)
	ds_write_b128 v67, v[78:81] offset:36864
	s_waitcnt vmcnt(8)
	ds_write_b128 v67, v[134:137] offset:55296
	v_mfma_f32_32x32x16_bf16 v[18:33], v[118:121], v[102:105], v[18:33]
	global_load_dwordx4 v[78:81], v71, s[26:27]
	global_load_dwordx4 v[102:105], v71, s[2:3]
	v_mfma_f32_32x32x16_bf16 v[2:17], v[122:125], v[114:117], v[2:17]
	v_mfma_f32_32x32x16_bf16 v[18:33], v[122:125], v[126:129], v[18:33]
	v_mfma_f32_32x32x16_bf16 v[34:49], v[110:113], v[114:117], v[34:49]
	v_mfma_f32_32x32x16_bf16 v[50:65], v[110:113], v[126:129], v[50:65]
	ds_read_b128 v[110:113], v0 offset:64
	ds_read_b128 v[114:117], v0 offset:4672
	ds_read_b128 v[118:121], v66 offset:18496
	ds_read_b128 v[134:137], v66 offset:23104
	s_waitcnt vmcnt(9)
	ds_write_b128 v67, v[82:85] offset:41472
	s_waitcnt vmcnt(8)
	ds_write_b128 v67, v[106:109] offset:59904
	global_load_dwordx4 v[82:85], v70, s[26:27]
	global_load_dwordx4 v[106:109], v70, s[2:3]
	s_waitcnt lgkmcnt(3)
	v_mfma_f32_32x32x16_bf16 v[2:17], v[114:117], v[118:121], v[2:17]
	s_waitcnt lgkmcnt(2)
	v_mfma_f32_32x32x16_bf16 v[18:33], v[114:117], v[134:137], v[18:33]
	v_mfma_f32_32x32x16_bf16 v[34:49], v[110:113], v[118:121], v[34:49]
	v_mfma_f32_32x32x16_bf16 v[50:65], v[110:113], v[134:137], v[50:65]
	ds_read_b128 v[110:113], v0 offset:96
	ds_read_b128 v[118:121], v0 offset:4704
	ds_read_b128 v[122:125], v66 offset:18528
	ds_read_b128 v[126:129], v66 offset:23136
	s_waitcnt vmcnt(9)
	ds_write_b128 v67, v[86:89] offset:46080
	s_waitcnt vmcnt(8)
	ds_write_b128 v67, v[94:97] offset:64512
	global_load_dwordx4 v[86:89], v69, s[26:27]
	global_load_dwordx4 v[94:97], v69, s[2:3]
	s_waitcnt lgkmcnt(3)
	v_mfma_f32_32x32x16_bf16 v[2:17], v[118:121], v[122:125], v[2:17]
	s_waitcnt vmcnt(9)
	ds_write_b128 v67, v[90:93] offset:50688
	s_waitcnt vmcnt(8)
	ds_write_b128 v68, v[98:101] offset:13824
	s_waitcnt lgkmcnt(4)
	v_mfma_f32_32x32x16_bf16 v[18:33], v[118:121], v[126:129], v[18:33]
	v_mfma_f32_32x32x16_bf16 v[34:49], v[110:113], v[122:125], v[34:49]
	v_mfma_f32_32x32x16_bf16 v[50:65], v[110:113], v[126:129], v[50:65]
	s_waitcnt lgkmcnt(0)
	s_barrier
; #define GL1_(RA, RB, i) { RA[i] = *(const u32x4*)(ap + (aoff + (i) * astep)); if ((i) < NB) RB[(i) < NB ? (i) : 0] = *(const u32x4*)(bp + (boff + (i) * bstep)); }
; #define LS1_(RA, RB, ST, i) { char* sn_ = lds + (ST) * STAGE; *(u32x4*)(sn_ + wofs + (i) * 32 * LROW) = RA[i]; \
;                               if ((i) < NB) *(u32x4*)(sn_ + STAGE_OP + wofs + (i) * 32 * LROW) = RB[(i) < NB ? (i) : 0]; }
; template <int NJ> DI void gemm_mainloop_reg(const bf16_t* __restrict__ A, int lda, const bf16_t* __restrict__ Bt, int ldb, int K, f32x16 (&acc)[2][NJ], char* lds) {
;     ...
; #pragma unroll
;   for (int i = 0; i < 4; ++i) GL1_(ra0, rb0, i);
;   ap += 128; bp += 128;
; #pragma unroll
;   for (int i = 0; i < 4; ++i) GL1_(ra1, rb1, i);
;   ap += 128; bp += 128;
; #pragma unroll
;   for (int i = 0; i < 4; ++i) LS1_(ra0, rb0, 0, i);
;   __syncthreads();
;   const int nk = K >> 6;
;   for (int kt = 0; kt < nk; kt += 2) {
;     const bool l0 = (kt + 2 < nk), l1 = (kt + 3 < nk);
;     STEP_(0, l0, ra0, rb0, true, ra1, rb1);
;     __syncthreads();
;     STEP_(1, l1, ra1, rb1, l0, ra0, rb0);
;     __syncthreads();
;   }
	ds_read_b128 v[90:93], v0 offset:36864
	ds_read_b128 v[98:101], v66 offset:55296
	ds_read_b128 v[110:113], v0 offset:36896
	ds_read_b128 v[114:117], v66 offset:55328
	ds_read_b128 v[118:121], v0 offset:41472
	ds_read_b128 v[122:125], v0 offset:41504
	s_waitcnt lgkmcnt(4)
	v_mfma_f32_32x32x16_bf16 v[34:49], v[90:93], v[98:101], v[34:49]
	s_add_u32 s2, s36, 0x1280
	s_addc_u32 s3, s37, 0
	s_add_u32 s26, s0, 0x1280
	s_addc_u32 s27, s1, 0
	ds_read_b128 v[126:129], v66 offset:59936
	s_waitcnt lgkmcnt(2)
	v_mfma_f32_32x32x16_bf16 v[2:17], v[118:121], v[98:101], v[2:17]
	ds_read_b128 v[98:101], v66 offset:59904
	s_waitcnt lgkmcnt(0)
	v_mfma_f32_32x32x16_bf16 v[50:65], v[90:93], v[98:101], v[50:65]
	global_load_dwordx4 v[90:93], v72, s[26:27]
	global_load_dwordx4 v[134:137], v72, s[2:3]
	s_waitcnt vmcnt(9)
	ds_write_b128 v67, v[74:77]
	s_waitcnt vmcnt(8)
	ds_write_b128 v67, v[130:133] offset:18432
	v_mfma_f32_32x32x16_bf16 v[18:33], v[118:121], v[98:101], v[18:33]
	global_load_dwordx4 v[74:77], v71, s[26:27]
	global_load_dwordx4 v[98:101], v71, s[2:3]
	v_mfma_f32_32x32x16_bf16 v[2:17], v[122:125], v[114:117], v[2:17]
	v_mfma_f32_32x32x16_bf16 v[18:33], v[122:125], v[126:129], v[18:33]
	v_mfma_f32_32x32x16_bf16 v[34:49], v[110:113], v[114:117], v[34:49]
	v_mfma_f32_32x32x16_bf16 v[50:65], v[110:113], v[126:129], v[50:65]
	ds_read_b128 v[110:113], v0 offset:36928
	ds_read_b128 v[114:117], v0 offset:41536
	ds_read_b128 v[118:121], v66 offset:55360
	ds_read_b128 v[130:133], v66 offset:59968
	s_waitcnt vmcnt(9)
	ds_write_b128 v67, v[78:81] offset:4608
	s_waitcnt vmcnt(8)
	ds_write_b128 v67, v[102:105] offset:23040
	global_load_dwordx4 v[78:81], v70, s[26:27]
	global_load_dwordx4 v[102:105], v70, s[2:3]
	s_waitcnt lgkmcnt(3)
	v_mfma_f32_32x32x16_bf16 v[2:17], v[114:117], v[118:121], v[2:17]
	s_waitcnt lgkmcnt(2)
	v_mfma_f32_32x32x16_bf16 v[18:33], v[114:117], v[130:133], v[18:33]
	v_mfma_f32_32x32x16_bf16 v[34:49], v[110:113], v[118:121], v[34:49]
	v_mfma_f32_32x32x16_bf16 v[50:65], v[110:113], v[130:133], v[50:65]
	ds_read_b128 v[110:113], v0 offset:36960
	ds_read_b128 v[118:121], v0 offset:41568
	ds_read_b128 v[122:125], v66 offset:55392
	ds_read_b128 v[126:129], v66 offset:60000
	s_waitcnt vmcnt(9)
	ds_write_b128 v67, v[82:85] offset:9216
	s_waitcnt vmcnt(8)
	ds_write_b128 v67, v[106:109] offset:27648
	global_load_dwordx4 v[82:85], v69, s[26:27]
	global_load_dwordx4 v[106:109], v69, s[2:3]
	s_waitcnt lgkmcnt(3)
	v_mfma_f32_32x32x16_bf16 v[2:17], v[118:121], v[122:125], v[2:17]
	s_waitcnt vmcnt(9)
	ds_write_b128 v67, v[86:89] offset:13824
	s_waitcnt vmcnt(8)
	ds_write_b128 v67, v[94:97] offset:32256
	s_waitcnt lgkmcnt(4)
	v_mfma_f32_32x32x16_bf16 v[18:33], v[118:121], v[126:129], v[18:33]
	v_mfma_f32_32x32x16_bf16 v[34:49], v[110:113], v[122:125], v[34:49]
	v_mfma_f32_32x32x16_bf16 v[50:65], v[110:113], v[126:129], v[50:65]
	s_waitcnt lgkmcnt(0)
	s_barrier
	ds_read_b128 v[86:89], v0
	ds_read_b128 v[94:97], v66 offset:18432
	ds_read_b128 v[110:113], v0 offset:32
	ds_read_b128 v[114:117], v66 offset:18464
	ds_read_b128 v[118:121], v0 offset:4608
	ds_read_b128 v[122:125], v0 offset:4640
	s_waitcnt lgkmcnt(4)
	v_mfma_f32_32x32x16_bf16 v[34:49], v[86:89], v[94:97], v[34:49]
	s_add_u32 s2, s36, 0x1300
	s_addc_u32 s3, s37, 0
	s_add_u32 s26, s0, 0x1300
	s_addc_u32 s27, s1, 0
	ds_read_b128 v[126:129], v66 offset:23072
	s_waitcnt lgkmcnt(2)
	v_mfma_f32_32x32x16_bf16 v[2:17], v[118:121], v[94:97], v[2:17]
	ds_read_b128 v[94:97], v66 offset:23040
	s_waitcnt lgkmcnt(0)
	v_mfma_f32_32x32x16_bf16 v[50:65], v[86:89], v[94:97], v[50:65]
	global_load_dwordx4 v[86:89], v72, s[26:27]
	global_load_dwordx4 v[130:133], v72, s[2:3]
	s_waitcnt vmcnt(9)
	ds_write_b128 v67, v[90:93] offset:36864
	s_waitcnt vmcnt(8)
	ds_write_b128 v67, v[134:137] offset:55296
	v_mfma_f32_32x32x16_bf16 v[18:33], v[118:121], v[94:97], v[18:33]
	global_load_dwordx4 v[90:93], v71, s[26:27]
	global_load_dwordx4 v[94:97], v71, s[2:3]
	v_mfma_f32_32x32x16_bf16 v[2:17], v[122:125], v[114:117], v[2:17]
	v_mfma_f32_32x32x16_bf16 v[18:33], v[122:125], v[126:129], v[18:33]
	v_mfma_f32_32x32x16_bf16 v[34:49], v[110:113], v[114:117], v[34:49]
	v_mfma_f32_32x32x16_bf16 v[50:65], v[110:113], v[126:129], v[50:65]
	ds_read_b128 v[110:113], v0 offset:64
	ds_read_b128 v[114:117], v0 offset:4672
	ds_read_b128 v[118:121], v66 offset:18496
	ds_read_b128 v[134:137], v66 offset:23104
	s_waitcnt vmcnt(9)
	ds_write_b128 v67, v[74:77] offset:41472
	s_waitcnt vmcnt(8)
	ds_write_b128 v67, v[98:101] offset:59904
	global_load_dwordx4 v[74:77], v70, s[26:27]
	global_load_dwordx4 v[98:101], v70, s[2:3]
	s_waitcnt lgkmcnt(3)
	v_mfma_f32_32x32x16_bf16 v[2:17], v[114:117], v[118:121], v[2:17]
	s_waitcnt lgkmcnt(2)
	v_mfma_f32_32x32x16_bf16 v[18:33], v[114:117], v[134:137], v[18:33]
	v_mfma_f32_32x32x16_bf16 v[34:49], v[110:113], v[118:121], v[34:49]
	v_mfma_f32_32x32x16_bf16 v[50:65], v[110:113], v[134:137], v[50:65]
	ds_read_b128 v[110:113], v0 offset:96
	ds_read_b128 v[118:121], v0 offset:4704
	ds_read_b128 v[122:125], v66 offset:18528
	ds_read_b128 v[126:129], v66 offset:23136
	s_waitcnt vmcnt(9)
	ds_write_b128 v67, v[78:81] offset:46080
	s_waitcnt vmcnt(8)
	ds_write_b128 v67, v[102:105] offset:64512
	global_load_dwordx4 v[78:81], v69, s[26:27]
	global_load_dwordx4 v[102:105], v69, s[2:3]
	s_waitcnt lgkmcnt(3)
	v_mfma_f32_32x32x16_bf16 v[2:17], v[118:121], v[122:125], v[2:17]
	s_waitcnt vmcnt(9)
	ds_write_b128 v67, v[82:85] offset:50688
	s_waitcnt vmcnt(8)
	ds_write_b128 v68, v[106:109] offset:13824
	s_waitcnt lgkmcnt(4)
	v_mfma_f32_32x32x16_bf16 v[18:33], v[118:121], v[126:129], v[18:33]
	v_mfma_f32_32x32x16_bf16 v[34:49], v[110:113], v[122:125], v[34:49]
	v_mfma_f32_32x32x16_bf16 v[50:65], v[110:113], v[126:129], v[50:65]
	s_waitcnt lgkmcnt(0)
	s_barrier
; #define GL1_(RA, RB, i) { RA[i] = *(const u32x4*)(ap + (aoff + (i) * astep)); if ((i) < NB) RB[(i) < NB ? (i) : 0] = *(const u32x4*)(bp + (boff + (i) * bstep)); }
; #define LS1_(RA, RB, ST, i) { char* sn_ = lds + (ST) * STAGE; *(u32x4*)(sn_ + wofs + (i) * 32 * LROW) = RA[i]; \
;                               if ((i) < NB) *(u32x4*)(sn_ + STAGE_OP + wofs + (i) * 32 * LROW) = RB[(i) < NB ? (i) : 0]; }
; template <int NJ> DI void gemm_mainloop_reg(const bf16_t* __restrict__ A, int lda, const bf16_t* __restrict__ Bt, int ldb, int K, f32x16 (&acc)[2][NJ], char* lds) {
;     ...
; #pragma unroll
;   for (int i = 0; i < 4; ++i) GL1_(ra0, rb0, i);
;   ap += 128; bp += 128;
; #pragma unroll
;   for (int i = 0; i < 4; ++i) GL1_(ra1, rb1, i);
;   ap += 128; bp += 128;
; #pragma unroll
;   for (int i = 0; i < 4; ++i) LS1_(ra0, rb0, 0, i);
;   __syncthreads();
;   const int nk = K >> 6;
;   for (int kt = 0; kt < nk; kt += 2) {
;     const bool l0 = (kt + 2 < nk), l1 = (kt + 3 < nk);
;     STEP_(0, l0, ra0, rb0, true, ra1, rb1);
;     __syncthreads();
;     STEP_(1, l1, ra1, rb1, l0, ra0, rb0);
;     __syncthreads();
;   }
	ds_read_b128 v[82:85], v0 offset:36864
	ds_read_b128 v[106:109], v66 offset:55296
	ds_read_b128 v[110:113], v0 offset:36896
	ds_read_b128 v[114:117], v66 offset:55328
	ds_read_b128 v[118:121], v0 offset:41472
	ds_read_b128 v[122:125], v0 offset:41504
	s_waitcnt lgkmcnt(4)
	v_mfma_f32_32x32x16_bf16 v[34:49], v[82:85], v[106:109], v[34:49]
	s_add_u32 s2, s36, 0x1380
	s_addc_u32 s3, s37, 0
	s_add_u32 s26, s0, 0x1380
	s_addc_u32 s27, s1, 0
	ds_read_b128 v[126:129], v66 offset:59936
	s_waitcnt lgkmcnt(2)
	v_mfma_f32_32x32x16_bf16 v[2:17], v[118:121], v[106:109], v[2:17]
	ds_read_b128 v[106:109], v66 offset:59904
	s_waitcnt lgkmcnt(0)
	v_mfma_f32_32x32x16_bf16 v[50:65], v[82:85], v[106:109], v[50:65]
	global_load_dwordx4 v[82:85], v72, s[26:27]
	global_load_dwordx4 v[134:137], v72, s[2:3]
	s_waitcnt vmcnt(9)
	ds_write_b128 v67, v[86:89]
	s_waitcnt vmcnt(8)
	ds_write_b128 v67, v[130:133] offset:18432
	v_mfma_f32_32x32x16_bf16 v[18:33], v[118:121], v[106:109], v[18:33]
	global_load_dwordx4 v[86:89], v71, s[26:27]
	global_load_dwordx4 v[106:109], v71, s[2:3]
	v_mfma_f32_32x32x16_bf16 v[2:17], v[122:125], v[114:117], v[2:17]
	v_mfma_f32_32x32x16_bf16 v[18:33], v[122:125], v[126:129], v[18:33]
	v_mfma_f32_32x32x16_bf16 v[34:49], v[110:113], v[114:117], v[34:49]
	v_mfma_f32_32x32x16_bf16 v[50:65], v[110:113], v[126:129], v[50:65]
	ds_read_b128 v[110:113], v0 offset:36928
	ds_read_b128 v[114:117], v0 offset:41536
	ds_read_b128 v[118:121], v66 offset:55360
	ds_read_b128 v[130:133], v66 offset:59968
	s_waitcnt vmcnt(9)
	ds_write_b128 v67, v[90:93] offset:4608
	s_waitcnt vmcnt(8)
	ds_write_b128 v67, v[94:97] offset:23040
	global_load_dwordx4 v[90:93], v70, s[26:27]
	global_load_dwordx4 v[94:97], v70, s[2:3]
	s_waitcnt lgkmcnt(3)
	v_mfma_f32_32x32x16_bf16 v[2:17], v[114:117], v[118:121], v[2:17]
	s_waitcnt lgkmcnt(2)
	v_mfma_f32_32x32x16_bf16 v[18:33], v[114:117], v[130:133], v[18:33]
	v_mfma_f32_32x32x16_bf16 v[34:49], v[110:113], v[118:121], v[34:49]
	v_mfma_f32_32x32x16_bf16 v[50:65], v[110:113], v[130:133], v[50:65]
	ds_read_b128 v[110:113], v0 offset:36960
	ds_read_b128 v[118:121], v0 offset:41568
	ds_read_b128 v[122:125], v66 offset:55392
	ds_read_b128 v[126:129], v66 offset:60000
	s_waitcnt vmcnt(9)
	ds_write_b128 v67, v[74:77] offset:9216
	s_waitcnt vmcnt(8)
	ds_write_b128 v67, v[98:101] offset:27648
	global_load_dwordx4 v[74:77], v69, s[26:27]
	global_load_dwordx4 v[98:101], v69, s[2:3]
	s_waitcnt lgkmcnt(3)
	v_mfma_f32_32x32x16_bf16 v[2:17], v[118:121], v[122:125], v[2:17]
	s_waitcnt vmcnt(9)
	ds_write_b128 v67, v[78:81] offset:13824
	s_waitcnt vmcnt(8)
	ds_write_b128 v67, v[102:105] offset:32256
	s_waitcnt lgkmcnt(4)
	v_mfma_f32_32x32x16_bf16 v[18:33], v[118:121], v[126:129], v[18:33]
	v_mfma_f32_32x32x16_bf16 v[34:49], v[110:113], v[122:125], v[34:49]
	v_mfma_f32_32x32x16_bf16 v[50:65], v[110:113], v[126:129], v[50:65]
	s_waitcnt lgkmcnt(0)
	s_barrier
	ds_read_b128 v[78:81], v0
	ds_read_b128 v[102:105], v66 offset:18432
	ds_read_b128 v[110:113], v0 offset:32
	ds_read_b128 v[114:117], v66 offset:18464
	ds_read_b128 v[118:121], v0 offset:4608
	ds_read_b128 v[122:125], v0 offset:4640
	s_waitcnt lgkmcnt(4)
	v_mfma_f32_32x32x16_bf16 v[34:49], v[78:81], v[102:105], v[34:49]
	s_add_u32 s2, s36, 0x1400
	s_addc_u32 s3, s37, 0
	s_add_u32 s26, s0, 0x1400
	s_addc_u32 s27, s1, 0
	ds_read_b128 v[126:129], v66 offset:23072
	s_waitcnt lgkmcnt(2)
	v_mfma_f32_32x32x16_bf16 v[2:17], v[118:121], v[102:105], v[2:17]
	ds_read_b128 v[102:105], v66 offset:23040
	s_waitcnt lgkmcnt(0)
	v_mfma_f32_32x32x16_bf16 v[50:65], v[78:81], v[102:105], v[50:65]
	global_load_dwordx4 v[78:81], v72, s[26:27]
	global_load_dwordx4 v[130:133], v72, s[2:3]
	s_waitcnt vmcnt(9)
	ds_write_b128 v67, v[82:85] offset:36864
	s_waitcnt vmcnt(8)
	ds_write_b128 v67, v[134:137] offset:55296
	v_mfma_f32_32x32x16_bf16 v[18:33], v[118:121], v[102:105], v[18:33]
	global_load_dwordx4 v[82:85], v71, s[26:27]
	global_load_dwordx4 v[102:105], v71, s[2:3]
	v_mfma_f32_32x32x16_bf16 v[2:17], v[122:125], v[114:117], v[2:17]
	v_mfma_f32_32x32x16_bf16 v[18:33], v[122:125], v[126:129], v[18:33]
	v_mfma_f32_32x32x16_bf16 v[34:49], v[110:113], v[114:117], v[34:49]
	v_mfma_f32_32x32x16_bf16 v[50:65], v[110:113], v[126:129], v[50:65]
	ds_read_b128 v[110:113], v0 offset:64
	ds_read_b128 v[114:117], v0 offset:4672
	ds_read_b128 v[118:121], v66 offset:18496
	ds_read_b128 v[134:137], v66 offset:23104
	s_waitcnt vmcnt(9)
	ds_write_b128 v67, v[86:89] offset:41472
	s_waitcnt vmcnt(8)
	ds_write_b128 v67, v[106:109] offset:59904
	global_load_dwordx4 v[86:89], v70, s[26:27]
	global_load_dwordx4 v[106:109], v70, s[2:3]
	s_waitcnt lgkmcnt(3)
	v_mfma_f32_32x32x16_bf16 v[2:17], v[114:117], v[118:121], v[2:17]
	s_waitcnt lgkmcnt(2)
	v_mfma_f32_32x32x16_bf16 v[18:33], v[114:117], v[134:137], v[18:33]
	v_mfma_f32_32x32x16_bf16 v[34:49], v[110:113], v[118:121], v[34:49]
	v_mfma_f32_32x32x16_bf16 v[50:65], v[110:113], v[134:137], v[50:65]
	ds_read_b128 v[110:113], v0 offset:96
	ds_read_b128 v[118:121], v0 offset:4704
	ds_read_b128 v[122:125], v66 offset:18528
	ds_read_b128 v[126:129], v66 offset:23136
	s_waitcnt vmcnt(9)
	ds_write_b128 v67, v[90:93] offset:46080
	s_waitcnt vmcnt(8)
	ds_write_b128 v67, v[94:97] offset:64512
	global_load_dwordx4 v[90:93], v69, s[26:27]
	global_load_dwordx4 v[94:97], v69, s[2:3]
	s_waitcnt lgkmcnt(3)
	v_mfma_f32_32x32x16_bf16 v[2:17], v[118:121], v[122:125], v[2:17]
	s_waitcnt vmcnt(9)
	ds_write_b128 v67, v[74:77] offset:50688
	s_waitcnt vmcnt(8)
	ds_write_b128 v68, v[98:101] offset:13824
	s_waitcnt lgkmcnt(4)
	v_mfma_f32_32x32x16_bf16 v[18:33], v[118:121], v[126:129], v[18:33]
	v_mfma_f32_32x32x16_bf16 v[34:49], v[110:113], v[122:125], v[34:49]
	v_mfma_f32_32x32x16_bf16 v[50:65], v[110:113], v[126:129], v[50:65]
	s_waitcnt lgkmcnt(0)
	s_barrier
; #define GL1_(RA, RB, i) { RA[i] = *(const u32x4*)(ap + (aoff + (i) * astep)); if ((i) < NB) RB[(i) < NB ? (i) : 0] = *(const u32x4*)(bp + (boff + (i) * bstep)); }
; #define LS1_(RA, RB, ST, i) { char* sn_ = lds + (ST) * STAGE; *(u32x4*)(sn_ + wofs + (i) * 32 * LROW) = RA[i]; \
;                               if ((i) < NB) *(u32x4*)(sn_ + STAGE_OP + wofs + (i) * 32 * LROW) = RB[(i) < NB ? (i) : 0]; }
; template <int NJ> DI void gemm_mainloop_reg(const bf16_t* __restrict__ A, int lda, const bf16_t* __restrict__ Bt, int ldb, int K, f32x16 (&acc)[2][NJ], char* lds) {
;     ...
; #pragma unroll
;   for (int i = 0; i < 4; ++i) GL1_(ra0, rb0, i);
;   ap += 128; bp += 128;
; #pragma unroll
;   for (int i = 0; i < 4; ++i) GL1_(ra1, rb1, i);
;   ap += 128; bp += 128;
; #pragma unroll
;   for (int i = 0; i < 4; ++i) LS1_(ra0, rb0, 0, i);
;   __syncthreads();
;   const int nk = K >> 6;
;   for (int kt = 0; kt < nk; kt += 2) {
;     const bool l0 = (kt + 2 < nk), l1 = (kt + 3 < nk);
;     STEP_(0, l0, ra0, rb0, true, ra1, rb1);
;     __syncthreads();
;     STEP_(1, l1, ra1, rb1, l0, ra0, rb0);
;     __syncthreads();
;   }
	ds_read_b128 v[74:77], v0 offset:36864
	ds_read_b128 v[98:101], v66 offset:55296
	ds_read_b128 v[110:113], v0 offset:36896
	ds_read_b128 v[114:117], v66 offset:55328
	ds_read_b128 v[118:121], v0 offset:41472
	ds_read_b128 v[122:125], v0 offset:41504
	s_waitcnt lgkmcnt(4)
	v_mfma_f32_32x32x16_bf16 v[34:49], v[74:77], v[98:101], v[34:49]
	s_add_u32 s2, s36, 0x1480
	s_addc_u32 s3, s37, 0
	s_add_u32 s26, s0, 0x1480
	s_addc_u32 s27, s1, 0
	ds_read_b128 v[126:129], v66 offset:59936
	s_waitcnt lgkmcnt(2)
	v_mfma_f32_32x32x16_bf16 v[2:17], v[118:121], v[98:101], v[2:17]
	ds_read_b128 v[98:101], v66 offset:59904
	s_waitcnt lgkmcnt(0)
	v_mfma_f32_32x32x16_bf16 v[50:65], v[74:77], v[98:101], v[50:65]
	global_load_dwordx4 v[74:77], v72, s[26:27]
	global_load_dwordx4 v[134:137], v72, s[2:3]
	s_waitcnt vmcnt(9)
	ds_write_b128 v67, v[78:81]
	s_waitcnt vmcnt(8)
	ds_write_b128 v67, v[130:133] offset:18432
	v_mfma_f32_32x32x16_bf16 v[18:33], v[118:121], v[98:101], v[18:33]
	global_load_dwordx4 v[78:81], v71, s[26:27]
	global_load_dwordx4 v[98:101], v71, s[2:3]
	v_mfma_f32_32x32x16_bf16 v[2:17], v[122:125], v[114:117], v[2:17]
	v_mfma_f32_32x32x16_bf16 v[18:33], v[122:125], v[126:129], v[18:33]
	v_mfma_f32_32x32x16_bf16 v[34:49], v[110:113], v[114:117], v[34:49]
	v_mfma_f32_32x32x16_bf16 v[50:65], v[110:113], v[126:129], v[50:65]
	ds_read_b128 v[110:113], v0 offset:36928
	ds_read_b128 v[114:117], v0 offset:41536
	ds_read_b128 v[118:121], v66 offset:55360
	ds_read_b128 v[130:133], v66 offset:59968
	s_waitcnt vmcnt(9)
	ds_write_b128 v67, v[82:85] offset:4608
	s_waitcnt vmcnt(8)
	ds_write_b128 v67, v[102:105] offset:23040
	global_load_dwordx4 v[82:85], v70, s[26:27]
	global_load_dwordx4 v[102:105], v70, s[2:3]
	s_waitcnt lgkmcnt(3)
	v_mfma_f32_32x32x16_bf16 v[2:17], v[114:117], v[118:121], v[2:17]
	s_waitcnt lgkmcnt(2)
	v_mfma_f32_32x32x16_bf16 v[18:33], v[114:117], v[130:133], v[18:33]
	v_mfma_f32_32x32x16_bf16 v[34:49], v[110:113], v[118:121], v[34:49]
	v_mfma_f32_32x32x16_bf16 v[50:65], v[110:113], v[130:133], v[50:65]
	ds_read_b128 v[110:113], v0 offset:36960
	ds_read_b128 v[118:121], v0 offset:41568
	ds_read_b128 v[122:125], v66 offset:55392
	ds_read_b128 v[126:129], v66 offset:60000
	s_waitcnt vmcnt(9)
	ds_write_b128 v67, v[86:89] offset:9216
	s_waitcnt vmcnt(8)
	ds_write_b128 v67, v[106:109] offset:27648
	global_load_dwordx4 v[86:89], v69, s[26:27]
	global_load_dwordx4 v[106:109], v69, s[2:3]
	s_waitcnt lgkmcnt(3)
	v_mfma_f32_32x32x16_bf16 v[2:17], v[118:121], v[122:125], v[2:17]
	s_waitcnt vmcnt(9)
	ds_write_b128 v67, v[90:93] offset:13824
	s_waitcnt vmcnt(8)
	ds_write_b128 v67, v[94:97] offset:32256
	s_waitcnt lgkmcnt(4)
	v_mfma_f32_32x32x16_bf16 v[18:33], v[118:121], v[126:129], v[18:33]
	v_mfma_f32_32x32x16_bf16 v[34:49], v[110:113], v[122:125], v[34:49]
	v_mfma_f32_32x32x16_bf16 v[50:65], v[110:113], v[126:129], v[50:65]
	s_waitcnt lgkmcnt(0)
	s_barrier
	ds_read_b128 v[90:93], v0
	ds_read_b128 v[94:97], v66 offset:18432
	ds_read_b128 v[110:113], v0 offset:32
	ds_read_b128 v[114:117], v66 offset:18464
	ds_read_b128 v[118:121], v0 offset:4608
	ds_read_b128 v[122:125], v0 offset:4640
	s_waitcnt lgkmcnt(4)
	v_mfma_f32_32x32x16_bf16 v[34:49], v[90:93], v[94:97], v[34:49]
	s_add_u32 s2, s36, 0x1500
	s_addc_u32 s3, s37, 0
	s_add_u32 s26, s0, 0x1500
	s_addc_u32 s27, s1, 0
	ds_read_b128 v[126:129], v66 offset:23072
	s_waitcnt lgkmcnt(2)
	v_mfma_f32_32x32x16_bf16 v[2:17], v[118:121], v[94:97], v[2:17]
	ds_read_b128 v[94:97], v66 offset:23040
	s_waitcnt lgkmcnt(0)
	v_mfma_f32_32x32x16_bf16 v[50:65], v[90:93], v[94:97], v[50:65]
	global_load_dwordx4 v[90:93], v72, s[26:27]
	global_load_dwordx4 v[130:133], v72, s[2:3]
	s_waitcnt vmcnt(9)
	ds_write_b128 v67, v[74:77] offset:36864
	s_waitcnt vmcnt(8)
	ds_write_b128 v67, v[134:137] offset:55296
	v_mfma_f32_32x32x16_bf16 v[18:33], v[118:121], v[94:97], v[18:33]
	global_load_dwordx4 v[74:77], v71, s[26:27]
	global_load_dwordx4 v[94:97], v71, s[2:3]
	v_mfma_f32_32x32x16_bf16 v[2:17], v[122:125], v[114:117], v[2:17]
	v_mfma_f32_32x32x16_bf16 v[18:33], v[122:125], v[126:129], v[18:33]
	v_mfma_f32_32x32x16_bf16 v[34:49], v[110:113], v[114:117], v[34:49]
	v_mfma_f32_32x32x16_bf16 v[50:65], v[110:113], v[126:129], v[50:65]
	ds_read_b128 v[110:113], v0 offset:64
	ds_read_b128 v[114:117], v0 offset:4672
	ds_read_b128 v[118:121], v66 offset:18496
	ds_read_b128 v[134:137], v66 offset:23104
	s_waitcnt vmcnt(9)
	ds_write_b128 v67, v[78:81] offset:41472
	s_waitcnt vmcnt(8)
	ds_write_b128 v67, v[98:101] offset:59904
	global_load_dwordx4 v[78:81], v70, s[26:27]
	global_load_dwordx4 v[98:101], v70, s[2:3]
	s_waitcnt lgkmcnt(3)
	v_mfma_f32_32x32x16_bf16 v[2:17], v[114:117], v[118:121], v[2:17]
	s_waitcnt lgkmcnt(2)
	v_mfma_f32_32x32x16_bf16 v[18:33], v[114:117], v[134:137], v[18:33]
	v_mfma_f32_32x32x16_bf16 v[34:49], v[110:113], v[118:121], v[34:49]
	v_mfma_f32_32x32x16_bf16 v[50:65], v[110:113], v[134:137], v[50:65]
	ds_read_b128 v[110:113], v0 offset:96
	ds_read_b128 v[118:121], v0 offset:4704
	ds_read_b128 v[122:125], v66 offset:18528
	ds_read_b128 v[126:129], v66 offset:23136
	s_waitcnt vmcnt(9)
	ds_write_b128 v67, v[82:85] offset:46080
	s_waitcnt vmcnt(8)
	ds_write_b128 v67, v[102:105] offset:64512
	global_load_dwordx4 v[82:85], v69, s[26:27]
	global_load_dwordx4 v[102:105], v69, s[2:3]
	s_waitcnt lgkmcnt(3)
	v_mfma_f32_32x32x16_bf16 v[2:17], v[118:121], v[122:125], v[2:17]
	s_waitcnt vmcnt(9)
	ds_write_b128 v67, v[86:89] offset:50688
	s_waitcnt vmcnt(8)
	ds_write_b128 v68, v[106:109] offset:13824
	s_waitcnt lgkmcnt(4)
	v_mfma_f32_32x32x16_bf16 v[18:33], v[118:121], v[126:129], v[18:33]
	v_mfma_f32_32x32x16_bf16 v[34:49], v[110:113], v[122:125], v[34:49]
	v_mfma_f32_32x32x16_bf16 v[50:65], v[110:113], v[126:129], v[50:65]
	s_waitcnt lgkmcnt(0)
	s_barrier
; #define GL1_(RA, RB, i) { RA[i] = *(const u32x4*)(ap + (aoff + (i) * astep)); if ((i) < NB) RB[(i) < NB ? (i) : 0] = *(const u32x4*)(bp + (boff + (i) * bstep)); }
; #define LS1_(RA, RB, ST, i) { char* sn_ = lds + (ST) * STAGE; *(u32x4*)(sn_ + wofs + (i) * 32 * LROW) = RA[i]; \
;                               if ((i) < NB) *(u32x4*)(sn_ + STAGE_OP + wofs + (i) * 32 * LROW) = RB[(i) < NB ? (i) : 0]; }
; template <int NJ> DI void gemm_mainloop_reg(const bf16_t* __restrict__ A, int lda, const bf16_t* __restrict__ Bt, int ldb, int K, f32x16 (&acc)[2][NJ], char* lds) {
;     ...
; #pragma unroll
;   for (int i = 0; i < 4; ++i) GL1_(ra0, rb0, i);
;   ap += 128; bp += 128;
; #pragma unroll
;   for (int i = 0; i < 4; ++i) GL1_(ra1, rb1, i);
;   ap += 128; bp += 128;
; #pragma unroll
;   for (int i = 0; i < 4; ++i) LS1_(ra0, rb0, 0, i);
;   __syncthreads();
;   const int nk = K >> 6;
;   for (int kt = 0; kt < nk; kt += 2) {
;     const bool l0 = (kt + 2 < nk), l1 = (kt + 3 < nk);
;     STEP_(0, l0, ra0, rb0, true, ra1, rb1);
;     __syncthreads();
;     STEP_(1, l1, ra1, rb1, l0, ra0, rb0);
;     __syncthreads();
;   }
	ds_read_b128 v[86:89], v0 offset:36864
	ds_read_b128 v[106:109], v66 offset:55296
	ds_read_b128 v[110:113], v0 offset:41472
	s_waitcnt lgkmcnt(1)
	v_mfma_f32_32x32x16_bf16 v[34:49], v[86:89], v[106:109], v[34:49]
	s_add_u32 s2, s36, 0x1580
	s_addc_u32 s3, s37, 0
	s_add_u32 s0, s0, 0x1580
	s_addc_u32 s1, s1, 0
	s_waitcnt lgkmcnt(0)
	v_mfma_f32_32x32x16_bf16 v[2:17], v[110:113], v[106:109], v[2:17]
	ds_read_b128 v[106:109], v66 offset:59904
	s_waitcnt lgkmcnt(0)
	v_mfma_f32_32x32x16_bf16 v[50:65], v[86:89], v[106:109], v[50:65]
	global_load_dwordx4 v[86:89], v72, s[0:1]
	global_load_dwordx4 v[114:117], v72, s[2:3]
	ds_read_b128 v[118:121], v0 offset:36896
	ds_read_b128 v[122:125], v66 offset:55328
	ds_read_b128 v[126:129], v0 offset:41504
	ds_read_b128 v[134:137], v66 offset:59936
	s_waitcnt vmcnt(9)
	ds_write_b128 v67, v[90:93]
	s_waitcnt vmcnt(8)
	ds_write_b128 v67, v[130:133] offset:18432
	v_mfma_f32_32x32x16_bf16 v[18:33], v[110:113], v[106:109], v[18:33]
	global_load_dwordx4 v[90:93], v71, s[0:1]
	global_load_dwordx4 v[106:109], v71, s[2:3]
	s_waitcnt lgkmcnt(3)
	v_mfma_f32_32x32x16_bf16 v[2:17], v[126:129], v[122:125], v[2:17]
	s_waitcnt lgkmcnt(2)
	v_mfma_f32_32x32x16_bf16 v[18:33], v[126:129], v[134:137], v[18:33]
	v_mfma_f32_32x32x16_bf16 v[34:49], v[118:121], v[122:125], v[34:49]
	v_mfma_f32_32x32x16_bf16 v[50:65], v[118:121], v[134:137], v[50:65]
	ds_read_b128 v[110:113], v0 offset:36928
	ds_read_b128 v[118:121], v0 offset:41536
	ds_read_b128 v[122:125], v66 offset:55360
	ds_read_b128 v[130:133], v66 offset:59968
	s_waitcnt vmcnt(9)
	ds_write_b128 v67, v[74:77] offset:4608
	s_waitcnt vmcnt(8)
	ds_write_b128 v67, v[94:97] offset:23040
	global_load_dwordx4 v[72:75], v70, s[0:1]
	global_load_dwordx4 v[94:97], v70, s[2:3]
	s_waitcnt lgkmcnt(3)
	v_mfma_f32_32x32x16_bf16 v[2:17], v[118:121], v[122:125], v[2:17]
	s_waitcnt lgkmcnt(2)
	v_mfma_f32_32x32x16_bf16 v[18:33], v[118:121], v[130:133], v[18:33]
	v_mfma_f32_32x32x16_bf16 v[34:49], v[110:113], v[122:125], v[34:49]
	v_mfma_f32_32x32x16_bf16 v[50:65], v[110:113], v[130:133], v[50:65]
	ds_read_b128 v[110:113], v0 offset:36960
	ds_read_b128 v[122:125], v0 offset:41568
	ds_read_b128 v[126:129], v66 offset:55392
	ds_read_b128 v[134:137], v66 offset:60000
	s_waitcnt vmcnt(9)
	ds_write_b128 v67, v[78:81] offset:9216
	s_waitcnt vmcnt(8)
	ds_write_b128 v67, v[98:101] offset:27648
	global_load_dwordx4 v[76:79], v69, s[0:1]
	global_load_dwordx4 v[98:101], v69, s[2:3]
	s_waitcnt lgkmcnt(3)
	v_mfma_f32_32x32x16_bf16 v[2:17], v[122:125], v[126:129], v[2:17]
	s_waitcnt vmcnt(9)
	ds_write_b128 v67, v[82:85] offset:13824
	s_waitcnt vmcnt(8)
	ds_write_b128 v67, v[102:105] offset:32256
	s_waitcnt lgkmcnt(4)
	v_mfma_f32_32x32x16_bf16 v[18:33], v[122:125], v[134:137], v[18:33]
	v_mfma_f32_32x32x16_bf16 v[34:49], v[110:113], v[126:129], v[34:49]
	v_mfma_f32_32x32x16_bf16 v[50:65], v[110:113], v[134:137], v[50:65]
	s_waitcnt lgkmcnt(0)
	s_barrier
	ds_read_b128 v[80:83], v0
	ds_read_b128 v[102:105], v66 offset:18432
	ds_read_b128 v[110:113], v0 offset:4608
	s_waitcnt lgkmcnt(1)
	v_mfma_f32_32x32x16_bf16 v[34:49], v[80:83], v[102:105], v[34:49]
	s_waitcnt lgkmcnt(0)
	v_mfma_f32_32x32x16_bf16 v[2:17], v[110:113], v[102:105], v[2:17]
	ds_read_b128 v[102:105], v66 offset:23040
	s_waitcnt lgkmcnt(0)
	v_mfma_f32_32x32x16_bf16 v[18:33], v[110:113], v[102:105], v[18:33]
	v_mfma_f32_32x32x16_bf16 v[50:65], v[80:83], v[102:105], v[50:65]
	ds_read_b128 v[80:83], v0 offset:32
	ds_read_b128 v[118:121], v66 offset:18464
	ds_read_b128 v[122:125], v0 offset:4640
	ds_read_b128 v[126:129], v66 offset:23072
	s_waitcnt vmcnt(7)
	ds_write_b128 v67, v[86:89] offset:36864
	s_waitcnt vmcnt(6)
	ds_write_b128 v67, v[114:117] offset:55296
	s_waitcnt lgkmcnt(3)
	v_mfma_f32_32x32x16_bf16 v[2:17], v[122:125], v[118:121], v[2:17]
	s_waitcnt lgkmcnt(2)
	v_mfma_f32_32x32x16_bf16 v[18:33], v[122:125], v[126:129], v[18:33]
	v_mfma_f32_32x32x16_bf16 v[34:49], v[80:83], v[118:121], v[34:49]
	v_mfma_f32_32x32x16_bf16 v[50:65], v[80:83], v[126:129], v[50:65]
	ds_read_b128 v[80:83], v0 offset:64
	ds_read_b128 v[84:87], v0 offset:4672
	ds_read_b128 v[102:105], v66 offset:18496
	ds_read_b128 v[110:113], v66 offset:23104
	s_waitcnt vmcnt(5)
	ds_write_b128 v67, v[90:93] offset:41472
	s_waitcnt vmcnt(4)
	ds_write_b128 v67, v[106:109] offset:59904
	s_waitcnt lgkmcnt(3)
	v_mfma_f32_32x32x16_bf16 v[2:17], v[84:87], v[102:105], v[2:17]
	s_waitcnt lgkmcnt(2)
	v_mfma_f32_32x32x16_bf16 v[18:33], v[84:87], v[110:113], v[18:33]
	v_mfma_f32_32x32x16_bf16 v[34:49], v[80:83], v[102:105], v[34:49]
	v_mfma_f32_32x32x16_bf16 v[50:65], v[80:83], v[110:113], v[50:65]
	ds_read_b128 v[80:83], v0 offset:96
	ds_read_b128 v[88:91], v0 offset:4704
	ds_read_b128 v[102:105], v66 offset:18528
	ds_read_b128 v[106:109], v66 offset:23136
	s_waitcnt vmcnt(3)
	ds_write_b128 v67, v[72:75] offset:46080
	s_waitcnt vmcnt(2)
	ds_write_b128 v67, v[94:97] offset:64512
	s_waitcnt lgkmcnt(3)
	v_mfma_f32_32x32x16_bf16 v[2:17], v[88:91], v[102:105], v[2:17]
	s_waitcnt vmcnt(1)
	ds_write_b128 v67, v[76:79] offset:50688
	s_waitcnt vmcnt(0)
	ds_write_b128 v68, v[98:101] offset:13824
	s_waitcnt lgkmcnt(4)
	v_mfma_f32_32x32x16_bf16 v[18:33], v[88:91], v[106:109], v[18:33]
	v_mfma_f32_32x32x16_bf16 v[34:49], v[80:83], v[102:105], v[34:49]
	v_mfma_f32_32x32x16_bf16 v[50:65], v[80:83], v[106:109], v[50:65]
	s_waitcnt lgkmcnt(0)
	s_barrier
; DI int tid_() { int t = threadIdx.x; asm volatile("" : "+v"(t)); return t; }
; DI unsigned pk2(float a, float b) { f32x2 v = {a, b}; bf16x2_t r = __builtin_convertvector(v, bf16x2_t); return __builtin_bit_cast(unsigned, r); }
; template <int NJ> DI void acc_to_lds(const f32x16 (&acc)[2][NJ], float* cl) {
;   const int tid = tid_(), lane = tid & 63, w = tid >> 6, wm = w >> 1, wn = w & 1, h = lane >> 5, c = lane & 31;
; #pragma unroll
;   for (int i = 0; i < 2; ++i)
; #pragma unroll
;     for (int j = 0; j < NJ; ++j)
; #pragma unroll
;       for (int r = 0; r < 16; ++r) {
;         const int row = wm * 64 + i * 32 + (r & 3) + 8 * (r >> 2) + 4 * h;
;         cl[row * CLD + wn * 32 * NJ + j * 32 + c] = acc[i][j][r];
;       }
; }
; template <int NJ> DI void resid_epilogue(float* __restrict__ x, bf16_t* __restrict__ xb, float* __restrict__ ssn, int mt, int nt, const float* cl, float scale) {
;   constexpr int LPR = 16 * NJ, RPP = 256 / LPR, NP = 128 / RPP;
;   const int tid = tid_(), c4 = (tid & (LPR - 1)) * 4, r0 = tid / LPR;
; #pragma unroll 4
;   for (int it = 0; it < NP; ++it) {
;     const int row = r0 + RPP * it;
;     const f32x4 c = *(const f32x4*)(cl + row * CLD + c4);
;     const size_t gi = (size_t)(mt * 128 + row) * DM + nt * (64 * NJ) + c4;
;     f32x4 xv = *(const f32x4*)(x + gi);
;     xv = xv + scale * c;
;     *(f32x4*)(x + gi) = xv;
;     u32x2 p; p.x = pk2(xv[0], xv[1]); p.y = pk2(xv[2], xv[3]);
;     *(u32x2*)(xb + (size_t)(mt * 128 + row) * LDX + nt * (64 * NJ) + c4) = p;
;     float s_ = xv[0] * xv[0] + xv[1] * xv[1] + xv[2] * xv[2] + xv[3] * xv[3];
;     if (NJ == 2) s_ += __shfl_xor(s_, 16);
;     s_ += __shfl_xor(s_, 8); s_ += __shfl_xor(s_, 4); s_ += __shfl_xor(s_, 2); s_ += __shfl_xor(s_, 1);
;     if ((tid & (LPR - 1)) == 0) atomicAdd(ssn + mt * 128 + row, s_);
;   }
; }
	ds_read_b128 v[68:71], v0 offset:36864
	ds_read_b128 v[72:75], v66 offset:55296
	ds_read_b128 v[76:79], v0 offset:41472
	s_waitcnt lgkmcnt(1)
	v_mfma_f32_32x32x16_bf16 v[34:49], v[68:71], v[72:75], v[34:49]
	s_waitcnt lgkmcnt(0)
	v_mfma_f32_32x32x16_bf16 v[2:17], v[76:79], v[72:75], v[2:17]
	ds_read_b128 v[72:75], v66 offset:59904
	s_waitcnt lgkmcnt(0)
	v_mfma_f32_32x32x16_bf16 v[18:33], v[76:79], v[72:75], v[18:33]
	v_mfma_f32_32x32x16_bf16 v[50:65], v[68:71], v[72:75], v[50:65]
	ds_read_b128 v[68:71], v0 offset:36896
	ds_read_b128 v[80:83], v66 offset:55328
	ds_read_b128 v[84:87], v0 offset:41504
	ds_read_b128 v[88:91], v66 offset:59936
	s_waitcnt lgkmcnt(1)
	v_mfma_f32_32x32x16_bf16 v[2:17], v[84:87], v[80:83], v[2:17]
	s_waitcnt lgkmcnt(0)
	v_mfma_f32_32x32x16_bf16 v[18:33], v[84:87], v[88:91], v[18:33]
	v_mfma_f32_32x32x16_bf16 v[34:49], v[68:71], v[80:83], v[34:49]
	v_mfma_f32_32x32x16_bf16 v[50:65], v[68:71], v[88:91], v[50:65]
	ds_read_b128 v[68:71], v0 offset:36928
	ds_read_b128 v[72:75], v0 offset:41536
	ds_read_b128 v[76:79], v66 offset:55360
	ds_read_b128 v[80:83], v66 offset:59968
	s_waitcnt lgkmcnt(1)
	v_mfma_f32_32x32x16_bf16 v[2:17], v[72:75], v[76:79], v[2:17]
	s_waitcnt lgkmcnt(0)
	v_mfma_f32_32x32x16_bf16 v[18:33], v[72:75], v[80:83], v[18:33]
	v_mfma_f32_32x32x16_bf16 v[34:49], v[68:71], v[76:79], v[34:49]
	v_mfma_f32_32x32x16_bf16 v[50:65], v[68:71], v[80:83], v[50:65]
	ds_read_b128 v[68:71], v0 offset:36960
	ds_read_b128 v[76:79], v0 offset:41568
	ds_read_b128 v[84:87], v66 offset:55392
	ds_read_b128 v[88:91], v66 offset:60000
	s_waitcnt lgkmcnt(1)
	v_mfma_f32_32x32x16_bf16 v[2:17], v[76:79], v[84:87], v[2:17]
	s_waitcnt lgkmcnt(0)
	v_mfma_f32_32x32x16_bf16 v[18:33], v[76:79], v[88:91], v[18:33]
	v_mfma_f32_32x32x16_bf16 v[34:49], v[68:71], v[84:87], v[34:49]
	v_mfma_f32_32x32x16_bf16 v[50:65], v[68:71], v[88:91], v[50:65]
	s_setprio 0
	s_nop 0
	v_mov_b32_e32 v0, v199
	s_barrier
	s_add_i32 s0, s39, s11
	v_lshrrev_b32_e32 v67, 3, v0
	v_lshrrev_b32_e32 v66, 1, v0
	v_and_b32_e32 v67, 4, v67
	v_and_b32_e32 v0, 0x5f, v0
	v_and_or_b32 v66, v66, s17, v67
	v_mul_lo_u32 v66, v66, s15
	v_lshlrev_b32_e32 v0, 2, v0
	v_add3_u32 v0, 0, v66, v0
	s_nop 0
	ds_write2_b32 v0, v34, v50 offset1:32
	ds_write2_b32 v0, v35, v51 offset0:132 offset1:164
	v_add_u32_e32 v34, 0x400, v0
	ds_write2_b32 v34, v36, v52 offset0:8 offset1:40
	ds_write2_b32 v34, v37, v53 offset0:140 offset1:172
	v_add_u32_e32 v34, 0x1000, v0
	ds_write2_b32 v34, v38, v54 offset0:32 offset1:64
	ds_write2_b32 v34, v39, v55 offset0:164 offset1:196
	v_add_u32_e32 v34, 0x1400, v0
	ds_write2_b32 v34, v40, v56 offset0:40 offset1:72
	ds_write2_b32 v34, v41, v57 offset0:172 offset1:204
	v_add_u32_e32 v34, 0x2000, v0
	ds_write2_b32 v34, v42, v58 offset0:64 offset1:96
	ds_write2_b32 v34, v43, v59 offset0:196 offset1:228
	v_add_u32_e32 v34, 0x2400, v0
	ds_write2_b32 v34, v44, v60 offset0:72 offset1:104
	ds_write2_b32 v34, v45, v61 offset0:204 offset1:236
	v_add_u32_e32 v34, 0x3000, v0
	ds_write2_b32 v34, v46, v62 offset0:96 offset1:128
	v_add_u32_e32 v34, 0x3200, v0
	ds_write2_b32 v34, v47, v63 offset0:100 offset1:132
	v_add_u32_e32 v34, 0x3400, v0
	ds_write2_b32 v34, v48, v64 offset0:104 offset1:136
	v_add_u32_e32 v34, 0x3600, v0
	ds_write2_b32 v34, v49, v65 offset0:108 offset1:140
	v_add_u32_e32 v34, 0x4000, v0
	ds_write2_b32 v34, v2, v18 offset0:128 offset1:160
	v_add_u32_e32 v2, 0x4400, v0
	ds_write2_b32 v2, v3, v19 offset0:4 offset1:36
	ds_write2_b32 v2, v4, v20 offset0:136 offset1:168
	v_add_u32_e32 v2, 0x4800, v0
	ds_write2_b32 v2, v5, v21 offset0:12 offset1:44
	v_add_u32_e32 v2, 0x5000, v0
	ds_write2_b32 v2, v6, v22 offset0:160 offset1:192
	v_add_u32_e32 v2, 0x5400, v0
	ds_write2_b32 v2, v7, v23 offset0:36 offset1:68
	ds_write2_b32 v2, v8, v24 offset0:168 offset1:200
	v_add_u32_e32 v2, 0x5800, v0
	ds_write2_b32 v2, v9, v25 offset0:44 offset1:76
	v_add_u32_e32 v2, 0x6000, v0
	ds_write2_b32 v2, v10, v26 offset0:192 offset1:224
	v_add_u32_e32 v2, 0x6400, v0
	ds_write2_b32 v2, v11, v27 offset0:68 offset1:100
	ds_write2_b32 v2, v12, v28 offset0:200 offset1:232
	v_add_u32_e32 v2, 0x6800, v0
	ds_write2_b32 v2, v13, v29 offset0:76 offset1:108
	v_add_u32_e32 v2, 0x7200, v0
	ds_write2_b32 v2, v14, v30 offset0:96 offset1:128
	v_add_u32_e32 v2, 0x7400, v0
	ds_write2_b32 v2, v15, v31 offset0:100 offset1:132
	v_add_u32_e32 v2, 0x7600, v0
	v_add_u32_e32 v0, 0x7800, v0
	ds_write2_b32 v0, v17, v33 offset0:108 offset1:140
	v_mov_b32_e32 v0, v199
	ds_write2_b32 v2, v16, v32 offset0:104 offset1:136
	s_waitcnt lgkmcnt(0)
	s_barrier
	v_mov_b64_e32 v[18:19], s[72:73]
	v_ashrrev_i32_e32 v2, 31, v0
	v_lshrrev_b32_e32 v2, 27, v2
	v_and_b32_e32 v6, 31, v0
	v_add_u32_e32 v0, v0, v2
	v_ashrrev_i32_e32 v14, 5, v0
	v_add_u32_e32 v4, s0, v14
	v_mad_i64_i32 v[2:3], s[0:1], v4, s9, v[18:19]
	v_cmp_lt_i32_e32 vcc, v222, v220
	s_add_i32 s0, s39, s12
	v_add_u32_e32 v10, s0, v14
	v_cndmask_b32_e32 v0, v219, v222, vcc
	v_cmp_lt_i32_e32 vcc, v223, v220
	v_lshlrev_b32_e32 v22, 2, v0
	v_mad_i64_i32 v[8:9], s[0:1], v10, s9, v[18:19]
	v_cndmask_b32_e32 v0, v219, v223, vcc
	v_cmp_lt_i32_e32 vcc, v224, v220
	v_lshlrev_b32_e32 v23, 2, v0
	s_add_u32 s0, s40, s6
	v_cndmask_b32_e32 v0, v219, v224, vcc
	v_cmp_lt_i32_e32 vcc, v225, v220
	v_lshlrev_b32_e32 v24, 2, v0
	s_addc_u32 s1, 0, s7
	v_cndmask_b32_e32 v0, v219, v225, vcc
	v_cmp_lt_i32_e32 vcc, v226, v220
	s_add_i32 s39, s39, s13
	v_lshlrev_b32_e32 v25, 2, v0
	v_cndmask_b32_e32 v0, v219, v226, vcc
	v_add_u32_e32 v20, s41, v14
	v_add_u32_e32 v16, s39, v14
	v_lshlrev_b32_e32 v26, 2, v0
	v_cmp_eq_u32_e32 vcc, 0, v6
	v_ashrrev_i32_e32 v15, 31, v14
	v_ashrrev_i32_e32 v5, 31, v4
	v_lshlrev_b32_e32 v0, 3, v6
	v_lshlrev_b32_e32 v28, 4, v6
	v_mul_lo_u32 v6, v14, s15
	v_ashrrev_i32_e32 v21, 31, v20
	v_ashrrev_i32_e32 v11, 31, v10
	v_ashrrev_i32_e32 v17, 31, v16
	v_lshlrev_b64 v[4:5], 12, v[4:5]
	v_add3_u32 v27, v6, v28, 0
	v_lshlrev_b64 v[6:7], 12, v[20:21]
	v_lshlrev_b64 v[10:11], 12, v[10:11]
	v_lshl_add_u64 v[12:13], v[14:15], 2, s[0:1]
	v_mad_i64_i32 v[14:15], s[0:1], v16, s9, v[18:19]
	v_lshlrev_b64 v[16:17], 12, v[16:17]
	v_mad_i64_i32 v[18:19], s[0:1], v20, s9, v[18:19]
	v_lshl_add_u64 v[2:3], v[2:3], 0, v[0:1]
	v_or3_b32 v4, v4, s38, v28
	v_or3_b32 v6, v6, s38, v28
	v_lshl_add_u64 v[8:9], v[8:9], 0, v[0:1]
	v_or3_b32 v10, v10, s38, v28
	v_lshl_add_u64 v[14:15], v[14:15], 0, v[0:1]
	v_or3_b32 v16, v16, s38, v28
	v_lshl_add_u64 v[18:19], v[18:19], 0, v[0:1]
	v_lshl_add_u64 v[2:3], v[2:3], 0, s[80:81]
	v_lshl_add_u64 v[4:5], s[92:93], 0, v[4:5]
	v_lshl_add_u64 v[6:7], s[92:93], 0, v[6:7]
	v_lshl_add_u64 v[8:9], v[8:9], 0, s[80:81]
	v_lshl_add_u64 v[10:11], s[92:93], 0, v[10:11]
	v_lshl_add_u64 v[14:15], v[14:15], 0, s[80:81]
	v_lshl_add_u64 v[16:17], s[92:93], 0, v[16:17]
	v_lshl_add_u64 v[18:19], v[18:19], 0, s[80:81]
	s_mov_b64 s[0:1], 0
	s_branch .LBB0_429

; #define GL1_(RA, RB, i) { RA[i] = *(const u32x4*)(ap + (aoff + (i) * astep)); if ((i) < NB) RB[(i) < NB ? (i) : 0] = *(const u32x4*)(bp + (boff + (i) * bstep)); }
; #define LS1_(RA, RB, ST, i) { char* sn_ = lds + (ST) * STAGE; *(u32x4*)(sn_ + wofs + (i) * 32 * LROW) = RA[i]; \
;                               if ((i) < NB) *(u32x4*)(sn_ + STAGE_OP + wofs + (i) * 32 * LROW) = RB[(i) < NB ? (i) : 0]; }
; template <int NJ> DI void gemm_mainloop_reg(const bf16_t* __restrict__ A, int lda, const bf16_t* __restrict__ Bt, int ldb, int K, f32x16 (&acc)[2][NJ], char* lds) {
;     ...
; #pragma unroll
;   for (int i = 0; i < 4; ++i) GL1_(ra0, rb0, i);
;   ap += 128; bp += 128;
; #pragma unroll
;   for (int i = 0; i < 4; ++i) GL1_(ra1, rb1, i);
;   ap += 128; bp += 128;
; #pragma unroll
;   for (int i = 0; i < 4; ++i) LS1_(ra0, rb0, 0, i);
;   __syncthreads();
;   const int nk = K >> 6;
;   for (int kt = 0; kt < nk; kt += 2) {
;     const bool l0 = (kt + 2 < nk), l1 = (kt + 3 < nk);
;     STEP_(0, l0, ra0, rb0, true, ra1, rb1);
;     __syncthreads();
;     STEP_(1, l1, ra1, rb1, l0, ra0, rb0);
;     __syncthreads();
;   }
; DI void phase_proj(const Ctx& c, bool dummy_ss = false) {
;     ...
;     const int j_ = grab_next(ctr, c.lds);
;     if (j_ >= 128 * 4) break;
;     const int mt = xcd_ * 16 + (j_ & 7) + 8 * ((j_ >> 6) & 1), nt = (j_ >> 7) * 8 + ((j_ >> 3) & 7);
;     if (nt >= 28) continue;
;     f32x16 acc[2][2]; zero_acc<2>(acc);
;     gemm_mainloop_reg<2>(A + (size_t)mt * 128 * LDX, LDX, Bt + (size_t)nt * 128 * LDX, LDX, DM, acc, c.lds);
.LBB0_497:
	s_or_b64 exec, exec, s[2:3]
	s_cmp_lg_u32 s24, -1
	s_cselect_b32 s2, s24, 0
	s_cselect_b32 s3, s79, 0
	v_mov_b32_e32 v2, s2
	v_mov_b32_e32 v3, s3
	s_waitcnt lgkmcnt(0)
	s_barrier
	flat_load_dword v0, v[2:3] sc0 sc1
	s_waitcnt vmcnt(0)
	s_mov_b64 s[2:3], -1
	s_waitcnt lgkmcnt(0)
	s_barrier
	v_readfirstlane_b32 s4, v0
	s_cmpk_gt_i32 s4, 0x1ff
	s_cbranch_scc1 .LBB0_492
	s_ashr_i32 s2, s4, 4
	s_and_b32 s2, s2, -8
	s_bfe_u32 s3, s4, 0x30003
	s_or_b32 s6, s2, s3
	s_cmp_gt_i32 s6, 27
	s_cbranch_scc1 .LBB0_491
	s_lshr_b32 s2, s4, 3
	s_and_b32 s3, s4, 7
	s_and_b32 s2, s2, 8
	s_or_b32 s2, s3, s2
	v_readlane_b32 s3, v250, 20
	s_or_b32 s7, s2, s3
	v_mov_b32_e32 v34, v199
	s_mul_i32 s2, s7, 0x44000
	v_readlane_b32 s3, v252, 10
	s_add_u32 s2, s3, s2
	v_ashrrev_i32_e32 v0, 3, v34
	v_lshlrev_b32_e32 v2, 4, v34
	v_readlane_b32 s3, v252, 11
	v_and_b32_e32 v35, 0x70, v2
	v_mul_lo_u32 v2, v0, s9
	s_addc_u32 s3, s3, 0
	s_mul_i32 s4, s6, 0x44000
	v_or_b32_e32 v72, v35, v2
	s_mul_hi_i32 s5, s6, 0x44000
	s_add_u32 s4, s37, s4
	v_add_u32_e32 v71, 0x11000, v72
	v_add_u32_e32 v70, 0x22000, v72
	v_add_u32_e32 v69, 0x33000, v72
	s_addc_u32 s5, s25, s5
	global_load_dwordx4 v[2:5], v72, s[2:3]
	global_load_dwordx4 v[6:9], v71, s[2:3]
	global_load_dwordx4 v[10:13], v70, s[2:3]
	global_load_dwordx4 v[14:17], v69, s[2:3]
	global_load_dwordx4 v[18:21], v72, s[4:5]
	global_load_dwordx4 v[22:25], v71, s[4:5]
	global_load_dwordx4 v[26:29], v70, s[4:5]
	global_load_dwordx4 v[30:33], v69, s[4:5]
	v_mul_lo_u32 v0, v0, s16
	v_lshrrev_b32_e32 v36, 1, v34
	v_and_b32_e32 v37, 31, v34
	v_add3_u32 v67, v0, v35, 0
	v_and_b32_e32 v38, 16, v36
	v_and_or_b32 v36, v36, s17, v37
	global_load_dwordx4 v[74:77], v72, s[2:3] offset:128
	global_load_dwordx4 v[78:81], v71, s[2:3] offset:128
	global_load_dwordx4 v[82:85], v70, s[2:3] offset:128
	global_load_dwordx4 v[86:89], v69, s[2:3] offset:128
	global_load_dwordx4 v[90:93], v72, s[4:5] offset:128
	global_load_dwordx4 v[94:97], v71, s[4:5] offset:128
	global_load_dwordx4 v[98:101], v70, s[4:5] offset:128
	global_load_dwordx4 v[102:105], v69, s[4:5] offset:128
	v_mul_lo_u32 v0, v36, s16
	v_add3_u32 v0, v0, v38, 0
	v_add_u32_e32 v68, 0xd800, v67
	s_waitcnt vmcnt(15)
	ds_write_b128 v67, v[2:5]
	s_waitcnt vmcnt(14)
	ds_write_b128 v67, v[6:9] offset:4608
	s_waitcnt vmcnt(13)
	ds_write_b128 v67, v[10:13] offset:9216
	s_waitcnt vmcnt(12)
	ds_write_b128 v67, v[14:17] offset:13824
	s_waitcnt vmcnt(11)
	ds_write_b128 v67, v[18:21] offset:18432
	s_waitcnt vmcnt(10)
	ds_write_b128 v67, v[22:25] offset:23040
	s_waitcnt vmcnt(9)
	ds_write_b128 v67, v[26:29] offset:27648
	s_waitcnt vmcnt(8)
	ds_write_b128 v67, v[30:33] offset:32256
	v_and_b32_e32 v2, 0x5f, v34
	v_mul_u32_u24_e32 v2, 0x90, v2
	v_add3_u32 v66, v2, v38, 0
	s_waitcnt lgkmcnt(0)
	s_barrier
	ds_read_b128 v[18:21], v0
	ds_read_b128 v[2:5], v66 offset:18432
	ds_read_b128 v[106:109], v0 offset:32
	ds_read_b128 v[110:113], v66 offset:18464
	ds_read_b128 v[22:25], v0 offset:4608
	ds_read_b128 v[114:117], v0 offset:4640
	ds_read_b128 v[26:29], v66 offset:23040
	ds_read_b128 v[118:121], v66 offset:23072
	global_load_dwordx4 v[122:125], v72, s[2:3] offset:256
	global_load_dwordx4 v[126:129], v72, s[4:5] offset:256
	s_waitcnt lgkmcnt(6)
	s_setprio 1
	s_nop 0
	v_mfma_f32_32x32x16_bf16 v[34:49], v[18:21], v[2:5], 0
	s_waitcnt vmcnt(9)
	ds_write_b128 v67, v[74:77] offset:36864
	s_waitcnt vmcnt(5)
	ds_write_b128 v67, v[90:93] offset:55296
	s_waitcnt lgkmcnt(5)
	v_mfma_f32_32x32x16_bf16 v[2:17], v[22:25], v[2:5], 0
	s_waitcnt lgkmcnt(3)
	v_mfma_f32_32x32x16_bf16 v[50:65], v[18:21], v[26:29], 0
	v_mfma_f32_32x32x16_bf16 v[18:33], v[22:25], v[26:29], 0
	global_load_dwordx4 v[74:77], v71, s[2:3] offset:256
	global_load_dwordx4 v[90:93], v71, s[4:5] offset:256
	v_mfma_f32_32x32x16_bf16 v[34:49], v[106:109], v[110:113], v[34:49]
	v_mfma_f32_32x32x16_bf16 v[2:17], v[114:117], v[110:113], v[2:17]
	s_waitcnt lgkmcnt(2)
	v_mfma_f32_32x32x16_bf16 v[50:65], v[106:109], v[118:121], v[50:65]
	ds_read_b128 v[106:109], v0 offset:64
	ds_read_b128 v[110:113], v0 offset:4672
	ds_read_b128 v[130:133], v66 offset:18496
	ds_read_b128 v[134:137], v66 offset:23104
	ds_write_b128 v67, v[78:81] offset:41472
	s_waitcnt vmcnt(6)
	ds_write_b128 v67, v[94:97] offset:59904
	v_mfma_f32_32x32x16_bf16 v[18:33], v[114:117], v[118:121], v[18:33]
	global_load_dwordx4 v[78:81], v70, s[2:3] offset:256
	global_load_dwordx4 v[94:97], v70, s[4:5] offset:256
	s_waitcnt lgkmcnt(3)
	v_mfma_f32_32x32x16_bf16 v[34:49], v[106:109], v[130:133], v[34:49]
	v_mfma_f32_32x32x16_bf16 v[2:17], v[110:113], v[130:133], v[2:17]
	s_waitcnt lgkmcnt(2)
	v_mfma_f32_32x32x16_bf16 v[50:65], v[106:109], v[134:137], v[50:65]
	ds_read_b128 v[106:109], v0 offset:96
	ds_read_b128 v[114:117], v0 offset:4704
	ds_read_b128 v[118:121], v66 offset:18528
	ds_read_b128 v[130:133], v66 offset:23136
	ds_write_b128 v67, v[82:85] offset:46080
	s_waitcnt vmcnt(7)
	ds_write_b128 v67, v[98:101] offset:64512
	v_mfma_f32_32x32x16_bf16 v[18:33], v[110:113], v[134:137], v[18:33]
	global_load_dwordx4 v[82:85], v69, s[2:3] offset:256
	global_load_dwordx4 v[98:101], v69, s[4:5] offset:256
	s_waitcnt lgkmcnt(3)
	v_mfma_f32_32x32x16_bf16 v[34:49], v[106:109], v[118:121], v[34:49]
	ds_write_b128 v67, v[86:89] offset:50688
	s_waitcnt vmcnt(8)
	ds_write_b128 v68, v[102:105] offset:13824
	v_mfma_f32_32x32x16_bf16 v[2:17], v[114:117], v[118:121], v[2:17]
	s_waitcnt lgkmcnt(4)
	v_mfma_f32_32x32x16_bf16 v[50:65], v[106:109], v[130:133], v[50:65]
	v_mfma_f32_32x32x16_bf16 v[18:33], v[114:117], v[130:133], v[18:33]
	s_waitcnt lgkmcnt(0)
	s_barrier
; #define GL1_(RA, RB, i) { RA[i] = *(const u32x4*)(ap + (aoff + (i) * astep)); if ((i) < NB) RB[(i) < NB ? (i) : 0] = *(const u32x4*)(bp + (boff + (i) * bstep)); }
; #define LS1_(RA, RB, ST, i) { char* sn_ = lds + (ST) * STAGE; *(u32x4*)(sn_ + wofs + (i) * 32 * LROW) = RA[i]; \
;                               if ((i) < NB) *(u32x4*)(sn_ + STAGE_OP + wofs + (i) * 32 * LROW) = RB[(i) < NB ? (i) : 0]; }
; template <int NJ> DI void gemm_mainloop_reg(const bf16_t* __restrict__ A, int lda, const bf16_t* __restrict__ Bt, int ldb, int K, f32x16 (&acc)[2][NJ], char* lds) {
;     ...
; #pragma unroll
;   for (int i = 0; i < 4; ++i) GL1_(ra0, rb0, i);
;   ap += 128; bp += 128;
; #pragma unroll
;   for (int i = 0; i < 4; ++i) GL1_(ra1, rb1, i);
;   ap += 128; bp += 128;
; #pragma unroll
;   for (int i = 0; i < 4; ++i) LS1_(ra0, rb0, 0, i);
;   __syncthreads();
;   const int nk = K >> 6;
;   for (int kt = 0; kt < nk; kt += 2) {
;     const bool l0 = (kt + 2 < nk), l1 = (kt + 3 < nk);
;     STEP_(0, l0, ra0, rb0, true, ra1, rb1);
;     __syncthreads();
;     STEP_(1, l1, ra1, rb1, l0, ra0, rb0);
;     __syncthreads();
;   }
	ds_read_b128 v[86:89], v0 offset:36864
	ds_read_b128 v[102:105], v66 offset:55296
	ds_read_b128 v[106:109], v0 offset:36896
	ds_read_b128 v[110:113], v66 offset:55328
	ds_read_b128 v[114:117], v0 offset:41472
	ds_read_b128 v[118:121], v0 offset:41504
	s_waitcnt lgkmcnt(4)
	v_mfma_f32_32x32x16_bf16 v[34:49], v[86:89], v[102:105], v[34:49]
	s_waitcnt lgkmcnt(1)
	v_mfma_f32_32x32x16_bf16 v[2:17], v[114:117], v[102:105], v[2:17]
	ds_read_b128 v[102:105], v66 offset:59904
	ds_read_b128 v[130:133], v66 offset:59936
	s_waitcnt lgkmcnt(1)
	v_mfma_f32_32x32x16_bf16 v[50:65], v[86:89], v[102:105], v[50:65]
	global_load_dwordx4 v[86:89], v72, s[2:3] offset:384
	global_load_dwordx4 v[134:137], v72, s[4:5] offset:384
	s_waitcnt vmcnt(9)
	ds_write_b128 v67, v[122:125]
	s_waitcnt vmcnt(8)
	ds_write_b128 v67, v[126:129] offset:18432
	v_mfma_f32_32x32x16_bf16 v[18:33], v[114:117], v[102:105], v[18:33]
	v_mfma_f32_32x32x16_bf16 v[34:49], v[106:109], v[110:113], v[34:49]
	s_waitcnt lgkmcnt(2)
	v_mfma_f32_32x32x16_bf16 v[50:65], v[106:109], v[130:133], v[50:65]
	global_load_dwordx4 v[102:105], v71, s[2:3] offset:384
	global_load_dwordx4 v[106:109], v71, s[4:5] offset:384
	v_mfma_f32_32x32x16_bf16 v[2:17], v[118:121], v[110:113], v[2:17]
	ds_read_b128 v[110:113], v0 offset:36928
	ds_read_b128 v[114:117], v0 offset:41536
	ds_read_b128 v[122:125], v66 offset:55360
	ds_read_b128 v[126:129], v66 offset:59968
	s_waitcnt vmcnt(9)
	ds_write_b128 v67, v[74:77] offset:4608
	s_waitcnt vmcnt(8)
	ds_write_b128 v67, v[90:93] offset:23040
	v_mfma_f32_32x32x16_bf16 v[18:33], v[118:121], v[130:133], v[18:33]
	global_load_dwordx4 v[74:77], v70, s[2:3] offset:384
	global_load_dwordx4 v[90:93], v70, s[4:5] offset:384
	s_waitcnt lgkmcnt(3)
	v_mfma_f32_32x32x16_bf16 v[34:49], v[110:113], v[122:125], v[34:49]
	v_mfma_f32_32x32x16_bf16 v[2:17], v[114:117], v[122:125], v[2:17]
	s_waitcnt lgkmcnt(2)
	v_mfma_f32_32x32x16_bf16 v[50:65], v[110:113], v[126:129], v[50:65]
	ds_read_b128 v[110:113], v0 offset:36960
	ds_read_b128 v[118:121], v0 offset:41568
	ds_read_b128 v[122:125], v66 offset:55392
	ds_read_b128 v[130:133], v66 offset:60000
	s_waitcnt vmcnt(9)
	ds_write_b128 v67, v[78:81] offset:9216
	s_waitcnt vmcnt(8)
	ds_write_b128 v67, v[94:97] offset:27648
	v_mfma_f32_32x32x16_bf16 v[18:33], v[114:117], v[126:129], v[18:33]
	global_load_dwordx4 v[78:81], v69, s[2:3] offset:384
	global_load_dwordx4 v[94:97], v69, s[4:5] offset:384
	s_waitcnt lgkmcnt(3)
	v_mfma_f32_32x32x16_bf16 v[34:49], v[110:113], v[122:125], v[34:49]
	s_waitcnt vmcnt(9)
	ds_write_b128 v67, v[82:85] offset:13824
	s_waitcnt vmcnt(8)
	ds_write_b128 v67, v[98:101] offset:32256
	v_mfma_f32_32x32x16_bf16 v[2:17], v[118:121], v[122:125], v[2:17]
	s_waitcnt lgkmcnt(4)
	v_mfma_f32_32x32x16_bf16 v[50:65], v[110:113], v[130:133], v[50:65]
	v_mfma_f32_32x32x16_bf16 v[18:33], v[118:121], v[130:133], v[18:33]
	s_waitcnt lgkmcnt(0)
	s_barrier
	ds_read_b128 v[82:85], v0
	ds_read_b128 v[98:101], v66 offset:18432
	ds_read_b128 v[110:113], v0 offset:32
	ds_read_b128 v[114:117], v66 offset:18464
	ds_read_b128 v[118:121], v0 offset:4608
	ds_read_b128 v[122:125], v0 offset:4640
	s_waitcnt lgkmcnt(4)
	v_mfma_f32_32x32x16_bf16 v[34:49], v[82:85], v[98:101], v[34:49]
	s_waitcnt lgkmcnt(1)
	v_mfma_f32_32x32x16_bf16 v[2:17], v[118:121], v[98:101], v[2:17]
	ds_read_b128 v[98:101], v66 offset:23040
	ds_read_b128 v[126:129], v66 offset:23072
	s_waitcnt lgkmcnt(1)
	v_mfma_f32_32x32x16_bf16 v[50:65], v[82:85], v[98:101], v[50:65]
	global_load_dwordx4 v[82:85], v72, s[2:3] offset:512
	global_load_dwordx4 v[130:133], v72, s[4:5] offset:512
	s_waitcnt vmcnt(9)
	ds_write_b128 v67, v[86:89] offset:36864
	s_waitcnt vmcnt(8)
	ds_write_b128 v67, v[134:137] offset:55296
	v_mfma_f32_32x32x16_bf16 v[18:33], v[118:121], v[98:101], v[18:33]
	global_load_dwordx4 v[86:89], v71, s[2:3] offset:512
	global_load_dwordx4 v[98:101], v71, s[4:5] offset:512
	v_mfma_f32_32x32x16_bf16 v[34:49], v[110:113], v[114:117], v[34:49]
	v_mfma_f32_32x32x16_bf16 v[2:17], v[122:125], v[114:117], v[2:17]
	s_waitcnt lgkmcnt(2)
	v_mfma_f32_32x32x16_bf16 v[50:65], v[110:113], v[126:129], v[50:65]
	ds_read_b128 v[110:113], v0 offset:64
	ds_read_b128 v[114:117], v0 offset:4672
	ds_read_b128 v[118:121], v66 offset:18496
	ds_read_b128 v[134:137], v66 offset:23104
	s_waitcnt vmcnt(9)
	ds_write_b128 v67, v[102:105] offset:41472
	s_waitcnt vmcnt(8)
	ds_write_b128 v67, v[106:109] offset:59904
	v_mfma_f32_32x32x16_bf16 v[18:33], v[122:125], v[126:129], v[18:33]
	global_load_dwordx4 v[102:105], v70, s[2:3] offset:512
	global_load_dwordx4 v[106:109], v70, s[4:5] offset:512
	s_waitcnt lgkmcnt(3)
	v_mfma_f32_32x32x16_bf16 v[34:49], v[110:113], v[118:121], v[34:49]
	v_mfma_f32_32x32x16_bf16 v[2:17], v[114:117], v[118:121], v[2:17]
	s_waitcnt lgkmcnt(2)
	v_mfma_f32_32x32x16_bf16 v[50:65], v[110:113], v[134:137], v[50:65]
	ds_read_b128 v[110:113], v0 offset:96
	ds_read_b128 v[118:121], v0 offset:4704
	ds_read_b128 v[122:125], v66 offset:18528
	ds_read_b128 v[126:129], v66 offset:23136
	s_waitcnt vmcnt(9)
	ds_write_b128 v67, v[74:77] offset:46080
	s_waitcnt vmcnt(8)
	ds_write_b128 v67, v[90:93] offset:64512
	v_mfma_f32_32x32x16_bf16 v[18:33], v[114:117], v[134:137], v[18:33]
	global_load_dwordx4 v[74:77], v69, s[2:3] offset:512
	global_load_dwordx4 v[90:93], v69, s[4:5] offset:512
	s_waitcnt lgkmcnt(3)
	v_mfma_f32_32x32x16_bf16 v[34:49], v[110:113], v[122:125], v[34:49]
	s_waitcnt vmcnt(9)
	ds_write_b128 v67, v[78:81] offset:50688
	s_waitcnt vmcnt(8)
	ds_write_b128 v68, v[94:97] offset:13824
	v_mfma_f32_32x32x16_bf16 v[2:17], v[118:121], v[122:125], v[2:17]
	s_waitcnt lgkmcnt(4)
	v_mfma_f32_32x32x16_bf16 v[50:65], v[110:113], v[126:129], v[50:65]
	v_mfma_f32_32x32x16_bf16 v[18:33], v[118:121], v[126:129], v[18:33]
	s_waitcnt lgkmcnt(0)
	s_barrier
; #define GL1_(RA, RB, i) { RA[i] = *(const u32x4*)(ap + (aoff + (i) * astep)); if ((i) < NB) RB[(i) < NB ? (i) : 0] = *(const u32x4*)(bp + (boff + (i) * bstep)); }
; #define LS1_(RA, RB, ST, i) { char* sn_ = lds + (ST) * STAGE; *(u32x4*)(sn_ + wofs + (i) * 32 * LROW) = RA[i]; \
;                               if ((i) < NB) *(u32x4*)(sn_ + STAGE_OP + wofs + (i) * 32 * LROW) = RB[(i) < NB ? (i) : 0]; }
; template <int NJ> DI void gemm_mainloop_reg(const bf16_t* __restrict__ A, int lda, const bf16_t* __restrict__ Bt, int ldb, int K, f32x16 (&acc)[2][NJ], char* lds) {
;     ...
; #pragma unroll
;   for (int i = 0; i < 4; ++i) GL1_(ra0, rb0, i);
;   ap += 128; bp += 128;
; #pragma unroll
;   for (int i = 0; i < 4; ++i) GL1_(ra1, rb1, i);
;   ap += 128; bp += 128;
; #pragma unroll
;   for (int i = 0; i < 4; ++i) LS1_(ra0, rb0, 0, i);
;   __syncthreads();
;   const int nk = K >> 6;
;   for (int kt = 0; kt < nk; kt += 2) {
;     const bool l0 = (kt + 2 < nk), l1 = (kt + 3 < nk);
;     STEP_(0, l0, ra0, rb0, true, ra1, rb1);
;     __syncthreads();
;     STEP_(1, l1, ra1, rb1, l0, ra0, rb0);
;     __syncthreads();
;   }
	ds_read_b128 v[78:81], v0 offset:36864
	ds_read_b128 v[94:97], v66 offset:55296
	ds_read_b128 v[110:113], v0 offset:36896
	ds_read_b128 v[114:117], v66 offset:55328
	ds_read_b128 v[118:121], v0 offset:41472
	ds_read_b128 v[122:125], v0 offset:41504
	s_waitcnt lgkmcnt(4)
	v_mfma_f32_32x32x16_bf16 v[34:49], v[78:81], v[94:97], v[34:49]
	s_waitcnt lgkmcnt(1)
	v_mfma_f32_32x32x16_bf16 v[2:17], v[118:121], v[94:97], v[2:17]
	ds_read_b128 v[94:97], v66 offset:59904
	ds_read_b128 v[126:129], v66 offset:59936
	s_waitcnt lgkmcnt(1)
	v_mfma_f32_32x32x16_bf16 v[50:65], v[78:81], v[94:97], v[50:65]
	global_load_dwordx4 v[78:81], v72, s[2:3] offset:640
	global_load_dwordx4 v[134:137], v72, s[4:5] offset:640
	s_waitcnt vmcnt(9)
	ds_write_b128 v67, v[82:85]
	s_waitcnt vmcnt(8)
	ds_write_b128 v67, v[130:133] offset:18432
	v_mfma_f32_32x32x16_bf16 v[18:33], v[118:121], v[94:97], v[18:33]
	global_load_dwordx4 v[82:85], v71, s[2:3] offset:640
	global_load_dwordx4 v[94:97], v71, s[4:5] offset:640
	v_mfma_f32_32x32x16_bf16 v[34:49], v[110:113], v[114:117], v[34:49]
	v_mfma_f32_32x32x16_bf16 v[2:17], v[122:125], v[114:117], v[2:17]
	s_waitcnt lgkmcnt(2)
	v_mfma_f32_32x32x16_bf16 v[50:65], v[110:113], v[126:129], v[50:65]
	ds_read_b128 v[110:113], v0 offset:36928
	ds_read_b128 v[114:117], v0 offset:41536
	ds_read_b128 v[118:121], v66 offset:55360
	ds_read_b128 v[130:133], v66 offset:59968
	s_waitcnt vmcnt(9)
	ds_write_b128 v67, v[86:89] offset:4608
	s_waitcnt vmcnt(8)
	ds_write_b128 v67, v[98:101] offset:23040
	v_mfma_f32_32x32x16_bf16 v[18:33], v[122:125], v[126:129], v[18:33]
	global_load_dwordx4 v[86:89], v70, s[2:3] offset:640
	global_load_dwordx4 v[98:101], v70, s[4:5] offset:640
	s_waitcnt lgkmcnt(3)
	v_mfma_f32_32x32x16_bf16 v[34:49], v[110:113], v[118:121], v[34:49]
	v_mfma_f32_32x32x16_bf16 v[2:17], v[114:117], v[118:121], v[2:17]
	s_waitcnt lgkmcnt(2)
	v_mfma_f32_32x32x16_bf16 v[50:65], v[110:113], v[130:133], v[50:65]
	ds_read_b128 v[110:113], v0 offset:36960
	ds_read_b128 v[118:121], v0 offset:41568
	ds_read_b128 v[122:125], v66 offset:55392
	ds_read_b128 v[126:129], v66 offset:60000
	s_waitcnt vmcnt(9)
	ds_write_b128 v67, v[102:105] offset:9216
	s_waitcnt vmcnt(8)
	ds_write_b128 v67, v[106:109] offset:27648
	v_mfma_f32_32x32x16_bf16 v[18:33], v[114:117], v[130:133], v[18:33]
	global_load_dwordx4 v[102:105], v69, s[2:3] offset:640
	global_load_dwordx4 v[106:109], v69, s[4:5] offset:640
	s_waitcnt lgkmcnt(3)
	v_mfma_f32_32x32x16_bf16 v[34:49], v[110:113], v[122:125], v[34:49]
	s_waitcnt vmcnt(9)
	ds_write_b128 v67, v[74:77] offset:13824
	s_waitcnt vmcnt(8)
	ds_write_b128 v67, v[90:93] offset:32256
	v_mfma_f32_32x32x16_bf16 v[2:17], v[118:121], v[122:125], v[2:17]
	s_waitcnt lgkmcnt(4)
	v_mfma_f32_32x32x16_bf16 v[50:65], v[110:113], v[126:129], v[50:65]
	v_mfma_f32_32x32x16_bf16 v[18:33], v[118:121], v[126:129], v[18:33]
	s_waitcnt lgkmcnt(0)
	s_barrier
	ds_read_b128 v[74:77], v0
	ds_read_b128 v[90:93], v66 offset:18432
	ds_read_b128 v[110:113], v0 offset:32
	ds_read_b128 v[114:117], v66 offset:18464
	ds_read_b128 v[118:121], v0 offset:4608
	ds_read_b128 v[122:125], v0 offset:4640
	s_waitcnt lgkmcnt(4)
	v_mfma_f32_32x32x16_bf16 v[34:49], v[74:77], v[90:93], v[34:49]
	s_waitcnt lgkmcnt(1)
	v_mfma_f32_32x32x16_bf16 v[2:17], v[118:121], v[90:93], v[2:17]
	ds_read_b128 v[90:93], v66 offset:23040
	ds_read_b128 v[126:129], v66 offset:23072
	s_waitcnt lgkmcnt(1)
	v_mfma_f32_32x32x16_bf16 v[50:65], v[74:77], v[90:93], v[50:65]
	global_load_dwordx4 v[74:77], v72, s[2:3] offset:768
	global_load_dwordx4 v[130:133], v72, s[4:5] offset:768
	s_waitcnt vmcnt(9)
	ds_write_b128 v67, v[78:81] offset:36864
	s_waitcnt vmcnt(8)
	ds_write_b128 v67, v[134:137] offset:55296
	v_mfma_f32_32x32x16_bf16 v[18:33], v[118:121], v[90:93], v[18:33]
	global_load_dwordx4 v[78:81], v71, s[2:3] offset:768
	global_load_dwordx4 v[90:93], v71, s[4:5] offset:768
	v_mfma_f32_32x32x16_bf16 v[34:49], v[110:113], v[114:117], v[34:49]
	v_mfma_f32_32x32x16_bf16 v[2:17], v[122:125], v[114:117], v[2:17]
	s_waitcnt lgkmcnt(2)
	v_mfma_f32_32x32x16_bf16 v[50:65], v[110:113], v[126:129], v[50:65]
	ds_read_b128 v[110:113], v0 offset:64
	ds_read_b128 v[114:117], v0 offset:4672
	ds_read_b128 v[118:121], v66 offset:18496
	ds_read_b128 v[134:137], v66 offset:23104
	s_waitcnt vmcnt(9)
	ds_write_b128 v67, v[82:85] offset:41472
	s_waitcnt vmcnt(8)
	ds_write_b128 v67, v[94:97] offset:59904
	v_mfma_f32_32x32x16_bf16 v[18:33], v[122:125], v[126:129], v[18:33]
	global_load_dwordx4 v[82:85], v70, s[2:3] offset:768
	global_load_dwordx4 v[94:97], v70, s[4:5] offset:768
	s_waitcnt lgkmcnt(3)
	v_mfma_f32_32x32x16_bf16 v[34:49], v[110:113], v[118:121], v[34:49]
	v_mfma_f32_32x32x16_bf16 v[2:17], v[114:117], v[118:121], v[2:17]
	s_waitcnt lgkmcnt(2)
	v_mfma_f32_32x32x16_bf16 v[50:65], v[110:113], v[134:137], v[50:65]
	ds_read_b128 v[110:113], v0 offset:96
	ds_read_b128 v[118:121], v0 offset:4704
	ds_read_b128 v[122:125], v66 offset:18528
	ds_read_b128 v[126:129], v66 offset:23136
	s_waitcnt vmcnt(9)
	ds_write_b128 v67, v[86:89] offset:46080
	s_waitcnt vmcnt(8)
	ds_write_b128 v67, v[98:101] offset:64512
	v_mfma_f32_32x32x16_bf16 v[18:33], v[114:117], v[134:137], v[18:33]
	global_load_dwordx4 v[86:89], v69, s[2:3] offset:768
	global_load_dwordx4 v[98:101], v69, s[4:5] offset:768
	s_waitcnt lgkmcnt(3)
	v_mfma_f32_32x32x16_bf16 v[34:49], v[110:113], v[122:125], v[34:49]
	s_waitcnt vmcnt(9)
	ds_write_b128 v67, v[102:105] offset:50688
	s_waitcnt vmcnt(8)
	ds_write_b128 v68, v[106:109] offset:13824
	v_mfma_f32_32x32x16_bf16 v[2:17], v[118:121], v[122:125], v[2:17]
	s_waitcnt lgkmcnt(4)
	v_mfma_f32_32x32x16_bf16 v[50:65], v[110:113], v[126:129], v[50:65]
	v_mfma_f32_32x32x16_bf16 v[18:33], v[118:121], v[126:129], v[18:33]
	s_waitcnt lgkmcnt(0)
	s_barrier
; #define GL1_(RA, RB, i) { RA[i] = *(const u32x4*)(ap + (aoff + (i) * astep)); if ((i) < NB) RB[(i) < NB ? (i) : 0] = *(const u32x4*)(bp + (boff + (i) * bstep)); }
; #define LS1_(RA, RB, ST, i) { char* sn_ = lds + (ST) * STAGE; *(u32x4*)(sn_ + wofs + (i) * 32 * LROW) = RA[i]; \
;                               if ((i) < NB) *(u32x4*)(sn_ + STAGE_OP + wofs + (i) * 32 * LROW) = RB[(i) < NB ? (i) : 0]; }
; template <int NJ> DI void gemm_mainloop_reg(const bf16_t* __restrict__ A, int lda, const bf16_t* __restrict__ Bt, int ldb, int K, f32x16 (&acc)[2][NJ], char* lds) {
;     ...
; #pragma unroll
;   for (int i = 0; i < 4; ++i) GL1_(ra0, rb0, i);
;   ap += 128; bp += 128;
; #pragma unroll
;   for (int i = 0; i < 4; ++i) GL1_(ra1, rb1, i);
;   ap += 128; bp += 128;
; #pragma unroll
;   for (int i = 0; i < 4; ++i) LS1_(ra0, rb0, 0, i);
;   __syncthreads();
;   const int nk = K >> 6;
;   for (int kt = 0; kt < nk; kt += 2) {
;     const bool l0 = (kt + 2 < nk), l1 = (kt + 3 < nk);
;     STEP_(0, l0, ra0, rb0, true, ra1, rb1);
;     __syncthreads();
;     STEP_(1, l1, ra1, rb1, l0, ra0, rb0);
;     __syncthreads();
;   }
	ds_read_b128 v[102:105], v0 offset:36864
	ds_read_b128 v[106:109], v66 offset:55296
	ds_read_b128 v[110:113], v0 offset:36896
	ds_read_b128 v[114:117], v66 offset:55328
	ds_read_b128 v[118:121], v0 offset:41472
	ds_read_b128 v[122:125], v0 offset:41504
	s_waitcnt lgkmcnt(4)
	v_mfma_f32_32x32x16_bf16 v[34:49], v[102:105], v[106:109], v[34:49]
	s_waitcnt lgkmcnt(1)
	v_mfma_f32_32x32x16_bf16 v[2:17], v[118:121], v[106:109], v[2:17]
	ds_read_b128 v[106:109], v66 offset:59904
	ds_read_b128 v[126:129], v66 offset:59936
	s_waitcnt lgkmcnt(1)
	v_mfma_f32_32x32x16_bf16 v[50:65], v[102:105], v[106:109], v[50:65]
	global_load_dwordx4 v[102:105], v72, s[2:3] offset:896
	global_load_dwordx4 v[134:137], v72, s[4:5] offset:896
	s_waitcnt vmcnt(9)
	ds_write_b128 v67, v[74:77]
	s_waitcnt vmcnt(8)
	ds_write_b128 v67, v[130:133] offset:18432
	v_mfma_f32_32x32x16_bf16 v[18:33], v[118:121], v[106:109], v[18:33]
	global_load_dwordx4 v[74:77], v71, s[2:3] offset:896
	global_load_dwordx4 v[106:109], v71, s[4:5] offset:896
	v_mfma_f32_32x32x16_bf16 v[34:49], v[110:113], v[114:117], v[34:49]
	v_mfma_f32_32x32x16_bf16 v[2:17], v[122:125], v[114:117], v[2:17]
	s_waitcnt lgkmcnt(2)
	v_mfma_f32_32x32x16_bf16 v[50:65], v[110:113], v[126:129], v[50:65]
	ds_read_b128 v[110:113], v0 offset:36928
	ds_read_b128 v[114:117], v0 offset:41536
	ds_read_b128 v[118:121], v66 offset:55360
	ds_read_b128 v[130:133], v66 offset:59968
	s_waitcnt vmcnt(9)
	ds_write_b128 v67, v[78:81] offset:4608
	s_waitcnt vmcnt(8)
	ds_write_b128 v67, v[90:93] offset:23040
	v_mfma_f32_32x32x16_bf16 v[18:33], v[122:125], v[126:129], v[18:33]
	global_load_dwordx4 v[78:81], v70, s[2:3] offset:896
	global_load_dwordx4 v[90:93], v70, s[4:5] offset:896
	s_waitcnt lgkmcnt(3)
	v_mfma_f32_32x32x16_bf16 v[34:49], v[110:113], v[118:121], v[34:49]
	v_mfma_f32_32x32x16_bf16 v[2:17], v[114:117], v[118:121], v[2:17]
	s_waitcnt lgkmcnt(2)
	v_mfma_f32_32x32x16_bf16 v[50:65], v[110:113], v[130:133], v[50:65]
	ds_read_b128 v[110:113], v0 offset:36960
	ds_read_b128 v[118:121], v0 offset:41568
	ds_read_b128 v[122:125], v66 offset:55392
	ds_read_b128 v[126:129], v66 offset:60000
	s_waitcnt vmcnt(9)
	ds_write_b128 v67, v[82:85] offset:9216
	s_waitcnt vmcnt(8)
	ds_write_b128 v67, v[94:97] offset:27648
	v_mfma_f32_32x32x16_bf16 v[18:33], v[114:117], v[130:133], v[18:33]
	global_load_dwordx4 v[82:85], v69, s[2:3] offset:896
	global_load_dwordx4 v[94:97], v69, s[4:5] offset:896
	s_waitcnt lgkmcnt(3)
	v_mfma_f32_32x32x16_bf16 v[34:49], v[110:113], v[122:125], v[34:49]
	s_waitcnt vmcnt(9)
	ds_write_b128 v67, v[86:89] offset:13824
	s_waitcnt vmcnt(8)
	ds_write_b128 v67, v[98:101] offset:32256
	v_mfma_f32_32x32x16_bf16 v[2:17], v[118:121], v[122:125], v[2:17]
	s_waitcnt lgkmcnt(4)
	v_mfma_f32_32x32x16_bf16 v[50:65], v[110:113], v[126:129], v[50:65]
	v_mfma_f32_32x32x16_bf16 v[18:33], v[118:121], v[126:129], v[18:33]
	s_waitcnt lgkmcnt(0)
	s_barrier
	ds_read_b128 v[86:89], v0
	ds_read_b128 v[98:101], v66 offset:18432
	ds_read_b128 v[110:113], v0 offset:32
	ds_read_b128 v[114:117], v66 offset:18464
	ds_read_b128 v[118:121], v0 offset:4608
	ds_read_b128 v[122:125], v0 offset:4640
	s_waitcnt lgkmcnt(4)
	v_mfma_f32_32x32x16_bf16 v[34:49], v[86:89], v[98:101], v[34:49]
	s_waitcnt lgkmcnt(1)
	v_mfma_f32_32x32x16_bf16 v[2:17], v[118:121], v[98:101], v[2:17]
	ds_read_b128 v[98:101], v66 offset:23040
	ds_read_b128 v[126:129], v66 offset:23072
	s_waitcnt lgkmcnt(1)
	v_mfma_f32_32x32x16_bf16 v[50:65], v[86:89], v[98:101], v[50:65]
	global_load_dwordx4 v[86:89], v72, s[2:3] offset:1024
	global_load_dwordx4 v[130:133], v72, s[4:5] offset:1024
	s_waitcnt vmcnt(9)
	ds_write_b128 v67, v[102:105] offset:36864
	s_waitcnt vmcnt(8)
	ds_write_b128 v67, v[134:137] offset:55296
	v_mfma_f32_32x32x16_bf16 v[18:33], v[118:121], v[98:101], v[18:33]
	global_load_dwordx4 v[98:101], v71, s[2:3] offset:1024
	global_load_dwordx4 v[102:105], v71, s[4:5] offset:1024
	v_mfma_f32_32x32x16_bf16 v[34:49], v[110:113], v[114:117], v[34:49]
	v_mfma_f32_32x32x16_bf16 v[2:17], v[122:125], v[114:117], v[2:17]
	s_waitcnt lgkmcnt(2)
	v_mfma_f32_32x32x16_bf16 v[50:65], v[110:113], v[126:129], v[50:65]
	ds_read_b128 v[110:113], v0 offset:64
	ds_read_b128 v[114:117], v0 offset:4672
	ds_read_b128 v[118:121], v66 offset:18496
	ds_read_b128 v[134:137], v66 offset:23104
	s_waitcnt vmcnt(9)
	ds_write_b128 v67, v[74:77] offset:41472
	s_waitcnt vmcnt(8)
	ds_write_b128 v67, v[106:109] offset:59904
	v_mfma_f32_32x32x16_bf16 v[18:33], v[122:125], v[126:129], v[18:33]
	global_load_dwordx4 v[74:77], v70, s[2:3] offset:1024
	global_load_dwordx4 v[106:109], v70, s[4:5] offset:1024
	s_waitcnt lgkmcnt(3)
	v_mfma_f32_32x32x16_bf16 v[34:49], v[110:113], v[118:121], v[34:49]
	v_mfma_f32_32x32x16_bf16 v[2:17], v[114:117], v[118:121], v[2:17]
	s_waitcnt lgkmcnt(2)
	v_mfma_f32_32x32x16_bf16 v[50:65], v[110:113], v[134:137], v[50:65]
	ds_read_b128 v[110:113], v0 offset:96
	ds_read_b128 v[118:121], v0 offset:4704
	ds_read_b128 v[122:125], v66 offset:18528
	ds_read_b128 v[126:129], v66 offset:23136
	s_waitcnt vmcnt(9)
	ds_write_b128 v67, v[78:81] offset:46080
	s_waitcnt vmcnt(8)
	ds_write_b128 v67, v[90:93] offset:64512
	v_mfma_f32_32x32x16_bf16 v[18:33], v[114:117], v[134:137], v[18:33]
	global_load_dwordx4 v[78:81], v69, s[2:3] offset:1024
	global_load_dwordx4 v[90:93], v69, s[4:5] offset:1024
	s_waitcnt lgkmcnt(3)
	v_mfma_f32_32x32x16_bf16 v[34:49], v[110:113], v[122:125], v[34:49]
	s_waitcnt vmcnt(9)
	ds_write_b128 v67, v[82:85] offset:50688
	s_waitcnt vmcnt(8)
	ds_write_b128 v68, v[94:97] offset:13824
	v_mfma_f32_32x32x16_bf16 v[2:17], v[118:121], v[122:125], v[2:17]
	s_waitcnt lgkmcnt(4)
	v_mfma_f32_32x32x16_bf16 v[50:65], v[110:113], v[126:129], v[50:65]
	v_mfma_f32_32x32x16_bf16 v[18:33], v[118:121], v[126:129], v[18:33]
	s_waitcnt lgkmcnt(0)
	s_barrier
; #define GL1_(RA, RB, i) { RA[i] = *(const u32x4*)(ap + (aoff + (i) * astep)); if ((i) < NB) RB[(i) < NB ? (i) : 0] = *(const u32x4*)(bp + (boff + (i) * bstep)); }
; #define LS1_(RA, RB, ST, i) { char* sn_ = lds + (ST) * STAGE; *(u32x4*)(sn_ + wofs + (i) * 32 * LROW) = RA[i]; \
;                               if ((i) < NB) *(u32x4*)(sn_ + STAGE_OP + wofs + (i) * 32 * LROW) = RB[(i) < NB ? (i) : 0]; }
; template <int NJ> DI void gemm_mainloop_reg(const bf16_t* __restrict__ A, int lda, const bf16_t* __restrict__ Bt, int ldb, int K, f32x16 (&acc)[2][NJ], char* lds) {
;     ...
; #pragma unroll
;   for (int i = 0; i < 4; ++i) GL1_(ra0, rb0, i);
;   ap += 128; bp += 128;
; #pragma unroll
;   for (int i = 0; i < 4; ++i) GL1_(ra1, rb1, i);
;   ap += 128; bp += 128;
; #pragma unroll
;   for (int i = 0; i < 4; ++i) LS1_(ra0, rb0, 0, i);
;   __syncthreads();
;   const int nk = K >> 6;
;   for (int kt = 0; kt < nk; kt += 2) {
;     const bool l0 = (kt + 2 < nk), l1 = (kt + 3 < nk);
;     STEP_(0, l0, ra0, rb0, true, ra1, rb1);
;     __syncthreads();
;     STEP_(1, l1, ra1, rb1, l0, ra0, rb0);
;     __syncthreads();
;   }
	ds_read_b128 v[82:85], v0 offset:36864
	ds_read_b128 v[94:97], v66 offset:55296
	ds_read_b128 v[110:113], v0 offset:36896
	ds_read_b128 v[114:117], v66 offset:55328
	ds_read_b128 v[118:121], v0 offset:41472
	ds_read_b128 v[122:125], v0 offset:41504
	s_waitcnt lgkmcnt(4)
	v_mfma_f32_32x32x16_bf16 v[34:49], v[82:85], v[94:97], v[34:49]
	s_waitcnt lgkmcnt(1)
	v_mfma_f32_32x32x16_bf16 v[2:17], v[118:121], v[94:97], v[2:17]
	ds_read_b128 v[94:97], v66 offset:59904
	ds_read_b128 v[126:129], v66 offset:59936
	s_waitcnt lgkmcnt(1)
	v_mfma_f32_32x32x16_bf16 v[50:65], v[82:85], v[94:97], v[50:65]
	global_load_dwordx4 v[82:85], v72, s[2:3] offset:1152
	global_load_dwordx4 v[134:137], v72, s[4:5] offset:1152
	s_waitcnt vmcnt(9)
	ds_write_b128 v67, v[86:89]
	s_waitcnt vmcnt(8)
	ds_write_b128 v67, v[130:133] offset:18432
	v_mfma_f32_32x32x16_bf16 v[18:33], v[118:121], v[94:97], v[18:33]
	global_load_dwordx4 v[86:89], v71, s[2:3] offset:1152
	global_load_dwordx4 v[94:97], v71, s[4:5] offset:1152
	v_mfma_f32_32x32x16_bf16 v[34:49], v[110:113], v[114:117], v[34:49]
	v_mfma_f32_32x32x16_bf16 v[2:17], v[122:125], v[114:117], v[2:17]
	s_waitcnt lgkmcnt(2)
	v_mfma_f32_32x32x16_bf16 v[50:65], v[110:113], v[126:129], v[50:65]
	ds_read_b128 v[110:113], v0 offset:36928
	ds_read_b128 v[114:117], v0 offset:41536
	ds_read_b128 v[118:121], v66 offset:55360
	ds_read_b128 v[130:133], v66 offset:59968
	s_waitcnt vmcnt(9)
	ds_write_b128 v67, v[98:101] offset:4608
	s_waitcnt vmcnt(8)
	ds_write_b128 v67, v[102:105] offset:23040
	v_mfma_f32_32x32x16_bf16 v[18:33], v[122:125], v[126:129], v[18:33]
	global_load_dwordx4 v[98:101], v70, s[2:3] offset:1152
	global_load_dwordx4 v[102:105], v70, s[4:5] offset:1152
	s_waitcnt lgkmcnt(3)
	v_mfma_f32_32x32x16_bf16 v[34:49], v[110:113], v[118:121], v[34:49]
	v_mfma_f32_32x32x16_bf16 v[2:17], v[114:117], v[118:121], v[2:17]
	s_waitcnt lgkmcnt(2)
	v_mfma_f32_32x32x16_bf16 v[50:65], v[110:113], v[130:133], v[50:65]
	ds_read_b128 v[110:113], v0 offset:36960
	ds_read_b128 v[118:121], v0 offset:41568
	ds_read_b128 v[122:125], v66 offset:55392
	ds_read_b128 v[126:129], v66 offset:60000
	s_waitcnt vmcnt(9)
	ds_write_b128 v67, v[74:77] offset:9216
	s_waitcnt vmcnt(8)
	ds_write_b128 v67, v[106:109] offset:27648
	v_mfma_f32_32x32x16_bf16 v[18:33], v[114:117], v[130:133], v[18:33]
	global_load_dwordx4 v[74:77], v69, s[2:3] offset:1152
	global_load_dwordx4 v[106:109], v69, s[4:5] offset:1152
	s_waitcnt lgkmcnt(3)
	v_mfma_f32_32x32x16_bf16 v[34:49], v[110:113], v[122:125], v[34:49]
	s_waitcnt vmcnt(9)
	ds_write_b128 v67, v[78:81] offset:13824
	s_waitcnt vmcnt(8)
	ds_write_b128 v67, v[90:93] offset:32256
	v_mfma_f32_32x32x16_bf16 v[2:17], v[118:121], v[122:125], v[2:17]
	s_waitcnt lgkmcnt(4)
	v_mfma_f32_32x32x16_bf16 v[50:65], v[110:113], v[126:129], v[50:65]
	v_mfma_f32_32x32x16_bf16 v[18:33], v[118:121], v[126:129], v[18:33]
	s_waitcnt lgkmcnt(0)
	s_barrier
	ds_read_b128 v[78:81], v0
	ds_read_b128 v[90:93], v66 offset:18432
	ds_read_b128 v[110:113], v0 offset:32
	ds_read_b128 v[114:117], v66 offset:18464
	ds_read_b128 v[118:121], v0 offset:4608
	ds_read_b128 v[122:125], v0 offset:4640
	s_waitcnt lgkmcnt(4)
	v_mfma_f32_32x32x16_bf16 v[34:49], v[78:81], v[90:93], v[34:49]
	s_waitcnt lgkmcnt(1)
	v_mfma_f32_32x32x16_bf16 v[2:17], v[118:121], v[90:93], v[2:17]
	ds_read_b128 v[90:93], v66 offset:23040
	ds_read_b128 v[126:129], v66 offset:23072
	s_waitcnt lgkmcnt(1)
	v_mfma_f32_32x32x16_bf16 v[50:65], v[78:81], v[90:93], v[50:65]
	global_load_dwordx4 v[78:81], v72, s[2:3] offset:1280
	global_load_dwordx4 v[130:133], v72, s[4:5] offset:1280
	s_waitcnt vmcnt(9)
	ds_write_b128 v67, v[82:85] offset:36864
	s_waitcnt vmcnt(8)
	ds_write_b128 v67, v[134:137] offset:55296
	v_mfma_f32_32x32x16_bf16 v[18:33], v[118:121], v[90:93], v[18:33]
	global_load_dwordx4 v[82:85], v71, s[2:3] offset:1280
	global_load_dwordx4 v[90:93], v71, s[4:5] offset:1280
	v_mfma_f32_32x32x16_bf16 v[34:49], v[110:113], v[114:117], v[34:49]
	v_mfma_f32_32x32x16_bf16 v[2:17], v[122:125], v[114:117], v[2:17]
	s_waitcnt lgkmcnt(2)
	v_mfma_f32_32x32x16_bf16 v[50:65], v[110:113], v[126:129], v[50:65]
	ds_read_b128 v[110:113], v0 offset:64
	ds_read_b128 v[114:117], v0 offset:4672
	ds_read_b128 v[118:121], v66 offset:18496
	ds_read_b128 v[134:137], v66 offset:23104
	s_waitcnt vmcnt(9)
	ds_write_b128 v67, v[86:89] offset:41472
	s_waitcnt vmcnt(8)
	ds_write_b128 v67, v[94:97] offset:59904
	v_mfma_f32_32x32x16_bf16 v[18:33], v[122:125], v[126:129], v[18:33]
	global_load_dwordx4 v[86:89], v70, s[2:3] offset:1280
	global_load_dwordx4 v[94:97], v70, s[4:5] offset:1280
	s_waitcnt lgkmcnt(3)
	v_mfma_f32_32x32x16_bf16 v[34:49], v[110:113], v[118:121], v[34:49]
	v_mfma_f32_32x32x16_bf16 v[2:17], v[114:117], v[118:121], v[2:17]
	s_waitcnt lgkmcnt(2)
	v_mfma_f32_32x32x16_bf16 v[50:65], v[110:113], v[134:137], v[50:65]
	ds_read_b128 v[110:113], v0 offset:96
	ds_read_b128 v[118:121], v0 offset:4704
	ds_read_b128 v[122:125], v66 offset:18528
	ds_read_b128 v[126:129], v66 offset:23136
	s_waitcnt vmcnt(9)
	ds_write_b128 v67, v[98:101] offset:46080
	s_waitcnt vmcnt(8)
	ds_write_b128 v67, v[102:105] offset:64512
	v_mfma_f32_32x32x16_bf16 v[18:33], v[114:117], v[134:137], v[18:33]
	global_load_dwordx4 v[98:101], v69, s[2:3] offset:1280
	global_load_dwordx4 v[102:105], v69, s[4:5] offset:1280
	s_waitcnt lgkmcnt(3)
	v_mfma_f32_32x32x16_bf16 v[34:49], v[110:113], v[122:125], v[34:49]
	s_waitcnt vmcnt(9)
	ds_write_b128 v67, v[74:77] offset:50688
	s_waitcnt vmcnt(8)
	ds_write_b128 v68, v[106:109] offset:13824
	v_mfma_f32_32x32x16_bf16 v[2:17], v[118:121], v[122:125], v[2:17]
	s_waitcnt lgkmcnt(4)
	v_mfma_f32_32x32x16_bf16 v[50:65], v[110:113], v[126:129], v[50:65]
	v_mfma_f32_32x32x16_bf16 v[18:33], v[118:121], v[126:129], v[18:33]
	s_waitcnt lgkmcnt(0)
	s_barrier
; #define GL1_(RA, RB, i) { RA[i] = *(const u32x4*)(ap + (aoff + (i) * astep)); if ((i) < NB) RB[(i) < NB ? (i) : 0] = *(const u32x4*)(bp + (boff + (i) * bstep)); }
; #define LS1_(RA, RB, ST, i) { char* sn_ = lds + (ST) * STAGE; *(u32x4*)(sn_ + wofs + (i) * 32 * LROW) = RA[i]; \
;                               if ((i) < NB) *(u32x4*)(sn_ + STAGE_OP + wofs + (i) * 32 * LROW) = RB[(i) < NB ? (i) : 0]; }
; template <int NJ> DI void gemm_mainloop_reg(const bf16_t* __restrict__ A, int lda, const bf16_t* __restrict__ Bt, int ldb, int K, f32x16 (&acc)[2][NJ], char* lds) {
;     ...
; #pragma unroll
;   for (int i = 0; i < 4; ++i) GL1_(ra0, rb0, i);
;   ap += 128; bp += 128;
; #pragma unroll
;   for (int i = 0; i < 4; ++i) GL1_(ra1, rb1, i);
;   ap += 128; bp += 128;
; #pragma unroll
;   for (int i = 0; i < 4; ++i) LS1_(ra0, rb0, 0, i);
;   __syncthreads();
;   const int nk = K >> 6;
;   for (int kt = 0; kt < nk; kt += 2) {
;     const bool l0 = (kt + 2 < nk), l1 = (kt + 3 < nk);
;     STEP_(0, l0, ra0, rb0, true, ra1, rb1);
;     __syncthreads();
;     STEP_(1, l1, ra1, rb1, l0, ra0, rb0);
;     __syncthreads();
;   }
	ds_read_b128 v[74:77], v0 offset:36864
	ds_read_b128 v[106:109], v66 offset:55296
	ds_read_b128 v[110:113], v0 offset:36896
	ds_read_b128 v[114:117], v66 offset:55328
	ds_read_b128 v[118:121], v0 offset:41472
	ds_read_b128 v[122:125], v0 offset:41504
	s_waitcnt lgkmcnt(4)
	v_mfma_f32_32x32x16_bf16 v[34:49], v[74:77], v[106:109], v[34:49]
	s_waitcnt lgkmcnt(1)
	v_mfma_f32_32x32x16_bf16 v[2:17], v[118:121], v[106:109], v[2:17]
	ds_read_b128 v[106:109], v66 offset:59904
	ds_read_b128 v[126:129], v66 offset:59936
	s_waitcnt lgkmcnt(1)
	v_mfma_f32_32x32x16_bf16 v[50:65], v[74:77], v[106:109], v[50:65]
	global_load_dwordx4 v[74:77], v72, s[2:3] offset:1408
	global_load_dwordx4 v[134:137], v72, s[4:5] offset:1408
	s_waitcnt vmcnt(9)
	ds_write_b128 v67, v[78:81]
	s_waitcnt vmcnt(8)
	ds_write_b128 v67, v[130:133] offset:18432
	v_mfma_f32_32x32x16_bf16 v[18:33], v[118:121], v[106:109], v[18:33]
	global_load_dwordx4 v[78:81], v71, s[2:3] offset:1408
	global_load_dwordx4 v[106:109], v71, s[4:5] offset:1408
	v_mfma_f32_32x32x16_bf16 v[34:49], v[110:113], v[114:117], v[34:49]
	v_mfma_f32_32x32x16_bf16 v[2:17], v[122:125], v[114:117], v[2:17]
	s_waitcnt lgkmcnt(2)
	v_mfma_f32_32x32x16_bf16 v[50:65], v[110:113], v[126:129], v[50:65]
	ds_read_b128 v[110:113], v0 offset:36928
	ds_read_b128 v[114:117], v0 offset:41536
	ds_read_b128 v[118:121], v66 offset:55360
	ds_read_b128 v[130:133], v66 offset:59968
	s_waitcnt vmcnt(9)
	ds_write_b128 v67, v[82:85] offset:4608
	s_waitcnt vmcnt(8)
	ds_write_b128 v67, v[90:93] offset:23040
	v_mfma_f32_32x32x16_bf16 v[18:33], v[122:125], v[126:129], v[18:33]
	global_load_dwordx4 v[82:85], v70, s[2:3] offset:1408
	global_load_dwordx4 v[90:93], v70, s[4:5] offset:1408
	s_waitcnt lgkmcnt(3)
	v_mfma_f32_32x32x16_bf16 v[34:49], v[110:113], v[118:121], v[34:49]
	v_mfma_f32_32x32x16_bf16 v[2:17], v[114:117], v[118:121], v[2:17]
	s_waitcnt lgkmcnt(2)
	v_mfma_f32_32x32x16_bf16 v[50:65], v[110:113], v[130:133], v[50:65]
	ds_read_b128 v[110:113], v0 offset:36960
	ds_read_b128 v[118:121], v0 offset:41568
	ds_read_b128 v[122:125], v66 offset:55392
	ds_read_b128 v[126:129], v66 offset:60000
	s_waitcnt vmcnt(9)
	ds_write_b128 v67, v[86:89] offset:9216
	s_waitcnt vmcnt(8)
	ds_write_b128 v67, v[94:97] offset:27648
	v_mfma_f32_32x32x16_bf16 v[18:33], v[114:117], v[130:133], v[18:33]
	global_load_dwordx4 v[86:89], v69, s[2:3] offset:1408
	global_load_dwordx4 v[94:97], v69, s[4:5] offset:1408
	s_waitcnt lgkmcnt(3)
	v_mfma_f32_32x32x16_bf16 v[34:49], v[110:113], v[122:125], v[34:49]
	s_waitcnt vmcnt(9)
	ds_write_b128 v67, v[98:101] offset:13824
	s_waitcnt vmcnt(8)
	ds_write_b128 v67, v[102:105] offset:32256
	v_mfma_f32_32x32x16_bf16 v[2:17], v[118:121], v[122:125], v[2:17]
	s_waitcnt lgkmcnt(4)
	v_mfma_f32_32x32x16_bf16 v[50:65], v[110:113], v[126:129], v[50:65]
	v_mfma_f32_32x32x16_bf16 v[18:33], v[118:121], v[126:129], v[18:33]
	s_waitcnt lgkmcnt(0)
	s_barrier
	ds_read_b128 v[98:101], v0
	ds_read_b128 v[102:105], v66 offset:18432
	ds_read_b128 v[110:113], v0 offset:32
	ds_read_b128 v[114:117], v66 offset:18464
	ds_read_b128 v[118:121], v0 offset:4608
	ds_read_b128 v[122:125], v0 offset:4640
	s_waitcnt lgkmcnt(4)
	v_mfma_f32_32x32x16_bf16 v[34:49], v[98:101], v[102:105], v[34:49]
	s_waitcnt lgkmcnt(1)
	v_mfma_f32_32x32x16_bf16 v[2:17], v[118:121], v[102:105], v[2:17]
	ds_read_b128 v[102:105], v66 offset:23040
	ds_read_b128 v[126:129], v66 offset:23072
	s_waitcnt lgkmcnt(1)
	v_mfma_f32_32x32x16_bf16 v[50:65], v[98:101], v[102:105], v[50:65]
	global_load_dwordx4 v[98:101], v72, s[2:3] offset:1536
	global_load_dwordx4 v[130:133], v72, s[4:5] offset:1536
	s_waitcnt vmcnt(9)
	ds_write_b128 v67, v[74:77] offset:36864
	s_waitcnt vmcnt(8)
	ds_write_b128 v67, v[134:137] offset:55296
	v_mfma_f32_32x32x16_bf16 v[18:33], v[118:121], v[102:105], v[18:33]
	global_load_dwordx4 v[74:77], v71, s[2:3] offset:1536
	global_load_dwordx4 v[102:105], v71, s[4:5] offset:1536
	v_mfma_f32_32x32x16_bf16 v[34:49], v[110:113], v[114:117], v[34:49]
	v_mfma_f32_32x32x16_bf16 v[2:17], v[122:125], v[114:117], v[2:17]
	s_waitcnt lgkmcnt(2)
	v_mfma_f32_32x32x16_bf16 v[50:65], v[110:113], v[126:129], v[50:65]
	ds_read_b128 v[110:113], v0 offset:64
	ds_read_b128 v[114:117], v0 offset:4672
	ds_read_b128 v[118:121], v66 offset:18496
	ds_read_b128 v[134:137], v66 offset:23104
	s_waitcnt vmcnt(9)
	ds_write_b128 v67, v[78:81] offset:41472
	s_waitcnt vmcnt(8)
	ds_write_b128 v67, v[106:109] offset:59904
	v_mfma_f32_32x32x16_bf16 v[18:33], v[122:125], v[126:129], v[18:33]
	global_load_dwordx4 v[78:81], v70, s[2:3] offset:1536
	global_load_dwordx4 v[106:109], v70, s[4:5] offset:1536
	s_waitcnt lgkmcnt(3)
	v_mfma_f32_32x32x16_bf16 v[34:49], v[110:113], v[118:121], v[34:49]
	v_mfma_f32_32x32x16_bf16 v[2:17], v[114:117], v[118:121], v[2:17]
	s_waitcnt lgkmcnt(2)
	v_mfma_f32_32x32x16_bf16 v[50:65], v[110:113], v[134:137], v[50:65]
	ds_read_b128 v[110:113], v0 offset:96
	ds_read_b128 v[118:121], v0 offset:4704
	ds_read_b128 v[122:125], v66 offset:18528
	ds_read_b128 v[126:129], v66 offset:23136
	s_waitcnt vmcnt(9)
	ds_write_b128 v67, v[82:85] offset:46080
	s_waitcnt vmcnt(8)
	ds_write_b128 v67, v[90:93] offset:64512
	v_mfma_f32_32x32x16_bf16 v[18:33], v[114:117], v[134:137], v[18:33]
	global_load_dwordx4 v[82:85], v69, s[2:3] offset:1536
	global_load_dwordx4 v[90:93], v69, s[4:5] offset:1536
	s_waitcnt lgkmcnt(3)
	v_mfma_f32_32x32x16_bf16 v[34:49], v[110:113], v[122:125], v[34:49]
	s_waitcnt vmcnt(9)
	ds_write_b128 v67, v[86:89] offset:50688
	s_waitcnt vmcnt(8)
	ds_write_b128 v68, v[94:97] offset:13824
	v_mfma_f32_32x32x16_bf16 v[2:17], v[118:121], v[122:125], v[2:17]
	s_waitcnt lgkmcnt(4)
	v_mfma_f32_32x32x16_bf16 v[50:65], v[110:113], v[126:129], v[50:65]
	v_mfma_f32_32x32x16_bf16 v[18:33], v[118:121], v[126:129], v[18:33]
	s_waitcnt lgkmcnt(0)
	s_barrier
; #define GL1_(RA, RB, i) { RA[i] = *(const u32x4*)(ap + (aoff + (i) * astep)); if ((i) < NB) RB[(i) < NB ? (i) : 0] = *(const u32x4*)(bp + (boff + (i) * bstep)); }
; #define LS1_(RA, RB, ST, i) { char* sn_ = lds + (ST) * STAGE; *(u32x4*)(sn_ + wofs + (i) * 32 * LROW) = RA[i]; \
;                               if ((i) < NB) *(u32x4*)(sn_ + STAGE_OP + wofs + (i) * 32 * LROW) = RB[(i) < NB ? (i) : 0]; }
; template <int NJ> DI void gemm_mainloop_reg(const bf16_t* __restrict__ A, int lda, const bf16_t* __restrict__ Bt, int ldb, int K, f32x16 (&acc)[2][NJ], char* lds) {
;     ...
; #pragma unroll
;   for (int i = 0; i < 4; ++i) GL1_(ra0, rb0, i);
;   ap += 128; bp += 128;
; #pragma unroll
;   for (int i = 0; i < 4; ++i) GL1_(ra1, rb1, i);
;   ap += 128; bp += 128;
; #pragma unroll
;   for (int i = 0; i < 4; ++i) LS1_(ra0, rb0, 0, i);
;   __syncthreads();
;   const int nk = K >> 6;
;   for (int kt = 0; kt < nk; kt += 2) {
;     const bool l0 = (kt + 2 < nk), l1 = (kt + 3 < nk);
;     STEP_(0, l0, ra0, rb0, true, ra1, rb1);
;     __syncthreads();
;     STEP_(1, l1, ra1, rb1, l0, ra0, rb0);
;     __syncthreads();
;   }
	ds_read_b128 v[86:89], v0 offset:36864
	ds_read_b128 v[94:97], v66 offset:55296
	ds_read_b128 v[110:113], v0 offset:36896
	ds_read_b128 v[114:117], v66 offset:55328
	ds_read_b128 v[118:121], v0 offset:41472
	ds_read_b128 v[122:125], v0 offset:41504
	s_waitcnt lgkmcnt(4)
	v_mfma_f32_32x32x16_bf16 v[34:49], v[86:89], v[94:97], v[34:49]
	s_waitcnt lgkmcnt(1)
	v_mfma_f32_32x32x16_bf16 v[2:17], v[118:121], v[94:97], v[2:17]
	ds_read_b128 v[94:97], v66 offset:59904
	ds_read_b128 v[126:129], v66 offset:59936
	s_waitcnt lgkmcnt(1)
	v_mfma_f32_32x32x16_bf16 v[50:65], v[86:89], v[94:97], v[50:65]
	global_load_dwordx4 v[86:89], v72, s[2:3] offset:1664
	global_load_dwordx4 v[134:137], v72, s[4:5] offset:1664
	s_waitcnt vmcnt(9)
	ds_write_b128 v67, v[98:101]
	s_waitcnt vmcnt(8)
	ds_write_b128 v67, v[130:133] offset:18432
	v_mfma_f32_32x32x16_bf16 v[18:33], v[118:121], v[94:97], v[18:33]
	global_load_dwordx4 v[94:97], v71, s[2:3] offset:1664
	global_load_dwordx4 v[98:101], v71, s[4:5] offset:1664
	v_mfma_f32_32x32x16_bf16 v[34:49], v[110:113], v[114:117], v[34:49]
	v_mfma_f32_32x32x16_bf16 v[2:17], v[122:125], v[114:117], v[2:17]
	s_waitcnt lgkmcnt(2)
	v_mfma_f32_32x32x16_bf16 v[50:65], v[110:113], v[126:129], v[50:65]
	ds_read_b128 v[110:113], v0 offset:36928
	ds_read_b128 v[114:117], v0 offset:41536
	ds_read_b128 v[118:121], v66 offset:55360
	ds_read_b128 v[130:133], v66 offset:59968
	s_waitcnt vmcnt(9)
	ds_write_b128 v67, v[74:77] offset:4608
	s_waitcnt vmcnt(8)
	ds_write_b128 v67, v[102:105] offset:23040
	v_mfma_f32_32x32x16_bf16 v[18:33], v[122:125], v[126:129], v[18:33]
	global_load_dwordx4 v[74:77], v70, s[2:3] offset:1664
	global_load_dwordx4 v[102:105], v70, s[4:5] offset:1664
	s_waitcnt lgkmcnt(3)
	v_mfma_f32_32x32x16_bf16 v[34:49], v[110:113], v[118:121], v[34:49]
	v_mfma_f32_32x32x16_bf16 v[2:17], v[114:117], v[118:121], v[2:17]
	s_waitcnt lgkmcnt(2)
	v_mfma_f32_32x32x16_bf16 v[50:65], v[110:113], v[130:133], v[50:65]
	ds_read_b128 v[110:113], v0 offset:36960
	ds_read_b128 v[118:121], v0 offset:41568
	ds_read_b128 v[122:125], v66 offset:55392
	ds_read_b128 v[126:129], v66 offset:60000
	s_waitcnt vmcnt(9)
	ds_write_b128 v67, v[78:81] offset:9216
	s_waitcnt vmcnt(8)
	ds_write_b128 v67, v[106:109] offset:27648
	v_mfma_f32_32x32x16_bf16 v[18:33], v[114:117], v[130:133], v[18:33]
	global_load_dwordx4 v[78:81], v69, s[2:3] offset:1664
	global_load_dwordx4 v[106:109], v69, s[4:5] offset:1664
	s_waitcnt lgkmcnt(3)
	v_mfma_f32_32x32x16_bf16 v[34:49], v[110:113], v[122:125], v[34:49]
	s_waitcnt vmcnt(9)
	ds_write_b128 v67, v[82:85] offset:13824
	s_waitcnt vmcnt(8)
	ds_write_b128 v67, v[90:93] offset:32256
	v_mfma_f32_32x32x16_bf16 v[2:17], v[118:121], v[122:125], v[2:17]
	s_waitcnt lgkmcnt(4)
	v_mfma_f32_32x32x16_bf16 v[50:65], v[110:113], v[126:129], v[50:65]
	v_mfma_f32_32x32x16_bf16 v[18:33], v[118:121], v[126:129], v[18:33]
	s_waitcnt lgkmcnt(0)
	s_barrier
	ds_read_b128 v[82:85], v0
	ds_read_b128 v[90:93], v66 offset:18432
	ds_read_b128 v[110:113], v0 offset:32
	ds_read_b128 v[114:117], v66 offset:18464
	ds_read_b128 v[118:121], v0 offset:4608
	ds_read_b128 v[122:125], v0 offset:4640
	s_waitcnt lgkmcnt(4)
	v_mfma_f32_32x32x16_bf16 v[34:49], v[82:85], v[90:93], v[34:49]
	s_waitcnt lgkmcnt(1)
	v_mfma_f32_32x32x16_bf16 v[2:17], v[118:121], v[90:93], v[2:17]
	ds_read_b128 v[90:93], v66 offset:23040
	ds_read_b128 v[126:129], v66 offset:23072
	s_waitcnt lgkmcnt(1)
	v_mfma_f32_32x32x16_bf16 v[50:65], v[82:85], v[90:93], v[50:65]
	global_load_dwordx4 v[82:85], v72, s[2:3] offset:1792
	global_load_dwordx4 v[130:133], v72, s[4:5] offset:1792
	s_waitcnt vmcnt(9)
	ds_write_b128 v67, v[86:89] offset:36864
	s_waitcnt vmcnt(8)
	ds_write_b128 v67, v[134:137] offset:55296
	v_mfma_f32_32x32x16_bf16 v[18:33], v[118:121], v[90:93], v[18:33]
	global_load_dwordx4 v[86:89], v71, s[2:3] offset:1792
	global_load_dwordx4 v[90:93], v71, s[4:5] offset:1792
	v_mfma_f32_32x32x16_bf16 v[34:49], v[110:113], v[114:117], v[34:49]
	v_mfma_f32_32x32x16_bf16 v[2:17], v[122:125], v[114:117], v[2:17]
	s_waitcnt lgkmcnt(2)
	v_mfma_f32_32x32x16_bf16 v[50:65], v[110:113], v[126:129], v[50:65]
	ds_read_b128 v[110:113], v0 offset:64
	ds_read_b128 v[114:117], v0 offset:4672
	ds_read_b128 v[118:121], v66 offset:18496
	ds_read_b128 v[134:137], v66 offset:23104
	s_waitcnt vmcnt(9)
	ds_write_b128 v67, v[94:97] offset:41472
	s_waitcnt vmcnt(8)
	ds_write_b128 v67, v[98:101] offset:59904
	v_mfma_f32_32x32x16_bf16 v[18:33], v[122:125], v[126:129], v[18:33]
	global_load_dwordx4 v[94:97], v70, s[2:3] offset:1792
	global_load_dwordx4 v[98:101], v70, s[4:5] offset:1792
	s_waitcnt lgkmcnt(3)
	v_mfma_f32_32x32x16_bf16 v[34:49], v[110:113], v[118:121], v[34:49]
	v_mfma_f32_32x32x16_bf16 v[2:17], v[114:117], v[118:121], v[2:17]
	s_waitcnt lgkmcnt(2)
	v_mfma_f32_32x32x16_bf16 v[50:65], v[110:113], v[134:137], v[50:65]
	ds_read_b128 v[110:113], v0 offset:96
	ds_read_b128 v[118:121], v0 offset:4704
	ds_read_b128 v[122:125], v66 offset:18528
	ds_read_b128 v[126:129], v66 offset:23136
	s_waitcnt vmcnt(9)
	ds_write_b128 v67, v[74:77] offset:46080
	s_waitcnt vmcnt(8)
	ds_write_b128 v67, v[102:105] offset:64512
	v_mfma_f32_32x32x16_bf16 v[18:33], v[114:117], v[134:137], v[18:33]
	global_load_dwordx4 v[74:77], v69, s[2:3] offset:1792
	global_load_dwordx4 v[102:105], v69, s[4:5] offset:1792
	s_waitcnt lgkmcnt(3)
	v_mfma_f32_32x32x16_bf16 v[34:49], v[110:113], v[122:125], v[34:49]
	s_waitcnt vmcnt(9)
	ds_write_b128 v67, v[78:81] offset:50688
	s_waitcnt vmcnt(8)
	ds_write_b128 v68, v[106:109] offset:13824
	v_mfma_f32_32x32x16_bf16 v[2:17], v[118:121], v[122:125], v[2:17]
	s_waitcnt lgkmcnt(4)
	v_mfma_f32_32x32x16_bf16 v[50:65], v[110:113], v[126:129], v[50:65]
	v_mfma_f32_32x32x16_bf16 v[18:33], v[118:121], v[126:129], v[18:33]
	s_waitcnt lgkmcnt(0)
	s_barrier
; #define GL1_(RA, RB, i) { RA[i] = *(const u32x4*)(ap + (aoff + (i) * astep)); if ((i) < NB) RB[(i) < NB ? (i) : 0] = *(const u32x4*)(bp + (boff + (i) * bstep)); }
; #define LS1_(RA, RB, ST, i) { char* sn_ = lds + (ST) * STAGE; *(u32x4*)(sn_ + wofs + (i) * 32 * LROW) = RA[i]; \
;                               if ((i) < NB) *(u32x4*)(sn_ + STAGE_OP + wofs + (i) * 32 * LROW) = RB[(i) < NB ? (i) : 0]; }
; template <int NJ> DI void gemm_mainloop_reg(const bf16_t* __restrict__ A, int lda, const bf16_t* __restrict__ Bt, int ldb, int K, f32x16 (&acc)[2][NJ], char* lds) {
;     ...
; #pragma unroll
;   for (int i = 0; i < 4; ++i) GL1_(ra0, rb0, i);
;   ap += 128; bp += 128;
; #pragma unroll
;   for (int i = 0; i < 4; ++i) GL1_(ra1, rb1, i);
;   ap += 128; bp += 128;
; #pragma unroll
;   for (int i = 0; i < 4; ++i) LS1_(ra0, rb0, 0, i);
;   __syncthreads();
;   const int nk = K >> 6;
;   for (int kt = 0; kt < nk; kt += 2) {
;     const bool l0 = (kt + 2 < nk), l1 = (kt + 3 < nk);
;     STEP_(0, l0, ra0, rb0, true, ra1, rb1);
;     __syncthreads();
;     STEP_(1, l1, ra1, rb1, l0, ra0, rb0);
;     __syncthreads();
;   }
	ds_read_b128 v[78:81], v0 offset:36864
	ds_read_b128 v[106:109], v66 offset:55296
	ds_read_b128 v[110:113], v0 offset:41472
	s_waitcnt lgkmcnt(1)
	v_mfma_f32_32x32x16_bf16 v[34:49], v[78:81], v[106:109], v[34:49]
	s_waitcnt lgkmcnt(0)
	v_mfma_f32_32x32x16_bf16 v[2:17], v[110:113], v[106:109], v[2:17]
	ds_read_b128 v[106:109], v66 offset:59904
	s_waitcnt lgkmcnt(0)
	v_mfma_f32_32x32x16_bf16 v[50:65], v[78:81], v[106:109], v[50:65]
	global_load_dwordx4 v[78:81], v72, s[2:3] offset:1920
	global_load_dwordx4 v[114:117], v72, s[4:5] offset:1920
	ds_read_b128 v[118:121], v0 offset:36896
	ds_read_b128 v[122:125], v66 offset:55328
	ds_read_b128 v[126:129], v0 offset:41504
	ds_read_b128 v[134:137], v66 offset:59936
	s_waitcnt vmcnt(9)
	ds_write_b128 v67, v[82:85]
	s_waitcnt vmcnt(8)
	ds_write_b128 v67, v[130:133] offset:18432
	v_mfma_f32_32x32x16_bf16 v[18:33], v[110:113], v[106:109], v[18:33]
	global_load_dwordx4 v[82:85], v71, s[2:3] offset:1920
	global_load_dwordx4 v[106:109], v71, s[4:5] offset:1920
	s_waitcnt lgkmcnt(4)
	v_mfma_f32_32x32x16_bf16 v[34:49], v[118:121], v[122:125], v[34:49]
	s_waitcnt lgkmcnt(3)
	v_mfma_f32_32x32x16_bf16 v[2:17], v[126:129], v[122:125], v[2:17]
	s_waitcnt lgkmcnt(2)
	v_mfma_f32_32x32x16_bf16 v[50:65], v[118:121], v[134:137], v[50:65]
	ds_read_b128 v[110:113], v0 offset:36928
	ds_read_b128 v[118:121], v0 offset:41536
	ds_read_b128 v[122:125], v66 offset:55360
	ds_read_b128 v[130:133], v66 offset:59968
	s_waitcnt vmcnt(9)
	ds_write_b128 v67, v[86:89] offset:4608
	s_waitcnt vmcnt(8)
	ds_write_b128 v67, v[90:93] offset:23040
	v_mfma_f32_32x32x16_bf16 v[18:33], v[126:129], v[134:137], v[18:33]
	global_load_dwordx4 v[86:89], v70, s[2:3] offset:1920
	s_nop 0
	global_load_dwordx4 v[70:73], v70, s[4:5] offset:1920
	s_waitcnt lgkmcnt(3)
	v_mfma_f32_32x32x16_bf16 v[34:49], v[110:113], v[122:125], v[34:49]
	v_mfma_f32_32x32x16_bf16 v[2:17], v[118:121], v[122:125], v[2:17]
	s_waitcnt lgkmcnt(2)
	v_mfma_f32_32x32x16_bf16 v[50:65], v[110:113], v[130:133], v[50:65]
	ds_read_b128 v[90:93], v0 offset:36960
	ds_read_b128 v[110:113], v0 offset:41568
	ds_read_b128 v[122:125], v66 offset:55392
	ds_read_b128 v[126:129], v66 offset:60000
	s_waitcnt vmcnt(9)
	ds_write_b128 v67, v[94:97] offset:9216
	s_waitcnt vmcnt(8)
	ds_write_b128 v67, v[98:101] offset:27648
	v_mfma_f32_32x32x16_bf16 v[18:33], v[118:121], v[130:133], v[18:33]
	s_waitcnt lgkmcnt(3)
	v_mfma_f32_32x32x16_bf16 v[34:49], v[90:93], v[122:125], v[34:49]
	s_waitcnt lgkmcnt(2)
	v_mfma_f32_32x32x16_bf16 v[50:65], v[90:93], v[126:129], v[50:65]
	global_load_dwordx4 v[90:93], v69, s[2:3] offset:1920
	global_load_dwordx4 v[94:97], v69, s[4:5] offset:1920
	s_waitcnt vmcnt(9)
	ds_write_b128 v67, v[74:77] offset:13824
	s_waitcnt vmcnt(8)
	ds_write_b128 v67, v[102:105] offset:32256
	v_mfma_f32_32x32x16_bf16 v[2:17], v[110:113], v[122:125], v[2:17]
	v_mfma_f32_32x32x16_bf16 v[18:33], v[110:113], v[126:129], v[18:33]
	s_waitcnt lgkmcnt(0)
	s_barrier
	ds_read_b128 v[74:77], v0
	ds_read_b128 v[98:101], v66 offset:18432
	ds_read_b128 v[102:105], v0 offset:4608
	s_waitcnt lgkmcnt(1)
	v_mfma_f32_32x32x16_bf16 v[34:49], v[74:77], v[98:101], v[34:49]
	s_waitcnt lgkmcnt(0)
	v_mfma_f32_32x32x16_bf16 v[2:17], v[102:105], v[98:101], v[2:17]
	ds_read_b128 v[98:101], v66 offset:23040
	s_waitcnt lgkmcnt(0)
	v_mfma_f32_32x32x16_bf16 v[50:65], v[74:77], v[98:101], v[50:65]
	ds_read_b128 v[74:77], v0 offset:32
	ds_read_b128 v[110:113], v66 offset:18464
	ds_read_b128 v[118:121], v0 offset:4640
	ds_read_b128 v[122:125], v66 offset:23072
	s_waitcnt vmcnt(7)
	ds_write_b128 v67, v[78:81] offset:36864
	s_waitcnt vmcnt(6)
	ds_write_b128 v67, v[114:117] offset:55296
	v_mfma_f32_32x32x16_bf16 v[18:33], v[102:105], v[98:101], v[18:33]
	s_waitcnt lgkmcnt(4)
	v_mfma_f32_32x32x16_bf16 v[34:49], v[74:77], v[110:113], v[34:49]
	s_waitcnt lgkmcnt(2)
	v_mfma_f32_32x32x16_bf16 v[50:65], v[74:77], v[122:125], v[50:65]
	ds_read_b128 v[74:77], v0 offset:64
	ds_read_b128 v[78:81], v0 offset:4672
	ds_read_b128 v[98:101], v66 offset:18496
	ds_read_b128 v[102:105], v66 offset:23104
	s_waitcnt vmcnt(5)
	ds_write_b128 v67, v[82:85] offset:41472
	s_waitcnt vmcnt(4)
	ds_write_b128 v67, v[106:109] offset:59904
	v_mfma_f32_32x32x16_bf16 v[2:17], v[118:121], v[110:113], v[2:17]
	v_mfma_f32_32x32x16_bf16 v[18:33], v[118:121], v[122:125], v[18:33]
	s_waitcnt lgkmcnt(3)
	v_mfma_f32_32x32x16_bf16 v[34:49], v[74:77], v[98:101], v[34:49]
	v_mfma_f32_32x32x16_bf16 v[2:17], v[78:81], v[98:101], v[2:17]
	s_waitcnt lgkmcnt(2)
	v_mfma_f32_32x32x16_bf16 v[50:65], v[74:77], v[102:105], v[50:65]
	ds_read_b128 v[74:77], v0 offset:96
	ds_read_b128 v[82:85], v0 offset:4704
	ds_read_b128 v[98:101], v66 offset:18528
	ds_read_b128 v[106:109], v66 offset:23136
	s_waitcnt vmcnt(3)
	ds_write_b128 v67, v[86:89] offset:46080
	s_waitcnt vmcnt(2)
	ds_write_b128 v67, v[70:73] offset:64512
	v_mfma_f32_32x32x16_bf16 v[18:33], v[78:81], v[102:105], v[18:33]
	s_waitcnt lgkmcnt(3)
	v_mfma_f32_32x32x16_bf16 v[34:49], v[74:77], v[98:101], v[34:49]
	s_waitcnt vmcnt(1)
	ds_write_b128 v67, v[90:93] offset:50688
	s_waitcnt vmcnt(0)
	ds_write_b128 v68, v[94:97] offset:13824
	v_mfma_f32_32x32x16_bf16 v[2:17], v[82:85], v[98:101], v[2:17]
	s_waitcnt lgkmcnt(4)
	v_mfma_f32_32x32x16_bf16 v[50:65], v[74:77], v[106:109], v[50:65]
	v_mfma_f32_32x32x16_bf16 v[18:33], v[82:85], v[106:109], v[18:33]
	s_waitcnt lgkmcnt(0)
	s_barrier
; DI int tid_() { int t = threadIdx.x; asm volatile("" : "+v"(t)); return t; }
; #define GL1_(RA, RB, i) { RA[i] = *(const u32x4*)(ap + (aoff + (i) * astep)); if ((i) < NB) RB[(i) < NB ? (i) : 0] = *(const u32x4*)(bp + (boff + (i) * bstep)); }
; #define LS1_(RA, RB, ST, i) { char* sn_ = lds + (ST) * STAGE; *(u32x4*)(sn_ + wofs + (i) * 32 * LROW) = RA[i]; \
;                               if ((i) < NB) *(u32x4*)(sn_ + STAGE_OP + wofs + (i) * 32 * LROW) = RB[(i) < NB ? (i) : 0]; }
; template <int NJ> DI void gemm_mainloop_reg(const bf16_t* __restrict__ A, int lda, const bf16_t* __restrict__ Bt, int ldb, int K, f32x16 (&acc)[2][NJ], char* lds) {
;     ...
; #pragma unroll
;   for (int i = 0; i < 4; ++i) GL1_(ra0, rb0, i);
;   ap += 128; bp += 128;
; #pragma unroll
;   for (int i = 0; i < 4; ++i) GL1_(ra1, rb1, i);
;   ap += 128; bp += 128;
; #pragma unroll
;   for (int i = 0; i < 4; ++i) LS1_(ra0, rb0, 0, i);
;   __syncthreads();
;   const int nk = K >> 6;
;   for (int kt = 0; kt < nk; kt += 2) {
;     const bool l0 = (kt + 2 < nk), l1 = (kt + 3 < nk);
;     STEP_(0, l0, ra0, rb0, true, ra1, rb1);
;     __syncthreads();
;     STEP_(1, l1, ra1, rb1, l0, ra0, rb0);
;     __syncthreads();
;   }
;     ...
; }
; template <int NJ> DI void acc_to_lds(const f32x16 (&acc)[2][NJ], float* cl) {
;   const int tid = tid_(), lane = tid & 63, w = tid >> 6, wm = w >> 1, wn = w & 1, h = lane >> 5, c = lane & 31;
; #pragma unroll
;   for (int i = 0; i < 2; ++i)
; #pragma unroll
;     for (int j = 0; j < NJ; ++j)
; #pragma unroll
;       for (int r = 0; r < 16; ++r) {
;         const int row = wm * 64 + i * 32 + (r & 3) + 8 * (r >> 2) + 4 * h;
;         cl[row * CLD + wn * 32 * NJ + j * 32 + c] = acc[i][j][r];
;       }
; DI void phase_proj(const Ctx& c, bool dummy_ss = false) {
;     ...
;     const int tid = tid_(), half = __builtin_amdgcn_readfirstlane(tid >> 7), u = tid & 127;
;     if (tid < 128) rr[tid] = rsqrtf(ss[mt * 128 + tid] * (1.0f / DM) + EPS);
	ds_read_b128 v[68:71], v0 offset:36864
	ds_read_b128 v[72:75], v66 offset:55296
	ds_read_b128 v[76:79], v0 offset:41472
	s_waitcnt lgkmcnt(1)
	v_mfma_f32_32x32x16_bf16 v[34:49], v[68:71], v[72:75], v[34:49]
	s_waitcnt lgkmcnt(0)
	v_mfma_f32_32x32x16_bf16 v[2:17], v[76:79], v[72:75], v[2:17]
	ds_read_b128 v[72:75], v66 offset:59904
	s_waitcnt lgkmcnt(0)
	v_mfma_f32_32x32x16_bf16 v[50:65], v[68:71], v[72:75], v[50:65]
	ds_read_b128 v[68:71], v0 offset:36896
	ds_read_b128 v[80:83], v66 offset:55328
	ds_read_b128 v[84:87], v0 offset:41504
	ds_read_b128 v[88:91], v66 offset:59936
	v_mfma_f32_32x32x16_bf16 v[18:33], v[76:79], v[72:75], v[18:33]
	s_waitcnt lgkmcnt(2)
	v_mfma_f32_32x32x16_bf16 v[34:49], v[68:71], v[80:83], v[34:49]
	s_waitcnt lgkmcnt(1)
	v_mfma_f32_32x32x16_bf16 v[2:17], v[84:87], v[80:83], v[2:17]
	s_waitcnt lgkmcnt(0)
	v_mfma_f32_32x32x16_bf16 v[50:65], v[68:71], v[88:91], v[50:65]
	ds_read_b128 v[68:71], v0 offset:36928
	ds_read_b128 v[72:75], v0 offset:41536
	ds_read_b128 v[76:79], v66 offset:55360
	ds_read_b128 v[80:83], v66 offset:59968
	v_mfma_f32_32x32x16_bf16 v[18:33], v[84:87], v[88:91], v[18:33]
	s_waitcnt lgkmcnt(1)
	v_mfma_f32_32x32x16_bf16 v[34:49], v[68:71], v[76:79], v[34:49]
	v_mfma_f32_32x32x16_bf16 v[2:17], v[72:75], v[76:79], v[2:17]
	s_waitcnt lgkmcnt(0)
	v_mfma_f32_32x32x16_bf16 v[50:65], v[68:71], v[80:83], v[50:65]
	ds_read_b128 v[68:71], v0 offset:36960
	ds_read_b128 v[76:79], v0 offset:41568
	ds_read_b128 v[84:87], v66 offset:55392
	ds_read_b128 v[88:91], v66 offset:60000
	v_mfma_f32_32x32x16_bf16 v[18:33], v[72:75], v[80:83], v[18:33]
	s_waitcnt lgkmcnt(1)
	v_mfma_f32_32x32x16_bf16 v[34:49], v[68:71], v[84:87], v[34:49]
	v_mfma_f32_32x32x16_bf16 v[2:17], v[76:79], v[84:87], v[2:17]
	s_waitcnt lgkmcnt(0)
	v_mfma_f32_32x32x16_bf16 v[50:65], v[68:71], v[88:91], v[50:65]
	v_mfma_f32_32x32x16_bf16 v[18:33], v[76:79], v[88:91], v[18:33]
	s_setprio 0
	s_nop 0
	v_mov_b32_e32 v0, v199
	s_barrier
	v_mov_b32_e32 v134, v199
	v_lshrrev_b32_e32 v67, 3, v0
	v_lshrrev_b32_e32 v66, 1, v0
	v_and_b32_e32 v67, 4, v67
	v_and_b32_e32 v0, 0x5f, v0
	v_and_or_b32 v66, v66, s17, v67
	v_mul_lo_u32 v66, v66, s15
	v_lshlrev_b32_e32 v0, 2, v0
	v_add3_u32 v0, 0, v66, v0
	ds_write2_b32 v0, v34, v50 offset1:32
	ds_write2_b32 v0, v35, v51 offset0:132 offset1:164
	v_add_u32_e32 v34, 0x400, v0
	ds_write2_b32 v34, v36, v52 offset0:8 offset1:40
	ds_write2_b32 v34, v37, v53 offset0:140 offset1:172
	v_add_u32_e32 v34, 0x1000, v0
	ds_write2_b32 v34, v38, v54 offset0:32 offset1:64
	ds_write2_b32 v34, v39, v55 offset0:164 offset1:196
	v_add_u32_e32 v34, 0x1400, v0
	ds_write2_b32 v34, v40, v56 offset0:40 offset1:72
	ds_write2_b32 v34, v41, v57 offset0:172 offset1:204
	v_add_u32_e32 v34, 0x2000, v0
	ds_write2_b32 v34, v42, v58 offset0:64 offset1:96
	ds_write2_b32 v34, v43, v59 offset0:196 offset1:228
	v_add_u32_e32 v34, 0x2400, v0
	ds_write2_b32 v34, v44, v60 offset0:72 offset1:104
	ds_write2_b32 v34, v45, v61 offset0:204 offset1:236
	v_add_u32_e32 v34, 0x3000, v0
	ds_write2_b32 v34, v46, v62 offset0:96 offset1:128
	v_add_u32_e32 v34, 0x3200, v0
	ds_write2_b32 v34, v47, v63 offset0:100 offset1:132
	v_add_u32_e32 v34, 0x3400, v0
	ds_write2_b32 v34, v48, v64 offset0:104 offset1:136
	v_add_u32_e32 v34, 0x3600, v0
	ds_write2_b32 v34, v49, v65 offset0:108 offset1:140
	v_add_u32_e32 v34, 0x4000, v0
	ds_write2_b32 v34, v2, v18 offset0:128 offset1:160
	v_add_u32_e32 v2, 0x4400, v0
	ds_write2_b32 v2, v3, v19 offset0:4 offset1:36
	ds_write2_b32 v2, v4, v20 offset0:136 offset1:168
	v_add_u32_e32 v2, 0x4800, v0
	ds_write2_b32 v2, v5, v21 offset0:12 offset1:44
	v_add_u32_e32 v2, 0x5000, v0
	ds_write2_b32 v2, v6, v22 offset0:160 offset1:192
	v_add_u32_e32 v2, 0x5400, v0
	ds_write2_b32 v2, v7, v23 offset0:36 offset1:68
	ds_write2_b32 v2, v8, v24 offset0:168 offset1:200
	v_add_u32_e32 v2, 0x5800, v0
	ds_write2_b32 v2, v9, v25 offset0:44 offset1:76
	v_add_u32_e32 v2, 0x6000, v0
	ds_write2_b32 v2, v10, v26 offset0:192 offset1:224
	v_add_u32_e32 v2, 0x6400, v0
	ds_write2_b32 v2, v11, v27 offset0:68 offset1:100
	ds_write2_b32 v2, v12, v28 offset0:200 offset1:232
	v_add_u32_e32 v2, 0x6800, v0
	ds_write2_b32 v2, v13, v29 offset0:76 offset1:108
	v_add_u32_e32 v2, 0x7200, v0
	ds_write2_b32 v2, v14, v30 offset0:96 offset1:128
	v_add_u32_e32 v2, 0x7400, v0
	ds_write2_b32 v2, v15, v31 offset0:100 offset1:132
	v_add_u32_e32 v2, 0x7600, v0
	v_add_u32_e32 v0, 0x7800, v0
	s_movk_i32 s2, 0x80
	ds_write2_b32 v2, v16, v32 offset0:104 offset1:136
	ds_write2_b32 v0, v17, v33 offset0:108 offset1:140
	s_lshl_b32 s52, s7, 7
	v_readfirstlane_b32 s4, v134
	v_cmp_gt_i32_e32 vcc, s2, v134
	s_and_saveexec_b64 s[2:3], vcc
	s_cbranch_execz .LBB0_501
	v_add_u32_e32 v2, s52, v134
	v_ashrrev_i32_e32 v3, 31, v2
	v_lshl_add_u64 v[2:3], v[2:3], 2, s[0:1]
	global_load_dword v0, v[2:3], off
	s_mov_b32 s5, 0x800000
	s_waitcnt vmcnt(0)
	v_fmamk_f32 v0, v0, 0x3a800000, v198
	v_mul_f32_e32 v2, 0x4b800000, v0
	v_cmp_gt_f32_e32 vcc, s5, v0
	s_nop 1
	v_cndmask_b32_e32 v0, v0, v2, vcc
	v_rsq_f32_e32 v0, v0
	v_lshl_add_u32 v2, v134, 2, 0
	v_add_u32_e32 v2, 0x12000, v2
	v_mul_f32_e32 v3, 0x45800000, v0
	v_cndmask_b32_e32 v0, v0, v3, vcc
	ds_write_b32 v2, v0

; DI int tid_() { int t = threadIdx.x; asm volatile("" : "+v"(t)); return t; }
; #define GL1_(RA, RB, i) { RA[i] = *(const u32x4*)(ap + (aoff + (i) * astep)); if ((i) < NB) RB[(i) < NB ? (i) : 0] = *(const u32x4*)(bp + (boff + (i) * bstep)); }
; #define LS1_(RA, RB, ST, i) { char* sn_ = lds + (ST) * STAGE; *(u32x4*)(sn_ + wofs + (i) * 32 * LROW) = RA[i]; \
;                               if ((i) < NB) *(u32x4*)(sn_ + STAGE_OP + wofs + (i) * 32 * LROW) = RB[(i) < NB ? (i) : 0]; }
; template <int NJ> DI void gemm_mainloop_reg(const bf16_t* __restrict__ A, int lda, const bf16_t* __restrict__ Bt, int ldb, int K, f32x16 (&acc)[2][NJ], char* lds) {
;   const int tid = tid_(), lane = tid & 63, w = tid >> 6, wm = w >> 1, wn = w & 1;
;   const int lr = tid >> 3, lc = tid & 7;
;   const char* ap = (const char*)A;
;   const char* bp = (const char*)Bt;
;   const unsigned aoff = (unsigned)(lr * lda + lc * 8) * 2u, boff = (unsigned)(lr * ldb + lc * 8) * 2u;
;   const unsigned astep = (unsigned)(32 * lda) * 2u, bstep = (unsigned)(32 * ldb) * 2u;
;   constexpr int NB = 2 * NJ;
;   u32x4 ra0[4], rb0[NB], ra1[4], rb1[NB];
;   const int wofs = lr * LROW + lc * 16;
;   const int a_rd = (wm * 64 + (lane & 31)) * LROW + (lane >> 5) * 16;
;   const int b_rd = STAGE_OP + (wn * 32 * NJ + (lane & 31)) * LROW + (lane >> 5) * 16;
;     ...
; #pragma unroll
;   for (int i = 0; i < 4; ++i) GL1_(ra0, rb0, i);
;   ap += 128; bp += 128;
; #pragma unroll
;   for (int i = 0; i < 4; ++i) GL1_(ra1, rb1, i);
;   ap += 128; bp += 128;
; #pragma unroll
;   for (int i = 0; i < 4; ++i) LS1_(ra0, rb0, 0, i);
;   __syncthreads();
;   const int nk = K >> 6;
;   for (int kt = 0; kt < nk; kt += 2) {
;     const bool l0 = (kt + 2 < nk), l1 = (kt + 3 < nk);
;     STEP_(0, l0, ra0, rb0, true, ra1, rb1);
; DI void phase_resid_gemm(const Ctx& c, const bf16_t* A, int K, size_t woff, float scale, float* ssn) {
;     ...
;   for (int j_ = slot_; j_ < 16 * 8; j_ += nslot_) {
;     const int mt = xcd_ * 16 + (j_ & 15), nt = j_ >> 4;
;     f32x16 acc[2][2]; zero_acc<2>(acc);
;     gemm_mainloop_reg<2>(A + (size_t)mt * 128 * (K + PADK), K + PADK, Bt + (size_t)nt * 128 * (K + PADK), K + PADK, K, acc, c.lds);
.LBB0_1025:
	s_and_b32 s0, s26, 15
	s_lshl_b32 s35, s0, 7
	s_lshl_b32 s0, s25, 1
	s_and_b32 s72, s0, 0x700
	s_lshl_b32 s0, s25, 2
	s_and_b32 s34, s0, 0xe00
	s_and_b32 s0, s27, 15
	s_add_i32 s37, s10, s35
	s_or_b32 s0, s0, s78
	s_lshl_b32 s36, s37, 2
	s_mul_i32 s0, s0, 0x44000
	s_add_u32 s0, s74, s0
	v_mov_b32_e32 v34, v199
	s_addc_u32 s1, s75, 0
	s_lshl_b32 s2, s27, 3
	s_and_b32 s2, s2, 0x380
	v_ashrrev_i32_e32 v0, 3, v34
	v_lshlrev_b32_e32 v2, 4, v34
	v_and_b32_e32 v35, 0x70, v2
	v_mul_lo_u32 v2, v0, s9
	s_mulk_i32 s2, 0x880
	v_or_b32_e32 v72, v35, v2
	s_add_u32 s2, s4, s2
	v_add_u32_e32 v71, 0x11000, v72
	v_add_u32_e32 v70, 0x22000, v72
	v_add_u32_e32 v69, 0x33000, v72
	s_addc_u32 s3, s5, 0
	global_load_dwordx4 v[2:5], v72, s[0:1]
	global_load_dwordx4 v[6:9], v71, s[0:1]
	global_load_dwordx4 v[10:13], v70, s[0:1]
	global_load_dwordx4 v[14:17], v69, s[0:1]
	global_load_dwordx4 v[18:21], v72, s[2:3]
	global_load_dwordx4 v[22:25], v71, s[2:3]
	global_load_dwordx4 v[26:29], v70, s[2:3]
	global_load_dwordx4 v[30:33], v69, s[2:3]
	v_mul_lo_u32 v0, v0, s16
	v_lshrrev_b32_e32 v36, 1, v34
	v_and_b32_e32 v37, 31, v34
	v_add3_u32 v67, v0, v35, 0
	v_and_b32_e32 v38, 16, v36
	v_and_or_b32 v36, v36, s17, v37
	global_load_dwordx4 v[74:77], v72, s[0:1] offset:128
	global_load_dwordx4 v[78:81], v71, s[0:1] offset:128
	global_load_dwordx4 v[82:85], v70, s[0:1] offset:128
	global_load_dwordx4 v[86:89], v69, s[0:1] offset:128
	global_load_dwordx4 v[90:93], v72, s[2:3] offset:128
	global_load_dwordx4 v[94:97], v71, s[2:3] offset:128
	global_load_dwordx4 v[98:101], v70, s[2:3] offset:128
	global_load_dwordx4 v[102:105], v69, s[2:3] offset:128
	v_mul_lo_u32 v0, v36, s16
	v_add3_u32 v0, v0, v38, 0
	v_add_u32_e32 v68, 0xd800, v67
	s_waitcnt vmcnt(15)
	ds_write_b128 v67, v[2:5]
	s_waitcnt vmcnt(14)
	ds_write_b128 v67, v[6:9] offset:4608
	s_waitcnt vmcnt(13)
	ds_write_b128 v67, v[10:13] offset:9216
	s_waitcnt vmcnt(12)
	ds_write_b128 v67, v[14:17] offset:13824
	s_waitcnt vmcnt(11)
	ds_write_b128 v67, v[18:21] offset:18432
	s_waitcnt vmcnt(10)
	ds_write_b128 v67, v[22:25] offset:23040
	s_waitcnt vmcnt(9)
	ds_write_b128 v67, v[26:29] offset:27648
	s_waitcnt vmcnt(8)
	ds_write_b128 v67, v[30:33] offset:32256
	v_and_b32_e32 v2, 0x5f, v34
	v_mul_u32_u24_e32 v2, 0x90, v2
	v_add3_u32 v66, v2, v38, 0
	s_waitcnt lgkmcnt(0)
	s_barrier
	ds_read_b128 v[18:21], v0
	ds_read_b128 v[2:5], v66 offset:18432
	ds_read_b128 v[106:109], v0 offset:32
	ds_read_b128 v[110:113], v66 offset:18464
	ds_read_b128 v[22:25], v0 offset:4608
	ds_read_b128 v[114:117], v0 offset:4640
	ds_read_b128 v[26:29], v66 offset:23040
	ds_read_b128 v[118:121], v66 offset:23072
	global_load_dwordx4 v[122:125], v72, s[0:1] offset:256
	global_load_dwordx4 v[126:129], v72, s[2:3] offset:256
	s_waitcnt lgkmcnt(6)
	s_setprio 1
	s_nop 0
	v_mfma_f32_32x32x16_bf16 v[34:49], v[18:21], v[2:5], 0
	s_waitcnt vmcnt(9)
	ds_write_b128 v67, v[74:77] offset:36864
	s_waitcnt vmcnt(5)
	ds_write_b128 v67, v[90:93] offset:55296
	s_waitcnt lgkmcnt(5)
	v_mfma_f32_32x32x16_bf16 v[2:17], v[22:25], v[2:5], 0
	s_waitcnt lgkmcnt(3)
	v_mfma_f32_32x32x16_bf16 v[50:65], v[18:21], v[26:29], 0
	v_mfma_f32_32x32x16_bf16 v[18:33], v[22:25], v[26:29], 0
	global_load_dwordx4 v[74:77], v71, s[0:1] offset:256
	global_load_dwordx4 v[90:93], v71, s[2:3] offset:256
	v_mfma_f32_32x32x16_bf16 v[2:17], v[114:117], v[110:113], v[2:17]
	s_waitcnt lgkmcnt(2)
	v_mfma_f32_32x32x16_bf16 v[18:33], v[114:117], v[118:121], v[18:33]
	v_mfma_f32_32x32x16_bf16 v[34:49], v[106:109], v[110:113], v[34:49]
	v_mfma_f32_32x32x16_bf16 v[50:65], v[106:109], v[118:121], v[50:65]
	ds_read_b128 v[106:109], v0 offset:64
	ds_read_b128 v[110:113], v0 offset:4672
	ds_read_b128 v[130:133], v66 offset:18496
	ds_read_b128 v[134:137], v66 offset:23104
	ds_write_b128 v67, v[78:81] offset:41472
	s_waitcnt vmcnt(6)
	ds_write_b128 v67, v[94:97] offset:59904
	global_load_dwordx4 v[78:81], v70, s[0:1] offset:256
	global_load_dwordx4 v[94:97], v70, s[2:3] offset:256
	s_waitcnt lgkmcnt(3)
	v_mfma_f32_32x32x16_bf16 v[2:17], v[110:113], v[130:133], v[2:17]
	s_waitcnt lgkmcnt(2)
	v_mfma_f32_32x32x16_bf16 v[18:33], v[110:113], v[134:137], v[18:33]
	v_mfma_f32_32x32x16_bf16 v[34:49], v[106:109], v[130:133], v[34:49]
	v_mfma_f32_32x32x16_bf16 v[50:65], v[106:109], v[134:137], v[50:65]
	ds_read_b128 v[106:109], v0 offset:96
	ds_read_b128 v[114:117], v0 offset:4704
	ds_read_b128 v[118:121], v66 offset:18528
	ds_read_b128 v[130:133], v66 offset:23136
	ds_write_b128 v67, v[82:85] offset:46080
	s_waitcnt vmcnt(7)
	ds_write_b128 v67, v[98:101] offset:64512
	global_load_dwordx4 v[82:85], v69, s[0:1] offset:256
	global_load_dwordx4 v[98:101], v69, s[2:3] offset:256
	s_waitcnt lgkmcnt(3)
	v_mfma_f32_32x32x16_bf16 v[2:17], v[114:117], v[118:121], v[2:17]
	ds_write_b128 v67, v[86:89] offset:50688
	s_waitcnt vmcnt(8)
	ds_write_b128 v68, v[102:105] offset:13824
	s_waitcnt lgkmcnt(4)
	v_mfma_f32_32x32x16_bf16 v[18:33], v[114:117], v[130:133], v[18:33]
	v_mfma_f32_32x32x16_bf16 v[34:49], v[106:109], v[118:121], v[34:49]
	v_mfma_f32_32x32x16_bf16 v[50:65], v[106:109], v[130:133], v[50:65]
	s_waitcnt lgkmcnt(0)
	s_barrier
; #define GL1_(RA, RB, i) { RA[i] = *(const u32x4*)(ap + (aoff + (i) * astep)); if ((i) < NB) RB[(i) < NB ? (i) : 0] = *(const u32x4*)(bp + (boff + (i) * bstep)); }
; #define LS1_(RA, RB, ST, i) { char* sn_ = lds + (ST) * STAGE; *(u32x4*)(sn_ + wofs + (i) * 32 * LROW) = RA[i]; \
;                               if ((i) < NB) *(u32x4*)(sn_ + STAGE_OP + wofs + (i) * 32 * LROW) = RB[(i) < NB ? (i) : 0]; }
; template <int NJ> DI void gemm_mainloop_reg(const bf16_t* __restrict__ A, int lda, const bf16_t* __restrict__ Bt, int ldb, int K, f32x16 (&acc)[2][NJ], char* lds) {
;     ...
; #pragma unroll
;   for (int i = 0; i < 4; ++i) GL1_(ra0, rb0, i);
;   ap += 128; bp += 128;
; #pragma unroll
;   for (int i = 0; i < 4; ++i) GL1_(ra1, rb1, i);
;   ap += 128; bp += 128;
; #pragma unroll
;   for (int i = 0; i < 4; ++i) LS1_(ra0, rb0, 0, i);
;   __syncthreads();
;   const int nk = K >> 6;
;   for (int kt = 0; kt < nk; kt += 2) {
;     const bool l0 = (kt + 2 < nk), l1 = (kt + 3 < nk);
;     STEP_(0, l0, ra0, rb0, true, ra1, rb1);
;     __syncthreads();
;     STEP_(1, l1, ra1, rb1, l0, ra0, rb0);
;     __syncthreads();
;   }
	ds_read_b128 v[86:89], v0 offset:36864
	ds_read_b128 v[102:105], v66 offset:55296
	ds_read_b128 v[106:109], v0 offset:36896
	ds_read_b128 v[110:113], v66 offset:55328
	ds_read_b128 v[114:117], v0 offset:41472
	ds_read_b128 v[118:121], v0 offset:41504
	s_waitcnt lgkmcnt(4)
	v_mfma_f32_32x32x16_bf16 v[34:49], v[86:89], v[102:105], v[34:49]
	s_waitcnt lgkmcnt(1)
	v_mfma_f32_32x32x16_bf16 v[2:17], v[114:117], v[102:105], v[2:17]
	ds_read_b128 v[102:105], v66 offset:59904
	ds_read_b128 v[130:133], v66 offset:59936
	s_waitcnt lgkmcnt(1)
	v_mfma_f32_32x32x16_bf16 v[50:65], v[86:89], v[102:105], v[50:65]
	global_load_dwordx4 v[86:89], v72, s[0:1] offset:384
	global_load_dwordx4 v[134:137], v72, s[2:3] offset:384
	s_waitcnt vmcnt(9)
	ds_write_b128 v67, v[122:125]
	s_waitcnt vmcnt(8)
	ds_write_b128 v67, v[126:129] offset:18432
	v_mfma_f32_32x32x16_bf16 v[18:33], v[114:117], v[102:105], v[18:33]
	v_mfma_f32_32x32x16_bf16 v[34:49], v[106:109], v[110:113], v[34:49]
	s_waitcnt lgkmcnt(2)
	v_mfma_f32_32x32x16_bf16 v[50:65], v[106:109], v[130:133], v[50:65]
	global_load_dwordx4 v[102:105], v71, s[0:1] offset:384
	global_load_dwordx4 v[106:109], v71, s[2:3] offset:384
	v_mfma_f32_32x32x16_bf16 v[2:17], v[118:121], v[110:113], v[2:17]
	ds_read_b128 v[110:113], v0 offset:36928
	ds_read_b128 v[114:117], v0 offset:41536
	ds_read_b128 v[122:125], v66 offset:55360
	ds_read_b128 v[126:129], v66 offset:59968
	s_waitcnt vmcnt(9)
	ds_write_b128 v67, v[74:77] offset:4608
	s_waitcnt vmcnt(8)
	ds_write_b128 v67, v[90:93] offset:23040
	v_mfma_f32_32x32x16_bf16 v[18:33], v[118:121], v[130:133], v[18:33]
	global_load_dwordx4 v[74:77], v70, s[0:1] offset:384
	global_load_dwordx4 v[90:93], v70, s[2:3] offset:384
	s_waitcnt lgkmcnt(3)
	v_mfma_f32_32x32x16_bf16 v[2:17], v[114:117], v[122:125], v[2:17]
	s_waitcnt lgkmcnt(2)
	v_mfma_f32_32x32x16_bf16 v[18:33], v[114:117], v[126:129], v[18:33]
	v_mfma_f32_32x32x16_bf16 v[34:49], v[110:113], v[122:125], v[34:49]
	v_mfma_f32_32x32x16_bf16 v[50:65], v[110:113], v[126:129], v[50:65]
	ds_read_b128 v[110:113], v0 offset:36960
	ds_read_b128 v[118:121], v0 offset:41568
	ds_read_b128 v[122:125], v66 offset:55392
	ds_read_b128 v[130:133], v66 offset:60000
	s_waitcnt vmcnt(9)
	ds_write_b128 v67, v[78:81] offset:9216
	s_waitcnt vmcnt(8)
	ds_write_b128 v67, v[94:97] offset:27648
	global_load_dwordx4 v[78:81], v69, s[0:1] offset:384
	global_load_dwordx4 v[94:97], v69, s[2:3] offset:384
	s_waitcnt lgkmcnt(3)
	v_mfma_f32_32x32x16_bf16 v[2:17], v[118:121], v[122:125], v[2:17]
	s_waitcnt vmcnt(9)
	ds_write_b128 v67, v[82:85] offset:13824
	s_waitcnt vmcnt(8)
	ds_write_b128 v67, v[98:101] offset:32256
	s_waitcnt lgkmcnt(4)
	v_mfma_f32_32x32x16_bf16 v[18:33], v[118:121], v[130:133], v[18:33]
	v_mfma_f32_32x32x16_bf16 v[34:49], v[110:113], v[122:125], v[34:49]
	v_mfma_f32_32x32x16_bf16 v[50:65], v[110:113], v[130:133], v[50:65]
	s_waitcnt lgkmcnt(0)
	s_barrier
	ds_read_b128 v[82:85], v0
	ds_read_b128 v[98:101], v66 offset:18432
	ds_read_b128 v[110:113], v0 offset:32
	ds_read_b128 v[114:117], v66 offset:18464
	ds_read_b128 v[118:121], v0 offset:4608
	ds_read_b128 v[122:125], v0 offset:4640
	s_waitcnt lgkmcnt(4)
	v_mfma_f32_32x32x16_bf16 v[34:49], v[82:85], v[98:101], v[34:49]
	s_waitcnt lgkmcnt(1)
	v_mfma_f32_32x32x16_bf16 v[2:17], v[118:121], v[98:101], v[2:17]
	ds_read_b128 v[98:101], v66 offset:23040
	ds_read_b128 v[126:129], v66 offset:23072
	s_waitcnt lgkmcnt(1)
	v_mfma_f32_32x32x16_bf16 v[50:65], v[82:85], v[98:101], v[50:65]
	global_load_dwordx4 v[82:85], v72, s[0:1] offset:512
	global_load_dwordx4 v[130:133], v72, s[2:3] offset:512
	s_waitcnt vmcnt(9)
	ds_write_b128 v67, v[86:89] offset:36864
	s_waitcnt vmcnt(8)
	ds_write_b128 v67, v[134:137] offset:55296
	v_mfma_f32_32x32x16_bf16 v[18:33], v[118:121], v[98:101], v[18:33]
	global_load_dwordx4 v[86:89], v71, s[0:1] offset:512
	global_load_dwordx4 v[98:101], v71, s[2:3] offset:512
	v_mfma_f32_32x32x16_bf16 v[2:17], v[122:125], v[114:117], v[2:17]
	s_waitcnt lgkmcnt(2)
	v_mfma_f32_32x32x16_bf16 v[18:33], v[122:125], v[126:129], v[18:33]
	v_mfma_f32_32x32x16_bf16 v[34:49], v[110:113], v[114:117], v[34:49]
	v_mfma_f32_32x32x16_bf16 v[50:65], v[110:113], v[126:129], v[50:65]
	ds_read_b128 v[110:113], v0 offset:64
	ds_read_b128 v[114:117], v0 offset:4672
	ds_read_b128 v[118:121], v66 offset:18496
	ds_read_b128 v[134:137], v66 offset:23104
	s_waitcnt vmcnt(9)
	ds_write_b128 v67, v[102:105] offset:41472
	s_waitcnt vmcnt(8)
	ds_write_b128 v67, v[106:109] offset:59904
	global_load_dwordx4 v[102:105], v70, s[0:1] offset:512
	global_load_dwordx4 v[106:109], v70, s[2:3] offset:512
	s_waitcnt lgkmcnt(3)
	v_mfma_f32_32x32x16_bf16 v[2:17], v[114:117], v[118:121], v[2:17]
	s_waitcnt lgkmcnt(2)
	v_mfma_f32_32x32x16_bf16 v[18:33], v[114:117], v[134:137], v[18:33]
	v_mfma_f32_32x32x16_bf16 v[34:49], v[110:113], v[118:121], v[34:49]
	v_mfma_f32_32x32x16_bf16 v[50:65], v[110:113], v[134:137], v[50:65]
	ds_read_b128 v[110:113], v0 offset:96
	ds_read_b128 v[118:121], v0 offset:4704
	ds_read_b128 v[122:125], v66 offset:18528
	ds_read_b128 v[126:129], v66 offset:23136
	s_waitcnt vmcnt(9)
	ds_write_b128 v67, v[74:77] offset:46080
	s_waitcnt vmcnt(8)
	ds_write_b128 v67, v[90:93] offset:64512
	global_load_dwordx4 v[74:77], v69, s[0:1] offset:512
	global_load_dwordx4 v[90:93], v69, s[2:3] offset:512
	s_waitcnt lgkmcnt(3)
	v_mfma_f32_32x32x16_bf16 v[2:17], v[118:121], v[122:125], v[2:17]
	s_waitcnt vmcnt(9)
	ds_write_b128 v67, v[78:81] offset:50688
	s_waitcnt vmcnt(8)
	ds_write_b128 v68, v[94:97] offset:13824
	s_waitcnt lgkmcnt(4)
	v_mfma_f32_32x32x16_bf16 v[18:33], v[118:121], v[126:129], v[18:33]
	v_mfma_f32_32x32x16_bf16 v[34:49], v[110:113], v[122:125], v[34:49]
	v_mfma_f32_32x32x16_bf16 v[50:65], v[110:113], v[126:129], v[50:65]
	s_waitcnt lgkmcnt(0)
	s_barrier
; #define GL1_(RA, RB, i) { RA[i] = *(const u32x4*)(ap + (aoff + (i) * astep)); if ((i) < NB) RB[(i) < NB ? (i) : 0] = *(const u32x4*)(bp + (boff + (i) * bstep)); }
; #define LS1_(RA, RB, ST, i) { char* sn_ = lds + (ST) * STAGE; *(u32x4*)(sn_ + wofs + (i) * 32 * LROW) = RA[i]; \
;                               if ((i) < NB) *(u32x4*)(sn_ + STAGE_OP + wofs + (i) * 32 * LROW) = RB[(i) < NB ? (i) : 0]; }
; template <int NJ> DI void gemm_mainloop_reg(const bf16_t* __restrict__ A, int lda, const bf16_t* __restrict__ Bt, int ldb, int K, f32x16 (&acc)[2][NJ], char* lds) {
;     ...
; #pragma unroll
;   for (int i = 0; i < 4; ++i) GL1_(ra0, rb0, i);
;   ap += 128; bp += 128;
; #pragma unroll
;   for (int i = 0; i < 4; ++i) GL1_(ra1, rb1, i);
;   ap += 128; bp += 128;
; #pragma unroll
;   for (int i = 0; i < 4; ++i) LS1_(ra0, rb0, 0, i);
;   __syncthreads();
;   const int nk = K >> 6;
;   for (int kt = 0; kt < nk; kt += 2) {
;     const bool l0 = (kt + 2 < nk), l1 = (kt + 3 < nk);
;     STEP_(0, l0, ra0, rb0, true, ra1, rb1);
;     __syncthreads();
;     STEP_(1, l1, ra1, rb1, l0, ra0, rb0);
;     __syncthreads();
;   }
	ds_read_b128 v[78:81], v0 offset:36864
	ds_read_b128 v[94:97], v66 offset:55296
	ds_read_b128 v[110:113], v0 offset:36896
	ds_read_b128 v[114:117], v66 offset:55328
	ds_read_b128 v[118:121], v0 offset:41472
	ds_read_b128 v[122:125], v0 offset:41504
	s_waitcnt lgkmcnt(4)
	v_mfma_f32_32x32x16_bf16 v[34:49], v[78:81], v[94:97], v[34:49]
	s_waitcnt lgkmcnt(1)
	v_mfma_f32_32x32x16_bf16 v[2:17], v[118:121], v[94:97], v[2:17]
	ds_read_b128 v[94:97], v66 offset:59904
	ds_read_b128 v[126:129], v66 offset:59936
	s_waitcnt lgkmcnt(1)
	v_mfma_f32_32x32x16_bf16 v[50:65], v[78:81], v[94:97], v[50:65]
	global_load_dwordx4 v[78:81], v72, s[0:1] offset:640
	global_load_dwordx4 v[134:137], v72, s[2:3] offset:640
	s_waitcnt vmcnt(9)
	ds_write_b128 v67, v[82:85]
	s_waitcnt vmcnt(8)
	ds_write_b128 v67, v[130:133] offset:18432
	v_mfma_f32_32x32x16_bf16 v[18:33], v[118:121], v[94:97], v[18:33]
	global_load_dwordx4 v[82:85], v71, s[0:1] offset:640
	global_load_dwordx4 v[94:97], v71, s[2:3] offset:640
	v_mfma_f32_32x32x16_bf16 v[2:17], v[122:125], v[114:117], v[2:17]
	s_waitcnt lgkmcnt(2)
	v_mfma_f32_32x32x16_bf16 v[18:33], v[122:125], v[126:129], v[18:33]
	v_mfma_f32_32x32x16_bf16 v[34:49], v[110:113], v[114:117], v[34:49]
	v_mfma_f32_32x32x16_bf16 v[50:65], v[110:113], v[126:129], v[50:65]
	ds_read_b128 v[110:113], v0 offset:36928
	ds_read_b128 v[114:117], v0 offset:41536
	ds_read_b128 v[118:121], v66 offset:55360
	ds_read_b128 v[130:133], v66 offset:59968
	s_waitcnt vmcnt(9)
	ds_write_b128 v67, v[86:89] offset:4608
	s_waitcnt vmcnt(8)
	ds_write_b128 v67, v[98:101] offset:23040
	global_load_dwordx4 v[86:89], v70, s[0:1] offset:640
	global_load_dwordx4 v[98:101], v70, s[2:3] offset:640
	s_waitcnt lgkmcnt(3)
	v_mfma_f32_32x32x16_bf16 v[2:17], v[114:117], v[118:121], v[2:17]
	s_waitcnt lgkmcnt(2)
	v_mfma_f32_32x32x16_bf16 v[18:33], v[114:117], v[130:133], v[18:33]
	v_mfma_f32_32x32x16_bf16 v[34:49], v[110:113], v[118:121], v[34:49]
	v_mfma_f32_32x32x16_bf16 v[50:65], v[110:113], v[130:133], v[50:65]
	ds_read_b128 v[110:113], v0 offset:36960
	ds_read_b128 v[118:121], v0 offset:41568
	ds_read_b128 v[122:125], v66 offset:55392
	ds_read_b128 v[126:129], v66 offset:60000
	s_waitcnt vmcnt(9)
	ds_write_b128 v67, v[102:105] offset:9216
	s_waitcnt vmcnt(8)
	ds_write_b128 v67, v[106:109] offset:27648
	global_load_dwordx4 v[102:105], v69, s[0:1] offset:640
	global_load_dwordx4 v[106:109], v69, s[2:3] offset:640
	s_waitcnt lgkmcnt(3)
	v_mfma_f32_32x32x16_bf16 v[2:17], v[118:121], v[122:125], v[2:17]
	s_waitcnt vmcnt(9)
	ds_write_b128 v67, v[74:77] offset:13824
	s_waitcnt vmcnt(8)
	ds_write_b128 v67, v[90:93] offset:32256
	s_waitcnt lgkmcnt(4)
	v_mfma_f32_32x32x16_bf16 v[18:33], v[118:121], v[126:129], v[18:33]
	v_mfma_f32_32x32x16_bf16 v[34:49], v[110:113], v[122:125], v[34:49]
	v_mfma_f32_32x32x16_bf16 v[50:65], v[110:113], v[126:129], v[50:65]
	s_waitcnt lgkmcnt(0)
	s_barrier
	ds_read_b128 v[74:77], v0
	ds_read_b128 v[90:93], v66 offset:18432
	ds_read_b128 v[110:113], v0 offset:32
	ds_read_b128 v[114:117], v66 offset:18464
	ds_read_b128 v[118:121], v0 offset:4608
	ds_read_b128 v[122:125], v0 offset:4640
	s_waitcnt lgkmcnt(4)
	v_mfma_f32_32x32x16_bf16 v[34:49], v[74:77], v[90:93], v[34:49]
	s_waitcnt lgkmcnt(1)
	v_mfma_f32_32x32x16_bf16 v[2:17], v[118:121], v[90:93], v[2:17]
	ds_read_b128 v[90:93], v66 offset:23040
	ds_read_b128 v[126:129], v66 offset:23072
	s_waitcnt lgkmcnt(1)
	v_mfma_f32_32x32x16_bf16 v[50:65], v[74:77], v[90:93], v[50:65]
	global_load_dwordx4 v[74:77], v72, s[0:1] offset:768
	global_load_dwordx4 v[130:133], v72, s[2:3] offset:768
	s_waitcnt vmcnt(9)
	ds_write_b128 v67, v[78:81] offset:36864
	s_waitcnt vmcnt(8)
	ds_write_b128 v67, v[134:137] offset:55296
	v_mfma_f32_32x32x16_bf16 v[18:33], v[118:121], v[90:93], v[18:33]
	global_load_dwordx4 v[78:81], v71, s[0:1] offset:768
	global_load_dwordx4 v[90:93], v71, s[2:3] offset:768
	v_mfma_f32_32x32x16_bf16 v[2:17], v[122:125], v[114:117], v[2:17]
	s_waitcnt lgkmcnt(2)
	v_mfma_f32_32x32x16_bf16 v[18:33], v[122:125], v[126:129], v[18:33]
	v_mfma_f32_32x32x16_bf16 v[34:49], v[110:113], v[114:117], v[34:49]
	v_mfma_f32_32x32x16_bf16 v[50:65], v[110:113], v[126:129], v[50:65]
	ds_read_b128 v[110:113], v0 offset:64
	ds_read_b128 v[114:117], v0 offset:4672
	ds_read_b128 v[118:121], v66 offset:18496
	ds_read_b128 v[134:137], v66 offset:23104
	s_waitcnt vmcnt(9)
	ds_write_b128 v67, v[82:85] offset:41472
	s_waitcnt vmcnt(8)
	ds_write_b128 v67, v[94:97] offset:59904
	global_load_dwordx4 v[82:85], v70, s[0:1] offset:768
	global_load_dwordx4 v[94:97], v70, s[2:3] offset:768
	s_waitcnt lgkmcnt(3)
	v_mfma_f32_32x32x16_bf16 v[2:17], v[114:117], v[118:121], v[2:17]
	s_waitcnt lgkmcnt(2)
	v_mfma_f32_32x32x16_bf16 v[18:33], v[114:117], v[134:137], v[18:33]
	v_mfma_f32_32x32x16_bf16 v[34:49], v[110:113], v[118:121], v[34:49]
	v_mfma_f32_32x32x16_bf16 v[50:65], v[110:113], v[134:137], v[50:65]
	ds_read_b128 v[110:113], v0 offset:96
	ds_read_b128 v[118:121], v0 offset:4704
	ds_read_b128 v[122:125], v66 offset:18528
	ds_read_b128 v[126:129], v66 offset:23136
	s_waitcnt vmcnt(9)
	ds_write_b128 v67, v[86:89] offset:46080
	s_waitcnt vmcnt(8)
	ds_write_b128 v67, v[98:101] offset:64512
	global_load_dwordx4 v[86:89], v69, s[0:1] offset:768
	global_load_dwordx4 v[98:101], v69, s[2:3] offset:768
	s_waitcnt lgkmcnt(3)
	v_mfma_f32_32x32x16_bf16 v[2:17], v[118:121], v[122:125], v[2:17]
	s_waitcnt vmcnt(9)
	ds_write_b128 v67, v[102:105] offset:50688
	s_waitcnt vmcnt(8)
	ds_write_b128 v68, v[106:109] offset:13824
	s_waitcnt lgkmcnt(4)
	v_mfma_f32_32x32x16_bf16 v[18:33], v[118:121], v[126:129], v[18:33]
	v_mfma_f32_32x32x16_bf16 v[34:49], v[110:113], v[122:125], v[34:49]
	v_mfma_f32_32x32x16_bf16 v[50:65], v[110:113], v[126:129], v[50:65]
	s_waitcnt lgkmcnt(0)
	s_barrier
; #define GL1_(RA, RB, i) { RA[i] = *(const u32x4*)(ap + (aoff + (i) * astep)); if ((i) < NB) RB[(i) < NB ? (i) : 0] = *(const u32x4*)(bp + (boff + (i) * bstep)); }
; #define LS1_(RA, RB, ST, i) { char* sn_ = lds + (ST) * STAGE; *(u32x4*)(sn_ + wofs + (i) * 32 * LROW) = RA[i]; \
;                               if ((i) < NB) *(u32x4*)(sn_ + STAGE_OP + wofs + (i) * 32 * LROW) = RB[(i) < NB ? (i) : 0]; }
; template <int NJ> DI void gemm_mainloop_reg(const bf16_t* __restrict__ A, int lda, const bf16_t* __restrict__ Bt, int ldb, int K, f32x16 (&acc)[2][NJ], char* lds) {
;     ...
; #pragma unroll
;   for (int i = 0; i < 4; ++i) GL1_(ra0, rb0, i);
;   ap += 128; bp += 128;
; #pragma unroll
;   for (int i = 0; i < 4; ++i) GL1_(ra1, rb1, i);
;   ap += 128; bp += 128;
; #pragma unroll
;   for (int i = 0; i < 4; ++i) LS1_(ra0, rb0, 0, i);
;   __syncthreads();
;   const int nk = K >> 6;
;   for (int kt = 0; kt < nk; kt += 2) {
;     const bool l0 = (kt + 2 < nk), l1 = (kt + 3 < nk);
;     STEP_(0, l0, ra0, rb0, true, ra1, rb1);
;     __syncthreads();
;     STEP_(1, l1, ra1, rb1, l0, ra0, rb0);
;     __syncthreads();
;   }
	ds_read_b128 v[102:105], v0 offset:36864
	ds_read_b128 v[106:109], v66 offset:55296
	ds_read_b128 v[110:113], v0 offset:36896
	ds_read_b128 v[114:117], v66 offset:55328
	ds_read_b128 v[118:121], v0 offset:41472
	ds_read_b128 v[122:125], v0 offset:41504
	s_waitcnt lgkmcnt(4)
	v_mfma_f32_32x32x16_bf16 v[34:49], v[102:105], v[106:109], v[34:49]
	s_waitcnt lgkmcnt(1)
	v_mfma_f32_32x32x16_bf16 v[2:17], v[118:121], v[106:109], v[2:17]
	ds_read_b128 v[106:109], v66 offset:59904
	ds_read_b128 v[126:129], v66 offset:59936
	s_waitcnt lgkmcnt(1)
	v_mfma_f32_32x32x16_bf16 v[50:65], v[102:105], v[106:109], v[50:65]
	global_load_dwordx4 v[102:105], v72, s[0:1] offset:896
	global_load_dwordx4 v[134:137], v72, s[2:3] offset:896
	s_waitcnt vmcnt(9)
	ds_write_b128 v67, v[74:77]
	s_waitcnt vmcnt(8)
	ds_write_b128 v67, v[130:133] offset:18432
	v_mfma_f32_32x32x16_bf16 v[18:33], v[118:121], v[106:109], v[18:33]
	global_load_dwordx4 v[74:77], v71, s[0:1] offset:896
	global_load_dwordx4 v[106:109], v71, s[2:3] offset:896
	v_mfma_f32_32x32x16_bf16 v[2:17], v[122:125], v[114:117], v[2:17]
	s_waitcnt lgkmcnt(2)
	v_mfma_f32_32x32x16_bf16 v[18:33], v[122:125], v[126:129], v[18:33]
	v_mfma_f32_32x32x16_bf16 v[34:49], v[110:113], v[114:117], v[34:49]
	v_mfma_f32_32x32x16_bf16 v[50:65], v[110:113], v[126:129], v[50:65]
	ds_read_b128 v[110:113], v0 offset:36928
	ds_read_b128 v[114:117], v0 offset:41536
	ds_read_b128 v[118:121], v66 offset:55360
	ds_read_b128 v[130:133], v66 offset:59968
	s_waitcnt vmcnt(9)
	ds_write_b128 v67, v[78:81] offset:4608
	s_waitcnt vmcnt(8)
	ds_write_b128 v67, v[90:93] offset:23040
	global_load_dwordx4 v[78:81], v70, s[0:1] offset:896
	global_load_dwordx4 v[90:93], v70, s[2:3] offset:896
	s_waitcnt lgkmcnt(3)
	v_mfma_f32_32x32x16_bf16 v[2:17], v[114:117], v[118:121], v[2:17]
	s_waitcnt lgkmcnt(2)
	v_mfma_f32_32x32x16_bf16 v[18:33], v[114:117], v[130:133], v[18:33]
	v_mfma_f32_32x32x16_bf16 v[34:49], v[110:113], v[118:121], v[34:49]
	v_mfma_f32_32x32x16_bf16 v[50:65], v[110:113], v[130:133], v[50:65]
	ds_read_b128 v[110:113], v0 offset:36960
	ds_read_b128 v[118:121], v0 offset:41568
	ds_read_b128 v[122:125], v66 offset:55392
	ds_read_b128 v[126:129], v66 offset:60000
	s_waitcnt vmcnt(9)
	ds_write_b128 v67, v[82:85] offset:9216
	s_waitcnt vmcnt(8)
	ds_write_b128 v67, v[94:97] offset:27648
	global_load_dwordx4 v[82:85], v69, s[0:1] offset:896
	global_load_dwordx4 v[94:97], v69, s[2:3] offset:896
	s_waitcnt lgkmcnt(3)
	v_mfma_f32_32x32x16_bf16 v[2:17], v[118:121], v[122:125], v[2:17]
	s_waitcnt vmcnt(9)
	ds_write_b128 v67, v[86:89] offset:13824
	s_waitcnt vmcnt(8)
	ds_write_b128 v67, v[98:101] offset:32256
	s_waitcnt lgkmcnt(4)
	v_mfma_f32_32x32x16_bf16 v[18:33], v[118:121], v[126:129], v[18:33]
	v_mfma_f32_32x32x16_bf16 v[34:49], v[110:113], v[122:125], v[34:49]
	v_mfma_f32_32x32x16_bf16 v[50:65], v[110:113], v[126:129], v[50:65]
	s_waitcnt lgkmcnt(0)
	s_barrier
	ds_read_b128 v[86:89], v0
	ds_read_b128 v[98:101], v66 offset:18432
	ds_read_b128 v[110:113], v0 offset:32
	ds_read_b128 v[114:117], v66 offset:18464
	ds_read_b128 v[118:121], v0 offset:4608
	ds_read_b128 v[122:125], v0 offset:4640
	s_waitcnt lgkmcnt(4)
	v_mfma_f32_32x32x16_bf16 v[34:49], v[86:89], v[98:101], v[34:49]
	s_waitcnt lgkmcnt(1)
	v_mfma_f32_32x32x16_bf16 v[2:17], v[118:121], v[98:101], v[2:17]
	ds_read_b128 v[98:101], v66 offset:23040
	ds_read_b128 v[126:129], v66 offset:23072
	s_waitcnt lgkmcnt(1)
	v_mfma_f32_32x32x16_bf16 v[50:65], v[86:89], v[98:101], v[50:65]
	global_load_dwordx4 v[86:89], v72, s[0:1] offset:1024
	global_load_dwordx4 v[130:133], v72, s[2:3] offset:1024
	s_waitcnt vmcnt(9)
	ds_write_b128 v67, v[102:105] offset:36864
	s_waitcnt vmcnt(8)
	ds_write_b128 v67, v[134:137] offset:55296
	v_mfma_f32_32x32x16_bf16 v[18:33], v[118:121], v[98:101], v[18:33]
	global_load_dwordx4 v[98:101], v71, s[0:1] offset:1024
	global_load_dwordx4 v[102:105], v71, s[2:3] offset:1024
	v_mfma_f32_32x32x16_bf16 v[2:17], v[122:125], v[114:117], v[2:17]
	s_waitcnt lgkmcnt(2)
	v_mfma_f32_32x32x16_bf16 v[18:33], v[122:125], v[126:129], v[18:33]
	v_mfma_f32_32x32x16_bf16 v[34:49], v[110:113], v[114:117], v[34:49]
	v_mfma_f32_32x32x16_bf16 v[50:65], v[110:113], v[126:129], v[50:65]
	ds_read_b128 v[110:113], v0 offset:64
	ds_read_b128 v[114:117], v0 offset:4672
	ds_read_b128 v[118:121], v66 offset:18496
	ds_read_b128 v[134:137], v66 offset:23104
	s_waitcnt vmcnt(9)
	ds_write_b128 v67, v[74:77] offset:41472
	s_waitcnt vmcnt(8)
	ds_write_b128 v67, v[106:109] offset:59904
	global_load_dwordx4 v[74:77], v70, s[0:1] offset:1024
	global_load_dwordx4 v[106:109], v70, s[2:3] offset:1024
	s_waitcnt lgkmcnt(3)
	v_mfma_f32_32x32x16_bf16 v[2:17], v[114:117], v[118:121], v[2:17]
	s_waitcnt lgkmcnt(2)
	v_mfma_f32_32x32x16_bf16 v[18:33], v[114:117], v[134:137], v[18:33]
	v_mfma_f32_32x32x16_bf16 v[34:49], v[110:113], v[118:121], v[34:49]
	v_mfma_f32_32x32x16_bf16 v[50:65], v[110:113], v[134:137], v[50:65]
	ds_read_b128 v[110:113], v0 offset:96
	ds_read_b128 v[118:121], v0 offset:4704
	ds_read_b128 v[122:125], v66 offset:18528
	ds_read_b128 v[126:129], v66 offset:23136
	s_waitcnt vmcnt(9)
	ds_write_b128 v67, v[78:81] offset:46080
	s_waitcnt vmcnt(8)
	ds_write_b128 v67, v[90:93] offset:64512
	global_load_dwordx4 v[78:81], v69, s[0:1] offset:1024
	global_load_dwordx4 v[90:93], v69, s[2:3] offset:1024
	s_waitcnt lgkmcnt(3)
	v_mfma_f32_32x32x16_bf16 v[2:17], v[118:121], v[122:125], v[2:17]
	s_waitcnt vmcnt(9)
	ds_write_b128 v67, v[82:85] offset:50688
	s_waitcnt vmcnt(8)
	ds_write_b128 v68, v[94:97] offset:13824
	s_waitcnt lgkmcnt(4)
	v_mfma_f32_32x32x16_bf16 v[18:33], v[118:121], v[126:129], v[18:33]
	v_mfma_f32_32x32x16_bf16 v[34:49], v[110:113], v[122:125], v[34:49]
	v_mfma_f32_32x32x16_bf16 v[50:65], v[110:113], v[126:129], v[50:65]
	s_waitcnt lgkmcnt(0)
	s_barrier
; #define GL1_(RA, RB, i) { RA[i] = *(const u32x4*)(ap + (aoff + (i) * astep)); if ((i) < NB) RB[(i) < NB ? (i) : 0] = *(const u32x4*)(bp + (boff + (i) * bstep)); }
; #define LS1_(RA, RB, ST, i) { char* sn_ = lds + (ST) * STAGE; *(u32x4*)(sn_ + wofs + (i) * 32 * LROW) = RA[i]; \
;                               if ((i) < NB) *(u32x4*)(sn_ + STAGE_OP + wofs + (i) * 32 * LROW) = RB[(i) < NB ? (i) : 0]; }
; template <int NJ> DI void gemm_mainloop_reg(const bf16_t* __restrict__ A, int lda, const bf16_t* __restrict__ Bt, int ldb, int K, f32x16 (&acc)[2][NJ], char* lds) {
;     ...
; #pragma unroll
;   for (int i = 0; i < 4; ++i) GL1_(ra0, rb0, i);
;   ap += 128; bp += 128;
; #pragma unroll
;   for (int i = 0; i < 4; ++i) GL1_(ra1, rb1, i);
;   ap += 128; bp += 128;
; #pragma unroll
;   for (int i = 0; i < 4; ++i) LS1_(ra0, rb0, 0, i);
;   __syncthreads();
;   const int nk = K >> 6;
;   for (int kt = 0; kt < nk; kt += 2) {
;     const bool l0 = (kt + 2 < nk), l1 = (kt + 3 < nk);
;     STEP_(0, l0, ra0, rb0, true, ra1, rb1);
;     __syncthreads();
;     STEP_(1, l1, ra1, rb1, l0, ra0, rb0);
;     __syncthreads();
;   }
	ds_read_b128 v[82:85], v0 offset:36864
	ds_read_b128 v[94:97], v66 offset:55296
	ds_read_b128 v[110:113], v0 offset:36896
	ds_read_b128 v[114:117], v66 offset:55328
	ds_read_b128 v[118:121], v0 offset:41472
	ds_read_b128 v[122:125], v0 offset:41504
	s_waitcnt lgkmcnt(4)
	v_mfma_f32_32x32x16_bf16 v[34:49], v[82:85], v[94:97], v[34:49]
	s_waitcnt lgkmcnt(1)
	v_mfma_f32_32x32x16_bf16 v[2:17], v[118:121], v[94:97], v[2:17]
	ds_read_b128 v[94:97], v66 offset:59904
	ds_read_b128 v[126:129], v66 offset:59936
	s_waitcnt lgkmcnt(1)
	v_mfma_f32_32x32x16_bf16 v[50:65], v[82:85], v[94:97], v[50:65]
	global_load_dwordx4 v[82:85], v72, s[0:1] offset:1152
	global_load_dwordx4 v[134:137], v72, s[2:3] offset:1152
	s_waitcnt vmcnt(9)
	ds_write_b128 v67, v[86:89]
	s_waitcnt vmcnt(8)
	ds_write_b128 v67, v[130:133] offset:18432
	v_mfma_f32_32x32x16_bf16 v[18:33], v[118:121], v[94:97], v[18:33]
	global_load_dwordx4 v[86:89], v71, s[0:1] offset:1152
	global_load_dwordx4 v[94:97], v71, s[2:3] offset:1152
	v_mfma_f32_32x32x16_bf16 v[2:17], v[122:125], v[114:117], v[2:17]
	s_waitcnt lgkmcnt(2)
	v_mfma_f32_32x32x16_bf16 v[18:33], v[122:125], v[126:129], v[18:33]
	v_mfma_f32_32x32x16_bf16 v[34:49], v[110:113], v[114:117], v[34:49]
	v_mfma_f32_32x32x16_bf16 v[50:65], v[110:113], v[126:129], v[50:65]
	ds_read_b128 v[110:113], v0 offset:36928
	ds_read_b128 v[114:117], v0 offset:41536
	ds_read_b128 v[118:121], v66 offset:55360
	ds_read_b128 v[130:133], v66 offset:59968
	s_waitcnt vmcnt(9)
	ds_write_b128 v67, v[98:101] offset:4608
	s_waitcnt vmcnt(8)
	ds_write_b128 v67, v[102:105] offset:23040
	global_load_dwordx4 v[98:101], v70, s[0:1] offset:1152
	global_load_dwordx4 v[102:105], v70, s[2:3] offset:1152
	s_waitcnt lgkmcnt(3)
	v_mfma_f32_32x32x16_bf16 v[2:17], v[114:117], v[118:121], v[2:17]
	s_waitcnt lgkmcnt(2)
	v_mfma_f32_32x32x16_bf16 v[18:33], v[114:117], v[130:133], v[18:33]
	v_mfma_f32_32x32x16_bf16 v[34:49], v[110:113], v[118:121], v[34:49]
	v_mfma_f32_32x32x16_bf16 v[50:65], v[110:113], v[130:133], v[50:65]
	ds_read_b128 v[110:113], v0 offset:36960
	ds_read_b128 v[118:121], v0 offset:41568
	ds_read_b128 v[122:125], v66 offset:55392
	ds_read_b128 v[126:129], v66 offset:60000
	s_waitcnt vmcnt(9)
	ds_write_b128 v67, v[74:77] offset:9216
	s_waitcnt vmcnt(8)
	ds_write_b128 v67, v[106:109] offset:27648
	global_load_dwordx4 v[74:77], v69, s[0:1] offset:1152
	global_load_dwordx4 v[106:109], v69, s[2:3] offset:1152
	s_waitcnt lgkmcnt(3)
	v_mfma_f32_32x32x16_bf16 v[2:17], v[118:121], v[122:125], v[2:17]
	s_waitcnt vmcnt(9)
	ds_write_b128 v67, v[78:81] offset:13824
	s_waitcnt vmcnt(8)
	ds_write_b128 v67, v[90:93] offset:32256
	s_waitcnt lgkmcnt(4)
	v_mfma_f32_32x32x16_bf16 v[18:33], v[118:121], v[126:129], v[18:33]
	v_mfma_f32_32x32x16_bf16 v[34:49], v[110:113], v[122:125], v[34:49]
	v_mfma_f32_32x32x16_bf16 v[50:65], v[110:113], v[126:129], v[50:65]
	s_waitcnt lgkmcnt(0)
	s_barrier
	ds_read_b128 v[78:81], v0
	ds_read_b128 v[90:93], v66 offset:18432
	ds_read_b128 v[110:113], v0 offset:32
	ds_read_b128 v[114:117], v66 offset:18464
	ds_read_b128 v[118:121], v0 offset:4608
	ds_read_b128 v[122:125], v0 offset:4640
	s_waitcnt lgkmcnt(4)
	v_mfma_f32_32x32x16_bf16 v[34:49], v[78:81], v[90:93], v[34:49]
	s_waitcnt lgkmcnt(1)
	v_mfma_f32_32x32x16_bf16 v[2:17], v[118:121], v[90:93], v[2:17]
	ds_read_b128 v[90:93], v66 offset:23040
	ds_read_b128 v[126:129], v66 offset:23072
	s_waitcnt lgkmcnt(1)
	v_mfma_f32_32x32x16_bf16 v[50:65], v[78:81], v[90:93], v[50:65]
	global_load_dwordx4 v[78:81], v72, s[0:1] offset:1280
	global_load_dwordx4 v[130:133], v72, s[2:3] offset:1280
	s_waitcnt vmcnt(9)
	ds_write_b128 v67, v[82:85] offset:36864
	s_waitcnt vmcnt(8)
	ds_write_b128 v67, v[134:137] offset:55296
	v_mfma_f32_32x32x16_bf16 v[18:33], v[118:121], v[90:93], v[18:33]
	global_load_dwordx4 v[82:85], v71, s[0:1] offset:1280
	global_load_dwordx4 v[90:93], v71, s[2:3] offset:1280
	v_mfma_f32_32x32x16_bf16 v[2:17], v[122:125], v[114:117], v[2:17]
	s_waitcnt lgkmcnt(2)
	v_mfma_f32_32x32x16_bf16 v[18:33], v[122:125], v[126:129], v[18:33]
	v_mfma_f32_32x32x16_bf16 v[34:49], v[110:113], v[114:117], v[34:49]
	v_mfma_f32_32x32x16_bf16 v[50:65], v[110:113], v[126:129], v[50:65]
	ds_read_b128 v[110:113], v0 offset:64
	ds_read_b128 v[114:117], v0 offset:4672
	ds_read_b128 v[118:121], v66 offset:18496
	ds_read_b128 v[134:137], v66 offset:23104
	s_waitcnt vmcnt(9)
	ds_write_b128 v67, v[86:89] offset:41472
	s_waitcnt vmcnt(8)
	ds_write_b128 v67, v[94:97] offset:59904
	global_load_dwordx4 v[86:89], v70, s[0:1] offset:1280
	global_load_dwordx4 v[94:97], v70, s[2:3] offset:1280
	s_waitcnt lgkmcnt(3)
	v_mfma_f32_32x32x16_bf16 v[2:17], v[114:117], v[118:121], v[2:17]
	s_waitcnt lgkmcnt(2)
	v_mfma_f32_32x32x16_bf16 v[18:33], v[114:117], v[134:137], v[18:33]
	v_mfma_f32_32x32x16_bf16 v[34:49], v[110:113], v[118:121], v[34:49]
	v_mfma_f32_32x32x16_bf16 v[50:65], v[110:113], v[134:137], v[50:65]
	ds_read_b128 v[110:113], v0 offset:96
	ds_read_b128 v[118:121], v0 offset:4704
	ds_read_b128 v[122:125], v66 offset:18528
	ds_read_b128 v[126:129], v66 offset:23136
	s_waitcnt vmcnt(9)
	ds_write_b128 v67, v[98:101] offset:46080
	s_waitcnt vmcnt(8)
	ds_write_b128 v67, v[102:105] offset:64512
	global_load_dwordx4 v[98:101], v69, s[0:1] offset:1280
	global_load_dwordx4 v[102:105], v69, s[2:3] offset:1280
	s_waitcnt lgkmcnt(3)
	v_mfma_f32_32x32x16_bf16 v[2:17], v[118:121], v[122:125], v[2:17]
	s_waitcnt vmcnt(9)
	ds_write_b128 v67, v[74:77] offset:50688
	s_waitcnt vmcnt(8)
	ds_write_b128 v68, v[106:109] offset:13824
	s_waitcnt lgkmcnt(4)
	v_mfma_f32_32x32x16_bf16 v[18:33], v[118:121], v[126:129], v[18:33]
	v_mfma_f32_32x32x16_bf16 v[34:49], v[110:113], v[122:125], v[34:49]
	v_mfma_f32_32x32x16_bf16 v[50:65], v[110:113], v[126:129], v[50:65]
	s_waitcnt lgkmcnt(0)
	s_barrier
; #define GL1_(RA, RB, i) { RA[i] = *(const u32x4*)(ap + (aoff + (i) * astep)); if ((i) < NB) RB[(i) < NB ? (i) : 0] = *(const u32x4*)(bp + (boff + (i) * bstep)); }
; #define LS1_(RA, RB, ST, i) { char* sn_ = lds + (ST) * STAGE; *(u32x4*)(sn_ + wofs + (i) * 32 * LROW) = RA[i]; \
;                               if ((i) < NB) *(u32x4*)(sn_ + STAGE_OP + wofs + (i) * 32 * LROW) = RB[(i) < NB ? (i) : 0]; }
; template <int NJ> DI void gemm_mainloop_reg(const bf16_t* __restrict__ A, int lda, const bf16_t* __restrict__ Bt, int ldb, int K, f32x16 (&acc)[2][NJ], char* lds) {
;     ...
; #pragma unroll
;   for (int i = 0; i < 4; ++i) GL1_(ra0, rb0, i);
;   ap += 128; bp += 128;
; #pragma unroll
;   for (int i = 0; i < 4; ++i) GL1_(ra1, rb1, i);
;   ap += 128; bp += 128;
; #pragma unroll
;   for (int i = 0; i < 4; ++i) LS1_(ra0, rb0, 0, i);
;   __syncthreads();
;   const int nk = K >> 6;
;   for (int kt = 0; kt < nk; kt += 2) {
;     const bool l0 = (kt + 2 < nk), l1 = (kt + 3 < nk);
;     STEP_(0, l0, ra0, rb0, true, ra1, rb1);
;     __syncthreads();
;     STEP_(1, l1, ra1, rb1, l0, ra0, rb0);
;     __syncthreads();
;   }
	ds_read_b128 v[74:77], v0 offset:36864
	ds_read_b128 v[106:109], v66 offset:55296
	ds_read_b128 v[110:113], v0 offset:36896
	ds_read_b128 v[114:117], v66 offset:55328
	ds_read_b128 v[118:121], v0 offset:41472
	ds_read_b128 v[122:125], v0 offset:41504
	s_waitcnt lgkmcnt(4)
	v_mfma_f32_32x32x16_bf16 v[34:49], v[74:77], v[106:109], v[34:49]
	s_waitcnt lgkmcnt(1)
	v_mfma_f32_32x32x16_bf16 v[2:17], v[118:121], v[106:109], v[2:17]
	ds_read_b128 v[106:109], v66 offset:59904
	ds_read_b128 v[126:129], v66 offset:59936
	s_waitcnt lgkmcnt(1)
	v_mfma_f32_32x32x16_bf16 v[50:65], v[74:77], v[106:109], v[50:65]
	global_load_dwordx4 v[74:77], v72, s[0:1] offset:1408
	global_load_dwordx4 v[134:137], v72, s[2:3] offset:1408
	s_waitcnt vmcnt(9)
	ds_write_b128 v67, v[78:81]
	s_waitcnt vmcnt(8)
	ds_write_b128 v67, v[130:133] offset:18432
	v_mfma_f32_32x32x16_bf16 v[18:33], v[118:121], v[106:109], v[18:33]
	global_load_dwordx4 v[78:81], v71, s[0:1] offset:1408
	global_load_dwordx4 v[106:109], v71, s[2:3] offset:1408
	v_mfma_f32_32x32x16_bf16 v[2:17], v[122:125], v[114:117], v[2:17]
	s_waitcnt lgkmcnt(2)
	v_mfma_f32_32x32x16_bf16 v[18:33], v[122:125], v[126:129], v[18:33]
	v_mfma_f32_32x32x16_bf16 v[34:49], v[110:113], v[114:117], v[34:49]
	v_mfma_f32_32x32x16_bf16 v[50:65], v[110:113], v[126:129], v[50:65]
	ds_read_b128 v[110:113], v0 offset:36928
	ds_read_b128 v[114:117], v0 offset:41536
	ds_read_b128 v[118:121], v66 offset:55360
	ds_read_b128 v[130:133], v66 offset:59968
	s_waitcnt vmcnt(9)
	ds_write_b128 v67, v[82:85] offset:4608
	s_waitcnt vmcnt(8)
	ds_write_b128 v67, v[90:93] offset:23040
	global_load_dwordx4 v[82:85], v70, s[0:1] offset:1408
	global_load_dwordx4 v[90:93], v70, s[2:3] offset:1408
	s_waitcnt lgkmcnt(3)
	v_mfma_f32_32x32x16_bf16 v[2:17], v[114:117], v[118:121], v[2:17]
	s_waitcnt lgkmcnt(2)
	v_mfma_f32_32x32x16_bf16 v[18:33], v[114:117], v[130:133], v[18:33]
	v_mfma_f32_32x32x16_bf16 v[34:49], v[110:113], v[118:121], v[34:49]
	v_mfma_f32_32x32x16_bf16 v[50:65], v[110:113], v[130:133], v[50:65]
	ds_read_b128 v[110:113], v0 offset:36960
	ds_read_b128 v[118:121], v0 offset:41568
	ds_read_b128 v[122:125], v66 offset:55392
	ds_read_b128 v[126:129], v66 offset:60000
	s_waitcnt vmcnt(9)
	ds_write_b128 v67, v[86:89] offset:9216
	s_waitcnt vmcnt(8)
	ds_write_b128 v67, v[94:97] offset:27648
	global_load_dwordx4 v[86:89], v69, s[0:1] offset:1408
	global_load_dwordx4 v[94:97], v69, s[2:3] offset:1408
	s_waitcnt lgkmcnt(3)
	v_mfma_f32_32x32x16_bf16 v[2:17], v[118:121], v[122:125], v[2:17]
	s_waitcnt vmcnt(9)
	ds_write_b128 v67, v[98:101] offset:13824
	s_waitcnt vmcnt(8)
	ds_write_b128 v67, v[102:105] offset:32256
	s_waitcnt lgkmcnt(4)
	v_mfma_f32_32x32x16_bf16 v[18:33], v[118:121], v[126:129], v[18:33]
	v_mfma_f32_32x32x16_bf16 v[34:49], v[110:113], v[122:125], v[34:49]
	v_mfma_f32_32x32x16_bf16 v[50:65], v[110:113], v[126:129], v[50:65]
	s_waitcnt lgkmcnt(0)
	s_barrier
	ds_read_b128 v[98:101], v0
	ds_read_b128 v[102:105], v66 offset:18432
	ds_read_b128 v[110:113], v0 offset:32
	ds_read_b128 v[114:117], v66 offset:18464
	ds_read_b128 v[118:121], v0 offset:4608
	ds_read_b128 v[122:125], v0 offset:4640
	s_waitcnt lgkmcnt(4)
	v_mfma_f32_32x32x16_bf16 v[34:49], v[98:101], v[102:105], v[34:49]
	s_waitcnt lgkmcnt(1)
	v_mfma_f32_32x32x16_bf16 v[2:17], v[118:121], v[102:105], v[2:17]
	ds_read_b128 v[102:105], v66 offset:23040
	ds_read_b128 v[126:129], v66 offset:23072
	s_waitcnt lgkmcnt(1)
	v_mfma_f32_32x32x16_bf16 v[50:65], v[98:101], v[102:105], v[50:65]
	global_load_dwordx4 v[98:101], v72, s[0:1] offset:1536
	global_load_dwordx4 v[130:133], v72, s[2:3] offset:1536
	s_waitcnt vmcnt(9)
	ds_write_b128 v67, v[74:77] offset:36864
	s_waitcnt vmcnt(8)
	ds_write_b128 v67, v[134:137] offset:55296
	v_mfma_f32_32x32x16_bf16 v[18:33], v[118:121], v[102:105], v[18:33]
	global_load_dwordx4 v[74:77], v71, s[0:1] offset:1536
	global_load_dwordx4 v[102:105], v71, s[2:3] offset:1536
	v_mfma_f32_32x32x16_bf16 v[2:17], v[122:125], v[114:117], v[2:17]
	s_waitcnt lgkmcnt(2)
	v_mfma_f32_32x32x16_bf16 v[18:33], v[122:125], v[126:129], v[18:33]
	v_mfma_f32_32x32x16_bf16 v[34:49], v[110:113], v[114:117], v[34:49]
	v_mfma_f32_32x32x16_bf16 v[50:65], v[110:113], v[126:129], v[50:65]
	ds_read_b128 v[110:113], v0 offset:64
	ds_read_b128 v[114:117], v0 offset:4672
	ds_read_b128 v[118:121], v66 offset:18496
	ds_read_b128 v[134:137], v66 offset:23104
	s_waitcnt vmcnt(9)
	ds_write_b128 v67, v[78:81] offset:41472
	s_waitcnt vmcnt(8)
	ds_write_b128 v67, v[106:109] offset:59904
	global_load_dwordx4 v[78:81], v70, s[0:1] offset:1536
	global_load_dwordx4 v[106:109], v70, s[2:3] offset:1536
	s_waitcnt lgkmcnt(3)
	v_mfma_f32_32x32x16_bf16 v[2:17], v[114:117], v[118:121], v[2:17]
	s_waitcnt lgkmcnt(2)
	v_mfma_f32_32x32x16_bf16 v[18:33], v[114:117], v[134:137], v[18:33]
	v_mfma_f32_32x32x16_bf16 v[34:49], v[110:113], v[118:121], v[34:49]
	v_mfma_f32_32x32x16_bf16 v[50:65], v[110:113], v[134:137], v[50:65]
	ds_read_b128 v[110:113], v0 offset:96
	ds_read_b128 v[118:121], v0 offset:4704
	ds_read_b128 v[122:125], v66 offset:18528
	ds_read_b128 v[126:129], v66 offset:23136
	s_waitcnt vmcnt(9)
	ds_write_b128 v67, v[82:85] offset:46080
	s_waitcnt vmcnt(8)
	ds_write_b128 v67, v[90:93] offset:64512
	global_load_dwordx4 v[82:85], v69, s[0:1] offset:1536
	global_load_dwordx4 v[90:93], v69, s[2:3] offset:1536
	s_waitcnt lgkmcnt(3)
	v_mfma_f32_32x32x16_bf16 v[2:17], v[118:121], v[122:125], v[2:17]
	s_waitcnt vmcnt(9)
	ds_write_b128 v67, v[86:89] offset:50688
	s_waitcnt vmcnt(8)
	ds_write_b128 v68, v[94:97] offset:13824
	s_waitcnt lgkmcnt(4)
	v_mfma_f32_32x32x16_bf16 v[18:33], v[118:121], v[126:129], v[18:33]
	v_mfma_f32_32x32x16_bf16 v[34:49], v[110:113], v[122:125], v[34:49]
	v_mfma_f32_32x32x16_bf16 v[50:65], v[110:113], v[126:129], v[50:65]
	s_waitcnt lgkmcnt(0)
	s_barrier
; #define GL1_(RA, RB, i) { RA[i] = *(const u32x4*)(ap + (aoff + (i) * astep)); if ((i) < NB) RB[(i) < NB ? (i) : 0] = *(const u32x4*)(bp + (boff + (i) * bstep)); }
; #define LS1_(RA, RB, ST, i) { char* sn_ = lds + (ST) * STAGE; *(u32x4*)(sn_ + wofs + (i) * 32 * LROW) = RA[i]; \
;                               if ((i) < NB) *(u32x4*)(sn_ + STAGE_OP + wofs + (i) * 32 * LROW) = RB[(i) < NB ? (i) : 0]; }
; template <int NJ> DI void gemm_mainloop_reg(const bf16_t* __restrict__ A, int lda, const bf16_t* __restrict__ Bt, int ldb, int K, f32x16 (&acc)[2][NJ], char* lds) {
;     ...
; #pragma unroll
;   for (int i = 0; i < 4; ++i) GL1_(ra0, rb0, i);
;   ap += 128; bp += 128;
; #pragma unroll
;   for (int i = 0; i < 4; ++i) GL1_(ra1, rb1, i);
;   ap += 128; bp += 128;
; #pragma unroll
;   for (int i = 0; i < 4; ++i) LS1_(ra0, rb0, 0, i);
;   __syncthreads();
;   const int nk = K >> 6;
;   for (int kt = 0; kt < nk; kt += 2) {
;     const bool l0 = (kt + 2 < nk), l1 = (kt + 3 < nk);
;     STEP_(0, l0, ra0, rb0, true, ra1, rb1);
;     __syncthreads();
;     STEP_(1, l1, ra1, rb1, l0, ra0, rb0);
;     __syncthreads();
;   }
	ds_read_b128 v[86:89], v0 offset:36864
	ds_read_b128 v[94:97], v66 offset:55296
	ds_read_b128 v[110:113], v0 offset:36896
	ds_read_b128 v[114:117], v66 offset:55328
	ds_read_b128 v[118:121], v0 offset:41472
	ds_read_b128 v[122:125], v0 offset:41504
	s_waitcnt lgkmcnt(4)
	v_mfma_f32_32x32x16_bf16 v[34:49], v[86:89], v[94:97], v[34:49]
	s_waitcnt lgkmcnt(1)
	v_mfma_f32_32x32x16_bf16 v[2:17], v[118:121], v[94:97], v[2:17]
	ds_read_b128 v[94:97], v66 offset:59904
	ds_read_b128 v[126:129], v66 offset:59936
	s_waitcnt lgkmcnt(1)
	v_mfma_f32_32x32x16_bf16 v[50:65], v[86:89], v[94:97], v[50:65]
	global_load_dwordx4 v[86:89], v72, s[0:1] offset:1664
	global_load_dwordx4 v[134:137], v72, s[2:3] offset:1664
	s_waitcnt vmcnt(9)
	ds_write_b128 v67, v[98:101]
	s_waitcnt vmcnt(8)
	ds_write_b128 v67, v[130:133] offset:18432
	v_mfma_f32_32x32x16_bf16 v[18:33], v[118:121], v[94:97], v[18:33]
	global_load_dwordx4 v[94:97], v71, s[0:1] offset:1664
	global_load_dwordx4 v[98:101], v71, s[2:3] offset:1664
	v_mfma_f32_32x32x16_bf16 v[2:17], v[122:125], v[114:117], v[2:17]
	s_waitcnt lgkmcnt(2)
	v_mfma_f32_32x32x16_bf16 v[18:33], v[122:125], v[126:129], v[18:33]
	v_mfma_f32_32x32x16_bf16 v[34:49], v[110:113], v[114:117], v[34:49]
	v_mfma_f32_32x32x16_bf16 v[50:65], v[110:113], v[126:129], v[50:65]
	ds_read_b128 v[110:113], v0 offset:36928
	ds_read_b128 v[114:117], v0 offset:41536
	ds_read_b128 v[118:121], v66 offset:55360
	ds_read_b128 v[130:133], v66 offset:59968
	s_waitcnt vmcnt(9)
	ds_write_b128 v67, v[74:77] offset:4608
	s_waitcnt vmcnt(8)
	ds_write_b128 v67, v[102:105] offset:23040
	global_load_dwordx4 v[74:77], v70, s[0:1] offset:1664
	global_load_dwordx4 v[102:105], v70, s[2:3] offset:1664
	s_waitcnt lgkmcnt(3)
	v_mfma_f32_32x32x16_bf16 v[2:17], v[114:117], v[118:121], v[2:17]
	s_waitcnt lgkmcnt(2)
	v_mfma_f32_32x32x16_bf16 v[18:33], v[114:117], v[130:133], v[18:33]
	v_mfma_f32_32x32x16_bf16 v[34:49], v[110:113], v[118:121], v[34:49]
	v_mfma_f32_32x32x16_bf16 v[50:65], v[110:113], v[130:133], v[50:65]
	ds_read_b128 v[110:113], v0 offset:36960
	ds_read_b128 v[118:121], v0 offset:41568
	ds_read_b128 v[122:125], v66 offset:55392
	ds_read_b128 v[126:129], v66 offset:60000
	s_waitcnt vmcnt(9)
	ds_write_b128 v67, v[78:81] offset:9216
	s_waitcnt vmcnt(8)
	ds_write_b128 v67, v[106:109] offset:27648
	global_load_dwordx4 v[78:81], v69, s[0:1] offset:1664
	global_load_dwordx4 v[106:109], v69, s[2:3] offset:1664
	s_waitcnt lgkmcnt(3)
	v_mfma_f32_32x32x16_bf16 v[2:17], v[118:121], v[122:125], v[2:17]
	s_waitcnt vmcnt(9)
	ds_write_b128 v67, v[82:85] offset:13824
	s_waitcnt vmcnt(8)
	ds_write_b128 v67, v[90:93] offset:32256
	s_waitcnt lgkmcnt(4)
	v_mfma_f32_32x32x16_bf16 v[18:33], v[118:121], v[126:129], v[18:33]
	v_mfma_f32_32x32x16_bf16 v[34:49], v[110:113], v[122:125], v[34:49]
	v_mfma_f32_32x32x16_bf16 v[50:65], v[110:113], v[126:129], v[50:65]
	s_waitcnt lgkmcnt(0)
	s_barrier
	ds_read_b128 v[82:85], v0
	ds_read_b128 v[90:93], v66 offset:18432
	ds_read_b128 v[110:113], v0 offset:32
	ds_read_b128 v[114:117], v66 offset:18464
	ds_read_b128 v[118:121], v0 offset:4608
	ds_read_b128 v[122:125], v0 offset:4640
	s_waitcnt lgkmcnt(4)
	v_mfma_f32_32x32x16_bf16 v[34:49], v[82:85], v[90:93], v[34:49]
	s_waitcnt lgkmcnt(1)
	v_mfma_f32_32x32x16_bf16 v[2:17], v[118:121], v[90:93], v[2:17]
	ds_read_b128 v[90:93], v66 offset:23040
	ds_read_b128 v[126:129], v66 offset:23072
	s_waitcnt lgkmcnt(1)
	v_mfma_f32_32x32x16_bf16 v[50:65], v[82:85], v[90:93], v[50:65]
	global_load_dwordx4 v[82:85], v72, s[0:1] offset:1792
	global_load_dwordx4 v[130:133], v72, s[2:3] offset:1792
	s_waitcnt vmcnt(9)
	ds_write_b128 v67, v[86:89] offset:36864
	s_waitcnt vmcnt(8)
	ds_write_b128 v67, v[134:137] offset:55296
	v_mfma_f32_32x32x16_bf16 v[18:33], v[118:121], v[90:93], v[18:33]
	global_load_dwordx4 v[86:89], v71, s[0:1] offset:1792
	global_load_dwordx4 v[90:93], v71, s[2:3] offset:1792
	v_mfma_f32_32x32x16_bf16 v[2:17], v[122:125], v[114:117], v[2:17]
	s_waitcnt lgkmcnt(2)
	v_mfma_f32_32x32x16_bf16 v[18:33], v[122:125], v[126:129], v[18:33]
	v_mfma_f32_32x32x16_bf16 v[34:49], v[110:113], v[114:117], v[34:49]
	v_mfma_f32_32x32x16_bf16 v[50:65], v[110:113], v[126:129], v[50:65]
	ds_read_b128 v[110:113], v0 offset:64
	ds_read_b128 v[114:117], v0 offset:4672
	ds_read_b128 v[118:121], v66 offset:18496
	ds_read_b128 v[134:137], v66 offset:23104
	s_waitcnt vmcnt(9)
	ds_write_b128 v67, v[94:97] offset:41472
	s_waitcnt vmcnt(8)
	ds_write_b128 v67, v[98:101] offset:59904
	global_load_dwordx4 v[94:97], v70, s[0:1] offset:1792
	global_load_dwordx4 v[98:101], v70, s[2:3] offset:1792
	s_waitcnt lgkmcnt(3)
	v_mfma_f32_32x32x16_bf16 v[2:17], v[114:117], v[118:121], v[2:17]
	s_waitcnt lgkmcnt(2)
	v_mfma_f32_32x32x16_bf16 v[18:33], v[114:117], v[134:137], v[18:33]
	v_mfma_f32_32x32x16_bf16 v[34:49], v[110:113], v[118:121], v[34:49]
	v_mfma_f32_32x32x16_bf16 v[50:65], v[110:113], v[134:137], v[50:65]
	ds_read_b128 v[110:113], v0 offset:96
	ds_read_b128 v[118:121], v0 offset:4704
	ds_read_b128 v[122:125], v66 offset:18528
	ds_read_b128 v[126:129], v66 offset:23136
	s_waitcnt vmcnt(9)
	ds_write_b128 v67, v[74:77] offset:46080
	s_waitcnt vmcnt(8)
	ds_write_b128 v67, v[102:105] offset:64512
	global_load_dwordx4 v[74:77], v69, s[0:1] offset:1792
	global_load_dwordx4 v[102:105], v69, s[2:3] offset:1792
	s_waitcnt lgkmcnt(3)
	v_mfma_f32_32x32x16_bf16 v[2:17], v[118:121], v[122:125], v[2:17]
	s_waitcnt vmcnt(9)
	ds_write_b128 v67, v[78:81] offset:50688
	s_waitcnt vmcnt(8)
	ds_write_b128 v68, v[106:109] offset:13824
	s_waitcnt lgkmcnt(4)
	v_mfma_f32_32x32x16_bf16 v[18:33], v[118:121], v[126:129], v[18:33]
	v_mfma_f32_32x32x16_bf16 v[34:49], v[110:113], v[122:125], v[34:49]
	v_mfma_f32_32x32x16_bf16 v[50:65], v[110:113], v[126:129], v[50:65]
	s_waitcnt lgkmcnt(0)
	s_barrier
; #define GL1_(RA, RB, i) { RA[i] = *(const u32x4*)(ap + (aoff + (i) * astep)); if ((i) < NB) RB[(i) < NB ? (i) : 0] = *(const u32x4*)(bp + (boff + (i) * bstep)); }
; #define LS1_(RA, RB, ST, i) { char* sn_ = lds + (ST) * STAGE; *(u32x4*)(sn_ + wofs + (i) * 32 * LROW) = RA[i]; \
;                               if ((i) < NB) *(u32x4*)(sn_ + STAGE_OP + wofs + (i) * 32 * LROW) = RB[(i) < NB ? (i) : 0]; }
; template <int NJ> DI void gemm_mainloop_reg(const bf16_t* __restrict__ A, int lda, const bf16_t* __restrict__ Bt, int ldb, int K, f32x16 (&acc)[2][NJ], char* lds) {
;     ...
; #pragma unroll
;   for (int i = 0; i < 4; ++i) GL1_(ra0, rb0, i);
;   ap += 128; bp += 128;
; #pragma unroll
;   for (int i = 0; i < 4; ++i) GL1_(ra1, rb1, i);
;   ap += 128; bp += 128;
; #pragma unroll
;   for (int i = 0; i < 4; ++i) LS1_(ra0, rb0, 0, i);
;   __syncthreads();
;   const int nk = K >> 6;
;   for (int kt = 0; kt < nk; kt += 2) {
;     const bool l0 = (kt + 2 < nk), l1 = (kt + 3 < nk);
;     STEP_(0, l0, ra0, rb0, true, ra1, rb1);
;     __syncthreads();
;     STEP_(1, l1, ra1, rb1, l0, ra0, rb0);
;     __syncthreads();
;   }
	ds_read_b128 v[78:81], v0 offset:36864
	ds_read_b128 v[106:109], v66 offset:55296
	ds_read_b128 v[110:113], v0 offset:41472
	s_waitcnt lgkmcnt(1)
	v_mfma_f32_32x32x16_bf16 v[34:49], v[78:81], v[106:109], v[34:49]
	s_waitcnt lgkmcnt(0)
	v_mfma_f32_32x32x16_bf16 v[2:17], v[110:113], v[106:109], v[2:17]
	ds_read_b128 v[106:109], v66 offset:59904
	s_waitcnt lgkmcnt(0)
	v_mfma_f32_32x32x16_bf16 v[50:65], v[78:81], v[106:109], v[50:65]
	global_load_dwordx4 v[78:81], v72, s[0:1] offset:1920
	global_load_dwordx4 v[114:117], v72, s[2:3] offset:1920
	ds_read_b128 v[118:121], v0 offset:36896
	ds_read_b128 v[122:125], v66 offset:55328
	ds_read_b128 v[126:129], v0 offset:41504
	ds_read_b128 v[134:137], v66 offset:59936
	s_waitcnt vmcnt(9)
	ds_write_b128 v67, v[82:85]
	s_waitcnt vmcnt(8)
	ds_write_b128 v67, v[130:133] offset:18432
	v_mfma_f32_32x32x16_bf16 v[18:33], v[110:113], v[106:109], v[18:33]
	global_load_dwordx4 v[82:85], v71, s[0:1] offset:1920
	global_load_dwordx4 v[106:109], v71, s[2:3] offset:1920
	s_waitcnt lgkmcnt(3)
	v_mfma_f32_32x32x16_bf16 v[2:17], v[126:129], v[122:125], v[2:17]
	s_waitcnt lgkmcnt(2)
	v_mfma_f32_32x32x16_bf16 v[18:33], v[126:129], v[134:137], v[18:33]
	v_mfma_f32_32x32x16_bf16 v[34:49], v[118:121], v[122:125], v[34:49]
	v_mfma_f32_32x32x16_bf16 v[50:65], v[118:121], v[134:137], v[50:65]
	ds_read_b128 v[110:113], v0 offset:36928
	ds_read_b128 v[118:121], v0 offset:41536
	ds_read_b128 v[122:125], v66 offset:55360
	ds_read_b128 v[130:133], v66 offset:59968
	s_waitcnt vmcnt(9)
	ds_write_b128 v67, v[86:89] offset:4608
	s_waitcnt vmcnt(8)
	ds_write_b128 v67, v[90:93] offset:23040
	global_load_dwordx4 v[86:89], v70, s[0:1] offset:1920
	s_nop 0
	global_load_dwordx4 v[70:73], v70, s[2:3] offset:1920
	s_waitcnt lgkmcnt(3)
	v_mfma_f32_32x32x16_bf16 v[2:17], v[118:121], v[122:125], v[2:17]
	s_waitcnt lgkmcnt(2)
	v_mfma_f32_32x32x16_bf16 v[18:33], v[118:121], v[130:133], v[18:33]
	v_mfma_f32_32x32x16_bf16 v[34:49], v[110:113], v[122:125], v[34:49]
	v_mfma_f32_32x32x16_bf16 v[50:65], v[110:113], v[130:133], v[50:65]
	ds_read_b128 v[90:93], v0 offset:36960
	ds_read_b128 v[110:113], v0 offset:41568
	ds_read_b128 v[122:125], v66 offset:55392
	ds_read_b128 v[126:129], v66 offset:60000
	s_waitcnt vmcnt(9)
	ds_write_b128 v67, v[94:97] offset:9216
	s_waitcnt vmcnt(8)
	ds_write_b128 v67, v[98:101] offset:27648
	s_waitcnt lgkmcnt(3)
	v_mfma_f32_32x32x16_bf16 v[34:49], v[90:93], v[122:125], v[34:49]
	s_waitcnt lgkmcnt(2)
	v_mfma_f32_32x32x16_bf16 v[50:65], v[90:93], v[126:129], v[50:65]
	global_load_dwordx4 v[90:93], v69, s[0:1] offset:1920
	global_load_dwordx4 v[94:97], v69, s[2:3] offset:1920
	s_waitcnt vmcnt(9)
	ds_write_b128 v67, v[74:77] offset:13824
	s_waitcnt vmcnt(8)
	ds_write_b128 v67, v[102:105] offset:32256
	v_mfma_f32_32x32x16_bf16 v[2:17], v[110:113], v[122:125], v[2:17]
	v_mfma_f32_32x32x16_bf16 v[18:33], v[110:113], v[126:129], v[18:33]
	s_waitcnt lgkmcnt(0)
	s_barrier
	ds_read_b128 v[74:77], v0
	ds_read_b128 v[98:101], v66 offset:18432
	ds_read_b128 v[102:105], v0 offset:4608
	s_waitcnt lgkmcnt(1)
	v_mfma_f32_32x32x16_bf16 v[34:49], v[74:77], v[98:101], v[34:49]
	s_waitcnt lgkmcnt(0)
	v_mfma_f32_32x32x16_bf16 v[2:17], v[102:105], v[98:101], v[2:17]
	ds_read_b128 v[98:101], v66 offset:23040
	s_waitcnt lgkmcnt(0)
	v_mfma_f32_32x32x16_bf16 v[18:33], v[102:105], v[98:101], v[18:33]
	v_mfma_f32_32x32x16_bf16 v[50:65], v[74:77], v[98:101], v[50:65]
	ds_read_b128 v[74:77], v0 offset:32
	ds_read_b128 v[110:113], v66 offset:18464
	ds_read_b128 v[118:121], v0 offset:4640
	ds_read_b128 v[122:125], v66 offset:23072
	s_waitcnt vmcnt(7)
	ds_write_b128 v67, v[78:81] offset:36864
	s_waitcnt vmcnt(6)
	ds_write_b128 v67, v[114:117] offset:55296
	s_waitcnt lgkmcnt(3)
	v_mfma_f32_32x32x16_bf16 v[2:17], v[118:121], v[110:113], v[2:17]
	s_waitcnt lgkmcnt(2)
	v_mfma_f32_32x32x16_bf16 v[18:33], v[118:121], v[122:125], v[18:33]
	v_mfma_f32_32x32x16_bf16 v[34:49], v[74:77], v[110:113], v[34:49]
	v_mfma_f32_32x32x16_bf16 v[50:65], v[74:77], v[122:125], v[50:65]
	ds_read_b128 v[74:77], v0 offset:64
	ds_read_b128 v[78:81], v0 offset:4672
	ds_read_b128 v[98:101], v66 offset:18496
	ds_read_b128 v[102:105], v66 offset:23104
	s_waitcnt vmcnt(5)
	ds_write_b128 v67, v[82:85] offset:41472
	s_waitcnt vmcnt(4)
	ds_write_b128 v67, v[106:109] offset:59904
	s_waitcnt lgkmcnt(3)
	v_mfma_f32_32x32x16_bf16 v[2:17], v[78:81], v[98:101], v[2:17]
	s_waitcnt lgkmcnt(2)
	v_mfma_f32_32x32x16_bf16 v[18:33], v[78:81], v[102:105], v[18:33]
	v_mfma_f32_32x32x16_bf16 v[34:49], v[74:77], v[98:101], v[34:49]
	v_mfma_f32_32x32x16_bf16 v[50:65], v[74:77], v[102:105], v[50:65]
	ds_read_b128 v[74:77], v0 offset:96
	ds_read_b128 v[82:85], v0 offset:4704
	ds_read_b128 v[98:101], v66 offset:18528
	ds_read_b128 v[106:109], v66 offset:23136
	s_waitcnt vmcnt(3)
	ds_write_b128 v67, v[86:89] offset:46080
	s_waitcnt vmcnt(2)
	ds_write_b128 v67, v[70:73] offset:64512
	s_waitcnt lgkmcnt(3)
	v_mfma_f32_32x32x16_bf16 v[2:17], v[82:85], v[98:101], v[2:17]
	s_waitcnt vmcnt(1)
	ds_write_b128 v67, v[90:93] offset:50688
	s_waitcnt vmcnt(0)
	ds_write_b128 v68, v[94:97] offset:13824
	s_waitcnt lgkmcnt(4)
	v_mfma_f32_32x32x16_bf16 v[18:33], v[82:85], v[106:109], v[18:33]
	v_mfma_f32_32x32x16_bf16 v[34:49], v[74:77], v[98:101], v[34:49]
	v_mfma_f32_32x32x16_bf16 v[50:65], v[74:77], v[106:109], v[50:65]
	s_waitcnt lgkmcnt(0)
	s_barrier
; DI int tid_() { int t = threadIdx.x; asm volatile("" : "+v"(t)); return t; }
; DI unsigned pk2(float a, float b) { f32x2 v = {a, b}; bf16x2_t r = __builtin_convertvector(v, bf16x2_t); return __builtin_bit_cast(unsigned, r); }
; template <int NJ> DI void acc_to_lds(const f32x16 (&acc)[2][NJ], float* cl) {
;   const int tid = tid_(), lane = tid & 63, w = tid >> 6, wm = w >> 1, wn = w & 1, h = lane >> 5, c = lane & 31;
; #pragma unroll
;   for (int i = 0; i < 2; ++i)
; #pragma unroll
;     for (int j = 0; j < NJ; ++j)
; #pragma unroll
;       for (int r = 0; r < 16; ++r) {
;         const int row = wm * 64 + i * 32 + (r & 3) + 8 * (r >> 2) + 4 * h;
;         cl[row * CLD + wn * 32 * NJ + j * 32 + c] = acc[i][j][r];
;       }
; }
; template <int NJ> DI void resid_epilogue(float* __restrict__ x, bf16_t* __restrict__ xb, float* __restrict__ ssn, int mt, int nt, const float* cl, float scale) {
;   constexpr int LPR = 16 * NJ, RPP = 256 / LPR, NP = 128 / RPP;
;   const int tid = tid_(), c4 = (tid & (LPR - 1)) * 4, r0 = tid / LPR;
; #pragma unroll 4
;   for (int it = 0; it < NP; ++it) {
;     const int row = r0 + RPP * it;
;     const f32x4 c = *(const f32x4*)(cl + row * CLD + c4);
;     const size_t gi = (size_t)(mt * 128 + row) * DM + nt * (64 * NJ) + c4;
;     f32x4 xv = *(const f32x4*)(x + gi);
;     xv = xv + scale * c;
;     *(f32x4*)(x + gi) = xv;
;     u32x2 p; p.x = pk2(xv[0], xv[1]); p.y = pk2(xv[2], xv[3]);
;     *(u32x2*)(xb + (size_t)(mt * 128 + row) * LDX + nt * (64 * NJ) + c4) = p;
;     float s_ = xv[0] * xv[0] + xv[1] * xv[1] + xv[2] * xv[2] + xv[3] * xv[3];
;     if (NJ == 2) s_ += __shfl_xor(s_, 16);
;     s_ += __shfl_xor(s_, 8); s_ += __shfl_xor(s_, 4); s_ += __shfl_xor(s_, 2); s_ += __shfl_xor(s_, 1);
;     if ((tid & (LPR - 1)) == 0) atomicAdd(ssn + mt * 128 + row, s_);
	ds_read_b128 v[68:71], v0 offset:36864
	ds_read_b128 v[72:75], v66 offset:55296
	ds_read_b128 v[76:79], v0 offset:41472
	s_waitcnt lgkmcnt(1)
	v_mfma_f32_32x32x16_bf16 v[34:49], v[68:71], v[72:75], v[34:49]
	s_waitcnt lgkmcnt(0)
	v_mfma_f32_32x32x16_bf16 v[2:17], v[76:79], v[72:75], v[2:17]
	ds_read_b128 v[72:75], v66 offset:59904
	s_waitcnt lgkmcnt(0)
	v_mfma_f32_32x32x16_bf16 v[18:33], v[76:79], v[72:75], v[18:33]
	v_mfma_f32_32x32x16_bf16 v[50:65], v[68:71], v[72:75], v[50:65]
	ds_read_b128 v[68:71], v0 offset:36896
	ds_read_b128 v[80:83], v66 offset:55328
	ds_read_b128 v[84:87], v0 offset:41504
	ds_read_b128 v[88:91], v66 offset:59936
	s_waitcnt lgkmcnt(1)
	v_mfma_f32_32x32x16_bf16 v[2:17], v[84:87], v[80:83], v[2:17]
	s_waitcnt lgkmcnt(0)
	v_mfma_f32_32x32x16_bf16 v[18:33], v[84:87], v[88:91], v[18:33]
	v_mfma_f32_32x32x16_bf16 v[34:49], v[68:71], v[80:83], v[34:49]
	v_mfma_f32_32x32x16_bf16 v[50:65], v[68:71], v[88:91], v[50:65]
	ds_read_b128 v[68:71], v0 offset:36928
	ds_read_b128 v[72:75], v0 offset:41536
	ds_read_b128 v[76:79], v66 offset:55360
	ds_read_b128 v[80:83], v66 offset:59968
	s_waitcnt lgkmcnt(1)
	v_mfma_f32_32x32x16_bf16 v[2:17], v[72:75], v[76:79], v[2:17]
	s_waitcnt lgkmcnt(0)
	v_mfma_f32_32x32x16_bf16 v[18:33], v[72:75], v[80:83], v[18:33]
	v_mfma_f32_32x32x16_bf16 v[34:49], v[68:71], v[76:79], v[34:49]
	v_mfma_f32_32x32x16_bf16 v[50:65], v[68:71], v[80:83], v[50:65]
	ds_read_b128 v[68:71], v0 offset:36960
	ds_read_b128 v[76:79], v0 offset:41568
	ds_read_b128 v[84:87], v66 offset:55392
	ds_read_b128 v[88:91], v66 offset:60000
	s_waitcnt lgkmcnt(1)
	v_mfma_f32_32x32x16_bf16 v[2:17], v[76:79], v[84:87], v[2:17]
	s_waitcnt lgkmcnt(0)
	v_mfma_f32_32x32x16_bf16 v[18:33], v[76:79], v[88:91], v[18:33]
	v_mfma_f32_32x32x16_bf16 v[34:49], v[68:71], v[84:87], v[34:49]
	v_mfma_f32_32x32x16_bf16 v[50:65], v[68:71], v[88:91], v[50:65]
	s_setprio 0
	s_nop 0
	v_mov_b32_e32 v0, v199
	s_barrier
	s_add_i32 s0, s35, s11
	v_lshrrev_b32_e32 v67, 3, v0
	v_lshrrev_b32_e32 v66, 1, v0
	v_and_b32_e32 v67, 4, v67
	v_and_b32_e32 v0, 0x5f, v0
	v_and_or_b32 v66, v66, s17, v67
	v_mul_lo_u32 v66, v66, s15
	v_lshlrev_b32_e32 v0, 2, v0
	v_add3_u32 v0, 0, v66, v0
	s_nop 0
	ds_write2_b32 v0, v34, v50 offset1:32
	ds_write2_b32 v0, v35, v51 offset0:132 offset1:164
	v_add_u32_e32 v34, 0x400, v0
	ds_write2_b32 v34, v36, v52 offset0:8 offset1:40
	ds_write2_b32 v34, v37, v53 offset0:140 offset1:172
	v_add_u32_e32 v34, 0x1000, v0
	ds_write2_b32 v34, v38, v54 offset0:32 offset1:64
	ds_write2_b32 v34, v39, v55 offset0:164 offset1:196
	v_add_u32_e32 v34, 0x1400, v0
	ds_write2_b32 v34, v40, v56 offset0:40 offset1:72
	ds_write2_b32 v34, v41, v57 offset0:172 offset1:204
	v_add_u32_e32 v34, 0x2000, v0
	ds_write2_b32 v34, v42, v58 offset0:64 offset1:96
	ds_write2_b32 v34, v43, v59 offset0:196 offset1:228
	v_add_u32_e32 v34, 0x2400, v0
	ds_write2_b32 v34, v44, v60 offset0:72 offset1:104
	ds_write2_b32 v34, v45, v61 offset0:204 offset1:236
	v_add_u32_e32 v34, 0x3000, v0
	ds_write2_b32 v34, v46, v62 offset0:96 offset1:128
	v_add_u32_e32 v34, 0x3200, v0
	ds_write2_b32 v34, v47, v63 offset0:100 offset1:132
	v_add_u32_e32 v34, 0x3400, v0
	ds_write2_b32 v34, v48, v64 offset0:104 offset1:136
	v_add_u32_e32 v34, 0x3600, v0
	ds_write2_b32 v34, v49, v65 offset0:108 offset1:140
	v_add_u32_e32 v34, 0x4000, v0
	ds_write2_b32 v34, v2, v18 offset0:128 offset1:160
	v_add_u32_e32 v2, 0x4400, v0
	ds_write2_b32 v2, v3, v19 offset0:4 offset1:36
	ds_write2_b32 v2, v4, v20 offset0:136 offset1:168
	v_add_u32_e32 v2, 0x4800, v0
	ds_write2_b32 v2, v5, v21 offset0:12 offset1:44
	v_add_u32_e32 v2, 0x5000, v0
	ds_write2_b32 v2, v6, v22 offset0:160 offset1:192
	v_add_u32_e32 v2, 0x5400, v0
	ds_write2_b32 v2, v7, v23 offset0:36 offset1:68
	ds_write2_b32 v2, v8, v24 offset0:168 offset1:200
	v_add_u32_e32 v2, 0x5800, v0
	ds_write2_b32 v2, v9, v25 offset0:44 offset1:76
	v_add_u32_e32 v2, 0x6000, v0
	ds_write2_b32 v2, v10, v26 offset0:192 offset1:224
	v_add_u32_e32 v2, 0x6400, v0
	ds_write2_b32 v2, v11, v27 offset0:68 offset1:100
	ds_write2_b32 v2, v12, v28 offset0:200 offset1:232
	v_add_u32_e32 v2, 0x6800, v0
	ds_write2_b32 v2, v13, v29 offset0:76 offset1:108
	v_add_u32_e32 v2, 0x7200, v0
	ds_write2_b32 v2, v14, v30 offset0:96 offset1:128
	v_add_u32_e32 v2, 0x7400, v0
	ds_write2_b32 v2, v15, v31 offset0:100 offset1:132
	v_add_u32_e32 v2, 0x7600, v0
	v_add_u32_e32 v0, 0x7800, v0
	ds_write2_b32 v0, v17, v33 offset0:108 offset1:140
	v_mov_b32_e32 v0, v199
	ds_write2_b32 v2, v16, v32 offset0:104 offset1:136
	s_waitcnt lgkmcnt(0)
	s_barrier
	v_mov_b64_e32 v[18:19], s[72:73]
	v_ashrrev_i32_e32 v2, 31, v0
	v_lshrrev_b32_e32 v2, 27, v2
	v_and_b32_e32 v6, 31, v0
	v_add_u32_e32 v0, v0, v2
	v_ashrrev_i32_e32 v14, 5, v0
	v_add_u32_e32 v4, s0, v14
	v_mad_i64_i32 v[2:3], s[0:1], v4, s9, v[18:19]
	v_cmp_lt_i32_e32 vcc, v222, v220
	s_add_i32 s0, s35, s12
	v_add_u32_e32 v10, s0, v14
	v_cndmask_b32_e32 v0, v219, v222, vcc
	v_cmp_lt_i32_e32 vcc, v223, v220
	v_lshlrev_b32_e32 v22, 2, v0
	v_mad_i64_i32 v[8:9], s[0:1], v10, s9, v[18:19]
	v_cndmask_b32_e32 v0, v219, v223, vcc
	v_cmp_lt_i32_e32 vcc, v224, v220
	v_lshlrev_b32_e32 v23, 2, v0
	s_add_u32 s0, s36, s6
	v_cndmask_b32_e32 v0, v219, v224, vcc
	v_cmp_lt_i32_e32 vcc, v225, v220
	v_lshlrev_b32_e32 v24, 2, v0
	s_addc_u32 s1, 0, s7
	v_cndmask_b32_e32 v0, v219, v225, vcc
	v_cmp_lt_i32_e32 vcc, v226, v220
	s_add_i32 s35, s35, s13
	v_lshlrev_b32_e32 v25, 2, v0
	v_cndmask_b32_e32 v0, v219, v226, vcc
	v_add_u32_e32 v20, s37, v14
	v_add_u32_e32 v16, s35, v14
	v_lshlrev_b32_e32 v26, 2, v0
	v_cmp_eq_u32_e32 vcc, 0, v6
	v_ashrrev_i32_e32 v15, 31, v14
	v_ashrrev_i32_e32 v5, 31, v4
	v_lshlrev_b32_e32 v0, 3, v6
	v_lshlrev_b32_e32 v28, 4, v6
	v_mul_lo_u32 v6, v14, s15
	v_ashrrev_i32_e32 v21, 31, v20
	v_ashrrev_i32_e32 v11, 31, v10
	v_ashrrev_i32_e32 v17, 31, v16
	v_lshlrev_b64 v[4:5], 12, v[4:5]
	v_add3_u32 v27, v6, v28, 0
	v_lshlrev_b64 v[6:7], 12, v[20:21]
	v_lshlrev_b64 v[10:11], 12, v[10:11]
	v_lshl_add_u64 v[12:13], v[14:15], 2, s[0:1]
	v_mad_i64_i32 v[14:15], s[0:1], v16, s9, v[18:19]
	v_lshlrev_b64 v[16:17], 12, v[16:17]
	v_mad_i64_i32 v[18:19], s[0:1], v20, s9, v[18:19]
	v_lshl_add_u64 v[2:3], v[2:3], 0, v[0:1]
	v_or3_b32 v4, v4, s34, v28
	v_or3_b32 v6, v6, s34, v28
	v_lshl_add_u64 v[8:9], v[8:9], 0, v[0:1]
	v_or3_b32 v10, v10, s34, v28
	v_lshl_add_u64 v[14:15], v[14:15], 0, v[0:1]
	v_or3_b32 v16, v16, s34, v28
	v_lshl_add_u64 v[18:19], v[18:19], 0, v[0:1]
	v_lshl_add_u64 v[2:3], v[2:3], 0, s[80:81]
	v_lshl_add_u64 v[4:5], s[92:93], 0, v[4:5]
	v_lshl_add_u64 v[6:7], s[92:93], 0, v[6:7]
	v_lshl_add_u64 v[8:9], v[8:9], 0, s[80:81]
	v_lshl_add_u64 v[10:11], s[92:93], 0, v[10:11]
	v_lshl_add_u64 v[14:15], v[14:15], 0, s[80:81]
	v_lshl_add_u64 v[16:17], s[92:93], 0, v[16:17]
	v_lshl_add_u64 v[18:19], v[18:19], 0, s[80:81]
	s_mov_b64 s[0:1], 0
	s_branch .LBB0_1027

; template <int NJ> DI void gemm_mainloop_reg(const bf16_t* __restrict__ A, int lda, const bf16_t* __restrict__ Bt, int ldb, int K, f32x16 (&acc)[2][NJ], char* lds) {
;   const int tid = tid_(), lane = tid & 63, w = tid >> 6, wm = w >> 1, wn = w & 1;
;   const int lr = tid >> 3, lc = tid & 7;
;   const char* ap = (const char*)A;
;   const char* bp = (const char*)Bt;
;   const unsigned aoff = (unsigned)(lr * lda + lc * 8) * 2u, boff = (unsigned)(lr * ldb + lc * 8) * 2u;
;   const unsigned astep = (unsigned)(32 * lda) * 2u, bstep = (unsigned)(32 * ldb) * 2u;
;   constexpr int NB = 2 * NJ;
;   u32x4 ra0[4], rb0[NB], ra1[4], rb1[NB];
;   const int wofs = lr * LROW + lc * 16;
;   const int a_rd = (wm * 64 + (lane & 31)) * LROW + (lane >> 5) * 16;
;   const int b_rd = STAGE_OP + (wn * 32 * NJ + (lane & 31)) * LROW + (lane >> 5) * 16;
;     ...
; #pragma unroll
; DI int grab_next(unsigned* ctr, char* lds) {
;   volatile int* nx = (volatile int*)(lds + OFF_RR + 528);
;   if (tid_() == 0) *nx = (int)__hip_atomic_fetch_add(ctr, 1u, __ATOMIC_RELAXED, __HIP_MEMORY_SCOPE_AGENT);
;   __syncthreads();
;   const int v = __builtin_amdgcn_readfirstlane(*nx);
;   __syncthreads();
;   return v;
; }
; DI bf16_t* wsb(const Ctx& c, size_t off) { return (bf16_t*)(c.ws + off); }
; DI float* ss_site(const Ctx& c, int layer, int site) { return (float*)(c.ws + OFF_SS) + ((size_t)layer * 6 + site) * TC; }
; DI const bf16_t* wgt(const Ctx& c, size_t off) { return (const bf16_t*)(c.ws + OFF_W) + (size_t)c.layer * W_LAYER + off; }
; DI void phase_ffn_in(const Ctx& c, const bf16_t* A, size_t woff, int site) {
;   const bf16_t* Bt = wgt(c, woff);
;   bf16_t* act = wsb(c, OFF_ACT);
;   const float* ss = ss_site(c, c.layer, site);
;   float* cl = (float*)c.lds; float* rr = (float*)(c.lds + OFF_RR);
;   const int tid = tid_();
;   const int xcd_ = blockIdx.x & 7;
;   unsigned* ctr = (unsigned*)(c.ws + OFF_BAR) + CTR_FFN + ((c.chunk * 2 + c.layer) * 2 + (site == 2 ? 1 : 0)) * 8 + xcd_;
;   for (;;) {
;     const int j_ = grab_next(ctr, c.lds);
;     if (j_ >= 128 * 6) break;
;     const int mt = xcd_ * 16 + (j_ & 7) + 8 * ((j_ >> 6) & 1), nt = (j_ >> 7) * 8 + ((j_ >> 3) & 7);
;     if (nt >= 44) continue;
;     f32x16 acc[2][2]; zero_acc<2>(acc);
;     gemm_mainloop_reg<2>(A + (size_t)mt * 128 * LDX, LDX, Bt + (size_t)nt * 128 * LDX, LDX, DM, acc, c.lds);
.LBB0_1094:
	s_or_b64 exec, exec, s[2:3]
	s_cmp_lg_u32 s24, -1
	s_cselect_b32 s2, s24, 0
	s_cselect_b32 s3, s79, 0
	v_mov_b32_e32 v2, s2
	v_mov_b32_e32 v3, s3
	s_waitcnt lgkmcnt(0)
	s_barrier
	flat_load_dword v2, v[2:3] sc0 sc1
	s_waitcnt vmcnt(0)
	s_mov_b64 s[2:3], -1
	s_waitcnt lgkmcnt(0)
	s_barrier
	v_readfirstlane_b32 s4, v2
	s_cmpk_gt_i32 s4, 0x2ff
	s_cbranch_scc1 .LBB0_1089
	s_ashr_i32 s2, s4, 4
	s_and_b32 s2, s2, -8
	s_bfe_u32 s3, s4, 0x30003
	s_or_b32 s6, s2, s3
	s_cmp_gt_i32 s6, 43
	s_cbranch_scc1 .LBB0_1088
	s_lshr_b32 s2, s4, 3
	s_and_b32 s7, s4, 7
	s_and_b32 s27, s2, 8
	s_or_b32 s2, s7, s27
	v_readlane_b32 s3, v250, 20
	s_or_b32 s36, s2, s3
	v_mov_b32_e32 v34, v199
	s_mul_i32 s2, s36, 0x44000
	v_readlane_b32 s3, v252, 10
	s_add_u32 s2, s3, s2
	v_ashrrev_i32_e32 v35, 3, v34
	v_lshlrev_b32_e32 v2, 4, v34
	v_readlane_b32 s3, v252, 11
	v_and_b32_e32 v36, 0x70, v2
	v_mul_lo_u32 v2, v35, s9
	s_addc_u32 s3, s3, 0
	s_mul_i32 s4, s6, 0x44000
	v_or_b32_e32 v80, v36, v2
	s_mul_hi_i32 s5, s6, 0x44000
	s_add_u32 s4, s25, s4
	v_add_u32_e32 v79, 0x11000, v80
	v_add_u32_e32 v78, 0x22000, v80
	v_add_u32_e32 v77, 0x33000, v80
	s_addc_u32 s5, s26, s5
	global_load_dwordx4 v[2:5], v80, s[2:3]
	global_load_dwordx4 v[6:9], v79, s[2:3]
	global_load_dwordx4 v[10:13], v78, s[2:3]
	global_load_dwordx4 v[14:17], v77, s[2:3]
	global_load_dwordx4 v[18:21], v80, s[4:5]
	global_load_dwordx4 v[22:25], v79, s[4:5]
	global_load_dwordx4 v[26:29], v78, s[4:5]
	global_load_dwordx4 v[30:33], v77, s[4:5]
	v_mul_lo_u32 v35, v35, s16
	v_lshrrev_b32_e32 v37, 1, v34
	v_and_b32_e32 v38, 31, v34
	v_add3_u32 v75, v35, v36, 0
	v_and_b32_e32 v39, 16, v37
	v_and_or_b32 v37, v37, s17, v38
	global_load_dwordx4 v[82:85], v80, s[2:3] offset:128
	global_load_dwordx4 v[86:89], v79, s[2:3] offset:128
	global_load_dwordx4 v[90:93], v78, s[2:3] offset:128
	global_load_dwordx4 v[94:97], v77, s[2:3] offset:128
	global_load_dwordx4 v[98:101], v80, s[4:5] offset:128
	global_load_dwordx4 v[102:105], v79, s[4:5] offset:128
	global_load_dwordx4 v[106:109], v78, s[4:5] offset:128
	global_load_dwordx4 v[110:113], v77, s[4:5] offset:128
	v_mul_lo_u32 v35, v37, s16
	v_add3_u32 v73, v35, v39, 0
	v_add_u32_e32 v76, 0xd800, v75
	s_waitcnt vmcnt(15)
	ds_write_b128 v75, v[2:5]
	s_waitcnt vmcnt(14)
	ds_write_b128 v75, v[6:9] offset:4608
	s_waitcnt vmcnt(13)
	ds_write_b128 v75, v[10:13] offset:9216
	s_waitcnt vmcnt(12)
	ds_write_b128 v75, v[14:17] offset:13824
	s_waitcnt vmcnt(11)
	ds_write_b128 v75, v[18:21] offset:18432
	s_waitcnt vmcnt(10)
	ds_write_b128 v75, v[22:25] offset:23040
	s_waitcnt vmcnt(9)
	ds_write_b128 v75, v[26:29] offset:27648
	s_waitcnt vmcnt(8)
	ds_write_b128 v75, v[30:33] offset:32256
	v_and_b32_e32 v2, 0x5f, v34
	v_mul_u32_u24_e32 v2, 0x90, v2
	v_add3_u32 v74, v2, v39, 0
	s_waitcnt lgkmcnt(0)
	s_barrier
	ds_read_b128 v[18:21], v73
	ds_read_b128 v[2:5], v74 offset:18432
	ds_read_b128 v[114:117], v73 offset:32
	ds_read_b128 v[118:121], v74 offset:18464
	ds_read_b128 v[22:25], v73 offset:4608
	ds_read_b128 v[122:125], v73 offset:4640
	ds_read_b128 v[26:29], v74 offset:23040
	ds_read_b128 v[126:129], v74 offset:23072
	global_load_dwordx4 v[130:133], v80, s[2:3] offset:256
	global_load_dwordx4 v[134:137], v80, s[4:5] offset:256
	s_waitcnt lgkmcnt(6)
	s_setprio 1
	s_nop 0
	v_mfma_f32_32x32x16_bf16 v[34:49], v[18:21], v[2:5], 0
	s_waitcnt vmcnt(9)
	ds_write_b128 v75, v[82:85] offset:36864
	s_waitcnt vmcnt(5)
	ds_write_b128 v75, v[98:101] offset:55296
	s_waitcnt lgkmcnt(5)
	v_mfma_f32_32x32x16_bf16 v[2:17], v[22:25], v[2:5], 0
	s_waitcnt lgkmcnt(3)
	v_mfma_f32_32x32x16_bf16 v[50:65], v[18:21], v[26:29], 0
	v_mfma_f32_32x32x16_bf16 v[18:33], v[22:25], v[26:29], 0
	global_load_dwordx4 v[82:85], v79, s[2:3] offset:256
	global_load_dwordx4 v[98:101], v79, s[4:5] offset:256
	v_mfma_f32_32x32x16_bf16 v[34:49], v[114:117], v[118:121], v[34:49]
	v_mfma_f32_32x32x16_bf16 v[2:17], v[122:125], v[118:121], v[2:17]
	s_waitcnt lgkmcnt(2)
	v_mfma_f32_32x32x16_bf16 v[50:65], v[114:117], v[126:129], v[50:65]
	ds_read_b128 v[114:117], v73 offset:64
	ds_read_b128 v[118:121], v73 offset:4672
	ds_read_b128 v[138:141], v74 offset:18496
	ds_read_b128 v[142:145], v74 offset:23104
	ds_write_b128 v75, v[86:89] offset:41472
	s_waitcnt vmcnt(6)
	ds_write_b128 v75, v[102:105] offset:59904
	v_mfma_f32_32x32x16_bf16 v[18:33], v[122:125], v[126:129], v[18:33]
	global_load_dwordx4 v[86:89], v78, s[2:3] offset:256
	global_load_dwordx4 v[102:105], v78, s[4:5] offset:256
	s_waitcnt lgkmcnt(3)
	v_mfma_f32_32x32x16_bf16 v[34:49], v[114:117], v[138:141], v[34:49]
	v_mfma_f32_32x32x16_bf16 v[2:17], v[118:121], v[138:141], v[2:17]
	s_waitcnt lgkmcnt(2)
	v_mfma_f32_32x32x16_bf16 v[50:65], v[114:117], v[142:145], v[50:65]
	ds_read_b128 v[114:117], v73 offset:96
	ds_read_b128 v[122:125], v73 offset:4704
	ds_read_b128 v[126:129], v74 offset:18528
	ds_read_b128 v[138:141], v74 offset:23136
	ds_write_b128 v75, v[90:93] offset:46080
	s_waitcnt vmcnt(7)
	ds_write_b128 v75, v[106:109] offset:64512
	v_mfma_f32_32x32x16_bf16 v[18:33], v[118:121], v[142:145], v[18:33]
	global_load_dwordx4 v[90:93], v77, s[2:3] offset:256
	global_load_dwordx4 v[106:109], v77, s[4:5] offset:256
	s_waitcnt lgkmcnt(3)
	v_mfma_f32_32x32x16_bf16 v[34:49], v[114:117], v[126:129], v[34:49]
	ds_write_b128 v75, v[94:97] offset:50688
	s_waitcnt vmcnt(8)
	ds_write_b128 v76, v[110:113] offset:13824
	v_mfma_f32_32x32x16_bf16 v[2:17], v[122:125], v[126:129], v[2:17]
	s_waitcnt lgkmcnt(4)
	v_mfma_f32_32x32x16_bf16 v[50:65], v[114:117], v[138:141], v[50:65]
	v_mfma_f32_32x32x16_bf16 v[18:33], v[122:125], v[138:141], v[18:33]
	s_waitcnt lgkmcnt(0)
	s_barrier
; #define GL1_(RA, RB, i) { RA[i] = *(const u32x4*)(ap + (aoff + (i) * astep)); if ((i) < NB) RB[(i) < NB ? (i) : 0] = *(const u32x4*)(bp + (boff + (i) * bstep)); }
; #define LS1_(RA, RB, ST, i) { char* sn_ = lds + (ST) * STAGE; *(u32x4*)(sn_ + wofs + (i) * 32 * LROW) = RA[i]; \
;                               if ((i) < NB) *(u32x4*)(sn_ + STAGE_OP + wofs + (i) * 32 * LROW) = RB[(i) < NB ? (i) : 0]; }
; template <int NJ> DI void gemm_mainloop_reg(const bf16_t* __restrict__ A, int lda, const bf16_t* __restrict__ Bt, int ldb, int K, f32x16 (&acc)[2][NJ], char* lds) {
;     ...
; #pragma unroll
;   for (int i = 0; i < 4; ++i) GL1_(ra0, rb0, i);
;   ap += 128; bp += 128;
; #pragma unroll
;   for (int i = 0; i < 4; ++i) GL1_(ra1, rb1, i);
;   ap += 128; bp += 128;
; #pragma unroll
;   for (int i = 0; i < 4; ++i) LS1_(ra0, rb0, 0, i);
;   __syncthreads();
;   const int nk = K >> 6;
;   for (int kt = 0; kt < nk; kt += 2) {
;     const bool l0 = (kt + 2 < nk), l1 = (kt + 3 < nk);
;     STEP_(0, l0, ra0, rb0, true, ra1, rb1);
;     __syncthreads();
;     STEP_(1, l1, ra1, rb1, l0, ra0, rb0);
;     __syncthreads();
;   }
	ds_read_b128 v[94:97], v73 offset:36864
	ds_read_b128 v[110:113], v74 offset:55296
	ds_read_b128 v[114:117], v73 offset:36896
	ds_read_b128 v[118:121], v74 offset:55328
	ds_read_b128 v[122:125], v73 offset:41472
	ds_read_b128 v[126:129], v73 offset:41504
	s_waitcnt lgkmcnt(4)
	v_mfma_f32_32x32x16_bf16 v[34:49], v[94:97], v[110:113], v[34:49]
	s_waitcnt lgkmcnt(1)
	v_mfma_f32_32x32x16_bf16 v[2:17], v[122:125], v[110:113], v[2:17]
	ds_read_b128 v[110:113], v74 offset:59904
	ds_read_b128 v[138:141], v74 offset:59936
	s_waitcnt lgkmcnt(1)
	v_mfma_f32_32x32x16_bf16 v[50:65], v[94:97], v[110:113], v[50:65]
	global_load_dwordx4 v[94:97], v80, s[2:3] offset:384
	global_load_dwordx4 v[142:145], v80, s[4:5] offset:384
	s_waitcnt vmcnt(9)
	ds_write_b128 v75, v[130:133]
	s_waitcnt vmcnt(8)
	ds_write_b128 v75, v[134:137] offset:18432
	v_mfma_f32_32x32x16_bf16 v[18:33], v[122:125], v[110:113], v[18:33]
	v_mfma_f32_32x32x16_bf16 v[34:49], v[114:117], v[118:121], v[34:49]
	s_waitcnt lgkmcnt(2)
	v_mfma_f32_32x32x16_bf16 v[50:65], v[114:117], v[138:141], v[50:65]
	global_load_dwordx4 v[110:113], v79, s[2:3] offset:384
	global_load_dwordx4 v[114:117], v79, s[4:5] offset:384
	v_mfma_f32_32x32x16_bf16 v[2:17], v[126:129], v[118:121], v[2:17]
	ds_read_b128 v[118:121], v73 offset:36928
	ds_read_b128 v[122:125], v73 offset:41536
	ds_read_b128 v[130:133], v74 offset:55360
	ds_read_b128 v[134:137], v74 offset:59968
	s_waitcnt vmcnt(9)
	ds_write_b128 v75, v[82:85] offset:4608
	s_waitcnt vmcnt(8)
	ds_write_b128 v75, v[98:101] offset:23040
	v_mfma_f32_32x32x16_bf16 v[18:33], v[126:129], v[138:141], v[18:33]
	global_load_dwordx4 v[82:85], v78, s[2:3] offset:384
	global_load_dwordx4 v[98:101], v78, s[4:5] offset:384
	s_waitcnt lgkmcnt(3)
	v_mfma_f32_32x32x16_bf16 v[34:49], v[118:121], v[130:133], v[34:49]
	v_mfma_f32_32x32x16_bf16 v[2:17], v[122:125], v[130:133], v[2:17]
	s_waitcnt lgkmcnt(2)
	v_mfma_f32_32x32x16_bf16 v[50:65], v[118:121], v[134:137], v[50:65]
	ds_read_b128 v[118:121], v73 offset:36960
	ds_read_b128 v[126:129], v73 offset:41568
	ds_read_b128 v[130:133], v74 offset:55392
	ds_read_b128 v[138:141], v74 offset:60000
	s_waitcnt vmcnt(9)
	ds_write_b128 v75, v[86:89] offset:9216
	s_waitcnt vmcnt(8)
	ds_write_b128 v75, v[102:105] offset:27648
	v_mfma_f32_32x32x16_bf16 v[18:33], v[122:125], v[134:137], v[18:33]
	global_load_dwordx4 v[86:89], v77, s[2:3] offset:384
	global_load_dwordx4 v[102:105], v77, s[4:5] offset:384
	s_waitcnt lgkmcnt(3)
	v_mfma_f32_32x32x16_bf16 v[34:49], v[118:121], v[130:133], v[34:49]
	s_waitcnt vmcnt(9)
	ds_write_b128 v75, v[90:93] offset:13824
	s_waitcnt vmcnt(8)
	ds_write_b128 v75, v[106:109] offset:32256
	v_mfma_f32_32x32x16_bf16 v[2:17], v[126:129], v[130:133], v[2:17]
	s_waitcnt lgkmcnt(4)
	v_mfma_f32_32x32x16_bf16 v[50:65], v[118:121], v[138:141], v[50:65]
	v_mfma_f32_32x32x16_bf16 v[18:33], v[126:129], v[138:141], v[18:33]
	s_waitcnt lgkmcnt(0)
	s_barrier
	ds_read_b128 v[90:93], v73
	ds_read_b128 v[106:109], v74 offset:18432
	ds_read_b128 v[118:121], v73 offset:32
	ds_read_b128 v[122:125], v74 offset:18464
	ds_read_b128 v[126:129], v73 offset:4608
	ds_read_b128 v[130:133], v73 offset:4640
	s_waitcnt lgkmcnt(4)
	v_mfma_f32_32x32x16_bf16 v[34:49], v[90:93], v[106:109], v[34:49]
	s_waitcnt lgkmcnt(1)
	v_mfma_f32_32x32x16_bf16 v[2:17], v[126:129], v[106:109], v[2:17]
	ds_read_b128 v[106:109], v74 offset:23040
	ds_read_b128 v[134:137], v74 offset:23072
	s_waitcnt lgkmcnt(1)
	v_mfma_f32_32x32x16_bf16 v[50:65], v[90:93], v[106:109], v[50:65]
	global_load_dwordx4 v[90:93], v80, s[2:3] offset:512
	global_load_dwordx4 v[138:141], v80, s[4:5] offset:512
	s_waitcnt vmcnt(9)
	ds_write_b128 v75, v[94:97] offset:36864
	s_waitcnt vmcnt(8)
	ds_write_b128 v75, v[142:145] offset:55296
	v_mfma_f32_32x32x16_bf16 v[18:33], v[126:129], v[106:109], v[18:33]
	global_load_dwordx4 v[94:97], v79, s[2:3] offset:512
	global_load_dwordx4 v[106:109], v79, s[4:5] offset:512
	v_mfma_f32_32x32x16_bf16 v[34:49], v[118:121], v[122:125], v[34:49]
	v_mfma_f32_32x32x16_bf16 v[2:17], v[130:133], v[122:125], v[2:17]
	s_waitcnt lgkmcnt(2)
	v_mfma_f32_32x32x16_bf16 v[50:65], v[118:121], v[134:137], v[50:65]
	ds_read_b128 v[118:121], v73 offset:64
	ds_read_b128 v[122:125], v73 offset:4672
	ds_read_b128 v[126:129], v74 offset:18496
	ds_read_b128 v[142:145], v74 offset:23104
	s_waitcnt vmcnt(9)
	ds_write_b128 v75, v[110:113] offset:41472
	s_waitcnt vmcnt(8)
	ds_write_b128 v75, v[114:117] offset:59904
	v_mfma_f32_32x32x16_bf16 v[18:33], v[130:133], v[134:137], v[18:33]
	global_load_dwordx4 v[110:113], v78, s[2:3] offset:512
	global_load_dwordx4 v[114:117], v78, s[4:5] offset:512
	s_waitcnt lgkmcnt(3)
	v_mfma_f32_32x32x16_bf16 v[34:49], v[118:121], v[126:129], v[34:49]
	v_mfma_f32_32x32x16_bf16 v[2:17], v[122:125], v[126:129], v[2:17]
	s_waitcnt lgkmcnt(2)
	v_mfma_f32_32x32x16_bf16 v[50:65], v[118:121], v[142:145], v[50:65]
	ds_read_b128 v[118:121], v73 offset:96
	ds_read_b128 v[126:129], v73 offset:4704
	ds_read_b128 v[130:133], v74 offset:18528
	ds_read_b128 v[134:137], v74 offset:23136
	s_waitcnt vmcnt(9)
	ds_write_b128 v75, v[82:85] offset:46080
	s_waitcnt vmcnt(8)
	ds_write_b128 v75, v[98:101] offset:64512
	v_mfma_f32_32x32x16_bf16 v[18:33], v[122:125], v[142:145], v[18:33]
	global_load_dwordx4 v[82:85], v77, s[2:3] offset:512
	global_load_dwordx4 v[98:101], v77, s[4:5] offset:512
	s_waitcnt lgkmcnt(3)
	v_mfma_f32_32x32x16_bf16 v[34:49], v[118:121], v[130:133], v[34:49]
	s_waitcnt vmcnt(9)
	ds_write_b128 v75, v[86:89] offset:50688
	s_waitcnt vmcnt(8)
	ds_write_b128 v76, v[102:105] offset:13824
	v_mfma_f32_32x32x16_bf16 v[2:17], v[126:129], v[130:133], v[2:17]
	s_waitcnt lgkmcnt(4)
	v_mfma_f32_32x32x16_bf16 v[50:65], v[118:121], v[134:137], v[50:65]
	v_mfma_f32_32x32x16_bf16 v[18:33], v[126:129], v[134:137], v[18:33]
	s_waitcnt lgkmcnt(0)
	s_barrier
; #define GL1_(RA, RB, i) { RA[i] = *(const u32x4*)(ap + (aoff + (i) * astep)); if ((i) < NB) RB[(i) < NB ? (i) : 0] = *(const u32x4*)(bp + (boff + (i) * bstep)); }
; #define LS1_(RA, RB, ST, i) { char* sn_ = lds + (ST) * STAGE; *(u32x4*)(sn_ + wofs + (i) * 32 * LROW) = RA[i]; \
;                               if ((i) < NB) *(u32x4*)(sn_ + STAGE_OP + wofs + (i) * 32 * LROW) = RB[(i) < NB ? (i) : 0]; }
; template <int NJ> DI void gemm_mainloop_reg(const bf16_t* __restrict__ A, int lda, const bf16_t* __restrict__ Bt, int ldb, int K, f32x16 (&acc)[2][NJ], char* lds) {
;     ...
; #pragma unroll
;   for (int i = 0; i < 4; ++i) GL1_(ra0, rb0, i);
;   ap += 128; bp += 128;
; #pragma unroll
;   for (int i = 0; i < 4; ++i) GL1_(ra1, rb1, i);
;   ap += 128; bp += 128;
; #pragma unroll
;   for (int i = 0; i < 4; ++i) LS1_(ra0, rb0, 0, i);
;   __syncthreads();
;   const int nk = K >> 6;
;   for (int kt = 0; kt < nk; kt += 2) {
;     const bool l0 = (kt + 2 < nk), l1 = (kt + 3 < nk);
;     STEP_(0, l0, ra0, rb0, true, ra1, rb1);
;     __syncthreads();
;     STEP_(1, l1, ra1, rb1, l0, ra0, rb0);
;     __syncthreads();
;   }
	ds_read_b128 v[86:89], v73 offset:36864
	ds_read_b128 v[102:105], v74 offset:55296
	ds_read_b128 v[118:121], v73 offset:36896
	ds_read_b128 v[122:125], v74 offset:55328
	ds_read_b128 v[126:129], v73 offset:41472
	ds_read_b128 v[130:133], v73 offset:41504
	s_waitcnt lgkmcnt(4)
	v_mfma_f32_32x32x16_bf16 v[34:49], v[86:89], v[102:105], v[34:49]
	s_waitcnt lgkmcnt(1)
	v_mfma_f32_32x32x16_bf16 v[2:17], v[126:129], v[102:105], v[2:17]
	ds_read_b128 v[102:105], v74 offset:59904
	ds_read_b128 v[134:137], v74 offset:59936
	s_waitcnt lgkmcnt(1)
	v_mfma_f32_32x32x16_bf16 v[50:65], v[86:89], v[102:105], v[50:65]
	global_load_dwordx4 v[86:89], v80, s[2:3] offset:640
	global_load_dwordx4 v[142:145], v80, s[4:5] offset:640
	s_waitcnt vmcnt(9)
	ds_write_b128 v75, v[90:93]
	s_waitcnt vmcnt(8)
	ds_write_b128 v75, v[138:141] offset:18432
	v_mfma_f32_32x32x16_bf16 v[18:33], v[126:129], v[102:105], v[18:33]
	global_load_dwordx4 v[90:93], v79, s[2:3] offset:640
	global_load_dwordx4 v[102:105], v79, s[4:5] offset:640
	v_mfma_f32_32x32x16_bf16 v[34:49], v[118:121], v[122:125], v[34:49]
	v_mfma_f32_32x32x16_bf16 v[2:17], v[130:133], v[122:125], v[2:17]
	s_waitcnt lgkmcnt(2)
	v_mfma_f32_32x32x16_bf16 v[50:65], v[118:121], v[134:137], v[50:65]
	ds_read_b128 v[118:121], v73 offset:36928
	ds_read_b128 v[122:125], v73 offset:41536
	ds_read_b128 v[126:129], v74 offset:55360
	ds_read_b128 v[138:141], v74 offset:59968
	s_waitcnt vmcnt(9)
	ds_write_b128 v75, v[94:97] offset:4608
	s_waitcnt vmcnt(8)
	ds_write_b128 v75, v[106:109] offset:23040
	v_mfma_f32_32x32x16_bf16 v[18:33], v[130:133], v[134:137], v[18:33]
	global_load_dwordx4 v[94:97], v78, s[2:3] offset:640
	global_load_dwordx4 v[106:109], v78, s[4:5] offset:640
	s_waitcnt lgkmcnt(3)
	v_mfma_f32_32x32x16_bf16 v[34:49], v[118:121], v[126:129], v[34:49]
	v_mfma_f32_32x32x16_bf16 v[2:17], v[122:125], v[126:129], v[2:17]
	s_waitcnt lgkmcnt(2)
	v_mfma_f32_32x32x16_bf16 v[50:65], v[118:121], v[138:141], v[50:65]
	ds_read_b128 v[118:121], v73 offset:36960
	ds_read_b128 v[126:129], v73 offset:41568
	ds_read_b128 v[130:133], v74 offset:55392
	ds_read_b128 v[134:137], v74 offset:60000
	s_waitcnt vmcnt(9)
	ds_write_b128 v75, v[110:113] offset:9216
	s_waitcnt vmcnt(8)
	ds_write_b128 v75, v[114:117] offset:27648
	v_mfma_f32_32x32x16_bf16 v[18:33], v[122:125], v[138:141], v[18:33]
	global_load_dwordx4 v[110:113], v77, s[2:3] offset:640
	global_load_dwordx4 v[114:117], v77, s[4:5] offset:640
	s_waitcnt lgkmcnt(3)
	v_mfma_f32_32x32x16_bf16 v[34:49], v[118:121], v[130:133], v[34:49]
	s_waitcnt vmcnt(9)
	ds_write_b128 v75, v[82:85] offset:13824
	s_waitcnt vmcnt(8)
	ds_write_b128 v75, v[98:101] offset:32256
	v_mfma_f32_32x32x16_bf16 v[2:17], v[126:129], v[130:133], v[2:17]
	s_waitcnt lgkmcnt(4)
	v_mfma_f32_32x32x16_bf16 v[50:65], v[118:121], v[134:137], v[50:65]
	v_mfma_f32_32x32x16_bf16 v[18:33], v[126:129], v[134:137], v[18:33]
	s_waitcnt lgkmcnt(0)
	s_barrier
	ds_read_b128 v[82:85], v73
	ds_read_b128 v[98:101], v74 offset:18432
	ds_read_b128 v[118:121], v73 offset:32
	ds_read_b128 v[122:125], v74 offset:18464
	ds_read_b128 v[126:129], v73 offset:4608
	ds_read_b128 v[130:133], v73 offset:4640
	s_waitcnt lgkmcnt(4)
	v_mfma_f32_32x32x16_bf16 v[34:49], v[82:85], v[98:101], v[34:49]
	s_waitcnt lgkmcnt(1)
	v_mfma_f32_32x32x16_bf16 v[2:17], v[126:129], v[98:101], v[2:17]
	ds_read_b128 v[98:101], v74 offset:23040
	ds_read_b128 v[134:137], v74 offset:23072
	s_waitcnt lgkmcnt(1)
	v_mfma_f32_32x32x16_bf16 v[50:65], v[82:85], v[98:101], v[50:65]
	global_load_dwordx4 v[82:85], v80, s[2:3] offset:768
	global_load_dwordx4 v[138:141], v80, s[4:5] offset:768
	s_waitcnt vmcnt(9)
	ds_write_b128 v75, v[86:89] offset:36864
	s_waitcnt vmcnt(8)
	ds_write_b128 v75, v[142:145] offset:55296
	v_mfma_f32_32x32x16_bf16 v[18:33], v[126:129], v[98:101], v[18:33]
	global_load_dwordx4 v[86:89], v79, s[2:3] offset:768
	global_load_dwordx4 v[98:101], v79, s[4:5] offset:768
	v_mfma_f32_32x32x16_bf16 v[34:49], v[118:121], v[122:125], v[34:49]
	v_mfma_f32_32x32x16_bf16 v[2:17], v[130:133], v[122:125], v[2:17]
	s_waitcnt lgkmcnt(2)
	v_mfma_f32_32x32x16_bf16 v[50:65], v[118:121], v[134:137], v[50:65]
	ds_read_b128 v[118:121], v73 offset:64
	ds_read_b128 v[122:125], v73 offset:4672
	ds_read_b128 v[126:129], v74 offset:18496
	ds_read_b128 v[142:145], v74 offset:23104
	s_waitcnt vmcnt(9)
	ds_write_b128 v75, v[90:93] offset:41472
	s_waitcnt vmcnt(8)
	ds_write_b128 v75, v[102:105] offset:59904
	v_mfma_f32_32x32x16_bf16 v[18:33], v[130:133], v[134:137], v[18:33]
	global_load_dwordx4 v[90:93], v78, s[2:3] offset:768
	global_load_dwordx4 v[102:105], v78, s[4:5] offset:768
	s_waitcnt lgkmcnt(3)
	v_mfma_f32_32x32x16_bf16 v[34:49], v[118:121], v[126:129], v[34:49]
	v_mfma_f32_32x32x16_bf16 v[2:17], v[122:125], v[126:129], v[2:17]
	s_waitcnt lgkmcnt(2)
	v_mfma_f32_32x32x16_bf16 v[50:65], v[118:121], v[142:145], v[50:65]
	ds_read_b128 v[118:121], v73 offset:96
	ds_read_b128 v[126:129], v73 offset:4704
	ds_read_b128 v[130:133], v74 offset:18528
	ds_read_b128 v[134:137], v74 offset:23136
	s_waitcnt vmcnt(9)
	ds_write_b128 v75, v[94:97] offset:46080
	s_waitcnt vmcnt(8)
	ds_write_b128 v75, v[106:109] offset:64512
	v_mfma_f32_32x32x16_bf16 v[18:33], v[122:125], v[142:145], v[18:33]
	global_load_dwordx4 v[94:97], v77, s[2:3] offset:768
	global_load_dwordx4 v[106:109], v77, s[4:5] offset:768
	s_waitcnt lgkmcnt(3)
	v_mfma_f32_32x32x16_bf16 v[34:49], v[118:121], v[130:133], v[34:49]
	s_waitcnt vmcnt(9)
	ds_write_b128 v75, v[110:113] offset:50688
	s_waitcnt vmcnt(8)
	ds_write_b128 v76, v[114:117] offset:13824
	v_mfma_f32_32x32x16_bf16 v[2:17], v[126:129], v[130:133], v[2:17]
	s_waitcnt lgkmcnt(4)
	v_mfma_f32_32x32x16_bf16 v[50:65], v[118:121], v[134:137], v[50:65]
	v_mfma_f32_32x32x16_bf16 v[18:33], v[126:129], v[134:137], v[18:33]
	s_waitcnt lgkmcnt(0)
	s_barrier
; #define GL1_(RA, RB, i) { RA[i] = *(const u32x4*)(ap + (aoff + (i) * astep)); if ((i) < NB) RB[(i) < NB ? (i) : 0] = *(const u32x4*)(bp + (boff + (i) * bstep)); }
; #define LS1_(RA, RB, ST, i) { char* sn_ = lds + (ST) * STAGE; *(u32x4*)(sn_ + wofs + (i) * 32 * LROW) = RA[i]; \
;                               if ((i) < NB) *(u32x4*)(sn_ + STAGE_OP + wofs + (i) * 32 * LROW) = RB[(i) < NB ? (i) : 0]; }
; template <int NJ> DI void gemm_mainloop_reg(const bf16_t* __restrict__ A, int lda, const bf16_t* __restrict__ Bt, int ldb, int K, f32x16 (&acc)[2][NJ], char* lds) {
;     ...
; #pragma unroll
;   for (int i = 0; i < 4; ++i) GL1_(ra0, rb0, i);
;   ap += 128; bp += 128;
; #pragma unroll
;   for (int i = 0; i < 4; ++i) GL1_(ra1, rb1, i);
;   ap += 128; bp += 128;
; #pragma unroll
;   for (int i = 0; i < 4; ++i) LS1_(ra0, rb0, 0, i);
;   __syncthreads();
;   const int nk = K >> 6;
;   for (int kt = 0; kt < nk; kt += 2) {
;     const bool l0 = (kt + 2 < nk), l1 = (kt + 3 < nk);
;     STEP_(0, l0, ra0, rb0, true, ra1, rb1);
;     __syncthreads();
;     STEP_(1, l1, ra1, rb1, l0, ra0, rb0);
;     __syncthreads();
;   }
	ds_read_b128 v[110:113], v73 offset:36864
	ds_read_b128 v[114:117], v74 offset:55296
	ds_read_b128 v[118:121], v73 offset:36896
	ds_read_b128 v[122:125], v74 offset:55328
	ds_read_b128 v[126:129], v73 offset:41472
	ds_read_b128 v[130:133], v73 offset:41504
	s_waitcnt lgkmcnt(4)
	v_mfma_f32_32x32x16_bf16 v[34:49], v[110:113], v[114:117], v[34:49]
	s_waitcnt lgkmcnt(1)
	v_mfma_f32_32x32x16_bf16 v[2:17], v[126:129], v[114:117], v[2:17]
	ds_read_b128 v[114:117], v74 offset:59904
	ds_read_b128 v[134:137], v74 offset:59936
	s_waitcnt lgkmcnt(1)
	v_mfma_f32_32x32x16_bf16 v[50:65], v[110:113], v[114:117], v[50:65]
	global_load_dwordx4 v[110:113], v80, s[2:3] offset:896
	global_load_dwordx4 v[142:145], v80, s[4:5] offset:896
	s_waitcnt vmcnt(9)
	ds_write_b128 v75, v[82:85]
	s_waitcnt vmcnt(8)
	ds_write_b128 v75, v[138:141] offset:18432
	v_mfma_f32_32x32x16_bf16 v[18:33], v[126:129], v[114:117], v[18:33]
	global_load_dwordx4 v[82:85], v79, s[2:3] offset:896
	global_load_dwordx4 v[114:117], v79, s[4:5] offset:896
	v_mfma_f32_32x32x16_bf16 v[34:49], v[118:121], v[122:125], v[34:49]
	v_mfma_f32_32x32x16_bf16 v[2:17], v[130:133], v[122:125], v[2:17]
	s_waitcnt lgkmcnt(2)
	v_mfma_f32_32x32x16_bf16 v[50:65], v[118:121], v[134:137], v[50:65]
	ds_read_b128 v[118:121], v73 offset:36928
	ds_read_b128 v[122:125], v73 offset:41536
	ds_read_b128 v[126:129], v74 offset:55360
	ds_read_b128 v[138:141], v74 offset:59968
	s_waitcnt vmcnt(9)
	ds_write_b128 v75, v[86:89] offset:4608
	s_waitcnt vmcnt(8)
	ds_write_b128 v75, v[98:101] offset:23040
	v_mfma_f32_32x32x16_bf16 v[18:33], v[130:133], v[134:137], v[18:33]
	global_load_dwordx4 v[86:89], v78, s[2:3] offset:896
	global_load_dwordx4 v[98:101], v78, s[4:5] offset:896
	s_waitcnt lgkmcnt(3)
	v_mfma_f32_32x32x16_bf16 v[34:49], v[118:121], v[126:129], v[34:49]
	v_mfma_f32_32x32x16_bf16 v[2:17], v[122:125], v[126:129], v[2:17]
	s_waitcnt lgkmcnt(2)
	v_mfma_f32_32x32x16_bf16 v[50:65], v[118:121], v[138:141], v[50:65]
	ds_read_b128 v[118:121], v73 offset:36960
	ds_read_b128 v[126:129], v73 offset:41568
	ds_read_b128 v[130:133], v74 offset:55392
	ds_read_b128 v[134:137], v74 offset:60000
	s_waitcnt vmcnt(9)
	ds_write_b128 v75, v[90:93] offset:9216
	s_waitcnt vmcnt(8)
	ds_write_b128 v75, v[102:105] offset:27648
	v_mfma_f32_32x32x16_bf16 v[18:33], v[122:125], v[138:141], v[18:33]
	global_load_dwordx4 v[90:93], v77, s[2:3] offset:896
	global_load_dwordx4 v[102:105], v77, s[4:5] offset:896
	s_waitcnt lgkmcnt(3)
	v_mfma_f32_32x32x16_bf16 v[34:49], v[118:121], v[130:133], v[34:49]
	s_waitcnt vmcnt(9)
	ds_write_b128 v75, v[94:97] offset:13824
	s_waitcnt vmcnt(8)
	ds_write_b128 v75, v[106:109] offset:32256
	v_mfma_f32_32x32x16_bf16 v[2:17], v[126:129], v[130:133], v[2:17]
	s_waitcnt lgkmcnt(4)
	v_mfma_f32_32x32x16_bf16 v[50:65], v[118:121], v[134:137], v[50:65]
	v_mfma_f32_32x32x16_bf16 v[18:33], v[126:129], v[134:137], v[18:33]
	s_waitcnt lgkmcnt(0)
	s_barrier
	ds_read_b128 v[94:97], v73
	ds_read_b128 v[106:109], v74 offset:18432
	ds_read_b128 v[118:121], v73 offset:32
	ds_read_b128 v[122:125], v74 offset:18464
	ds_read_b128 v[126:129], v73 offset:4608
	ds_read_b128 v[130:133], v73 offset:4640
	s_waitcnt lgkmcnt(4)
	v_mfma_f32_32x32x16_bf16 v[34:49], v[94:97], v[106:109], v[34:49]
	s_waitcnt lgkmcnt(1)
	v_mfma_f32_32x32x16_bf16 v[2:17], v[126:129], v[106:109], v[2:17]
	ds_read_b128 v[106:109], v74 offset:23040
	ds_read_b128 v[134:137], v74 offset:23072
	s_waitcnt lgkmcnt(1)
	v_mfma_f32_32x32x16_bf16 v[50:65], v[94:97], v[106:109], v[50:65]
	global_load_dwordx4 v[94:97], v80, s[2:3] offset:1024
	global_load_dwordx4 v[138:141], v80, s[4:5] offset:1024
	s_waitcnt vmcnt(9)
	ds_write_b128 v75, v[110:113] offset:36864
	s_waitcnt vmcnt(8)
	ds_write_b128 v75, v[142:145] offset:55296
	v_mfma_f32_32x32x16_bf16 v[18:33], v[126:129], v[106:109], v[18:33]
	global_load_dwordx4 v[106:109], v79, s[2:3] offset:1024
	global_load_dwordx4 v[110:113], v79, s[4:5] offset:1024
	v_mfma_f32_32x32x16_bf16 v[34:49], v[118:121], v[122:125], v[34:49]
	v_mfma_f32_32x32x16_bf16 v[2:17], v[130:133], v[122:125], v[2:17]
	s_waitcnt lgkmcnt(2)
	v_mfma_f32_32x32x16_bf16 v[50:65], v[118:121], v[134:137], v[50:65]
	ds_read_b128 v[118:121], v73 offset:64
	ds_read_b128 v[122:125], v73 offset:4672
	ds_read_b128 v[126:129], v74 offset:18496
	ds_read_b128 v[142:145], v74 offset:23104
	s_waitcnt vmcnt(9)
	ds_write_b128 v75, v[82:85] offset:41472
	s_waitcnt vmcnt(8)
	ds_write_b128 v75, v[114:117] offset:59904
	v_mfma_f32_32x32x16_bf16 v[18:33], v[130:133], v[134:137], v[18:33]
	global_load_dwordx4 v[82:85], v78, s[2:3] offset:1024
	global_load_dwordx4 v[114:117], v78, s[4:5] offset:1024
	s_waitcnt lgkmcnt(3)
	v_mfma_f32_32x32x16_bf16 v[34:49], v[118:121], v[126:129], v[34:49]
	v_mfma_f32_32x32x16_bf16 v[2:17], v[122:125], v[126:129], v[2:17]
	s_waitcnt lgkmcnt(2)
	v_mfma_f32_32x32x16_bf16 v[50:65], v[118:121], v[142:145], v[50:65]
	ds_read_b128 v[118:121], v73 offset:96
	ds_read_b128 v[126:129], v73 offset:4704
	ds_read_b128 v[130:133], v74 offset:18528
	ds_read_b128 v[134:137], v74 offset:23136
	s_waitcnt vmcnt(9)
	ds_write_b128 v75, v[86:89] offset:46080
	s_waitcnt vmcnt(8)
	ds_write_b128 v75, v[98:101] offset:64512
	v_mfma_f32_32x32x16_bf16 v[18:33], v[122:125], v[142:145], v[18:33]
	global_load_dwordx4 v[86:89], v77, s[2:3] offset:1024
	global_load_dwordx4 v[98:101], v77, s[4:5] offset:1024
	s_waitcnt lgkmcnt(3)
	v_mfma_f32_32x32x16_bf16 v[34:49], v[118:121], v[130:133], v[34:49]
	s_waitcnt vmcnt(9)
	ds_write_b128 v75, v[90:93] offset:50688
	s_waitcnt vmcnt(8)
	ds_write_b128 v76, v[102:105] offset:13824
	v_mfma_f32_32x32x16_bf16 v[2:17], v[126:129], v[130:133], v[2:17]
	s_waitcnt lgkmcnt(4)
	v_mfma_f32_32x32x16_bf16 v[50:65], v[118:121], v[134:137], v[50:65]
	v_mfma_f32_32x32x16_bf16 v[18:33], v[126:129], v[134:137], v[18:33]
	s_waitcnt lgkmcnt(0)
	s_barrier
; #define GL1_(RA, RB, i) { RA[i] = *(const u32x4*)(ap + (aoff + (i) * astep)); if ((i) < NB) RB[(i) < NB ? (i) : 0] = *(const u32x4*)(bp + (boff + (i) * bstep)); }
; #define LS1_(RA, RB, ST, i) { char* sn_ = lds + (ST) * STAGE; *(u32x4*)(sn_ + wofs + (i) * 32 * LROW) = RA[i]; \
;                               if ((i) < NB) *(u32x4*)(sn_ + STAGE_OP + wofs + (i) * 32 * LROW) = RB[(i) < NB ? (i) : 0]; }
; template <int NJ> DI void gemm_mainloop_reg(const bf16_t* __restrict__ A, int lda, const bf16_t* __restrict__ Bt, int ldb, int K, f32x16 (&acc)[2][NJ], char* lds) {
;     ...
; #pragma unroll
;   for (int i = 0; i < 4; ++i) GL1_(ra0, rb0, i);
;   ap += 128; bp += 128;
; #pragma unroll
;   for (int i = 0; i < 4; ++i) GL1_(ra1, rb1, i);
;   ap += 128; bp += 128;
; #pragma unroll
;   for (int i = 0; i < 4; ++i) LS1_(ra0, rb0, 0, i);
;   __syncthreads();
;   const int nk = K >> 6;
;   for (int kt = 0; kt < nk; kt += 2) {
;     const bool l0 = (kt + 2 < nk), l1 = (kt + 3 < nk);
;     STEP_(0, l0, ra0, rb0, true, ra1, rb1);
;     __syncthreads();
;     STEP_(1, l1, ra1, rb1, l0, ra0, rb0);
;     __syncthreads();
;   }
	ds_read_b128 v[90:93], v73 offset:36864
	ds_read_b128 v[102:105], v74 offset:55296
	ds_read_b128 v[118:121], v73 offset:36896
	ds_read_b128 v[122:125], v74 offset:55328
	ds_read_b128 v[126:129], v73 offset:41472
	ds_read_b128 v[130:133], v73 offset:41504
	s_waitcnt lgkmcnt(4)
	v_mfma_f32_32x32x16_bf16 v[34:49], v[90:93], v[102:105], v[34:49]
	s_waitcnt lgkmcnt(1)
	v_mfma_f32_32x32x16_bf16 v[2:17], v[126:129], v[102:105], v[2:17]
	ds_read_b128 v[102:105], v74 offset:59904
	ds_read_b128 v[134:137], v74 offset:59936
	s_waitcnt lgkmcnt(1)
	v_mfma_f32_32x32x16_bf16 v[50:65], v[90:93], v[102:105], v[50:65]
	global_load_dwordx4 v[90:93], v80, s[2:3] offset:1152
	global_load_dwordx4 v[142:145], v80, s[4:5] offset:1152
	s_waitcnt vmcnt(9)
	ds_write_b128 v75, v[94:97]
	s_waitcnt vmcnt(8)
	ds_write_b128 v75, v[138:141] offset:18432
	v_mfma_f32_32x32x16_bf16 v[18:33], v[126:129], v[102:105], v[18:33]
	global_load_dwordx4 v[94:97], v79, s[2:3] offset:1152
	global_load_dwordx4 v[102:105], v79, s[4:5] offset:1152
	v_mfma_f32_32x32x16_bf16 v[34:49], v[118:121], v[122:125], v[34:49]
	v_mfma_f32_32x32x16_bf16 v[2:17], v[130:133], v[122:125], v[2:17]
	s_waitcnt lgkmcnt(2)
	v_mfma_f32_32x32x16_bf16 v[50:65], v[118:121], v[134:137], v[50:65]
	ds_read_b128 v[118:121], v73 offset:36928
	ds_read_b128 v[122:125], v73 offset:41536
	ds_read_b128 v[126:129], v74 offset:55360
	ds_read_b128 v[138:141], v74 offset:59968
	s_waitcnt vmcnt(9)
	ds_write_b128 v75, v[106:109] offset:4608
	s_waitcnt vmcnt(8)
	ds_write_b128 v75, v[110:113] offset:23040
	v_mfma_f32_32x32x16_bf16 v[18:33], v[130:133], v[134:137], v[18:33]
	global_load_dwordx4 v[106:109], v78, s[2:3] offset:1152
	global_load_dwordx4 v[110:113], v78, s[4:5] offset:1152
	s_waitcnt lgkmcnt(3)
	v_mfma_f32_32x32x16_bf16 v[34:49], v[118:121], v[126:129], v[34:49]
	v_mfma_f32_32x32x16_bf16 v[2:17], v[122:125], v[126:129], v[2:17]
	s_waitcnt lgkmcnt(2)
	v_mfma_f32_32x32x16_bf16 v[50:65], v[118:121], v[138:141], v[50:65]
	ds_read_b128 v[118:121], v73 offset:36960
	ds_read_b128 v[126:129], v73 offset:41568
	ds_read_b128 v[130:133], v74 offset:55392
	ds_read_b128 v[134:137], v74 offset:60000
	s_waitcnt vmcnt(9)
	ds_write_b128 v75, v[82:85] offset:9216
	s_waitcnt vmcnt(8)
	ds_write_b128 v75, v[114:117] offset:27648
	v_mfma_f32_32x32x16_bf16 v[18:33], v[122:125], v[138:141], v[18:33]
	global_load_dwordx4 v[82:85], v77, s[2:3] offset:1152
	global_load_dwordx4 v[114:117], v77, s[4:5] offset:1152
	s_waitcnt lgkmcnt(3)
	v_mfma_f32_32x32x16_bf16 v[34:49], v[118:121], v[130:133], v[34:49]
	s_waitcnt vmcnt(9)
	ds_write_b128 v75, v[86:89] offset:13824
	s_waitcnt vmcnt(8)
	ds_write_b128 v75, v[98:101] offset:32256
	v_mfma_f32_32x32x16_bf16 v[2:17], v[126:129], v[130:133], v[2:17]
	s_waitcnt lgkmcnt(4)
	v_mfma_f32_32x32x16_bf16 v[50:65], v[118:121], v[134:137], v[50:65]
	v_mfma_f32_32x32x16_bf16 v[18:33], v[126:129], v[134:137], v[18:33]
	s_waitcnt lgkmcnt(0)
	s_barrier
	ds_read_b128 v[86:89], v73
	ds_read_b128 v[98:101], v74 offset:18432
	ds_read_b128 v[118:121], v73 offset:32
	ds_read_b128 v[122:125], v74 offset:18464
	ds_read_b128 v[126:129], v73 offset:4608
	ds_read_b128 v[130:133], v73 offset:4640
	s_waitcnt lgkmcnt(4)
	v_mfma_f32_32x32x16_bf16 v[34:49], v[86:89], v[98:101], v[34:49]
	s_waitcnt lgkmcnt(1)
	v_mfma_f32_32x32x16_bf16 v[2:17], v[126:129], v[98:101], v[2:17]
	ds_read_b128 v[98:101], v74 offset:23040
	ds_read_b128 v[134:137], v74 offset:23072
	s_waitcnt lgkmcnt(1)
	v_mfma_f32_32x32x16_bf16 v[50:65], v[86:89], v[98:101], v[50:65]
	global_load_dwordx4 v[86:89], v80, s[2:3] offset:1280
	global_load_dwordx4 v[138:141], v80, s[4:5] offset:1280
	s_waitcnt vmcnt(9)
	ds_write_b128 v75, v[90:93] offset:36864
	s_waitcnt vmcnt(8)
	ds_write_b128 v75, v[142:145] offset:55296
	v_mfma_f32_32x32x16_bf16 v[18:33], v[126:129], v[98:101], v[18:33]
	global_load_dwordx4 v[90:93], v79, s[2:3] offset:1280
	global_load_dwordx4 v[98:101], v79, s[4:5] offset:1280
	v_mfma_f32_32x32x16_bf16 v[34:49], v[118:121], v[122:125], v[34:49]
	v_mfma_f32_32x32x16_bf16 v[2:17], v[130:133], v[122:125], v[2:17]
	s_waitcnt lgkmcnt(2)
	v_mfma_f32_32x32x16_bf16 v[50:65], v[118:121], v[134:137], v[50:65]
	ds_read_b128 v[118:121], v73 offset:64
	ds_read_b128 v[122:125], v73 offset:4672
	ds_read_b128 v[126:129], v74 offset:18496
	ds_read_b128 v[142:145], v74 offset:23104
	s_waitcnt vmcnt(9)
	ds_write_b128 v75, v[94:97] offset:41472
	s_waitcnt vmcnt(8)
	ds_write_b128 v75, v[102:105] offset:59904
	v_mfma_f32_32x32x16_bf16 v[18:33], v[130:133], v[134:137], v[18:33]
	global_load_dwordx4 v[94:97], v78, s[2:3] offset:1280
	global_load_dwordx4 v[102:105], v78, s[4:5] offset:1280
	s_waitcnt lgkmcnt(3)
	v_mfma_f32_32x32x16_bf16 v[34:49], v[118:121], v[126:129], v[34:49]
	v_mfma_f32_32x32x16_bf16 v[2:17], v[122:125], v[126:129], v[2:17]
	s_waitcnt lgkmcnt(2)
	v_mfma_f32_32x32x16_bf16 v[50:65], v[118:121], v[142:145], v[50:65]
	ds_read_b128 v[118:121], v73 offset:96
	ds_read_b128 v[126:129], v73 offset:4704
	ds_read_b128 v[130:133], v74 offset:18528
	ds_read_b128 v[134:137], v74 offset:23136
	s_waitcnt vmcnt(9)
	ds_write_b128 v75, v[106:109] offset:46080
	s_waitcnt vmcnt(8)
	ds_write_b128 v75, v[110:113] offset:64512
	v_mfma_f32_32x32x16_bf16 v[18:33], v[122:125], v[142:145], v[18:33]
	global_load_dwordx4 v[106:109], v77, s[2:3] offset:1280
	global_load_dwordx4 v[110:113], v77, s[4:5] offset:1280
	s_waitcnt lgkmcnt(3)
	v_mfma_f32_32x32x16_bf16 v[34:49], v[118:121], v[130:133], v[34:49]
	s_waitcnt vmcnt(9)
	ds_write_b128 v75, v[82:85] offset:50688
	s_waitcnt vmcnt(8)
	ds_write_b128 v76, v[114:117] offset:13824
	v_mfma_f32_32x32x16_bf16 v[2:17], v[126:129], v[130:133], v[2:17]
	s_waitcnt lgkmcnt(4)
	v_mfma_f32_32x32x16_bf16 v[50:65], v[118:121], v[134:137], v[50:65]
	v_mfma_f32_32x32x16_bf16 v[18:33], v[126:129], v[134:137], v[18:33]
	s_waitcnt lgkmcnt(0)
	s_barrier
; #define GL1_(RA, RB, i) { RA[i] = *(const u32x4*)(ap + (aoff + (i) * astep)); if ((i) < NB) RB[(i) < NB ? (i) : 0] = *(const u32x4*)(bp + (boff + (i) * bstep)); }
; #define LS1_(RA, RB, ST, i) { char* sn_ = lds + (ST) * STAGE; *(u32x4*)(sn_ + wofs + (i) * 32 * LROW) = RA[i]; \
;                               if ((i) < NB) *(u32x4*)(sn_ + STAGE_OP + wofs + (i) * 32 * LROW) = RB[(i) < NB ? (i) : 0]; }
; template <int NJ> DI void gemm_mainloop_reg(const bf16_t* __restrict__ A, int lda, const bf16_t* __restrict__ Bt, int ldb, int K, f32x16 (&acc)[2][NJ], char* lds) {
;     ...
; #pragma unroll
;   for (int i = 0; i < 4; ++i) GL1_(ra0, rb0, i);
;   ap += 128; bp += 128;
; #pragma unroll
;   for (int i = 0; i < 4; ++i) GL1_(ra1, rb1, i);
;   ap += 128; bp += 128;
; #pragma unroll
;   for (int i = 0; i < 4; ++i) LS1_(ra0, rb0, 0, i);
;   __syncthreads();
;   const int nk = K >> 6;
;   for (int kt = 0; kt < nk; kt += 2) {
;     const bool l0 = (kt + 2 < nk), l1 = (kt + 3 < nk);
;     STEP_(0, l0, ra0, rb0, true, ra1, rb1);
;     __syncthreads();
;     STEP_(1, l1, ra1, rb1, l0, ra0, rb0);
;     __syncthreads();
;   }
	ds_read_b128 v[82:85], v73 offset:36864
	ds_read_b128 v[114:117], v74 offset:55296
	ds_read_b128 v[118:121], v73 offset:36896
	ds_read_b128 v[122:125], v74 offset:55328
	ds_read_b128 v[126:129], v73 offset:41472
	ds_read_b128 v[130:133], v73 offset:41504
	s_waitcnt lgkmcnt(4)
	v_mfma_f32_32x32x16_bf16 v[34:49], v[82:85], v[114:117], v[34:49]
	s_waitcnt lgkmcnt(1)
	v_mfma_f32_32x32x16_bf16 v[2:17], v[126:129], v[114:117], v[2:17]
	ds_read_b128 v[114:117], v74 offset:59904
	ds_read_b128 v[134:137], v74 offset:59936
	s_waitcnt lgkmcnt(1)
	v_mfma_f32_32x32x16_bf16 v[50:65], v[82:85], v[114:117], v[50:65]
	global_load_dwordx4 v[82:85], v80, s[2:3] offset:1408
	global_load_dwordx4 v[142:145], v80, s[4:5] offset:1408
	s_waitcnt vmcnt(9)
	ds_write_b128 v75, v[86:89]
	s_waitcnt vmcnt(8)
	ds_write_b128 v75, v[138:141] offset:18432
	v_mfma_f32_32x32x16_bf16 v[18:33], v[126:129], v[114:117], v[18:33]
	global_load_dwordx4 v[86:89], v79, s[2:3] offset:1408
	global_load_dwordx4 v[114:117], v79, s[4:5] offset:1408
	v_mfma_f32_32x32x16_bf16 v[34:49], v[118:121], v[122:125], v[34:49]
	v_mfma_f32_32x32x16_bf16 v[2:17], v[130:133], v[122:125], v[2:17]
	s_waitcnt lgkmcnt(2)
	v_mfma_f32_32x32x16_bf16 v[50:65], v[118:121], v[134:137], v[50:65]
	ds_read_b128 v[118:121], v73 offset:36928
	ds_read_b128 v[122:125], v73 offset:41536
	ds_read_b128 v[126:129], v74 offset:55360
	ds_read_b128 v[138:141], v74 offset:59968
	s_waitcnt vmcnt(9)
	ds_write_b128 v75, v[90:93] offset:4608
	s_waitcnt vmcnt(8)
	ds_write_b128 v75, v[98:101] offset:23040
	v_mfma_f32_32x32x16_bf16 v[18:33], v[130:133], v[134:137], v[18:33]
	global_load_dwordx4 v[90:93], v78, s[2:3] offset:1408
	global_load_dwordx4 v[98:101], v78, s[4:5] offset:1408
	s_waitcnt lgkmcnt(3)
	v_mfma_f32_32x32x16_bf16 v[34:49], v[118:121], v[126:129], v[34:49]
	v_mfma_f32_32x32x16_bf16 v[2:17], v[122:125], v[126:129], v[2:17]
	s_waitcnt lgkmcnt(2)
	v_mfma_f32_32x32x16_bf16 v[50:65], v[118:121], v[138:141], v[50:65]
	ds_read_b128 v[118:121], v73 offset:36960
	ds_read_b128 v[126:129], v73 offset:41568
	ds_read_b128 v[130:133], v74 offset:55392
	ds_read_b128 v[134:137], v74 offset:60000
	s_waitcnt vmcnt(9)
	ds_write_b128 v75, v[94:97] offset:9216
	s_waitcnt vmcnt(8)
	ds_write_b128 v75, v[102:105] offset:27648
	v_mfma_f32_32x32x16_bf16 v[18:33], v[122:125], v[138:141], v[18:33]
	global_load_dwordx4 v[94:97], v77, s[2:3] offset:1408
	global_load_dwordx4 v[102:105], v77, s[4:5] offset:1408
	s_waitcnt lgkmcnt(3)
	v_mfma_f32_32x32x16_bf16 v[34:49], v[118:121], v[130:133], v[34:49]
	s_waitcnt vmcnt(9)
	ds_write_b128 v75, v[106:109] offset:13824
	s_waitcnt vmcnt(8)
	ds_write_b128 v75, v[110:113] offset:32256
	v_mfma_f32_32x32x16_bf16 v[2:17], v[126:129], v[130:133], v[2:17]
	s_waitcnt lgkmcnt(4)
	v_mfma_f32_32x32x16_bf16 v[50:65], v[118:121], v[134:137], v[50:65]
	v_mfma_f32_32x32x16_bf16 v[18:33], v[126:129], v[134:137], v[18:33]
	s_waitcnt lgkmcnt(0)
	s_barrier
	ds_read_b128 v[106:109], v73
	ds_read_b128 v[110:113], v74 offset:18432
	ds_read_b128 v[118:121], v73 offset:32
	ds_read_b128 v[122:125], v74 offset:18464
	ds_read_b128 v[126:129], v73 offset:4608
	ds_read_b128 v[130:133], v73 offset:4640
	s_waitcnt lgkmcnt(4)
	v_mfma_f32_32x32x16_bf16 v[34:49], v[106:109], v[110:113], v[34:49]
	s_waitcnt lgkmcnt(1)
	v_mfma_f32_32x32x16_bf16 v[2:17], v[126:129], v[110:113], v[2:17]
	ds_read_b128 v[110:113], v74 offset:23040
	ds_read_b128 v[134:137], v74 offset:23072
	s_waitcnt lgkmcnt(1)
	v_mfma_f32_32x32x16_bf16 v[50:65], v[106:109], v[110:113], v[50:65]
	global_load_dwordx4 v[106:109], v80, s[2:3] offset:1536
	global_load_dwordx4 v[138:141], v80, s[4:5] offset:1536
	s_waitcnt vmcnt(9)
	ds_write_b128 v75, v[82:85] offset:36864
	s_waitcnt vmcnt(8)
	ds_write_b128 v75, v[142:145] offset:55296
	v_mfma_f32_32x32x16_bf16 v[18:33], v[126:129], v[110:113], v[18:33]
	global_load_dwordx4 v[82:85], v79, s[2:3] offset:1536
	global_load_dwordx4 v[110:113], v79, s[4:5] offset:1536
	v_mfma_f32_32x32x16_bf16 v[34:49], v[118:121], v[122:125], v[34:49]
	v_mfma_f32_32x32x16_bf16 v[2:17], v[130:133], v[122:125], v[2:17]
	s_waitcnt lgkmcnt(2)
	v_mfma_f32_32x32x16_bf16 v[50:65], v[118:121], v[134:137], v[50:65]
	ds_read_b128 v[118:121], v73 offset:64
	ds_read_b128 v[122:125], v73 offset:4672
	ds_read_b128 v[126:129], v74 offset:18496
	ds_read_b128 v[142:145], v74 offset:23104
	s_waitcnt vmcnt(9)
	ds_write_b128 v75, v[86:89] offset:41472
	s_waitcnt vmcnt(8)
	ds_write_b128 v75, v[114:117] offset:59904
	v_mfma_f32_32x32x16_bf16 v[18:33], v[130:133], v[134:137], v[18:33]
	global_load_dwordx4 v[86:89], v78, s[2:3] offset:1536
	global_load_dwordx4 v[114:117], v78, s[4:5] offset:1536
	s_waitcnt lgkmcnt(3)
	v_mfma_f32_32x32x16_bf16 v[34:49], v[118:121], v[126:129], v[34:49]
	v_mfma_f32_32x32x16_bf16 v[2:17], v[122:125], v[126:129], v[2:17]
	s_waitcnt lgkmcnt(2)
	v_mfma_f32_32x32x16_bf16 v[50:65], v[118:121], v[142:145], v[50:65]
	ds_read_b128 v[118:121], v73 offset:96
	ds_read_b128 v[126:129], v73 offset:4704
	ds_read_b128 v[130:133], v74 offset:18528
	ds_read_b128 v[134:137], v74 offset:23136
	s_waitcnt vmcnt(9)
	ds_write_b128 v75, v[90:93] offset:46080
	s_waitcnt vmcnt(8)
	ds_write_b128 v75, v[98:101] offset:64512
	v_mfma_f32_32x32x16_bf16 v[18:33], v[122:125], v[142:145], v[18:33]
	global_load_dwordx4 v[90:93], v77, s[2:3] offset:1536
	global_load_dwordx4 v[98:101], v77, s[4:5] offset:1536
	s_waitcnt lgkmcnt(3)
	v_mfma_f32_32x32x16_bf16 v[34:49], v[118:121], v[130:133], v[34:49]
	s_waitcnt vmcnt(9)
	ds_write_b128 v75, v[94:97] offset:50688
	s_waitcnt vmcnt(8)
	ds_write_b128 v76, v[102:105] offset:13824
	v_mfma_f32_32x32x16_bf16 v[2:17], v[126:129], v[130:133], v[2:17]
	s_waitcnt lgkmcnt(4)
	v_mfma_f32_32x32x16_bf16 v[50:65], v[118:121], v[134:137], v[50:65]
	v_mfma_f32_32x32x16_bf16 v[18:33], v[126:129], v[134:137], v[18:33]
	s_waitcnt lgkmcnt(0)
	s_barrier
; #define GL1_(RA, RB, i) { RA[i] = *(const u32x4*)(ap + (aoff + (i) * astep)); if ((i) < NB) RB[(i) < NB ? (i) : 0] = *(const u32x4*)(bp + (boff + (i) * bstep)); }
; #define LS1_(RA, RB, ST, i) { char* sn_ = lds + (ST) * STAGE; *(u32x4*)(sn_ + wofs + (i) * 32 * LROW) = RA[i]; \
;                               if ((i) < NB) *(u32x4*)(sn_ + STAGE_OP + wofs + (i) * 32 * LROW) = RB[(i) < NB ? (i) : 0]; }
; template <int NJ> DI void gemm_mainloop_reg(const bf16_t* __restrict__ A, int lda, const bf16_t* __restrict__ Bt, int ldb, int K, f32x16 (&acc)[2][NJ], char* lds) {
;     ...
; #pragma unroll
;   for (int i = 0; i < 4; ++i) GL1_(ra0, rb0, i);
;   ap += 128; bp += 128;
; #pragma unroll
;   for (int i = 0; i < 4; ++i) GL1_(ra1, rb1, i);
;   ap += 128; bp += 128;
; #pragma unroll
;   for (int i = 0; i < 4; ++i) LS1_(ra0, rb0, 0, i);
;   __syncthreads();
;   const int nk = K >> 6;
;   for (int kt = 0; kt < nk; kt += 2) {
;     const bool l0 = (kt + 2 < nk), l1 = (kt + 3 < nk);
;     STEP_(0, l0, ra0, rb0, true, ra1, rb1);
;     __syncthreads();
;     STEP_(1, l1, ra1, rb1, l0, ra0, rb0);
;     __syncthreads();
;   }
	ds_read_b128 v[94:97], v73 offset:36864
	ds_read_b128 v[102:105], v74 offset:55296
	ds_read_b128 v[118:121], v73 offset:36896
	ds_read_b128 v[122:125], v74 offset:55328
	ds_read_b128 v[126:129], v73 offset:41472
	ds_read_b128 v[130:133], v73 offset:41504
	s_waitcnt lgkmcnt(4)
	v_mfma_f32_32x32x16_bf16 v[34:49], v[94:97], v[102:105], v[34:49]
	s_waitcnt lgkmcnt(1)
	v_mfma_f32_32x32x16_bf16 v[2:17], v[126:129], v[102:105], v[2:17]
	ds_read_b128 v[102:105], v74 offset:59904
	ds_read_b128 v[134:137], v74 offset:59936
	s_waitcnt lgkmcnt(1)
	v_mfma_f32_32x32x16_bf16 v[50:65], v[94:97], v[102:105], v[50:65]
	global_load_dwordx4 v[94:97], v80, s[2:3] offset:1664
	global_load_dwordx4 v[142:145], v80, s[4:5] offset:1664
	s_waitcnt vmcnt(9)
	ds_write_b128 v75, v[106:109]
	s_waitcnt vmcnt(8)
	ds_write_b128 v75, v[138:141] offset:18432
	v_mfma_f32_32x32x16_bf16 v[18:33], v[126:129], v[102:105], v[18:33]
	global_load_dwordx4 v[102:105], v79, s[2:3] offset:1664
	global_load_dwordx4 v[106:109], v79, s[4:5] offset:1664
	v_mfma_f32_32x32x16_bf16 v[34:49], v[118:121], v[122:125], v[34:49]
	v_mfma_f32_32x32x16_bf16 v[2:17], v[130:133], v[122:125], v[2:17]
	s_waitcnt lgkmcnt(2)
	v_mfma_f32_32x32x16_bf16 v[50:65], v[118:121], v[134:137], v[50:65]
	ds_read_b128 v[118:121], v73 offset:36928
	ds_read_b128 v[122:125], v73 offset:41536
	ds_read_b128 v[126:129], v74 offset:55360
	ds_read_b128 v[138:141], v74 offset:59968
	s_waitcnt vmcnt(9)
	ds_write_b128 v75, v[82:85] offset:4608
	s_waitcnt vmcnt(8)
	ds_write_b128 v75, v[110:113] offset:23040
	v_mfma_f32_32x32x16_bf16 v[18:33], v[130:133], v[134:137], v[18:33]
	global_load_dwordx4 v[82:85], v78, s[2:3] offset:1664
	global_load_dwordx4 v[110:113], v78, s[4:5] offset:1664
	s_waitcnt lgkmcnt(3)
	v_mfma_f32_32x32x16_bf16 v[34:49], v[118:121], v[126:129], v[34:49]
	v_mfma_f32_32x32x16_bf16 v[2:17], v[122:125], v[126:129], v[2:17]
	s_waitcnt lgkmcnt(2)
	v_mfma_f32_32x32x16_bf16 v[50:65], v[118:121], v[138:141], v[50:65]
	ds_read_b128 v[118:121], v73 offset:36960
	ds_read_b128 v[126:129], v73 offset:41568
	ds_read_b128 v[130:133], v74 offset:55392
	ds_read_b128 v[134:137], v74 offset:60000
	s_waitcnt vmcnt(9)
	ds_write_b128 v75, v[86:89] offset:9216
	s_waitcnt vmcnt(8)
	ds_write_b128 v75, v[114:117] offset:27648
	v_mfma_f32_32x32x16_bf16 v[18:33], v[122:125], v[138:141], v[18:33]
	global_load_dwordx4 v[86:89], v77, s[2:3] offset:1664
	global_load_dwordx4 v[114:117], v77, s[4:5] offset:1664
	s_waitcnt lgkmcnt(3)
	v_mfma_f32_32x32x16_bf16 v[34:49], v[118:121], v[130:133], v[34:49]
	s_waitcnt vmcnt(9)
	ds_write_b128 v75, v[90:93] offset:13824
	s_waitcnt vmcnt(8)
	ds_write_b128 v75, v[98:101] offset:32256
	v_mfma_f32_32x32x16_bf16 v[2:17], v[126:129], v[130:133], v[2:17]
	s_waitcnt lgkmcnt(4)
	v_mfma_f32_32x32x16_bf16 v[50:65], v[118:121], v[134:137], v[50:65]
	v_mfma_f32_32x32x16_bf16 v[18:33], v[126:129], v[134:137], v[18:33]
	s_waitcnt lgkmcnt(0)
	s_barrier
	ds_read_b128 v[90:93], v73
	ds_read_b128 v[98:101], v74 offset:18432
	ds_read_b128 v[118:121], v73 offset:32
	ds_read_b128 v[122:125], v74 offset:18464
	ds_read_b128 v[126:129], v73 offset:4608
	ds_read_b128 v[130:133], v73 offset:4640
	s_waitcnt lgkmcnt(4)
	v_mfma_f32_32x32x16_bf16 v[34:49], v[90:93], v[98:101], v[34:49]
	s_waitcnt lgkmcnt(1)
	v_mfma_f32_32x32x16_bf16 v[2:17], v[126:129], v[98:101], v[2:17]
	ds_read_b128 v[98:101], v74 offset:23040
	ds_read_b128 v[134:137], v74 offset:23072
	s_waitcnt lgkmcnt(1)
	v_mfma_f32_32x32x16_bf16 v[50:65], v[90:93], v[98:101], v[50:65]
	global_load_dwordx4 v[90:93], v80, s[2:3] offset:1792
	global_load_dwordx4 v[138:141], v80, s[4:5] offset:1792
	s_waitcnt vmcnt(9)
	ds_write_b128 v75, v[94:97] offset:36864
	s_waitcnt vmcnt(8)
	ds_write_b128 v75, v[142:145] offset:55296
	v_mfma_f32_32x32x16_bf16 v[18:33], v[126:129], v[98:101], v[18:33]
	global_load_dwordx4 v[94:97], v79, s[2:3] offset:1792
	global_load_dwordx4 v[98:101], v79, s[4:5] offset:1792
	v_mfma_f32_32x32x16_bf16 v[34:49], v[118:121], v[122:125], v[34:49]
	v_mfma_f32_32x32x16_bf16 v[2:17], v[130:133], v[122:125], v[2:17]
	s_waitcnt lgkmcnt(2)
	v_mfma_f32_32x32x16_bf16 v[50:65], v[118:121], v[134:137], v[50:65]
	ds_read_b128 v[118:121], v73 offset:64
	ds_read_b128 v[122:125], v73 offset:4672
	ds_read_b128 v[126:129], v74 offset:18496
	ds_read_b128 v[142:145], v74 offset:23104
	s_waitcnt vmcnt(9)
	ds_write_b128 v75, v[102:105] offset:41472
	s_waitcnt vmcnt(8)
	ds_write_b128 v75, v[106:109] offset:59904
	v_mfma_f32_32x32x16_bf16 v[18:33], v[130:133], v[134:137], v[18:33]
	global_load_dwordx4 v[102:105], v78, s[2:3] offset:1792
	global_load_dwordx4 v[106:109], v78, s[4:5] offset:1792
	s_waitcnt lgkmcnt(3)
	v_mfma_f32_32x32x16_bf16 v[34:49], v[118:121], v[126:129], v[34:49]
	v_mfma_f32_32x32x16_bf16 v[2:17], v[122:125], v[126:129], v[2:17]
	s_waitcnt lgkmcnt(2)
	v_mfma_f32_32x32x16_bf16 v[50:65], v[118:121], v[142:145], v[50:65]
	ds_read_b128 v[118:121], v73 offset:96
	ds_read_b128 v[126:129], v73 offset:4704
	ds_read_b128 v[130:133], v74 offset:18528
	ds_read_b128 v[134:137], v74 offset:23136
	s_waitcnt vmcnt(9)
	ds_write_b128 v75, v[82:85] offset:46080
	s_waitcnt vmcnt(8)
	ds_write_b128 v75, v[110:113] offset:64512
	v_mfma_f32_32x32x16_bf16 v[18:33], v[122:125], v[142:145], v[18:33]
	global_load_dwordx4 v[82:85], v77, s[2:3] offset:1792
	global_load_dwordx4 v[110:113], v77, s[4:5] offset:1792
	s_waitcnt lgkmcnt(3)
	v_mfma_f32_32x32x16_bf16 v[34:49], v[118:121], v[130:133], v[34:49]
	s_waitcnt vmcnt(9)
	ds_write_b128 v75, v[86:89] offset:50688
	s_waitcnt vmcnt(8)
	ds_write_b128 v76, v[114:117] offset:13824
	v_mfma_f32_32x32x16_bf16 v[2:17], v[126:129], v[130:133], v[2:17]
	s_waitcnt lgkmcnt(4)
	v_mfma_f32_32x32x16_bf16 v[50:65], v[118:121], v[134:137], v[50:65]
	v_mfma_f32_32x32x16_bf16 v[18:33], v[126:129], v[134:137], v[18:33]
	s_waitcnt lgkmcnt(0)
	s_barrier
; #define GL1_(RA, RB, i) { RA[i] = *(const u32x4*)(ap + (aoff + (i) * astep)); if ((i) < NB) RB[(i) < NB ? (i) : 0] = *(const u32x4*)(bp + (boff + (i) * bstep)); }
; #define LS1_(RA, RB, ST, i) { char* sn_ = lds + (ST) * STAGE; *(u32x4*)(sn_ + wofs + (i) * 32 * LROW) = RA[i]; \
;                               if ((i) < NB) *(u32x4*)(sn_ + STAGE_OP + wofs + (i) * 32 * LROW) = RB[(i) < NB ? (i) : 0]; }
; template <int NJ> DI void gemm_mainloop_reg(const bf16_t* __restrict__ A, int lda, const bf16_t* __restrict__ Bt, int ldb, int K, f32x16 (&acc)[2][NJ], char* lds) {
;     ...
; #pragma unroll
;   for (int i = 0; i < 4; ++i) GL1_(ra0, rb0, i);
;   ap += 128; bp += 128;
; #pragma unroll
;   for (int i = 0; i < 4; ++i) GL1_(ra1, rb1, i);
;   ap += 128; bp += 128;
; #pragma unroll
;   for (int i = 0; i < 4; ++i) LS1_(ra0, rb0, 0, i);
;   __syncthreads();
;   const int nk = K >> 6;
;   for (int kt = 0; kt < nk; kt += 2) {
;     const bool l0 = (kt + 2 < nk), l1 = (kt + 3 < nk);
;     STEP_(0, l0, ra0, rb0, true, ra1, rb1);
;     __syncthreads();
;     STEP_(1, l1, ra1, rb1, l0, ra0, rb0);
;     __syncthreads();
;   }
	ds_read_b128 v[86:89], v73 offset:36864
	ds_read_b128 v[114:117], v74 offset:55296
	ds_read_b128 v[118:121], v73 offset:41472
	s_waitcnt lgkmcnt(1)
	v_mfma_f32_32x32x16_bf16 v[34:49], v[86:89], v[114:117], v[34:49]
	s_waitcnt lgkmcnt(0)
	v_mfma_f32_32x32x16_bf16 v[2:17], v[118:121], v[114:117], v[2:17]
	ds_read_b128 v[114:117], v74 offset:59904
	s_waitcnt lgkmcnt(0)
	v_mfma_f32_32x32x16_bf16 v[50:65], v[86:89], v[114:117], v[50:65]
	global_load_dwordx4 v[86:89], v80, s[2:3] offset:1920
	global_load_dwordx4 v[122:125], v80, s[4:5] offset:1920
	ds_read_b128 v[126:129], v73 offset:36896
	ds_read_b128 v[130:133], v74 offset:55328
	ds_read_b128 v[134:137], v73 offset:41504
	ds_read_b128 v[142:145], v74 offset:59936
	s_waitcnt vmcnt(9)
	ds_write_b128 v75, v[90:93]
	s_waitcnt vmcnt(8)
	ds_write_b128 v75, v[138:141] offset:18432
	v_mfma_f32_32x32x16_bf16 v[18:33], v[118:121], v[114:117], v[18:33]
	global_load_dwordx4 v[90:93], v79, s[2:3] offset:1920
	global_load_dwordx4 v[114:117], v79, s[4:5] offset:1920
	s_waitcnt lgkmcnt(4)
	v_mfma_f32_32x32x16_bf16 v[34:49], v[126:129], v[130:133], v[34:49]
	s_waitcnt lgkmcnt(3)
	v_mfma_f32_32x32x16_bf16 v[2:17], v[134:137], v[130:133], v[2:17]
	s_waitcnt lgkmcnt(2)
	v_mfma_f32_32x32x16_bf16 v[50:65], v[126:129], v[142:145], v[50:65]
	ds_read_b128 v[118:121], v73 offset:36928
	ds_read_b128 v[126:129], v73 offset:41536
	ds_read_b128 v[130:133], v74 offset:55360
	ds_read_b128 v[138:141], v74 offset:59968
	s_waitcnt vmcnt(9)
	ds_write_b128 v75, v[94:97] offset:4608
	s_waitcnt vmcnt(8)
	ds_write_b128 v75, v[98:101] offset:23040
	v_mfma_f32_32x32x16_bf16 v[18:33], v[134:137], v[142:145], v[18:33]
	global_load_dwordx4 v[94:97], v78, s[2:3] offset:1920
	s_nop 0
	global_load_dwordx4 v[78:81], v78, s[4:5] offset:1920
	s_waitcnt lgkmcnt(3)
	v_mfma_f32_32x32x16_bf16 v[34:49], v[118:121], v[130:133], v[34:49]
	v_mfma_f32_32x32x16_bf16 v[2:17], v[126:129], v[130:133], v[2:17]
	s_waitcnt lgkmcnt(2)
	v_mfma_f32_32x32x16_bf16 v[50:65], v[118:121], v[138:141], v[50:65]
	ds_read_b128 v[98:101], v73 offset:36960
	ds_read_b128 v[118:121], v73 offset:41568
	ds_read_b128 v[130:133], v74 offset:55392
	ds_read_b128 v[134:137], v74 offset:60000
	s_waitcnt vmcnt(9)
	ds_write_b128 v75, v[102:105] offset:9216
	s_waitcnt vmcnt(8)
	ds_write_b128 v75, v[106:109] offset:27648
	v_mfma_f32_32x32x16_bf16 v[18:33], v[126:129], v[138:141], v[18:33]
	s_waitcnt lgkmcnt(3)
	v_mfma_f32_32x32x16_bf16 v[34:49], v[98:101], v[130:133], v[34:49]
	s_waitcnt lgkmcnt(2)
	v_mfma_f32_32x32x16_bf16 v[50:65], v[98:101], v[134:137], v[50:65]
	global_load_dwordx4 v[98:101], v77, s[2:3] offset:1920
	global_load_dwordx4 v[102:105], v77, s[4:5] offset:1920
	s_waitcnt vmcnt(9)
	ds_write_b128 v75, v[82:85] offset:13824
	s_waitcnt vmcnt(8)
	ds_write_b128 v75, v[110:113] offset:32256
	v_mfma_f32_32x32x16_bf16 v[2:17], v[118:121], v[130:133], v[2:17]
	v_mfma_f32_32x32x16_bf16 v[18:33], v[118:121], v[134:137], v[18:33]
	s_waitcnt lgkmcnt(0)
	s_barrier
	ds_read_b128 v[82:85], v73
	ds_read_b128 v[106:109], v74 offset:18432
	ds_read_b128 v[110:113], v73 offset:4608
	s_waitcnt lgkmcnt(1)
	v_mfma_f32_32x32x16_bf16 v[34:49], v[82:85], v[106:109], v[34:49]
	s_waitcnt lgkmcnt(0)
	v_mfma_f32_32x32x16_bf16 v[2:17], v[110:113], v[106:109], v[2:17]
	ds_read_b128 v[106:109], v74 offset:23040
	s_waitcnt lgkmcnt(0)
	v_mfma_f32_32x32x16_bf16 v[50:65], v[82:85], v[106:109], v[50:65]
	ds_read_b128 v[82:85], v73 offset:32
	ds_read_b128 v[118:121], v74 offset:18464
	ds_read_b128 v[126:129], v73 offset:4640
	ds_read_b128 v[130:133], v74 offset:23072
	s_waitcnt vmcnt(7)
	ds_write_b128 v75, v[86:89] offset:36864
	s_waitcnt vmcnt(6)
	ds_write_b128 v75, v[122:125] offset:55296
	v_mfma_f32_32x32x16_bf16 v[18:33], v[110:113], v[106:109], v[18:33]
	s_waitcnt lgkmcnt(4)
	v_mfma_f32_32x32x16_bf16 v[34:49], v[82:85], v[118:121], v[34:49]
	s_waitcnt lgkmcnt(2)
	v_mfma_f32_32x32x16_bf16 v[50:65], v[82:85], v[130:133], v[50:65]
	ds_read_b128 v[82:85], v73 offset:64
	ds_read_b128 v[86:89], v73 offset:4672
	ds_read_b128 v[106:109], v74 offset:18496
	ds_read_b128 v[110:113], v74 offset:23104
	s_waitcnt vmcnt(5)
	ds_write_b128 v75, v[90:93] offset:41472
	s_waitcnt vmcnt(4)
	ds_write_b128 v75, v[114:117] offset:59904
	v_mfma_f32_32x32x16_bf16 v[2:17], v[126:129], v[118:121], v[2:17]
	v_mfma_f32_32x32x16_bf16 v[18:33], v[126:129], v[130:133], v[18:33]
	s_waitcnt lgkmcnt(3)
	v_mfma_f32_32x32x16_bf16 v[34:49], v[82:85], v[106:109], v[34:49]
	v_mfma_f32_32x32x16_bf16 v[2:17], v[86:89], v[106:109], v[2:17]
	s_waitcnt lgkmcnt(2)
	v_mfma_f32_32x32x16_bf16 v[50:65], v[82:85], v[110:113], v[50:65]
	ds_read_b128 v[82:85], v73 offset:96
	ds_read_b128 v[90:93], v73 offset:4704
	ds_read_b128 v[106:109], v74 offset:18528
	ds_read_b128 v[114:117], v74 offset:23136
	s_waitcnt vmcnt(3)
	ds_write_b128 v75, v[94:97] offset:46080
	s_waitcnt vmcnt(2)
	ds_write_b128 v75, v[78:81] offset:64512
	v_mfma_f32_32x32x16_bf16 v[18:33], v[86:89], v[110:113], v[18:33]
	s_waitcnt lgkmcnt(3)
	v_mfma_f32_32x32x16_bf16 v[34:49], v[82:85], v[106:109], v[34:49]
	s_waitcnt vmcnt(1)
	ds_write_b128 v75, v[98:101] offset:50688
	s_waitcnt vmcnt(0)
	ds_write_b128 v76, v[102:105] offset:13824
	v_mfma_f32_32x32x16_bf16 v[2:17], v[90:93], v[106:109], v[2:17]
	s_waitcnt lgkmcnt(4)
	v_mfma_f32_32x32x16_bf16 v[50:65], v[82:85], v[114:117], v[50:65]
	v_mfma_f32_32x32x16_bf16 v[18:33], v[90:93], v[114:117], v[18:33]
	s_waitcnt lgkmcnt(0)
	s_barrier
; DI int tid_() { int t = threadIdx.x; asm volatile("" : "+v"(t)); return t; }
; #define GL1_(RA, RB, i) { RA[i] = *(const u32x4*)(ap + (aoff + (i) * astep)); if ((i) < NB) RB[(i) < NB ? (i) : 0] = *(const u32x4*)(bp + (boff + (i) * bstep)); }
; #define LS1_(RA, RB, ST, i) { char* sn_ = lds + (ST) * STAGE; *(u32x4*)(sn_ + wofs + (i) * 32 * LROW) = RA[i]; \
;                               if ((i) < NB) *(u32x4*)(sn_ + STAGE_OP + wofs + (i) * 32 * LROW) = RB[(i) < NB ? (i) : 0]; }
; template <int NJ> DI void gemm_mainloop_reg(const bf16_t* __restrict__ A, int lda, const bf16_t* __restrict__ Bt, int ldb, int K, f32x16 (&acc)[2][NJ], char* lds) {
;     ...
; #pragma unroll
;   for (int i = 0; i < 4; ++i) GL1_(ra0, rb0, i);
;   ap += 128; bp += 128;
; #pragma unroll
;   for (int i = 0; i < 4; ++i) GL1_(ra1, rb1, i);
;   ap += 128; bp += 128;
; #pragma unroll
;   for (int i = 0; i < 4; ++i) LS1_(ra0, rb0, 0, i);
;   __syncthreads();
;   const int nk = K >> 6;
;   for (int kt = 0; kt < nk; kt += 2) {
;     const bool l0 = (kt + 2 < nk), l1 = (kt + 3 < nk);
;     STEP_(0, l0, ra0, rb0, true, ra1, rb1);
;     __syncthreads();
;     STEP_(1, l1, ra1, rb1, l0, ra0, rb0);
;     __syncthreads();
;   }
;     ...
; }
; template <int NJ> DI void acc_to_lds(const f32x16 (&acc)[2][NJ], float* cl) {
;   const int tid = tid_(), lane = tid & 63, w = tid >> 6, wm = w >> 1, wn = w & 1, h = lane >> 5, c = lane & 31;
; #pragma unroll
;   for (int i = 0; i < 2; ++i)
; #pragma unroll
;     for (int j = 0; j < NJ; ++j)
; #pragma unroll
;       for (int r = 0; r < 16; ++r) {
;         const int row = wm * 64 + i * 32 + (r & 3) + 8 * (r >> 2) + 4 * h;
;         cl[row * CLD + wn * 32 * NJ + j * 32 + c] = acc[i][j][r];
;       }
; DI void phase_ffn_in(const Ctx& c, const bf16_t* A, size_t woff, int site) {
;     ...
;     if (tid < 128) rr[tid] = rsqrtf(ss[mt * 128 + tid] * (1.0f / DM) + EPS);
	ds_read_b128 v[76:79], v73 offset:36864
	ds_read_b128 v[80:83], v74 offset:55296
	ds_read_b128 v[84:87], v73 offset:41472
	s_waitcnt lgkmcnt(1)
	v_mfma_f32_32x32x16_bf16 v[34:49], v[76:79], v[80:83], v[34:49]
	s_waitcnt lgkmcnt(0)
	v_mfma_f32_32x32x16_bf16 v[2:17], v[84:87], v[80:83], v[2:17]
	ds_read_b128 v[80:83], v74 offset:59904
	s_waitcnt lgkmcnt(0)
	v_mfma_f32_32x32x16_bf16 v[50:65], v[76:79], v[80:83], v[50:65]
	ds_read_b128 v[76:79], v73 offset:36896
	ds_read_b128 v[88:91], v74 offset:55328
	ds_read_b128 v[92:95], v73 offset:41504
	ds_read_b128 v[96:99], v74 offset:59936
	v_mfma_f32_32x32x16_bf16 v[18:33], v[84:87], v[80:83], v[18:33]
	s_waitcnt lgkmcnt(2)
	v_mfma_f32_32x32x16_bf16 v[34:49], v[76:79], v[88:91], v[34:49]
	s_waitcnt lgkmcnt(1)
	v_mfma_f32_32x32x16_bf16 v[2:17], v[92:95], v[88:91], v[2:17]
	s_waitcnt lgkmcnt(0)
	v_mfma_f32_32x32x16_bf16 v[50:65], v[76:79], v[96:99], v[50:65]
	ds_read_b128 v[76:79], v73 offset:36928
	ds_read_b128 v[80:83], v73 offset:41536
	ds_read_b128 v[84:87], v74 offset:55360
	ds_read_b128 v[88:91], v74 offset:59968
	v_mfma_f32_32x32x16_bf16 v[18:33], v[92:95], v[96:99], v[18:33]
	s_waitcnt lgkmcnt(1)
	v_mfma_f32_32x32x16_bf16 v[34:49], v[76:79], v[84:87], v[34:49]
	v_mfma_f32_32x32x16_bf16 v[2:17], v[80:83], v[84:87], v[2:17]
	s_waitcnt lgkmcnt(0)
	v_mfma_f32_32x32x16_bf16 v[50:65], v[76:79], v[88:91], v[50:65]
	ds_read_b128 v[76:79], v73 offset:36960
	ds_read_b128 v[84:87], v73 offset:41568
	ds_read_b128 v[92:95], v74 offset:55392
	ds_read_b128 v[96:99], v74 offset:60000
	v_mfma_f32_32x32x16_bf16 v[18:33], v[80:83], v[88:91], v[18:33]
	s_waitcnt lgkmcnt(1)
	v_mfma_f32_32x32x16_bf16 v[34:49], v[76:79], v[92:95], v[34:49]
	v_mfma_f32_32x32x16_bf16 v[2:17], v[84:87], v[92:95], v[2:17]
	s_waitcnt lgkmcnt(0)
	v_mfma_f32_32x32x16_bf16 v[50:65], v[76:79], v[96:99], v[50:65]
	v_mfma_f32_32x32x16_bf16 v[18:33], v[84:87], v[96:99], v[18:33]
	s_setprio 0
	s_nop 0
	v_mov_b32_e32 v73, v199
	s_barrier
	s_nop 0
	v_lshrrev_b32_e32 v75, 3, v73
	v_lshrrev_b32_e32 v74, 1, v73
	v_and_b32_e32 v75, 4, v75
	v_and_b32_e32 v73, 0x5f, v73
	v_and_or_b32 v74, v74, s17, v75
	v_mul_lo_u32 v74, v74, s15
	v_lshlrev_b32_e32 v73, 2, v73
	v_add3_u32 v73, 0, v74, v73
	ds_write2_b32 v73, v34, v50 offset1:32
	ds_write2_b32 v73, v35, v51 offset0:132 offset1:164
	v_add_u32_e32 v34, 0x400, v73
	ds_write2_b32 v34, v36, v52 offset0:8 offset1:40
	ds_write2_b32 v34, v37, v53 offset0:140 offset1:172
	v_add_u32_e32 v34, 0x1000, v73
	ds_write2_b32 v34, v38, v54 offset0:32 offset1:64
	ds_write2_b32 v34, v39, v55 offset0:164 offset1:196
	v_add_u32_e32 v34, 0x1400, v73
	ds_write2_b32 v34, v40, v56 offset0:40 offset1:72
	ds_write2_b32 v34, v41, v57 offset0:172 offset1:204
	v_add_u32_e32 v34, 0x2000, v73
	ds_write2_b32 v34, v42, v58 offset0:64 offset1:96
	ds_write2_b32 v34, v43, v59 offset0:196 offset1:228
	v_add_u32_e32 v34, 0x2400, v73
	ds_write2_b32 v34, v44, v60 offset0:72 offset1:104
	ds_write2_b32 v34, v45, v61 offset0:204 offset1:236
	v_add_u32_e32 v34, 0x3000, v73
	ds_write2_b32 v34, v46, v62 offset0:96 offset1:128
	v_add_u32_e32 v34, 0x3200, v73
	ds_write2_b32 v34, v47, v63 offset0:100 offset1:132
	v_add_u32_e32 v34, 0x3400, v73
	ds_write2_b32 v34, v48, v64 offset0:104 offset1:136
	v_add_u32_e32 v34, 0x3600, v73
	ds_write2_b32 v34, v49, v65 offset0:108 offset1:140
	v_add_u32_e32 v34, 0x4000, v73
	ds_write2_b32 v34, v2, v18 offset0:128 offset1:160
	v_add_u32_e32 v2, 0x4400, v73
	ds_write2_b32 v2, v3, v19 offset0:4 offset1:36
	ds_write2_b32 v2, v4, v20 offset0:136 offset1:168
	v_add_u32_e32 v2, 0x4800, v73
	ds_write2_b32 v2, v5, v21 offset0:12 offset1:44
	v_add_u32_e32 v2, 0x5000, v73
	ds_write2_b32 v2, v6, v22 offset0:160 offset1:192
	v_add_u32_e32 v2, 0x5400, v73
	ds_write2_b32 v2, v7, v23 offset0:36 offset1:68
	ds_write2_b32 v2, v8, v24 offset0:168 offset1:200
	v_add_u32_e32 v2, 0x5800, v73
	ds_write2_b32 v2, v9, v25 offset0:44 offset1:76
	v_add_u32_e32 v2, 0x6000, v73
	ds_write2_b32 v2, v10, v26 offset0:192 offset1:224
	v_add_u32_e32 v2, 0x6400, v73
	ds_write2_b32 v2, v11, v27 offset0:68 offset1:100
	ds_write2_b32 v2, v12, v28 offset0:200 offset1:232
	v_add_u32_e32 v2, 0x6800, v73
	ds_write2_b32 v2, v13, v29 offset0:76 offset1:108
	v_add_u32_e32 v2, 0x7200, v73
	ds_write2_b32 v2, v14, v30 offset0:96 offset1:128
	v_add_u32_e32 v2, 0x7400, v73
	ds_write2_b32 v2, v15, v31 offset0:100 offset1:132
	v_add_u32_e32 v2, 0x7600, v73
	ds_write2_b32 v2, v16, v32 offset0:104 offset1:136
	v_add_u32_e32 v2, 0x7800, v73
	ds_write2_b32 v2, v17, v33 offset0:108 offset1:140
	s_and_saveexec_b64 s[2:3], s[38:39]
	s_cbranch_execz .LBB0_1098
	v_lshl_add_u32 v2, s36, 7, v68
	v_ashrrev_i32_e32 v3, 31, v2
	v_lshl_add_u64 v[2:3], v[2:3], 2, s[0:1]
	global_load_dword v2, v[2:3], off
	s_mov_b32 s4, 0x800000
	s_waitcnt vmcnt(0)
	v_fmamk_f32 v2, v2, 0x3a800000, v198
	v_mul_f32_e32 v3, 0x4b800000, v2
	v_cmp_gt_f32_e32 vcc, s4, v2
	s_nop 1
	v_cndmask_b32_e32 v2, v2, v3, vcc
	v_rsq_f32_e32 v2, v2
	s_nop 0
	v_mul_f32_e32 v3, 0x45800000, v2
	v_cndmask_b32_e32 v2, v2, v3, vcc
	ds_write_b32 v69, v2

; DI int tid_() { int t = threadIdx.x; asm volatile("" : "+v"(t)); return t; }
; #define GL1_(RA, RB, i) { RA[i] = *(const u32x4*)(ap + (aoff + (i) * astep)); if ((i) < NB) RB[(i) < NB ? (i) : 0] = *(const u32x4*)(bp + (boff + (i) * bstep)); }
; #define LS1_(RA, RB, ST, i) { char* sn_ = lds + (ST) * STAGE; *(u32x4*)(sn_ + wofs + (i) * 32 * LROW) = RA[i]; \
;                               if ((i) < NB) *(u32x4*)(sn_ + STAGE_OP + wofs + (i) * 32 * LROW) = RB[(i) < NB ? (i) : 0]; }
; template <int NJ> DI void gemm_mainloop_reg(const bf16_t* __restrict__ A, int lda, const bf16_t* __restrict__ Bt, int ldb, int K, f32x16 (&acc)[2][NJ], char* lds) {
;   const int tid = tid_(), lane = tid & 63, w = tid >> 6, wm = w >> 1, wn = w & 1;
;   const int lr = tid >> 3, lc = tid & 7;
;   const char* ap = (const char*)A;
;   const char* bp = (const char*)Bt;
;   const unsigned aoff = (unsigned)(lr * lda + lc * 8) * 2u, boff = (unsigned)(lr * ldb + lc * 8) * 2u;
;   const unsigned astep = (unsigned)(32 * lda) * 2u, bstep = (unsigned)(32 * ldb) * 2u;
;   constexpr int NB = 2 * NJ;
;   u32x4 ra0[4], rb0[NB], ra1[4], rb1[NB];
;   const int wofs = lr * LROW + lc * 16;
;   const int a_rd = (wm * 64 + (lane & 31)) * LROW + (lane >> 5) * 16;
;   const int b_rd = STAGE_OP + (wn * 32 * NJ + (lane & 31)) * LROW + (lane >> 5) * 16;
;     ...
; #pragma unroll
;   for (int i = 0; i < 4; ++i) GL1_(ra0, rb0, i);
;   ap += 128; bp += 128;
; #pragma unroll
;   for (int i = 0; i < 4; ++i) GL1_(ra1, rb1, i);
;   ap += 128; bp += 128;
; #pragma unroll
;   for (int i = 0; i < 4; ++i) LS1_(ra0, rb0, 0, i);
;   __syncthreads();
;   const int nk = K >> 6;
;   for (int kt = 0; kt < nk; kt += 2) {
;     const bool l0 = (kt + 2 < nk), l1 = (kt + 3 < nk);
;     STEP_(0, l0, ra0, rb0, true, ra1, rb1);
.LBB0_1156:
	s_and_b32 s0, s25, 15
	s_lshl_b32 s38, s0, 7
	s_lshl_b32 s0, s24, 1
	s_and_b32 s72, s0, 0x700
	s_lshl_b32 s0, s24, 2
	s_and_b32 s35, s0, 0xe00
	s_and_b32 s0, s34, 15
	s_add_i32 s40, s10, s38
	s_or_b32 s0, s0, s78
	s_lshl_b32 s39, s40, 2
	s_mul_i32 s0, s0, 0xb4000
	s_add_u32 s0, s86, s0
	s_addc_u32 s1, s87, 0
	s_lshl_b32 s2, s34, 3
	s_and_b32 s2, s2, 0x380
	s_mulk_i32 s2, 0x1680
	v_mov_b32_e32 v34, v199
	s_add_u32 s36, s4, s2
	s_movk_i32 s2, 0x1680
	v_ashrrev_i32_e32 v0, 3, v34
	v_lshlrev_b32_e32 v2, 4, v34
	v_and_b32_e32 v35, 0x70, v2
	v_mul_lo_u32 v2, v0, s2
	v_or_b32_e32 v72, v35, v2
	v_add_u32_e32 v71, 0x2d000, v72
	v_add_u32_e32 v70, 0x5a000, v72
	v_add_u32_e32 v69, 0x87000, v72
	s_addc_u32 s37, s5, 0
	global_load_dwordx4 v[2:5], v72, s[0:1]
	global_load_dwordx4 v[6:9], v71, s[0:1]
	global_load_dwordx4 v[10:13], v70, s[0:1]
	global_load_dwordx4 v[14:17], v69, s[0:1]
	global_load_dwordx4 v[18:21], v72, s[36:37]
	global_load_dwordx4 v[22:25], v71, s[36:37]
	global_load_dwordx4 v[26:29], v70, s[36:37]
	global_load_dwordx4 v[30:33], v69, s[36:37]
	v_mul_lo_u32 v0, v0, s16
	v_lshrrev_b32_e32 v36, 1, v34
	v_and_b32_e32 v37, 31, v34
	v_add3_u32 v67, v0, v35, 0
	v_and_b32_e32 v38, 16, v36
	v_and_or_b32 v36, v36, s17, v37
	global_load_dwordx4 v[74:77], v72, s[0:1] offset:128
	global_load_dwordx4 v[78:81], v71, s[0:1] offset:128
	global_load_dwordx4 v[82:85], v70, s[0:1] offset:128
	global_load_dwordx4 v[86:89], v69, s[0:1] offset:128
	global_load_dwordx4 v[90:93], v72, s[36:37] offset:128
	global_load_dwordx4 v[94:97], v71, s[36:37] offset:128
	global_load_dwordx4 v[98:101], v70, s[36:37] offset:128
	global_load_dwordx4 v[102:105], v69, s[36:37] offset:128
	v_mul_lo_u32 v0, v36, s16
	v_add3_u32 v0, v0, v38, 0
	v_add_u32_e32 v68, 0xd800, v67
	s_waitcnt vmcnt(15)
	ds_write_b128 v67, v[2:5]
	s_waitcnt vmcnt(14)
	ds_write_b128 v67, v[6:9] offset:4608
	s_waitcnt vmcnt(13)
	ds_write_b128 v67, v[10:13] offset:9216
	s_waitcnt vmcnt(12)
	ds_write_b128 v67, v[14:17] offset:13824
	s_waitcnt vmcnt(11)
	ds_write_b128 v67, v[18:21] offset:18432
	s_waitcnt vmcnt(10)
	ds_write_b128 v67, v[22:25] offset:23040
	s_waitcnt vmcnt(9)
	ds_write_b128 v67, v[26:29] offset:27648
	s_waitcnt vmcnt(8)
	ds_write_b128 v67, v[30:33] offset:32256
	v_and_b32_e32 v2, 0x5f, v34
	v_mul_u32_u24_e32 v2, 0x90, v2
	v_add3_u32 v66, v2, v38, 0
	s_waitcnt lgkmcnt(0)
	s_barrier
	ds_read_b128 v[18:21], v0
	ds_read_b128 v[2:5], v66 offset:18432
	ds_read_b128 v[106:109], v0 offset:32
	ds_read_b128 v[110:113], v66 offset:18464
	ds_read_b128 v[22:25], v0 offset:4608
	ds_read_b128 v[114:117], v0 offset:4640
	ds_read_b128 v[26:29], v66 offset:23040
	ds_read_b128 v[118:121], v66 offset:23072
	global_load_dwordx4 v[122:125], v72, s[0:1] offset:256
	global_load_dwordx4 v[126:129], v72, s[36:37] offset:256
	s_waitcnt lgkmcnt(6)
	s_setprio 1
	s_nop 0
	v_mfma_f32_32x32x16_bf16 v[34:49], v[18:21], v[2:5], 0
	s_waitcnt vmcnt(9)
	ds_write_b128 v67, v[74:77] offset:36864
	s_waitcnt vmcnt(5)
	ds_write_b128 v67, v[90:93] offset:55296
	s_waitcnt lgkmcnt(5)
	v_mfma_f32_32x32x16_bf16 v[2:17], v[22:25], v[2:5], 0
	s_waitcnt lgkmcnt(3)
	v_mfma_f32_32x32x16_bf16 v[50:65], v[18:21], v[26:29], 0
	v_mfma_f32_32x32x16_bf16 v[18:33], v[22:25], v[26:29], 0
	global_load_dwordx4 v[74:77], v71, s[0:1] offset:256
	global_load_dwordx4 v[90:93], v71, s[36:37] offset:256
	v_mfma_f32_32x32x16_bf16 v[2:17], v[114:117], v[110:113], v[2:17]
	s_waitcnt lgkmcnt(2)
	v_mfma_f32_32x32x16_bf16 v[18:33], v[114:117], v[118:121], v[18:33]
	v_mfma_f32_32x32x16_bf16 v[34:49], v[106:109], v[110:113], v[34:49]
	v_mfma_f32_32x32x16_bf16 v[50:65], v[106:109], v[118:121], v[50:65]
	ds_read_b128 v[106:109], v0 offset:64
	ds_read_b128 v[110:113], v0 offset:4672
	ds_read_b128 v[130:133], v66 offset:18496
	ds_read_b128 v[134:137], v66 offset:23104
	ds_write_b128 v67, v[78:81] offset:41472
	s_waitcnt vmcnt(6)
	ds_write_b128 v67, v[94:97] offset:59904
	global_load_dwordx4 v[78:81], v70, s[0:1] offset:256
	global_load_dwordx4 v[94:97], v70, s[36:37] offset:256
	s_waitcnt lgkmcnt(3)
	v_mfma_f32_32x32x16_bf16 v[2:17], v[110:113], v[130:133], v[2:17]
	s_waitcnt lgkmcnt(2)
	v_mfma_f32_32x32x16_bf16 v[18:33], v[110:113], v[134:137], v[18:33]
	v_mfma_f32_32x32x16_bf16 v[34:49], v[106:109], v[130:133], v[34:49]
	v_mfma_f32_32x32x16_bf16 v[50:65], v[106:109], v[134:137], v[50:65]
	ds_read_b128 v[106:109], v0 offset:96
	ds_read_b128 v[114:117], v0 offset:4704
	ds_read_b128 v[118:121], v66 offset:18528
	ds_read_b128 v[130:133], v66 offset:23136
	ds_write_b128 v67, v[82:85] offset:46080
	s_waitcnt vmcnt(7)
	ds_write_b128 v67, v[98:101] offset:64512
	global_load_dwordx4 v[82:85], v69, s[0:1] offset:256
	global_load_dwordx4 v[98:101], v69, s[36:37] offset:256
	s_waitcnt lgkmcnt(3)
	v_mfma_f32_32x32x16_bf16 v[2:17], v[114:117], v[118:121], v[2:17]
	ds_write_b128 v67, v[86:89] offset:50688
	s_waitcnt vmcnt(8)
	ds_write_b128 v68, v[102:105] offset:13824
	s_waitcnt lgkmcnt(4)
	v_mfma_f32_32x32x16_bf16 v[18:33], v[114:117], v[130:133], v[18:33]
	v_mfma_f32_32x32x16_bf16 v[34:49], v[106:109], v[118:121], v[34:49]
	v_mfma_f32_32x32x16_bf16 v[50:65], v[106:109], v[130:133], v[50:65]
	s_waitcnt lgkmcnt(0)
	s_barrier
; #define GL1_(RA, RB, i) { RA[i] = *(const u32x4*)(ap + (aoff + (i) * astep)); if ((i) < NB) RB[(i) < NB ? (i) : 0] = *(const u32x4*)(bp + (boff + (i) * bstep)); }
; #define LS1_(RA, RB, ST, i) { char* sn_ = lds + (ST) * STAGE; *(u32x4*)(sn_ + wofs + (i) * 32 * LROW) = RA[i]; \
;                               if ((i) < NB) *(u32x4*)(sn_ + STAGE_OP + wofs + (i) * 32 * LROW) = RB[(i) < NB ? (i) : 0]; }
; template <int NJ> DI void gemm_mainloop_reg(const bf16_t* __restrict__ A, int lda, const bf16_t* __restrict__ Bt, int ldb, int K, f32x16 (&acc)[2][NJ], char* lds) {
;     ...
; #pragma unroll
;   for (int i = 0; i < 4; ++i) GL1_(ra0, rb0, i);
;   ap += 128; bp += 128;
; #pragma unroll
;   for (int i = 0; i < 4; ++i) GL1_(ra1, rb1, i);
;   ap += 128; bp += 128;
; #pragma unroll
;   for (int i = 0; i < 4; ++i) LS1_(ra0, rb0, 0, i);
;   __syncthreads();
;   const int nk = K >> 6;
;   for (int kt = 0; kt < nk; kt += 2) {
;     const bool l0 = (kt + 2 < nk), l1 = (kt + 3 < nk);
;     STEP_(0, l0, ra0, rb0, true, ra1, rb1);
;     __syncthreads();
;     STEP_(1, l1, ra1, rb1, l0, ra0, rb0);
;     __syncthreads();
;   }
	ds_read_b128 v[86:89], v0 offset:36864
	ds_read_b128 v[102:105], v66 offset:55296
	ds_read_b128 v[106:109], v0 offset:36896
	ds_read_b128 v[110:113], v66 offset:55328
	ds_read_b128 v[114:117], v0 offset:41472
	ds_read_b128 v[118:121], v0 offset:41504
	s_waitcnt lgkmcnt(4)
	v_mfma_f32_32x32x16_bf16 v[34:49], v[86:89], v[102:105], v[34:49]
	s_waitcnt lgkmcnt(1)
	v_mfma_f32_32x32x16_bf16 v[2:17], v[114:117], v[102:105], v[2:17]
	ds_read_b128 v[102:105], v66 offset:59904
	ds_read_b128 v[130:133], v66 offset:59936
	s_waitcnt lgkmcnt(1)
	v_mfma_f32_32x32x16_bf16 v[50:65], v[86:89], v[102:105], v[50:65]
	global_load_dwordx4 v[86:89], v72, s[0:1] offset:384
	global_load_dwordx4 v[134:137], v72, s[36:37] offset:384
	s_waitcnt vmcnt(9)
	ds_write_b128 v67, v[122:125]
	s_waitcnt vmcnt(8)
	ds_write_b128 v67, v[126:129] offset:18432
	v_mfma_f32_32x32x16_bf16 v[18:33], v[114:117], v[102:105], v[18:33]
	v_mfma_f32_32x32x16_bf16 v[34:49], v[106:109], v[110:113], v[34:49]
	s_waitcnt lgkmcnt(2)
	v_mfma_f32_32x32x16_bf16 v[50:65], v[106:109], v[130:133], v[50:65]
	global_load_dwordx4 v[102:105], v71, s[0:1] offset:384
	global_load_dwordx4 v[106:109], v71, s[36:37] offset:384
	v_mfma_f32_32x32x16_bf16 v[2:17], v[118:121], v[110:113], v[2:17]
	ds_read_b128 v[110:113], v0 offset:36928
	ds_read_b128 v[114:117], v0 offset:41536
	ds_read_b128 v[122:125], v66 offset:55360
	ds_read_b128 v[126:129], v66 offset:59968
	s_waitcnt vmcnt(9)
	ds_write_b128 v67, v[74:77] offset:4608
	s_waitcnt vmcnt(8)
	ds_write_b128 v67, v[90:93] offset:23040
	v_mfma_f32_32x32x16_bf16 v[18:33], v[118:121], v[130:133], v[18:33]
	global_load_dwordx4 v[74:77], v70, s[0:1] offset:384
	global_load_dwordx4 v[90:93], v70, s[36:37] offset:384
	s_waitcnt lgkmcnt(3)
	v_mfma_f32_32x32x16_bf16 v[2:17], v[114:117], v[122:125], v[2:17]
	s_waitcnt lgkmcnt(2)
	v_mfma_f32_32x32x16_bf16 v[18:33], v[114:117], v[126:129], v[18:33]
	v_mfma_f32_32x32x16_bf16 v[34:49], v[110:113], v[122:125], v[34:49]
	v_mfma_f32_32x32x16_bf16 v[50:65], v[110:113], v[126:129], v[50:65]
	ds_read_b128 v[110:113], v0 offset:36960
	ds_read_b128 v[118:121], v0 offset:41568
	ds_read_b128 v[122:125], v66 offset:55392
	ds_read_b128 v[130:133], v66 offset:60000
	s_waitcnt vmcnt(9)
	ds_write_b128 v67, v[78:81] offset:9216
	s_waitcnt vmcnt(8)
	ds_write_b128 v67, v[94:97] offset:27648
	global_load_dwordx4 v[78:81], v69, s[0:1] offset:384
	global_load_dwordx4 v[94:97], v69, s[36:37] offset:384
	s_waitcnt lgkmcnt(3)
	v_mfma_f32_32x32x16_bf16 v[2:17], v[118:121], v[122:125], v[2:17]
	s_waitcnt vmcnt(9)
	ds_write_b128 v67, v[82:85] offset:13824
	s_waitcnt vmcnt(8)
	ds_write_b128 v67, v[98:101] offset:32256
	s_waitcnt lgkmcnt(4)
	v_mfma_f32_32x32x16_bf16 v[18:33], v[118:121], v[130:133], v[18:33]
	v_mfma_f32_32x32x16_bf16 v[34:49], v[110:113], v[122:125], v[34:49]
	v_mfma_f32_32x32x16_bf16 v[50:65], v[110:113], v[130:133], v[50:65]
	s_waitcnt lgkmcnt(0)
	s_barrier
	ds_read_b128 v[82:85], v0
	ds_read_b128 v[98:101], v66 offset:18432
	ds_read_b128 v[110:113], v0 offset:32
	ds_read_b128 v[114:117], v66 offset:18464
	ds_read_b128 v[118:121], v0 offset:4608
	ds_read_b128 v[122:125], v0 offset:4640
	s_waitcnt lgkmcnt(4)
	v_mfma_f32_32x32x16_bf16 v[34:49], v[82:85], v[98:101], v[34:49]
	s_waitcnt lgkmcnt(1)
	v_mfma_f32_32x32x16_bf16 v[2:17], v[118:121], v[98:101], v[2:17]
	ds_read_b128 v[98:101], v66 offset:23040
	ds_read_b128 v[126:129], v66 offset:23072
	s_waitcnt lgkmcnt(1)
	v_mfma_f32_32x32x16_bf16 v[50:65], v[82:85], v[98:101], v[50:65]
	global_load_dwordx4 v[82:85], v72, s[0:1] offset:512
	global_load_dwordx4 v[130:133], v72, s[36:37] offset:512
	s_waitcnt vmcnt(9)
	ds_write_b128 v67, v[86:89] offset:36864
	s_waitcnt vmcnt(8)
	ds_write_b128 v67, v[134:137] offset:55296
	v_mfma_f32_32x32x16_bf16 v[18:33], v[118:121], v[98:101], v[18:33]
	global_load_dwordx4 v[86:89], v71, s[0:1] offset:512
	global_load_dwordx4 v[98:101], v71, s[36:37] offset:512
	v_mfma_f32_32x32x16_bf16 v[2:17], v[122:125], v[114:117], v[2:17]
	s_waitcnt lgkmcnt(2)
	v_mfma_f32_32x32x16_bf16 v[18:33], v[122:125], v[126:129], v[18:33]
	v_mfma_f32_32x32x16_bf16 v[34:49], v[110:113], v[114:117], v[34:49]
	v_mfma_f32_32x32x16_bf16 v[50:65], v[110:113], v[126:129], v[50:65]
	ds_read_b128 v[110:113], v0 offset:64
	ds_read_b128 v[114:117], v0 offset:4672
	ds_read_b128 v[118:121], v66 offset:18496
	ds_read_b128 v[134:137], v66 offset:23104
	s_waitcnt vmcnt(9)
	ds_write_b128 v67, v[102:105] offset:41472
	s_waitcnt vmcnt(8)
	ds_write_b128 v67, v[106:109] offset:59904
	global_load_dwordx4 v[102:105], v70, s[0:1] offset:512
	global_load_dwordx4 v[106:109], v70, s[36:37] offset:512
	s_waitcnt lgkmcnt(3)
	v_mfma_f32_32x32x16_bf16 v[2:17], v[114:117], v[118:121], v[2:17]
	s_waitcnt lgkmcnt(2)
	v_mfma_f32_32x32x16_bf16 v[18:33], v[114:117], v[134:137], v[18:33]
	v_mfma_f32_32x32x16_bf16 v[34:49], v[110:113], v[118:121], v[34:49]
	v_mfma_f32_32x32x16_bf16 v[50:65], v[110:113], v[134:137], v[50:65]
	ds_read_b128 v[110:113], v0 offset:96
	ds_read_b128 v[118:121], v0 offset:4704
	ds_read_b128 v[122:125], v66 offset:18528
	ds_read_b128 v[126:129], v66 offset:23136
	s_waitcnt vmcnt(9)
	ds_write_b128 v67, v[74:77] offset:46080
	s_waitcnt vmcnt(8)
	ds_write_b128 v67, v[90:93] offset:64512
	global_load_dwordx4 v[74:77], v69, s[0:1] offset:512
	global_load_dwordx4 v[90:93], v69, s[36:37] offset:512
	s_waitcnt lgkmcnt(3)
	v_mfma_f32_32x32x16_bf16 v[2:17], v[118:121], v[122:125], v[2:17]
	s_waitcnt vmcnt(9)
	ds_write_b128 v67, v[78:81] offset:50688
	s_waitcnt vmcnt(8)
	ds_write_b128 v68, v[94:97] offset:13824
	s_waitcnt lgkmcnt(4)
	v_mfma_f32_32x32x16_bf16 v[18:33], v[118:121], v[126:129], v[18:33]
	v_mfma_f32_32x32x16_bf16 v[34:49], v[110:113], v[122:125], v[34:49]
	v_mfma_f32_32x32x16_bf16 v[50:65], v[110:113], v[126:129], v[50:65]
	s_waitcnt lgkmcnt(0)
	s_barrier
; #define GL1_(RA, RB, i) { RA[i] = *(const u32x4*)(ap + (aoff + (i) * astep)); if ((i) < NB) RB[(i) < NB ? (i) : 0] = *(const u32x4*)(bp + (boff + (i) * bstep)); }
; #define LS1_(RA, RB, ST, i) { char* sn_ = lds + (ST) * STAGE; *(u32x4*)(sn_ + wofs + (i) * 32 * LROW) = RA[i]; \
;                               if ((i) < NB) *(u32x4*)(sn_ + STAGE_OP + wofs + (i) * 32 * LROW) = RB[(i) < NB ? (i) : 0]; }
; template <int NJ> DI void gemm_mainloop_reg(const bf16_t* __restrict__ A, int lda, const bf16_t* __restrict__ Bt, int ldb, int K, f32x16 (&acc)[2][NJ], char* lds) {
;     ...
; #pragma unroll
;   for (int i = 0; i < 4; ++i) GL1_(ra0, rb0, i);
;   ap += 128; bp += 128;
; #pragma unroll
;   for (int i = 0; i < 4; ++i) GL1_(ra1, rb1, i);
;   ap += 128; bp += 128;
; #pragma unroll
;   for (int i = 0; i < 4; ++i) LS1_(ra0, rb0, 0, i);
;   __syncthreads();
;   const int nk = K >> 6;
;   for (int kt = 0; kt < nk; kt += 2) {
;     const bool l0 = (kt + 2 < nk), l1 = (kt + 3 < nk);
;     STEP_(0, l0, ra0, rb0, true, ra1, rb1);
;     __syncthreads();
;     STEP_(1, l1, ra1, rb1, l0, ra0, rb0);
;     __syncthreads();
;   }
	ds_read_b128 v[78:81], v0 offset:36864
	ds_read_b128 v[94:97], v66 offset:55296
	ds_read_b128 v[110:113], v0 offset:36896
	ds_read_b128 v[114:117], v66 offset:55328
	ds_read_b128 v[118:121], v0 offset:41472
	ds_read_b128 v[122:125], v0 offset:41504
	s_waitcnt lgkmcnt(4)
	v_mfma_f32_32x32x16_bf16 v[34:49], v[78:81], v[94:97], v[34:49]
	s_waitcnt lgkmcnt(1)
	v_mfma_f32_32x32x16_bf16 v[2:17], v[118:121], v[94:97], v[2:17]
	ds_read_b128 v[94:97], v66 offset:59904
	ds_read_b128 v[126:129], v66 offset:59936
	s_waitcnt lgkmcnt(1)
	v_mfma_f32_32x32x16_bf16 v[50:65], v[78:81], v[94:97], v[50:65]
	global_load_dwordx4 v[78:81], v72, s[0:1] offset:640
	global_load_dwordx4 v[134:137], v72, s[36:37] offset:640
	s_waitcnt vmcnt(9)
	ds_write_b128 v67, v[82:85]
	s_waitcnt vmcnt(8)
	ds_write_b128 v67, v[130:133] offset:18432
	v_mfma_f32_32x32x16_bf16 v[18:33], v[118:121], v[94:97], v[18:33]
	global_load_dwordx4 v[82:85], v71, s[0:1] offset:640
	global_load_dwordx4 v[94:97], v71, s[36:37] offset:640
	v_mfma_f32_32x32x16_bf16 v[2:17], v[122:125], v[114:117], v[2:17]
	s_waitcnt lgkmcnt(2)
	v_mfma_f32_32x32x16_bf16 v[18:33], v[122:125], v[126:129], v[18:33]
	v_mfma_f32_32x32x16_bf16 v[34:49], v[110:113], v[114:117], v[34:49]
	v_mfma_f32_32x32x16_bf16 v[50:65], v[110:113], v[126:129], v[50:65]
	ds_read_b128 v[110:113], v0 offset:36928
	ds_read_b128 v[114:117], v0 offset:41536
	ds_read_b128 v[118:121], v66 offset:55360
	ds_read_b128 v[130:133], v66 offset:59968
	s_waitcnt vmcnt(9)
	ds_write_b128 v67, v[86:89] offset:4608
	s_waitcnt vmcnt(8)
	ds_write_b128 v67, v[98:101] offset:23040
	global_load_dwordx4 v[86:89], v70, s[0:1] offset:640
	global_load_dwordx4 v[98:101], v70, s[36:37] offset:640
	s_waitcnt lgkmcnt(3)
	v_mfma_f32_32x32x16_bf16 v[2:17], v[114:117], v[118:121], v[2:17]
	s_waitcnt lgkmcnt(2)
	v_mfma_f32_32x32x16_bf16 v[18:33], v[114:117], v[130:133], v[18:33]
	v_mfma_f32_32x32x16_bf16 v[34:49], v[110:113], v[118:121], v[34:49]
	v_mfma_f32_32x32x16_bf16 v[50:65], v[110:113], v[130:133], v[50:65]
	ds_read_b128 v[110:113], v0 offset:36960
	ds_read_b128 v[118:121], v0 offset:41568
	ds_read_b128 v[122:125], v66 offset:55392
	ds_read_b128 v[126:129], v66 offset:60000
	s_waitcnt vmcnt(9)
	ds_write_b128 v67, v[102:105] offset:9216
	s_waitcnt vmcnt(8)
	ds_write_b128 v67, v[106:109] offset:27648
	global_load_dwordx4 v[102:105], v69, s[0:1] offset:640
	global_load_dwordx4 v[106:109], v69, s[36:37] offset:640
	s_waitcnt lgkmcnt(3)
	v_mfma_f32_32x32x16_bf16 v[2:17], v[118:121], v[122:125], v[2:17]
	s_waitcnt vmcnt(9)
	ds_write_b128 v67, v[74:77] offset:13824
	s_waitcnt vmcnt(8)
	ds_write_b128 v67, v[90:93] offset:32256
	s_waitcnt lgkmcnt(4)
	v_mfma_f32_32x32x16_bf16 v[18:33], v[118:121], v[126:129], v[18:33]
	v_mfma_f32_32x32x16_bf16 v[34:49], v[110:113], v[122:125], v[34:49]
	v_mfma_f32_32x32x16_bf16 v[50:65], v[110:113], v[126:129], v[50:65]
	s_waitcnt lgkmcnt(0)
	s_barrier
	ds_read_b128 v[74:77], v0
	ds_read_b128 v[90:93], v66 offset:18432
	ds_read_b128 v[110:113], v0 offset:32
	ds_read_b128 v[114:117], v66 offset:18464
	ds_read_b128 v[118:121], v0 offset:4608
	ds_read_b128 v[122:125], v0 offset:4640
	s_waitcnt lgkmcnt(4)
	v_mfma_f32_32x32x16_bf16 v[34:49], v[74:77], v[90:93], v[34:49]
	s_waitcnt lgkmcnt(1)
	v_mfma_f32_32x32x16_bf16 v[2:17], v[118:121], v[90:93], v[2:17]
	ds_read_b128 v[90:93], v66 offset:23040
	ds_read_b128 v[126:129], v66 offset:23072
	s_waitcnt lgkmcnt(1)
	v_mfma_f32_32x32x16_bf16 v[50:65], v[74:77], v[90:93], v[50:65]
	global_load_dwordx4 v[74:77], v72, s[0:1] offset:768
	global_load_dwordx4 v[130:133], v72, s[36:37] offset:768
	s_waitcnt vmcnt(9)
	ds_write_b128 v67, v[78:81] offset:36864
	s_waitcnt vmcnt(8)
	ds_write_b128 v67, v[134:137] offset:55296
	v_mfma_f32_32x32x16_bf16 v[18:33], v[118:121], v[90:93], v[18:33]
	global_load_dwordx4 v[78:81], v71, s[0:1] offset:768
	global_load_dwordx4 v[90:93], v71, s[36:37] offset:768
	v_mfma_f32_32x32x16_bf16 v[2:17], v[122:125], v[114:117], v[2:17]
	s_waitcnt lgkmcnt(2)
	v_mfma_f32_32x32x16_bf16 v[18:33], v[122:125], v[126:129], v[18:33]
	v_mfma_f32_32x32x16_bf16 v[34:49], v[110:113], v[114:117], v[34:49]
	v_mfma_f32_32x32x16_bf16 v[50:65], v[110:113], v[126:129], v[50:65]
	ds_read_b128 v[110:113], v0 offset:64
	ds_read_b128 v[114:117], v0 offset:4672
	ds_read_b128 v[118:121], v66 offset:18496
	ds_read_b128 v[134:137], v66 offset:23104
	s_waitcnt vmcnt(9)
	ds_write_b128 v67, v[82:85] offset:41472
	s_waitcnt vmcnt(8)
	ds_write_b128 v67, v[94:97] offset:59904
	global_load_dwordx4 v[82:85], v70, s[0:1] offset:768
	global_load_dwordx4 v[94:97], v70, s[36:37] offset:768
	s_waitcnt lgkmcnt(3)
	v_mfma_f32_32x32x16_bf16 v[2:17], v[114:117], v[118:121], v[2:17]
	s_waitcnt lgkmcnt(2)
	v_mfma_f32_32x32x16_bf16 v[18:33], v[114:117], v[134:137], v[18:33]
	v_mfma_f32_32x32x16_bf16 v[34:49], v[110:113], v[118:121], v[34:49]
	v_mfma_f32_32x32x16_bf16 v[50:65], v[110:113], v[134:137], v[50:65]
	ds_read_b128 v[110:113], v0 offset:96
	ds_read_b128 v[118:121], v0 offset:4704
	ds_read_b128 v[122:125], v66 offset:18528
	ds_read_b128 v[126:129], v66 offset:23136
	s_waitcnt vmcnt(9)
	ds_write_b128 v67, v[86:89] offset:46080
	s_waitcnt vmcnt(8)
	ds_write_b128 v67, v[98:101] offset:64512
	global_load_dwordx4 v[86:89], v69, s[0:1] offset:768
	global_load_dwordx4 v[98:101], v69, s[36:37] offset:768
	s_waitcnt lgkmcnt(3)
	v_mfma_f32_32x32x16_bf16 v[2:17], v[118:121], v[122:125], v[2:17]
	s_waitcnt vmcnt(9)
	ds_write_b128 v67, v[102:105] offset:50688
	s_waitcnt vmcnt(8)
	ds_write_b128 v68, v[106:109] offset:13824
	s_waitcnt lgkmcnt(4)
	v_mfma_f32_32x32x16_bf16 v[18:33], v[118:121], v[126:129], v[18:33]
	v_mfma_f32_32x32x16_bf16 v[34:49], v[110:113], v[122:125], v[34:49]
	v_mfma_f32_32x32x16_bf16 v[50:65], v[110:113], v[126:129], v[50:65]
	s_waitcnt lgkmcnt(0)
	s_barrier
; #define GL1_(RA, RB, i) { RA[i] = *(const u32x4*)(ap + (aoff + (i) * astep)); if ((i) < NB) RB[(i) < NB ? (i) : 0] = *(const u32x4*)(bp + (boff + (i) * bstep)); }
; #define LS1_(RA, RB, ST, i) { char* sn_ = lds + (ST) * STAGE; *(u32x4*)(sn_ + wofs + (i) * 32 * LROW) = RA[i]; \
;                               if ((i) < NB) *(u32x4*)(sn_ + STAGE_OP + wofs + (i) * 32 * LROW) = RB[(i) < NB ? (i) : 0]; }
; template <int NJ> DI void gemm_mainloop_reg(const bf16_t* __restrict__ A, int lda, const bf16_t* __restrict__ Bt, int ldb, int K, f32x16 (&acc)[2][NJ], char* lds) {
;     ...
; #pragma unroll
;   for (int i = 0; i < 4; ++i) GL1_(ra0, rb0, i);
;   ap += 128; bp += 128;
; #pragma unroll
;   for (int i = 0; i < 4; ++i) GL1_(ra1, rb1, i);
;   ap += 128; bp += 128;
; #pragma unroll
;   for (int i = 0; i < 4; ++i) LS1_(ra0, rb0, 0, i);
;   __syncthreads();
;   const int nk = K >> 6;
;   for (int kt = 0; kt < nk; kt += 2) {
;     const bool l0 = (kt + 2 < nk), l1 = (kt + 3 < nk);
;     STEP_(0, l0, ra0, rb0, true, ra1, rb1);
;     __syncthreads();
;     STEP_(1, l1, ra1, rb1, l0, ra0, rb0);
;     __syncthreads();
;   }
	ds_read_b128 v[102:105], v0 offset:36864
	ds_read_b128 v[106:109], v66 offset:55296
	ds_read_b128 v[110:113], v0 offset:36896
	ds_read_b128 v[114:117], v66 offset:55328
	ds_read_b128 v[118:121], v0 offset:41472
	ds_read_b128 v[122:125], v0 offset:41504
	s_waitcnt lgkmcnt(4)
	v_mfma_f32_32x32x16_bf16 v[34:49], v[102:105], v[106:109], v[34:49]
	s_waitcnt lgkmcnt(1)
	v_mfma_f32_32x32x16_bf16 v[2:17], v[118:121], v[106:109], v[2:17]
	ds_read_b128 v[106:109], v66 offset:59904
	ds_read_b128 v[126:129], v66 offset:59936
	s_waitcnt lgkmcnt(1)
	v_mfma_f32_32x32x16_bf16 v[50:65], v[102:105], v[106:109], v[50:65]
	global_load_dwordx4 v[102:105], v72, s[0:1] offset:896
	global_load_dwordx4 v[134:137], v72, s[36:37] offset:896
	s_waitcnt vmcnt(9)
	ds_write_b128 v67, v[74:77]
	s_waitcnt vmcnt(8)
	ds_write_b128 v67, v[130:133] offset:18432
	v_mfma_f32_32x32x16_bf16 v[18:33], v[118:121], v[106:109], v[18:33]
	global_load_dwordx4 v[74:77], v71, s[0:1] offset:896
	global_load_dwordx4 v[106:109], v71, s[36:37] offset:896
	v_mfma_f32_32x32x16_bf16 v[2:17], v[122:125], v[114:117], v[2:17]
	s_waitcnt lgkmcnt(2)
	v_mfma_f32_32x32x16_bf16 v[18:33], v[122:125], v[126:129], v[18:33]
	v_mfma_f32_32x32x16_bf16 v[34:49], v[110:113], v[114:117], v[34:49]
	v_mfma_f32_32x32x16_bf16 v[50:65], v[110:113], v[126:129], v[50:65]
	ds_read_b128 v[110:113], v0 offset:36928
	ds_read_b128 v[114:117], v0 offset:41536
	ds_read_b128 v[118:121], v66 offset:55360
	ds_read_b128 v[130:133], v66 offset:59968
	s_waitcnt vmcnt(9)
	ds_write_b128 v67, v[78:81] offset:4608
	s_waitcnt vmcnt(8)
	ds_write_b128 v67, v[90:93] offset:23040
	global_load_dwordx4 v[78:81], v70, s[0:1] offset:896
	global_load_dwordx4 v[90:93], v70, s[36:37] offset:896
	s_waitcnt lgkmcnt(3)
	v_mfma_f32_32x32x16_bf16 v[2:17], v[114:117], v[118:121], v[2:17]
	s_waitcnt lgkmcnt(2)
	v_mfma_f32_32x32x16_bf16 v[18:33], v[114:117], v[130:133], v[18:33]
	v_mfma_f32_32x32x16_bf16 v[34:49], v[110:113], v[118:121], v[34:49]
	v_mfma_f32_32x32x16_bf16 v[50:65], v[110:113], v[130:133], v[50:65]
	ds_read_b128 v[110:113], v0 offset:36960
	ds_read_b128 v[118:121], v0 offset:41568
	ds_read_b128 v[122:125], v66 offset:55392
	ds_read_b128 v[126:129], v66 offset:60000
	s_waitcnt vmcnt(9)
	ds_write_b128 v67, v[82:85] offset:9216
	s_waitcnt vmcnt(8)
	ds_write_b128 v67, v[94:97] offset:27648
	global_load_dwordx4 v[82:85], v69, s[0:1] offset:896
	global_load_dwordx4 v[94:97], v69, s[36:37] offset:896
	s_waitcnt lgkmcnt(3)
	v_mfma_f32_32x32x16_bf16 v[2:17], v[118:121], v[122:125], v[2:17]
	s_waitcnt vmcnt(9)
	ds_write_b128 v67, v[86:89] offset:13824
	s_waitcnt vmcnt(8)
	ds_write_b128 v67, v[98:101] offset:32256
	s_waitcnt lgkmcnt(4)
	v_mfma_f32_32x32x16_bf16 v[18:33], v[118:121], v[126:129], v[18:33]
	v_mfma_f32_32x32x16_bf16 v[34:49], v[110:113], v[122:125], v[34:49]
	v_mfma_f32_32x32x16_bf16 v[50:65], v[110:113], v[126:129], v[50:65]
	s_waitcnt lgkmcnt(0)
	s_barrier
	ds_read_b128 v[86:89], v0
	ds_read_b128 v[98:101], v66 offset:18432
	ds_read_b128 v[110:113], v0 offset:32
	ds_read_b128 v[114:117], v66 offset:18464
	ds_read_b128 v[118:121], v0 offset:4608
	ds_read_b128 v[122:125], v0 offset:4640
	s_waitcnt lgkmcnt(4)
	v_mfma_f32_32x32x16_bf16 v[34:49], v[86:89], v[98:101], v[34:49]
	s_waitcnt lgkmcnt(1)
	v_mfma_f32_32x32x16_bf16 v[2:17], v[118:121], v[98:101], v[2:17]
	ds_read_b128 v[98:101], v66 offset:23040
	ds_read_b128 v[126:129], v66 offset:23072
	s_waitcnt lgkmcnt(1)
	v_mfma_f32_32x32x16_bf16 v[50:65], v[86:89], v[98:101], v[50:65]
	global_load_dwordx4 v[86:89], v72, s[0:1] offset:1024
	global_load_dwordx4 v[130:133], v72, s[36:37] offset:1024
	s_waitcnt vmcnt(9)
	ds_write_b128 v67, v[102:105] offset:36864
	s_waitcnt vmcnt(8)
	ds_write_b128 v67, v[134:137] offset:55296
	v_mfma_f32_32x32x16_bf16 v[18:33], v[118:121], v[98:101], v[18:33]
	global_load_dwordx4 v[98:101], v71, s[0:1] offset:1024
	global_load_dwordx4 v[102:105], v71, s[36:37] offset:1024
	v_mfma_f32_32x32x16_bf16 v[2:17], v[122:125], v[114:117], v[2:17]
	s_waitcnt lgkmcnt(2)
	v_mfma_f32_32x32x16_bf16 v[18:33], v[122:125], v[126:129], v[18:33]
	v_mfma_f32_32x32x16_bf16 v[34:49], v[110:113], v[114:117], v[34:49]
	v_mfma_f32_32x32x16_bf16 v[50:65], v[110:113], v[126:129], v[50:65]
	ds_read_b128 v[110:113], v0 offset:64
	ds_read_b128 v[114:117], v0 offset:4672
	ds_read_b128 v[118:121], v66 offset:18496
	ds_read_b128 v[134:137], v66 offset:23104
	s_waitcnt vmcnt(9)
	ds_write_b128 v67, v[74:77] offset:41472
	s_waitcnt vmcnt(8)
	ds_write_b128 v67, v[106:109] offset:59904
	global_load_dwordx4 v[74:77], v70, s[0:1] offset:1024
	global_load_dwordx4 v[106:109], v70, s[36:37] offset:1024
	s_waitcnt lgkmcnt(3)
	v_mfma_f32_32x32x16_bf16 v[2:17], v[114:117], v[118:121], v[2:17]
	s_waitcnt lgkmcnt(2)
	v_mfma_f32_32x32x16_bf16 v[18:33], v[114:117], v[134:137], v[18:33]
	v_mfma_f32_32x32x16_bf16 v[34:49], v[110:113], v[118:121], v[34:49]
	v_mfma_f32_32x32x16_bf16 v[50:65], v[110:113], v[134:137], v[50:65]
	ds_read_b128 v[110:113], v0 offset:96
	ds_read_b128 v[118:121], v0 offset:4704
	ds_read_b128 v[122:125], v66 offset:18528
	ds_read_b128 v[126:129], v66 offset:23136
	s_waitcnt vmcnt(9)
	ds_write_b128 v67, v[78:81] offset:46080
	s_waitcnt vmcnt(8)
	ds_write_b128 v67, v[90:93] offset:64512
	global_load_dwordx4 v[78:81], v69, s[0:1] offset:1024
	global_load_dwordx4 v[90:93], v69, s[36:37] offset:1024
	s_waitcnt lgkmcnt(3)
	v_mfma_f32_32x32x16_bf16 v[2:17], v[118:121], v[122:125], v[2:17]
	s_waitcnt vmcnt(9)
	ds_write_b128 v67, v[82:85] offset:50688
	s_waitcnt vmcnt(8)
	ds_write_b128 v68, v[94:97] offset:13824
	s_waitcnt lgkmcnt(4)
	v_mfma_f32_32x32x16_bf16 v[18:33], v[118:121], v[126:129], v[18:33]
	v_mfma_f32_32x32x16_bf16 v[34:49], v[110:113], v[122:125], v[34:49]
	v_mfma_f32_32x32x16_bf16 v[50:65], v[110:113], v[126:129], v[50:65]
	s_waitcnt lgkmcnt(0)
	s_barrier
; #define GL1_(RA, RB, i) { RA[i] = *(const u32x4*)(ap + (aoff + (i) * astep)); if ((i) < NB) RB[(i) < NB ? (i) : 0] = *(const u32x4*)(bp + (boff + (i) * bstep)); }
; #define LS1_(RA, RB, ST, i) { char* sn_ = lds + (ST) * STAGE; *(u32x4*)(sn_ + wofs + (i) * 32 * LROW) = RA[i]; \
;                               if ((i) < NB) *(u32x4*)(sn_ + STAGE_OP + wofs + (i) * 32 * LROW) = RB[(i) < NB ? (i) : 0]; }
; template <int NJ> DI void gemm_mainloop_reg(const bf16_t* __restrict__ A, int lda, const bf16_t* __restrict__ Bt, int ldb, int K, f32x16 (&acc)[2][NJ], char* lds) {
;     ...
; #pragma unroll
;   for (int i = 0; i < 4; ++i) GL1_(ra0, rb0, i);
;   ap += 128; bp += 128;
; #pragma unroll
;   for (int i = 0; i < 4; ++i) GL1_(ra1, rb1, i);
;   ap += 128; bp += 128;
; #pragma unroll
;   for (int i = 0; i < 4; ++i) LS1_(ra0, rb0, 0, i);
;   __syncthreads();
;   const int nk = K >> 6;
;   for (int kt = 0; kt < nk; kt += 2) {
;     const bool l0 = (kt + 2 < nk), l1 = (kt + 3 < nk);
;     STEP_(0, l0, ra0, rb0, true, ra1, rb1);
;     __syncthreads();
;     STEP_(1, l1, ra1, rb1, l0, ra0, rb0);
;     __syncthreads();
;   }
	ds_read_b128 v[82:85], v0 offset:36864
	ds_read_b128 v[94:97], v66 offset:55296
	ds_read_b128 v[110:113], v0 offset:36896
	ds_read_b128 v[114:117], v66 offset:55328
	ds_read_b128 v[118:121], v0 offset:41472
	ds_read_b128 v[122:125], v0 offset:41504
	s_waitcnt lgkmcnt(4)
	v_mfma_f32_32x32x16_bf16 v[34:49], v[82:85], v[94:97], v[34:49]
	s_waitcnt lgkmcnt(1)
	v_mfma_f32_32x32x16_bf16 v[2:17], v[118:121], v[94:97], v[2:17]
	ds_read_b128 v[94:97], v66 offset:59904
	ds_read_b128 v[126:129], v66 offset:59936
	s_waitcnt lgkmcnt(1)
	v_mfma_f32_32x32x16_bf16 v[50:65], v[82:85], v[94:97], v[50:65]
	global_load_dwordx4 v[82:85], v72, s[0:1] offset:1152
	global_load_dwordx4 v[134:137], v72, s[36:37] offset:1152
	s_waitcnt vmcnt(9)
	ds_write_b128 v67, v[86:89]
	s_waitcnt vmcnt(8)
	ds_write_b128 v67, v[130:133] offset:18432
	v_mfma_f32_32x32x16_bf16 v[18:33], v[118:121], v[94:97], v[18:33]
	global_load_dwordx4 v[86:89], v71, s[0:1] offset:1152
	global_load_dwordx4 v[94:97], v71, s[36:37] offset:1152
	v_mfma_f32_32x32x16_bf16 v[2:17], v[122:125], v[114:117], v[2:17]
	s_waitcnt lgkmcnt(2)
	v_mfma_f32_32x32x16_bf16 v[18:33], v[122:125], v[126:129], v[18:33]
	v_mfma_f32_32x32x16_bf16 v[34:49], v[110:113], v[114:117], v[34:49]
	v_mfma_f32_32x32x16_bf16 v[50:65], v[110:113], v[126:129], v[50:65]
	ds_read_b128 v[110:113], v0 offset:36928
	ds_read_b128 v[114:117], v0 offset:41536
	ds_read_b128 v[118:121], v66 offset:55360
	ds_read_b128 v[130:133], v66 offset:59968
	s_waitcnt vmcnt(9)
	ds_write_b128 v67, v[98:101] offset:4608
	s_waitcnt vmcnt(8)
	ds_write_b128 v67, v[102:105] offset:23040
	global_load_dwordx4 v[98:101], v70, s[0:1] offset:1152
	global_load_dwordx4 v[102:105], v70, s[36:37] offset:1152
	s_waitcnt lgkmcnt(3)
	v_mfma_f32_32x32x16_bf16 v[2:17], v[114:117], v[118:121], v[2:17]
	s_waitcnt lgkmcnt(2)
	v_mfma_f32_32x32x16_bf16 v[18:33], v[114:117], v[130:133], v[18:33]
	v_mfma_f32_32x32x16_bf16 v[34:49], v[110:113], v[118:121], v[34:49]
	v_mfma_f32_32x32x16_bf16 v[50:65], v[110:113], v[130:133], v[50:65]
	ds_read_b128 v[110:113], v0 offset:36960
	ds_read_b128 v[118:121], v0 offset:41568
	ds_read_b128 v[122:125], v66 offset:55392
	ds_read_b128 v[126:129], v66 offset:60000
	s_waitcnt vmcnt(9)
	ds_write_b128 v67, v[74:77] offset:9216
	s_waitcnt vmcnt(8)
	ds_write_b128 v67, v[106:109] offset:27648
	global_load_dwordx4 v[74:77], v69, s[0:1] offset:1152
	global_load_dwordx4 v[106:109], v69, s[36:37] offset:1152
	s_waitcnt lgkmcnt(3)
	v_mfma_f32_32x32x16_bf16 v[2:17], v[118:121], v[122:125], v[2:17]
	s_waitcnt vmcnt(9)
	ds_write_b128 v67, v[78:81] offset:13824
	s_waitcnt vmcnt(8)
	ds_write_b128 v67, v[90:93] offset:32256
	s_waitcnt lgkmcnt(4)
	v_mfma_f32_32x32x16_bf16 v[18:33], v[118:121], v[126:129], v[18:33]
	v_mfma_f32_32x32x16_bf16 v[34:49], v[110:113], v[122:125], v[34:49]
	v_mfma_f32_32x32x16_bf16 v[50:65], v[110:113], v[126:129], v[50:65]
	s_waitcnt lgkmcnt(0)
	s_barrier
	ds_read_b128 v[78:81], v0
	ds_read_b128 v[90:93], v66 offset:18432
	ds_read_b128 v[110:113], v0 offset:32
	ds_read_b128 v[114:117], v66 offset:18464
	ds_read_b128 v[118:121], v0 offset:4608
	ds_read_b128 v[122:125], v0 offset:4640
	s_waitcnt lgkmcnt(4)
	v_mfma_f32_32x32x16_bf16 v[34:49], v[78:81], v[90:93], v[34:49]
	s_waitcnt lgkmcnt(1)
	v_mfma_f32_32x32x16_bf16 v[2:17], v[118:121], v[90:93], v[2:17]
	ds_read_b128 v[90:93], v66 offset:23040
	ds_read_b128 v[126:129], v66 offset:23072
	s_waitcnt lgkmcnt(1)
	v_mfma_f32_32x32x16_bf16 v[50:65], v[78:81], v[90:93], v[50:65]
	global_load_dwordx4 v[78:81], v72, s[0:1] offset:1280
	global_load_dwordx4 v[130:133], v72, s[36:37] offset:1280
	s_waitcnt vmcnt(9)
	ds_write_b128 v67, v[82:85] offset:36864
	s_waitcnt vmcnt(8)
	ds_write_b128 v67, v[134:137] offset:55296
	v_mfma_f32_32x32x16_bf16 v[18:33], v[118:121], v[90:93], v[18:33]
	global_load_dwordx4 v[82:85], v71, s[0:1] offset:1280
	global_load_dwordx4 v[90:93], v71, s[36:37] offset:1280
	v_mfma_f32_32x32x16_bf16 v[2:17], v[122:125], v[114:117], v[2:17]
	s_waitcnt lgkmcnt(2)
	v_mfma_f32_32x32x16_bf16 v[18:33], v[122:125], v[126:129], v[18:33]
	v_mfma_f32_32x32x16_bf16 v[34:49], v[110:113], v[114:117], v[34:49]
	v_mfma_f32_32x32x16_bf16 v[50:65], v[110:113], v[126:129], v[50:65]
	ds_read_b128 v[110:113], v0 offset:64
	ds_read_b128 v[114:117], v0 offset:4672
	ds_read_b128 v[118:121], v66 offset:18496
	ds_read_b128 v[134:137], v66 offset:23104
	s_waitcnt vmcnt(9)
	ds_write_b128 v67, v[86:89] offset:41472
	s_waitcnt vmcnt(8)
	ds_write_b128 v67, v[94:97] offset:59904
	global_load_dwordx4 v[86:89], v70, s[0:1] offset:1280
	global_load_dwordx4 v[94:97], v70, s[36:37] offset:1280
	s_waitcnt lgkmcnt(3)
	v_mfma_f32_32x32x16_bf16 v[2:17], v[114:117], v[118:121], v[2:17]
	s_waitcnt lgkmcnt(2)
	v_mfma_f32_32x32x16_bf16 v[18:33], v[114:117], v[134:137], v[18:33]
	v_mfma_f32_32x32x16_bf16 v[34:49], v[110:113], v[118:121], v[34:49]
	v_mfma_f32_32x32x16_bf16 v[50:65], v[110:113], v[134:137], v[50:65]
	ds_read_b128 v[110:113], v0 offset:96
	ds_read_b128 v[118:121], v0 offset:4704
	ds_read_b128 v[122:125], v66 offset:18528
	ds_read_b128 v[126:129], v66 offset:23136
	s_waitcnt vmcnt(9)
	ds_write_b128 v67, v[98:101] offset:46080
	s_waitcnt vmcnt(8)
	ds_write_b128 v67, v[102:105] offset:64512
	global_load_dwordx4 v[98:101], v69, s[0:1] offset:1280
	global_load_dwordx4 v[102:105], v69, s[36:37] offset:1280
	s_waitcnt lgkmcnt(3)
	v_mfma_f32_32x32x16_bf16 v[2:17], v[118:121], v[122:125], v[2:17]
	s_waitcnt vmcnt(9)
	ds_write_b128 v67, v[74:77] offset:50688
	s_waitcnt vmcnt(8)
	ds_write_b128 v68, v[106:109] offset:13824
	s_waitcnt lgkmcnt(4)
	v_mfma_f32_32x32x16_bf16 v[18:33], v[118:121], v[126:129], v[18:33]
	v_mfma_f32_32x32x16_bf16 v[34:49], v[110:113], v[122:125], v[34:49]
	v_mfma_f32_32x32x16_bf16 v[50:65], v[110:113], v[126:129], v[50:65]
	s_waitcnt lgkmcnt(0)
	s_barrier
; #define GL1_(RA, RB, i) { RA[i] = *(const u32x4*)(ap + (aoff + (i) * astep)); if ((i) < NB) RB[(i) < NB ? (i) : 0] = *(const u32x4*)(bp + (boff + (i) * bstep)); }
; #define LS1_(RA, RB, ST, i) { char* sn_ = lds + (ST) * STAGE; *(u32x4*)(sn_ + wofs + (i) * 32 * LROW) = RA[i]; \
;                               if ((i) < NB) *(u32x4*)(sn_ + STAGE_OP + wofs + (i) * 32 * LROW) = RB[(i) < NB ? (i) : 0]; }
; template <int NJ> DI void gemm_mainloop_reg(const bf16_t* __restrict__ A, int lda, const bf16_t* __restrict__ Bt, int ldb, int K, f32x16 (&acc)[2][NJ], char* lds) {
;     ...
; #pragma unroll
;   for (int i = 0; i < 4; ++i) GL1_(ra0, rb0, i);
;   ap += 128; bp += 128;
; #pragma unroll
;   for (int i = 0; i < 4; ++i) GL1_(ra1, rb1, i);
;   ap += 128; bp += 128;
; #pragma unroll
;   for (int i = 0; i < 4; ++i) LS1_(ra0, rb0, 0, i);
;   __syncthreads();
;   const int nk = K >> 6;
;   for (int kt = 0; kt < nk; kt += 2) {
;     const bool l0 = (kt + 2 < nk), l1 = (kt + 3 < nk);
;     STEP_(0, l0, ra0, rb0, true, ra1, rb1);
;     __syncthreads();
;     STEP_(1, l1, ra1, rb1, l0, ra0, rb0);
;     __syncthreads();
;   }
	ds_read_b128 v[74:77], v0 offset:36864
	ds_read_b128 v[106:109], v66 offset:55296
	ds_read_b128 v[110:113], v0 offset:36896
	ds_read_b128 v[114:117], v66 offset:55328
	ds_read_b128 v[118:121], v0 offset:41472
	ds_read_b128 v[122:125], v0 offset:41504
	s_waitcnt lgkmcnt(4)
	v_mfma_f32_32x32x16_bf16 v[34:49], v[74:77], v[106:109], v[34:49]
	s_waitcnt lgkmcnt(1)
	v_mfma_f32_32x32x16_bf16 v[2:17], v[118:121], v[106:109], v[2:17]
	ds_read_b128 v[106:109], v66 offset:59904
	ds_read_b128 v[126:129], v66 offset:59936
	s_waitcnt lgkmcnt(1)
	v_mfma_f32_32x32x16_bf16 v[50:65], v[74:77], v[106:109], v[50:65]
	global_load_dwordx4 v[74:77], v72, s[0:1] offset:1408
	global_load_dwordx4 v[134:137], v72, s[36:37] offset:1408
	s_waitcnt vmcnt(9)
	ds_write_b128 v67, v[78:81]
	s_waitcnt vmcnt(8)
	ds_write_b128 v67, v[130:133] offset:18432
	v_mfma_f32_32x32x16_bf16 v[18:33], v[118:121], v[106:109], v[18:33]
	global_load_dwordx4 v[78:81], v71, s[0:1] offset:1408
	global_load_dwordx4 v[106:109], v71, s[36:37] offset:1408
	v_mfma_f32_32x32x16_bf16 v[2:17], v[122:125], v[114:117], v[2:17]
	s_waitcnt lgkmcnt(2)
	v_mfma_f32_32x32x16_bf16 v[18:33], v[122:125], v[126:129], v[18:33]
	v_mfma_f32_32x32x16_bf16 v[34:49], v[110:113], v[114:117], v[34:49]
	v_mfma_f32_32x32x16_bf16 v[50:65], v[110:113], v[126:129], v[50:65]
	ds_read_b128 v[110:113], v0 offset:36928
	ds_read_b128 v[114:117], v0 offset:41536
	ds_read_b128 v[118:121], v66 offset:55360
	ds_read_b128 v[130:133], v66 offset:59968
	s_waitcnt vmcnt(9)
	ds_write_b128 v67, v[82:85] offset:4608
	s_waitcnt vmcnt(8)
	ds_write_b128 v67, v[90:93] offset:23040
	global_load_dwordx4 v[82:85], v70, s[0:1] offset:1408
	global_load_dwordx4 v[90:93], v70, s[36:37] offset:1408
	s_waitcnt lgkmcnt(3)
	v_mfma_f32_32x32x16_bf16 v[2:17], v[114:117], v[118:121], v[2:17]
	s_waitcnt lgkmcnt(2)
	v_mfma_f32_32x32x16_bf16 v[18:33], v[114:117], v[130:133], v[18:33]
	v_mfma_f32_32x32x16_bf16 v[34:49], v[110:113], v[118:121], v[34:49]
	v_mfma_f32_32x32x16_bf16 v[50:65], v[110:113], v[130:133], v[50:65]
	ds_read_b128 v[110:113], v0 offset:36960
	ds_read_b128 v[118:121], v0 offset:41568
	ds_read_b128 v[122:125], v66 offset:55392
	ds_read_b128 v[126:129], v66 offset:60000
	s_waitcnt vmcnt(9)
	ds_write_b128 v67, v[86:89] offset:9216
	s_waitcnt vmcnt(8)
	ds_write_b128 v67, v[94:97] offset:27648
	global_load_dwordx4 v[86:89], v69, s[0:1] offset:1408
	global_load_dwordx4 v[94:97], v69, s[36:37] offset:1408
	s_waitcnt lgkmcnt(3)
	v_mfma_f32_32x32x16_bf16 v[2:17], v[118:121], v[122:125], v[2:17]
	s_waitcnt vmcnt(9)
	ds_write_b128 v67, v[98:101] offset:13824
	s_waitcnt vmcnt(8)
	ds_write_b128 v67, v[102:105] offset:32256
	s_waitcnt lgkmcnt(4)
	v_mfma_f32_32x32x16_bf16 v[18:33], v[118:121], v[126:129], v[18:33]
	v_mfma_f32_32x32x16_bf16 v[34:49], v[110:113], v[122:125], v[34:49]
	v_mfma_f32_32x32x16_bf16 v[50:65], v[110:113], v[126:129], v[50:65]
	s_waitcnt lgkmcnt(0)
	s_barrier
	ds_read_b128 v[98:101], v0
	ds_read_b128 v[102:105], v66 offset:18432
	ds_read_b128 v[110:113], v0 offset:32
	ds_read_b128 v[114:117], v66 offset:18464
	ds_read_b128 v[118:121], v0 offset:4608
	ds_read_b128 v[122:125], v0 offset:4640
	s_waitcnt lgkmcnt(4)
	v_mfma_f32_32x32x16_bf16 v[34:49], v[98:101], v[102:105], v[34:49]
	s_waitcnt lgkmcnt(1)
	v_mfma_f32_32x32x16_bf16 v[2:17], v[118:121], v[102:105], v[2:17]
	ds_read_b128 v[102:105], v66 offset:23040
	ds_read_b128 v[126:129], v66 offset:23072
	s_waitcnt lgkmcnt(1)
	v_mfma_f32_32x32x16_bf16 v[50:65], v[98:101], v[102:105], v[50:65]
	global_load_dwordx4 v[98:101], v72, s[0:1] offset:1536
	global_load_dwordx4 v[130:133], v72, s[36:37] offset:1536
	s_waitcnt vmcnt(9)
	ds_write_b128 v67, v[74:77] offset:36864
	s_waitcnt vmcnt(8)
	ds_write_b128 v67, v[134:137] offset:55296
	v_mfma_f32_32x32x16_bf16 v[18:33], v[118:121], v[102:105], v[18:33]
	global_load_dwordx4 v[74:77], v71, s[0:1] offset:1536
	global_load_dwordx4 v[102:105], v71, s[36:37] offset:1536
	v_mfma_f32_32x32x16_bf16 v[2:17], v[122:125], v[114:117], v[2:17]
	s_waitcnt lgkmcnt(2)
	v_mfma_f32_32x32x16_bf16 v[18:33], v[122:125], v[126:129], v[18:33]
	v_mfma_f32_32x32x16_bf16 v[34:49], v[110:113], v[114:117], v[34:49]
	v_mfma_f32_32x32x16_bf16 v[50:65], v[110:113], v[126:129], v[50:65]
	ds_read_b128 v[110:113], v0 offset:64
	ds_read_b128 v[114:117], v0 offset:4672
	ds_read_b128 v[118:121], v66 offset:18496
	ds_read_b128 v[134:137], v66 offset:23104
	s_waitcnt vmcnt(9)
	ds_write_b128 v67, v[78:81] offset:41472
	s_waitcnt vmcnt(8)
	ds_write_b128 v67, v[106:109] offset:59904
	global_load_dwordx4 v[78:81], v70, s[0:1] offset:1536
	global_load_dwordx4 v[106:109], v70, s[36:37] offset:1536
	s_waitcnt lgkmcnt(3)
	v_mfma_f32_32x32x16_bf16 v[2:17], v[114:117], v[118:121], v[2:17]
	s_waitcnt lgkmcnt(2)
	v_mfma_f32_32x32x16_bf16 v[18:33], v[114:117], v[134:137], v[18:33]
	v_mfma_f32_32x32x16_bf16 v[34:49], v[110:113], v[118:121], v[34:49]
	v_mfma_f32_32x32x16_bf16 v[50:65], v[110:113], v[134:137], v[50:65]
	ds_read_b128 v[110:113], v0 offset:96
	ds_read_b128 v[118:121], v0 offset:4704
	ds_read_b128 v[122:125], v66 offset:18528
	ds_read_b128 v[126:129], v66 offset:23136
	s_waitcnt vmcnt(9)
	ds_write_b128 v67, v[82:85] offset:46080
	s_waitcnt vmcnt(8)
	ds_write_b128 v67, v[90:93] offset:64512
	global_load_dwordx4 v[82:85], v69, s[0:1] offset:1536
	global_load_dwordx4 v[90:93], v69, s[36:37] offset:1536
	s_waitcnt lgkmcnt(3)
	v_mfma_f32_32x32x16_bf16 v[2:17], v[118:121], v[122:125], v[2:17]
	s_waitcnt vmcnt(9)
	ds_write_b128 v67, v[86:89] offset:50688
	s_waitcnt vmcnt(8)
	ds_write_b128 v68, v[94:97] offset:13824
	s_waitcnt lgkmcnt(4)
	v_mfma_f32_32x32x16_bf16 v[18:33], v[118:121], v[126:129], v[18:33]
	v_mfma_f32_32x32x16_bf16 v[34:49], v[110:113], v[122:125], v[34:49]
	v_mfma_f32_32x32x16_bf16 v[50:65], v[110:113], v[126:129], v[50:65]
	s_waitcnt lgkmcnt(0)
	s_barrier
; #define GL1_(RA, RB, i) { RA[i] = *(const u32x4*)(ap + (aoff + (i) * astep)); if ((i) < NB) RB[(i) < NB ? (i) : 0] = *(const u32x4*)(bp + (boff + (i) * bstep)); }
; #define LS1_(RA, RB, ST, i) { char* sn_ = lds + (ST) * STAGE; *(u32x4*)(sn_ + wofs + (i) * 32 * LROW) = RA[i]; \
;                               if ((i) < NB) *(u32x4*)(sn_ + STAGE_OP + wofs + (i) * 32 * LROW) = RB[(i) < NB ? (i) : 0]; }
; template <int NJ> DI void gemm_mainloop_reg(const bf16_t* __restrict__ A, int lda, const bf16_t* __restrict__ Bt, int ldb, int K, f32x16 (&acc)[2][NJ], char* lds) {
;     ...
; #pragma unroll
;   for (int i = 0; i < 4; ++i) GL1_(ra0, rb0, i);
;   ap += 128; bp += 128;
; #pragma unroll
;   for (int i = 0; i < 4; ++i) GL1_(ra1, rb1, i);
;   ap += 128; bp += 128;
; #pragma unroll
;   for (int i = 0; i < 4; ++i) LS1_(ra0, rb0, 0, i);
;   __syncthreads();
;   const int nk = K >> 6;
;   for (int kt = 0; kt < nk; kt += 2) {
;     const bool l0 = (kt + 2 < nk), l1 = (kt + 3 < nk);
;     STEP_(0, l0, ra0, rb0, true, ra1, rb1);
;     __syncthreads();
;     STEP_(1, l1, ra1, rb1, l0, ra0, rb0);
;     __syncthreads();
;   }
	ds_read_b128 v[86:89], v0 offset:36864
	ds_read_b128 v[94:97], v66 offset:55296
	ds_read_b128 v[110:113], v0 offset:36896
	ds_read_b128 v[114:117], v66 offset:55328
	ds_read_b128 v[118:121], v0 offset:41472
	ds_read_b128 v[122:125], v0 offset:41504
	s_waitcnt lgkmcnt(4)
	v_mfma_f32_32x32x16_bf16 v[34:49], v[86:89], v[94:97], v[34:49]
	s_waitcnt lgkmcnt(1)
	v_mfma_f32_32x32x16_bf16 v[2:17], v[118:121], v[94:97], v[2:17]
	ds_read_b128 v[94:97], v66 offset:59904
	ds_read_b128 v[126:129], v66 offset:59936
	s_waitcnt lgkmcnt(1)
	v_mfma_f32_32x32x16_bf16 v[50:65], v[86:89], v[94:97], v[50:65]
	global_load_dwordx4 v[86:89], v72, s[0:1] offset:1664
	global_load_dwordx4 v[134:137], v72, s[36:37] offset:1664
	s_waitcnt vmcnt(9)
	ds_write_b128 v67, v[98:101]
	s_waitcnt vmcnt(8)
	ds_write_b128 v67, v[130:133] offset:18432
	v_mfma_f32_32x32x16_bf16 v[18:33], v[118:121], v[94:97], v[18:33]
	global_load_dwordx4 v[94:97], v71, s[0:1] offset:1664
	global_load_dwordx4 v[98:101], v71, s[36:37] offset:1664
	v_mfma_f32_32x32x16_bf16 v[2:17], v[122:125], v[114:117], v[2:17]
	s_waitcnt lgkmcnt(2)
	v_mfma_f32_32x32x16_bf16 v[18:33], v[122:125], v[126:129], v[18:33]
	v_mfma_f32_32x32x16_bf16 v[34:49], v[110:113], v[114:117], v[34:49]
	v_mfma_f32_32x32x16_bf16 v[50:65], v[110:113], v[126:129], v[50:65]
	ds_read_b128 v[110:113], v0 offset:36928
	ds_read_b128 v[114:117], v0 offset:41536
	ds_read_b128 v[118:121], v66 offset:55360
	ds_read_b128 v[130:133], v66 offset:59968
	s_waitcnt vmcnt(9)
	ds_write_b128 v67, v[74:77] offset:4608
	s_waitcnt vmcnt(8)
	ds_write_b128 v67, v[102:105] offset:23040
	global_load_dwordx4 v[74:77], v70, s[0:1] offset:1664
	global_load_dwordx4 v[102:105], v70, s[36:37] offset:1664
	s_waitcnt lgkmcnt(3)
	v_mfma_f32_32x32x16_bf16 v[2:17], v[114:117], v[118:121], v[2:17]
	s_waitcnt lgkmcnt(2)
	v_mfma_f32_32x32x16_bf16 v[18:33], v[114:117], v[130:133], v[18:33]
	v_mfma_f32_32x32x16_bf16 v[34:49], v[110:113], v[118:121], v[34:49]
	v_mfma_f32_32x32x16_bf16 v[50:65], v[110:113], v[130:133], v[50:65]
	ds_read_b128 v[110:113], v0 offset:36960
	ds_read_b128 v[118:121], v0 offset:41568
	ds_read_b128 v[122:125], v66 offset:55392
	ds_read_b128 v[126:129], v66 offset:60000
	s_waitcnt vmcnt(9)
	ds_write_b128 v67, v[78:81] offset:9216
	s_waitcnt vmcnt(8)
	ds_write_b128 v67, v[106:109] offset:27648
	global_load_dwordx4 v[78:81], v69, s[0:1] offset:1664
	global_load_dwordx4 v[106:109], v69, s[36:37] offset:1664
	s_waitcnt lgkmcnt(3)
	v_mfma_f32_32x32x16_bf16 v[2:17], v[118:121], v[122:125], v[2:17]
	s_waitcnt vmcnt(9)
	ds_write_b128 v67, v[82:85] offset:13824
	s_waitcnt vmcnt(8)
	ds_write_b128 v67, v[90:93] offset:32256
	s_waitcnt lgkmcnt(4)
	v_mfma_f32_32x32x16_bf16 v[18:33], v[118:121], v[126:129], v[18:33]
	v_mfma_f32_32x32x16_bf16 v[34:49], v[110:113], v[122:125], v[34:49]
	v_mfma_f32_32x32x16_bf16 v[50:65], v[110:113], v[126:129], v[50:65]
	s_waitcnt lgkmcnt(0)
	s_barrier
	ds_read_b128 v[82:85], v0
	ds_read_b128 v[90:93], v66 offset:18432
	ds_read_b128 v[110:113], v0 offset:32
	ds_read_b128 v[114:117], v66 offset:18464
	ds_read_b128 v[118:121], v0 offset:4608
	ds_read_b128 v[122:125], v0 offset:4640
	s_waitcnt lgkmcnt(4)
	v_mfma_f32_32x32x16_bf16 v[34:49], v[82:85], v[90:93], v[34:49]
	s_waitcnt lgkmcnt(1)
	v_mfma_f32_32x32x16_bf16 v[2:17], v[118:121], v[90:93], v[2:17]
	ds_read_b128 v[90:93], v66 offset:23040
	ds_read_b128 v[126:129], v66 offset:23072
	s_waitcnt lgkmcnt(1)
	v_mfma_f32_32x32x16_bf16 v[50:65], v[82:85], v[90:93], v[50:65]
	global_load_dwordx4 v[82:85], v72, s[0:1] offset:1792
	global_load_dwordx4 v[130:133], v72, s[36:37] offset:1792
	s_waitcnt vmcnt(9)
	ds_write_b128 v67, v[86:89] offset:36864
	s_waitcnt vmcnt(8)
	ds_write_b128 v67, v[134:137] offset:55296
	v_mfma_f32_32x32x16_bf16 v[18:33], v[118:121], v[90:93], v[18:33]
	global_load_dwordx4 v[86:89], v71, s[0:1] offset:1792
	global_load_dwordx4 v[90:93], v71, s[36:37] offset:1792
	v_mfma_f32_32x32x16_bf16 v[2:17], v[122:125], v[114:117], v[2:17]
	s_waitcnt lgkmcnt(2)
	v_mfma_f32_32x32x16_bf16 v[18:33], v[122:125], v[126:129], v[18:33]
	v_mfma_f32_32x32x16_bf16 v[34:49], v[110:113], v[114:117], v[34:49]
	v_mfma_f32_32x32x16_bf16 v[50:65], v[110:113], v[126:129], v[50:65]
	ds_read_b128 v[110:113], v0 offset:64
	ds_read_b128 v[114:117], v0 offset:4672
	ds_read_b128 v[118:121], v66 offset:18496
	ds_read_b128 v[134:137], v66 offset:23104
	s_waitcnt vmcnt(9)
	ds_write_b128 v67, v[94:97] offset:41472
	s_waitcnt vmcnt(8)
	ds_write_b128 v67, v[98:101] offset:59904
	global_load_dwordx4 v[94:97], v70, s[0:1] offset:1792
	global_load_dwordx4 v[98:101], v70, s[36:37] offset:1792
	s_waitcnt lgkmcnt(3)
	v_mfma_f32_32x32x16_bf16 v[2:17], v[114:117], v[118:121], v[2:17]
	s_waitcnt lgkmcnt(2)
	v_mfma_f32_32x32x16_bf16 v[18:33], v[114:117], v[134:137], v[18:33]
	v_mfma_f32_32x32x16_bf16 v[34:49], v[110:113], v[118:121], v[34:49]
	v_mfma_f32_32x32x16_bf16 v[50:65], v[110:113], v[134:137], v[50:65]
	ds_read_b128 v[110:113], v0 offset:96
	ds_read_b128 v[118:121], v0 offset:4704
	ds_read_b128 v[122:125], v66 offset:18528
	ds_read_b128 v[126:129], v66 offset:23136
	s_waitcnt vmcnt(9)
	ds_write_b128 v67, v[74:77] offset:46080
	s_waitcnt vmcnt(8)
	ds_write_b128 v67, v[102:105] offset:64512
	global_load_dwordx4 v[74:77], v69, s[0:1] offset:1792
	global_load_dwordx4 v[102:105], v69, s[36:37] offset:1792
	s_waitcnt lgkmcnt(3)
	v_mfma_f32_32x32x16_bf16 v[2:17], v[118:121], v[122:125], v[2:17]
	s_waitcnt vmcnt(9)
	ds_write_b128 v67, v[78:81] offset:50688
	s_waitcnt vmcnt(8)
	ds_write_b128 v68, v[106:109] offset:13824
	s_waitcnt lgkmcnt(4)
	v_mfma_f32_32x32x16_bf16 v[18:33], v[118:121], v[126:129], v[18:33]
	v_mfma_f32_32x32x16_bf16 v[34:49], v[110:113], v[122:125], v[34:49]
	v_mfma_f32_32x32x16_bf16 v[50:65], v[110:113], v[126:129], v[50:65]
	s_waitcnt lgkmcnt(0)
	s_barrier
; #define GL1_(RA, RB, i) { RA[i] = *(const u32x4*)(ap + (aoff + (i) * astep)); if ((i) < NB) RB[(i) < NB ? (i) : 0] = *(const u32x4*)(bp + (boff + (i) * bstep)); }
; #define LS1_(RA, RB, ST, i) { char* sn_ = lds + (ST) * STAGE; *(u32x4*)(sn_ + wofs + (i) * 32 * LROW) = RA[i]; \
;                               if ((i) < NB) *(u32x4*)(sn_ + STAGE_OP + wofs + (i) * 32 * LROW) = RB[(i) < NB ? (i) : 0]; }
; template <int NJ> DI void gemm_mainloop_reg(const bf16_t* __restrict__ A, int lda, const bf16_t* __restrict__ Bt, int ldb, int K, f32x16 (&acc)[2][NJ], char* lds) {
;     ...
; #pragma unroll
;   for (int i = 0; i < 4; ++i) GL1_(ra0, rb0, i);
;   ap += 128; bp += 128;
; #pragma unroll
;   for (int i = 0; i < 4; ++i) GL1_(ra1, rb1, i);
;   ap += 128; bp += 128;
; #pragma unroll
;   for (int i = 0; i < 4; ++i) LS1_(ra0, rb0, 0, i);
;   __syncthreads();
;   const int nk = K >> 6;
;   for (int kt = 0; kt < nk; kt += 2) {
;     const bool l0 = (kt + 2 < nk), l1 = (kt + 3 < nk);
;     STEP_(0, l0, ra0, rb0, true, ra1, rb1);
;     __syncthreads();
;     STEP_(1, l1, ra1, rb1, l0, ra0, rb0);
;     __syncthreads();
;   }
	ds_read_b128 v[78:81], v0 offset:36864
	ds_read_b128 v[106:109], v66 offset:55296
	ds_read_b128 v[110:113], v0 offset:36896
	ds_read_b128 v[114:117], v66 offset:55328
	ds_read_b128 v[118:121], v0 offset:41472
	ds_read_b128 v[122:125], v0 offset:41504
	s_waitcnt lgkmcnt(4)
	v_mfma_f32_32x32x16_bf16 v[34:49], v[78:81], v[106:109], v[34:49]
	s_waitcnt lgkmcnt(1)
	v_mfma_f32_32x32x16_bf16 v[2:17], v[118:121], v[106:109], v[2:17]
	ds_read_b128 v[106:109], v66 offset:59904
	ds_read_b128 v[126:129], v66 offset:59936
	s_waitcnt lgkmcnt(1)
	v_mfma_f32_32x32x16_bf16 v[50:65], v[78:81], v[106:109], v[50:65]
	global_load_dwordx4 v[78:81], v72, s[0:1] offset:1920
	global_load_dwordx4 v[134:137], v72, s[36:37] offset:1920
	s_waitcnt vmcnt(9)
	ds_write_b128 v67, v[82:85]
	s_waitcnt vmcnt(8)
	ds_write_b128 v67, v[130:133] offset:18432
	v_mfma_f32_32x32x16_bf16 v[18:33], v[118:121], v[106:109], v[18:33]
	global_load_dwordx4 v[82:85], v71, s[0:1] offset:1920
	global_load_dwordx4 v[106:109], v71, s[36:37] offset:1920
	v_mfma_f32_32x32x16_bf16 v[2:17], v[122:125], v[114:117], v[2:17]
	s_waitcnt lgkmcnt(2)
	v_mfma_f32_32x32x16_bf16 v[18:33], v[122:125], v[126:129], v[18:33]
	v_mfma_f32_32x32x16_bf16 v[34:49], v[110:113], v[114:117], v[34:49]
	v_mfma_f32_32x32x16_bf16 v[50:65], v[110:113], v[126:129], v[50:65]
	ds_read_b128 v[110:113], v0 offset:36928
	ds_read_b128 v[114:117], v0 offset:41536
	ds_read_b128 v[118:121], v66 offset:55360
	ds_read_b128 v[130:133], v66 offset:59968
	s_waitcnt vmcnt(9)
	ds_write_b128 v67, v[86:89] offset:4608
	s_waitcnt vmcnt(8)
	ds_write_b128 v67, v[90:93] offset:23040
	global_load_dwordx4 v[86:89], v70, s[0:1] offset:1920
	global_load_dwordx4 v[90:93], v70, s[36:37] offset:1920
	s_waitcnt lgkmcnt(3)
	v_mfma_f32_32x32x16_bf16 v[2:17], v[114:117], v[118:121], v[2:17]
	s_waitcnt lgkmcnt(2)
	v_mfma_f32_32x32x16_bf16 v[18:33], v[114:117], v[130:133], v[18:33]
	v_mfma_f32_32x32x16_bf16 v[34:49], v[110:113], v[118:121], v[34:49]
	v_mfma_f32_32x32x16_bf16 v[50:65], v[110:113], v[130:133], v[50:65]
	ds_read_b128 v[110:113], v0 offset:36960
	ds_read_b128 v[118:121], v0 offset:41568
	ds_read_b128 v[122:125], v66 offset:55392
	ds_read_b128 v[126:129], v66 offset:60000
	s_waitcnt vmcnt(9)
	ds_write_b128 v67, v[94:97] offset:9216
	s_waitcnt vmcnt(8)
	ds_write_b128 v67, v[98:101] offset:27648
	global_load_dwordx4 v[94:97], v69, s[0:1] offset:1920
	global_load_dwordx4 v[98:101], v69, s[36:37] offset:1920
	s_waitcnt lgkmcnt(3)
	v_mfma_f32_32x32x16_bf16 v[2:17], v[118:121], v[122:125], v[2:17]
	s_waitcnt vmcnt(9)
	ds_write_b128 v67, v[74:77] offset:13824
	s_waitcnt vmcnt(8)
	ds_write_b128 v67, v[102:105] offset:32256
	s_waitcnt lgkmcnt(4)
	v_mfma_f32_32x32x16_bf16 v[18:33], v[118:121], v[126:129], v[18:33]
	v_mfma_f32_32x32x16_bf16 v[34:49], v[110:113], v[122:125], v[34:49]
	v_mfma_f32_32x32x16_bf16 v[50:65], v[110:113], v[126:129], v[50:65]
	s_waitcnt lgkmcnt(0)
	s_barrier
	ds_read_b128 v[74:77], v0
	ds_read_b128 v[102:105], v66 offset:18432
	ds_read_b128 v[110:113], v0 offset:32
	ds_read_b128 v[114:117], v66 offset:18464
	ds_read_b128 v[118:121], v0 offset:4608
	ds_read_b128 v[122:125], v0 offset:4640
	s_waitcnt lgkmcnt(4)
	v_mfma_f32_32x32x16_bf16 v[34:49], v[74:77], v[102:105], v[34:49]
	s_waitcnt lgkmcnt(1)
	v_mfma_f32_32x32x16_bf16 v[2:17], v[118:121], v[102:105], v[2:17]
	ds_read_b128 v[102:105], v66 offset:23040
	ds_read_b128 v[126:129], v66 offset:23072
	s_waitcnt lgkmcnt(1)
	v_mfma_f32_32x32x16_bf16 v[50:65], v[74:77], v[102:105], v[50:65]
	global_load_dwordx4 v[74:77], v72, s[0:1] offset:2048
	global_load_dwordx4 v[130:133], v72, s[36:37] offset:2048
	s_waitcnt vmcnt(9)
	ds_write_b128 v67, v[78:81] offset:36864
	s_waitcnt vmcnt(8)
	ds_write_b128 v67, v[134:137] offset:55296
	v_mfma_f32_32x32x16_bf16 v[18:33], v[118:121], v[102:105], v[18:33]
	global_load_dwordx4 v[78:81], v71, s[0:1] offset:2048
	global_load_dwordx4 v[102:105], v71, s[36:37] offset:2048
	v_mfma_f32_32x32x16_bf16 v[2:17], v[122:125], v[114:117], v[2:17]
	s_waitcnt lgkmcnt(2)
	v_mfma_f32_32x32x16_bf16 v[18:33], v[122:125], v[126:129], v[18:33]
	v_mfma_f32_32x32x16_bf16 v[34:49], v[110:113], v[114:117], v[34:49]
	v_mfma_f32_32x32x16_bf16 v[50:65], v[110:113], v[126:129], v[50:65]
	ds_read_b128 v[110:113], v0 offset:64
	ds_read_b128 v[114:117], v0 offset:4672
	ds_read_b128 v[118:121], v66 offset:18496
	ds_read_b128 v[134:137], v66 offset:23104
	s_waitcnt vmcnt(9)
	ds_write_b128 v67, v[82:85] offset:41472
	s_waitcnt vmcnt(8)
	ds_write_b128 v67, v[106:109] offset:59904
	global_load_dwordx4 v[82:85], v70, s[0:1] offset:2048
	global_load_dwordx4 v[106:109], v70, s[36:37] offset:2048
	s_waitcnt lgkmcnt(3)
	v_mfma_f32_32x32x16_bf16 v[2:17], v[114:117], v[118:121], v[2:17]
	s_waitcnt lgkmcnt(2)
	v_mfma_f32_32x32x16_bf16 v[18:33], v[114:117], v[134:137], v[18:33]
	v_mfma_f32_32x32x16_bf16 v[34:49], v[110:113], v[118:121], v[34:49]
	v_mfma_f32_32x32x16_bf16 v[50:65], v[110:113], v[134:137], v[50:65]
	ds_read_b128 v[110:113], v0 offset:96
	ds_read_b128 v[118:121], v0 offset:4704
	ds_read_b128 v[122:125], v66 offset:18528
	ds_read_b128 v[126:129], v66 offset:23136
	s_waitcnt vmcnt(9)
	ds_write_b128 v67, v[86:89] offset:46080
	s_waitcnt vmcnt(8)
	ds_write_b128 v67, v[90:93] offset:64512
	global_load_dwordx4 v[86:89], v69, s[0:1] offset:2048
	global_load_dwordx4 v[90:93], v69, s[36:37] offset:2048
	s_waitcnt lgkmcnt(3)
	v_mfma_f32_32x32x16_bf16 v[2:17], v[118:121], v[122:125], v[2:17]
	s_waitcnt vmcnt(9)
	ds_write_b128 v67, v[94:97] offset:50688
	s_waitcnt vmcnt(8)
	ds_write_b128 v68, v[98:101] offset:13824
	s_waitcnt lgkmcnt(4)
	v_mfma_f32_32x32x16_bf16 v[18:33], v[118:121], v[126:129], v[18:33]
	v_mfma_f32_32x32x16_bf16 v[34:49], v[110:113], v[122:125], v[34:49]
	v_mfma_f32_32x32x16_bf16 v[50:65], v[110:113], v[126:129], v[50:65]
	s_waitcnt lgkmcnt(0)
	s_barrier
; #define GL1_(RA, RB, i) { RA[i] = *(const u32x4*)(ap + (aoff + (i) * astep)); if ((i) < NB) RB[(i) < NB ? (i) : 0] = *(const u32x4*)(bp + (boff + (i) * bstep)); }
; #define LS1_(RA, RB, ST, i) { char* sn_ = lds + (ST) * STAGE; *(u32x4*)(sn_ + wofs + (i) * 32 * LROW) = RA[i]; \
;                               if ((i) < NB) *(u32x4*)(sn_ + STAGE_OP + wofs + (i) * 32 * LROW) = RB[(i) < NB ? (i) : 0]; }
; template <int NJ> DI void gemm_mainloop_reg(const bf16_t* __restrict__ A, int lda, const bf16_t* __restrict__ Bt, int ldb, int K, f32x16 (&acc)[2][NJ], char* lds) {
;     ...
; #pragma unroll
;   for (int i = 0; i < 4; ++i) GL1_(ra0, rb0, i);
;   ap += 128; bp += 128;
; #pragma unroll
;   for (int i = 0; i < 4; ++i) GL1_(ra1, rb1, i);
;   ap += 128; bp += 128;
; #pragma unroll
;   for (int i = 0; i < 4; ++i) LS1_(ra0, rb0, 0, i);
;   __syncthreads();
;   const int nk = K >> 6;
;   for (int kt = 0; kt < nk; kt += 2) {
;     const bool l0 = (kt + 2 < nk), l1 = (kt + 3 < nk);
;     STEP_(0, l0, ra0, rb0, true, ra1, rb1);
;     __syncthreads();
;     STEP_(1, l1, ra1, rb1, l0, ra0, rb0);
;     __syncthreads();
;   }
	ds_read_b128 v[94:97], v0 offset:36864
	ds_read_b128 v[98:101], v66 offset:55296
	ds_read_b128 v[110:113], v0 offset:36896
	ds_read_b128 v[114:117], v66 offset:55328
	ds_read_b128 v[118:121], v0 offset:41472
	ds_read_b128 v[122:125], v0 offset:41504
	s_waitcnt lgkmcnt(4)
	v_mfma_f32_32x32x16_bf16 v[34:49], v[94:97], v[98:101], v[34:49]
	s_waitcnt lgkmcnt(1)
	v_mfma_f32_32x32x16_bf16 v[2:17], v[118:121], v[98:101], v[2:17]
	ds_read_b128 v[98:101], v66 offset:59904
	ds_read_b128 v[126:129], v66 offset:59936
	s_waitcnt lgkmcnt(1)
	v_mfma_f32_32x32x16_bf16 v[50:65], v[94:97], v[98:101], v[50:65]
	global_load_dwordx4 v[94:97], v72, s[0:1] offset:2176
	global_load_dwordx4 v[134:137], v72, s[36:37] offset:2176
	s_waitcnt vmcnt(9)
	ds_write_b128 v67, v[74:77]
	s_waitcnt vmcnt(8)
	ds_write_b128 v67, v[130:133] offset:18432
	v_mfma_f32_32x32x16_bf16 v[18:33], v[118:121], v[98:101], v[18:33]
	global_load_dwordx4 v[74:77], v71, s[0:1] offset:2176
	global_load_dwordx4 v[98:101], v71, s[36:37] offset:2176
	v_mfma_f32_32x32x16_bf16 v[2:17], v[122:125], v[114:117], v[2:17]
	s_waitcnt lgkmcnt(2)
	v_mfma_f32_32x32x16_bf16 v[18:33], v[122:125], v[126:129], v[18:33]
	v_mfma_f32_32x32x16_bf16 v[34:49], v[110:113], v[114:117], v[34:49]
	v_mfma_f32_32x32x16_bf16 v[50:65], v[110:113], v[126:129], v[50:65]
	ds_read_b128 v[110:113], v0 offset:36928
	ds_read_b128 v[114:117], v0 offset:41536
	ds_read_b128 v[118:121], v66 offset:55360
	ds_read_b128 v[130:133], v66 offset:59968
	s_waitcnt vmcnt(9)
	ds_write_b128 v67, v[78:81] offset:4608
	s_waitcnt vmcnt(8)
	ds_write_b128 v67, v[102:105] offset:23040
	global_load_dwordx4 v[78:81], v70, s[0:1] offset:2176
	global_load_dwordx4 v[102:105], v70, s[36:37] offset:2176
	s_waitcnt lgkmcnt(3)
	v_mfma_f32_32x32x16_bf16 v[2:17], v[114:117], v[118:121], v[2:17]
	s_waitcnt lgkmcnt(2)
	v_mfma_f32_32x32x16_bf16 v[18:33], v[114:117], v[130:133], v[18:33]
	v_mfma_f32_32x32x16_bf16 v[34:49], v[110:113], v[118:121], v[34:49]
	v_mfma_f32_32x32x16_bf16 v[50:65], v[110:113], v[130:133], v[50:65]
	ds_read_b128 v[110:113], v0 offset:36960
	ds_read_b128 v[118:121], v0 offset:41568
	ds_read_b128 v[122:125], v66 offset:55392
	ds_read_b128 v[126:129], v66 offset:60000
	s_waitcnt vmcnt(9)
	ds_write_b128 v67, v[82:85] offset:9216
	s_waitcnt vmcnt(8)
	ds_write_b128 v67, v[106:109] offset:27648
	global_load_dwordx4 v[82:85], v69, s[0:1] offset:2176
	global_load_dwordx4 v[106:109], v69, s[36:37] offset:2176
	s_waitcnt lgkmcnt(3)
	v_mfma_f32_32x32x16_bf16 v[2:17], v[118:121], v[122:125], v[2:17]
	s_waitcnt vmcnt(9)
	ds_write_b128 v67, v[86:89] offset:13824
	s_waitcnt vmcnt(8)
	ds_write_b128 v67, v[90:93] offset:32256
	s_waitcnt lgkmcnt(4)
	v_mfma_f32_32x32x16_bf16 v[18:33], v[118:121], v[126:129], v[18:33]
	v_mfma_f32_32x32x16_bf16 v[34:49], v[110:113], v[122:125], v[34:49]
	v_mfma_f32_32x32x16_bf16 v[50:65], v[110:113], v[126:129], v[50:65]
	s_waitcnt lgkmcnt(0)
	s_barrier
	ds_read_b128 v[86:89], v0
	ds_read_b128 v[90:93], v66 offset:18432
	ds_read_b128 v[110:113], v0 offset:32
	ds_read_b128 v[114:117], v66 offset:18464
	ds_read_b128 v[118:121], v0 offset:4608
	ds_read_b128 v[122:125], v0 offset:4640
	s_waitcnt lgkmcnt(4)
	v_mfma_f32_32x32x16_bf16 v[34:49], v[86:89], v[90:93], v[34:49]
	s_waitcnt lgkmcnt(1)
	v_mfma_f32_32x32x16_bf16 v[2:17], v[118:121], v[90:93], v[2:17]
	ds_read_b128 v[90:93], v66 offset:23040
	ds_read_b128 v[126:129], v66 offset:23072
	s_waitcnt lgkmcnt(1)
	v_mfma_f32_32x32x16_bf16 v[50:65], v[86:89], v[90:93], v[50:65]
	global_load_dwordx4 v[86:89], v72, s[0:1] offset:2304
	global_load_dwordx4 v[130:133], v72, s[36:37] offset:2304
	s_waitcnt vmcnt(9)
	ds_write_b128 v67, v[94:97] offset:36864
	s_waitcnt vmcnt(8)
	ds_write_b128 v67, v[134:137] offset:55296
	v_mfma_f32_32x32x16_bf16 v[18:33], v[118:121], v[90:93], v[18:33]
	global_load_dwordx4 v[90:93], v71, s[0:1] offset:2304
	global_load_dwordx4 v[94:97], v71, s[36:37] offset:2304
	v_mfma_f32_32x32x16_bf16 v[2:17], v[122:125], v[114:117], v[2:17]
	s_waitcnt lgkmcnt(2)
	v_mfma_f32_32x32x16_bf16 v[18:33], v[122:125], v[126:129], v[18:33]
	v_mfma_f32_32x32x16_bf16 v[34:49], v[110:113], v[114:117], v[34:49]
	v_mfma_f32_32x32x16_bf16 v[50:65], v[110:113], v[126:129], v[50:65]
	ds_read_b128 v[110:113], v0 offset:64
	ds_read_b128 v[114:117], v0 offset:4672
	ds_read_b128 v[118:121], v66 offset:18496
	ds_read_b128 v[134:137], v66 offset:23104
	s_waitcnt vmcnt(9)
	ds_write_b128 v67, v[74:77] offset:41472
	s_waitcnt vmcnt(8)
	ds_write_b128 v67, v[98:101] offset:59904
	global_load_dwordx4 v[74:77], v70, s[0:1] offset:2304
	global_load_dwordx4 v[98:101], v70, s[36:37] offset:2304
	s_waitcnt lgkmcnt(3)
	v_mfma_f32_32x32x16_bf16 v[2:17], v[114:117], v[118:121], v[2:17]
	s_waitcnt lgkmcnt(2)
	v_mfma_f32_32x32x16_bf16 v[18:33], v[114:117], v[134:137], v[18:33]
	v_mfma_f32_32x32x16_bf16 v[34:49], v[110:113], v[118:121], v[34:49]
	v_mfma_f32_32x32x16_bf16 v[50:65], v[110:113], v[134:137], v[50:65]
	ds_read_b128 v[110:113], v0 offset:96
	ds_read_b128 v[118:121], v0 offset:4704
	ds_read_b128 v[122:125], v66 offset:18528
	ds_read_b128 v[126:129], v66 offset:23136
	s_waitcnt vmcnt(9)
	ds_write_b128 v67, v[78:81] offset:46080
	s_waitcnt vmcnt(8)
	ds_write_b128 v67, v[102:105] offset:64512
	global_load_dwordx4 v[78:81], v69, s[0:1] offset:2304
	global_load_dwordx4 v[102:105], v69, s[36:37] offset:2304
	s_waitcnt lgkmcnt(3)
	v_mfma_f32_32x32x16_bf16 v[2:17], v[118:121], v[122:125], v[2:17]
	s_waitcnt vmcnt(9)
	ds_write_b128 v67, v[82:85] offset:50688
	s_waitcnt vmcnt(8)
	ds_write_b128 v68, v[106:109] offset:13824
	s_waitcnt lgkmcnt(4)
	v_mfma_f32_32x32x16_bf16 v[18:33], v[118:121], v[126:129], v[18:33]
	v_mfma_f32_32x32x16_bf16 v[34:49], v[110:113], v[122:125], v[34:49]
	v_mfma_f32_32x32x16_bf16 v[50:65], v[110:113], v[126:129], v[50:65]
	s_waitcnt lgkmcnt(0)
	s_barrier
; #define GL1_(RA, RB, i) { RA[i] = *(const u32x4*)(ap + (aoff + (i) * astep)); if ((i) < NB) RB[(i) < NB ? (i) : 0] = *(const u32x4*)(bp + (boff + (i) * bstep)); }
; #define LS1_(RA, RB, ST, i) { char* sn_ = lds + (ST) * STAGE; *(u32x4*)(sn_ + wofs + (i) * 32 * LROW) = RA[i]; \
;                               if ((i) < NB) *(u32x4*)(sn_ + STAGE_OP + wofs + (i) * 32 * LROW) = RB[(i) < NB ? (i) : 0]; }
; template <int NJ> DI void gemm_mainloop_reg(const bf16_t* __restrict__ A, int lda, const bf16_t* __restrict__ Bt, int ldb, int K, f32x16 (&acc)[2][NJ], char* lds) {
;     ...
; #pragma unroll
;   for (int i = 0; i < 4; ++i) GL1_(ra0, rb0, i);
;   ap += 128; bp += 128;
; #pragma unroll
;   for (int i = 0; i < 4; ++i) GL1_(ra1, rb1, i);
;   ap += 128; bp += 128;
; #pragma unroll
;   for (int i = 0; i < 4; ++i) LS1_(ra0, rb0, 0, i);
;   __syncthreads();
;   const int nk = K >> 6;
;   for (int kt = 0; kt < nk; kt += 2) {
;     const bool l0 = (kt + 2 < nk), l1 = (kt + 3 < nk);
;     STEP_(0, l0, ra0, rb0, true, ra1, rb1);
;     __syncthreads();
;     STEP_(1, l1, ra1, rb1, l0, ra0, rb0);
;     __syncthreads();
;   }
	ds_read_b128 v[82:85], v0 offset:36864
	ds_read_b128 v[106:109], v66 offset:55296
	ds_read_b128 v[110:113], v0 offset:36896
	ds_read_b128 v[114:117], v66 offset:55328
	ds_read_b128 v[118:121], v0 offset:41472
	ds_read_b128 v[122:125], v0 offset:41504
	s_waitcnt lgkmcnt(4)
	v_mfma_f32_32x32x16_bf16 v[34:49], v[82:85], v[106:109], v[34:49]
	s_waitcnt lgkmcnt(1)
	v_mfma_f32_32x32x16_bf16 v[2:17], v[118:121], v[106:109], v[2:17]
	ds_read_b128 v[106:109], v66 offset:59904
	ds_read_b128 v[126:129], v66 offset:59936
	s_waitcnt lgkmcnt(1)
	v_mfma_f32_32x32x16_bf16 v[50:65], v[82:85], v[106:109], v[50:65]
	global_load_dwordx4 v[82:85], v72, s[0:1] offset:2432
	global_load_dwordx4 v[134:137], v72, s[36:37] offset:2432
	s_waitcnt vmcnt(9)
	ds_write_b128 v67, v[86:89]
	s_waitcnt vmcnt(8)
	ds_write_b128 v67, v[130:133] offset:18432
	v_mfma_f32_32x32x16_bf16 v[18:33], v[118:121], v[106:109], v[18:33]
	global_load_dwordx4 v[86:89], v71, s[0:1] offset:2432
	global_load_dwordx4 v[106:109], v71, s[36:37] offset:2432
	v_mfma_f32_32x32x16_bf16 v[2:17], v[122:125], v[114:117], v[2:17]
	s_waitcnt lgkmcnt(2)
	v_mfma_f32_32x32x16_bf16 v[18:33], v[122:125], v[126:129], v[18:33]
	v_mfma_f32_32x32x16_bf16 v[34:49], v[110:113], v[114:117], v[34:49]
	v_mfma_f32_32x32x16_bf16 v[50:65], v[110:113], v[126:129], v[50:65]
	ds_read_b128 v[110:113], v0 offset:36928
	ds_read_b128 v[114:117], v0 offset:41536
	ds_read_b128 v[118:121], v66 offset:55360
	ds_read_b128 v[130:133], v66 offset:59968
	s_waitcnt vmcnt(9)
	ds_write_b128 v67, v[90:93] offset:4608
	s_waitcnt vmcnt(8)
	ds_write_b128 v67, v[94:97] offset:23040
	global_load_dwordx4 v[90:93], v70, s[0:1] offset:2432
	global_load_dwordx4 v[94:97], v70, s[36:37] offset:2432
	s_waitcnt lgkmcnt(3)
	v_mfma_f32_32x32x16_bf16 v[2:17], v[114:117], v[118:121], v[2:17]
	s_waitcnt lgkmcnt(2)
	v_mfma_f32_32x32x16_bf16 v[18:33], v[114:117], v[130:133], v[18:33]
	v_mfma_f32_32x32x16_bf16 v[34:49], v[110:113], v[118:121], v[34:49]
	v_mfma_f32_32x32x16_bf16 v[50:65], v[110:113], v[130:133], v[50:65]
	ds_read_b128 v[110:113], v0 offset:36960
	ds_read_b128 v[118:121], v0 offset:41568
	ds_read_b128 v[122:125], v66 offset:55392
	ds_read_b128 v[126:129], v66 offset:60000
	s_waitcnt vmcnt(9)
	ds_write_b128 v67, v[74:77] offset:9216
	s_waitcnt vmcnt(8)
	ds_write_b128 v67, v[98:101] offset:27648
	global_load_dwordx4 v[74:77], v69, s[0:1] offset:2432
	global_load_dwordx4 v[98:101], v69, s[36:37] offset:2432
	s_waitcnt lgkmcnt(3)
	v_mfma_f32_32x32x16_bf16 v[2:17], v[118:121], v[122:125], v[2:17]
	s_waitcnt vmcnt(9)
	ds_write_b128 v67, v[78:81] offset:13824
	s_waitcnt vmcnt(8)
	ds_write_b128 v67, v[102:105] offset:32256
	s_waitcnt lgkmcnt(4)
	v_mfma_f32_32x32x16_bf16 v[18:33], v[118:121], v[126:129], v[18:33]
	v_mfma_f32_32x32x16_bf16 v[34:49], v[110:113], v[122:125], v[34:49]
	v_mfma_f32_32x32x16_bf16 v[50:65], v[110:113], v[126:129], v[50:65]
	s_waitcnt lgkmcnt(0)
	s_barrier
	ds_read_b128 v[78:81], v0
	ds_read_b128 v[102:105], v66 offset:18432
	ds_read_b128 v[110:113], v0 offset:32
	ds_read_b128 v[114:117], v66 offset:18464
	ds_read_b128 v[118:121], v0 offset:4608
	ds_read_b128 v[122:125], v0 offset:4640
	s_waitcnt lgkmcnt(4)
	v_mfma_f32_32x32x16_bf16 v[34:49], v[78:81], v[102:105], v[34:49]
	s_waitcnt lgkmcnt(1)
	v_mfma_f32_32x32x16_bf16 v[2:17], v[118:121], v[102:105], v[2:17]
	ds_read_b128 v[102:105], v66 offset:23040
	ds_read_b128 v[126:129], v66 offset:23072
	s_waitcnt lgkmcnt(1)
	v_mfma_f32_32x32x16_bf16 v[50:65], v[78:81], v[102:105], v[50:65]
	global_load_dwordx4 v[78:81], v72, s[0:1] offset:2560
	global_load_dwordx4 v[130:133], v72, s[36:37] offset:2560
	s_waitcnt vmcnt(9)
	ds_write_b128 v67, v[82:85] offset:36864
	s_waitcnt vmcnt(8)
	ds_write_b128 v67, v[134:137] offset:55296
	v_mfma_f32_32x32x16_bf16 v[18:33], v[118:121], v[102:105], v[18:33]
	global_load_dwordx4 v[82:85], v71, s[0:1] offset:2560
	global_load_dwordx4 v[102:105], v71, s[36:37] offset:2560
	v_mfma_f32_32x32x16_bf16 v[2:17], v[122:125], v[114:117], v[2:17]
	s_waitcnt lgkmcnt(2)
	v_mfma_f32_32x32x16_bf16 v[18:33], v[122:125], v[126:129], v[18:33]
	v_mfma_f32_32x32x16_bf16 v[34:49], v[110:113], v[114:117], v[34:49]
	v_mfma_f32_32x32x16_bf16 v[50:65], v[110:113], v[126:129], v[50:65]
	ds_read_b128 v[110:113], v0 offset:64
	ds_read_b128 v[114:117], v0 offset:4672
	ds_read_b128 v[118:121], v66 offset:18496
	ds_read_b128 v[134:137], v66 offset:23104
	s_waitcnt vmcnt(9)
	ds_write_b128 v67, v[86:89] offset:41472
	s_waitcnt vmcnt(8)
	ds_write_b128 v67, v[106:109] offset:59904
	global_load_dwordx4 v[86:89], v70, s[0:1] offset:2560
	global_load_dwordx4 v[106:109], v70, s[36:37] offset:2560
	s_waitcnt lgkmcnt(3)
	v_mfma_f32_32x32x16_bf16 v[2:17], v[114:117], v[118:121], v[2:17]
	s_waitcnt lgkmcnt(2)
	v_mfma_f32_32x32x16_bf16 v[18:33], v[114:117], v[134:137], v[18:33]
	v_mfma_f32_32x32x16_bf16 v[34:49], v[110:113], v[118:121], v[34:49]
	v_mfma_f32_32x32x16_bf16 v[50:65], v[110:113], v[134:137], v[50:65]
	ds_read_b128 v[110:113], v0 offset:96
	ds_read_b128 v[118:121], v0 offset:4704
	ds_read_b128 v[122:125], v66 offset:18528
	ds_read_b128 v[126:129], v66 offset:23136
	s_waitcnt vmcnt(9)
	ds_write_b128 v67, v[90:93] offset:46080
	s_waitcnt vmcnt(8)
	ds_write_b128 v67, v[94:97] offset:64512
	global_load_dwordx4 v[90:93], v69, s[0:1] offset:2560
	global_load_dwordx4 v[94:97], v69, s[36:37] offset:2560
	s_waitcnt lgkmcnt(3)
	v_mfma_f32_32x32x16_bf16 v[2:17], v[118:121], v[122:125], v[2:17]
	s_waitcnt vmcnt(9)
	ds_write_b128 v67, v[74:77] offset:50688
	s_waitcnt vmcnt(8)
	ds_write_b128 v68, v[98:101] offset:13824
	s_waitcnt lgkmcnt(4)
	v_mfma_f32_32x32x16_bf16 v[18:33], v[118:121], v[126:129], v[18:33]
	v_mfma_f32_32x32x16_bf16 v[34:49], v[110:113], v[122:125], v[34:49]
	v_mfma_f32_32x32x16_bf16 v[50:65], v[110:113], v[126:129], v[50:65]
	s_waitcnt lgkmcnt(0)
	s_barrier
; #define GL1_(RA, RB, i) { RA[i] = *(const u32x4*)(ap + (aoff + (i) * astep)); if ((i) < NB) RB[(i) < NB ? (i) : 0] = *(const u32x4*)(bp + (boff + (i) * bstep)); }
; #define LS1_(RA, RB, ST, i) { char* sn_ = lds + (ST) * STAGE; *(u32x4*)(sn_ + wofs + (i) * 32 * LROW) = RA[i]; \
;                               if ((i) < NB) *(u32x4*)(sn_ + STAGE_OP + wofs + (i) * 32 * LROW) = RB[(i) < NB ? (i) : 0]; }
; template <int NJ> DI void gemm_mainloop_reg(const bf16_t* __restrict__ A, int lda, const bf16_t* __restrict__ Bt, int ldb, int K, f32x16 (&acc)[2][NJ], char* lds) {
;     ...
; #pragma unroll
;   for (int i = 0; i < 4; ++i) GL1_(ra0, rb0, i);
;   ap += 128; bp += 128;
; #pragma unroll
;   for (int i = 0; i < 4; ++i) GL1_(ra1, rb1, i);
;   ap += 128; bp += 128;
; #pragma unroll
;   for (int i = 0; i < 4; ++i) LS1_(ra0, rb0, 0, i);
;   __syncthreads();
;   const int nk = K >> 6;
;   for (int kt = 0; kt < nk; kt += 2) {
;     const bool l0 = (kt + 2 < nk), l1 = (kt + 3 < nk);
;     STEP_(0, l0, ra0, rb0, true, ra1, rb1);
;     __syncthreads();
;     STEP_(1, l1, ra1, rb1, l0, ra0, rb0);
;     __syncthreads();
;   }
	ds_read_b128 v[74:77], v0 offset:36864
	ds_read_b128 v[98:101], v66 offset:55296
	ds_read_b128 v[110:113], v0 offset:36896
	ds_read_b128 v[114:117], v66 offset:55328
	ds_read_b128 v[118:121], v0 offset:41472
	ds_read_b128 v[122:125], v0 offset:41504
	s_waitcnt lgkmcnt(4)
	v_mfma_f32_32x32x16_bf16 v[34:49], v[74:77], v[98:101], v[34:49]
	s_waitcnt lgkmcnt(1)
	v_mfma_f32_32x32x16_bf16 v[2:17], v[118:121], v[98:101], v[2:17]
	ds_read_b128 v[98:101], v66 offset:59904
	ds_read_b128 v[126:129], v66 offset:59936
	s_waitcnt lgkmcnt(1)
	v_mfma_f32_32x32x16_bf16 v[50:65], v[74:77], v[98:101], v[50:65]
	global_load_dwordx4 v[74:77], v72, s[0:1] offset:2688
	global_load_dwordx4 v[134:137], v72, s[36:37] offset:2688
	s_waitcnt vmcnt(9)
	ds_write_b128 v67, v[78:81]
	s_waitcnt vmcnt(8)
	ds_write_b128 v67, v[130:133] offset:18432
	v_mfma_f32_32x32x16_bf16 v[18:33], v[118:121], v[98:101], v[18:33]
	global_load_dwordx4 v[78:81], v71, s[0:1] offset:2688
	global_load_dwordx4 v[98:101], v71, s[36:37] offset:2688
	v_mfma_f32_32x32x16_bf16 v[2:17], v[122:125], v[114:117], v[2:17]
	s_waitcnt lgkmcnt(2)
	v_mfma_f32_32x32x16_bf16 v[18:33], v[122:125], v[126:129], v[18:33]
	v_mfma_f32_32x32x16_bf16 v[34:49], v[110:113], v[114:117], v[34:49]
	v_mfma_f32_32x32x16_bf16 v[50:65], v[110:113], v[126:129], v[50:65]
	ds_read_b128 v[110:113], v0 offset:36928
	ds_read_b128 v[114:117], v0 offset:41536
	ds_read_b128 v[118:121], v66 offset:55360
	ds_read_b128 v[130:133], v66 offset:59968
	s_waitcnt vmcnt(9)
	ds_write_b128 v67, v[82:85] offset:4608
	s_waitcnt vmcnt(8)
	ds_write_b128 v67, v[102:105] offset:23040
	global_load_dwordx4 v[82:85], v70, s[0:1] offset:2688
	global_load_dwordx4 v[102:105], v70, s[36:37] offset:2688
	s_waitcnt lgkmcnt(3)
	v_mfma_f32_32x32x16_bf16 v[2:17], v[114:117], v[118:121], v[2:17]
	s_waitcnt lgkmcnt(2)
	v_mfma_f32_32x32x16_bf16 v[18:33], v[114:117], v[130:133], v[18:33]
	v_mfma_f32_32x32x16_bf16 v[34:49], v[110:113], v[118:121], v[34:49]
	v_mfma_f32_32x32x16_bf16 v[50:65], v[110:113], v[130:133], v[50:65]
	ds_read_b128 v[110:113], v0 offset:36960
	ds_read_b128 v[118:121], v0 offset:41568
	ds_read_b128 v[122:125], v66 offset:55392
	ds_read_b128 v[126:129], v66 offset:60000
	s_waitcnt vmcnt(9)
	ds_write_b128 v67, v[86:89] offset:9216
	s_waitcnt vmcnt(8)
	ds_write_b128 v67, v[106:109] offset:27648
	global_load_dwordx4 v[86:89], v69, s[0:1] offset:2688
	global_load_dwordx4 v[106:109], v69, s[36:37] offset:2688
	s_waitcnt lgkmcnt(3)
	v_mfma_f32_32x32x16_bf16 v[2:17], v[118:121], v[122:125], v[2:17]
	s_waitcnt vmcnt(9)
	ds_write_b128 v67, v[90:93] offset:13824
	s_waitcnt vmcnt(8)
	ds_write_b128 v67, v[94:97] offset:32256
	s_waitcnt lgkmcnt(4)
	v_mfma_f32_32x32x16_bf16 v[18:33], v[118:121], v[126:129], v[18:33]
	v_mfma_f32_32x32x16_bf16 v[34:49], v[110:113], v[122:125], v[34:49]
	v_mfma_f32_32x32x16_bf16 v[50:65], v[110:113], v[126:129], v[50:65]
	s_waitcnt lgkmcnt(0)
	s_barrier
	ds_read_b128 v[90:93], v0
	ds_read_b128 v[94:97], v66 offset:18432
	ds_read_b128 v[110:113], v0 offset:32
	ds_read_b128 v[114:117], v66 offset:18464
	ds_read_b128 v[118:121], v0 offset:4608
	ds_read_b128 v[122:125], v0 offset:4640
	s_waitcnt lgkmcnt(4)
	v_mfma_f32_32x32x16_bf16 v[34:49], v[90:93], v[94:97], v[34:49]
	s_waitcnt lgkmcnt(1)
	v_mfma_f32_32x32x16_bf16 v[2:17], v[118:121], v[94:97], v[2:17]
	ds_read_b128 v[94:97], v66 offset:23040
	ds_read_b128 v[126:129], v66 offset:23072
	s_waitcnt lgkmcnt(1)
	v_mfma_f32_32x32x16_bf16 v[50:65], v[90:93], v[94:97], v[50:65]
	global_load_dwordx4 v[90:93], v72, s[0:1] offset:2816
	global_load_dwordx4 v[130:133], v72, s[36:37] offset:2816
	s_waitcnt vmcnt(9)
	ds_write_b128 v67, v[74:77] offset:36864
	s_waitcnt vmcnt(8)
	ds_write_b128 v67, v[134:137] offset:55296
	v_mfma_f32_32x32x16_bf16 v[18:33], v[118:121], v[94:97], v[18:33]
	global_load_dwordx4 v[74:77], v71, s[0:1] offset:2816
	global_load_dwordx4 v[94:97], v71, s[36:37] offset:2816
	v_mfma_f32_32x32x16_bf16 v[2:17], v[122:125], v[114:117], v[2:17]
	s_waitcnt lgkmcnt(2)
	v_mfma_f32_32x32x16_bf16 v[18:33], v[122:125], v[126:129], v[18:33]
	v_mfma_f32_32x32x16_bf16 v[34:49], v[110:113], v[114:117], v[34:49]
	v_mfma_f32_32x32x16_bf16 v[50:65], v[110:113], v[126:129], v[50:65]
	ds_read_b128 v[110:113], v0 offset:64
	ds_read_b128 v[114:117], v0 offset:4672
	ds_read_b128 v[118:121], v66 offset:18496
	ds_read_b128 v[134:137], v66 offset:23104
	s_waitcnt vmcnt(9)
	ds_write_b128 v67, v[78:81] offset:41472
	s_waitcnt vmcnt(8)
	ds_write_b128 v67, v[98:101] offset:59904
	global_load_dwordx4 v[78:81], v70, s[0:1] offset:2816
	global_load_dwordx4 v[98:101], v70, s[36:37] offset:2816
	s_waitcnt lgkmcnt(3)
	v_mfma_f32_32x32x16_bf16 v[2:17], v[114:117], v[118:121], v[2:17]
	s_waitcnt lgkmcnt(2)
	v_mfma_f32_32x32x16_bf16 v[18:33], v[114:117], v[134:137], v[18:33]
	v_mfma_f32_32x32x16_bf16 v[34:49], v[110:113], v[118:121], v[34:49]
	v_mfma_f32_32x32x16_bf16 v[50:65], v[110:113], v[134:137], v[50:65]
	ds_read_b128 v[110:113], v0 offset:96
	ds_read_b128 v[118:121], v0 offset:4704
	ds_read_b128 v[122:125], v66 offset:18528
	ds_read_b128 v[126:129], v66 offset:23136
	s_waitcnt vmcnt(9)
	ds_write_b128 v67, v[82:85] offset:46080
	s_waitcnt vmcnt(8)
	ds_write_b128 v67, v[102:105] offset:64512
	global_load_dwordx4 v[82:85], v69, s[0:1] offset:2816
	global_load_dwordx4 v[102:105], v69, s[36:37] offset:2816
	s_waitcnt lgkmcnt(3)
	v_mfma_f32_32x32x16_bf16 v[2:17], v[118:121], v[122:125], v[2:17]
	s_waitcnt vmcnt(9)
	ds_write_b128 v67, v[86:89] offset:50688
	s_waitcnt vmcnt(8)
	ds_write_b128 v68, v[106:109] offset:13824
	s_waitcnt lgkmcnt(4)
	v_mfma_f32_32x32x16_bf16 v[18:33], v[118:121], v[126:129], v[18:33]
	v_mfma_f32_32x32x16_bf16 v[34:49], v[110:113], v[122:125], v[34:49]
	v_mfma_f32_32x32x16_bf16 v[50:65], v[110:113], v[126:129], v[50:65]
	s_waitcnt lgkmcnt(0)
	s_barrier
; #define GL1_(RA, RB, i) { RA[i] = *(const u32x4*)(ap + (aoff + (i) * astep)); if ((i) < NB) RB[(i) < NB ? (i) : 0] = *(const u32x4*)(bp + (boff + (i) * bstep)); }
; #define LS1_(RA, RB, ST, i) { char* sn_ = lds + (ST) * STAGE; *(u32x4*)(sn_ + wofs + (i) * 32 * LROW) = RA[i]; \
;                               if ((i) < NB) *(u32x4*)(sn_ + STAGE_OP + wofs + (i) * 32 * LROW) = RB[(i) < NB ? (i) : 0]; }
; template <int NJ> DI void gemm_mainloop_reg(const bf16_t* __restrict__ A, int lda, const bf16_t* __restrict__ Bt, int ldb, int K, f32x16 (&acc)[2][NJ], char* lds) {
;     ...
; #pragma unroll
;   for (int i = 0; i < 4; ++i) GL1_(ra0, rb0, i);
;   ap += 128; bp += 128;
; #pragma unroll
;   for (int i = 0; i < 4; ++i) GL1_(ra1, rb1, i);
;   ap += 128; bp += 128;
; #pragma unroll
;   for (int i = 0; i < 4; ++i) LS1_(ra0, rb0, 0, i);
;   __syncthreads();
;   const int nk = K >> 6;
;   for (int kt = 0; kt < nk; kt += 2) {
;     const bool l0 = (kt + 2 < nk), l1 = (kt + 3 < nk);
;     STEP_(0, l0, ra0, rb0, true, ra1, rb1);
;     __syncthreads();
;     STEP_(1, l1, ra1, rb1, l0, ra0, rb0);
;     __syncthreads();
;   }
	ds_read_b128 v[86:89], v0 offset:36864
	ds_read_b128 v[106:109], v66 offset:55296
	ds_read_b128 v[110:113], v0 offset:36896
	ds_read_b128 v[114:117], v66 offset:55328
	ds_read_b128 v[118:121], v0 offset:41472
	ds_read_b128 v[122:125], v0 offset:41504
	s_waitcnt lgkmcnt(4)
	v_mfma_f32_32x32x16_bf16 v[34:49], v[86:89], v[106:109], v[34:49]
	s_waitcnt lgkmcnt(1)
	v_mfma_f32_32x32x16_bf16 v[2:17], v[118:121], v[106:109], v[2:17]
	ds_read_b128 v[106:109], v66 offset:59904
	ds_read_b128 v[126:129], v66 offset:59936
	s_waitcnt lgkmcnt(1)
	v_mfma_f32_32x32x16_bf16 v[50:65], v[86:89], v[106:109], v[50:65]
	global_load_dwordx4 v[86:89], v72, s[0:1] offset:2944
	global_load_dwordx4 v[134:137], v72, s[36:37] offset:2944
	s_waitcnt vmcnt(9)
	ds_write_b128 v67, v[90:93]
	s_waitcnt vmcnt(8)
	ds_write_b128 v67, v[130:133] offset:18432
	v_mfma_f32_32x32x16_bf16 v[18:33], v[118:121], v[106:109], v[18:33]
	global_load_dwordx4 v[90:93], v71, s[0:1] offset:2944
	global_load_dwordx4 v[106:109], v71, s[36:37] offset:2944
	v_mfma_f32_32x32x16_bf16 v[2:17], v[122:125], v[114:117], v[2:17]
	s_waitcnt lgkmcnt(2)
	v_mfma_f32_32x32x16_bf16 v[18:33], v[122:125], v[126:129], v[18:33]
	v_mfma_f32_32x32x16_bf16 v[34:49], v[110:113], v[114:117], v[34:49]
	v_mfma_f32_32x32x16_bf16 v[50:65], v[110:113], v[126:129], v[50:65]
	ds_read_b128 v[110:113], v0 offset:36928
	ds_read_b128 v[114:117], v0 offset:41536
	ds_read_b128 v[118:121], v66 offset:55360
	ds_read_b128 v[130:133], v66 offset:59968
	s_waitcnt vmcnt(9)
	ds_write_b128 v67, v[74:77] offset:4608
	s_waitcnt vmcnt(8)
	ds_write_b128 v67, v[94:97] offset:23040
	global_load_dwordx4 v[74:77], v70, s[0:1] offset:2944
	global_load_dwordx4 v[94:97], v70, s[36:37] offset:2944
	s_waitcnt lgkmcnt(3)
	v_mfma_f32_32x32x16_bf16 v[2:17], v[114:117], v[118:121], v[2:17]
	s_waitcnt lgkmcnt(2)
	v_mfma_f32_32x32x16_bf16 v[18:33], v[114:117], v[130:133], v[18:33]
	v_mfma_f32_32x32x16_bf16 v[34:49], v[110:113], v[118:121], v[34:49]
	v_mfma_f32_32x32x16_bf16 v[50:65], v[110:113], v[130:133], v[50:65]
	ds_read_b128 v[110:113], v0 offset:36960
	ds_read_b128 v[118:121], v0 offset:41568
	ds_read_b128 v[122:125], v66 offset:55392
	ds_read_b128 v[126:129], v66 offset:60000
	s_waitcnt vmcnt(9)
	ds_write_b128 v67, v[78:81] offset:9216
	s_waitcnt vmcnt(8)
	ds_write_b128 v67, v[98:101] offset:27648
	global_load_dwordx4 v[78:81], v69, s[0:1] offset:2944
	global_load_dwordx4 v[98:101], v69, s[36:37] offset:2944
	s_waitcnt lgkmcnt(3)
	v_mfma_f32_32x32x16_bf16 v[2:17], v[118:121], v[122:125], v[2:17]
	s_waitcnt vmcnt(9)
	ds_write_b128 v67, v[82:85] offset:13824
	s_waitcnt vmcnt(8)
	ds_write_b128 v67, v[102:105] offset:32256
	s_waitcnt lgkmcnt(4)
	v_mfma_f32_32x32x16_bf16 v[18:33], v[118:121], v[126:129], v[18:33]
	v_mfma_f32_32x32x16_bf16 v[34:49], v[110:113], v[122:125], v[34:49]
	v_mfma_f32_32x32x16_bf16 v[50:65], v[110:113], v[126:129], v[50:65]
	s_waitcnt lgkmcnt(0)
	s_barrier
	ds_read_b128 v[82:85], v0
	ds_read_b128 v[102:105], v66 offset:18432
	ds_read_b128 v[110:113], v0 offset:32
	ds_read_b128 v[114:117], v66 offset:18464
	ds_read_b128 v[118:121], v0 offset:4608
	ds_read_b128 v[122:125], v0 offset:4640
	s_waitcnt lgkmcnt(4)
	v_mfma_f32_32x32x16_bf16 v[34:49], v[82:85], v[102:105], v[34:49]
	s_waitcnt lgkmcnt(1)
	v_mfma_f32_32x32x16_bf16 v[2:17], v[118:121], v[102:105], v[2:17]
	ds_read_b128 v[102:105], v66 offset:23040
	ds_read_b128 v[126:129], v66 offset:23072
	s_waitcnt lgkmcnt(1)
	v_mfma_f32_32x32x16_bf16 v[50:65], v[82:85], v[102:105], v[50:65]
	global_load_dwordx4 v[82:85], v72, s[0:1] offset:3072
	global_load_dwordx4 v[130:133], v72, s[36:37] offset:3072
	s_waitcnt vmcnt(9)
	ds_write_b128 v67, v[86:89] offset:36864
	s_waitcnt vmcnt(8)
	ds_write_b128 v67, v[134:137] offset:55296
	v_mfma_f32_32x32x16_bf16 v[18:33], v[118:121], v[102:105], v[18:33]
	global_load_dwordx4 v[86:89], v71, s[0:1] offset:3072
	global_load_dwordx4 v[102:105], v71, s[36:37] offset:3072
	v_mfma_f32_32x32x16_bf16 v[2:17], v[122:125], v[114:117], v[2:17]
	s_waitcnt lgkmcnt(2)
	v_mfma_f32_32x32x16_bf16 v[18:33], v[122:125], v[126:129], v[18:33]
	v_mfma_f32_32x32x16_bf16 v[34:49], v[110:113], v[114:117], v[34:49]
	v_mfma_f32_32x32x16_bf16 v[50:65], v[110:113], v[126:129], v[50:65]
	ds_read_b128 v[110:113], v0 offset:64
	ds_read_b128 v[114:117], v0 offset:4672
	ds_read_b128 v[118:121], v66 offset:18496
	ds_read_b128 v[134:137], v66 offset:23104
	s_waitcnt vmcnt(9)
	ds_write_b128 v67, v[90:93] offset:41472
	s_waitcnt vmcnt(8)
	ds_write_b128 v67, v[106:109] offset:59904
	global_load_dwordx4 v[90:93], v70, s[0:1] offset:3072
	global_load_dwordx4 v[106:109], v70, s[36:37] offset:3072
	s_waitcnt lgkmcnt(3)
	v_mfma_f32_32x32x16_bf16 v[2:17], v[114:117], v[118:121], v[2:17]
	s_waitcnt lgkmcnt(2)
	v_mfma_f32_32x32x16_bf16 v[18:33], v[114:117], v[134:137], v[18:33]
	v_mfma_f32_32x32x16_bf16 v[34:49], v[110:113], v[118:121], v[34:49]
	v_mfma_f32_32x32x16_bf16 v[50:65], v[110:113], v[134:137], v[50:65]
	ds_read_b128 v[110:113], v0 offset:96
	ds_read_b128 v[118:121], v0 offset:4704
	ds_read_b128 v[122:125], v66 offset:18528
	ds_read_b128 v[126:129], v66 offset:23136
	s_waitcnt vmcnt(9)
	ds_write_b128 v67, v[74:77] offset:46080
	s_waitcnt vmcnt(8)
	ds_write_b128 v67, v[94:97] offset:64512
	global_load_dwordx4 v[74:77], v69, s[0:1] offset:3072
	global_load_dwordx4 v[94:97], v69, s[36:37] offset:3072
	s_waitcnt lgkmcnt(3)
	v_mfma_f32_32x32x16_bf16 v[2:17], v[118:121], v[122:125], v[2:17]
	s_waitcnt vmcnt(9)
	ds_write_b128 v67, v[78:81] offset:50688
	s_waitcnt vmcnt(8)
	ds_write_b128 v68, v[98:101] offset:13824
	s_waitcnt lgkmcnt(4)
	v_mfma_f32_32x32x16_bf16 v[18:33], v[118:121], v[126:129], v[18:33]
	v_mfma_f32_32x32x16_bf16 v[34:49], v[110:113], v[122:125], v[34:49]
	v_mfma_f32_32x32x16_bf16 v[50:65], v[110:113], v[126:129], v[50:65]
	s_waitcnt lgkmcnt(0)
	s_barrier
; #define GL1_(RA, RB, i) { RA[i] = *(const u32x4*)(ap + (aoff + (i) * astep)); if ((i) < NB) RB[(i) < NB ? (i) : 0] = *(const u32x4*)(bp + (boff + (i) * bstep)); }
; #define LS1_(RA, RB, ST, i) { char* sn_ = lds + (ST) * STAGE; *(u32x4*)(sn_ + wofs + (i) * 32 * LROW) = RA[i]; \
;                               if ((i) < NB) *(u32x4*)(sn_ + STAGE_OP + wofs + (i) * 32 * LROW) = RB[(i) < NB ? (i) : 0]; }
; template <int NJ> DI void gemm_mainloop_reg(const bf16_t* __restrict__ A, int lda, const bf16_t* __restrict__ Bt, int ldb, int K, f32x16 (&acc)[2][NJ], char* lds) {
;     ...
; #pragma unroll
;   for (int i = 0; i < 4; ++i) GL1_(ra0, rb0, i);
;   ap += 128; bp += 128;
; #pragma unroll
;   for (int i = 0; i < 4; ++i) GL1_(ra1, rb1, i);
;   ap += 128; bp += 128;
; #pragma unroll
;   for (int i = 0; i < 4; ++i) LS1_(ra0, rb0, 0, i);
;   __syncthreads();
;   const int nk = K >> 6;
;   for (int kt = 0; kt < nk; kt += 2) {
;     const bool l0 = (kt + 2 < nk), l1 = (kt + 3 < nk);
;     STEP_(0, l0, ra0, rb0, true, ra1, rb1);
;     __syncthreads();
;     STEP_(1, l1, ra1, rb1, l0, ra0, rb0);
;     __syncthreads();
;   }
	ds_read_b128 v[78:81], v0 offset:36864
	ds_read_b128 v[98:101], v66 offset:55296
	ds_read_b128 v[110:113], v0 offset:36896
	ds_read_b128 v[114:117], v66 offset:55328
	ds_read_b128 v[118:121], v0 offset:41472
	ds_read_b128 v[122:125], v0 offset:41504
	s_waitcnt lgkmcnt(4)
	v_mfma_f32_32x32x16_bf16 v[34:49], v[78:81], v[98:101], v[34:49]
	s_waitcnt lgkmcnt(1)
	v_mfma_f32_32x32x16_bf16 v[2:17], v[118:121], v[98:101], v[2:17]
	ds_read_b128 v[98:101], v66 offset:59904
	ds_read_b128 v[126:129], v66 offset:59936
	s_waitcnt lgkmcnt(1)
	v_mfma_f32_32x32x16_bf16 v[50:65], v[78:81], v[98:101], v[50:65]
	global_load_dwordx4 v[78:81], v72, s[0:1] offset:3200
	global_load_dwordx4 v[134:137], v72, s[36:37] offset:3200
	s_waitcnt vmcnt(9)
	ds_write_b128 v67, v[82:85]
	s_waitcnt vmcnt(8)
	ds_write_b128 v67, v[130:133] offset:18432
	v_mfma_f32_32x32x16_bf16 v[18:33], v[118:121], v[98:101], v[18:33]
	global_load_dwordx4 v[82:85], v71, s[0:1] offset:3200
	global_load_dwordx4 v[98:101], v71, s[36:37] offset:3200
	v_mfma_f32_32x32x16_bf16 v[2:17], v[122:125], v[114:117], v[2:17]
	s_waitcnt lgkmcnt(2)
	v_mfma_f32_32x32x16_bf16 v[18:33], v[122:125], v[126:129], v[18:33]
	v_mfma_f32_32x32x16_bf16 v[34:49], v[110:113], v[114:117], v[34:49]
	v_mfma_f32_32x32x16_bf16 v[50:65], v[110:113], v[126:129], v[50:65]
	ds_read_b128 v[110:113], v0 offset:36928
	ds_read_b128 v[114:117], v0 offset:41536
	ds_read_b128 v[118:121], v66 offset:55360
	ds_read_b128 v[130:133], v66 offset:59968
	s_waitcnt vmcnt(9)
	ds_write_b128 v67, v[86:89] offset:4608
	s_waitcnt vmcnt(8)
	ds_write_b128 v67, v[102:105] offset:23040
	global_load_dwordx4 v[86:89], v70, s[0:1] offset:3200
	global_load_dwordx4 v[102:105], v70, s[36:37] offset:3200
	s_waitcnt lgkmcnt(3)
	v_mfma_f32_32x32x16_bf16 v[2:17], v[114:117], v[118:121], v[2:17]
	s_waitcnt lgkmcnt(2)
	v_mfma_f32_32x32x16_bf16 v[18:33], v[114:117], v[130:133], v[18:33]
	v_mfma_f32_32x32x16_bf16 v[34:49], v[110:113], v[118:121], v[34:49]
	v_mfma_f32_32x32x16_bf16 v[50:65], v[110:113], v[130:133], v[50:65]
	ds_read_b128 v[110:113], v0 offset:36960
	ds_read_b128 v[118:121], v0 offset:41568
	ds_read_b128 v[122:125], v66 offset:55392
	ds_read_b128 v[126:129], v66 offset:60000
	s_waitcnt vmcnt(9)
	ds_write_b128 v67, v[90:93] offset:9216
	s_waitcnt vmcnt(8)
	ds_write_b128 v67, v[106:109] offset:27648
	global_load_dwordx4 v[90:93], v69, s[0:1] offset:3200
	global_load_dwordx4 v[106:109], v69, s[36:37] offset:3200
	s_waitcnt lgkmcnt(3)
	v_mfma_f32_32x32x16_bf16 v[2:17], v[118:121], v[122:125], v[2:17]
	s_waitcnt vmcnt(9)
	ds_write_b128 v67, v[74:77] offset:13824
	s_waitcnt vmcnt(8)
	ds_write_b128 v67, v[94:97] offset:32256
	s_waitcnt lgkmcnt(4)
	v_mfma_f32_32x32x16_bf16 v[18:33], v[118:121], v[126:129], v[18:33]
	v_mfma_f32_32x32x16_bf16 v[34:49], v[110:113], v[122:125], v[34:49]
	v_mfma_f32_32x32x16_bf16 v[50:65], v[110:113], v[126:129], v[50:65]
	s_waitcnt lgkmcnt(0)
	s_barrier
	ds_read_b128 v[74:77], v0
	ds_read_b128 v[94:97], v66 offset:18432
	ds_read_b128 v[110:113], v0 offset:32
	ds_read_b128 v[114:117], v66 offset:18464
	ds_read_b128 v[118:121], v0 offset:4608
	ds_read_b128 v[122:125], v0 offset:4640
	s_waitcnt lgkmcnt(4)
	v_mfma_f32_32x32x16_bf16 v[34:49], v[74:77], v[94:97], v[34:49]
	s_waitcnt lgkmcnt(1)
	v_mfma_f32_32x32x16_bf16 v[2:17], v[118:121], v[94:97], v[2:17]
	ds_read_b128 v[94:97], v66 offset:23040
	ds_read_b128 v[126:129], v66 offset:23072
	s_waitcnt lgkmcnt(1)
	v_mfma_f32_32x32x16_bf16 v[50:65], v[74:77], v[94:97], v[50:65]
	global_load_dwordx4 v[74:77], v72, s[0:1] offset:3328
	global_load_dwordx4 v[130:133], v72, s[36:37] offset:3328
	s_waitcnt vmcnt(9)
	ds_write_b128 v67, v[78:81] offset:36864
	s_waitcnt vmcnt(8)
	ds_write_b128 v67, v[134:137] offset:55296
	v_mfma_f32_32x32x16_bf16 v[18:33], v[118:121], v[94:97], v[18:33]
	global_load_dwordx4 v[78:81], v71, s[0:1] offset:3328
	global_load_dwordx4 v[94:97], v71, s[36:37] offset:3328
	v_mfma_f32_32x32x16_bf16 v[2:17], v[122:125], v[114:117], v[2:17]
	s_waitcnt lgkmcnt(2)
	v_mfma_f32_32x32x16_bf16 v[18:33], v[122:125], v[126:129], v[18:33]
	v_mfma_f32_32x32x16_bf16 v[34:49], v[110:113], v[114:117], v[34:49]
	v_mfma_f32_32x32x16_bf16 v[50:65], v[110:113], v[126:129], v[50:65]
	ds_read_b128 v[110:113], v0 offset:64
	ds_read_b128 v[114:117], v0 offset:4672
	ds_read_b128 v[118:121], v66 offset:18496
	ds_read_b128 v[134:137], v66 offset:23104
	s_waitcnt vmcnt(9)
	ds_write_b128 v67, v[82:85] offset:41472
	s_waitcnt vmcnt(8)
	ds_write_b128 v67, v[98:101] offset:59904
	global_load_dwordx4 v[82:85], v70, s[0:1] offset:3328
	global_load_dwordx4 v[98:101], v70, s[36:37] offset:3328
	s_waitcnt lgkmcnt(3)
	v_mfma_f32_32x32x16_bf16 v[2:17], v[114:117], v[118:121], v[2:17]
	s_waitcnt lgkmcnt(2)
	v_mfma_f32_32x32x16_bf16 v[18:33], v[114:117], v[134:137], v[18:33]
	v_mfma_f32_32x32x16_bf16 v[34:49], v[110:113], v[118:121], v[34:49]
	v_mfma_f32_32x32x16_bf16 v[50:65], v[110:113], v[134:137], v[50:65]
	ds_read_b128 v[110:113], v0 offset:96
	ds_read_b128 v[118:121], v0 offset:4704
	ds_read_b128 v[122:125], v66 offset:18528
	ds_read_b128 v[126:129], v66 offset:23136
	s_waitcnt vmcnt(9)
	ds_write_b128 v67, v[86:89] offset:46080
	s_waitcnt vmcnt(8)
	ds_write_b128 v67, v[102:105] offset:64512
	global_load_dwordx4 v[86:89], v69, s[0:1] offset:3328
	global_load_dwordx4 v[102:105], v69, s[36:37] offset:3328
	s_waitcnt lgkmcnt(3)
	v_mfma_f32_32x32x16_bf16 v[2:17], v[118:121], v[122:125], v[2:17]
	s_waitcnt vmcnt(9)
	ds_write_b128 v67, v[90:93] offset:50688
	s_waitcnt vmcnt(8)
	ds_write_b128 v68, v[106:109] offset:13824
	s_waitcnt lgkmcnt(4)
	v_mfma_f32_32x32x16_bf16 v[18:33], v[118:121], v[126:129], v[18:33]
	v_mfma_f32_32x32x16_bf16 v[34:49], v[110:113], v[122:125], v[34:49]
	v_mfma_f32_32x32x16_bf16 v[50:65], v[110:113], v[126:129], v[50:65]
	s_waitcnt lgkmcnt(0)
	s_barrier
; #define GL1_(RA, RB, i) { RA[i] = *(const u32x4*)(ap + (aoff + (i) * astep)); if ((i) < NB) RB[(i) < NB ? (i) : 0] = *(const u32x4*)(bp + (boff + (i) * bstep)); }
; #define LS1_(RA, RB, ST, i) { char* sn_ = lds + (ST) * STAGE; *(u32x4*)(sn_ + wofs + (i) * 32 * LROW) = RA[i]; \
;                               if ((i) < NB) *(u32x4*)(sn_ + STAGE_OP + wofs + (i) * 32 * LROW) = RB[(i) < NB ? (i) : 0]; }
; template <int NJ> DI void gemm_mainloop_reg(const bf16_t* __restrict__ A, int lda, const bf16_t* __restrict__ Bt, int ldb, int K, f32x16 (&acc)[2][NJ], char* lds) {
;     ...
; #pragma unroll
;   for (int i = 0; i < 4; ++i) GL1_(ra0, rb0, i);
;   ap += 128; bp += 128;
; #pragma unroll
;   for (int i = 0; i < 4; ++i) GL1_(ra1, rb1, i);
;   ap += 128; bp += 128;
; #pragma unroll
;   for (int i = 0; i < 4; ++i) LS1_(ra0, rb0, 0, i);
;   __syncthreads();
;   const int nk = K >> 6;
;   for (int kt = 0; kt < nk; kt += 2) {
;     const bool l0 = (kt + 2 < nk), l1 = (kt + 3 < nk);
;     STEP_(0, l0, ra0, rb0, true, ra1, rb1);
;     __syncthreads();
;     STEP_(1, l1, ra1, rb1, l0, ra0, rb0);
;     __syncthreads();
;   }
	ds_read_b128 v[90:93], v0 offset:36864
	ds_read_b128 v[106:109], v66 offset:55296
	ds_read_b128 v[110:113], v0 offset:36896
	ds_read_b128 v[114:117], v66 offset:55328
	ds_read_b128 v[118:121], v0 offset:41472
	ds_read_b128 v[122:125], v0 offset:41504
	s_waitcnt lgkmcnt(4)
	v_mfma_f32_32x32x16_bf16 v[34:49], v[90:93], v[106:109], v[34:49]
	s_waitcnt lgkmcnt(1)
	v_mfma_f32_32x32x16_bf16 v[2:17], v[118:121], v[106:109], v[2:17]
	ds_read_b128 v[106:109], v66 offset:59904
	ds_read_b128 v[126:129], v66 offset:59936
	s_waitcnt lgkmcnt(1)
	v_mfma_f32_32x32x16_bf16 v[50:65], v[90:93], v[106:109], v[50:65]
	global_load_dwordx4 v[90:93], v72, s[0:1] offset:3456
	global_load_dwordx4 v[134:137], v72, s[36:37] offset:3456
	s_waitcnt vmcnt(9)
	ds_write_b128 v67, v[74:77]
	s_waitcnt vmcnt(8)
	ds_write_b128 v67, v[130:133] offset:18432
	v_mfma_f32_32x32x16_bf16 v[18:33], v[118:121], v[106:109], v[18:33]
	global_load_dwordx4 v[74:77], v71, s[0:1] offset:3456
	global_load_dwordx4 v[106:109], v71, s[36:37] offset:3456
	v_mfma_f32_32x32x16_bf16 v[2:17], v[122:125], v[114:117], v[2:17]
	s_waitcnt lgkmcnt(2)
	v_mfma_f32_32x32x16_bf16 v[18:33], v[122:125], v[126:129], v[18:33]
	v_mfma_f32_32x32x16_bf16 v[34:49], v[110:113], v[114:117], v[34:49]
	v_mfma_f32_32x32x16_bf16 v[50:65], v[110:113], v[126:129], v[50:65]
	ds_read_b128 v[110:113], v0 offset:36928
	ds_read_b128 v[114:117], v0 offset:41536
	ds_read_b128 v[118:121], v66 offset:55360
	ds_read_b128 v[130:133], v66 offset:59968
	s_waitcnt vmcnt(9)
	ds_write_b128 v67, v[78:81] offset:4608
	s_waitcnt vmcnt(8)
	ds_write_b128 v67, v[94:97] offset:23040
	global_load_dwordx4 v[78:81], v70, s[0:1] offset:3456
	global_load_dwordx4 v[94:97], v70, s[36:37] offset:3456
	s_waitcnt lgkmcnt(3)
	v_mfma_f32_32x32x16_bf16 v[2:17], v[114:117], v[118:121], v[2:17]
	s_waitcnt lgkmcnt(2)
	v_mfma_f32_32x32x16_bf16 v[18:33], v[114:117], v[130:133], v[18:33]
	v_mfma_f32_32x32x16_bf16 v[34:49], v[110:113], v[118:121], v[34:49]
	v_mfma_f32_32x32x16_bf16 v[50:65], v[110:113], v[130:133], v[50:65]
	ds_read_b128 v[110:113], v0 offset:36960
	ds_read_b128 v[118:121], v0 offset:41568
	ds_read_b128 v[122:125], v66 offset:55392
	ds_read_b128 v[126:129], v66 offset:60000
	s_waitcnt vmcnt(9)
	ds_write_b128 v67, v[82:85] offset:9216
	s_waitcnt vmcnt(8)
	ds_write_b128 v67, v[98:101] offset:27648
	global_load_dwordx4 v[82:85], v69, s[0:1] offset:3456
	global_load_dwordx4 v[98:101], v69, s[36:37] offset:3456
	s_waitcnt lgkmcnt(3)
	v_mfma_f32_32x32x16_bf16 v[2:17], v[118:121], v[122:125], v[2:17]
	s_waitcnt vmcnt(9)
	ds_write_b128 v67, v[86:89] offset:13824
	s_waitcnt vmcnt(8)
	ds_write_b128 v67, v[102:105] offset:32256
	s_waitcnt lgkmcnt(4)
	v_mfma_f32_32x32x16_bf16 v[18:33], v[118:121], v[126:129], v[18:33]
	v_mfma_f32_32x32x16_bf16 v[34:49], v[110:113], v[122:125], v[34:49]
	v_mfma_f32_32x32x16_bf16 v[50:65], v[110:113], v[126:129], v[50:65]
	s_waitcnt lgkmcnt(0)
	s_barrier
	ds_read_b128 v[86:89], v0
	ds_read_b128 v[102:105], v66 offset:18432
	ds_read_b128 v[110:113], v0 offset:32
	ds_read_b128 v[114:117], v66 offset:18464
	ds_read_b128 v[118:121], v0 offset:4608
	ds_read_b128 v[122:125], v0 offset:4640
	s_waitcnt lgkmcnt(4)
	v_mfma_f32_32x32x16_bf16 v[34:49], v[86:89], v[102:105], v[34:49]
	s_waitcnt lgkmcnt(1)
	v_mfma_f32_32x32x16_bf16 v[2:17], v[118:121], v[102:105], v[2:17]
	ds_read_b128 v[102:105], v66 offset:23040
	ds_read_b128 v[126:129], v66 offset:23072
	s_waitcnt lgkmcnt(1)
	v_mfma_f32_32x32x16_bf16 v[50:65], v[86:89], v[102:105], v[50:65]
	global_load_dwordx4 v[86:89], v72, s[0:1] offset:3584
	global_load_dwordx4 v[130:133], v72, s[36:37] offset:3584
	s_waitcnt vmcnt(9)
	ds_write_b128 v67, v[90:93] offset:36864
	s_waitcnt vmcnt(8)
	ds_write_b128 v67, v[134:137] offset:55296
	v_mfma_f32_32x32x16_bf16 v[18:33], v[118:121], v[102:105], v[18:33]
	global_load_dwordx4 v[90:93], v71, s[0:1] offset:3584
	global_load_dwordx4 v[102:105], v71, s[36:37] offset:3584
	v_mfma_f32_32x32x16_bf16 v[2:17], v[122:125], v[114:117], v[2:17]
	s_waitcnt lgkmcnt(2)
	v_mfma_f32_32x32x16_bf16 v[18:33], v[122:125], v[126:129], v[18:33]
	v_mfma_f32_32x32x16_bf16 v[34:49], v[110:113], v[114:117], v[34:49]
	v_mfma_f32_32x32x16_bf16 v[50:65], v[110:113], v[126:129], v[50:65]
	ds_read_b128 v[110:113], v0 offset:64
	ds_read_b128 v[114:117], v0 offset:4672
	ds_read_b128 v[118:121], v66 offset:18496
	ds_read_b128 v[134:137], v66 offset:23104
	s_waitcnt vmcnt(9)
	ds_write_b128 v67, v[74:77] offset:41472
	s_waitcnt vmcnt(8)
	ds_write_b128 v67, v[106:109] offset:59904
	global_load_dwordx4 v[74:77], v70, s[0:1] offset:3584
	global_load_dwordx4 v[106:109], v70, s[36:37] offset:3584
	s_waitcnt lgkmcnt(3)
	v_mfma_f32_32x32x16_bf16 v[2:17], v[114:117], v[118:121], v[2:17]
	s_waitcnt lgkmcnt(2)
	v_mfma_f32_32x32x16_bf16 v[18:33], v[114:117], v[134:137], v[18:33]
	v_mfma_f32_32x32x16_bf16 v[34:49], v[110:113], v[118:121], v[34:49]
	v_mfma_f32_32x32x16_bf16 v[50:65], v[110:113], v[134:137], v[50:65]
	ds_read_b128 v[110:113], v0 offset:96
	ds_read_b128 v[118:121], v0 offset:4704
	ds_read_b128 v[122:125], v66 offset:18528
	ds_read_b128 v[126:129], v66 offset:23136
	s_waitcnt vmcnt(9)
	ds_write_b128 v67, v[78:81] offset:46080
	s_waitcnt vmcnt(8)
	ds_write_b128 v67, v[94:97] offset:64512
	global_load_dwordx4 v[78:81], v69, s[0:1] offset:3584
	global_load_dwordx4 v[94:97], v69, s[36:37] offset:3584
	s_waitcnt lgkmcnt(3)
	v_mfma_f32_32x32x16_bf16 v[2:17], v[118:121], v[122:125], v[2:17]
	s_waitcnt vmcnt(9)
	ds_write_b128 v67, v[82:85] offset:50688
	s_waitcnt vmcnt(8)
	ds_write_b128 v68, v[98:101] offset:13824
	s_waitcnt lgkmcnt(4)
	v_mfma_f32_32x32x16_bf16 v[18:33], v[118:121], v[126:129], v[18:33]
	v_mfma_f32_32x32x16_bf16 v[34:49], v[110:113], v[122:125], v[34:49]
	v_mfma_f32_32x32x16_bf16 v[50:65], v[110:113], v[126:129], v[50:65]
	s_waitcnt lgkmcnt(0)
	s_barrier
; #define GL1_(RA, RB, i) { RA[i] = *(const u32x4*)(ap + (aoff + (i) * astep)); if ((i) < NB) RB[(i) < NB ? (i) : 0] = *(const u32x4*)(bp + (boff + (i) * bstep)); }
; #define LS1_(RA, RB, ST, i) { char* sn_ = lds + (ST) * STAGE; *(u32x4*)(sn_ + wofs + (i) * 32 * LROW) = RA[i]; \
;                               if ((i) < NB) *(u32x4*)(sn_ + STAGE_OP + wofs + (i) * 32 * LROW) = RB[(i) < NB ? (i) : 0]; }
; template <int NJ> DI void gemm_mainloop_reg(const bf16_t* __restrict__ A, int lda, const bf16_t* __restrict__ Bt, int ldb, int K, f32x16 (&acc)[2][NJ], char* lds) {
;     ...
; #pragma unroll
;   for (int i = 0; i < 4; ++i) GL1_(ra0, rb0, i);
;   ap += 128; bp += 128;
; #pragma unroll
;   for (int i = 0; i < 4; ++i) GL1_(ra1, rb1, i);
;   ap += 128; bp += 128;
; #pragma unroll
;   for (int i = 0; i < 4; ++i) LS1_(ra0, rb0, 0, i);
;   __syncthreads();
;   const int nk = K >> 6;
;   for (int kt = 0; kt < nk; kt += 2) {
;     const bool l0 = (kt + 2 < nk), l1 = (kt + 3 < nk);
;     STEP_(0, l0, ra0, rb0, true, ra1, rb1);
;     __syncthreads();
;     STEP_(1, l1, ra1, rb1, l0, ra0, rb0);
;     __syncthreads();
;   }
	ds_read_b128 v[82:85], v0 offset:36864
	ds_read_b128 v[98:101], v66 offset:55296
	ds_read_b128 v[110:113], v0 offset:36896
	ds_read_b128 v[114:117], v66 offset:55328
	ds_read_b128 v[118:121], v0 offset:41472
	ds_read_b128 v[122:125], v0 offset:41504
	s_waitcnt lgkmcnt(4)
	v_mfma_f32_32x32x16_bf16 v[34:49], v[82:85], v[98:101], v[34:49]
	s_waitcnt lgkmcnt(1)
	v_mfma_f32_32x32x16_bf16 v[2:17], v[118:121], v[98:101], v[2:17]
	ds_read_b128 v[98:101], v66 offset:59904
	ds_read_b128 v[126:129], v66 offset:59936
	s_waitcnt lgkmcnt(1)
	v_mfma_f32_32x32x16_bf16 v[50:65], v[82:85], v[98:101], v[50:65]
	global_load_dwordx4 v[82:85], v72, s[0:1] offset:3712
	global_load_dwordx4 v[134:137], v72, s[36:37] offset:3712
	s_waitcnt vmcnt(9)
	ds_write_b128 v67, v[86:89]
	s_waitcnt vmcnt(8)
	ds_write_b128 v67, v[130:133] offset:18432
	v_mfma_f32_32x32x16_bf16 v[18:33], v[118:121], v[98:101], v[18:33]
	global_load_dwordx4 v[86:89], v71, s[0:1] offset:3712
	global_load_dwordx4 v[98:101], v71, s[36:37] offset:3712
	v_mfma_f32_32x32x16_bf16 v[2:17], v[122:125], v[114:117], v[2:17]
	s_waitcnt lgkmcnt(2)
	v_mfma_f32_32x32x16_bf16 v[18:33], v[122:125], v[126:129], v[18:33]
	v_mfma_f32_32x32x16_bf16 v[34:49], v[110:113], v[114:117], v[34:49]
	v_mfma_f32_32x32x16_bf16 v[50:65], v[110:113], v[126:129], v[50:65]
	ds_read_b128 v[110:113], v0 offset:36928
	ds_read_b128 v[114:117], v0 offset:41536
	ds_read_b128 v[118:121], v66 offset:55360
	ds_read_b128 v[130:133], v66 offset:59968
	s_waitcnt vmcnt(9)
	ds_write_b128 v67, v[90:93] offset:4608
	s_waitcnt vmcnt(8)
	ds_write_b128 v67, v[102:105] offset:23040
	global_load_dwordx4 v[90:93], v70, s[0:1] offset:3712
	global_load_dwordx4 v[102:105], v70, s[36:37] offset:3712
	s_waitcnt lgkmcnt(3)
	v_mfma_f32_32x32x16_bf16 v[2:17], v[114:117], v[118:121], v[2:17]
	s_waitcnt lgkmcnt(2)
	v_mfma_f32_32x32x16_bf16 v[18:33], v[114:117], v[130:133], v[18:33]
	v_mfma_f32_32x32x16_bf16 v[34:49], v[110:113], v[118:121], v[34:49]
	v_mfma_f32_32x32x16_bf16 v[50:65], v[110:113], v[130:133], v[50:65]
	ds_read_b128 v[110:113], v0 offset:36960
	ds_read_b128 v[118:121], v0 offset:41568
	ds_read_b128 v[122:125], v66 offset:55392
	ds_read_b128 v[126:129], v66 offset:60000
	s_waitcnt vmcnt(9)
	ds_write_b128 v67, v[74:77] offset:9216
	s_waitcnt vmcnt(8)
	ds_write_b128 v67, v[106:109] offset:27648
	global_load_dwordx4 v[74:77], v69, s[0:1] offset:3712
	global_load_dwordx4 v[106:109], v69, s[36:37] offset:3712
	s_waitcnt lgkmcnt(3)
	v_mfma_f32_32x32x16_bf16 v[2:17], v[118:121], v[122:125], v[2:17]
	s_waitcnt vmcnt(9)
	ds_write_b128 v67, v[78:81] offset:13824
	s_waitcnt vmcnt(8)
	ds_write_b128 v67, v[94:97] offset:32256
	s_waitcnt lgkmcnt(4)
	v_mfma_f32_32x32x16_bf16 v[18:33], v[118:121], v[126:129], v[18:33]
	v_mfma_f32_32x32x16_bf16 v[34:49], v[110:113], v[122:125], v[34:49]
	v_mfma_f32_32x32x16_bf16 v[50:65], v[110:113], v[126:129], v[50:65]
	s_waitcnt lgkmcnt(0)
	s_barrier
	ds_read_b128 v[78:81], v0
	ds_read_b128 v[94:97], v66 offset:18432
	ds_read_b128 v[110:113], v0 offset:32
	ds_read_b128 v[114:117], v66 offset:18464
	ds_read_b128 v[118:121], v0 offset:4608
	ds_read_b128 v[122:125], v0 offset:4640
	s_waitcnt lgkmcnt(4)
	v_mfma_f32_32x32x16_bf16 v[34:49], v[78:81], v[94:97], v[34:49]
	s_waitcnt lgkmcnt(1)
	v_mfma_f32_32x32x16_bf16 v[2:17], v[118:121], v[94:97], v[2:17]
	ds_read_b128 v[94:97], v66 offset:23040
	ds_read_b128 v[126:129], v66 offset:23072
	s_waitcnt lgkmcnt(1)
	v_mfma_f32_32x32x16_bf16 v[50:65], v[78:81], v[94:97], v[50:65]
	global_load_dwordx4 v[78:81], v72, s[0:1] offset:3840
	global_load_dwordx4 v[130:133], v72, s[36:37] offset:3840
	s_waitcnt vmcnt(9)
	ds_write_b128 v67, v[82:85] offset:36864
	s_waitcnt vmcnt(8)
	ds_write_b128 v67, v[134:137] offset:55296
	v_mfma_f32_32x32x16_bf16 v[18:33], v[118:121], v[94:97], v[18:33]
	global_load_dwordx4 v[82:85], v71, s[0:1] offset:3840
	global_load_dwordx4 v[94:97], v71, s[36:37] offset:3840
	v_mfma_f32_32x32x16_bf16 v[2:17], v[122:125], v[114:117], v[2:17]
	s_waitcnt lgkmcnt(2)
	v_mfma_f32_32x32x16_bf16 v[18:33], v[122:125], v[126:129], v[18:33]
	v_mfma_f32_32x32x16_bf16 v[34:49], v[110:113], v[114:117], v[34:49]
	v_mfma_f32_32x32x16_bf16 v[50:65], v[110:113], v[126:129], v[50:65]
	ds_read_b128 v[110:113], v0 offset:64
	ds_read_b128 v[114:117], v0 offset:4672
	ds_read_b128 v[118:121], v66 offset:18496
	ds_read_b128 v[134:137], v66 offset:23104
	s_waitcnt vmcnt(9)
	ds_write_b128 v67, v[86:89] offset:41472
	s_waitcnt vmcnt(8)
	ds_write_b128 v67, v[98:101] offset:59904
	global_load_dwordx4 v[86:89], v70, s[0:1] offset:3840
	global_load_dwordx4 v[98:101], v70, s[36:37] offset:3840
	s_waitcnt lgkmcnt(3)
	v_mfma_f32_32x32x16_bf16 v[2:17], v[114:117], v[118:121], v[2:17]
	s_waitcnt lgkmcnt(2)
	v_mfma_f32_32x32x16_bf16 v[18:33], v[114:117], v[134:137], v[18:33]
	v_mfma_f32_32x32x16_bf16 v[34:49], v[110:113], v[118:121], v[34:49]
	v_mfma_f32_32x32x16_bf16 v[50:65], v[110:113], v[134:137], v[50:65]
	ds_read_b128 v[110:113], v0 offset:96
	ds_read_b128 v[118:121], v0 offset:4704
	ds_read_b128 v[122:125], v66 offset:18528
	ds_read_b128 v[126:129], v66 offset:23136
	s_waitcnt vmcnt(9)
	ds_write_b128 v67, v[90:93] offset:46080
	s_waitcnt vmcnt(8)
	ds_write_b128 v67, v[102:105] offset:64512
	global_load_dwordx4 v[90:93], v69, s[0:1] offset:3840
	global_load_dwordx4 v[102:105], v69, s[36:37] offset:3840
	s_waitcnt lgkmcnt(3)
	v_mfma_f32_32x32x16_bf16 v[2:17], v[118:121], v[122:125], v[2:17]
	s_waitcnt vmcnt(9)
	ds_write_b128 v67, v[74:77] offset:50688
	s_waitcnt vmcnt(8)
	ds_write_b128 v68, v[106:109] offset:13824
	s_waitcnt lgkmcnt(4)
	v_mfma_f32_32x32x16_bf16 v[18:33], v[118:121], v[126:129], v[18:33]
	v_mfma_f32_32x32x16_bf16 v[34:49], v[110:113], v[122:125], v[34:49]
	v_mfma_f32_32x32x16_bf16 v[50:65], v[110:113], v[126:129], v[50:65]
	s_waitcnt lgkmcnt(0)
	s_barrier
; #define GL1_(RA, RB, i) { RA[i] = *(const u32x4*)(ap + (aoff + (i) * astep)); if ((i) < NB) RB[(i) < NB ? (i) : 0] = *(const u32x4*)(bp + (boff + (i) * bstep)); }
; #define LS1_(RA, RB, ST, i) { char* sn_ = lds + (ST) * STAGE; *(u32x4*)(sn_ + wofs + (i) * 32 * LROW) = RA[i]; \
;                               if ((i) < NB) *(u32x4*)(sn_ + STAGE_OP + wofs + (i) * 32 * LROW) = RB[(i) < NB ? (i) : 0]; }
; template <int NJ> DI void gemm_mainloop_reg(const bf16_t* __restrict__ A, int lda, const bf16_t* __restrict__ Bt, int ldb, int K, f32x16 (&acc)[2][NJ], char* lds) {
;     ...
; #pragma unroll
;   for (int i = 0; i < 4; ++i) GL1_(ra0, rb0, i);
;   ap += 128; bp += 128;
; #pragma unroll
;   for (int i = 0; i < 4; ++i) GL1_(ra1, rb1, i);
;   ap += 128; bp += 128;
; #pragma unroll
;   for (int i = 0; i < 4; ++i) LS1_(ra0, rb0, 0, i);
;   __syncthreads();
;   const int nk = K >> 6;
;   for (int kt = 0; kt < nk; kt += 2) {
;     const bool l0 = (kt + 2 < nk), l1 = (kt + 3 < nk);
;     STEP_(0, l0, ra0, rb0, true, ra1, rb1);
;     __syncthreads();
;     STEP_(1, l1, ra1, rb1, l0, ra0, rb0);
;     __syncthreads();
;   }
	ds_read_b128 v[74:77], v0 offset:36864
	ds_read_b128 v[106:109], v66 offset:55296
	ds_read_b128 v[110:113], v0 offset:36896
	ds_read_b128 v[114:117], v66 offset:55328
	ds_read_b128 v[118:121], v0 offset:41472
	ds_read_b128 v[122:125], v0 offset:41504
	s_waitcnt lgkmcnt(4)
	v_mfma_f32_32x32x16_bf16 v[34:49], v[74:77], v[106:109], v[34:49]
	s_waitcnt lgkmcnt(1)
	v_mfma_f32_32x32x16_bf16 v[2:17], v[118:121], v[106:109], v[2:17]
	ds_read_b128 v[106:109], v66 offset:59904
	ds_read_b128 v[126:129], v66 offset:59936
	s_waitcnt lgkmcnt(1)
	v_mfma_f32_32x32x16_bf16 v[50:65], v[74:77], v[106:109], v[50:65]
	global_load_dwordx4 v[74:77], v72, s[0:1] offset:3968
	global_load_dwordx4 v[134:137], v72, s[36:37] offset:3968
	s_waitcnt vmcnt(9)
	ds_write_b128 v67, v[78:81]
	s_waitcnt vmcnt(8)
	ds_write_b128 v67, v[130:133] offset:18432
	v_mfma_f32_32x32x16_bf16 v[18:33], v[118:121], v[106:109], v[18:33]
	global_load_dwordx4 v[78:81], v71, s[0:1] offset:3968
	global_load_dwordx4 v[106:109], v71, s[36:37] offset:3968
	v_mfma_f32_32x32x16_bf16 v[2:17], v[122:125], v[114:117], v[2:17]
	s_waitcnt lgkmcnt(2)
	v_mfma_f32_32x32x16_bf16 v[18:33], v[122:125], v[126:129], v[18:33]
	v_mfma_f32_32x32x16_bf16 v[34:49], v[110:113], v[114:117], v[34:49]
	v_mfma_f32_32x32x16_bf16 v[50:65], v[110:113], v[126:129], v[50:65]
	ds_read_b128 v[110:113], v0 offset:36928
	ds_read_b128 v[114:117], v0 offset:41536
	ds_read_b128 v[118:121], v66 offset:55360
	ds_read_b128 v[130:133], v66 offset:59968
	s_waitcnt vmcnt(9)
	ds_write_b128 v67, v[82:85] offset:4608
	s_waitcnt vmcnt(8)
	ds_write_b128 v67, v[94:97] offset:23040
	global_load_dwordx4 v[82:85], v70, s[0:1] offset:3968
	global_load_dwordx4 v[94:97], v70, s[36:37] offset:3968
	s_waitcnt lgkmcnt(3)
	v_mfma_f32_32x32x16_bf16 v[2:17], v[114:117], v[118:121], v[2:17]
	s_waitcnt lgkmcnt(2)
	v_mfma_f32_32x32x16_bf16 v[18:33], v[114:117], v[130:133], v[18:33]
	v_mfma_f32_32x32x16_bf16 v[34:49], v[110:113], v[118:121], v[34:49]
	v_mfma_f32_32x32x16_bf16 v[50:65], v[110:113], v[130:133], v[50:65]
	ds_read_b128 v[110:113], v0 offset:36960
	ds_read_b128 v[118:121], v0 offset:41568
	ds_read_b128 v[122:125], v66 offset:55392
	ds_read_b128 v[126:129], v66 offset:60000
	s_waitcnt vmcnt(9)
	ds_write_b128 v67, v[86:89] offset:9216
	s_waitcnt vmcnt(8)
	ds_write_b128 v67, v[98:101] offset:27648
	global_load_dwordx4 v[86:89], v69, s[0:1] offset:3968
	global_load_dwordx4 v[98:101], v69, s[36:37] offset:3968
	s_waitcnt lgkmcnt(3)
	v_mfma_f32_32x32x16_bf16 v[2:17], v[118:121], v[122:125], v[2:17]
	s_waitcnt vmcnt(9)
	ds_write_b128 v67, v[90:93] offset:13824
	s_waitcnt vmcnt(8)
	ds_write_b128 v67, v[102:105] offset:32256
	s_waitcnt lgkmcnt(4)
	v_mfma_f32_32x32x16_bf16 v[18:33], v[118:121], v[126:129], v[18:33]
	v_mfma_f32_32x32x16_bf16 v[34:49], v[110:113], v[122:125], v[34:49]
	v_mfma_f32_32x32x16_bf16 v[50:65], v[110:113], v[126:129], v[50:65]
	s_waitcnt lgkmcnt(0)
	s_barrier
	ds_read_b128 v[90:93], v0
	ds_read_b128 v[102:105], v66 offset:18432
	ds_read_b128 v[110:113], v0 offset:32
	ds_read_b128 v[114:117], v66 offset:18464
	ds_read_b128 v[118:121], v0 offset:4608
	ds_read_b128 v[122:125], v0 offset:4640
	s_waitcnt lgkmcnt(4)
	v_mfma_f32_32x32x16_bf16 v[34:49], v[90:93], v[102:105], v[34:49]
	s_add_u32 s2, s36, 0x1000
	s_addc_u32 s3, s37, 0
	s_add_u32 s26, s0, 0x1000
	s_addc_u32 s27, s1, 0
	ds_read_b128 v[126:129], v66 offset:23072
	s_waitcnt lgkmcnt(2)
	v_mfma_f32_32x32x16_bf16 v[2:17], v[118:121], v[102:105], v[2:17]
	ds_read_b128 v[102:105], v66 offset:23040
	s_waitcnt lgkmcnt(0)
	v_mfma_f32_32x32x16_bf16 v[50:65], v[90:93], v[102:105], v[50:65]
	global_load_dwordx4 v[90:93], v72, s[26:27]
	global_load_dwordx4 v[130:133], v72, s[2:3]
	s_waitcnt vmcnt(9)
	ds_write_b128 v67, v[74:77] offset:36864
	s_waitcnt vmcnt(8)
	ds_write_b128 v67, v[134:137] offset:55296
	v_mfma_f32_32x32x16_bf16 v[18:33], v[118:121], v[102:105], v[18:33]
	global_load_dwordx4 v[74:77], v71, s[26:27]
	global_load_dwordx4 v[102:105], v71, s[2:3]
	v_mfma_f32_32x32x16_bf16 v[2:17], v[122:125], v[114:117], v[2:17]
	v_mfma_f32_32x32x16_bf16 v[18:33], v[122:125], v[126:129], v[18:33]
	v_mfma_f32_32x32x16_bf16 v[34:49], v[110:113], v[114:117], v[34:49]
	v_mfma_f32_32x32x16_bf16 v[50:65], v[110:113], v[126:129], v[50:65]
	ds_read_b128 v[110:113], v0 offset:64
	ds_read_b128 v[114:117], v0 offset:4672
	ds_read_b128 v[118:121], v66 offset:18496
	ds_read_b128 v[134:137], v66 offset:23104
	s_waitcnt vmcnt(9)
	ds_write_b128 v67, v[78:81] offset:41472
	s_waitcnt vmcnt(8)
	ds_write_b128 v67, v[106:109] offset:59904
	global_load_dwordx4 v[78:81], v70, s[26:27]
	global_load_dwordx4 v[106:109], v70, s[2:3]
	s_waitcnt lgkmcnt(3)
	v_mfma_f32_32x32x16_bf16 v[2:17], v[114:117], v[118:121], v[2:17]
	s_waitcnt lgkmcnt(2)
	v_mfma_f32_32x32x16_bf16 v[18:33], v[114:117], v[134:137], v[18:33]
	v_mfma_f32_32x32x16_bf16 v[34:49], v[110:113], v[118:121], v[34:49]
	v_mfma_f32_32x32x16_bf16 v[50:65], v[110:113], v[134:137], v[50:65]
	ds_read_b128 v[110:113], v0 offset:96
	ds_read_b128 v[118:121], v0 offset:4704
	ds_read_b128 v[122:125], v66 offset:18528
	ds_read_b128 v[126:129], v66 offset:23136
	s_waitcnt vmcnt(9)
	ds_write_b128 v67, v[82:85] offset:46080
	s_waitcnt vmcnt(8)
	ds_write_b128 v67, v[94:97] offset:64512
	global_load_dwordx4 v[82:85], v69, s[26:27]
	global_load_dwordx4 v[94:97], v69, s[2:3]
	s_waitcnt lgkmcnt(3)
	v_mfma_f32_32x32x16_bf16 v[2:17], v[118:121], v[122:125], v[2:17]
	s_waitcnt vmcnt(9)
	ds_write_b128 v67, v[86:89] offset:50688
	s_waitcnt vmcnt(8)
	ds_write_b128 v68, v[98:101] offset:13824
	s_waitcnt lgkmcnt(4)
	v_mfma_f32_32x32x16_bf16 v[18:33], v[118:121], v[126:129], v[18:33]
	v_mfma_f32_32x32x16_bf16 v[34:49], v[110:113], v[122:125], v[34:49]
	v_mfma_f32_32x32x16_bf16 v[50:65], v[110:113], v[126:129], v[50:65]
	s_waitcnt lgkmcnt(0)
	s_barrier
; #define GL1_(RA, RB, i) { RA[i] = *(const u32x4*)(ap + (aoff + (i) * astep)); if ((i) < NB) RB[(i) < NB ? (i) : 0] = *(const u32x4*)(bp + (boff + (i) * bstep)); }
; #define LS1_(RA, RB, ST, i) { char* sn_ = lds + (ST) * STAGE; *(u32x4*)(sn_ + wofs + (i) * 32 * LROW) = RA[i]; \
;                               if ((i) < NB) *(u32x4*)(sn_ + STAGE_OP + wofs + (i) * 32 * LROW) = RB[(i) < NB ? (i) : 0]; }
; template <int NJ> DI void gemm_mainloop_reg(const bf16_t* __restrict__ A, int lda, const bf16_t* __restrict__ Bt, int ldb, int K, f32x16 (&acc)[2][NJ], char* lds) {
;     ...
; #pragma unroll
;   for (int i = 0; i < 4; ++i) GL1_(ra0, rb0, i);
;   ap += 128; bp += 128;
; #pragma unroll
;   for (int i = 0; i < 4; ++i) GL1_(ra1, rb1, i);
;   ap += 128; bp += 128;
; #pragma unroll
;   for (int i = 0; i < 4; ++i) LS1_(ra0, rb0, 0, i);
;   __syncthreads();
;   const int nk = K >> 6;
;   for (int kt = 0; kt < nk; kt += 2) {
;     const bool l0 = (kt + 2 < nk), l1 = (kt + 3 < nk);
;     STEP_(0, l0, ra0, rb0, true, ra1, rb1);
;     __syncthreads();
;     STEP_(1, l1, ra1, rb1, l0, ra0, rb0);
;     __syncthreads();
;   }
	ds_read_b128 v[86:89], v0 offset:36864
	ds_read_b128 v[98:101], v66 offset:55296
	ds_read_b128 v[110:113], v0 offset:36896
	ds_read_b128 v[114:117], v66 offset:55328
	ds_read_b128 v[118:121], v0 offset:41472
	ds_read_b128 v[122:125], v0 offset:41504
	s_waitcnt lgkmcnt(4)
	v_mfma_f32_32x32x16_bf16 v[34:49], v[86:89], v[98:101], v[34:49]
	s_add_u32 s2, s36, 0x1080
	s_addc_u32 s3, s37, 0
	s_add_u32 s26, s0, 0x1080
	s_addc_u32 s27, s1, 0
	ds_read_b128 v[126:129], v66 offset:59936
	s_waitcnt lgkmcnt(2)
	v_mfma_f32_32x32x16_bf16 v[2:17], v[118:121], v[98:101], v[2:17]
	ds_read_b128 v[98:101], v66 offset:59904
	s_waitcnt lgkmcnt(0)
	v_mfma_f32_32x32x16_bf16 v[50:65], v[86:89], v[98:101], v[50:65]
	global_load_dwordx4 v[86:89], v72, s[26:27]
	global_load_dwordx4 v[134:137], v72, s[2:3]
	s_waitcnt vmcnt(9)
	ds_write_b128 v67, v[90:93]
	s_waitcnt vmcnt(8)
	ds_write_b128 v67, v[130:133] offset:18432
	v_mfma_f32_32x32x16_bf16 v[18:33], v[118:121], v[98:101], v[18:33]
	global_load_dwordx4 v[90:93], v71, s[26:27]
	global_load_dwordx4 v[98:101], v71, s[2:3]
	v_mfma_f32_32x32x16_bf16 v[2:17], v[122:125], v[114:117], v[2:17]
	v_mfma_f32_32x32x16_bf16 v[18:33], v[122:125], v[126:129], v[18:33]
	v_mfma_f32_32x32x16_bf16 v[34:49], v[110:113], v[114:117], v[34:49]
	v_mfma_f32_32x32x16_bf16 v[50:65], v[110:113], v[126:129], v[50:65]
	ds_read_b128 v[110:113], v0 offset:36928
	ds_read_b128 v[114:117], v0 offset:41536
	ds_read_b128 v[118:121], v66 offset:55360
	ds_read_b128 v[130:133], v66 offset:59968
	s_waitcnt vmcnt(9)
	ds_write_b128 v67, v[74:77] offset:4608
	s_waitcnt vmcnt(8)
	ds_write_b128 v67, v[102:105] offset:23040
	global_load_dwordx4 v[74:77], v70, s[26:27]
	global_load_dwordx4 v[102:105], v70, s[2:3]
	s_waitcnt lgkmcnt(3)
	v_mfma_f32_32x32x16_bf16 v[2:17], v[114:117], v[118:121], v[2:17]
	s_waitcnt lgkmcnt(2)
	v_mfma_f32_32x32x16_bf16 v[18:33], v[114:117], v[130:133], v[18:33]
	v_mfma_f32_32x32x16_bf16 v[34:49], v[110:113], v[118:121], v[34:49]
	v_mfma_f32_32x32x16_bf16 v[50:65], v[110:113], v[130:133], v[50:65]
	ds_read_b128 v[110:113], v0 offset:36960
	ds_read_b128 v[118:121], v0 offset:41568
	ds_read_b128 v[122:125], v66 offset:55392
	ds_read_b128 v[126:129], v66 offset:60000
	s_waitcnt vmcnt(9)
	ds_write_b128 v67, v[78:81] offset:9216
	s_waitcnt vmcnt(8)
	ds_write_b128 v67, v[106:109] offset:27648
	global_load_dwordx4 v[78:81], v69, s[26:27]
	global_load_dwordx4 v[106:109], v69, s[2:3]
	s_waitcnt lgkmcnt(3)
	v_mfma_f32_32x32x16_bf16 v[2:17], v[118:121], v[122:125], v[2:17]
	s_waitcnt vmcnt(9)
	ds_write_b128 v67, v[82:85] offset:13824
	s_waitcnt vmcnt(8)
	ds_write_b128 v67, v[94:97] offset:32256
	s_waitcnt lgkmcnt(4)
	v_mfma_f32_32x32x16_bf16 v[18:33], v[118:121], v[126:129], v[18:33]
	v_mfma_f32_32x32x16_bf16 v[34:49], v[110:113], v[122:125], v[34:49]
	v_mfma_f32_32x32x16_bf16 v[50:65], v[110:113], v[126:129], v[50:65]
	s_waitcnt lgkmcnt(0)
	s_barrier
	ds_read_b128 v[82:85], v0
	ds_read_b128 v[94:97], v66 offset:18432
	ds_read_b128 v[110:113], v0 offset:32
	ds_read_b128 v[114:117], v66 offset:18464
	ds_read_b128 v[118:121], v0 offset:4608
	ds_read_b128 v[122:125], v0 offset:4640
	s_waitcnt lgkmcnt(4)
	v_mfma_f32_32x32x16_bf16 v[34:49], v[82:85], v[94:97], v[34:49]
	s_add_u32 s2, s36, 0x1100
	s_addc_u32 s3, s37, 0
	s_add_u32 s26, s0, 0x1100
	s_addc_u32 s27, s1, 0
	ds_read_b128 v[126:129], v66 offset:23072
	s_waitcnt lgkmcnt(2)
	v_mfma_f32_32x32x16_bf16 v[2:17], v[118:121], v[94:97], v[2:17]
	ds_read_b128 v[94:97], v66 offset:23040
	s_waitcnt lgkmcnt(0)
	v_mfma_f32_32x32x16_bf16 v[50:65], v[82:85], v[94:97], v[50:65]
	global_load_dwordx4 v[82:85], v72, s[26:27]
	global_load_dwordx4 v[130:133], v72, s[2:3]
	s_waitcnt vmcnt(9)
	ds_write_b128 v67, v[86:89] offset:36864
	s_waitcnt vmcnt(8)
	ds_write_b128 v67, v[134:137] offset:55296
	v_mfma_f32_32x32x16_bf16 v[18:33], v[118:121], v[94:97], v[18:33]
	global_load_dwordx4 v[86:89], v71, s[26:27]
	global_load_dwordx4 v[94:97], v71, s[2:3]
	v_mfma_f32_32x32x16_bf16 v[2:17], v[122:125], v[114:117], v[2:17]
	v_mfma_f32_32x32x16_bf16 v[18:33], v[122:125], v[126:129], v[18:33]
	v_mfma_f32_32x32x16_bf16 v[34:49], v[110:113], v[114:117], v[34:49]
	v_mfma_f32_32x32x16_bf16 v[50:65], v[110:113], v[126:129], v[50:65]
	ds_read_b128 v[110:113], v0 offset:64
	ds_read_b128 v[114:117], v0 offset:4672
	ds_read_b128 v[118:121], v66 offset:18496
	ds_read_b128 v[134:137], v66 offset:23104
	s_waitcnt vmcnt(9)
	ds_write_b128 v67, v[90:93] offset:41472
	s_waitcnt vmcnt(8)
	ds_write_b128 v67, v[98:101] offset:59904
	global_load_dwordx4 v[90:93], v70, s[26:27]
	global_load_dwordx4 v[98:101], v70, s[2:3]
	s_waitcnt lgkmcnt(3)
	v_mfma_f32_32x32x16_bf16 v[2:17], v[114:117], v[118:121], v[2:17]
	s_waitcnt lgkmcnt(2)
	v_mfma_f32_32x32x16_bf16 v[18:33], v[114:117], v[134:137], v[18:33]
	v_mfma_f32_32x32x16_bf16 v[34:49], v[110:113], v[118:121], v[34:49]
	v_mfma_f32_32x32x16_bf16 v[50:65], v[110:113], v[134:137], v[50:65]
	ds_read_b128 v[110:113], v0 offset:96
	ds_read_b128 v[118:121], v0 offset:4704
	ds_read_b128 v[122:125], v66 offset:18528
	ds_read_b128 v[126:129], v66 offset:23136
	s_waitcnt vmcnt(9)
	ds_write_b128 v67, v[74:77] offset:46080
	s_waitcnt vmcnt(8)
	ds_write_b128 v67, v[102:105] offset:64512
	global_load_dwordx4 v[74:77], v69, s[26:27]
	global_load_dwordx4 v[102:105], v69, s[2:3]
	s_waitcnt lgkmcnt(3)
	v_mfma_f32_32x32x16_bf16 v[2:17], v[118:121], v[122:125], v[2:17]
	s_waitcnt vmcnt(9)
	ds_write_b128 v67, v[78:81] offset:50688
	s_waitcnt vmcnt(8)
	ds_write_b128 v68, v[106:109] offset:13824
	s_waitcnt lgkmcnt(4)
	v_mfma_f32_32x32x16_bf16 v[18:33], v[118:121], v[126:129], v[18:33]
	v_mfma_f32_32x32x16_bf16 v[34:49], v[110:113], v[122:125], v[34:49]
	v_mfma_f32_32x32x16_bf16 v[50:65], v[110:113], v[126:129], v[50:65]
	s_waitcnt lgkmcnt(0)
	s_barrier
; #define GL1_(RA, RB, i) { RA[i] = *(const u32x4*)(ap + (aoff + (i) * astep)); if ((i) < NB) RB[(i) < NB ? (i) : 0] = *(const u32x4*)(bp + (boff + (i) * bstep)); }
; #define LS1_(RA, RB, ST, i) { char* sn_ = lds + (ST) * STAGE; *(u32x4*)(sn_ + wofs + (i) * 32 * LROW) = RA[i]; \
;                               if ((i) < NB) *(u32x4*)(sn_ + STAGE_OP + wofs + (i) * 32 * LROW) = RB[(i) < NB ? (i) : 0]; }
; template <int NJ> DI void gemm_mainloop_reg(const bf16_t* __restrict__ A, int lda, const bf16_t* __restrict__ Bt, int ldb, int K, f32x16 (&acc)[2][NJ], char* lds) {
;     ...
; #pragma unroll
;   for (int i = 0; i < 4; ++i) GL1_(ra0, rb0, i);
;   ap += 128; bp += 128;
; #pragma unroll
;   for (int i = 0; i < 4; ++i) GL1_(ra1, rb1, i);
;   ap += 128; bp += 128;
; #pragma unroll
;   for (int i = 0; i < 4; ++i) LS1_(ra0, rb0, 0, i);
;   __syncthreads();
;   const int nk = K >> 6;
;   for (int kt = 0; kt < nk; kt += 2) {
;     const bool l0 = (kt + 2 < nk), l1 = (kt + 3 < nk);
;     STEP_(0, l0, ra0, rb0, true, ra1, rb1);
;     __syncthreads();
;     STEP_(1, l1, ra1, rb1, l0, ra0, rb0);
;     __syncthreads();
;   }
	ds_read_b128 v[78:81], v0 offset:36864
	ds_read_b128 v[106:109], v66 offset:55296
	ds_read_b128 v[110:113], v0 offset:36896
	ds_read_b128 v[114:117], v66 offset:55328
	ds_read_b128 v[118:121], v0 offset:41472
	ds_read_b128 v[122:125], v0 offset:41504
	s_waitcnt lgkmcnt(4)
	v_mfma_f32_32x32x16_bf16 v[34:49], v[78:81], v[106:109], v[34:49]
	s_add_u32 s2, s36, 0x1180
	s_addc_u32 s3, s37, 0
	s_add_u32 s26, s0, 0x1180
	s_addc_u32 s27, s1, 0
	ds_read_b128 v[126:129], v66 offset:59936
	s_waitcnt lgkmcnt(2)
	v_mfma_f32_32x32x16_bf16 v[2:17], v[118:121], v[106:109], v[2:17]
	ds_read_b128 v[106:109], v66 offset:59904
	s_waitcnt lgkmcnt(0)
	v_mfma_f32_32x32x16_bf16 v[50:65], v[78:81], v[106:109], v[50:65]
	global_load_dwordx4 v[78:81], v72, s[26:27]
	global_load_dwordx4 v[134:137], v72, s[2:3]
	s_waitcnt vmcnt(9)
	ds_write_b128 v67, v[82:85]
	s_waitcnt vmcnt(8)
	ds_write_b128 v67, v[130:133] offset:18432
	v_mfma_f32_32x32x16_bf16 v[18:33], v[118:121], v[106:109], v[18:33]
	global_load_dwordx4 v[82:85], v71, s[26:27]
	global_load_dwordx4 v[106:109], v71, s[2:3]
	v_mfma_f32_32x32x16_bf16 v[2:17], v[122:125], v[114:117], v[2:17]
	v_mfma_f32_32x32x16_bf16 v[18:33], v[122:125], v[126:129], v[18:33]
	v_mfma_f32_32x32x16_bf16 v[34:49], v[110:113], v[114:117], v[34:49]
	v_mfma_f32_32x32x16_bf16 v[50:65], v[110:113], v[126:129], v[50:65]
	ds_read_b128 v[110:113], v0 offset:36928
	ds_read_b128 v[114:117], v0 offset:41536
	ds_read_b128 v[118:121], v66 offset:55360
	ds_read_b128 v[130:133], v66 offset:59968
	s_waitcnt vmcnt(9)
	ds_write_b128 v67, v[86:89] offset:4608
	s_waitcnt vmcnt(8)
	ds_write_b128 v67, v[94:97] offset:23040
	global_load_dwordx4 v[86:89], v70, s[26:27]
	global_load_dwordx4 v[94:97], v70, s[2:3]
	s_waitcnt lgkmcnt(3)
	v_mfma_f32_32x32x16_bf16 v[2:17], v[114:117], v[118:121], v[2:17]
	s_waitcnt lgkmcnt(2)
	v_mfma_f32_32x32x16_bf16 v[18:33], v[114:117], v[130:133], v[18:33]
	v_mfma_f32_32x32x16_bf16 v[34:49], v[110:113], v[118:121], v[34:49]
	v_mfma_f32_32x32x16_bf16 v[50:65], v[110:113], v[130:133], v[50:65]
	ds_read_b128 v[110:113], v0 offset:36960
	ds_read_b128 v[118:121], v0 offset:41568
	ds_read_b128 v[122:125], v66 offset:55392
	ds_read_b128 v[126:129], v66 offset:60000
	s_waitcnt vmcnt(9)
	ds_write_b128 v67, v[90:93] offset:9216
	s_waitcnt vmcnt(8)
	ds_write_b128 v67, v[98:101] offset:27648
	global_load_dwordx4 v[90:93], v69, s[26:27]
	global_load_dwordx4 v[98:101], v69, s[2:3]
	s_waitcnt lgkmcnt(3)
	v_mfma_f32_32x32x16_bf16 v[2:17], v[118:121], v[122:125], v[2:17]
	s_waitcnt vmcnt(9)
	ds_write_b128 v67, v[74:77] offset:13824
	s_waitcnt vmcnt(8)
	ds_write_b128 v67, v[102:105] offset:32256
	s_waitcnt lgkmcnt(4)
	v_mfma_f32_32x32x16_bf16 v[18:33], v[118:121], v[126:129], v[18:33]
	v_mfma_f32_32x32x16_bf16 v[34:49], v[110:113], v[122:125], v[34:49]
	v_mfma_f32_32x32x16_bf16 v[50:65], v[110:113], v[126:129], v[50:65]
	s_waitcnt lgkmcnt(0)
	s_barrier
	ds_read_b128 v[74:77], v0
	ds_read_b128 v[102:105], v66 offset:18432
	ds_read_b128 v[110:113], v0 offset:32
	ds_read_b128 v[114:117], v66 offset:18464
	ds_read_b128 v[118:121], v0 offset:4608
	ds_read_b128 v[122:125], v0 offset:4640
	s_waitcnt lgkmcnt(4)
	v_mfma_f32_32x32x16_bf16 v[34:49], v[74:77], v[102:105], v[34:49]
	s_add_u32 s2, s36, 0x1200
	s_addc_u32 s3, s37, 0
	s_add_u32 s26, s0, 0x1200
	s_addc_u32 s27, s1, 0
	ds_read_b128 v[126:129], v66 offset:23072
	s_waitcnt lgkmcnt(2)
	v_mfma_f32_32x32x16_bf16 v[2:17], v[118:121], v[102:105], v[2:17]
	ds_read_b128 v[102:105], v66 offset:23040
	s_waitcnt lgkmcnt(0)
	v_mfma_f32_32x32x16_bf16 v[50:65], v[74:77], v[102:105], v[50:65]
	global_load_dwordx4 v[74:77], v72, s[26:27]
	global_load_dwordx4 v[130:133], v72, s[2:3]
	s_waitcnt vmcnt(9)
	ds_write_b128 v67, v[78:81] offset:36864
	s_waitcnt vmcnt(8)
	ds_write_b128 v67, v[134:137] offset:55296
	v_mfma_f32_32x32x16_bf16 v[18:33], v[118:121], v[102:105], v[18:33]
	global_load_dwordx4 v[78:81], v71, s[26:27]
	global_load_dwordx4 v[102:105], v71, s[2:3]
	v_mfma_f32_32x32x16_bf16 v[2:17], v[122:125], v[114:117], v[2:17]
	v_mfma_f32_32x32x16_bf16 v[18:33], v[122:125], v[126:129], v[18:33]
	v_mfma_f32_32x32x16_bf16 v[34:49], v[110:113], v[114:117], v[34:49]
	v_mfma_f32_32x32x16_bf16 v[50:65], v[110:113], v[126:129], v[50:65]
	ds_read_b128 v[110:113], v0 offset:64
	ds_read_b128 v[114:117], v0 offset:4672
	ds_read_b128 v[118:121], v66 offset:18496
	ds_read_b128 v[134:137], v66 offset:23104
	s_waitcnt vmcnt(9)
	ds_write_b128 v67, v[82:85] offset:41472
	s_waitcnt vmcnt(8)
	ds_write_b128 v67, v[106:109] offset:59904
	global_load_dwordx4 v[82:85], v70, s[26:27]
	global_load_dwordx4 v[106:109], v70, s[2:3]
	s_waitcnt lgkmcnt(3)
	v_mfma_f32_32x32x16_bf16 v[2:17], v[114:117], v[118:121], v[2:17]
	s_waitcnt lgkmcnt(2)
	v_mfma_f32_32x32x16_bf16 v[18:33], v[114:117], v[134:137], v[18:33]
	v_mfma_f32_32x32x16_bf16 v[34:49], v[110:113], v[118:121], v[34:49]
	v_mfma_f32_32x32x16_bf16 v[50:65], v[110:113], v[134:137], v[50:65]
	ds_read_b128 v[110:113], v0 offset:96
	ds_read_b128 v[118:121], v0 offset:4704
	ds_read_b128 v[122:125], v66 offset:18528
	ds_read_b128 v[126:129], v66 offset:23136
	s_waitcnt vmcnt(9)
	ds_write_b128 v67, v[86:89] offset:46080
	s_waitcnt vmcnt(8)
	ds_write_b128 v67, v[94:97] offset:64512
	global_load_dwordx4 v[86:89], v69, s[26:27]
	global_load_dwordx4 v[94:97], v69, s[2:3]
	s_waitcnt lgkmcnt(3)
	v_mfma_f32_32x32x16_bf16 v[2:17], v[118:121], v[122:125], v[2:17]
	s_waitcnt vmcnt(9)
	ds_write_b128 v67, v[90:93] offset:50688
	s_waitcnt vmcnt(8)
	ds_write_b128 v68, v[98:101] offset:13824
	s_waitcnt lgkmcnt(4)
	v_mfma_f32_32x32x16_bf16 v[18:33], v[118:121], v[126:129], v[18:33]
	v_mfma_f32_32x32x16_bf16 v[34:49], v[110:113], v[122:125], v[34:49]
	v_mfma_f32_32x32x16_bf16 v[50:65], v[110:113], v[126:129], v[50:65]
	s_waitcnt lgkmcnt(0)
	s_barrier
; #define GL1_(RA, RB, i) { RA[i] = *(const u32x4*)(ap + (aoff + (i) * astep)); if ((i) < NB) RB[(i) < NB ? (i) : 0] = *(const u32x4*)(bp + (boff + (i) * bstep)); }
; #define LS1_(RA, RB, ST, i) { char* sn_ = lds + (ST) * STAGE; *(u32x4*)(sn_ + wofs + (i) * 32 * LROW) = RA[i]; \
;                               if ((i) < NB) *(u32x4*)(sn_ + STAGE_OP + wofs + (i) * 32 * LROW) = RB[(i) < NB ? (i) : 0]; }
; template <int NJ> DI void gemm_mainloop_reg(const bf16_t* __restrict__ A, int lda, const bf16_t* __restrict__ Bt, int ldb, int K, f32x16 (&acc)[2][NJ], char* lds) {
;     ...
; #pragma unroll
;   for (int i = 0; i < 4; ++i) GL1_(ra0, rb0, i);
;   ap += 128; bp += 128;
; #pragma unroll
;   for (int i = 0; i < 4; ++i) GL1_(ra1, rb1, i);
;   ap += 128; bp += 128;
; #pragma unroll
;   for (int i = 0; i < 4; ++i) LS1_(ra0, rb0, 0, i);
;   __syncthreads();
;   const int nk = K >> 6;
;   for (int kt = 0; kt < nk; kt += 2) {
;     const bool l0 = (kt + 2 < nk), l1 = (kt + 3 < nk);
;     STEP_(0, l0, ra0, rb0, true, ra1, rb1);
;     __syncthreads();
;     STEP_(1, l1, ra1, rb1, l0, ra0, rb0);
;     __syncthreads();
;   }
	ds_read_b128 v[90:93], v0 offset:36864
	ds_read_b128 v[98:101], v66 offset:55296
	ds_read_b128 v[110:113], v0 offset:36896
	ds_read_b128 v[114:117], v66 offset:55328
	ds_read_b128 v[118:121], v0 offset:41472
	ds_read_b128 v[122:125], v0 offset:41504
	s_waitcnt lgkmcnt(4)
	v_mfma_f32_32x32x16_bf16 v[34:49], v[90:93], v[98:101], v[34:49]
	s_add_u32 s2, s36, 0x1280
	s_addc_u32 s3, s37, 0
	s_add_u32 s26, s0, 0x1280
	s_addc_u32 s27, s1, 0
	ds_read_b128 v[126:129], v66 offset:59936
	s_waitcnt lgkmcnt(2)
	v_mfma_f32_32x32x16_bf16 v[2:17], v[118:121], v[98:101], v[2:17]
	ds_read_b128 v[98:101], v66 offset:59904
	s_waitcnt lgkmcnt(0)
	v_mfma_f32_32x32x16_bf16 v[50:65], v[90:93], v[98:101], v[50:65]
	global_load_dwordx4 v[90:93], v72, s[26:27]
	global_load_dwordx4 v[134:137], v72, s[2:3]
	s_waitcnt vmcnt(9)
	ds_write_b128 v67, v[74:77]
	s_waitcnt vmcnt(8)
	ds_write_b128 v67, v[130:133] offset:18432
	v_mfma_f32_32x32x16_bf16 v[18:33], v[118:121], v[98:101], v[18:33]
	global_load_dwordx4 v[74:77], v71, s[26:27]
	global_load_dwordx4 v[98:101], v71, s[2:3]
	v_mfma_f32_32x32x16_bf16 v[2:17], v[122:125], v[114:117], v[2:17]
	v_mfma_f32_32x32x16_bf16 v[18:33], v[122:125], v[126:129], v[18:33]
	v_mfma_f32_32x32x16_bf16 v[34:49], v[110:113], v[114:117], v[34:49]
	v_mfma_f32_32x32x16_bf16 v[50:65], v[110:113], v[126:129], v[50:65]
	ds_read_b128 v[110:113], v0 offset:36928
	ds_read_b128 v[114:117], v0 offset:41536
	ds_read_b128 v[118:121], v66 offset:55360
	ds_read_b128 v[130:133], v66 offset:59968
	s_waitcnt vmcnt(9)
	ds_write_b128 v67, v[78:81] offset:4608
	s_waitcnt vmcnt(8)
	ds_write_b128 v67, v[102:105] offset:23040
	global_load_dwordx4 v[78:81], v70, s[26:27]
	global_load_dwordx4 v[102:105], v70, s[2:3]
	s_waitcnt lgkmcnt(3)
	v_mfma_f32_32x32x16_bf16 v[2:17], v[114:117], v[118:121], v[2:17]
	s_waitcnt lgkmcnt(2)
	v_mfma_f32_32x32x16_bf16 v[18:33], v[114:117], v[130:133], v[18:33]
	v_mfma_f32_32x32x16_bf16 v[34:49], v[110:113], v[118:121], v[34:49]
	v_mfma_f32_32x32x16_bf16 v[50:65], v[110:113], v[130:133], v[50:65]
	ds_read_b128 v[110:113], v0 offset:36960
	ds_read_b128 v[118:121], v0 offset:41568
	ds_read_b128 v[122:125], v66 offset:55392
	ds_read_b128 v[126:129], v66 offset:60000
	s_waitcnt vmcnt(9)
	ds_write_b128 v67, v[82:85] offset:9216
	s_waitcnt vmcnt(8)
	ds_write_b128 v67, v[106:109] offset:27648
	global_load_dwordx4 v[82:85], v69, s[26:27]
	global_load_dwordx4 v[106:109], v69, s[2:3]
	s_waitcnt lgkmcnt(3)
	v_mfma_f32_32x32x16_bf16 v[2:17], v[118:121], v[122:125], v[2:17]
	s_waitcnt vmcnt(9)
	ds_write_b128 v67, v[86:89] offset:13824
	s_waitcnt vmcnt(8)
	ds_write_b128 v67, v[94:97] offset:32256
	s_waitcnt lgkmcnt(4)
	v_mfma_f32_32x32x16_bf16 v[18:33], v[118:121], v[126:129], v[18:33]
	v_mfma_f32_32x32x16_bf16 v[34:49], v[110:113], v[122:125], v[34:49]
	v_mfma_f32_32x32x16_bf16 v[50:65], v[110:113], v[126:129], v[50:65]
	s_waitcnt lgkmcnt(0)
	s_barrier
	ds_read_b128 v[86:89], v0
	ds_read_b128 v[94:97], v66 offset:18432
	ds_read_b128 v[110:113], v0 offset:32
	ds_read_b128 v[114:117], v66 offset:18464
	ds_read_b128 v[118:121], v0 offset:4608
	ds_read_b128 v[122:125], v0 offset:4640
	s_waitcnt lgkmcnt(4)
	v_mfma_f32_32x32x16_bf16 v[34:49], v[86:89], v[94:97], v[34:49]
	s_add_u32 s2, s36, 0x1300
	s_addc_u32 s3, s37, 0
	s_add_u32 s26, s0, 0x1300
	s_addc_u32 s27, s1, 0
	ds_read_b128 v[126:129], v66 offset:23072
	s_waitcnt lgkmcnt(2)
	v_mfma_f32_32x32x16_bf16 v[2:17], v[118:121], v[94:97], v[2:17]
	ds_read_b128 v[94:97], v66 offset:23040
	s_waitcnt lgkmcnt(0)
	v_mfma_f32_32x32x16_bf16 v[50:65], v[86:89], v[94:97], v[50:65]
	global_load_dwordx4 v[86:89], v72, s[26:27]
	global_load_dwordx4 v[130:133], v72, s[2:3]
	s_waitcnt vmcnt(9)
	ds_write_b128 v67, v[90:93] offset:36864
	s_waitcnt vmcnt(8)
	ds_write_b128 v67, v[134:137] offset:55296
	v_mfma_f32_32x32x16_bf16 v[18:33], v[118:121], v[94:97], v[18:33]
	global_load_dwordx4 v[90:93], v71, s[26:27]
	global_load_dwordx4 v[94:97], v71, s[2:3]
	v_mfma_f32_32x32x16_bf16 v[2:17], v[122:125], v[114:117], v[2:17]
	v_mfma_f32_32x32x16_bf16 v[18:33], v[122:125], v[126:129], v[18:33]
	v_mfma_f32_32x32x16_bf16 v[34:49], v[110:113], v[114:117], v[34:49]
	v_mfma_f32_32x32x16_bf16 v[50:65], v[110:113], v[126:129], v[50:65]
	ds_read_b128 v[110:113], v0 offset:64
	ds_read_b128 v[114:117], v0 offset:4672
	ds_read_b128 v[118:121], v66 offset:18496
	ds_read_b128 v[134:137], v66 offset:23104
	s_waitcnt vmcnt(9)
	ds_write_b128 v67, v[74:77] offset:41472
	s_waitcnt vmcnt(8)
	ds_write_b128 v67, v[98:101] offset:59904
	global_load_dwordx4 v[74:77], v70, s[26:27]
	global_load_dwordx4 v[98:101], v70, s[2:3]
	s_waitcnt lgkmcnt(3)
	v_mfma_f32_32x32x16_bf16 v[2:17], v[114:117], v[118:121], v[2:17]
	s_waitcnt lgkmcnt(2)
	v_mfma_f32_32x32x16_bf16 v[18:33], v[114:117], v[134:137], v[18:33]
	v_mfma_f32_32x32x16_bf16 v[34:49], v[110:113], v[118:121], v[34:49]
	v_mfma_f32_32x32x16_bf16 v[50:65], v[110:113], v[134:137], v[50:65]
	ds_read_b128 v[110:113], v0 offset:96
	ds_read_b128 v[118:121], v0 offset:4704
	ds_read_b128 v[122:125], v66 offset:18528
	ds_read_b128 v[126:129], v66 offset:23136
	s_waitcnt vmcnt(9)
	ds_write_b128 v67, v[78:81] offset:46080
	s_waitcnt vmcnt(8)
	ds_write_b128 v67, v[102:105] offset:64512
	global_load_dwordx4 v[78:81], v69, s[26:27]
	global_load_dwordx4 v[102:105], v69, s[2:3]
	s_waitcnt lgkmcnt(3)
	v_mfma_f32_32x32x16_bf16 v[2:17], v[118:121], v[122:125], v[2:17]
	s_waitcnt vmcnt(9)
	ds_write_b128 v67, v[82:85] offset:50688
	s_waitcnt vmcnt(8)
	ds_write_b128 v68, v[106:109] offset:13824
	s_waitcnt lgkmcnt(4)
	v_mfma_f32_32x32x16_bf16 v[18:33], v[118:121], v[126:129], v[18:33]
	v_mfma_f32_32x32x16_bf16 v[34:49], v[110:113], v[122:125], v[34:49]
	v_mfma_f32_32x32x16_bf16 v[50:65], v[110:113], v[126:129], v[50:65]
	s_waitcnt lgkmcnt(0)
	s_barrier
; #define GL1_(RA, RB, i) { RA[i] = *(const u32x4*)(ap + (aoff + (i) * astep)); if ((i) < NB) RB[(i) < NB ? (i) : 0] = *(const u32x4*)(bp + (boff + (i) * bstep)); }
; #define LS1_(RA, RB, ST, i) { char* sn_ = lds + (ST) * STAGE; *(u32x4*)(sn_ + wofs + (i) * 32 * LROW) = RA[i]; \
;                               if ((i) < NB) *(u32x4*)(sn_ + STAGE_OP + wofs + (i) * 32 * LROW) = RB[(i) < NB ? (i) : 0]; }
; template <int NJ> DI void gemm_mainloop_reg(const bf16_t* __restrict__ A, int lda, const bf16_t* __restrict__ Bt, int ldb, int K, f32x16 (&acc)[2][NJ], char* lds) {
;     ...
; #pragma unroll
;   for (int i = 0; i < 4; ++i) GL1_(ra0, rb0, i);
;   ap += 128; bp += 128;
; #pragma unroll
;   for (int i = 0; i < 4; ++i) GL1_(ra1, rb1, i);
;   ap += 128; bp += 128;
; #pragma unroll
;   for (int i = 0; i < 4; ++i) LS1_(ra0, rb0, 0, i);
;   __syncthreads();
;   const int nk = K >> 6;
;   for (int kt = 0; kt < nk; kt += 2) {
;     const bool l0 = (kt + 2 < nk), l1 = (kt + 3 < nk);
;     STEP_(0, l0, ra0, rb0, true, ra1, rb1);
;     __syncthreads();
;     STEP_(1, l1, ra1, rb1, l0, ra0, rb0);
;     __syncthreads();
;   }
	ds_read_b128 v[82:85], v0 offset:36864
	ds_read_b128 v[106:109], v66 offset:55296
	ds_read_b128 v[110:113], v0 offset:36896
	ds_read_b128 v[114:117], v66 offset:55328
	ds_read_b128 v[118:121], v0 offset:41472
	ds_read_b128 v[122:125], v0 offset:41504
	s_waitcnt lgkmcnt(4)
	v_mfma_f32_32x32x16_bf16 v[34:49], v[82:85], v[106:109], v[34:49]
	s_add_u32 s2, s36, 0x1380
	s_addc_u32 s3, s37, 0
	s_add_u32 s26, s0, 0x1380
	s_addc_u32 s27, s1, 0
	ds_read_b128 v[126:129], v66 offset:59936
	s_waitcnt lgkmcnt(2)
	v_mfma_f32_32x32x16_bf16 v[2:17], v[118:121], v[106:109], v[2:17]
	ds_read_b128 v[106:109], v66 offset:59904
	s_waitcnt lgkmcnt(0)
	v_mfma_f32_32x32x16_bf16 v[50:65], v[82:85], v[106:109], v[50:65]
	global_load_dwordx4 v[82:85], v72, s[26:27]
	global_load_dwordx4 v[134:137], v72, s[2:3]
	s_waitcnt vmcnt(9)
	ds_write_b128 v67, v[86:89]
	s_waitcnt vmcnt(8)
	ds_write_b128 v67, v[130:133] offset:18432
	v_mfma_f32_32x32x16_bf16 v[18:33], v[118:121], v[106:109], v[18:33]
	global_load_dwordx4 v[86:89], v71, s[26:27]
	global_load_dwordx4 v[106:109], v71, s[2:3]
	v_mfma_f32_32x32x16_bf16 v[2:17], v[122:125], v[114:117], v[2:17]
	v_mfma_f32_32x32x16_bf16 v[18:33], v[122:125], v[126:129], v[18:33]
	v_mfma_f32_32x32x16_bf16 v[34:49], v[110:113], v[114:117], v[34:49]
	v_mfma_f32_32x32x16_bf16 v[50:65], v[110:113], v[126:129], v[50:65]
	ds_read_b128 v[110:113], v0 offset:36928
	ds_read_b128 v[114:117], v0 offset:41536
	ds_read_b128 v[118:121], v66 offset:55360
	ds_read_b128 v[130:133], v66 offset:59968
	s_waitcnt vmcnt(9)
	ds_write_b128 v67, v[90:93] offset:4608
	s_waitcnt vmcnt(8)
	ds_write_b128 v67, v[94:97] offset:23040
	global_load_dwordx4 v[90:93], v70, s[26:27]
	global_load_dwordx4 v[94:97], v70, s[2:3]
	s_waitcnt lgkmcnt(3)
	v_mfma_f32_32x32x16_bf16 v[2:17], v[114:117], v[118:121], v[2:17]
	s_waitcnt lgkmcnt(2)
	v_mfma_f32_32x32x16_bf16 v[18:33], v[114:117], v[130:133], v[18:33]
	v_mfma_f32_32x32x16_bf16 v[34:49], v[110:113], v[118:121], v[34:49]
	v_mfma_f32_32x32x16_bf16 v[50:65], v[110:113], v[130:133], v[50:65]
	ds_read_b128 v[110:113], v0 offset:36960
	ds_read_b128 v[118:121], v0 offset:41568
	ds_read_b128 v[122:125], v66 offset:55392
	ds_read_b128 v[126:129], v66 offset:60000
	s_waitcnt vmcnt(9)
	ds_write_b128 v67, v[74:77] offset:9216
	s_waitcnt vmcnt(8)
	ds_write_b128 v67, v[98:101] offset:27648
	global_load_dwordx4 v[74:77], v69, s[26:27]
	global_load_dwordx4 v[98:101], v69, s[2:3]
	s_waitcnt lgkmcnt(3)
	v_mfma_f32_32x32x16_bf16 v[2:17], v[118:121], v[122:125], v[2:17]
	s_waitcnt vmcnt(9)
	ds_write_b128 v67, v[78:81] offset:13824
	s_waitcnt vmcnt(8)
	ds_write_b128 v67, v[102:105] offset:32256
	s_waitcnt lgkmcnt(4)
	v_mfma_f32_32x32x16_bf16 v[18:33], v[118:121], v[126:129], v[18:33]
	v_mfma_f32_32x32x16_bf16 v[34:49], v[110:113], v[122:125], v[34:49]
	v_mfma_f32_32x32x16_bf16 v[50:65], v[110:113], v[126:129], v[50:65]
	s_waitcnt lgkmcnt(0)
	s_barrier
	ds_read_b128 v[78:81], v0
	ds_read_b128 v[102:105], v66 offset:18432
	ds_read_b128 v[110:113], v0 offset:32
	ds_read_b128 v[114:117], v66 offset:18464
	ds_read_b128 v[118:121], v0 offset:4608
	ds_read_b128 v[122:125], v0 offset:4640
	s_waitcnt lgkmcnt(4)
	v_mfma_f32_32x32x16_bf16 v[34:49], v[78:81], v[102:105], v[34:49]
	s_add_u32 s2, s36, 0x1400
	s_addc_u32 s3, s37, 0
	s_add_u32 s26, s0, 0x1400
	s_addc_u32 s27, s1, 0
	ds_read_b128 v[126:129], v66 offset:23072
	s_waitcnt lgkmcnt(2)
	v_mfma_f32_32x32x16_bf16 v[2:17], v[118:121], v[102:105], v[2:17]
	ds_read_b128 v[102:105], v66 offset:23040
	s_waitcnt lgkmcnt(0)
	v_mfma_f32_32x32x16_bf16 v[50:65], v[78:81], v[102:105], v[50:65]
	global_load_dwordx4 v[78:81], v72, s[26:27]
	global_load_dwordx4 v[130:133], v72, s[2:3]
	s_waitcnt vmcnt(9)
	ds_write_b128 v67, v[82:85] offset:36864
	s_waitcnt vmcnt(8)
	ds_write_b128 v67, v[134:137] offset:55296
	v_mfma_f32_32x32x16_bf16 v[18:33], v[118:121], v[102:105], v[18:33]
	global_load_dwordx4 v[82:85], v71, s[26:27]
	global_load_dwordx4 v[102:105], v71, s[2:3]
	v_mfma_f32_32x32x16_bf16 v[2:17], v[122:125], v[114:117], v[2:17]
	v_mfma_f32_32x32x16_bf16 v[18:33], v[122:125], v[126:129], v[18:33]
	v_mfma_f32_32x32x16_bf16 v[34:49], v[110:113], v[114:117], v[34:49]
	v_mfma_f32_32x32x16_bf16 v[50:65], v[110:113], v[126:129], v[50:65]
	ds_read_b128 v[110:113], v0 offset:64
	ds_read_b128 v[114:117], v0 offset:4672
	ds_read_b128 v[118:121], v66 offset:18496
	ds_read_b128 v[134:137], v66 offset:23104
	s_waitcnt vmcnt(9)
	ds_write_b128 v67, v[86:89] offset:41472
	s_waitcnt vmcnt(8)
	ds_write_b128 v67, v[106:109] offset:59904
	global_load_dwordx4 v[86:89], v70, s[26:27]
	global_load_dwordx4 v[106:109], v70, s[2:3]
	s_waitcnt lgkmcnt(3)
	v_mfma_f32_32x32x16_bf16 v[2:17], v[114:117], v[118:121], v[2:17]
	s_waitcnt lgkmcnt(2)
	v_mfma_f32_32x32x16_bf16 v[18:33], v[114:117], v[134:137], v[18:33]
	v_mfma_f32_32x32x16_bf16 v[34:49], v[110:113], v[118:121], v[34:49]
	v_mfma_f32_32x32x16_bf16 v[50:65], v[110:113], v[134:137], v[50:65]
	ds_read_b128 v[110:113], v0 offset:96
	ds_read_b128 v[118:121], v0 offset:4704
	ds_read_b128 v[122:125], v66 offset:18528
	ds_read_b128 v[126:129], v66 offset:23136
	s_waitcnt vmcnt(9)
	ds_write_b128 v67, v[90:93] offset:46080
	s_waitcnt vmcnt(8)
	ds_write_b128 v67, v[94:97] offset:64512
	global_load_dwordx4 v[90:93], v69, s[26:27]
	global_load_dwordx4 v[94:97], v69, s[2:3]
	s_waitcnt lgkmcnt(3)
	v_mfma_f32_32x32x16_bf16 v[2:17], v[118:121], v[122:125], v[2:17]
	s_waitcnt vmcnt(9)
	ds_write_b128 v67, v[74:77] offset:50688
	s_waitcnt vmcnt(8)
	ds_write_b128 v68, v[98:101] offset:13824
	s_waitcnt lgkmcnt(4)
	v_mfma_f32_32x32x16_bf16 v[18:33], v[118:121], v[126:129], v[18:33]
	v_mfma_f32_32x32x16_bf16 v[34:49], v[110:113], v[122:125], v[34:49]
	v_mfma_f32_32x32x16_bf16 v[50:65], v[110:113], v[126:129], v[50:65]
	s_waitcnt lgkmcnt(0)
	s_barrier
; #define GL1_(RA, RB, i) { RA[i] = *(const u32x4*)(ap + (aoff + (i) * astep)); if ((i) < NB) RB[(i) < NB ? (i) : 0] = *(const u32x4*)(bp + (boff + (i) * bstep)); }
; #define LS1_(RA, RB, ST, i) { char* sn_ = lds + (ST) * STAGE; *(u32x4*)(sn_ + wofs + (i) * 32 * LROW) = RA[i]; \
;                               if ((i) < NB) *(u32x4*)(sn_ + STAGE_OP + wofs + (i) * 32 * LROW) = RB[(i) < NB ? (i) : 0]; }
; template <int NJ> DI void gemm_mainloop_reg(const bf16_t* __restrict__ A, int lda, const bf16_t* __restrict__ Bt, int ldb, int K, f32x16 (&acc)[2][NJ], char* lds) {
;     ...
; #pragma unroll
;   for (int i = 0; i < 4; ++i) GL1_(ra0, rb0, i);
;   ap += 128; bp += 128;
; #pragma unroll
;   for (int i = 0; i < 4; ++i) GL1_(ra1, rb1, i);
;   ap += 128; bp += 128;
; #pragma unroll
;   for (int i = 0; i < 4; ++i) LS1_(ra0, rb0, 0, i);
;   __syncthreads();
;   const int nk = K >> 6;
;   for (int kt = 0; kt < nk; kt += 2) {
;     const bool l0 = (kt + 2 < nk), l1 = (kt + 3 < nk);
;     STEP_(0, l0, ra0, rb0, true, ra1, rb1);
;     __syncthreads();
;     STEP_(1, l1, ra1, rb1, l0, ra0, rb0);
;     __syncthreads();
;   }
	ds_read_b128 v[74:77], v0 offset:36864
	ds_read_b128 v[98:101], v66 offset:55296
	ds_read_b128 v[110:113], v0 offset:36896
	ds_read_b128 v[114:117], v66 offset:55328
	ds_read_b128 v[118:121], v0 offset:41472
	ds_read_b128 v[122:125], v0 offset:41504
	s_waitcnt lgkmcnt(4)
	v_mfma_f32_32x32x16_bf16 v[34:49], v[74:77], v[98:101], v[34:49]
	s_add_u32 s2, s36, 0x1480
	s_addc_u32 s3, s37, 0
	s_add_u32 s26, s0, 0x1480
	s_addc_u32 s27, s1, 0
	ds_read_b128 v[126:129], v66 offset:59936
	s_waitcnt lgkmcnt(2)
	v_mfma_f32_32x32x16_bf16 v[2:17], v[118:121], v[98:101], v[2:17]
	ds_read_b128 v[98:101], v66 offset:59904
	s_waitcnt lgkmcnt(0)
	v_mfma_f32_32x32x16_bf16 v[50:65], v[74:77], v[98:101], v[50:65]
	global_load_dwordx4 v[74:77], v72, s[26:27]
	global_load_dwordx4 v[134:137], v72, s[2:3]
	s_waitcnt vmcnt(9)
	ds_write_b128 v67, v[78:81]
	s_waitcnt vmcnt(8)
	ds_write_b128 v67, v[130:133] offset:18432
	v_mfma_f32_32x32x16_bf16 v[18:33], v[118:121], v[98:101], v[18:33]
	global_load_dwordx4 v[78:81], v71, s[26:27]
	global_load_dwordx4 v[98:101], v71, s[2:3]
	v_mfma_f32_32x32x16_bf16 v[2:17], v[122:125], v[114:117], v[2:17]
	v_mfma_f32_32x32x16_bf16 v[18:33], v[122:125], v[126:129], v[18:33]
	v_mfma_f32_32x32x16_bf16 v[34:49], v[110:113], v[114:117], v[34:49]
	v_mfma_f32_32x32x16_bf16 v[50:65], v[110:113], v[126:129], v[50:65]
	ds_read_b128 v[110:113], v0 offset:36928
	ds_read_b128 v[114:117], v0 offset:41536
	ds_read_b128 v[118:121], v66 offset:55360
	ds_read_b128 v[130:133], v66 offset:59968
	s_waitcnt vmcnt(9)
	ds_write_b128 v67, v[82:85] offset:4608
	s_waitcnt vmcnt(8)
	ds_write_b128 v67, v[102:105] offset:23040
	global_load_dwordx4 v[82:85], v70, s[26:27]
	global_load_dwordx4 v[102:105], v70, s[2:3]
	s_waitcnt lgkmcnt(3)
	v_mfma_f32_32x32x16_bf16 v[2:17], v[114:117], v[118:121], v[2:17]
	s_waitcnt lgkmcnt(2)
	v_mfma_f32_32x32x16_bf16 v[18:33], v[114:117], v[130:133], v[18:33]
	v_mfma_f32_32x32x16_bf16 v[34:49], v[110:113], v[118:121], v[34:49]
	v_mfma_f32_32x32x16_bf16 v[50:65], v[110:113], v[130:133], v[50:65]
	ds_read_b128 v[110:113], v0 offset:36960
	ds_read_b128 v[118:121], v0 offset:41568
	ds_read_b128 v[122:125], v66 offset:55392
	ds_read_b128 v[126:129], v66 offset:60000
	s_waitcnt vmcnt(9)
	ds_write_b128 v67, v[86:89] offset:9216
	s_waitcnt vmcnt(8)
	ds_write_b128 v67, v[106:109] offset:27648
	global_load_dwordx4 v[86:89], v69, s[26:27]
	global_load_dwordx4 v[106:109], v69, s[2:3]
	s_waitcnt lgkmcnt(3)
	v_mfma_f32_32x32x16_bf16 v[2:17], v[118:121], v[122:125], v[2:17]
	s_waitcnt vmcnt(9)
	ds_write_b128 v67, v[90:93] offset:13824
	s_waitcnt vmcnt(8)
	ds_write_b128 v67, v[94:97] offset:32256
	s_waitcnt lgkmcnt(4)
	v_mfma_f32_32x32x16_bf16 v[18:33], v[118:121], v[126:129], v[18:33]
	v_mfma_f32_32x32x16_bf16 v[34:49], v[110:113], v[122:125], v[34:49]
	v_mfma_f32_32x32x16_bf16 v[50:65], v[110:113], v[126:129], v[50:65]
	s_waitcnt lgkmcnt(0)
	s_barrier
	ds_read_b128 v[90:93], v0
	ds_read_b128 v[94:97], v66 offset:18432
	ds_read_b128 v[110:113], v0 offset:32
	ds_read_b128 v[114:117], v66 offset:18464
	ds_read_b128 v[118:121], v0 offset:4608
	ds_read_b128 v[122:125], v0 offset:4640
	s_waitcnt lgkmcnt(4)
	v_mfma_f32_32x32x16_bf16 v[34:49], v[90:93], v[94:97], v[34:49]
	s_add_u32 s2, s36, 0x1500
	s_addc_u32 s3, s37, 0
	s_add_u32 s26, s0, 0x1500
	s_addc_u32 s27, s1, 0
	ds_read_b128 v[126:129], v66 offset:23072
	s_waitcnt lgkmcnt(2)
	v_mfma_f32_32x32x16_bf16 v[2:17], v[118:121], v[94:97], v[2:17]
	ds_read_b128 v[94:97], v66 offset:23040
	s_waitcnt lgkmcnt(0)
	v_mfma_f32_32x32x16_bf16 v[50:65], v[90:93], v[94:97], v[50:65]
	global_load_dwordx4 v[90:93], v72, s[26:27]
	global_load_dwordx4 v[130:133], v72, s[2:3]
	s_waitcnt vmcnt(9)
	ds_write_b128 v67, v[74:77] offset:36864
	s_waitcnt vmcnt(8)
	ds_write_b128 v67, v[134:137] offset:55296
	v_mfma_f32_32x32x16_bf16 v[18:33], v[118:121], v[94:97], v[18:33]
	global_load_dwordx4 v[74:77], v71, s[26:27]
	global_load_dwordx4 v[94:97], v71, s[2:3]
	v_mfma_f32_32x32x16_bf16 v[2:17], v[122:125], v[114:117], v[2:17]
	v_mfma_f32_32x32x16_bf16 v[18:33], v[122:125], v[126:129], v[18:33]
	v_mfma_f32_32x32x16_bf16 v[34:49], v[110:113], v[114:117], v[34:49]
	v_mfma_f32_32x32x16_bf16 v[50:65], v[110:113], v[126:129], v[50:65]
	ds_read_b128 v[110:113], v0 offset:64
	ds_read_b128 v[114:117], v0 offset:4672
	ds_read_b128 v[118:121], v66 offset:18496
	ds_read_b128 v[134:137], v66 offset:23104
	s_waitcnt vmcnt(9)
	ds_write_b128 v67, v[78:81] offset:41472
	s_waitcnt vmcnt(8)
	ds_write_b128 v67, v[98:101] offset:59904
	global_load_dwordx4 v[78:81], v70, s[26:27]
	global_load_dwordx4 v[98:101], v70, s[2:3]
	s_waitcnt lgkmcnt(3)
	v_mfma_f32_32x32x16_bf16 v[2:17], v[114:117], v[118:121], v[2:17]
	s_waitcnt lgkmcnt(2)
	v_mfma_f32_32x32x16_bf16 v[18:33], v[114:117], v[134:137], v[18:33]
	v_mfma_f32_32x32x16_bf16 v[34:49], v[110:113], v[118:121], v[34:49]
	v_mfma_f32_32x32x16_bf16 v[50:65], v[110:113], v[134:137], v[50:65]
	ds_read_b128 v[110:113], v0 offset:96
	ds_read_b128 v[118:121], v0 offset:4704
	ds_read_b128 v[122:125], v66 offset:18528
	ds_read_b128 v[126:129], v66 offset:23136
	s_waitcnt vmcnt(9)
	ds_write_b128 v67, v[82:85] offset:46080
	s_waitcnt vmcnt(8)
	ds_write_b128 v67, v[102:105] offset:64512
	global_load_dwordx4 v[82:85], v69, s[26:27]
	global_load_dwordx4 v[102:105], v69, s[2:3]
	s_waitcnt lgkmcnt(3)
	v_mfma_f32_32x32x16_bf16 v[2:17], v[118:121], v[122:125], v[2:17]
	s_waitcnt vmcnt(9)
	ds_write_b128 v67, v[86:89] offset:50688
	s_waitcnt vmcnt(8)
	ds_write_b128 v68, v[106:109] offset:13824
	s_waitcnt lgkmcnt(4)
	v_mfma_f32_32x32x16_bf16 v[18:33], v[118:121], v[126:129], v[18:33]
	v_mfma_f32_32x32x16_bf16 v[34:49], v[110:113], v[122:125], v[34:49]
	v_mfma_f32_32x32x16_bf16 v[50:65], v[110:113], v[126:129], v[50:65]
	s_waitcnt lgkmcnt(0)
	s_barrier
; #define GL1_(RA, RB, i) { RA[i] = *(const u32x4*)(ap + (aoff + (i) * astep)); if ((i) < NB) RB[(i) < NB ? (i) : 0] = *(const u32x4*)(bp + (boff + (i) * bstep)); }
; #define LS1_(RA, RB, ST, i) { char* sn_ = lds + (ST) * STAGE; *(u32x4*)(sn_ + wofs + (i) * 32 * LROW) = RA[i]; \
;                               if ((i) < NB) *(u32x4*)(sn_ + STAGE_OP + wofs + (i) * 32 * LROW) = RB[(i) < NB ? (i) : 0]; }
; template <int NJ> DI void gemm_mainloop_reg(const bf16_t* __restrict__ A, int lda, const bf16_t* __restrict__ Bt, int ldb, int K, f32x16 (&acc)[2][NJ], char* lds) {
;     ...
; #pragma unroll
;   for (int i = 0; i < 4; ++i) GL1_(ra0, rb0, i);
;   ap += 128; bp += 128;
; #pragma unroll
;   for (int i = 0; i < 4; ++i) GL1_(ra1, rb1, i);
;   ap += 128; bp += 128;
; #pragma unroll
;   for (int i = 0; i < 4; ++i) LS1_(ra0, rb0, 0, i);
;   __syncthreads();
;   const int nk = K >> 6;
;   for (int kt = 0; kt < nk; kt += 2) {
;     const bool l0 = (kt + 2 < nk), l1 = (kt + 3 < nk);
;     STEP_(0, l0, ra0, rb0, true, ra1, rb1);
;     __syncthreads();
;     STEP_(1, l1, ra1, rb1, l0, ra0, rb0);
;     __syncthreads();
;   }
	ds_read_b128 v[86:89], v0 offset:36864
	ds_read_b128 v[106:109], v66 offset:55296
	ds_read_b128 v[110:113], v0 offset:41472
	s_waitcnt lgkmcnt(1)
	v_mfma_f32_32x32x16_bf16 v[34:49], v[86:89], v[106:109], v[34:49]
	s_add_u32 s2, s36, 0x1580
	s_addc_u32 s3, s37, 0
	s_add_u32 s0, s0, 0x1580
	s_addc_u32 s1, s1, 0
	s_waitcnt lgkmcnt(0)
	v_mfma_f32_32x32x16_bf16 v[2:17], v[110:113], v[106:109], v[2:17]
	ds_read_b128 v[106:109], v66 offset:59904
	s_waitcnt lgkmcnt(0)
	v_mfma_f32_32x32x16_bf16 v[50:65], v[86:89], v[106:109], v[50:65]
	global_load_dwordx4 v[86:89], v72, s[0:1]
	global_load_dwordx4 v[114:117], v72, s[2:3]
	ds_read_b128 v[118:121], v0 offset:36896
	ds_read_b128 v[122:125], v66 offset:55328
	ds_read_b128 v[126:129], v0 offset:41504
	ds_read_b128 v[134:137], v66 offset:59936
	s_waitcnt vmcnt(9)
	ds_write_b128 v67, v[90:93]
	s_waitcnt vmcnt(8)
	ds_write_b128 v67, v[130:133] offset:18432
	v_mfma_f32_32x32x16_bf16 v[18:33], v[110:113], v[106:109], v[18:33]
	global_load_dwordx4 v[90:93], v71, s[0:1]
	global_load_dwordx4 v[106:109], v71, s[2:3]
	s_waitcnt lgkmcnt(3)
	v_mfma_f32_32x32x16_bf16 v[2:17], v[126:129], v[122:125], v[2:17]
	s_waitcnt lgkmcnt(2)
	v_mfma_f32_32x32x16_bf16 v[18:33], v[126:129], v[134:137], v[18:33]
	v_mfma_f32_32x32x16_bf16 v[34:49], v[118:121], v[122:125], v[34:49]
	v_mfma_f32_32x32x16_bf16 v[50:65], v[118:121], v[134:137], v[50:65]
	ds_read_b128 v[110:113], v0 offset:36928
	ds_read_b128 v[118:121], v0 offset:41536
	ds_read_b128 v[122:125], v66 offset:55360
	ds_read_b128 v[130:133], v66 offset:59968
	s_waitcnt vmcnt(9)
	ds_write_b128 v67, v[74:77] offset:4608
	s_waitcnt vmcnt(8)
	ds_write_b128 v67, v[94:97] offset:23040
	global_load_dwordx4 v[72:75], v70, s[0:1]
	global_load_dwordx4 v[94:97], v70, s[2:3]
	s_waitcnt lgkmcnt(3)
	v_mfma_f32_32x32x16_bf16 v[2:17], v[118:121], v[122:125], v[2:17]
	s_waitcnt lgkmcnt(2)
	v_mfma_f32_32x32x16_bf16 v[18:33], v[118:121], v[130:133], v[18:33]
	v_mfma_f32_32x32x16_bf16 v[34:49], v[110:113], v[122:125], v[34:49]
	v_mfma_f32_32x32x16_bf16 v[50:65], v[110:113], v[130:133], v[50:65]
	ds_read_b128 v[110:113], v0 offset:36960
	ds_read_b128 v[122:125], v0 offset:41568
	ds_read_b128 v[126:129], v66 offset:55392
	ds_read_b128 v[134:137], v66 offset:60000
	s_waitcnt vmcnt(9)
	ds_write_b128 v67, v[78:81] offset:9216
	s_waitcnt vmcnt(8)
	ds_write_b128 v67, v[98:101] offset:27648
	global_load_dwordx4 v[76:79], v69, s[0:1]
	global_load_dwordx4 v[98:101], v69, s[2:3]
	s_waitcnt lgkmcnt(3)
	v_mfma_f32_32x32x16_bf16 v[2:17], v[122:125], v[126:129], v[2:17]
	s_waitcnt vmcnt(9)
	ds_write_b128 v67, v[82:85] offset:13824
	s_waitcnt vmcnt(8)
	ds_write_b128 v67, v[102:105] offset:32256
	s_waitcnt lgkmcnt(4)
	v_mfma_f32_32x32x16_bf16 v[18:33], v[122:125], v[134:137], v[18:33]
	v_mfma_f32_32x32x16_bf16 v[34:49], v[110:113], v[126:129], v[34:49]
	v_mfma_f32_32x32x16_bf16 v[50:65], v[110:113], v[134:137], v[50:65]
	s_waitcnt lgkmcnt(0)
	s_barrier
	ds_read_b128 v[80:83], v0
	ds_read_b128 v[102:105], v66 offset:18432
	ds_read_b128 v[110:113], v0 offset:4608
	s_waitcnt lgkmcnt(1)
	v_mfma_f32_32x32x16_bf16 v[34:49], v[80:83], v[102:105], v[34:49]
	s_waitcnt lgkmcnt(0)
	v_mfma_f32_32x32x16_bf16 v[2:17], v[110:113], v[102:105], v[2:17]
	ds_read_b128 v[102:105], v66 offset:23040
	s_waitcnt lgkmcnt(0)
	v_mfma_f32_32x32x16_bf16 v[18:33], v[110:113], v[102:105], v[18:33]
	v_mfma_f32_32x32x16_bf16 v[50:65], v[80:83], v[102:105], v[50:65]
	ds_read_b128 v[80:83], v0 offset:32
	ds_read_b128 v[118:121], v66 offset:18464
	ds_read_b128 v[122:125], v0 offset:4640
	ds_read_b128 v[126:129], v66 offset:23072
	s_waitcnt vmcnt(7)
	ds_write_b128 v67, v[86:89] offset:36864
	s_waitcnt vmcnt(6)
	ds_write_b128 v67, v[114:117] offset:55296
	s_waitcnt lgkmcnt(3)
	v_mfma_f32_32x32x16_bf16 v[2:17], v[122:125], v[118:121], v[2:17]
	s_waitcnt lgkmcnt(2)
	v_mfma_f32_32x32x16_bf16 v[18:33], v[122:125], v[126:129], v[18:33]
	v_mfma_f32_32x32x16_bf16 v[34:49], v[80:83], v[118:121], v[34:49]
	v_mfma_f32_32x32x16_bf16 v[50:65], v[80:83], v[126:129], v[50:65]
	ds_read_b128 v[80:83], v0 offset:64
	ds_read_b128 v[84:87], v0 offset:4672
	ds_read_b128 v[102:105], v66 offset:18496
	ds_read_b128 v[110:113], v66 offset:23104
	s_waitcnt vmcnt(5)
	ds_write_b128 v67, v[90:93] offset:41472
	s_waitcnt vmcnt(4)
	ds_write_b128 v67, v[106:109] offset:59904
	s_waitcnt lgkmcnt(3)
	v_mfma_f32_32x32x16_bf16 v[2:17], v[84:87], v[102:105], v[2:17]
	s_waitcnt lgkmcnt(2)
	v_mfma_f32_32x32x16_bf16 v[18:33], v[84:87], v[110:113], v[18:33]
	v_mfma_f32_32x32x16_bf16 v[34:49], v[80:83], v[102:105], v[34:49]
	v_mfma_f32_32x32x16_bf16 v[50:65], v[80:83], v[110:113], v[50:65]
	ds_read_b128 v[80:83], v0 offset:96
	ds_read_b128 v[88:91], v0 offset:4704
	ds_read_b128 v[102:105], v66 offset:18528
	ds_read_b128 v[106:109], v66 offset:23136
	s_waitcnt vmcnt(3)
	ds_write_b128 v67, v[72:75] offset:46080
	s_waitcnt vmcnt(2)
	ds_write_b128 v67, v[94:97] offset:64512
	s_waitcnt lgkmcnt(3)
	v_mfma_f32_32x32x16_bf16 v[2:17], v[88:91], v[102:105], v[2:17]
	s_waitcnt vmcnt(1)
	ds_write_b128 v67, v[76:79] offset:50688
	s_waitcnt vmcnt(0)
	ds_write_b128 v68, v[98:101] offset:13824
	s_waitcnt lgkmcnt(4)
	v_mfma_f32_32x32x16_bf16 v[18:33], v[88:91], v[106:109], v[18:33]
	v_mfma_f32_32x32x16_bf16 v[34:49], v[80:83], v[102:105], v[34:49]
	v_mfma_f32_32x32x16_bf16 v[50:65], v[80:83], v[106:109], v[50:65]
	s_waitcnt lgkmcnt(0)
	s_barrier
; DI int tid_() { int t = threadIdx.x; asm volatile("" : "+v"(t)); return t; }
; template <int NJ> DI void acc_to_lds(const f32x16 (&acc)[2][NJ], float* cl) {
;   const int tid = tid_(), lane = tid & 63, w = tid >> 6, wm = w >> 1, wn = w & 1, h = lane >> 5, c = lane & 31;
; #pragma unroll
;   for (int i = 0; i < 2; ++i)
; #pragma unroll
;     for (int j = 0; j < NJ; ++j)
; #pragma unroll
;       for (int r = 0; r < 16; ++r) {
;         const int row = wm * 64 + i * 32 + (r & 3) + 8 * (r >> 2) + 4 * h;
;         cl[row * CLD + wn * 32 * NJ + j * 32 + c] = acc[i][j][r];
;       }
; }
; template <int NJ> DI void resid_epilogue(float* __restrict__ x, bf16_t* __restrict__ xb, float* __restrict__ ssn, int mt, int nt, const float* cl, float scale) {
;   constexpr int LPR = 16 * NJ, RPP = 256 / LPR, NP = 128 / RPP;
;   const int tid = tid_(), c4 = (tid & (LPR - 1)) * 4, r0 = tid / LPR;
; #pragma unroll 4
;   for (int it = 0; it < NP; ++it) {
;     const int row = r0 + RPP * it;
;     const f32x4 c = *(const f32x4*)(cl + row * CLD + c4);
;     const size_t gi = (size_t)(mt * 128 + row) * DM + nt * (64 * NJ) + c4;
	ds_read_b128 v[68:71], v0 offset:36864
	ds_read_b128 v[72:75], v66 offset:55296
	ds_read_b128 v[76:79], v0 offset:41472
	s_waitcnt lgkmcnt(1)
	v_mfma_f32_32x32x16_bf16 v[34:49], v[68:71], v[72:75], v[34:49]
	s_waitcnt lgkmcnt(0)
	v_mfma_f32_32x32x16_bf16 v[2:17], v[76:79], v[72:75], v[2:17]
	ds_read_b128 v[72:75], v66 offset:59904
	s_waitcnt lgkmcnt(0)
	v_mfma_f32_32x32x16_bf16 v[18:33], v[76:79], v[72:75], v[18:33]
	v_mfma_f32_32x32x16_bf16 v[50:65], v[68:71], v[72:75], v[50:65]
	ds_read_b128 v[68:71], v0 offset:36896
	ds_read_b128 v[80:83], v66 offset:55328
	ds_read_b128 v[84:87], v0 offset:41504
	ds_read_b128 v[88:91], v66 offset:59936
	s_waitcnt lgkmcnt(1)
	v_mfma_f32_32x32x16_bf16 v[2:17], v[84:87], v[80:83], v[2:17]
	s_waitcnt lgkmcnt(0)
	v_mfma_f32_32x32x16_bf16 v[18:33], v[84:87], v[88:91], v[18:33]
	v_mfma_f32_32x32x16_bf16 v[34:49], v[68:71], v[80:83], v[34:49]
	v_mfma_f32_32x32x16_bf16 v[50:65], v[68:71], v[88:91], v[50:65]
	ds_read_b128 v[68:71], v0 offset:36928
	ds_read_b128 v[72:75], v0 offset:41536
	ds_read_b128 v[76:79], v66 offset:55360
	ds_read_b128 v[80:83], v66 offset:59968
	s_waitcnt lgkmcnt(1)
	v_mfma_f32_32x32x16_bf16 v[2:17], v[72:75], v[76:79], v[2:17]
	s_waitcnt lgkmcnt(0)
	v_mfma_f32_32x32x16_bf16 v[18:33], v[72:75], v[80:83], v[18:33]
	v_mfma_f32_32x32x16_bf16 v[34:49], v[68:71], v[76:79], v[34:49]
	v_mfma_f32_32x32x16_bf16 v[50:65], v[68:71], v[80:83], v[50:65]
	ds_read_b128 v[68:71], v0 offset:36960
	ds_read_b128 v[76:79], v0 offset:41568
	ds_read_b128 v[84:87], v66 offset:55392
	ds_read_b128 v[88:91], v66 offset:60000
	s_waitcnt lgkmcnt(1)
	v_mfma_f32_32x32x16_bf16 v[2:17], v[76:79], v[84:87], v[2:17]
	s_waitcnt lgkmcnt(0)
	v_mfma_f32_32x32x16_bf16 v[18:33], v[76:79], v[88:91], v[18:33]
	v_mfma_f32_32x32x16_bf16 v[34:49], v[68:71], v[84:87], v[34:49]
	v_mfma_f32_32x32x16_bf16 v[50:65], v[68:71], v[88:91], v[50:65]
	s_setprio 0
	s_nop 0
	v_mov_b32_e32 v0, v199
	s_barrier
	s_add_i32 s0, s38, s11
	v_lshrrev_b32_e32 v67, 3, v0
	v_lshrrev_b32_e32 v66, 1, v0
	v_and_b32_e32 v67, 4, v67
	v_and_b32_e32 v0, 0x5f, v0
	v_and_or_b32 v66, v66, s17, v67
	v_mul_lo_u32 v66, v66, s15
	v_lshlrev_b32_e32 v0, 2, v0
	v_add3_u32 v0, 0, v66, v0
	s_nop 0
	ds_write2_b32 v0, v34, v50 offset1:32
	ds_write2_b32 v0, v35, v51 offset0:132 offset1:164
	v_add_u32_e32 v34, 0x400, v0
	ds_write2_b32 v34, v36, v52 offset0:8 offset1:40
	ds_write2_b32 v34, v37, v53 offset0:140 offset1:172
	v_add_u32_e32 v34, 0x1000, v0
	ds_write2_b32 v34, v38, v54 offset0:32 offset1:64
	ds_write2_b32 v34, v39, v55 offset0:164 offset1:196
	v_add_u32_e32 v34, 0x1400, v0
	ds_write2_b32 v34, v40, v56 offset0:40 offset1:72
	ds_write2_b32 v34, v41, v57 offset0:172 offset1:204
	v_add_u32_e32 v34, 0x2000, v0
	ds_write2_b32 v34, v42, v58 offset0:64 offset1:96
	ds_write2_b32 v34, v43, v59 offset0:196 offset1:228
	v_add_u32_e32 v34, 0x2400, v0
	ds_write2_b32 v34, v44, v60 offset0:72 offset1:104
	ds_write2_b32 v34, v45, v61 offset0:204 offset1:236
	v_add_u32_e32 v34, 0x3000, v0
	ds_write2_b32 v34, v46, v62 offset0:96 offset1:128
	v_add_u32_e32 v34, 0x3200, v0
	ds_write2_b32 v34, v47, v63 offset0:100 offset1:132
	v_add_u32_e32 v34, 0x3400, v0
	ds_write2_b32 v34, v48, v64 offset0:104 offset1:136
	v_add_u32_e32 v34, 0x3600, v0
	ds_write2_b32 v34, v49, v65 offset0:108 offset1:140
	v_add_u32_e32 v34, 0x4000, v0
	ds_write2_b32 v34, v2, v18 offset0:128 offset1:160
	v_add_u32_e32 v2, 0x4400, v0
	ds_write2_b32 v2, v3, v19 offset0:4 offset1:36
	ds_write2_b32 v2, v4, v20 offset0:136 offset1:168
	v_add_u32_e32 v2, 0x4800, v0
	ds_write2_b32 v2, v5, v21 offset0:12 offset1:44
	v_add_u32_e32 v2, 0x5000, v0
	ds_write2_b32 v2, v6, v22 offset0:160 offset1:192
	v_add_u32_e32 v2, 0x5400, v0
	ds_write2_b32 v2, v7, v23 offset0:36 offset1:68
	ds_write2_b32 v2, v8, v24 offset0:168 offset1:200
	v_add_u32_e32 v2, 0x5800, v0
	ds_write2_b32 v2, v9, v25 offset0:44 offset1:76
	v_add_u32_e32 v2, 0x6000, v0
	ds_write2_b32 v2, v10, v26 offset0:192 offset1:224
	v_add_u32_e32 v2, 0x6400, v0
	ds_write2_b32 v2, v11, v27 offset0:68 offset1:100
	ds_write2_b32 v2, v12, v28 offset0:200 offset1:232
	v_add_u32_e32 v2, 0x6800, v0
	ds_write2_b32 v2, v13, v29 offset0:76 offset1:108
	v_add_u32_e32 v2, 0x7200, v0
	ds_write2_b32 v2, v14, v30 offset0:96 offset1:128
	v_add_u32_e32 v2, 0x7400, v0
	ds_write2_b32 v2, v15, v31 offset0:100 offset1:132
	v_add_u32_e32 v2, 0x7600, v0
	v_add_u32_e32 v0, 0x7800, v0
	ds_write2_b32 v0, v17, v33 offset0:108 offset1:140
	v_mov_b32_e32 v0, v199
	ds_write2_b32 v2, v16, v32 offset0:104 offset1:136
	s_waitcnt lgkmcnt(0)
	s_barrier
	v_mov_b64_e32 v[18:19], s[72:73]
	v_ashrrev_i32_e32 v2, 31, v0
	v_lshrrev_b32_e32 v2, 27, v2
	v_and_b32_e32 v6, 31, v0
	v_add_u32_e32 v0, v0, v2
	v_ashrrev_i32_e32 v14, 5, v0
	v_add_u32_e32 v4, s0, v14
	v_mad_i64_i32 v[2:3], s[0:1], v4, s9, v[18:19]
	v_cmp_lt_i32_e32 vcc, v222, v220
	s_add_i32 s0, s38, s12
	v_add_u32_e32 v10, s0, v14
	v_cndmask_b32_e32 v0, v219, v222, vcc
	v_cmp_lt_i32_e32 vcc, v223, v220
	v_lshlrev_b32_e32 v22, 2, v0
	v_mad_i64_i32 v[8:9], s[0:1], v10, s9, v[18:19]
	v_cndmask_b32_e32 v0, v219, v223, vcc
	v_cmp_lt_i32_e32 vcc, v224, v220
	v_lshlrev_b32_e32 v23, 2, v0
	s_add_u32 s0, s39, s6
	v_cndmask_b32_e32 v0, v219, v224, vcc
	v_cmp_lt_i32_e32 vcc, v225, v220
	v_lshlrev_b32_e32 v24, 2, v0
	s_addc_u32 s1, 0, s7
	v_cndmask_b32_e32 v0, v219, v225, vcc
	v_cmp_lt_i32_e32 vcc, v226, v220
	s_add_i32 s38, s38, s13
	v_lshlrev_b32_e32 v25, 2, v0
	v_cndmask_b32_e32 v0, v219, v226, vcc
	v_add_u32_e32 v20, s40, v14
	v_add_u32_e32 v16, s38, v14
	v_lshlrev_b32_e32 v26, 2, v0
	v_cmp_eq_u32_e32 vcc, 0, v6
	v_ashrrev_i32_e32 v15, 31, v14
	v_ashrrev_i32_e32 v5, 31, v4
	v_lshlrev_b32_e32 v0, 3, v6
	v_lshlrev_b32_e32 v28, 4, v6
	v_mul_lo_u32 v6, v14, s15
	v_ashrrev_i32_e32 v21, 31, v20
	v_ashrrev_i32_e32 v11, 31, v10
	v_ashrrev_i32_e32 v17, 31, v16
	v_lshlrev_b64 v[4:5], 12, v[4:5]
	v_add3_u32 v27, v6, v28, 0
	v_lshlrev_b64 v[6:7], 12, v[20:21]
	v_lshlrev_b64 v[10:11], 12, v[10:11]
	v_lshl_add_u64 v[12:13], v[14:15], 2, s[0:1]
	v_mad_i64_i32 v[14:15], s[0:1], v16, s9, v[18:19]
	v_lshlrev_b64 v[16:17], 12, v[16:17]
	v_mad_i64_i32 v[18:19], s[0:1], v20, s9, v[18:19]
	v_lshl_add_u64 v[2:3], v[2:3], 0, v[0:1]
	v_or3_b32 v4, v4, s35, v28
	v_or3_b32 v6, v6, s35, v28
	v_lshl_add_u64 v[8:9], v[8:9], 0, v[0:1]
	v_or3_b32 v10, v10, s35, v28
	v_lshl_add_u64 v[14:15], v[14:15], 0, v[0:1]
	v_or3_b32 v16, v16, s35, v28
	v_lshl_add_u64 v[18:19], v[18:19], 0, v[0:1]
	v_lshl_add_u64 v[2:3], v[2:3], 0, s[80:81]
	v_lshl_add_u64 v[4:5], s[92:93], 0, v[4:5]
	v_lshl_add_u64 v[6:7], s[92:93], 0, v[6:7]
	v_lshl_add_u64 v[8:9], v[8:9], 0, s[80:81]
	v_lshl_add_u64 v[10:11], s[92:93], 0, v[10:11]
	v_lshl_add_u64 v[14:15], v[14:15], 0, s[80:81]
	v_lshl_add_u64 v[16:17], s[92:93], 0, v[16:17]
	v_lshl_add_u64 v[18:19], v[18:19], 0, s[80:81]
	s_mov_b64 s[0:1], 0
	s_branch .LBB0_1158
